# GEMM K-loops: 248 LDS-DMA pieces use the voffset+SGPR-base form of global_load_lds (no 64-bit per-lane address add in the load segment)
# baseline (speedup 1.0000x reference)
; #define PG8_STAGE(bufoff, gbase, voff) do { _Pragma("unroll") for (int _i = 0; _i < 2; ++_i) \
;         __builtin_amdgcn_global_load_lds((const unsigned*)((const char*)(gbase) + (voff)[_i]), (PG8_LAS unsigned*)(lds + (bufoff) + ldsw + _i * 8192), 16, 0, 0); } while (0)
; #define PG8_WAIT_V(n) asm volatile("s_waitcnt vmcnt(" #n ")" ::: "memory")
; #define PG8_BAR __builtin_amdgcn_s_barrier()
; template <class Epi, class Sched, bool ALIGN_EPI = false, bool SP2 = false, bool F16 = false>
; __device__ __forceinline__ void gemm_phase(PG8_LAS unsigned char* lds, const Gemm g, const Sched& S, const Epi& E, const int wid_in) {
;     ...
;     const int wid = wid_in, lane = lane_, tid = wid * 64 + lane, wr = wid >> 2, wc = wid & 3, fr = lane & 15, fq = lane >> 4;
;     const int K = g.K, nt = K / BK;
;     unsigned voffA[2], voffB[2];
; #pragma unroll
;     for (int i = 0; i < 2; ++i) { int R, C; stage_rc(tid * 16 + i * 8192, R, C); const int Rb = Epi::PERM ? ((R & ~31) + perm32(R & 31)) : R;
;         voffA[i] = (unsigned)(R * K + C) * 2u; voffB[i] = (unsigned)(Rb * K + C) * 2u; }
;     const size_t kstep = (size_t)(BK * 2);
;     const size_t hstep = (size_t)HALF * K * 2;
;     const size_t tstep = 2 * hstep;
;     const unsigned ldsw = (unsigned)wid * 1024u;
;     const int aoff = lds_byte(wr * 64 + fr, fq * 8), boff = lds_byte(wc * 32 + fr, fq * 8);
;     ...
;         PG8_STAGE(PG8_SB(1, 0), cB + kstep, voffB); PG8_STAGE(PG8_SA(1, 0), cA + kstep, voffA); PG8_STAGE(PG8_SB(1, 1), cB + hstep + kstep, voffB);
;         PG8_WAIT_V(6); PG8_BAR;
.LBB0_218:
	s_add_u32 s88, s75, 0x9400000
	s_mov_b64 s[24:25], 0x80
	s_addc_u32 s89, s78, 0
	s_add_i32 m0, s83, 0x18000
	v_lshl_add_u64 v[6:7], v[6:7], 0, s[24:25]
	s_waitcnt vmcnt(2)
	s_barrier
	global_load_lds_dwordx4 v[6:7], off
	v_lshl_add_u64 v[2:3], v[2:3], 0, s[24:25]
	s_add_i32 m0, s83, 0x1a000
	s_add_i32 s90, s83, 0x8000
	s_add_i32 s91, s83, 0xa000
	global_load_lds_dwordx4 v[2:3], off
	v_lshl_add_u64 v[0:1], v[0:1], 0, s[24:25]
	s_mov_b32 m0, s90
	s_add_u32 s6, s58, 0x40080
	global_load_lds_dwordx4 v[0:1], off
	v_lshl_add_u64 v[0:1], v[4:5], 0, s[24:25]
	s_mov_b32 m0, s91
	s_addc_u32 s7, s59, 0
	global_load_lds_dwordx4 v[0:1], off
	s_add_i32 m0, s83, 0x1c000
	s_nop 0
	global_load_lds_dwordx4 v158, s[6:7]
	s_add_i32 m0, s83, 0x1e000
	v_and_b32_e32 v181, 15, v8
	global_load_lds_dwordx4 v162, s[6:7]
	v_or_b32_e32 v0, s70, v181
	v_lshlrev_b32_e32 v1, 6, v0
	v_and_b32_e32 v2, 48, v8
	s_movk_i32 s6, 0x3c0
	v_and_b32_e32 v3, 0xfffffc00, v12
	v_lshlrev_b32_e32 v0, 2, v0
	v_and_or_b32 v1, v1, s6, v2
	v_add_u32_e32 v4, s73, v3
	v_and_b32_e32 v0, 32, v0
	v_bitop3_b32 v0, v1, v4, v0 bitop3:0xde
	v_lshl_or_b32 v1, v181, 6, v2
	v_add_u32_e32 v2, s72, v3
	v_lshlrev_b32_e32 v3, 2, v8
	v_and_b32_e32 v3, 32, v3
	v_bitop3_b32 v183, v1, v2, v3 bitop3:0xde
	v_lshlrev_b32_e32 v1, 14, v9
	v_and_b32_e32 v1, 0xffff8000, v1
	v_lshl_add_u32 v1, v10, 11, v1
	v_and_b32_e32 v2, 1, v9
	v_lshl_or_b32 v1, v2, 6, v1
	v_lshl_add_u32 v166, v11, 1, v1
	v_lshlrev_b32_e32 v1, 14, v13
	v_and_b32_e32 v1, 0xffff8000, v1
	s_waitcnt vmcnt(6)
	s_cmpk_lt_u32 s93, 0x100
	s_mul_i32 s6, s3, 0x210
	v_lshl_add_u32 v1, v14, 11, v1
	v_and_b32_e32 v2, 1, v13
	s_cselect_b64 s[26:27], -1, 0
	s_add_i32 s94, s6, 0
	v_lshl_or_b32 v1, v2, 6, v1
	s_add_i32 s40, 0, 0x10000
	s_add_i32 s41, 0, 0x14000
	v_ashrrev_i32_e32 v182, 4, v8
	s_bfe_u32 s14, s93, 0x10006
	s_ashr_i32 s15, s38, 31
	s_mov_b32 s76, s38
	s_ashr_i32 s92, s74, 31
	s_add_i32 s94, s94, 0x20400
	v_mov_b32_e32 v167, v164
	v_lshl_add_u32 v168, v15, 1, v1
	v_mov_b32_e32 v169, v164
	v_mov_b64_e32 v[170:171], 0x300
	v_mov_b64_e32 v[172:173], 0x2ff
	v_add_u32_e32 v184, s40, v183
	v_add_u32_e32 v185, s41, v183
	v_add_u32_e32 v186, 0, v0
	v_mov_b32_e32 v187, 0x358637bd
	s_mov_b64 s[28:29], 0x8000
	s_mov_b64 s[30:31], 0x10000
	s_mov_b64 s[34:35], 0x18000
	s_mov_b64 s[36:37], 0x48000
	s_mov_b64 s[44:45], 0x50000
	s_mov_b64 s[46:47], 0x58000
	v_mov_b32_e32 v188, 0x3e38aa3b
	s_barrier
	s_branch .LBB0_221

; #define PG8_STAGE(bufoff, gbase, voff) do { _Pragma("unroll") for (int _i = 0; _i < 2; ++_i) \
;         __builtin_amdgcn_global_load_lds((const unsigned*)((const char*)(gbase) + (voff)[_i]), (PG8_LAS unsigned*)(lds + (bufoff) + ldsw + _i * 8192), 16, 0, 0); } while (0)
; #define PG8_LDA(dst, b, h) do { _Pragma("unroll") for (int m = 0; m < 4; ++m) _Pragma("unroll") for (int k = 0; k < 2; ++k) dst[m][k] = *(const PG8_LAS bf16x8*)(lds + PG8_SA(b, h) + aoff + m * 2048 + k * 1024); } while (0)
; #define PG8_LDB(dst, b, h) do { _Pragma("unroll") for (int n = 0; n < 2; ++n) _Pragma("unroll") for (int k = 0; k < 2; ++k) dst[n][k] = *(const PG8_LAS bf16x8*)(lds + PG8_SB(b, h) + boff + n * 2048 + k * 1024); } while (0)
; #define PG8_MMA(ai, bj, At, Bt) do { __builtin_amdgcn_s_setprio(1); _Pragma("unroll") for (int m = 0; m < 4; ++m) _Pragma("unroll") for (int n = 0; n < 2; ++n) _Pragma("unroll") for (int k = 0; k < 2; ++k) \
;         acc[ai][bj][m][n] = mma16<F16>(Bt[n][k], At[m][k], acc[ai][bj][m][n]); __builtin_amdgcn_s_setprio(0); } while (0)
; #define PG8_WAIT_V(n) asm volatile("s_waitcnt vmcnt(" #n ")" ::: "memory")
; #define PG8_WAIT_L(n) asm volatile("s_waitcnt lgkmcnt(" #n ")" ::: "memory")
; #define PG8_BAR __builtin_amdgcn_s_barrier()
; #define PG8_SCHED __builtin_amdgcn_sched_barrier(0)
; template <class Epi, class Sched, bool ALIGN_EPI = false, bool SP2 = false, bool F16 = false>
; __device__ __forceinline__ void gemm_phase(PG8_LAS unsigned char* lds, const Gemm g, const Sched& S, const Epi& E, const int wid_in) {
;     ...
;             PG8_LDB(B0, 0, 0); PG8_LDB(B1, 0, 1); PG8_SCHED; PG8_LDA(At, 0, 0); PG8_STAGE(PG8_SA(1, 1), a1 + hstep, voffA);
;             PG8_WAIT_V(8); PG8_WAIT_L(0); PG8_BAR; PG8_MMA(0, 0, At, B0); PG8_MMA(0, 1, At, B1); PG8_BAR; PG8_SCHED;
;             PG8_LDA(At, 0, 1); PG8_STAGE(PG8_SB(0, 0), b2, voffB); PG8_STAGE(PG8_SB(0, 1), b2 + hstep, voffB); PG8_STAGE(PG8_SA(0, 0), a2, voffA);
;             PG8_WAIT_V(8); PG8_WAIT_L(0); PG8_BAR; PG8_MMA(1, 0, At, B0); PG8_MMA(1, 1, At, B1); PG8_BAR; PG8_SCHED;
.LBB0_224:
	ds_read_b128 v[128:131], v184
	ds_read_b128 v[132:135], v184 offset:1024
	ds_read_b128 v[136:139], v184 offset:2048
	ds_read_b128 v[140:143], v184 offset:3072
	ds_read_b128 v[144:147], v185
	ds_read_b128 v[148:151], v185 offset:1024
	ds_read_b128 v[152:155], v185 offset:2048
	ds_read_b128 v[174:177], v185 offset:3072
	s_add_u32 s58, s56, 0xfffc0080
	s_addc_u32 s59, s57, -1
	s_cmp_eq_u32 s62, 12
	s_cselect_b32 s61, s9, s59
	s_cselect_b32 s60, s21, s58
	s_cselect_b32 s59, s42, s51
	s_cselect_b32 s58, s43, s49
	s_add_i32 m0, s83, 0xc000
	ds_read_b128 v[190:193], v186
	ds_read_b128 v[194:197], v186 offset:1024
	ds_read_b128 v[198:201], v186 offset:2048
	ds_read_b128 v[202:205], v186 offset:3072
	ds_read_b128 v[206:209], v186 offset:4096
	ds_read_b128 v[210:213], v186 offset:5120
	ds_read_b128 v[214:217], v186 offset:6144
	ds_read_b128 v[218:221], v186 offset:7168
	global_load_lds_dwordx4 v166, s[56:57]
	s_add_i32 m0, s83, 0xe000
	s_nop 0
	global_load_lds_dwordx4 v168, s[56:57]
	s_waitcnt vmcnt(8)
	s_waitcnt lgkmcnt(0)
	s_barrier
	s_setprio 1
	s_waitcnt lgkmcnt(0)
	v_mfma_f32_16x16x32_f16 v[124:127], v[128:131], v[190:193], v[124:127]
	v_mfma_f32_16x16x32_f16 v[120:123], v[136:139], v[190:193], v[120:123]
	v_mfma_f32_16x16x32_f16 v[108:111], v[128:131], v[198:201], v[108:111]
	v_mfma_f32_16x16x32_f16 v[104:107], v[136:139], v[198:201], v[104:107]
	v_mfma_f32_16x16x32_f16 v[92:95], v[128:131], v[206:209], v[92:95]
	v_mfma_f32_16x16x32_f16 v[88:91], v[136:139], v[206:209], v[88:91]
	v_mfma_f32_16x16x32_f16 v[76:79], v[128:131], v[214:217], v[76:79]
	v_mfma_f32_16x16x32_f16 v[72:75], v[136:139], v[214:217], v[72:75]
	v_mfma_f32_16x16x32_f16 v[124:127], v[132:135], v[194:197], v[124:127]
	v_mfma_f32_16x16x32_f16 v[120:123], v[140:143], v[194:197], v[120:123]
	v_mfma_f32_16x16x32_f16 v[108:111], v[132:135], v[202:205], v[108:111]
	v_mfma_f32_16x16x32_f16 v[104:107], v[140:143], v[202:205], v[104:107]
	v_mfma_f32_16x16x32_f16 v[92:95], v[132:135], v[210:213], v[92:95]
	v_mfma_f32_16x16x32_f16 v[88:91], v[140:143], v[210:213], v[88:91]
	v_mfma_f32_16x16x32_f16 v[76:79], v[132:135], v[218:221], v[76:79]
	v_mfma_f32_16x16x32_f16 v[72:75], v[140:143], v[218:221], v[72:75]
	s_setprio 0
	s_setprio 1
	v_mfma_f32_16x16x32_f16 v[116:119], v[144:147], v[190:193], v[116:119]
	v_mfma_f32_16x16x32_f16 v[112:115], v[152:155], v[190:193], v[112:115]
	v_mfma_f32_16x16x32_f16 v[100:103], v[144:147], v[198:201], v[100:103]
	v_mfma_f32_16x16x32_f16 v[96:99], v[152:155], v[198:201], v[96:99]
	v_mfma_f32_16x16x32_f16 v[84:87], v[144:147], v[206:209], v[84:87]
	v_mfma_f32_16x16x32_f16 v[80:83], v[152:155], v[206:209], v[80:83]
	v_mfma_f32_16x16x32_f16 v[68:71], v[144:147], v[214:217], v[68:71]
	v_mfma_f32_16x16x32_f16 v[64:67], v[152:155], v[214:217], v[64:67]
	v_mfma_f32_16x16x32_f16 v[116:119], v[148:151], v[194:197], v[116:119]
	v_mfma_f32_16x16x32_f16 v[112:115], v[174:177], v[194:197], v[112:115]
	v_mfma_f32_16x16x32_f16 v[100:103], v[148:151], v[202:205], v[100:103]
	v_mfma_f32_16x16x32_f16 v[96:99], v[174:177], v[202:205], v[96:99]
	v_mfma_f32_16x16x32_f16 v[84:87], v[148:151], v[210:213], v[84:87]
	v_mfma_f32_16x16x32_f16 v[80:83], v[174:177], v[210:213], v[80:83]
	v_mfma_f32_16x16x32_f16 v[68:71], v[148:151], v[218:221], v[68:71]
	v_mfma_f32_16x16x32_f16 v[64:67], v[174:177], v[218:221], v[64:67]
	s_setprio 0
	s_barrier
	s_add_i32 s63, s40, s68
	v_lshl_add_u64 v[178:179], s[58:59], 0, v[158:159]
	s_mov_b32 m0, s63
	ds_read_b128 v[190:193], v186 offset:16384
	ds_read_b128 v[194:197], v186 offset:17408
	ds_read_b128 v[198:201], v186 offset:18432
	ds_read_b128 v[202:205], v186 offset:19456
	ds_read_b128 v[206:209], v186 offset:20480
	ds_read_b128 v[210:213], v186 offset:21504
	ds_read_b128 v[214:217], v186 offset:22528
	ds_read_b128 v[218:221], v186 offset:23552
	global_load_lds_dwordx4 v[178:179], off
	s_add_i32 m0, s63, 0x2000
	s_add_u32 s64, s58, 0x40000
	v_lshl_add_u64 v[222:223], s[58:59], 0, v[162:163]
	s_addc_u32 s65, s59, 0
	s_add_i32 s63, s41, s68
	global_load_lds_dwordx4 v[222:223], off
	s_mov_b32 m0, s63
	v_lshl_add_u64 v[226:227], s[60:61], 0, v[160:161]
	global_load_lds_dwordx4 v158, s[64:65]
	s_add_i32 m0, s63, 0x2000
	s_nop 0
	global_load_lds_dwordx4 v162, s[64:65]
	v_lshl_add_u64 v[224:225], s[60:61], 0, v[156:157]
	s_mov_b32 m0, s83
	s_nop 0
	global_load_lds_dwordx4 v[224:225], off
	s_mov_b32 m0, s84
	s_nop 0
	global_load_lds_dwordx4 v[226:227], off
	s_waitcnt vmcnt(8)
	s_waitcnt lgkmcnt(0)
	s_barrier
	s_setprio 1
	s_waitcnt lgkmcnt(0)
	v_mfma_f32_16x16x32_f16 v[60:63], v[128:131], v[190:193], v[60:63]
	v_mfma_f32_16x16x32_f16 v[56:59], v[136:139], v[190:193], v[56:59]
	v_mfma_f32_16x16x32_f16 v[44:47], v[128:131], v[198:201], v[44:47]
	v_mfma_f32_16x16x32_f16 v[40:43], v[136:139], v[198:201], v[40:43]
	v_mfma_f32_16x16x32_f16 v[28:31], v[128:131], v[206:209], v[28:31]
	v_mfma_f32_16x16x32_f16 v[24:27], v[136:139], v[206:209], v[24:27]
	v_mfma_f32_16x16x32_f16 v[12:15], v[128:131], v[214:217], v[12:15]
	v_mfma_f32_16x16x32_f16 v[8:11], v[136:139], v[214:217], v[8:11]
	v_mfma_f32_16x16x32_f16 v[60:63], v[132:135], v[194:197], v[60:63]
	v_mfma_f32_16x16x32_f16 v[56:59], v[140:143], v[194:197], v[56:59]
	v_mfma_f32_16x16x32_f16 v[44:47], v[132:135], v[202:205], v[44:47]
	v_mfma_f32_16x16x32_f16 v[40:43], v[140:143], v[202:205], v[40:43]
	v_mfma_f32_16x16x32_f16 v[28:31], v[132:135], v[210:213], v[28:31]
	v_mfma_f32_16x16x32_f16 v[24:27], v[140:143], v[210:213], v[24:27]
	v_mfma_f32_16x16x32_f16 v[12:15], v[132:135], v[218:221], v[12:15]
	v_mfma_f32_16x16x32_f16 v[8:11], v[140:143], v[218:221], v[8:11]
	s_setprio 0
	s_setprio 1
	v_mfma_f32_16x16x32_f16 v[52:55], v[144:147], v[190:193], v[52:55]
	v_mfma_f32_16x16x32_f16 v[48:51], v[152:155], v[190:193], v[48:51]
	v_mfma_f32_16x16x32_f16 v[36:39], v[144:147], v[198:201], v[36:39]
	v_mfma_f32_16x16x32_f16 v[32:35], v[152:155], v[198:201], v[32:35]
	v_mfma_f32_16x16x32_f16 v[20:23], v[144:147], v[206:209], v[20:23]
	v_mfma_f32_16x16x32_f16 v[16:19], v[152:155], v[206:209], v[16:19]
	v_mfma_f32_16x16x32_f16 v[4:7], v[144:147], v[214:217], v[4:7]
	v_mfma_f32_16x16x32_f16 v[0:3], v[152:155], v[214:217], v[0:3]
	v_mfma_f32_16x16x32_f16 v[52:55], v[148:151], v[194:197], v[52:55]
	v_mfma_f32_16x16x32_f16 v[48:51], v[174:177], v[194:197], v[48:51]
	v_mfma_f32_16x16x32_f16 v[36:39], v[148:151], v[202:205], v[36:39]
	v_mfma_f32_16x16x32_f16 v[32:35], v[174:177], v[202:205], v[32:35]
	v_mfma_f32_16x16x32_f16 v[20:23], v[148:151], v[210:213], v[20:23]
	v_mfma_f32_16x16x32_f16 v[16:19], v[174:177], v[210:213], v[16:19]
	v_mfma_f32_16x16x32_f16 v[4:7], v[148:151], v[218:221], v[4:7]
	v_mfma_f32_16x16x32_f16 v[0:3], v[174:177], v[218:221], v[0:3]
	s_setprio 0
	s_barrier
; #define PG8_STAGE(bufoff, gbase, voff) do { _Pragma("unroll") for (int _i = 0; _i < 2; ++_i) \
;         __builtin_amdgcn_global_load_lds((const unsigned*)((const char*)(gbase) + (voff)[_i]), (PG8_LAS unsigned*)(lds + (bufoff) + ldsw + _i * 8192), 16, 0, 0); } while (0)
; #define PG8_LDA(dst, b, h) do { _Pragma("unroll") for (int m = 0; m < 4; ++m) _Pragma("unroll") for (int k = 0; k < 2; ++k) dst[m][k] = *(const PG8_LAS bf16x8*)(lds + PG8_SA(b, h) + aoff + m * 2048 + k * 1024); } while (0)
; #define PG8_LDB(dst, b, h) do { _Pragma("unroll") for (int n = 0; n < 2; ++n) _Pragma("unroll") for (int k = 0; k < 2; ++k) dst[n][k] = *(const PG8_LAS bf16x8*)(lds + PG8_SB(b, h) + boff + n * 2048 + k * 1024); } while (0)
; #define PG8_MMA(ai, bj, At, Bt) do { __builtin_amdgcn_s_setprio(1); _Pragma("unroll") for (int m = 0; m < 4; ++m) _Pragma("unroll") for (int n = 0; n < 2; ++n) _Pragma("unroll") for (int k = 0; k < 2; ++k) \
;         acc[ai][bj][m][n] = mma16<F16>(Bt[n][k], At[m][k], acc[ai][bj][m][n]); __builtin_amdgcn_s_setprio(0); } while (0)
; #define PG8_WAIT_V(n) asm volatile("s_waitcnt vmcnt(" #n ")" ::: "memory")
; #define PG8_WAIT_L(n) asm volatile("s_waitcnt lgkmcnt(" #n ")" ::: "memory")
; #define PG8_BAR __builtin_amdgcn_s_barrier()
; #define PG8_SCHED __builtin_amdgcn_sched_barrier(0)
; template <class Epi, class Sched, bool ALIGN_EPI = false, bool SP2 = false, bool F16 = false>
; __device__ __forceinline__ void gemm_phase(PG8_LAS unsigned char* lds, const Gemm g, const Sched& S, const Epi& E, const int wid_in) {
;     ...
;             PG8_LDB(B0, 1, 0); PG8_LDB(B1, 1, 1); PG8_SCHED; PG8_LDA(At, 1, 0); PG8_STAGE(PG8_SA(0, 1), a2 + hstep, voffA);
;             PG8_WAIT_V(8); PG8_WAIT_L(0); PG8_BAR; PG8_MMA(0, 0, At, B0); PG8_MMA(0, 1, At, B1); PG8_BAR; PG8_SCHED;
;             PG8_LDA(At, 1, 1); PG8_STAGE(PG8_SB(1, 0), b3, voffB); PG8_STAGE(PG8_SB(1, 1), b3 + hstep, voffB); PG8_STAGE(PG8_SA(1, 0), a3, voffA);
;             PG8_WAIT_V(8); PG8_WAIT_L(0); PG8_BAR; PG8_MMA(1, 0, At, B0); PG8_MMA(1, 1, At, B1); PG8_BAR; PG8_SCHED;
	s_add_i32 s63, 0, 0x18000
	s_add_i32 s64, 0, 0x1c000
	v_add_u32_e32 v140, s63, v183
	v_add_u32_e32 v165, s64, v183
	ds_read_b128 v[128:131], v140
	ds_read_b128 v[132:135], v140 offset:1024
	ds_read_b128 v[136:139], v140 offset:2048
	ds_read_b128 v[140:143], v140 offset:3072
	ds_read_b128 v[144:147], v165
	ds_read_b128 v[148:151], v165 offset:1024
	ds_read_b128 v[152:155], v165 offset:2048
	ds_read_b128 v[174:177], v165 offset:3072
	s_add_u32 s60, s60, 0x40000
	s_addc_u32 s61, s61, 0
	s_mov_b32 m0, s85
	ds_read_b128 v[190:193], v186 offset:32768
	ds_read_b128 v[194:197], v186 offset:33792
	ds_read_b128 v[198:201], v186 offset:34816
	ds_read_b128 v[202:205], v186 offset:35840
	ds_read_b128 v[206:209], v186 offset:36864
	ds_read_b128 v[210:213], v186 offset:37888
	ds_read_b128 v[214:217], v186 offset:38912
	ds_read_b128 v[218:221], v186 offset:39936
	global_load_lds_dwordx4 v156, s[60:61]
	v_lshl_add_u64 v[228:229], s[60:61], 0, v[160:161]
	s_mov_b32 m0, s86
	s_nop 0
	global_load_lds_dwordx4 v[228:229], off
	s_waitcnt vmcnt(8)
	s_waitcnt lgkmcnt(0)
	s_barrier
	s_setprio 1
	s_waitcnt lgkmcnt(0)
	v_mfma_f32_16x16x32_f16 v[124:127], v[128:131], v[190:193], v[124:127]
	v_mfma_f32_16x16x32_f16 v[120:123], v[136:139], v[190:193], v[120:123]
	v_mfma_f32_16x16x32_f16 v[108:111], v[128:131], v[198:201], v[108:111]
	v_mfma_f32_16x16x32_f16 v[104:107], v[136:139], v[198:201], v[104:107]
	v_mfma_f32_16x16x32_f16 v[92:95], v[128:131], v[206:209], v[92:95]
	v_mfma_f32_16x16x32_f16 v[88:91], v[136:139], v[206:209], v[88:91]
	v_mfma_f32_16x16x32_f16 v[76:79], v[128:131], v[214:217], v[76:79]
	v_mfma_f32_16x16x32_f16 v[72:75], v[136:139], v[214:217], v[72:75]
	v_mfma_f32_16x16x32_f16 v[124:127], v[132:135], v[194:197], v[124:127]
	v_mfma_f32_16x16x32_f16 v[120:123], v[140:143], v[194:197], v[120:123]
	v_mfma_f32_16x16x32_f16 v[108:111], v[132:135], v[202:205], v[108:111]
	v_mfma_f32_16x16x32_f16 v[104:107], v[140:143], v[202:205], v[104:107]
	v_mfma_f32_16x16x32_f16 v[92:95], v[132:135], v[210:213], v[92:95]
	v_mfma_f32_16x16x32_f16 v[88:91], v[140:143], v[210:213], v[88:91]
	v_mfma_f32_16x16x32_f16 v[76:79], v[132:135], v[218:221], v[76:79]
	v_mfma_f32_16x16x32_f16 v[72:75], v[140:143], v[218:221], v[72:75]
	s_setprio 0
	s_setprio 1
	v_mfma_f32_16x16x32_f16 v[116:119], v[144:147], v[190:193], v[116:119]
	v_mfma_f32_16x16x32_f16 v[112:115], v[152:155], v[190:193], v[112:115]
	v_mfma_f32_16x16x32_f16 v[100:103], v[144:147], v[198:201], v[100:103]
	v_mfma_f32_16x16x32_f16 v[96:99], v[152:155], v[198:201], v[96:99]
	v_mfma_f32_16x16x32_f16 v[84:87], v[144:147], v[206:209], v[84:87]
	v_mfma_f32_16x16x32_f16 v[80:83], v[152:155], v[206:209], v[80:83]
	v_mfma_f32_16x16x32_f16 v[68:71], v[144:147], v[214:217], v[68:71]
	v_mfma_f32_16x16x32_f16 v[64:67], v[152:155], v[214:217], v[64:67]
	v_mfma_f32_16x16x32_f16 v[116:119], v[148:151], v[194:197], v[116:119]
	v_mfma_f32_16x16x32_f16 v[112:115], v[174:177], v[194:197], v[112:115]
	v_mfma_f32_16x16x32_f16 v[100:103], v[148:151], v[202:205], v[100:103]
	v_mfma_f32_16x16x32_f16 v[96:99], v[174:177], v[202:205], v[96:99]
	v_mfma_f32_16x16x32_f16 v[84:87], v[148:151], v[210:213], v[84:87]
	v_mfma_f32_16x16x32_f16 v[80:83], v[174:177], v[210:213], v[80:83]
	v_mfma_f32_16x16x32_f16 v[68:71], v[148:151], v[218:221], v[68:71]
	v_mfma_f32_16x16x32_f16 v[64:67], v[174:177], v[218:221], v[64:67]
	s_setprio 0
	s_barrier
	s_add_i32 s60, s63, s68
	v_lshl_add_u64 v[178:179], v[178:179], 0, s[24:25]
	s_mov_b32 m0, s60
	ds_read_b128 v[190:193], v186 offset:49152
	ds_read_b128 v[194:197], v186 offset:50176
	ds_read_b128 v[198:201], v186 offset:51200
	ds_read_b128 v[202:205], v186 offset:52224
	ds_read_b128 v[206:209], v186 offset:53248
	ds_read_b128 v[210:213], v186 offset:54272
	ds_read_b128 v[214:217], v186 offset:55296
	ds_read_b128 v[218:221], v186 offset:56320
	global_load_lds_dwordx4 v[178:179], off
	s_add_i32 m0, s60, 0x2000
	s_add_u32 s58, s58, 0x40080
	v_lshl_add_u64 v[178:179], v[222:223], 0, s[24:25]
	s_addc_u32 s59, s59, 0
	s_add_i32 s60, s64, s68
	global_load_lds_dwordx4 v[178:179], off
	s_mov_b32 m0, s60
	s_nop 0
	global_load_lds_dwordx4 v158, s[58:59]
	s_add_i32 m0, s60, 0x2000
	s_nop 0
	global_load_lds_dwordx4 v162, s[58:59]
	v_lshl_add_u64 v[178:179], v[224:225], 0, s[24:25]
	s_mov_b32 m0, s90
	s_nop 0
	global_load_lds_dwordx4 v[178:179], off
	v_lshl_add_u64 v[178:179], v[226:227], 0, s[24:25]
	s_mov_b32 m0, s91
	s_nop 0
	global_load_lds_dwordx4 v[178:179], off
	s_waitcnt vmcnt(8)
	s_waitcnt lgkmcnt(0)
	s_barrier
	s_setprio 1
	s_waitcnt lgkmcnt(0)
	v_mfma_f32_16x16x32_f16 v[60:63], v[128:131], v[190:193], v[60:63]
	v_mfma_f32_16x16x32_f16 v[56:59], v[136:139], v[190:193], v[56:59]
	v_mfma_f32_16x16x32_f16 v[44:47], v[128:131], v[198:201], v[44:47]
	v_mfma_f32_16x16x32_f16 v[40:43], v[136:139], v[198:201], v[40:43]
	v_mfma_f32_16x16x32_f16 v[28:31], v[128:131], v[206:209], v[28:31]
	v_mfma_f32_16x16x32_f16 v[24:27], v[136:139], v[206:209], v[24:27]
	v_mfma_f32_16x16x32_f16 v[12:15], v[128:131], v[214:217], v[12:15]
	v_mfma_f32_16x16x32_f16 v[8:11], v[136:139], v[214:217], v[8:11]
	v_mfma_f32_16x16x32_f16 v[60:63], v[132:135], v[194:197], v[60:63]
	v_mfma_f32_16x16x32_f16 v[56:59], v[140:143], v[194:197], v[56:59]
	v_mfma_f32_16x16x32_f16 v[44:47], v[132:135], v[202:205], v[44:47]
	v_mfma_f32_16x16x32_f16 v[40:43], v[140:143], v[202:205], v[40:43]
	v_mfma_f32_16x16x32_f16 v[28:31], v[132:135], v[210:213], v[28:31]
	v_mfma_f32_16x16x32_f16 v[24:27], v[140:143], v[210:213], v[24:27]
	v_mfma_f32_16x16x32_f16 v[12:15], v[132:135], v[218:221], v[12:15]
	v_mfma_f32_16x16x32_f16 v[8:11], v[140:143], v[218:221], v[8:11]
	s_setprio 0
	s_setprio 1
	v_mfma_f32_16x16x32_f16 v[52:55], v[144:147], v[190:193], v[52:55]
	v_mfma_f32_16x16x32_f16 v[48:51], v[152:155], v[190:193], v[48:51]
	v_mfma_f32_16x16x32_f16 v[36:39], v[144:147], v[198:201], v[36:39]
	v_mfma_f32_16x16x32_f16 v[32:35], v[152:155], v[198:201], v[32:35]
	v_mfma_f32_16x16x32_f16 v[20:23], v[144:147], v[206:209], v[20:23]
	v_mfma_f32_16x16x32_f16 v[16:19], v[152:155], v[206:209], v[16:19]
	v_mfma_f32_16x16x32_f16 v[4:7], v[144:147], v[214:217], v[4:7]
	v_mfma_f32_16x16x32_f16 v[0:3], v[152:155], v[214:217], v[0:3]
	v_mfma_f32_16x16x32_f16 v[52:55], v[148:151], v[194:197], v[52:55]
	v_mfma_f32_16x16x32_f16 v[48:51], v[174:177], v[194:197], v[48:51]
	v_mfma_f32_16x16x32_f16 v[36:39], v[148:151], v[202:205], v[36:39]
	v_mfma_f32_16x16x32_f16 v[32:35], v[174:177], v[202:205], v[32:35]
	v_mfma_f32_16x16x32_f16 v[20:23], v[148:151], v[210:213], v[20:23]
	v_mfma_f32_16x16x32_f16 v[16:19], v[174:177], v[210:213], v[16:19]
	v_mfma_f32_16x16x32_f16 v[4:7], v[148:151], v[218:221], v[4:7]
	v_mfma_f32_16x16x32_f16 v[0:3], v[174:177], v[218:221], v[0:3]
	s_setprio 0
	s_barrier
	s_add_i32 s62, s62, 2
	s_add_u32 s56, s56, 0x100
	s_addc_u32 s57, s57, 0
	s_add_u32 s49, s49, 0x100
	s_addc_u32 s51, s51, 0
	s_cmp_gt_u32 s62, 13
	s_cbranch_scc0 .LBB0_224
	s_and_b64 vcc, exec, s[26:27]
	s_cbranch_vccz .LBB0_227
	s_barrier

; #define PG8_STAGE(bufoff, gbase, voff) do { _Pragma("unroll") for (int _i = 0; _i < 2; ++_i) \
;         __builtin_amdgcn_global_load_lds((const unsigned*)((const char*)(gbase) + (voff)[_i]), (PG8_LAS unsigned*)(lds + (bufoff) + ldsw + _i * 8192), 16, 0, 0); } while (0)
; #define PG8_WAIT_V(n) asm volatile("s_waitcnt vmcnt(" #n ")" ::: "memory")
; #define PG8_BAR __builtin_amdgcn_s_barrier()
; template <class Epi, class Sched, bool ALIGN_EPI = false, bool SP2 = false, bool F16 = false>
; __device__ __forceinline__ void gemm_phase(PG8_LAS unsigned char* lds, const Gemm g, const Sched& S, const Epi& E, const int wid_in) {
;     ...
;     const int wid = wid_in, lane = lane_, tid = wid * 64 + lane, wr = wid >> 2, wc = wid & 3, fr = lane & 15, fq = lane >> 4;
;     const int K = g.K, nt = K / BK;
;     unsigned voffA[2], voffB[2];
; #pragma unroll
;     for (int i = 0; i < 2; ++i) { int R, C; stage_rc(tid * 16 + i * 8192, R, C); const int Rb = Epi::PERM ? ((R & ~31) + perm32(R & 31)) : R;
;         voffA[i] = (unsigned)(R * K + C) * 2u; voffB[i] = (unsigned)(Rb * K + C) * 2u; }
;     const size_t kstep = (size_t)(BK * 2);
;     const size_t hstep = (size_t)HALF * K * 2;
;     const size_t tstep = 2 * hstep;
;     const unsigned ldsw = (unsigned)wid * 1024u;
;     const int aoff = lds_byte(wr * 64 + fr, fq * 8), boff = lds_byte(wc * 32 + fr, fq * 8);
;     ...
;         PG8_STAGE(PG8_SB(1, 0), cB + kstep, voffB); PG8_STAGE(PG8_SA(1, 0), cA + kstep, voffA); PG8_STAGE(PG8_SB(1, 1), cB + hstep + kstep, voffB);
;         PG8_WAIT_V(6); PG8_BAR;
.LBB0_498:
	s_add_u32 s12, s8, 0x7400000
	s_addc_u32 s13, s9, 0
	s_add_u32 s18, s8, 0x13400000
	s_addc_u32 s19, s9, 0
	s_add_u32 s20, s8, 0x15500000
	s_mov_b64 s[22:23], 0x80
	s_addc_u32 s21, s9, 0
	s_add_i32 m0, s74, 0x18000
	v_lshl_add_u64 v[6:7], v[6:7], 0, s[22:23]
	s_waitcnt vmcnt(2)
	s_barrier
	global_load_lds_dwordx4 v[6:7], off
	v_lshl_add_u64 v[4:5], v[4:5], 0, s[22:23]
	s_add_i32 m0, s74, 0x1a000
	s_add_i32 s54, s74, 0xa000
	global_load_lds_dwordx4 v[4:5], off
	v_lshl_add_u64 v[0:1], v[0:1], 0, s[22:23]
	s_mov_b32 m0, s75
	s_add_u32 s8, s46, 0x40080
	global_load_lds_dwordx4 v[0:1], off
	v_lshl_add_u64 v[0:1], v[2:3], 0, s[22:23]
	s_mov_b32 m0, s54
	s_addc_u32 s9, s47, 0
	global_load_lds_dwordx4 v[0:1], off
	s_add_i32 m0, s74, 0x1c000
	s_nop 0
	global_load_lds_dwordx4 v154, s[8:9]
	s_add_i32 m0, s74, 0x1e000
	v_and_b32_e32 v187, 15, v8
	global_load_lds_dwordx4 v158, s[8:9]
	v_or_b32_e32 v0, s70, v187
	v_lshlrev_b32_e32 v1, 6, v0
	v_and_b32_e32 v2, 48, v8
	s_movk_i32 s8, 0x3c0
	v_and_b32_e32 v3, 0xfffffc00, v12
	v_lshlrev_b32_e32 v0, 2, v0
	v_and_or_b32 v1, v1, s8, v2
	v_add_u32_e32 v4, s73, v3
	v_and_b32_e32 v0, 32, v0
	v_bitop3_b32 v0, v1, v4, v0 bitop3:0xde
	v_lshl_or_b32 v1, v187, 6, v2
	v_add_u32_e32 v2, s72, v3
	v_lshlrev_b32_e32 v3, 2, v8
	v_and_b32_e32 v3, 32, v3
	v_bitop3_b32 v188, v1, v2, v3 bitop3:0xde
	v_lshlrev_b32_e32 v1, 14, v9
	v_and_b32_e32 v1, 0xffff8000, v1
	v_lshl_add_u32 v1, v10, 11, v1
	v_and_b32_e32 v2, 1, v9
	v_lshl_or_b32 v1, v2, 6, v1
	v_lshl_add_u32 v160, v11, 1, v1
	v_lshlrev_b32_e32 v1, 14, v13
	v_and_b32_e32 v1, 0xffff8000, v1
	s_waitcnt vmcnt(6)
	v_lshl_add_u32 v1, v14, 11, v1
	v_and_b32_e32 v2, 1, v13
	v_lshl_or_b32 v1, v2, 6, v1
	s_add_i32 s60, 0, 0x10000
	s_add_i32 s61, 0, 0x14000
	v_ashrrev_i32_e32 v186, 4, v8
	s_ashr_i32 s55, s38, 31
	s_mov_b32 s58, s38
	s_ashr_i32 s59, s14, 31
	v_mov_b32_e32 v161, v155
	v_lshl_add_u32 v162, v15, 1, v1
	v_mov_b32_e32 v163, v155
	v_mov_b64_e32 v[164:165], 0x100
	v_mov_b64_e32 v[166:167], 0xff
	v_add_u32_e32 v189, s60, v188
	v_add_u32_e32 v190, s61, v188
	v_add_u32_e32 v191, 0, v0
	s_mov_b32 s62, 0
	s_barrier
	s_branch .LBB0_501

; #define PG8_STAGE(bufoff, gbase, voff) do { _Pragma("unroll") for (int _i = 0; _i < 2; ++_i) \
;         __builtin_amdgcn_global_load_lds((const unsigned*)((const char*)(gbase) + (voff)[_i]), (PG8_LAS unsigned*)(lds + (bufoff) + ldsw + _i * 8192), 16, 0, 0); } while (0)
; #define PG8_LDA(dst, b, h) do { _Pragma("unroll") for (int m = 0; m < 4; ++m) _Pragma("unroll") for (int k = 0; k < 2; ++k) dst[m][k] = *(const PG8_LAS bf16x8*)(lds + PG8_SA(b, h) + aoff + m * 2048 + k * 1024); } while (0)
; #define PG8_LDB(dst, b, h) do { _Pragma("unroll") for (int n = 0; n < 2; ++n) _Pragma("unroll") for (int k = 0; k < 2; ++k) dst[n][k] = *(const PG8_LAS bf16x8*)(lds + PG8_SB(b, h) + boff + n * 2048 + k * 1024); } while (0)
; #define PG8_MMA(ai, bj, At, Bt) do { __builtin_amdgcn_s_setprio(1); _Pragma("unroll") for (int m = 0; m < 4; ++m) _Pragma("unroll") for (int n = 0; n < 2; ++n) _Pragma("unroll") for (int k = 0; k < 2; ++k) \
;         acc[ai][bj][m][n] = mma16<F16>(Bt[n][k], At[m][k], acc[ai][bj][m][n]); __builtin_amdgcn_s_setprio(0); } while (0)
; #define PG8_WAIT_V(n) asm volatile("s_waitcnt vmcnt(" #n ")" ::: "memory")
; #define PG8_WAIT_L(n) asm volatile("s_waitcnt lgkmcnt(" #n ")" ::: "memory")
; #define PG8_BAR __builtin_amdgcn_s_barrier()
; #define PG8_SCHED __builtin_amdgcn_sched_barrier(0)
; template <class Epi, class Sched, bool ALIGN_EPI = false, bool SP2 = false, bool F16 = false>
; __device__ __forceinline__ void gemm_phase(PG8_LAS unsigned char* lds, const Gemm g, const Sched& S, const Epi& E, const int wid_in) {
;     ...
;             PG8_LDB(B0, 0, 0); PG8_LDB(B1, 0, 1); PG8_SCHED; PG8_LDA(At, 0, 0); PG8_STAGE(PG8_SA(1, 1), a1 + hstep, voffA);
;             PG8_WAIT_V(8); PG8_WAIT_L(0); PG8_BAR; PG8_MMA(0, 0, At, B0); PG8_MMA(0, 1, At, B1); PG8_BAR; PG8_SCHED;
;             PG8_LDA(At, 0, 1); PG8_STAGE(PG8_SB(0, 0), b2, voffB); PG8_STAGE(PG8_SB(0, 1), b2 + hstep, voffB); PG8_STAGE(PG8_SA(0, 0), a2, voffA);
;             PG8_WAIT_V(8); PG8_WAIT_L(0); PG8_BAR; PG8_MMA(1, 0, At, B0); PG8_MMA(1, 1, At, B1); PG8_BAR; PG8_SCHED;
.LBB0_508:
	ds_read_b128 v[128:131], v189
	ds_read_b128 v[132:135], v189 offset:1024
	ds_read_b128 v[136:139], v189 offset:2048
	ds_read_b128 v[140:143], v189 offset:3072
	ds_read_b128 v[144:147], v190
	ds_read_b128 v[148:151], v190 offset:1024
	ds_read_b128 v[168:171], v190 offset:2048
	ds_read_b128 v[172:175], v190 offset:3072
	s_add_u32 s46, s44, 0xfffc0080
	s_addc_u32 s47, s45, -1
	s_cmp_eq_u32 s43, 12
	s_cselect_b32 s49, s10, s47
	s_cselect_b32 s48, s27, s46
	s_cselect_b32 s47, s25, s42
	s_cselect_b32 s46, s35, s37
	s_add_i32 m0, s74, 0xc000
	ds_read_b128 v[176:179], v191
	ds_read_b128 v[180:183], v191 offset:1024
	ds_read_b128 v[192:195], v191 offset:2048
	ds_read_b128 v[196:199], v191 offset:3072
	ds_read_b128 v[200:203], v191 offset:4096
	ds_read_b128 v[204:207], v191 offset:5120
	ds_read_b128 v[208:211], v191 offset:6144
	ds_read_b128 v[212:215], v191 offset:7168
	global_load_lds_dwordx4 v160, s[44:45]
	s_add_i32 m0, s74, 0xe000
	s_nop 0
	global_load_lds_dwordx4 v162, s[44:45]
	s_waitcnt vmcnt(8)
	s_waitcnt lgkmcnt(0)
	s_barrier
	s_setprio 1
	s_waitcnt lgkmcnt(0)
	v_mfma_f32_16x16x32_bf16 v[124:127], v[128:131], v[176:179], v[124:127]
	v_mfma_f32_16x16x32_bf16 v[120:123], v[136:139], v[176:179], v[120:123]
	v_mfma_f32_16x16x32_bf16 v[108:111], v[128:131], v[192:195], v[108:111]
	v_mfma_f32_16x16x32_bf16 v[104:107], v[136:139], v[192:195], v[104:107]
	v_mfma_f32_16x16x32_bf16 v[92:95], v[128:131], v[200:203], v[92:95]
	v_mfma_f32_16x16x32_bf16 v[88:91], v[136:139], v[200:203], v[88:91]
	v_mfma_f32_16x16x32_bf16 v[76:79], v[128:131], v[208:211], v[76:79]
	v_mfma_f32_16x16x32_bf16 v[72:75], v[136:139], v[208:211], v[72:75]
	v_mfma_f32_16x16x32_bf16 v[124:127], v[132:135], v[180:183], v[124:127]
	v_mfma_f32_16x16x32_bf16 v[120:123], v[140:143], v[180:183], v[120:123]
	v_mfma_f32_16x16x32_bf16 v[108:111], v[132:135], v[196:199], v[108:111]
	v_mfma_f32_16x16x32_bf16 v[104:107], v[140:143], v[196:199], v[104:107]
	v_mfma_f32_16x16x32_bf16 v[92:95], v[132:135], v[204:207], v[92:95]
	v_mfma_f32_16x16x32_bf16 v[88:91], v[140:143], v[204:207], v[88:91]
	v_mfma_f32_16x16x32_bf16 v[76:79], v[132:135], v[212:215], v[76:79]
	v_mfma_f32_16x16x32_bf16 v[72:75], v[140:143], v[212:215], v[72:75]
	s_setprio 0
	s_setprio 1
	v_mfma_f32_16x16x32_bf16 v[116:119], v[144:147], v[176:179], v[116:119]
	v_mfma_f32_16x16x32_bf16 v[112:115], v[168:171], v[176:179], v[112:115]
	v_mfma_f32_16x16x32_bf16 v[100:103], v[144:147], v[192:195], v[100:103]
	v_mfma_f32_16x16x32_bf16 v[96:99], v[168:171], v[192:195], v[96:99]
	v_mfma_f32_16x16x32_bf16 v[84:87], v[144:147], v[200:203], v[84:87]
	v_mfma_f32_16x16x32_bf16 v[80:83], v[168:171], v[200:203], v[80:83]
	v_mfma_f32_16x16x32_bf16 v[68:71], v[144:147], v[208:211], v[68:71]
	v_mfma_f32_16x16x32_bf16 v[64:67], v[168:171], v[208:211], v[64:67]
	v_mfma_f32_16x16x32_bf16 v[116:119], v[148:151], v[180:183], v[116:119]
	v_mfma_f32_16x16x32_bf16 v[112:115], v[172:175], v[180:183], v[112:115]
	v_mfma_f32_16x16x32_bf16 v[100:103], v[148:151], v[196:199], v[100:103]
	v_mfma_f32_16x16x32_bf16 v[96:99], v[172:175], v[196:199], v[96:99]
	v_mfma_f32_16x16x32_bf16 v[84:87], v[148:151], v[204:207], v[84:87]
	v_mfma_f32_16x16x32_bf16 v[80:83], v[172:175], v[204:207], v[80:83]
	v_mfma_f32_16x16x32_bf16 v[68:71], v[148:151], v[212:215], v[68:71]
	v_mfma_f32_16x16x32_bf16 v[64:67], v[172:175], v[212:215], v[64:67]
	s_setprio 0
	s_barrier
	s_add_i32 s63, s60, s68
	v_lshl_add_u64 v[184:185], s[46:47], 0, v[154:155]
	s_mov_b32 m0, s63
	ds_read_b128 v[176:179], v191 offset:16384
	ds_read_b128 v[180:183], v191 offset:17408
	ds_read_b128 v[192:195], v191 offset:18432
	ds_read_b128 v[196:199], v191 offset:19456
	ds_read_b128 v[200:203], v191 offset:20480
	ds_read_b128 v[204:207], v191 offset:21504
	ds_read_b128 v[208:211], v191 offset:22528
	ds_read_b128 v[212:215], v191 offset:23552
	global_load_lds_dwordx4 v[184:185], off
	s_add_i32 m0, s63, 0x2000
	s_add_u32 s64, s46, 0x40000
	v_lshl_add_u64 v[216:217], s[46:47], 0, v[158:159]
	s_addc_u32 s65, s47, 0
	s_add_i32 s63, s61, s68
	global_load_lds_dwordx4 v[216:217], off
	s_mov_b32 m0, s63
	v_lshl_add_u64 v[220:221], s[48:49], 0, v[156:157]
	global_load_lds_dwordx4 v154, s[64:65]
	s_add_i32 m0, s63, 0x2000
	s_nop 0
	global_load_lds_dwordx4 v158, s[64:65]
	v_lshl_add_u64 v[218:219], s[48:49], 0, v[152:153]
	s_mov_b32 m0, s74
	s_nop 0
	global_load_lds_dwordx4 v[218:219], off
	s_mov_b32 m0, s51
	s_nop 0
	global_load_lds_dwordx4 v[220:221], off
	s_waitcnt vmcnt(8)
	s_waitcnt lgkmcnt(0)
	s_barrier
; #define PG8_STAGE(bufoff, gbase, voff) do { _Pragma("unroll") for (int _i = 0; _i < 2; ++_i) \
;         __builtin_amdgcn_global_load_lds((const unsigned*)((const char*)(gbase) + (voff)[_i]), (PG8_LAS unsigned*)(lds + (bufoff) + ldsw + _i * 8192), 16, 0, 0); } while (0)
; #define PG8_LDA(dst, b, h) do { _Pragma("unroll") for (int m = 0; m < 4; ++m) _Pragma("unroll") for (int k = 0; k < 2; ++k) dst[m][k] = *(const PG8_LAS bf16x8*)(lds + PG8_SA(b, h) + aoff + m * 2048 + k * 1024); } while (0)
; #define PG8_LDB(dst, b, h) do { _Pragma("unroll") for (int n = 0; n < 2; ++n) _Pragma("unroll") for (int k = 0; k < 2; ++k) dst[n][k] = *(const PG8_LAS bf16x8*)(lds + PG8_SB(b, h) + boff + n * 2048 + k * 1024); } while (0)
; #define PG8_MMA(ai, bj, At, Bt) do { __builtin_amdgcn_s_setprio(1); _Pragma("unroll") for (int m = 0; m < 4; ++m) _Pragma("unroll") for (int n = 0; n < 2; ++n) _Pragma("unroll") for (int k = 0; k < 2; ++k) \
;         acc[ai][bj][m][n] = mma16<F16>(Bt[n][k], At[m][k], acc[ai][bj][m][n]); __builtin_amdgcn_s_setprio(0); } while (0)
; #define PG8_WAIT_V(n) asm volatile("s_waitcnt vmcnt(" #n ")" ::: "memory")
; #define PG8_WAIT_L(n) asm volatile("s_waitcnt lgkmcnt(" #n ")" ::: "memory")
; #define PG8_BAR __builtin_amdgcn_s_barrier()
; #define PG8_SCHED __builtin_amdgcn_sched_barrier(0)
; template <class Epi, class Sched, bool ALIGN_EPI = false, bool SP2 = false, bool F16 = false>
; __device__ __forceinline__ void gemm_phase(PG8_LAS unsigned char* lds, const Gemm g, const Sched& S, const Epi& E, const int wid_in) {
;     ...
;             PG8_LDA(At, 0, 1); PG8_STAGE(PG8_SB(0, 0), b2, voffB); PG8_STAGE(PG8_SB(0, 1), b2 + hstep, voffB); PG8_STAGE(PG8_SA(0, 0), a2, voffA);
;             PG8_WAIT_V(8); PG8_WAIT_L(0); PG8_BAR; PG8_MMA(1, 0, At, B0); PG8_MMA(1, 1, At, B1); PG8_BAR; PG8_SCHED;
;             PG8_LDB(B0, 1, 0); PG8_LDB(B1, 1, 1); PG8_SCHED; PG8_LDA(At, 1, 0); PG8_STAGE(PG8_SA(0, 1), a2 + hstep, voffA);
;             PG8_WAIT_V(8); PG8_WAIT_L(0); PG8_BAR; PG8_MMA(0, 0, At, B0); PG8_MMA(0, 1, At, B1); PG8_BAR; PG8_SCHED;
;             PG8_LDA(At, 1, 1); PG8_STAGE(PG8_SB(1, 0), b3, voffB); PG8_STAGE(PG8_SB(1, 1), b3 + hstep, voffB); PG8_STAGE(PG8_SA(1, 0), a3, voffA);
	s_setprio 1
	s_waitcnt lgkmcnt(0)
	v_mfma_f32_16x16x32_bf16 v[60:63], v[128:131], v[176:179], v[60:63]
	v_mfma_f32_16x16x32_bf16 v[56:59], v[136:139], v[176:179], v[56:59]
	v_mfma_f32_16x16x32_bf16 v[44:47], v[128:131], v[192:195], v[44:47]
	v_mfma_f32_16x16x32_bf16 v[40:43], v[136:139], v[192:195], v[40:43]
	v_mfma_f32_16x16x32_bf16 v[28:31], v[128:131], v[200:203], v[28:31]
	v_mfma_f32_16x16x32_bf16 v[24:27], v[136:139], v[200:203], v[24:27]
	v_mfma_f32_16x16x32_bf16 v[12:15], v[128:131], v[208:211], v[12:15]
	v_mfma_f32_16x16x32_bf16 v[8:11], v[136:139], v[208:211], v[8:11]
	v_mfma_f32_16x16x32_bf16 v[60:63], v[132:135], v[180:183], v[60:63]
	v_mfma_f32_16x16x32_bf16 v[56:59], v[140:143], v[180:183], v[56:59]
	v_mfma_f32_16x16x32_bf16 v[44:47], v[132:135], v[196:199], v[44:47]
	v_mfma_f32_16x16x32_bf16 v[40:43], v[140:143], v[196:199], v[40:43]
	v_mfma_f32_16x16x32_bf16 v[28:31], v[132:135], v[204:207], v[28:31]
	v_mfma_f32_16x16x32_bf16 v[24:27], v[140:143], v[204:207], v[24:27]
	v_mfma_f32_16x16x32_bf16 v[12:15], v[132:135], v[212:215], v[12:15]
	v_mfma_f32_16x16x32_bf16 v[8:11], v[140:143], v[212:215], v[8:11]
	s_setprio 0
	s_setprio 1
	v_mfma_f32_16x16x32_bf16 v[52:55], v[144:147], v[176:179], v[52:55]
	v_mfma_f32_16x16x32_bf16 v[48:51], v[168:171], v[176:179], v[48:51]
	v_mfma_f32_16x16x32_bf16 v[36:39], v[144:147], v[192:195], v[36:39]
	v_mfma_f32_16x16x32_bf16 v[32:35], v[168:171], v[192:195], v[32:35]
	v_mfma_f32_16x16x32_bf16 v[20:23], v[144:147], v[200:203], v[20:23]
	v_mfma_f32_16x16x32_bf16 v[16:19], v[168:171], v[200:203], v[16:19]
	v_mfma_f32_16x16x32_bf16 v[4:7], v[144:147], v[208:211], v[4:7]
	v_mfma_f32_16x16x32_bf16 v[0:3], v[168:171], v[208:211], v[0:3]
	v_mfma_f32_16x16x32_bf16 v[52:55], v[148:151], v[180:183], v[52:55]
	v_mfma_f32_16x16x32_bf16 v[48:51], v[172:175], v[180:183], v[48:51]
	v_mfma_f32_16x16x32_bf16 v[36:39], v[148:151], v[196:199], v[36:39]
	v_mfma_f32_16x16x32_bf16 v[32:35], v[172:175], v[196:199], v[32:35]
	v_mfma_f32_16x16x32_bf16 v[20:23], v[148:151], v[204:207], v[20:23]
	v_mfma_f32_16x16x32_bf16 v[16:19], v[172:175], v[204:207], v[16:19]
	v_mfma_f32_16x16x32_bf16 v[4:7], v[148:151], v[212:215], v[4:7]
	v_mfma_f32_16x16x32_bf16 v[0:3], v[172:175], v[212:215], v[0:3]
	s_setprio 0
	s_barrier
	s_add_i32 s63, 0, 0x18000
	s_add_i32 s64, 0, 0x1c000
	v_add_u32_e32 v140, s63, v188
	v_add_u32_e32 v172, s64, v188
	ds_read_b128 v[128:131], v140
	ds_read_b128 v[132:135], v140 offset:1024
	ds_read_b128 v[136:139], v140 offset:2048
	ds_read_b128 v[140:143], v140 offset:3072
	ds_read_b128 v[144:147], v172
	ds_read_b128 v[148:151], v172 offset:1024
	ds_read_b128 v[168:171], v172 offset:2048
	ds_read_b128 v[172:175], v172 offset:3072
	s_add_u32 s48, s48, 0x40000
	s_addc_u32 s49, s49, 0
	s_mov_b32 m0, s52
	ds_read_b128 v[176:179], v191 offset:32768
	ds_read_b128 v[180:183], v191 offset:33792
	ds_read_b128 v[192:195], v191 offset:34816
	ds_read_b128 v[196:199], v191 offset:35840
	ds_read_b128 v[200:203], v191 offset:36864
	ds_read_b128 v[204:207], v191 offset:37888
	ds_read_b128 v[208:211], v191 offset:38912
	ds_read_b128 v[212:215], v191 offset:39936
	global_load_lds_dwordx4 v152, s[48:49]
	v_lshl_add_u64 v[222:223], s[48:49], 0, v[156:157]
	s_mov_b32 m0, s53
	s_nop 0
	global_load_lds_dwordx4 v[222:223], off
	s_waitcnt vmcnt(8)
	s_waitcnt lgkmcnt(0)
	s_barrier
	s_setprio 1
	s_waitcnt lgkmcnt(0)
	v_mfma_f32_16x16x32_bf16 v[124:127], v[128:131], v[176:179], v[124:127]
	v_mfma_f32_16x16x32_bf16 v[120:123], v[136:139], v[176:179], v[120:123]
	v_mfma_f32_16x16x32_bf16 v[108:111], v[128:131], v[192:195], v[108:111]
	v_mfma_f32_16x16x32_bf16 v[104:107], v[136:139], v[192:195], v[104:107]
	v_mfma_f32_16x16x32_bf16 v[92:95], v[128:131], v[200:203], v[92:95]
	v_mfma_f32_16x16x32_bf16 v[88:91], v[136:139], v[200:203], v[88:91]
	v_mfma_f32_16x16x32_bf16 v[76:79], v[128:131], v[208:211], v[76:79]
	v_mfma_f32_16x16x32_bf16 v[72:75], v[136:139], v[208:211], v[72:75]
	v_mfma_f32_16x16x32_bf16 v[124:127], v[132:135], v[180:183], v[124:127]
	v_mfma_f32_16x16x32_bf16 v[120:123], v[140:143], v[180:183], v[120:123]
	v_mfma_f32_16x16x32_bf16 v[108:111], v[132:135], v[196:199], v[108:111]
	v_mfma_f32_16x16x32_bf16 v[104:107], v[140:143], v[196:199], v[104:107]
	v_mfma_f32_16x16x32_bf16 v[92:95], v[132:135], v[204:207], v[92:95]
	v_mfma_f32_16x16x32_bf16 v[88:91], v[140:143], v[204:207], v[88:91]
	v_mfma_f32_16x16x32_bf16 v[76:79], v[132:135], v[212:215], v[76:79]
	v_mfma_f32_16x16x32_bf16 v[72:75], v[140:143], v[212:215], v[72:75]
	s_setprio 0
	s_setprio 1
	v_mfma_f32_16x16x32_bf16 v[116:119], v[144:147], v[176:179], v[116:119]
	v_mfma_f32_16x16x32_bf16 v[112:115], v[168:171], v[176:179], v[112:115]
	v_mfma_f32_16x16x32_bf16 v[100:103], v[144:147], v[192:195], v[100:103]
	v_mfma_f32_16x16x32_bf16 v[96:99], v[168:171], v[192:195], v[96:99]
	v_mfma_f32_16x16x32_bf16 v[84:87], v[144:147], v[200:203], v[84:87]
	v_mfma_f32_16x16x32_bf16 v[80:83], v[168:171], v[200:203], v[80:83]
	v_mfma_f32_16x16x32_bf16 v[68:71], v[144:147], v[208:211], v[68:71]
	v_mfma_f32_16x16x32_bf16 v[64:67], v[168:171], v[208:211], v[64:67]
	v_mfma_f32_16x16x32_bf16 v[116:119], v[148:151], v[180:183], v[116:119]
	v_mfma_f32_16x16x32_bf16 v[112:115], v[172:175], v[180:183], v[112:115]
	v_mfma_f32_16x16x32_bf16 v[100:103], v[148:151], v[196:199], v[100:103]
	v_mfma_f32_16x16x32_bf16 v[96:99], v[172:175], v[196:199], v[96:99]
	v_mfma_f32_16x16x32_bf16 v[84:87], v[148:151], v[204:207], v[84:87]
	v_mfma_f32_16x16x32_bf16 v[80:83], v[172:175], v[204:207], v[80:83]
	v_mfma_f32_16x16x32_bf16 v[68:71], v[148:151], v[212:215], v[68:71]
	v_mfma_f32_16x16x32_bf16 v[64:67], v[172:175], v[212:215], v[64:67]
	s_setprio 0
	s_barrier
; #define PG8_STAGE(bufoff, gbase, voff) do { _Pragma("unroll") for (int _i = 0; _i < 2; ++_i) \
;         __builtin_amdgcn_global_load_lds((const unsigned*)((const char*)(gbase) + (voff)[_i]), (PG8_LAS unsigned*)(lds + (bufoff) + ldsw + _i * 8192), 16, 0, 0); } while (0)
; #define PG8_LDA(dst, b, h) do { _Pragma("unroll") for (int m = 0; m < 4; ++m) _Pragma("unroll") for (int k = 0; k < 2; ++k) dst[m][k] = *(const PG8_LAS bf16x8*)(lds + PG8_SA(b, h) + aoff + m * 2048 + k * 1024); } while (0)
; #define PG8_MMA(ai, bj, At, Bt) do { __builtin_amdgcn_s_setprio(1); _Pragma("unroll") for (int m = 0; m < 4; ++m) _Pragma("unroll") for (int n = 0; n < 2; ++n) _Pragma("unroll") for (int k = 0; k < 2; ++k) \
;         acc[ai][bj][m][n] = mma16<F16>(Bt[n][k], At[m][k], acc[ai][bj][m][n]); __builtin_amdgcn_s_setprio(0); } while (0)
; #define PG8_WAIT_V(n) asm volatile("s_waitcnt vmcnt(" #n ")" ::: "memory")
; #define PG8_WAIT_L(n) asm volatile("s_waitcnt lgkmcnt(" #n ")" ::: "memory")
; #define PG8_BAR __builtin_amdgcn_s_barrier()
; #define PG8_SCHED __builtin_amdgcn_sched_barrier(0)
; template <class Epi, class Sched, bool ALIGN_EPI = false, bool SP2 = false, bool F16 = false>
; __device__ __forceinline__ void gemm_phase(PG8_LAS unsigned char* lds, const Gemm g, const Sched& S, const Epi& E, const int wid_in) {
;     ...
;             PG8_LDA(At, 1, 1); PG8_STAGE(PG8_SB(1, 0), b3, voffB); PG8_STAGE(PG8_SB(1, 1), b3 + hstep, voffB); PG8_STAGE(PG8_SA(1, 0), a3, voffA);
;             PG8_WAIT_V(8); PG8_WAIT_L(0); PG8_BAR; PG8_MMA(1, 0, At, B0); PG8_MMA(1, 1, At, B1); PG8_BAR; PG8_SCHED;
	s_add_i32 s48, s63, s68
	v_lshl_add_u64 v[184:185], v[184:185], 0, s[22:23]
	s_mov_b32 m0, s48
	ds_read_b128 v[176:179], v191 offset:49152
	ds_read_b128 v[180:183], v191 offset:50176
	ds_read_b128 v[192:195], v191 offset:51200
	ds_read_b128 v[196:199], v191 offset:52224
	ds_read_b128 v[200:203], v191 offset:53248
	ds_read_b128 v[204:207], v191 offset:54272
	ds_read_b128 v[208:211], v191 offset:55296
	ds_read_b128 v[212:215], v191 offset:56320
	global_load_lds_dwordx4 v[184:185], off
	s_add_i32 m0, s48, 0x2000
	s_add_u32 s46, s46, 0x40080
	v_lshl_add_u64 v[184:185], v[216:217], 0, s[22:23]
	s_addc_u32 s47, s47, 0
	s_add_i32 s48, s64, s68
	global_load_lds_dwordx4 v[184:185], off
	s_mov_b32 m0, s48
	s_nop 0
	global_load_lds_dwordx4 v154, s[46:47]
	s_add_i32 m0, s48, 0x2000
	s_nop 0
	global_load_lds_dwordx4 v158, s[46:47]
	v_lshl_add_u64 v[184:185], v[218:219], 0, s[22:23]
	s_mov_b32 m0, s75
	s_nop 0
	global_load_lds_dwordx4 v[184:185], off
	v_lshl_add_u64 v[184:185], v[220:221], 0, s[22:23]
	s_mov_b32 m0, s54
	s_nop 0
	global_load_lds_dwordx4 v[184:185], off
	s_waitcnt vmcnt(8)
	s_waitcnt lgkmcnt(0)
	s_barrier
	s_setprio 1
	s_waitcnt lgkmcnt(0)
	v_mfma_f32_16x16x32_bf16 v[60:63], v[128:131], v[176:179], v[60:63]
	v_mfma_f32_16x16x32_bf16 v[56:59], v[136:139], v[176:179], v[56:59]
	v_mfma_f32_16x16x32_bf16 v[44:47], v[128:131], v[192:195], v[44:47]
	v_mfma_f32_16x16x32_bf16 v[40:43], v[136:139], v[192:195], v[40:43]
	v_mfma_f32_16x16x32_bf16 v[28:31], v[128:131], v[200:203], v[28:31]
	v_mfma_f32_16x16x32_bf16 v[24:27], v[136:139], v[200:203], v[24:27]
	v_mfma_f32_16x16x32_bf16 v[12:15], v[128:131], v[208:211], v[12:15]
	v_mfma_f32_16x16x32_bf16 v[8:11], v[136:139], v[208:211], v[8:11]
	v_mfma_f32_16x16x32_bf16 v[60:63], v[132:135], v[180:183], v[60:63]
	v_mfma_f32_16x16x32_bf16 v[56:59], v[140:143], v[180:183], v[56:59]
	v_mfma_f32_16x16x32_bf16 v[44:47], v[132:135], v[196:199], v[44:47]
	v_mfma_f32_16x16x32_bf16 v[40:43], v[140:143], v[196:199], v[40:43]
	v_mfma_f32_16x16x32_bf16 v[28:31], v[132:135], v[204:207], v[28:31]
	v_mfma_f32_16x16x32_bf16 v[24:27], v[140:143], v[204:207], v[24:27]
	v_mfma_f32_16x16x32_bf16 v[12:15], v[132:135], v[212:215], v[12:15]
	v_mfma_f32_16x16x32_bf16 v[8:11], v[140:143], v[212:215], v[8:11]
	s_setprio 0
	s_setprio 1
	v_mfma_f32_16x16x32_bf16 v[52:55], v[144:147], v[176:179], v[52:55]
	v_mfma_f32_16x16x32_bf16 v[48:51], v[168:171], v[176:179], v[48:51]
	v_mfma_f32_16x16x32_bf16 v[36:39], v[144:147], v[192:195], v[36:39]
	v_mfma_f32_16x16x32_bf16 v[32:35], v[168:171], v[192:195], v[32:35]
	v_mfma_f32_16x16x32_bf16 v[20:23], v[144:147], v[200:203], v[20:23]
	v_mfma_f32_16x16x32_bf16 v[16:19], v[168:171], v[200:203], v[16:19]
	v_mfma_f32_16x16x32_bf16 v[4:7], v[144:147], v[208:211], v[4:7]
	v_mfma_f32_16x16x32_bf16 v[0:3], v[168:171], v[208:211], v[0:3]
	v_mfma_f32_16x16x32_bf16 v[52:55], v[148:151], v[180:183], v[52:55]
	v_mfma_f32_16x16x32_bf16 v[48:51], v[172:175], v[180:183], v[48:51]
	v_mfma_f32_16x16x32_bf16 v[36:39], v[148:151], v[196:199], v[36:39]
	v_mfma_f32_16x16x32_bf16 v[32:35], v[172:175], v[196:199], v[32:35]
	v_mfma_f32_16x16x32_bf16 v[20:23], v[148:151], v[204:207], v[20:23]
	v_mfma_f32_16x16x32_bf16 v[16:19], v[172:175], v[204:207], v[16:19]
	v_mfma_f32_16x16x32_bf16 v[4:7], v[148:151], v[212:215], v[4:7]
	v_mfma_f32_16x16x32_bf16 v[0:3], v[172:175], v[212:215], v[0:3]
	s_setprio 0
	s_barrier
	s_add_i32 s43, s43, 2
	s_add_u32 s44, s44, 0x100
	s_addc_u32 s45, s45, 0
	s_add_u32 s37, s37, 0x100
	s_addc_u32 s42, s42, 0
	s_cmp_gt_u32 s43, 13
	s_cbranch_scc0 .LBB0_508
	s_and_b64 vcc, exec, s[16:17]
	s_cbranch_vccz .LBB0_511
	s_barrier

; #define PG8_STAGE(bufoff, gbase, voff) do { _Pragma("unroll") for (int _i = 0; _i < 2; ++_i) \
;         __builtin_amdgcn_global_load_lds((const unsigned*)((const char*)(gbase) + (voff)[_i]), (PG8_LAS unsigned*)(lds + (bufoff) + ldsw + _i * 8192), 16, 0, 0); } while (0)
; #define PG8_WAIT_V(n) asm volatile("s_waitcnt vmcnt(" #n ")" ::: "memory")
; #define PG8_BAR __builtin_amdgcn_s_barrier()
; template <class Epi, class Sched, bool ALIGN_EPI = false, bool SP2 = false, bool F16 = false>
; __device__ __forceinline__ void gemm_phase(PG8_LAS unsigned char* lds, const Gemm g, const Sched& S, const Epi& E, const int wid_in) {
;     ...
;     const int wid = wid_in, lane = lane_, tid = wid * 64 + lane, wr = wid >> 2, wc = wid & 3, fr = lane & 15, fq = lane >> 4;
;     const int K = g.K, nt = K / BK;
;     unsigned voffA[2], voffB[2];
; #pragma unroll
;     for (int i = 0; i < 2; ++i) { int R, C; stage_rc(tid * 16 + i * 8192, R, C); const int Rb = Epi::PERM ? ((R & ~31) + perm32(R & 31)) : R;
;         voffA[i] = (unsigned)(R * K + C) * 2u; voffB[i] = (unsigned)(Rb * K + C) * 2u; }
;     const size_t kstep = (size_t)(BK * 2);
;     const size_t hstep = (size_t)HALF * K * 2;
;     const size_t tstep = 2 * hstep;
;     const unsigned ldsw = (unsigned)wid * 1024u;
;     const int aoff = lds_byte(wr * 64 + fr, fq * 8), boff = lds_byte(wc * 32 + fr, fq * 8);
;     ...
;         PG8_STAGE(PG8_SB(1, 0), cB + kstep, voffB); PG8_STAGE(PG8_SA(1, 0), cA + kstep, voffA); PG8_STAGE(PG8_SB(1, 1), cB + hstep + kstep, voffB);
;         PG8_WAIT_V(6); PG8_BAR;
.LBB0_579:
	s_add_u32 s10, s14, 0x15500000
	s_addc_u32 s11, s15, 0
	s_add_u32 s12, s14, 0x9400000
	s_mov_b64 s[18:19], 0x80
	s_addc_u32 s13, s15, 0
	s_add_i32 m0, s74, 0x18000
	v_lshl_add_u64 v[6:7], v[6:7], 0, s[18:19]
	s_waitcnt vmcnt(2)
	s_barrier
	global_load_lds_dwordx4 v[6:7], off
	v_lshl_add_u64 v[4:5], v[4:5], 0, s[18:19]
	s_add_i32 m0, s74, 0x1a000
	s_add_i32 s53, s74, 0xa000
	global_load_lds_dwordx4 v[4:5], off
	v_lshl_add_u64 v[0:1], v[0:1], 0, s[18:19]
	s_mov_b32 m0, s75
	s_add_u32 s8, s36, 0x40080
	global_load_lds_dwordx4 v[0:1], off
	v_lshl_add_u64 v[0:1], v[2:3], 0, s[18:19]
	s_mov_b32 m0, s53
	s_addc_u32 s9, s37, 0
	global_load_lds_dwordx4 v[0:1], off
	s_add_i32 m0, s74, 0x1c000
	s_nop 0
	global_load_lds_dwordx4 v162, s[8:9]
	s_add_i32 m0, s74, 0x1e000
	v_and_b32_e32 v190, 15, v8
	global_load_lds_dwordx4 v166, s[8:9]
	v_or_b32_e32 v0, s70, v190
	v_lshlrev_b32_e32 v1, 6, v0
	v_and_b32_e32 v2, 48, v8
	s_movk_i32 s8, 0x3c0
	v_and_b32_e32 v3, 0xfffffc00, v12
	v_lshlrev_b32_e32 v0, 2, v0
	v_and_or_b32 v1, v1, s8, v2
	v_add_u32_e32 v4, s73, v3
	v_and_b32_e32 v0, 32, v0
	v_bitop3_b32 v0, v1, v4, v0 bitop3:0xde
	v_lshl_or_b32 v1, v190, 6, v2
	v_add_u32_e32 v2, s72, v3
	v_lshlrev_b32_e32 v3, 2, v8
	v_and_b32_e32 v3, 32, v3
	v_bitop3_b32 v192, v1, v2, v3 bitop3:0xde
	v_lshlrev_b32_e32 v1, 14, v9
	v_and_b32_e32 v1, 0xffff8000, v1
	v_lshl_add_u32 v1, v10, 11, v1
	v_and_b32_e32 v2, 1, v9
	v_lshl_or_b32 v1, v2, 6, v1
	v_lshl_add_u32 v168, v11, 1, v1
	v_lshlrev_b32_e32 v1, 14, v13
	v_and_b32_e32 v1, 0xffff8000, v1
	s_waitcnt vmcnt(6)
	s_mul_i32 s8, s3, 0x210
	v_lshl_add_u32 v1, v14, 11, v1
	v_and_b32_e32 v2, 1, v13
	s_add_i32 s59, s8, 0
	v_lshl_or_b32 v1, v2, 6, v1
	s_add_i32 s61, 0, 0x10000
	s_add_i32 s62, 0, 0x14000
	v_ashrrev_i32_e32 v191, 4, v8
	s_ashr_i32 s54, s38, 31
	s_mov_b32 s55, s38
	s_ashr_i32 s58, s40, 31
	s_add_i32 s59, s59, 0x20400
	v_mov_b32_e32 v169, v163
	v_lshl_add_u32 v170, v15, 1, v1
	v_mov_b32_e32 v171, v163
	v_mov_b64_e32 v[172:173], 0x580
	v_mov_b64_e32 v[174:175], 0x57f
	s_movk_i32 s60, 0xb1
	v_add_u32_e32 v193, s61, v192
	v_add_u32_e32 v194, s62, v192
	v_add_u32_e32 v195, 0, v0
	v_mov_b32_e32 v196, 0x358637bd
	s_movk_i32 s63, 0x1600
	s_barrier
	s_branch .LBB0_582

; #define PG8_STAGE(bufoff, gbase, voff) do { _Pragma("unroll") for (int _i = 0; _i < 2; ++_i) \
;         __builtin_amdgcn_global_load_lds((const unsigned*)((const char*)(gbase) + (voff)[_i]), (PG8_LAS unsigned*)(lds + (bufoff) + ldsw + _i * 8192), 16, 0, 0); } while (0)
; #define PG8_LDA(dst, b, h) do { _Pragma("unroll") for (int m = 0; m < 4; ++m) _Pragma("unroll") for (int k = 0; k < 2; ++k) dst[m][k] = *(const PG8_LAS bf16x8*)(lds + PG8_SA(b, h) + aoff + m * 2048 + k * 1024); } while (0)
; #define PG8_LDB(dst, b, h) do { _Pragma("unroll") for (int n = 0; n < 2; ++n) _Pragma("unroll") for (int k = 0; k < 2; ++k) dst[n][k] = *(const PG8_LAS bf16x8*)(lds + PG8_SB(b, h) + boff + n * 2048 + k * 1024); } while (0)
; #define PG8_MMA(ai, bj, At, Bt) do { __builtin_amdgcn_s_setprio(1); _Pragma("unroll") for (int m = 0; m < 4; ++m) _Pragma("unroll") for (int n = 0; n < 2; ++n) _Pragma("unroll") for (int k = 0; k < 2; ++k) \
;         acc[ai][bj][m][n] = mma16<F16>(Bt[n][k], At[m][k], acc[ai][bj][m][n]); __builtin_amdgcn_s_setprio(0); } while (0)
; #define PG8_WAIT_V(n) asm volatile("s_waitcnt vmcnt(" #n ")" ::: "memory")
; #define PG8_WAIT_L(n) asm volatile("s_waitcnt lgkmcnt(" #n ")" ::: "memory")
; #define PG8_BAR __builtin_amdgcn_s_barrier()
; #define PG8_SCHED __builtin_amdgcn_sched_barrier(0)
; template <class Epi, class Sched, bool ALIGN_EPI = false, bool SP2 = false, bool F16 = false>
; __device__ __forceinline__ void gemm_phase(PG8_LAS unsigned char* lds, const Gemm g, const Sched& S, const Epi& E, const int wid_in) {
;     ...
;             PG8_LDB(B0, 0, 0); PG8_LDB(B1, 0, 1); PG8_SCHED; PG8_LDA(At, 0, 0); PG8_STAGE(PG8_SA(1, 1), a1 + hstep, voffA);
;             PG8_WAIT_V(8); PG8_WAIT_L(0); PG8_BAR; PG8_MMA(0, 0, At, B0); PG8_MMA(0, 1, At, B1); PG8_BAR; PG8_SCHED;
;             PG8_LDA(At, 0, 1); PG8_STAGE(PG8_SB(0, 0), b2, voffB); PG8_STAGE(PG8_SB(0, 1), b2 + hstep, voffB); PG8_STAGE(PG8_SA(0, 0), a2, voffA);
;             PG8_WAIT_V(8); PG8_WAIT_L(0); PG8_BAR; PG8_MMA(1, 0, At, B0); PG8_MMA(1, 1, At, B1); PG8_BAR; PG8_SCHED;
.LBB0_585:
	ds_read_b128 v[0:3], v193
	ds_read_b128 v[4:7], v193 offset:1024
	ds_read_b128 v[136:139], v193 offset:2048
	ds_read_b128 v[140:143], v193 offset:3072
	ds_read_b128 v[144:147], v194
	ds_read_b128 v[148:151], v194 offset:1024
	ds_read_b128 v[152:155], v194 offset:2048
	ds_read_b128 v[156:159], v194 offset:3072
	s_add_u32 s36, s34, 0xfffc0080
	s_addc_u32 s37, s35, -1
	s_cmp_eq_u32 s65, 12
	s_cselect_b32 s45, s23, s37
	s_cselect_b32 s44, s31, s36
	s_cselect_b32 s37, s21, s64
	s_cselect_b32 s36, s42, s43
	s_add_i32 m0, s74, 0xc000
	ds_read_b128 v[176:179], v195
	ds_read_b128 v[180:183], v195 offset:1024
	ds_read_b128 v[184:187], v195 offset:2048
	ds_read_b128 v[198:201], v195 offset:3072
	ds_read_b128 v[202:205], v195 offset:4096
	ds_read_b128 v[206:209], v195 offset:5120
	ds_read_b128 v[210:213], v195 offset:6144
	ds_read_b128 v[214:217], v195 offset:7168
	global_load_lds_dwordx4 v168, s[34:35]
	s_add_i32 m0, s74, 0xe000
	s_nop 0
	global_load_lds_dwordx4 v170, s[34:35]
	s_waitcnt vmcnt(8)
	s_waitcnt lgkmcnt(0)
	s_barrier
	s_setprio 1
	s_waitcnt lgkmcnt(0)
	v_mfma_f32_16x16x32_f16 v[132:135], v[0:3], v[176:179], v[132:135]
	v_mfma_f32_16x16x32_f16 v[128:131], v[136:139], v[176:179], v[128:131]
	v_mfma_f32_16x16x32_f16 v[116:119], v[0:3], v[184:187], v[116:119]
	v_mfma_f32_16x16x32_f16 v[112:115], v[136:139], v[184:187], v[112:115]
	v_mfma_f32_16x16x32_f16 v[100:103], v[0:3], v[202:205], v[100:103]
	v_mfma_f32_16x16x32_f16 v[96:99], v[136:139], v[202:205], v[96:99]
	v_mfma_f32_16x16x32_f16 v[84:87], v[0:3], v[210:213], v[84:87]
	v_mfma_f32_16x16x32_f16 v[80:83], v[136:139], v[210:213], v[80:83]
	v_mfma_f32_16x16x32_f16 v[132:135], v[4:7], v[180:183], v[132:135]
	v_mfma_f32_16x16x32_f16 v[128:131], v[140:143], v[180:183], v[128:131]
	v_mfma_f32_16x16x32_f16 v[116:119], v[4:7], v[198:201], v[116:119]
	v_mfma_f32_16x16x32_f16 v[112:115], v[140:143], v[198:201], v[112:115]
	v_mfma_f32_16x16x32_f16 v[100:103], v[4:7], v[206:209], v[100:103]
	v_mfma_f32_16x16x32_f16 v[96:99], v[140:143], v[206:209], v[96:99]
	v_mfma_f32_16x16x32_f16 v[84:87], v[4:7], v[214:217], v[84:87]
	v_mfma_f32_16x16x32_f16 v[80:83], v[140:143], v[214:217], v[80:83]
	s_setprio 0
	s_setprio 1
	v_mfma_f32_16x16x32_f16 v[124:127], v[144:147], v[176:179], v[124:127]
	v_mfma_f32_16x16x32_f16 v[120:123], v[152:155], v[176:179], v[120:123]
	v_mfma_f32_16x16x32_f16 v[108:111], v[144:147], v[184:187], v[108:111]
	v_mfma_f32_16x16x32_f16 v[104:107], v[152:155], v[184:187], v[104:107]
	v_mfma_f32_16x16x32_f16 v[92:95], v[144:147], v[202:205], v[92:95]
	v_mfma_f32_16x16x32_f16 v[88:91], v[152:155], v[202:205], v[88:91]
	v_mfma_f32_16x16x32_f16 v[76:79], v[144:147], v[210:213], v[76:79]
	v_mfma_f32_16x16x32_f16 v[72:75], v[152:155], v[210:213], v[72:75]
	v_mfma_f32_16x16x32_f16 v[124:127], v[148:151], v[180:183], v[124:127]
	v_mfma_f32_16x16x32_f16 v[120:123], v[156:159], v[180:183], v[120:123]
	v_mfma_f32_16x16x32_f16 v[108:111], v[148:151], v[198:201], v[108:111]
	v_mfma_f32_16x16x32_f16 v[104:107], v[156:159], v[198:201], v[104:107]
	v_mfma_f32_16x16x32_f16 v[92:95], v[148:151], v[206:209], v[92:95]
	v_mfma_f32_16x16x32_f16 v[88:91], v[156:159], v[206:209], v[88:91]
	v_mfma_f32_16x16x32_f16 v[76:79], v[148:151], v[214:217], v[76:79]
	v_mfma_f32_16x16x32_f16 v[72:75], v[156:159], v[214:217], v[72:75]
	s_setprio 0
	s_barrier
	s_add_i32 s66, s61, s68
	v_lshl_add_u64 v[188:189], s[36:37], 0, v[162:163]
	s_mov_b32 m0, s66
	ds_read_b128 v[176:179], v195 offset:16384
	ds_read_b128 v[180:183], v195 offset:17408
	ds_read_b128 v[184:187], v195 offset:18432
	ds_read_b128 v[198:201], v195 offset:19456
	ds_read_b128 v[202:205], v195 offset:20480
	ds_read_b128 v[206:209], v195 offset:21504
	ds_read_b128 v[210:213], v195 offset:22528
	ds_read_b128 v[214:217], v195 offset:23552
	global_load_lds_dwordx4 v[188:189], off
	s_add_i32 m0, s66, 0x2000
	s_add_u32 s66, s36, 0x40000
	v_lshl_add_u64 v[218:219], s[36:37], 0, v[166:167]
	s_addc_u32 s67, s37, 0
	s_add_i32 s76, s62, s68
	global_load_lds_dwordx4 v[218:219], off
	s_mov_b32 m0, s76
	v_lshl_add_u64 v[222:223], s[44:45], 0, v[164:165]
	global_load_lds_dwordx4 v162, s[66:67]
	s_add_i32 m0, s76, 0x2000
	s_nop 0
	global_load_lds_dwordx4 v166, s[66:67]
	v_lshl_add_u64 v[220:221], s[44:45], 0, v[160:161]
	s_mov_b32 m0, s74
	s_nop 0
	global_load_lds_dwordx4 v[220:221], off
	s_mov_b32 m0, s29
	s_nop 0
	global_load_lds_dwordx4 v[222:223], off
	s_waitcnt vmcnt(8)
	s_waitcnt lgkmcnt(0)
	s_barrier
	s_setprio 1
	s_waitcnt lgkmcnt(0)
	v_mfma_f32_16x16x32_f16 v[68:71], v[0:3], v[176:179], v[68:71]
	v_mfma_f32_16x16x32_f16 v[64:67], v[136:139], v[176:179], v[64:67]
	v_mfma_f32_16x16x32_f16 v[52:55], v[0:3], v[184:187], v[52:55]
	v_mfma_f32_16x16x32_f16 v[48:51], v[136:139], v[184:187], v[48:51]
	v_mfma_f32_16x16x32_f16 v[36:39], v[0:3], v[202:205], v[36:39]
	v_mfma_f32_16x16x32_f16 v[32:35], v[136:139], v[202:205], v[32:35]
	v_mfma_f32_16x16x32_f16 v[0:3], v[0:3], v[210:213], v[20:23]
	v_mfma_f32_16x16x32_f16 v[68:71], v[4:7], v[180:183], v[68:71]
	v_mfma_f32_16x16x32_f16 v[64:67], v[140:143], v[180:183], v[64:67]
	v_mfma_f32_16x16x32_f16 v[52:55], v[4:7], v[198:201], v[52:55]
	v_mfma_f32_16x16x32_f16 v[48:51], v[140:143], v[198:201], v[48:51]
	v_mfma_f32_16x16x32_f16 v[36:39], v[4:7], v[206:209], v[36:39]
	v_mfma_f32_16x16x32_f16 v[32:35], v[140:143], v[206:209], v[32:35]
	v_mfma_f32_16x16x32_f16 v[0:3], v[4:7], v[214:217], v[0:3]
	v_mfma_f32_16x16x32_f16 v[4:7], v[136:139], v[210:213], v[16:19]
	v_mfma_f32_16x16x32_f16 v[4:7], v[140:143], v[214:217], v[4:7]
	s_setprio 0
	s_setprio 1
	v_mfma_f32_16x16x32_f16 v[16:19], v[144:147], v[176:179], v[60:63]
	v_mfma_f32_16x16x32_f16 v[60:63], v[148:151], v[180:183], v[16:19]
	v_mfma_f32_16x16x32_f16 v[16:19], v[152:155], v[176:179], v[56:59]
	v_mfma_f32_16x16x32_f16 v[56:59], v[156:159], v[180:183], v[16:19]
	v_mfma_f32_16x16x32_f16 v[16:19], v[144:147], v[184:187], v[44:47]
	v_mfma_f32_16x16x32_f16 v[44:47], v[148:151], v[198:201], v[16:19]
	v_mfma_f32_16x16x32_f16 v[16:19], v[152:155], v[184:187], v[40:43]
	v_mfma_f32_16x16x32_f16 v[40:43], v[156:159], v[198:201], v[16:19]
	v_mfma_f32_16x16x32_f16 v[16:19], v[144:147], v[202:205], v[28:31]
	v_mfma_f32_16x16x32_f16 v[28:31], v[148:151], v[206:209], v[16:19]
	v_mfma_f32_16x16x32_f16 v[16:19], v[152:155], v[202:205], v[24:27]
	v_mfma_f32_16x16x32_f16 v[12:15], v[144:147], v[210:213], v[12:15]
	v_mfma_f32_16x16x32_f16 v[8:11], v[152:155], v[210:213], v[8:11]
	v_mfma_f32_16x16x32_f16 v[24:27], v[156:159], v[206:209], v[16:19]
	v_mfma_f32_16x16x32_f16 v[12:15], v[148:151], v[214:217], v[12:15]
	v_mfma_f32_16x16x32_f16 v[8:11], v[156:159], v[214:217], v[8:11]
	s_setprio 0
	s_barrier
; #define PG8_STAGE(bufoff, gbase, voff) do { _Pragma("unroll") for (int _i = 0; _i < 2; ++_i) \
;         __builtin_amdgcn_global_load_lds((const unsigned*)((const char*)(gbase) + (voff)[_i]), (PG8_LAS unsigned*)(lds + (bufoff) + ldsw + _i * 8192), 16, 0, 0); } while (0)
; #define PG8_LDA(dst, b, h) do { _Pragma("unroll") for (int m = 0; m < 4; ++m) _Pragma("unroll") for (int k = 0; k < 2; ++k) dst[m][k] = *(const PG8_LAS bf16x8*)(lds + PG8_SA(b, h) + aoff + m * 2048 + k * 1024); } while (0)
; #define PG8_LDB(dst, b, h) do { _Pragma("unroll") for (int n = 0; n < 2; ++n) _Pragma("unroll") for (int k = 0; k < 2; ++k) dst[n][k] = *(const PG8_LAS bf16x8*)(lds + PG8_SB(b, h) + boff + n * 2048 + k * 1024); } while (0)
; #define PG8_MMA(ai, bj, At, Bt) do { __builtin_amdgcn_s_setprio(1); _Pragma("unroll") for (int m = 0; m < 4; ++m) _Pragma("unroll") for (int n = 0; n < 2; ++n) _Pragma("unroll") for (int k = 0; k < 2; ++k) \
;         acc[ai][bj][m][n] = mma16<F16>(Bt[n][k], At[m][k], acc[ai][bj][m][n]); __builtin_amdgcn_s_setprio(0); } while (0)
; #define PG8_WAIT_V(n) asm volatile("s_waitcnt vmcnt(" #n ")" ::: "memory")
; #define PG8_WAIT_L(n) asm volatile("s_waitcnt lgkmcnt(" #n ")" ::: "memory")
; #define PG8_BAR __builtin_amdgcn_s_barrier()
; #define PG8_SCHED __builtin_amdgcn_sched_barrier(0)
; template <class Epi, class Sched, bool ALIGN_EPI = false, bool SP2 = false, bool F16 = false>
; __device__ __forceinline__ void gemm_phase(PG8_LAS unsigned char* lds, const Gemm g, const Sched& S, const Epi& E, const int wid_in) {
;     ...
;             PG8_LDB(B0, 1, 0); PG8_LDB(B1, 1, 1); PG8_SCHED; PG8_LDA(At, 1, 0); PG8_STAGE(PG8_SA(0, 1), a2 + hstep, voffA);
;             PG8_WAIT_V(8); PG8_WAIT_L(0); PG8_BAR; PG8_MMA(0, 0, At, B0); PG8_MMA(0, 1, At, B1); PG8_BAR; PG8_SCHED;
;             PG8_LDA(At, 1, 1); PG8_STAGE(PG8_SB(1, 0), b3, voffB); PG8_STAGE(PG8_SB(1, 1), b3 + hstep, voffB); PG8_STAGE(PG8_SA(1, 0), a3, voffA);
;             PG8_WAIT_V(8); PG8_WAIT_L(0); PG8_BAR; PG8_MMA(1, 0, At, B0); PG8_MMA(1, 1, At, B1); PG8_BAR; PG8_SCHED;
	s_add_i32 s66, 0, 0x18000
	s_add_i32 s67, 0, 0x1c000
	v_add_u32_e32 v140, s66, v192
	v_add_u32_e32 v156, s67, v192
	ds_read_b128 v[16:19], v140
	ds_read_b128 v[20:23], v140 offset:1024
	ds_read_b128 v[136:139], v140 offset:2048
	ds_read_b128 v[140:143], v140 offset:3072
	ds_read_b128 v[144:147], v156
	ds_read_b128 v[148:151], v156 offset:1024
	ds_read_b128 v[152:155], v156 offset:2048
	ds_read_b128 v[156:159], v156 offset:3072
	s_add_u32 s44, s44, 0x40000
	s_addc_u32 s45, s45, 0
	s_mov_b32 m0, s49
	ds_read_b128 v[176:179], v195 offset:32768
	ds_read_b128 v[180:183], v195 offset:33792
	ds_read_b128 v[184:187], v195 offset:34816
	ds_read_b128 v[198:201], v195 offset:35840
	ds_read_b128 v[202:205], v195 offset:36864
	ds_read_b128 v[206:209], v195 offset:37888
	ds_read_b128 v[210:213], v195 offset:38912
	ds_read_b128 v[214:217], v195 offset:39936
	global_load_lds_dwordx4 v160, s[44:45]
	v_lshl_add_u64 v[224:225], s[44:45], 0, v[164:165]
	s_mov_b32 m0, s50
	s_nop 0
	global_load_lds_dwordx4 v[224:225], off
	s_waitcnt vmcnt(8)
	s_waitcnt lgkmcnt(0)
	s_barrier
	s_setprio 1
	s_waitcnt lgkmcnt(0)
	v_mfma_f32_16x16x32_f16 v[132:135], v[16:19], v[176:179], v[132:135]
	v_mfma_f32_16x16x32_f16 v[128:131], v[136:139], v[176:179], v[128:131]
	v_mfma_f32_16x16x32_f16 v[116:119], v[16:19], v[184:187], v[116:119]
	v_mfma_f32_16x16x32_f16 v[112:115], v[136:139], v[184:187], v[112:115]
	v_mfma_f32_16x16x32_f16 v[100:103], v[16:19], v[202:205], v[100:103]
	v_mfma_f32_16x16x32_f16 v[96:99], v[136:139], v[202:205], v[96:99]
	v_mfma_f32_16x16x32_f16 v[84:87], v[16:19], v[210:213], v[84:87]
	v_mfma_f32_16x16x32_f16 v[80:83], v[136:139], v[210:213], v[80:83]
	v_mfma_f32_16x16x32_f16 v[132:135], v[20:23], v[180:183], v[132:135]
	v_mfma_f32_16x16x32_f16 v[128:131], v[140:143], v[180:183], v[128:131]
	v_mfma_f32_16x16x32_f16 v[116:119], v[20:23], v[198:201], v[116:119]
	v_mfma_f32_16x16x32_f16 v[112:115], v[140:143], v[198:201], v[112:115]
	v_mfma_f32_16x16x32_f16 v[100:103], v[20:23], v[206:209], v[100:103]
	v_mfma_f32_16x16x32_f16 v[96:99], v[140:143], v[206:209], v[96:99]
	v_mfma_f32_16x16x32_f16 v[84:87], v[20:23], v[214:217], v[84:87]
	v_mfma_f32_16x16x32_f16 v[80:83], v[140:143], v[214:217], v[80:83]
	s_setprio 0
	s_setprio 1
	v_mfma_f32_16x16x32_f16 v[124:127], v[144:147], v[176:179], v[124:127]
	v_mfma_f32_16x16x32_f16 v[120:123], v[152:155], v[176:179], v[120:123]
	v_mfma_f32_16x16x32_f16 v[108:111], v[144:147], v[184:187], v[108:111]
	v_mfma_f32_16x16x32_f16 v[104:107], v[152:155], v[184:187], v[104:107]
	v_mfma_f32_16x16x32_f16 v[92:95], v[144:147], v[202:205], v[92:95]
	v_mfma_f32_16x16x32_f16 v[88:91], v[152:155], v[202:205], v[88:91]
	v_mfma_f32_16x16x32_f16 v[76:79], v[144:147], v[210:213], v[76:79]
	v_mfma_f32_16x16x32_f16 v[72:75], v[152:155], v[210:213], v[72:75]
	v_mfma_f32_16x16x32_f16 v[124:127], v[148:151], v[180:183], v[124:127]
	v_mfma_f32_16x16x32_f16 v[120:123], v[156:159], v[180:183], v[120:123]
	v_mfma_f32_16x16x32_f16 v[108:111], v[148:151], v[198:201], v[108:111]
	v_mfma_f32_16x16x32_f16 v[104:107], v[156:159], v[198:201], v[104:107]
	v_mfma_f32_16x16x32_f16 v[92:95], v[148:151], v[206:209], v[92:95]
	v_mfma_f32_16x16x32_f16 v[88:91], v[156:159], v[206:209], v[88:91]
	v_mfma_f32_16x16x32_f16 v[76:79], v[148:151], v[214:217], v[76:79]
	v_mfma_f32_16x16x32_f16 v[72:75], v[156:159], v[214:217], v[72:75]
	s_setprio 0
	s_barrier
	s_add_i32 s44, s66, s68
	v_lshl_add_u64 v[188:189], v[188:189], 0, s[18:19]
	s_mov_b32 m0, s44
	ds_read_b128 v[176:179], v195 offset:49152
	ds_read_b128 v[180:183], v195 offset:50176
	ds_read_b128 v[184:187], v195 offset:51200
	ds_read_b128 v[198:201], v195 offset:52224
	ds_read_b128 v[202:205], v195 offset:53248
	ds_read_b128 v[206:209], v195 offset:54272
	ds_read_b128 v[210:213], v195 offset:55296
	ds_read_b128 v[214:217], v195 offset:56320
	global_load_lds_dwordx4 v[188:189], off
	s_add_i32 m0, s44, 0x2000
	s_add_u32 s36, s36, 0x40080
	v_lshl_add_u64 v[188:189], v[218:219], 0, s[18:19]
	s_addc_u32 s37, s37, 0
	s_add_i32 s44, s67, s68
	global_load_lds_dwordx4 v[188:189], off
	s_mov_b32 m0, s44
	s_nop 0
	global_load_lds_dwordx4 v162, s[36:37]
	s_add_i32 m0, s44, 0x2000
	s_nop 0
	global_load_lds_dwordx4 v166, s[36:37]
	v_lshl_add_u64 v[188:189], v[220:221], 0, s[18:19]
	s_mov_b32 m0, s75
	s_nop 0
	global_load_lds_dwordx4 v[188:189], off
	v_lshl_add_u64 v[188:189], v[222:223], 0, s[18:19]
	s_mov_b32 m0, s53
	s_nop 0
	global_load_lds_dwordx4 v[188:189], off
	s_waitcnt vmcnt(8)
	s_waitcnt lgkmcnt(0)
	s_barrier
	s_setprio 1
	s_waitcnt lgkmcnt(0)
	v_mfma_f32_16x16x32_f16 v[68:71], v[16:19], v[176:179], v[68:71]
	v_mfma_f32_16x16x32_f16 v[52:55], v[16:19], v[184:187], v[52:55]
	v_mfma_f32_16x16x32_f16 v[36:39], v[16:19], v[202:205], v[36:39]
	v_mfma_f32_16x16x32_f16 v[0:3], v[16:19], v[210:213], v[0:3]
	v_mfma_f32_16x16x32_f16 v[68:71], v[20:23], v[180:183], v[68:71]
	v_mfma_f32_16x16x32_f16 v[64:67], v[136:139], v[176:179], v[64:67]
	v_mfma_f32_16x16x32_f16 v[52:55], v[20:23], v[198:201], v[52:55]
	v_mfma_f32_16x16x32_f16 v[48:51], v[136:139], v[184:187], v[48:51]
	v_mfma_f32_16x16x32_f16 v[36:39], v[20:23], v[206:209], v[36:39]
	v_mfma_f32_16x16x32_f16 v[32:35], v[136:139], v[202:205], v[32:35]
	v_mfma_f32_16x16x32_f16 v[20:23], v[20:23], v[214:217], v[0:3]
	v_mfma_f32_16x16x32_f16 v[0:3], v[136:139], v[210:213], v[4:7]
	v_mfma_f32_16x16x32_f16 v[64:67], v[140:143], v[180:183], v[64:67]
	v_mfma_f32_16x16x32_f16 v[48:51], v[140:143], v[198:201], v[48:51]
	v_mfma_f32_16x16x32_f16 v[32:35], v[140:143], v[206:209], v[32:35]
	v_mfma_f32_16x16x32_f16 v[16:19], v[140:143], v[214:217], v[0:3]
	s_setprio 0
	s_setprio 1
	v_mfma_f32_16x16x32_f16 v[0:3], v[144:147], v[176:179], v[60:63]
	v_mfma_f32_16x16x32_f16 v[60:63], v[148:151], v[180:183], v[0:3]
	v_mfma_f32_16x16x32_f16 v[0:3], v[152:155], v[176:179], v[56:59]
	v_mfma_f32_16x16x32_f16 v[56:59], v[156:159], v[180:183], v[0:3]
	v_mfma_f32_16x16x32_f16 v[0:3], v[144:147], v[184:187], v[44:47]
	v_mfma_f32_16x16x32_f16 v[44:47], v[148:151], v[198:201], v[0:3]
	v_mfma_f32_16x16x32_f16 v[0:3], v[152:155], v[184:187], v[40:43]
	v_mfma_f32_16x16x32_f16 v[40:43], v[156:159], v[198:201], v[0:3]
	v_mfma_f32_16x16x32_f16 v[0:3], v[144:147], v[202:205], v[28:31]
	v_mfma_f32_16x16x32_f16 v[28:31], v[148:151], v[206:209], v[0:3]
	v_mfma_f32_16x16x32_f16 v[0:3], v[152:155], v[202:205], v[24:27]
	v_mfma_f32_16x16x32_f16 v[24:27], v[156:159], v[206:209], v[0:3]
	v_mfma_f32_16x16x32_f16 v[0:3], v[144:147], v[210:213], v[12:15]
	v_mfma_f32_16x16x32_f16 v[12:15], v[148:151], v[214:217], v[0:3]
	v_mfma_f32_16x16x32_f16 v[0:3], v[152:155], v[210:213], v[8:11]
	v_mfma_f32_16x16x32_f16 v[8:11], v[156:159], v[214:217], v[0:3]
	s_setprio 0
	s_barrier
	s_add_i32 s65, s65, 2
	s_add_u32 s34, s34, 0x100
	s_addc_u32 s35, s35, 0
	s_add_u32 s43, s43, 0x100
	s_addc_u32 s64, s64, 0
	s_cmp_gt_u32 s65, 13
	s_cbranch_scc0 .LBB0_585
	s_and_b64 vcc, exec, s[16:17]
	s_cbranch_vccz .LBB0_588
	s_barrier

; #define PG8_STAGE(bufoff, gbase, voff) do { _Pragma("unroll") for (int _i = 0; _i < 2; ++_i) \
;         __builtin_amdgcn_global_load_lds((const unsigned*)((const char*)(gbase) + (voff)[_i]), (PG8_LAS unsigned*)(lds + (bufoff) + ldsw + _i * 8192), 16, 0, 0); } while (0)
; #define PG8_WAIT_V(n) asm volatile("s_waitcnt vmcnt(" #n ")" ::: "memory")
; #define PG8_BAR __builtin_amdgcn_s_barrier()
; template <class Epi, class Sched, bool ALIGN_EPI = false, bool SP2 = false, bool F16 = false>
; __device__ __forceinline__ void gemm_phase(PG8_LAS unsigned char* lds, const Gemm g, const Sched& S, const Epi& E, const int wid_in) {
;     ...
;     const int wid = wid_in, lane = lane_, tid = wid * 64 + lane, wr = wid >> 2, wc = wid & 3, fr = lane & 15, fq = lane >> 4;
;     const int K = g.K, nt = K / BK;
;     unsigned voffA[2], voffB[2];
; #pragma unroll
;     for (int i = 0; i < 2; ++i) { int R, C; stage_rc(tid * 16 + i * 8192, R, C); const int Rb = Epi::PERM ? ((R & ~31) + perm32(R & 31)) : R;
;         voffA[i] = (unsigned)(R * K + C) * 2u; voffB[i] = (unsigned)(Rb * K + C) * 2u; }
;     const size_t kstep = (size_t)(BK * 2);
;     const size_t hstep = (size_t)HALF * K * 2;
;     const size_t tstep = 2 * hstep;
;     const unsigned ldsw = (unsigned)wid * 1024u;
;     const int aoff = lds_byte(wr * 64 + fr, fq * 8), boff = lds_byte(wc * 32 + fr, fq * 8);
;     ...
;         PG8_STAGE(PG8_SB(1, 0), cB + kstep, voffB); PG8_STAGE(PG8_SA(1, 0), cA + kstep, voffA); PG8_STAGE(PG8_SB(1, 1), cB + hstep + kstep, voffB);
;         PG8_WAIT_V(6); PG8_BAR;
.LBB0_617:
	s_add_u32 s18, s14, 0xf400000
	s_mov_b64 s[20:21], 0x80
	s_addc_u32 s19, s15, 0
	s_add_i32 m0, s74, 0x18000
	v_lshl_add_u64 v[6:7], v[6:7], 0, s[20:21]
	s_waitcnt vmcnt(2)
	s_barrier
	global_load_lds_dwordx4 v[6:7], off
	v_lshl_add_u64 v[4:5], v[4:5], 0, s[20:21]
	s_add_i32 m0, s74, 0x1a000
	s_add_i32 s14, s74, 0xa000
	global_load_lds_dwordx4 v[4:5], off
	v_lshl_add_u64 v[2:3], v[2:3], 0, s[20:21]
	s_mov_b32 m0, s75
	s_add_u32 s8, s10, 0x10080
	global_load_lds_dwordx4 v[2:3], off
	v_lshl_add_u64 v[0:1], v[0:1], 0, s[20:21]
	s_mov_b32 m0, s14
	s_addc_u32 s9, s11, 0
	global_load_lds_dwordx4 v[0:1], off
	s_add_i32 m0, s74, 0x1c000
	s_nop 0
	global_load_lds_dwordx4 v130, s[8:9]
	s_add_i32 m0, s74, 0x1e000
	v_and_b32_e32 v132, 15, v8
	global_load_lds_dwordx4 v128, s[8:9]
	v_or_b32_e32 v0, s70, v132
	v_ashrrev_i32_e32 v1, 6, v8
	v_lshlrev_b32_e32 v2, 6, v0
	v_and_b32_e32 v3, 48, v8
	s_movk_i32 s8, 0x3c0
	v_lshlrev_b32_e32 v0, 2, v0
	v_and_or_b32 v2, v2, s8, v3
	v_lshl_add_u32 v4, v1, 10, s73
	v_and_b32_e32 v0, 32, v0
	v_bitop3_b32 v0, v2, v4, v0 bitop3:0xde
	v_lshl_or_b32 v2, v132, 6, v3
	v_lshlrev_b32_e32 v3, 2, v8
	v_add_lshl_u32 v1, v1, s96, 10
	v_and_b32_e32 v3, 32, v3
	v_bitop3_b32 v1, v2, v1, v3 bitop3:0xde
	s_waitcnt vmcnt(6)
	s_add_i32 s51, 0, 0x10000
	s_add_i32 s53, 0, 0x14000
	s_add_i32 s55, 0, 0x18000
	s_add_i32 s59, 0, 0x1c000
	v_add_u32_e32 v134, s51, v1
	v_add_u32_e32 v135, s53, v1
	v_add_u32_e32 v136, 0, v0
	s_add_i32 s51, s51, s68
	s_add_i32 s53, s53, s68
	v_add_u32_e32 v137, s55, v1
	v_add_u32_e32 v138, s59, v1
	s_add_i32 s55, s55, s68
	s_add_i32 s59, s59, s68
	v_cndmask_b32_e64 v0, 0, 1, s[16:17]
	v_ashrrev_i32_e32 v133, 4, v8
	s_mov_b64 s[26:27], -1
	s_add_i32 s15, s74, 0xc000
	s_add_i32 s50, s74, 0xe000
	s_mov_b64 s[22:23], 0x100
	s_add_i32 s52, s51, 0x2000
	s_add_i32 s54, s53, 0x2000
	s_mov_b64 s[24:25], 0x180
	s_add_i32 s58, s55, 0x2000
	s_add_i32 s60, s59, 0x2000
	v_cmp_ne_u32_e64 s[8:9], 1, v0
	s_barrier
	s_branch .LBB0_620

; #define PG8_STAGE(bufoff, gbase, voff) do { _Pragma("unroll") for (int _i = 0; _i < 2; ++_i) \
;         __builtin_amdgcn_global_load_lds((const unsigned*)((const char*)(gbase) + (voff)[_i]), (PG8_LAS unsigned*)(lds + (bufoff) + ldsw + _i * 8192), 16, 0, 0); } while (0)
; #define PG8_LDA(dst, b, h) do { _Pragma("unroll") for (int m = 0; m < 4; ++m) _Pragma("unroll") for (int k = 0; k < 2; ++k) dst[m][k] = *(const PG8_LAS bf16x8*)(lds + PG8_SA(b, h) + aoff + m * 2048 + k * 1024); } while (0)
; #define PG8_LDB(dst, b, h) do { _Pragma("unroll") for (int n = 0; n < 2; ++n) _Pragma("unroll") for (int k = 0; k < 2; ++k) dst[n][k] = *(const PG8_LAS bf16x8*)(lds + PG8_SB(b, h) + boff + n * 2048 + k * 1024); } while (0)
; #define PG8_WAIT_V(n) asm volatile("s_waitcnt vmcnt(" #n ")" ::: "memory")
; #define PG8_WAIT_L(n) asm volatile("s_waitcnt lgkmcnt(" #n ")" ::: "memory")
; #define PG8_BAR __builtin_amdgcn_s_barrier()
; #define PG8_SCHED __builtin_amdgcn_sched_barrier(0)
; template <class Epi, class Sched, bool ALIGN_EPI = false, bool SP2 = false, bool F16 = false>
; __device__ __forceinline__ void gemm_phase(PG8_LAS unsigned char* lds, const Gemm g, const Sched& S, const Epi& E, const int wid_in) {
;     ...
;         const bool has_next = S.next(ui + 1, nxt);
;         const char* nA = has_next ? (const char*)g.A + (size_t)nxt.pm * tstep : cA; const char* nB = has_next ? (const char*)g.Bt + (size_t)nxt.pn * tstep : cB;
;         for (int t = 0; t < nt; t += 2) {
;             const bool last = (t == nt - 2);
;             const char* a1 = cA + (size_t)(t + 1) * kstep;
;             const char* a2 = last ? nA : cA + (size_t)(t + 2) * kstep; const char* b2 = last ? nB : cB + (size_t)(t + 2) * kstep;
;             const char* a3 = a2 + kstep; const char* b3 = b2 + kstep;
;             if (last && has_next) S.a_ready(nxt);
;             if constexpr (SP2) {
;             PG8_LDB(B0, 0, 0); PG8_LDB(B1, 0, 1); PG8_SCHED; PG8_LDA(At, 0, 0); PG8_STAGE(PG8_SA(1, 1), a1 + hstep, voffA);
;             PG8_WAIT_V(8); PG8_WAIT_L(0); PG8_BAR; PG8_MMA(0, 0, At, B0); PG8_MMA(0, 1, At, B1); PG8_BAR; PG8_SCHED;
;             PG8_LDA(At, 0, 1); PG8_STAGE(PG8_SB(0, 0), b2, voffB); PG8_STAGE(PG8_SB(0, 1), b2 + hstep, voffB); PG8_STAGE(PG8_SA(0, 0), a2, voffA);
;             PG8_WAIT_V(8); PG8_WAIT_L(0); PG8_BAR; PG8_MMA(1, 0, At, B0); PG8_MMA(1, 1, At, B1); PG8_BAR; PG8_SCHED;
.LBB0_620:
	s_mov_b64 s[44:45], s[10:11]
	s_add_i32 s10, s30, s40
	s_mov_b64 s[36:37], s[12:13]
	s_mov_b32 s12, s62
	s_mov_b32 s13, s61
	s_and_b32 s61, s10, 3
	s_ashr_i32 s62, s10, 2
	s_and_b64 s[10:11], s[26:27], exec
	s_cselect_b32 s12, s62, s12
	ds_read_b128 v[0:3], v134
	ds_read_b128 v[4:7], v134 offset:1024
	ds_read_b128 v[8:11], v134 offset:2048
	ds_read_b128 v[12:15], v134 offset:3072
	ds_read_b128 v[16:19], v135
	ds_read_b128 v[20:23], v135 offset:1024
	ds_read_b128 v[24:27], v135 offset:2048
	ds_read_b128 v[28:31], v135 offset:3072
	s_cselect_b32 s10, s61, s13
	s_ashr_i32 s13, s12, 31
	s_lshl_b64 s[12:13], s[12:13], 17
	s_add_u32 s12, s43, s12
	s_addc_u32 s13, s46, s13
	s_and_b64 s[30:31], s[26:27], exec
	s_cselect_b32 s35, s13, s37
	s_cselect_b32 s34, s12, s36
	s_ashr_i32 s11, s10, 31
	s_lshl_b64 s[10:11], s[10:11], 17
	s_add_u32 s10, s41, s10
	s_addc_u32 s11, s42, s11
	s_and_b64 s[30:31], s[26:27], exec
	s_cselect_b32 s31, s11, s45
	s_cselect_b32 s30, s10, s44
	s_add_u32 s64, s36, 0x10080
	s_addc_u32 s65, s37, 0
	s_mov_b32 m0, s15
	ds_read_b128 v[32:35], v136
	ds_read_b128 v[36:39], v136 offset:1024
	ds_read_b128 v[40:43], v136 offset:2048
	ds_read_b128 v[44:47], v136 offset:3072
	ds_read_b128 v[48:51], v136 offset:4096
	ds_read_b128 v[52:55], v136 offset:5120
	ds_read_b128 v[56:59], v136 offset:6144
	ds_read_b128 v[60:63], v136 offset:7168
	global_load_lds_dwordx4 v130, s[64:65]
	s_mov_b32 m0, s50
	s_nop 0
	global_load_lds_dwordx4 v128, s[64:65]
	s_waitcnt vmcnt(8)
	s_waitcnt lgkmcnt(0)
	s_barrier
	s_setprio 1
	s_waitcnt lgkmcnt(0)
	v_mfma_f32_16x16x32_bf16 v[64:67], v[0:3], v[32:35], 0
	v_mfma_f32_16x16x32_bf16 v[68:71], v[8:11], v[32:35], 0
	v_mfma_f32_16x16x32_bf16 v[72:75], v[0:3], v[40:43], 0
	v_mfma_f32_16x16x32_bf16 v[76:79], v[8:11], v[40:43], 0
	v_mfma_f32_16x16x32_bf16 v[80:83], v[0:3], v[48:51], 0
	v_mfma_f32_16x16x32_bf16 v[84:87], v[8:11], v[48:51], 0
	v_mfma_f32_16x16x32_bf16 v[88:91], v[0:3], v[56:59], 0
	v_mfma_f32_16x16x32_bf16 v[92:95], v[8:11], v[56:59], 0
	v_mfma_f32_16x16x32_bf16 v[64:67], v[4:7], v[36:39], v[64:67]
	v_mfma_f32_16x16x32_bf16 v[68:71], v[12:15], v[36:39], v[68:71]
	v_mfma_f32_16x16x32_bf16 v[72:75], v[4:7], v[44:47], v[72:75]
	v_mfma_f32_16x16x32_bf16 v[76:79], v[12:15], v[44:47], v[76:79]
	v_mfma_f32_16x16x32_bf16 v[80:83], v[4:7], v[52:55], v[80:83]
	v_mfma_f32_16x16x32_bf16 v[84:87], v[12:15], v[52:55], v[84:87]
	v_mfma_f32_16x16x32_bf16 v[88:91], v[4:7], v[60:63], v[88:91]
	v_mfma_f32_16x16x32_bf16 v[92:95], v[12:15], v[60:63], v[92:95]
	s_setprio 0
	s_setprio 1
	v_mfma_f32_16x16x32_bf16 v[96:99], v[16:19], v[32:35], 0
	v_mfma_f32_16x16x32_bf16 v[32:35], v[24:27], v[32:35], 0
	v_mfma_f32_16x16x32_bf16 v[96:99], v[20:23], v[36:39], v[96:99]
	v_mfma_f32_16x16x32_bf16 v[32:35], v[28:31], v[36:39], v[32:35]
	v_mfma_f32_16x16x32_bf16 v[36:39], v[16:19], v[40:43], 0
	v_mfma_f32_16x16x32_bf16 v[40:43], v[24:27], v[40:43], 0
	v_mfma_f32_16x16x32_bf16 v[36:39], v[20:23], v[44:47], v[36:39]
	v_mfma_f32_16x16x32_bf16 v[40:43], v[28:31], v[44:47], v[40:43]
	v_mfma_f32_16x16x32_bf16 v[44:47], v[16:19], v[48:51], 0
	v_mfma_f32_16x16x32_bf16 v[48:51], v[24:27], v[48:51], 0
	v_mfma_f32_16x16x32_bf16 v[44:47], v[20:23], v[52:55], v[44:47]
	v_mfma_f32_16x16x32_bf16 v[48:51], v[28:31], v[52:55], v[48:51]
	v_mfma_f32_16x16x32_bf16 v[52:55], v[16:19], v[56:59], 0
	v_mfma_f32_16x16x32_bf16 v[56:59], v[24:27], v[56:59], 0
	v_mfma_f32_16x16x32_bf16 v[52:55], v[20:23], v[60:63], v[52:55]
	v_mfma_f32_16x16x32_bf16 v[56:59], v[28:31], v[60:63], v[56:59]
	s_setprio 0
	s_barrier
	v_lshl_add_u64 v[204:205], s[44:45], 0, v[130:131]
	s_mov_b32 m0, s51
	v_lshl_add_u64 v[140:141], v[204:205], 0, s[22:23]
	v_lshl_add_u64 v[206:207], s[44:45], 0, v[128:129]
	s_add_u32 s64, s44, 0x10100
	ds_read_b128 v[60:63], v136 offset:16384
	ds_read_b128 v[100:103], v136 offset:17408
	ds_read_b128 v[104:107], v136 offset:18432
	ds_read_b128 v[108:111], v136 offset:19456
	ds_read_b128 v[112:115], v136 offset:20480
	ds_read_b128 v[116:119], v136 offset:21504
	ds_read_b128 v[120:123], v136 offset:22528
	ds_read_b128 v[124:127], v136 offset:23552
	global_load_lds_dwordx4 v[140:141], off
	v_lshl_add_u64 v[140:141], v[206:207], 0, s[22:23]
	s_mov_b32 m0, s52
	s_addc_u32 s65, s45, 0
	global_load_lds_dwordx4 v[140:141], off
	s_mov_b32 m0, s53
	v_lshl_add_u64 v[208:209], s[36:37], 0, v[130:131]
	global_load_lds_dwordx4 v130, s[64:65]
	s_mov_b32 m0, s54
	v_lshl_add_u64 v[210:211], s[36:37], 0, v[128:129]
	global_load_lds_dwordx4 v128, s[64:65]
	v_lshl_add_u64 v[140:141], v[208:209], 0, s[22:23]
	s_mov_b32 m0, s74
	s_nop 0
	global_load_lds_dwordx4 v[140:141], off
	v_lshl_add_u64 v[140:141], v[210:211], 0, s[22:23]
	s_mov_b32 m0, s47
	s_nop 0
	global_load_lds_dwordx4 v[140:141], off
	s_waitcnt vmcnt(8)
	s_waitcnt lgkmcnt(0)
	s_barrier
; #define PG8_STAGE(bufoff, gbase, voff) do { _Pragma("unroll") for (int _i = 0; _i < 2; ++_i) \
;         __builtin_amdgcn_global_load_lds((const unsigned*)((const char*)(gbase) + (voff)[_i]), (PG8_LAS unsigned*)(lds + (bufoff) + ldsw + _i * 8192), 16, 0, 0); } while (0)
; #define PG8_LDA(dst, b, h) do { _Pragma("unroll") for (int m = 0; m < 4; ++m) _Pragma("unroll") for (int k = 0; k < 2; ++k) dst[m][k] = *(const PG8_LAS bf16x8*)(lds + PG8_SA(b, h) + aoff + m * 2048 + k * 1024); } while (0)
; #define PG8_LDB(dst, b, h) do { _Pragma("unroll") for (int n = 0; n < 2; ++n) _Pragma("unroll") for (int k = 0; k < 2; ++k) dst[n][k] = *(const PG8_LAS bf16x8*)(lds + PG8_SB(b, h) + boff + n * 2048 + k * 1024); } while (0)
; #define PG8_MMA(ai, bj, At, Bt) do { __builtin_amdgcn_s_setprio(1); _Pragma("unroll") for (int m = 0; m < 4; ++m) _Pragma("unroll") for (int n = 0; n < 2; ++n) _Pragma("unroll") for (int k = 0; k < 2; ++k) \
;         acc[ai][bj][m][n] = mma16<F16>(Bt[n][k], At[m][k], acc[ai][bj][m][n]); __builtin_amdgcn_s_setprio(0); } while (0)
; #define PG8_WAIT_V(n) asm volatile("s_waitcnt vmcnt(" #n ")" ::: "memory")
; #define PG8_WAIT_L(n) asm volatile("s_waitcnt lgkmcnt(" #n ")" ::: "memory")
; #define PG8_BAR __builtin_amdgcn_s_barrier()
; #define PG8_SCHED __builtin_amdgcn_sched_barrier(0)
; template <class Epi, class Sched, bool ALIGN_EPI = false, bool SP2 = false, bool F16 = false>
; __device__ __forceinline__ void gemm_phase(PG8_LAS unsigned char* lds, const Gemm g, const Sched& S, const Epi& E, const int wid_in) {
;     ...
;             PG8_LDA(At, 0, 1); PG8_STAGE(PG8_SB(0, 0), b2, voffB); PG8_STAGE(PG8_SB(0, 1), b2 + hstep, voffB); PG8_STAGE(PG8_SA(0, 0), a2, voffA);
;             PG8_WAIT_V(8); PG8_WAIT_L(0); PG8_BAR; PG8_MMA(1, 0, At, B0); PG8_MMA(1, 1, At, B1); PG8_BAR; PG8_SCHED;
;             PG8_LDB(B0, 1, 0); PG8_LDB(B1, 1, 1); PG8_SCHED; PG8_LDA(At, 1, 0); PG8_STAGE(PG8_SA(0, 1), a2 + hstep, voffA);
;             PG8_WAIT_V(8); PG8_WAIT_L(0); PG8_BAR; PG8_MMA(0, 0, At, B0); PG8_MMA(0, 1, At, B1); PG8_BAR; PG8_SCHED;
	s_setprio 1
	s_waitcnt lgkmcnt(0)
	v_mfma_f32_16x16x32_bf16 v[140:143], v[0:3], v[60:63], 0
	v_mfma_f32_16x16x32_bf16 v[148:151], v[0:3], v[104:107], 0
	v_mfma_f32_16x16x32_bf16 v[156:159], v[0:3], v[112:115], 0
	v_mfma_f32_16x16x32_bf16 v[0:3], v[0:3], v[120:123], 0
	v_mfma_f32_16x16x32_bf16 v[140:143], v[4:7], v[100:103], v[140:143]
	v_mfma_f32_16x16x32_bf16 v[148:151], v[4:7], v[108:111], v[148:151]
	v_mfma_f32_16x16x32_bf16 v[156:159], v[4:7], v[116:119], v[156:159]
	v_mfma_f32_16x16x32_bf16 v[0:3], v[4:7], v[124:127], v[0:3]
	v_mfma_f32_16x16x32_bf16 v[4:7], v[8:11], v[120:123], 0
	v_mfma_f32_16x16x32_bf16 v[144:147], v[8:11], v[60:63], 0
	v_mfma_f32_16x16x32_bf16 v[152:155], v[8:11], v[104:107], 0
	v_mfma_f32_16x16x32_bf16 v[160:163], v[8:11], v[112:115], 0
	v_mfma_f32_16x16x32_bf16 v[4:7], v[12:15], v[124:127], v[4:7]
	v_mfma_f32_16x16x32_bf16 v[144:147], v[12:15], v[100:103], v[144:147]
	v_mfma_f32_16x16x32_bf16 v[152:155], v[12:15], v[108:111], v[152:155]
	v_mfma_f32_16x16x32_bf16 v[160:163], v[12:15], v[116:119], v[160:163]
	s_setprio 0
	s_setprio 1
	v_mfma_f32_16x16x32_bf16 v[8:11], v[16:19], v[60:63], 0
	v_mfma_f32_16x16x32_bf16 v[12:15], v[24:27], v[60:63], 0
	v_mfma_f32_16x16x32_bf16 v[8:11], v[20:23], v[100:103], v[8:11]
	v_mfma_f32_16x16x32_bf16 v[12:15], v[28:31], v[100:103], v[12:15]
	v_mfma_f32_16x16x32_bf16 v[60:63], v[16:19], v[104:107], 0
	v_mfma_f32_16x16x32_bf16 v[100:103], v[24:27], v[104:107], 0
	v_mfma_f32_16x16x32_bf16 v[104:107], v[16:19], v[112:115], 0
	v_mfma_f32_16x16x32_bf16 v[16:19], v[16:19], v[120:123], 0
	v_mfma_f32_16x16x32_bf16 v[60:63], v[20:23], v[108:111], v[60:63]
	v_mfma_f32_16x16x32_bf16 v[100:103], v[28:31], v[108:111], v[100:103]
	v_mfma_f32_16x16x32_bf16 v[104:107], v[20:23], v[116:119], v[104:107]
	v_mfma_f32_16x16x32_bf16 v[108:111], v[24:27], v[112:115], 0
	v_mfma_f32_16x16x32_bf16 v[16:19], v[20:23], v[124:127], v[16:19]
	v_mfma_f32_16x16x32_bf16 v[20:23], v[24:27], v[120:123], 0
	v_mfma_f32_16x16x32_bf16 v[108:111], v[28:31], v[116:119], v[108:111]
	v_mfma_f32_16x16x32_bf16 v[20:23], v[28:31], v[124:127], v[20:23]
	s_setprio 0
	s_barrier
	ds_read_b128 v[24:27], v137
	ds_read_b128 v[28:31], v137 offset:1024
	ds_read_b128 v[112:115], v137 offset:2048
	ds_read_b128 v[116:119], v137 offset:3072
	ds_read_b128 v[120:123], v138
	ds_read_b128 v[124:127], v138 offset:1024
	ds_read_b128 v[164:167], v138 offset:2048
	ds_read_b128 v[168:171], v138 offset:3072
	s_add_u32 s64, s36, 0x10100
	s_addc_u32 s65, s37, 0
	s_mov_b32 m0, s48
	ds_read_b128 v[172:175], v136 offset:32768
	ds_read_b128 v[176:179], v136 offset:33792
	ds_read_b128 v[180:183], v136 offset:34816
	ds_read_b128 v[184:187], v136 offset:35840
	ds_read_b128 v[188:191], v136 offset:36864
	ds_read_b128 v[192:195], v136 offset:37888
	ds_read_b128 v[196:199], v136 offset:38912
	ds_read_b128 v[200:203], v136 offset:39936
	global_load_lds_dwordx4 v130, s[64:65]
	s_mov_b32 m0, s49
	s_nop 0
	global_load_lds_dwordx4 v128, s[64:65]
	s_waitcnt vmcnt(8)
	s_waitcnt lgkmcnt(0)
	s_barrier
	s_setprio 1
	s_waitcnt lgkmcnt(0)
	v_mfma_f32_16x16x32_bf16 v[64:67], v[24:27], v[172:175], v[64:67]
	v_mfma_f32_16x16x32_bf16 v[68:71], v[112:115], v[172:175], v[68:71]
	v_mfma_f32_16x16x32_bf16 v[72:75], v[24:27], v[180:183], v[72:75]
	v_mfma_f32_16x16x32_bf16 v[76:79], v[112:115], v[180:183], v[76:79]
	v_mfma_f32_16x16x32_bf16 v[80:83], v[24:27], v[188:191], v[80:83]
	v_mfma_f32_16x16x32_bf16 v[84:87], v[112:115], v[188:191], v[84:87]
	v_mfma_f32_16x16x32_bf16 v[88:91], v[24:27], v[196:199], v[88:91]
	v_mfma_f32_16x16x32_bf16 v[92:95], v[112:115], v[196:199], v[92:95]
	v_mfma_f32_16x16x32_bf16 v[64:67], v[28:31], v[176:179], v[64:67]
	v_mfma_f32_16x16x32_bf16 v[68:71], v[116:119], v[176:179], v[68:71]
	v_mfma_f32_16x16x32_bf16 v[72:75], v[28:31], v[184:187], v[72:75]
	v_mfma_f32_16x16x32_bf16 v[76:79], v[116:119], v[184:187], v[76:79]
	v_mfma_f32_16x16x32_bf16 v[80:83], v[28:31], v[192:195], v[80:83]
	v_mfma_f32_16x16x32_bf16 v[84:87], v[116:119], v[192:195], v[84:87]
	v_mfma_f32_16x16x32_bf16 v[88:91], v[28:31], v[200:203], v[88:91]
	v_mfma_f32_16x16x32_bf16 v[92:95], v[116:119], v[200:203], v[92:95]
	s_setprio 0
	s_setprio 1
	v_mfma_f32_16x16x32_bf16 v[96:99], v[120:123], v[172:175], v[96:99]
	v_mfma_f32_16x16x32_bf16 v[32:35], v[164:167], v[172:175], v[32:35]
	v_mfma_f32_16x16x32_bf16 v[36:39], v[120:123], v[180:183], v[36:39]
	v_mfma_f32_16x16x32_bf16 v[40:43], v[164:167], v[180:183], v[40:43]
	v_mfma_f32_16x16x32_bf16 v[44:47], v[120:123], v[188:191], v[44:47]
	v_mfma_f32_16x16x32_bf16 v[48:51], v[164:167], v[188:191], v[48:51]
	v_mfma_f32_16x16x32_bf16 v[52:55], v[120:123], v[196:199], v[52:55]
	v_mfma_f32_16x16x32_bf16 v[56:59], v[164:167], v[196:199], v[56:59]
	v_mfma_f32_16x16x32_bf16 v[96:99], v[124:127], v[176:179], v[96:99]
	v_mfma_f32_16x16x32_bf16 v[32:35], v[168:171], v[176:179], v[32:35]
	v_mfma_f32_16x16x32_bf16 v[36:39], v[124:127], v[184:187], v[36:39]
	v_mfma_f32_16x16x32_bf16 v[40:43], v[168:171], v[184:187], v[40:43]
	v_mfma_f32_16x16x32_bf16 v[44:47], v[124:127], v[192:195], v[44:47]
	v_mfma_f32_16x16x32_bf16 v[48:51], v[168:171], v[192:195], v[48:51]
	v_mfma_f32_16x16x32_bf16 v[52:55], v[124:127], v[200:203], v[52:55]
	v_mfma_f32_16x16x32_bf16 v[56:59], v[168:171], v[200:203], v[56:59]
	s_setprio 0
	s_barrier
; #define PG8_STAGE(bufoff, gbase, voff) do { _Pragma("unroll") for (int _i = 0; _i < 2; ++_i) \
;         __builtin_amdgcn_global_load_lds((const unsigned*)((const char*)(gbase) + (voff)[_i]), (PG8_LAS unsigned*)(lds + (bufoff) + ldsw + _i * 8192), 16, 0, 0); } while (0)
; #define PG8_LDA(dst, b, h) do { _Pragma("unroll") for (int m = 0; m < 4; ++m) _Pragma("unroll") for (int k = 0; k < 2; ++k) dst[m][k] = *(const PG8_LAS bf16x8*)(lds + PG8_SA(b, h) + aoff + m * 2048 + k * 1024); } while (0)
; #define PG8_LDB(dst, b, h) do { _Pragma("unroll") for (int n = 0; n < 2; ++n) _Pragma("unroll") for (int k = 0; k < 2; ++k) dst[n][k] = *(const PG8_LAS bf16x8*)(lds + PG8_SB(b, h) + boff + n * 2048 + k * 1024); } while (0)
; #define PG8_MMA(ai, bj, At, Bt) do { __builtin_amdgcn_s_setprio(1); _Pragma("unroll") for (int m = 0; m < 4; ++m) _Pragma("unroll") for (int n = 0; n < 2; ++n) _Pragma("unroll") for (int k = 0; k < 2; ++k) \
;         acc[ai][bj][m][n] = mma16<F16>(Bt[n][k], At[m][k], acc[ai][bj][m][n]); __builtin_amdgcn_s_setprio(0); } while (0)
; #define PG8_WAIT_V(n) asm volatile("s_waitcnt vmcnt(" #n ")" ::: "memory")
; #define PG8_WAIT_L(n) asm volatile("s_waitcnt lgkmcnt(" #n ")" ::: "memory")
; #define PG8_BAR __builtin_amdgcn_s_barrier()
; #define PG8_SCHED __builtin_amdgcn_sched_barrier(0)
; template <class Epi, class Sched, bool ALIGN_EPI = false, bool SP2 = false, bool F16 = false>
; __device__ __forceinline__ void gemm_phase(PG8_LAS unsigned char* lds, const Gemm g, const Sched& S, const Epi& E, const int wid_in) {
;     ...
;             PG8_LDB(B0, 1, 0); PG8_LDB(B1, 1, 1); PG8_SCHED; PG8_LDA(At, 1, 0); PG8_STAGE(PG8_SA(0, 1), a2 + hstep, voffA);
;             PG8_WAIT_V(8); PG8_WAIT_L(0); PG8_BAR; PG8_MMA(0, 0, At, B0); PG8_MMA(0, 1, At, B1); PG8_BAR; PG8_SCHED;
;             PG8_LDA(At, 1, 1); PG8_STAGE(PG8_SB(1, 0), b3, voffB); PG8_STAGE(PG8_SB(1, 1), b3 + hstep, voffB); PG8_STAGE(PG8_SA(1, 0), a3, voffA);
;             PG8_WAIT_V(8); PG8_WAIT_L(0); PG8_BAR; PG8_MMA(1, 0, At, B0); PG8_MMA(1, 1, At, B1); PG8_BAR; PG8_SCHED;
	s_mov_b32 m0, s55
	v_lshl_add_u64 v[204:205], v[204:205], 0, s[24:25]
	s_add_u32 s44, s44, 0x10180
	ds_read_b128 v[172:175], v136 offset:49152
	ds_read_b128 v[176:179], v136 offset:50176
	ds_read_b128 v[180:183], v136 offset:51200
	ds_read_b128 v[184:187], v136 offset:52224
	ds_read_b128 v[188:191], v136 offset:53248
	ds_read_b128 v[192:195], v136 offset:54272
	ds_read_b128 v[196:199], v136 offset:55296
	ds_read_b128 v[200:203], v136 offset:56320
	global_load_lds_dwordx4 v[204:205], off
	v_lshl_add_u64 v[204:205], v[206:207], 0, s[24:25]
	s_mov_b32 m0, s58
	s_addc_u32 s45, s45, 0
	global_load_lds_dwordx4 v[204:205], off
	s_mov_b32 m0, s59
	s_nop 0
	global_load_lds_dwordx4 v130, s[44:45]
	s_mov_b32 m0, s60
	s_nop 0
	global_load_lds_dwordx4 v128, s[44:45]
	v_lshl_add_u64 v[204:205], v[208:209], 0, s[24:25]
	s_mov_b32 m0, s75
	s_nop 0
	global_load_lds_dwordx4 v[204:205], off
	v_lshl_add_u64 v[204:205], v[210:211], 0, s[24:25]
	s_mov_b32 m0, s14
	s_nop 0
	global_load_lds_dwordx4 v[204:205], off
	s_waitcnt vmcnt(8)
	s_waitcnt lgkmcnt(0)
	s_barrier
	s_setprio 1
	s_waitcnt lgkmcnt(0)
	v_mfma_f32_16x16x32_bf16 v[0:3], v[24:27], v[196:199], v[0:3]
	v_mfma_f32_16x16x32_bf16 v[4:7], v[112:115], v[196:199], v[4:7]
	v_mfma_f32_16x16x32_bf16 v[140:143], v[24:27], v[172:175], v[140:143]
	v_mfma_f32_16x16x32_bf16 v[144:147], v[112:115], v[172:175], v[144:147]
	v_mfma_f32_16x16x32_bf16 v[148:151], v[24:27], v[180:183], v[148:151]
	v_mfma_f32_16x16x32_bf16 v[152:155], v[112:115], v[180:183], v[152:155]
	v_mfma_f32_16x16x32_bf16 v[156:159], v[24:27], v[188:191], v[156:159]
	v_mfma_f32_16x16x32_bf16 v[160:163], v[112:115], v[188:191], v[160:163]
	v_mfma_f32_16x16x32_bf16 v[0:3], v[28:31], v[200:203], v[0:3]
	v_mfma_f32_16x16x32_bf16 v[4:7], v[116:119], v[200:203], v[4:7]
	v_mfma_f32_16x16x32_bf16 v[140:143], v[28:31], v[176:179], v[140:143]
	v_mfma_f32_16x16x32_bf16 v[144:147], v[116:119], v[176:179], v[144:147]
	v_mfma_f32_16x16x32_bf16 v[148:151], v[28:31], v[184:187], v[148:151]
	v_mfma_f32_16x16x32_bf16 v[152:155], v[116:119], v[184:187], v[152:155]
	v_mfma_f32_16x16x32_bf16 v[156:159], v[28:31], v[192:195], v[156:159]
	v_mfma_f32_16x16x32_bf16 v[160:163], v[116:119], v[192:195], v[160:163]
	s_setprio 0
	s_setprio 1
	v_mfma_f32_16x16x32_bf16 v[8:11], v[120:123], v[172:175], v[8:11]
	v_mfma_f32_16x16x32_bf16 v[12:15], v[164:167], v[172:175], v[12:15]
	v_mfma_f32_16x16x32_bf16 v[24:27], v[120:123], v[180:183], v[60:63]
	v_mfma_f32_16x16x32_bf16 v[28:31], v[164:167], v[180:183], v[100:103]
	v_mfma_f32_16x16x32_bf16 v[60:63], v[120:123], v[188:191], v[104:107]
	v_mfma_f32_16x16x32_bf16 v[100:103], v[164:167], v[188:191], v[108:111]
	v_mfma_f32_16x16x32_bf16 v[16:19], v[120:123], v[196:199], v[16:19]
	v_mfma_f32_16x16x32_bf16 v[20:23], v[164:167], v[196:199], v[20:23]
	v_mfma_f32_16x16x32_bf16 v[8:11], v[124:127], v[176:179], v[8:11]
	v_mfma_f32_16x16x32_bf16 v[12:15], v[168:171], v[176:179], v[12:15]
	v_mfma_f32_16x16x32_bf16 v[24:27], v[124:127], v[184:187], v[24:27]
	v_mfma_f32_16x16x32_bf16 v[28:31], v[168:171], v[184:187], v[28:31]
	v_mfma_f32_16x16x32_bf16 v[60:63], v[124:127], v[192:195], v[60:63]
	v_mfma_f32_16x16x32_bf16 v[100:103], v[168:171], v[192:195], v[100:103]
	v_mfma_f32_16x16x32_bf16 v[16:19], v[124:127], v[200:203], v[16:19]
	v_mfma_f32_16x16x32_bf16 v[20:23], v[168:171], v[200:203], v[20:23]
	s_setprio 0
	s_barrier
	ds_read_b128 v[104:107], v134
	ds_read_b128 v[108:111], v134 offset:1024
	ds_read_b128 v[112:115], v134 offset:2048
	ds_read_b128 v[116:119], v134 offset:3072
	ds_read_b128 v[120:123], v135
	ds_read_b128 v[124:127], v135 offset:1024
	ds_read_b128 v[164:167], v135 offset:2048
	ds_read_b128 v[168:171], v135 offset:3072
	s_add_u32 s36, s36, 0x10180
	s_addc_u32 s37, s37, 0
	s_mov_b32 m0, s15
	ds_read_b128 v[172:175], v136
	ds_read_b128 v[176:179], v136 offset:1024
	ds_read_b128 v[180:183], v136 offset:2048
	ds_read_b128 v[184:187], v136 offset:3072
	ds_read_b128 v[188:191], v136 offset:4096
	ds_read_b128 v[192:195], v136 offset:5120
	ds_read_b128 v[196:199], v136 offset:6144
	ds_read_b128 v[200:203], v136 offset:7168
	global_load_lds_dwordx4 v130, s[36:37]
	s_mov_b32 m0, s50
	s_nop 0
	global_load_lds_dwordx4 v128, s[36:37]
	s_waitcnt vmcnt(8)
	s_waitcnt lgkmcnt(0)
	s_barrier
	s_setprio 1
	s_waitcnt lgkmcnt(0)
	v_mfma_f32_16x16x32_bf16 v[64:67], v[104:107], v[172:175], v[64:67]
	v_mfma_f32_16x16x32_bf16 v[68:71], v[112:115], v[172:175], v[68:71]
	v_mfma_f32_16x16x32_bf16 v[72:75], v[104:107], v[180:183], v[72:75]
	v_mfma_f32_16x16x32_bf16 v[76:79], v[112:115], v[180:183], v[76:79]
	v_mfma_f32_16x16x32_bf16 v[80:83], v[104:107], v[188:191], v[80:83]
	v_mfma_f32_16x16x32_bf16 v[84:87], v[112:115], v[188:191], v[84:87]
	v_mfma_f32_16x16x32_bf16 v[88:91], v[104:107], v[196:199], v[88:91]
	v_mfma_f32_16x16x32_bf16 v[92:95], v[112:115], v[196:199], v[92:95]
	v_mfma_f32_16x16x32_bf16 v[64:67], v[108:111], v[176:179], v[64:67]
	v_mfma_f32_16x16x32_bf16 v[68:71], v[116:119], v[176:179], v[68:71]
	v_mfma_f32_16x16x32_bf16 v[72:75], v[108:111], v[184:187], v[72:75]
	v_mfma_f32_16x16x32_bf16 v[76:79], v[116:119], v[184:187], v[76:79]
	v_mfma_f32_16x16x32_bf16 v[80:83], v[108:111], v[192:195], v[80:83]
	v_mfma_f32_16x16x32_bf16 v[84:87], v[116:119], v[192:195], v[84:87]
	v_mfma_f32_16x16x32_bf16 v[88:91], v[108:111], v[200:203], v[88:91]
	v_mfma_f32_16x16x32_bf16 v[92:95], v[116:119], v[200:203], v[92:95]
	s_setprio 0
	s_setprio 1
	v_mfma_f32_16x16x32_bf16 v[32:35], v[164:167], v[172:175], v[32:35]
	v_mfma_f32_16x16x32_bf16 v[96:99], v[120:123], v[172:175], v[96:99]
	v_mfma_f32_16x16x32_bf16 v[172:175], v[168:171], v[176:179], v[32:35]
	v_mfma_f32_16x16x32_bf16 v[32:35], v[120:123], v[180:183], v[36:39]
	v_mfma_f32_16x16x32_bf16 v[204:207], v[124:127], v[176:179], v[96:99]
	v_mfma_f32_16x16x32_bf16 v[176:179], v[124:127], v[184:187], v[32:35]
	v_mfma_f32_16x16x32_bf16 v[32:35], v[164:167], v[180:183], v[40:43]
	v_mfma_f32_16x16x32_bf16 v[40:43], v[168:171], v[184:187], v[32:35]
	v_mfma_f32_16x16x32_bf16 v[32:35], v[120:123], v[188:191], v[44:47]
	v_mfma_f32_16x16x32_bf16 v[44:47], v[124:127], v[192:195], v[32:35]
	v_mfma_f32_16x16x32_bf16 v[32:35], v[164:167], v[188:191], v[48:51]
	v_mfma_f32_16x16x32_bf16 v[48:51], v[168:171], v[192:195], v[32:35]
	v_mfma_f32_16x16x32_bf16 v[32:35], v[120:123], v[196:199], v[52:55]
	v_mfma_f32_16x16x32_bf16 v[52:55], v[124:127], v[200:203], v[32:35]
	v_mfma_f32_16x16x32_bf16 v[32:35], v[164:167], v[196:199], v[56:59]
	v_mfma_f32_16x16x32_bf16 v[56:59], v[168:171], v[200:203], v[32:35]
	s_setprio 0
	s_barrier
; #define PG8_STAGE(bufoff, gbase, voff) do { _Pragma("unroll") for (int _i = 0; _i < 2; ++_i) \
;         __builtin_amdgcn_global_load_lds((const unsigned*)((const char*)(gbase) + (voff)[_i]), (PG8_LAS unsigned*)(lds + (bufoff) + ldsw + _i * 8192), 16, 0, 0); } while (0)
; #define PG8_LDA(dst, b, h) do { _Pragma("unroll") for (int m = 0; m < 4; ++m) _Pragma("unroll") for (int k = 0; k < 2; ++k) dst[m][k] = *(const PG8_LAS bf16x8*)(lds + PG8_SA(b, h) + aoff + m * 2048 + k * 1024); } while (0)
; #define PG8_LDB(dst, b, h) do { _Pragma("unroll") for (int n = 0; n < 2; ++n) _Pragma("unroll") for (int k = 0; k < 2; ++k) dst[n][k] = *(const PG8_LAS bf16x8*)(lds + PG8_SB(b, h) + boff + n * 2048 + k * 1024); } while (0)
; #define PG8_MMA(ai, bj, At, Bt) do { __builtin_amdgcn_s_setprio(1); _Pragma("unroll") for (int m = 0; m < 4; ++m) _Pragma("unroll") for (int n = 0; n < 2; ++n) _Pragma("unroll") for (int k = 0; k < 2; ++k) \
;         acc[ai][bj][m][n] = mma16<F16>(Bt[n][k], At[m][k], acc[ai][bj][m][n]); __builtin_amdgcn_s_setprio(0); } while (0)
; #define PG8_WAIT_V(n) asm volatile("s_waitcnt vmcnt(" #n ")" ::: "memory")
; #define PG8_WAIT_L(n) asm volatile("s_waitcnt lgkmcnt(" #n ")" ::: "memory")
; #define PG8_BAR __builtin_amdgcn_s_barrier()
; #define PG8_SCHED __builtin_amdgcn_sched_barrier(0)
; template <class Epi, class Sched, bool ALIGN_EPI = false, bool SP2 = false, bool F16 = false>
; __device__ __forceinline__ void gemm_phase(PG8_LAS unsigned char* lds, const Gemm g, const Sched& S, const Epi& E, const int wid_in) {
;     ...
;             PG8_LDB(B0, 0, 0); PG8_LDB(B1, 0, 1); PG8_SCHED; PG8_LDA(At, 0, 0); PG8_STAGE(PG8_SA(1, 1), a1 + hstep, voffA);
;             PG8_WAIT_V(8); PG8_WAIT_L(0); PG8_BAR; PG8_MMA(0, 0, At, B0); PG8_MMA(0, 1, At, B1); PG8_BAR; PG8_SCHED;
;             PG8_LDA(At, 0, 1); PG8_STAGE(PG8_SB(0, 0), b2, voffB); PG8_STAGE(PG8_SB(0, 1), b2 + hstep, voffB); PG8_STAGE(PG8_SA(0, 0), a2, voffA);
;             PG8_WAIT_V(8); PG8_WAIT_L(0); PG8_BAR; PG8_MMA(1, 0, At, B0); PG8_MMA(1, 1, At, B1); PG8_BAR; PG8_SCHED;
;             PG8_LDB(B0, 1, 0); PG8_LDB(B1, 1, 1); PG8_SCHED; PG8_LDA(At, 1, 0); PG8_STAGE(PG8_SA(0, 1), a2 + hstep, voffA);
;             PG8_WAIT_V(8); PG8_WAIT_L(0); PG8_BAR; PG8_MMA(0, 0, At, B0); PG8_MMA(0, 1, At, B1); PG8_BAR; PG8_SCHED;
	s_mov_b32 m0, s51
	v_lshl_add_u64 v[240:241], s[30:31], 0, v[130:131]
	s_add_u32 s36, s30, 0x10000
	s_nop 1
	ds_read_b128 v[32:35], v136 offset:16384
	ds_read_b128 v[36:39], v136 offset:17408
	ds_read_b128 v[96:99], v136 offset:18432
	ds_read_b128 v[180:183], v136 offset:19456
	ds_read_b128 v[184:187], v136 offset:20480
	ds_read_b128 v[188:191], v136 offset:21504
	ds_read_b128 v[192:195], v136 offset:22528
	ds_read_b128 v[196:199], v136 offset:23552
	global_load_lds_dwordx4 v[240:241], off
	v_lshl_add_u64 v[242:243], s[30:31], 0, v[128:129]
	s_mov_b32 m0, s52
	s_addc_u32 s37, s31, 0
	global_load_lds_dwordx4 v[242:243], off
	s_mov_b32 m0, s53
	v_lshl_add_u64 v[244:245], s[34:35], 0, v[130:131]
	global_load_lds_dwordx4 v130, s[36:37]
	s_mov_b32 m0, s54
	v_lshl_add_u64 v[246:247], s[34:35], 0, v[128:129]
	global_load_lds_dwordx4 v128, s[36:37]
	s_mov_b32 m0, s74
	s_nop 0
	global_load_lds_dwordx4 v[244:245], off
	s_mov_b32 m0, s47
	s_nop 0
	global_load_lds_dwordx4 v[246:247], off
	s_waitcnt vmcnt(8)
	s_waitcnt lgkmcnt(0)
	s_barrier
	s_setprio 1
	s_waitcnt lgkmcnt(0)
	v_mfma_f32_16x16x32_bf16 v[0:3], v[104:107], v[192:195], v[0:3]
	v_mfma_f32_16x16x32_bf16 v[140:143], v[104:107], v[32:35], v[140:143]
	v_mfma_f32_16x16x32_bf16 v[144:147], v[112:115], v[32:35], v[144:147]
	v_mfma_f32_16x16x32_bf16 v[148:151], v[104:107], v[96:99], v[148:151]
	v_mfma_f32_16x16x32_bf16 v[152:155], v[112:115], v[96:99], v[152:155]
	v_mfma_f32_16x16x32_bf16 v[156:159], v[104:107], v[184:187], v[156:159]
	v_mfma_f32_16x16x32_bf16 v[160:163], v[112:115], v[184:187], v[160:163]
	v_mfma_f32_16x16x32_bf16 v[0:3], v[108:111], v[196:199], v[0:3]
	v_mfma_f32_16x16x32_bf16 v[4:7], v[112:115], v[192:195], v[4:7]
	v_mfma_f32_16x16x32_bf16 v[140:143], v[108:111], v[36:39], v[140:143]
	v_mfma_f32_16x16x32_bf16 v[144:147], v[116:119], v[36:39], v[144:147]
	v_mfma_f32_16x16x32_bf16 v[148:151], v[108:111], v[180:183], v[148:151]
	v_mfma_f32_16x16x32_bf16 v[152:155], v[116:119], v[180:183], v[152:155]
	v_mfma_f32_16x16x32_bf16 v[156:159], v[108:111], v[188:191], v[156:159]
	v_mfma_f32_16x16x32_bf16 v[160:163], v[116:119], v[188:191], v[160:163]
	v_mfma_f32_16x16x32_bf16 v[200:203], v[116:119], v[196:199], v[4:7]
	s_setprio 0
	s_setprio 1
	v_mfma_f32_16x16x32_bf16 v[4:7], v[120:123], v[32:35], v[8:11]
	v_mfma_f32_16x16x32_bf16 v[8:11], v[124:127], v[36:39], v[4:7]
	v_mfma_f32_16x16x32_bf16 v[4:7], v[164:167], v[32:35], v[12:15]
	v_mfma_f32_16x16x32_bf16 v[12:15], v[168:171], v[36:39], v[4:7]
	v_mfma_f32_16x16x32_bf16 v[4:7], v[120:123], v[96:99], v[24:27]
	v_mfma_f32_16x16x32_bf16 v[24:27], v[124:127], v[180:183], v[4:7]
	v_mfma_f32_16x16x32_bf16 v[4:7], v[164:167], v[96:99], v[28:31]
	v_mfma_f32_16x16x32_bf16 v[28:31], v[168:171], v[180:183], v[4:7]
	v_mfma_f32_16x16x32_bf16 v[4:7], v[120:123], v[184:187], v[60:63]
	v_mfma_f32_16x16x32_bf16 v[180:183], v[124:127], v[188:191], v[4:7]
	v_mfma_f32_16x16x32_bf16 v[4:7], v[164:167], v[184:187], v[100:103]
	v_mfma_f32_16x16x32_bf16 v[184:187], v[168:171], v[188:191], v[4:7]
	v_mfma_f32_16x16x32_bf16 v[4:7], v[120:123], v[192:195], v[16:19]
	v_mfma_f32_16x16x32_bf16 v[188:191], v[124:127], v[196:199], v[4:7]
	v_mfma_f32_16x16x32_bf16 v[4:7], v[164:167], v[192:195], v[20:23]
	v_mfma_f32_16x16x32_bf16 v[164:167], v[168:171], v[196:199], v[4:7]
	s_setprio 0
	s_barrier
	s_nop 4
	ds_read_b128 v[4:7], v137
	ds_read_b128 v[60:63], v137 offset:1024
	ds_read_b128 v[168:171], v137 offset:2048
	ds_read_b128 v[192:195], v137 offset:3072
	ds_read_b128 v[196:199], v138
	ds_read_b128 v[208:211], v138 offset:1024
	ds_read_b128 v[212:215], v138 offset:2048
	ds_read_b128 v[216:219], v138 offset:3072
	s_add_u32 s34, s34, 0x10000
	s_addc_u32 s35, s35, 0
	s_mov_b32 m0, s48
	ds_read_b128 v[16:19], v136 offset:32768
	ds_read_b128 v[20:23], v136 offset:33792
	ds_read_b128 v[104:107], v136 offset:34816
	ds_read_b128 v[220:223], v136 offset:35840
	ds_read_b128 v[224:227], v136 offset:36864
	ds_read_b128 v[228:231], v136 offset:37888
	ds_read_b128 v[232:235], v136 offset:38912
	ds_read_b128 v[236:239], v136 offset:39936
	global_load_lds_dwordx4 v130, s[34:35]
	s_mov_b32 m0, s49
	s_nop 0
	global_load_lds_dwordx4 v128, s[34:35]
	s_waitcnt vmcnt(8)
	s_waitcnt lgkmcnt(0)
	s_barrier
; #define PG8_STAGE(bufoff, gbase, voff) do { _Pragma("unroll") for (int _i = 0; _i < 2; ++_i) \
;         __builtin_amdgcn_global_load_lds((const unsigned*)((const char*)(gbase) + (voff)[_i]), (PG8_LAS unsigned*)(lds + (bufoff) + ldsw + _i * 8192), 16, 0, 0); } while (0)
; #define PG8_LDA(dst, b, h) do { _Pragma("unroll") for (int m = 0; m < 4; ++m) _Pragma("unroll") for (int k = 0; k < 2; ++k) dst[m][k] = *(const PG8_LAS bf16x8*)(lds + PG8_SA(b, h) + aoff + m * 2048 + k * 1024); } while (0)
; #define PG8_LDB(dst, b, h) do { _Pragma("unroll") for (int n = 0; n < 2; ++n) _Pragma("unroll") for (int k = 0; k < 2; ++k) dst[n][k] = *(const PG8_LAS bf16x8*)(lds + PG8_SB(b, h) + boff + n * 2048 + k * 1024); } while (0)
; #define PG8_MMA(ai, bj, At, Bt) do { __builtin_amdgcn_s_setprio(1); _Pragma("unroll") for (int m = 0; m < 4; ++m) _Pragma("unroll") for (int n = 0; n < 2; ++n) _Pragma("unroll") for (int k = 0; k < 2; ++k) \
;         acc[ai][bj][m][n] = mma16<F16>(Bt[n][k], At[m][k], acc[ai][bj][m][n]); __builtin_amdgcn_s_setprio(0); } while (0)
; #define PG8_WAIT_V(n) asm volatile("s_waitcnt vmcnt(" #n ")" ::: "memory")
; #define PG8_WAIT_L(n) asm volatile("s_waitcnt lgkmcnt(" #n ")" ::: "memory")
; #define PG8_BAR __builtin_amdgcn_s_barrier()
; #define PG8_SCHED __builtin_amdgcn_sched_barrier(0)
; template <class Epi, class Sched, bool ALIGN_EPI = false, bool SP2 = false, bool F16 = false>
; __device__ __forceinline__ void gemm_phase(PG8_LAS unsigned char* lds, const Gemm g, const Sched& S, const Epi& E, const int wid_in) {
;     ...
;             PG8_LDB(B0, 1, 0); PG8_LDB(B1, 1, 1); PG8_SCHED; PG8_LDA(At, 1, 0); PG8_STAGE(PG8_SA(0, 1), a2 + hstep, voffA);
;             PG8_WAIT_V(8); PG8_WAIT_L(0); PG8_BAR; PG8_MMA(0, 0, At, B0); PG8_MMA(0, 1, At, B1); PG8_BAR; PG8_SCHED;
;             PG8_LDA(At, 1, 1); PG8_STAGE(PG8_SB(1, 0), b3, voffB); PG8_STAGE(PG8_SB(1, 1), b3 + hstep, voffB); PG8_STAGE(PG8_SA(1, 0), a3, voffA);
;             PG8_WAIT_V(8); PG8_WAIT_L(0); PG8_BAR; PG8_MMA(1, 0, At, B0); PG8_MMA(1, 1, At, B1); PG8_BAR; PG8_SCHED;
;     ...
;         if (!has_next) break;
	s_setprio 1
	s_waitcnt lgkmcnt(0)
	v_mfma_f32_16x16x32_bf16 v[32:35], v[4:7], v[16:19], v[64:67]
	v_mfma_f32_16x16x32_bf16 v[116:119], v[60:63], v[20:23], v[32:35]
	v_mfma_f32_16x16x32_bf16 v[32:35], v[168:171], v[16:19], v[68:71]
	v_mfma_f32_16x16x32_bf16 v[112:115], v[192:195], v[20:23], v[32:35]
	v_mfma_f32_16x16x32_bf16 v[32:35], v[4:7], v[104:107], v[72:75]
	v_mfma_f32_16x16x32_bf16 v[100:103], v[60:63], v[220:223], v[32:35]
	v_mfma_f32_16x16x32_bf16 v[32:35], v[168:171], v[104:107], v[76:79]
	v_mfma_f32_16x16x32_bf16 v[96:99], v[192:195], v[220:223], v[32:35]
	v_mfma_f32_16x16x32_bf16 v[32:35], v[4:7], v[224:227], v[80:83]
	v_mfma_f32_16x16x32_bf16 v[68:71], v[60:63], v[228:231], v[32:35]
	v_mfma_f32_16x16x32_bf16 v[32:35], v[168:171], v[224:227], v[84:87]
	v_mfma_f32_16x16x32_bf16 v[64:67], v[192:195], v[228:231], v[32:35]
	v_mfma_f32_16x16x32_bf16 v[32:35], v[4:7], v[232:235], v[88:91]
	v_mfma_f32_16x16x32_bf16 v[36:39], v[60:63], v[236:239], v[32:35]
	v_mfma_f32_16x16x32_bf16 v[32:35], v[168:171], v[232:235], v[92:95]
	v_mfma_f32_16x16x32_bf16 v[32:35], v[192:195], v[236:239], v[32:35]
	s_setprio 0
	s_setprio 1
	v_mfma_f32_16x16x32_bf16 v[72:75], v[196:199], v[16:19], v[204:207]
	v_mfma_f32_16x16x32_bf16 v[16:19], v[212:215], v[16:19], v[172:175]
	v_mfma_f32_16x16x32_bf16 v[120:123], v[216:219], v[20:23], v[16:19]
	v_mfma_f32_16x16x32_bf16 v[16:19], v[196:199], v[104:107], v[176:179]
	v_mfma_f32_16x16x32_bf16 v[108:111], v[208:211], v[220:223], v[16:19]
	v_mfma_f32_16x16x32_bf16 v[16:19], v[212:215], v[104:107], v[40:43]
	v_mfma_f32_16x16x32_bf16 v[104:107], v[216:219], v[220:223], v[16:19]
	v_mfma_f32_16x16x32_bf16 v[16:19], v[196:199], v[224:227], v[44:47]
	v_mfma_f32_16x16x32_bf16 v[80:83], v[208:211], v[228:231], v[16:19]
	v_mfma_f32_16x16x32_bf16 v[16:19], v[212:215], v[224:227], v[48:51]
	v_mfma_f32_16x16x32_bf16 v[124:127], v[208:211], v[20:23], v[72:75]
	v_mfma_f32_16x16x32_bf16 v[72:75], v[216:219], v[228:231], v[16:19]
	v_mfma_f32_16x16x32_bf16 v[16:19], v[196:199], v[232:235], v[52:55]
	v_mfma_f32_16x16x32_bf16 v[48:51], v[208:211], v[236:239], v[16:19]
	v_mfma_f32_16x16x32_bf16 v[16:19], v[212:215], v[232:235], v[56:59]
	v_mfma_f32_16x16x32_bf16 v[40:43], v[216:219], v[236:239], v[16:19]
	s_setprio 0
	s_barrier
	s_mov_b32 m0, s55
	s_nop 3
	v_lshl_add_u64 v[16:17], v[240:241], 0, s[20:21]
	s_add_u32 s30, s30, 0x10080
	ds_read_b128 v[56:59], v136 offset:49152
	ds_read_b128 v[88:91], v136 offset:50176
	ds_read_b128 v[172:175], v136 offset:51200
	ds_read_b128 v[176:179], v136 offset:52224
	ds_read_b128 v[204:207], v136 offset:53248
	ds_read_b128 v[220:223], v136 offset:54272
	ds_read_b128 v[224:227], v136 offset:55296
	ds_read_b128 v[228:231], v136 offset:56320
	global_load_lds_dwordx4 v[16:17], off
	v_lshl_add_u64 v[16:17], v[242:243], 0, s[20:21]
	s_mov_b32 m0, s58
	s_addc_u32 s31, s31, 0
	global_load_lds_dwordx4 v[16:17], off
	s_mov_b32 m0, s59
	s_nop 0
	global_load_lds_dwordx4 v130, s[30:31]
	s_mov_b32 m0, s60
	s_nop 0
	global_load_lds_dwordx4 v128, s[30:31]
	v_lshl_add_u64 v[16:17], v[244:245], 0, s[20:21]
	s_mov_b32 m0, s75
	s_nop 0
	global_load_lds_dwordx4 v[16:17], off
	v_lshl_add_u64 v[16:17], v[246:247], 0, s[20:21]
	s_mov_b32 m0, s14
	s_nop 0
	global_load_lds_dwordx4 v[16:17], off
	s_waitcnt vmcnt(8)
	s_waitcnt lgkmcnt(0)
	s_barrier
	s_setprio 1
	s_waitcnt lgkmcnt(0)
	v_mfma_f32_16x16x32_bf16 v[16:19], v[4:7], v[56:59], v[140:143]
	v_mfma_f32_16x16x32_bf16 v[84:87], v[60:63], v[88:91], v[16:19]
	v_mfma_f32_16x16x32_bf16 v[16:19], v[168:171], v[56:59], v[144:147]
	v_mfma_f32_16x16x32_bf16 v[76:79], v[192:195], v[88:91], v[16:19]
	v_mfma_f32_16x16x32_bf16 v[16:19], v[4:7], v[172:175], v[148:151]
	v_mfma_f32_16x16x32_bf16 v[52:55], v[60:63], v[176:179], v[16:19]
	v_mfma_f32_16x16x32_bf16 v[16:19], v[168:171], v[172:175], v[152:155]
	v_mfma_f32_16x16x32_bf16 v[44:47], v[192:195], v[176:179], v[16:19]
	v_mfma_f32_16x16x32_bf16 v[16:19], v[4:7], v[204:207], v[156:159]
	v_mfma_f32_16x16x32_bf16 v[0:3], v[4:7], v[224:227], v[0:3]
	v_mfma_f32_16x16x32_bf16 v[20:23], v[60:63], v[220:223], v[16:19]
	v_mfma_f32_16x16x32_bf16 v[16:19], v[168:171], v[204:207], v[160:163]
	v_mfma_f32_16x16x32_bf16 v[4:7], v[60:63], v[228:231], v[0:3]
	v_mfma_f32_16x16x32_bf16 v[0:3], v[168:171], v[224:227], v[200:203]
	v_mfma_f32_16x16x32_bf16 v[16:19], v[192:195], v[220:223], v[16:19]
	v_mfma_f32_16x16x32_bf16 v[0:3], v[192:195], v[228:231], v[0:3]
	s_setprio 0
	s_setprio 1
	v_mfma_f32_16x16x32_bf16 v[8:11], v[196:199], v[56:59], v[8:11]
	v_mfma_f32_16x16x32_bf16 v[92:95], v[208:211], v[88:91], v[8:11]
	v_mfma_f32_16x16x32_bf16 v[8:11], v[212:215], v[56:59], v[12:15]
	v_mfma_f32_16x16x32_bf16 v[88:91], v[216:219], v[88:91], v[8:11]
	v_mfma_f32_16x16x32_bf16 v[8:11], v[196:199], v[172:175], v[24:27]
	v_mfma_f32_16x16x32_bf16 v[60:63], v[208:211], v[176:179], v[8:11]
	v_mfma_f32_16x16x32_bf16 v[8:11], v[212:215], v[172:175], v[28:31]
	v_mfma_f32_16x16x32_bf16 v[56:59], v[216:219], v[176:179], v[8:11]
	v_mfma_f32_16x16x32_bf16 v[8:11], v[196:199], v[204:207], v[180:183]
	v_mfma_f32_16x16x32_bf16 v[28:31], v[208:211], v[220:223], v[8:11]
	v_mfma_f32_16x16x32_bf16 v[8:11], v[212:215], v[204:207], v[184:187]
	v_mfma_f32_16x16x32_bf16 v[24:27], v[216:219], v[220:223], v[8:11]
	v_mfma_f32_16x16x32_bf16 v[8:11], v[196:199], v[224:227], v[188:191]
	v_mfma_f32_16x16x32_bf16 v[12:15], v[208:211], v[228:231], v[8:11]
	v_mfma_f32_16x16x32_bf16 v[8:11], v[212:215], v[224:227], v[164:167]
	v_mfma_f32_16x16x32_bf16 v[8:11], v[216:219], v[228:231], v[8:11]
	s_setprio 0
	s_barrier
	s_and_b64 vcc, exec, s[8:9]
	s_cbranch_vccnz .LBB0_622
	s_barrier

; #define PG8_STAGE(bufoff, gbase, voff) do { _Pragma("unroll") for (int _i = 0; _i < 2; ++_i) \
;         __builtin_amdgcn_global_load_lds((const unsigned*)((const char*)(gbase) + (voff)[_i]), (PG8_LAS unsigned*)(lds + (bufoff) + ldsw + _i * 8192), 16, 0, 0); } while (0)
; #define PG8_WAIT_V(n) asm volatile("s_waitcnt vmcnt(" #n ")" ::: "memory")
; #define PG8_BAR __builtin_amdgcn_s_barrier()
; template <class Epi, class Sched, bool ALIGN_EPI = false, bool SP2 = false, bool F16 = false>
; __device__ __forceinline__ void gemm_phase(PG8_LAS unsigned char* lds, const Gemm g, const Sched& S, const Epi& E, const int wid_in) {
;     ...
;     const int wid = wid_in, lane = lane_, tid = wid * 64 + lane, wr = wid >> 2, wc = wid & 3, fr = lane & 15, fq = lane >> 4;
;     const int K = g.K, nt = K / BK;
;     unsigned voffA[2], voffB[2];
; #pragma unroll
;     for (int i = 0; i < 2; ++i) { int R, C; stage_rc(tid * 16 + i * 8192, R, C); const int Rb = Epi::PERM ? ((R & ~31) + perm32(R & 31)) : R;
;         voffA[i] = (unsigned)(R * K + C) * 2u; voffB[i] = (unsigned)(Rb * K + C) * 2u; }
;     const size_t kstep = (size_t)(BK * 2);
;     const size_t hstep = (size_t)HALF * K * 2;
;     const size_t tstep = 2 * hstep;
;     const unsigned ldsw = (unsigned)wid * 1024u;
;     const int aoff = lds_byte(wr * 64 + fr, fq * 8), boff = lds_byte(wc * 32 + fr, fq * 8);
;     ...
;         PG8_STAGE(PG8_SB(1, 0), cB + kstep, voffB); PG8_STAGE(PG8_SA(1, 0), cA + kstep, voffA); PG8_STAGE(PG8_SB(1, 1), cB + hstep + kstep, voffB);
;         PG8_WAIT_V(6); PG8_BAR;
.LBB0_702:
	s_add_u32 s18, s9, 0x7400000
	s_addc_u32 s19, s10, 0
	s_add_u32 s20, s9, 0x13400000
	s_addc_u32 s21, s10, 0
	s_add_u32 s22, s9, 0x15600000
	s_mov_b64 s[24:25], 0x80
	s_addc_u32 s23, s10, 0
	s_add_i32 m0, s74, 0x18000
	v_lshl_add_u64 v[6:7], v[6:7], 0, s[24:25]
	s_waitcnt vmcnt(2)
	s_barrier
	global_load_lds_dwordx4 v[6:7], off
	v_lshl_add_u64 v[4:5], v[4:5], 0, s[24:25]
	s_add_i32 m0, s74, 0x1a000
	s_add_i32 s48, s74, 0xa000
	global_load_lds_dwordx4 v[4:5], off
	v_lshl_add_u64 v[0:1], v[0:1], 0, s[24:25]
	s_mov_b32 m0, s75
	s_add_u32 s10, s30, 0xb0080
	global_load_lds_dwordx4 v[0:1], off
	v_lshl_add_u64 v[0:1], v[2:3], 0, s[24:25]
	s_mov_b32 m0, s48
	s_addc_u32 s11, s31, 0
	global_load_lds_dwordx4 v[0:1], off
	s_add_i32 m0, s74, 0x1c000
	s_nop 0
	global_load_lds_dwordx4 v154, s[10:11]
	s_add_i32 m0, s74, 0x1e000
	v_and_b32_e32 v187, 15, v8
	global_load_lds_dwordx4 v158, s[10:11]
	v_or_b32_e32 v0, s70, v187
	v_lshlrev_b32_e32 v1, 6, v0
	v_and_b32_e32 v2, 48, v8
	s_movk_i32 s9, 0x3c0
	v_and_b32_e32 v3, 0xfffffc00, v13
	v_lshlrev_b32_e32 v0, 2, v0
	v_and_or_b32 v1, v1, s9, v2
	v_add_u32_e32 v4, s73, v3
	v_and_b32_e32 v0, 32, v0
	v_bitop3_b32 v4, v1, v4, v0 bitop3:0xde
	v_lshl_or_b32 v0, v187, 6, v2
	v_lshlrev_b32_e32 v2, 2, v8
	v_add_u32_e32 v1, s72, v3
	v_and_b32_e32 v2, 32, v2
	v_bitop3_b32 v188, v0, v1, v2 bitop3:0xde
	v_lshrrev_b32_e32 v1, 1, v9
	v_mul_lo_u32 v0, v11, s8
	s_mov_b32 s9, 0xb000
	v_mad_u64_u32 v[0:1], s[26:27], v1, s9, v[0:1]
	v_or_b32_e32 v0, v0, v10
	s_mov_b64 s[10:11], 0xb0080
	v_add_lshl_u32 v0, v0, v12, 1
	v_mov_b32_e32 v1, v155
	v_lshl_add_u64 v[160:161], v[0:1], 0, s[10:11]
	v_lshrrev_b32_e32 v1, 1, v14
	v_mul_lo_u32 v0, v15, s8
	v_mad_u64_u32 v[0:1], s[8:9], v1, s9, v[0:1]
	s_waitcnt vmcnt(6)
	v_or_b32_e32 v0, v0, v16
	v_add_lshl_u32 v0, v0, v17, 1
	v_mov_b32_e32 v1, v155
	s_add_i32 s52, 0, 0x10000
	s_add_i32 s53, 0, 0x14000
	v_ashrrev_i32_e32 v186, 4, v8
	s_ashr_i32 s49, s38, 31
	s_mov_b32 s50, s38
	s_ashr_i32 s51, s14, 31
	v_lshl_add_u64 v[162:163], v[0:1], 0, s[10:11]
	v_mov_b64_e32 v[164:165], 0x100
	v_mov_b64_e32 v[166:167], 0xff
	v_add_u32_e32 v189, s52, v188
	v_add_u32_e32 v190, s53, v188
	v_add_u32_e32 v191, 0, v4
	s_mov_b32 s54, 0
	s_barrier
	s_branch .LBB0_705

; #define PG8_STAGE(bufoff, gbase, voff) do { _Pragma("unroll") for (int _i = 0; _i < 2; ++_i) \
;         __builtin_amdgcn_global_load_lds((const unsigned*)((const char*)(gbase) + (voff)[_i]), (PG8_LAS unsigned*)(lds + (bufoff) + ldsw + _i * 8192), 16, 0, 0); } while (0)
; #define PG8_LDA(dst, b, h) do { _Pragma("unroll") for (int m = 0; m < 4; ++m) _Pragma("unroll") for (int k = 0; k < 2; ++k) dst[m][k] = *(const PG8_LAS bf16x8*)(lds + PG8_SA(b, h) + aoff + m * 2048 + k * 1024); } while (0)
; #define PG8_LDB(dst, b, h) do { _Pragma("unroll") for (int n = 0; n < 2; ++n) _Pragma("unroll") for (int k = 0; k < 2; ++k) dst[n][k] = *(const PG8_LAS bf16x8*)(lds + PG8_SB(b, h) + boff + n * 2048 + k * 1024); } while (0)
; #define PG8_MMA(ai, bj, At, Bt) do { __builtin_amdgcn_s_setprio(1); _Pragma("unroll") for (int m = 0; m < 4; ++m) _Pragma("unroll") for (int n = 0; n < 2; ++n) _Pragma("unroll") for (int k = 0; k < 2; ++k) \
;         acc[ai][bj][m][n] = mma16<F16>(Bt[n][k], At[m][k], acc[ai][bj][m][n]); __builtin_amdgcn_s_setprio(0); } while (0)
; #define PG8_WAIT_V(n) asm volatile("s_waitcnt vmcnt(" #n ")" ::: "memory")
; #define PG8_WAIT_L(n) asm volatile("s_waitcnt lgkmcnt(" #n ")" ::: "memory")
; #define PG8_BAR __builtin_amdgcn_s_barrier()
; #define PG8_SCHED __builtin_amdgcn_sched_barrier(0)
; template <class Epi, class Sched, bool ALIGN_EPI = false, bool SP2 = false, bool F16 = false>
; __device__ __forceinline__ void gemm_phase(PG8_LAS unsigned char* lds, const Gemm g, const Sched& S, const Epi& E, const int wid_in) {
;     ...
;             PG8_LDB(B0, 0, 0); PG8_LDB(B1, 0, 1); PG8_SCHED; PG8_LDA(At, 0, 0); PG8_STAGE(PG8_SA(1, 1), a1 + hstep, voffA);
;             PG8_WAIT_V(8); PG8_WAIT_L(0); PG8_BAR; PG8_MMA(0, 0, At, B0); PG8_MMA(0, 1, At, B1); PG8_BAR; PG8_SCHED;
;             PG8_LDA(At, 0, 1); PG8_STAGE(PG8_SB(0, 0), b2, voffB); PG8_STAGE(PG8_SB(0, 1), b2 + hstep, voffB); PG8_STAGE(PG8_SA(0, 0), a2, voffA);
;             PG8_WAIT_V(8); PG8_WAIT_L(0); PG8_BAR; PG8_MMA(1, 0, At, B0); PG8_MMA(1, 1, At, B1); PG8_BAR; PG8_SCHED;
.LBB0_716:
	ds_read_b128 v[128:131], v189
	ds_read_b128 v[132:135], v189 offset:1024
	ds_read_b128 v[136:139], v189 offset:2048
	ds_read_b128 v[140:143], v189 offset:3072
	ds_read_b128 v[144:147], v190
	ds_read_b128 v[148:151], v190 offset:1024
	ds_read_b128 v[168:171], v190 offset:2048
	ds_read_b128 v[172:175], v190 offset:3072
	s_add_u32 s30, s28, 0x100
	s_addc_u32 s31, s29, 0
	s_cmp_eq_u32 s60, 40
	s_cselect_b32 s37, s11, s31
	s_cselect_b32 s36, s10, s30
	s_cselect_b32 s35, s27, s59
	s_cselect_b32 s34, s26, s43
	v_lshl_add_u64 v[184:185], s[28:29], 0, v[160:161]
	s_add_i32 m0, s74, 0xc000
	ds_read_b128 v[176:179], v191
	ds_read_b128 v[180:183], v191 offset:1024
	ds_read_b128 v[192:195], v191 offset:2048
	ds_read_b128 v[196:199], v191 offset:3072
	ds_read_b128 v[200:203], v191 offset:4096
	ds_read_b128 v[204:207], v191 offset:5120
	ds_read_b128 v[208:211], v191 offset:6144
	ds_read_b128 v[212:215], v191 offset:7168
	global_load_lds_dwordx4 v[184:185], off
	v_lshl_add_u64 v[184:185], s[28:29], 0, v[162:163]
	s_add_i32 m0, s74, 0xe000
	s_nop 0
	global_load_lds_dwordx4 v[184:185], off
	s_waitcnt vmcnt(8)
	s_waitcnt lgkmcnt(0)
	s_barrier
	s_setprio 1
	s_waitcnt lgkmcnt(0)
	v_mfma_f32_16x16x32_bf16 v[124:127], v[128:131], v[176:179], v[124:127]
	v_mfma_f32_16x16x32_bf16 v[120:123], v[136:139], v[176:179], v[120:123]
	v_mfma_f32_16x16x32_bf16 v[108:111], v[128:131], v[192:195], v[108:111]
	v_mfma_f32_16x16x32_bf16 v[104:107], v[136:139], v[192:195], v[104:107]
	v_mfma_f32_16x16x32_bf16 v[92:95], v[128:131], v[200:203], v[92:95]
	v_mfma_f32_16x16x32_bf16 v[88:91], v[136:139], v[200:203], v[88:91]
	v_mfma_f32_16x16x32_bf16 v[76:79], v[128:131], v[208:211], v[76:79]
	v_mfma_f32_16x16x32_bf16 v[72:75], v[136:139], v[208:211], v[72:75]
	v_mfma_f32_16x16x32_bf16 v[124:127], v[132:135], v[180:183], v[124:127]
	v_mfma_f32_16x16x32_bf16 v[120:123], v[140:143], v[180:183], v[120:123]
	v_mfma_f32_16x16x32_bf16 v[108:111], v[132:135], v[196:199], v[108:111]
	v_mfma_f32_16x16x32_bf16 v[104:107], v[140:143], v[196:199], v[104:107]
	v_mfma_f32_16x16x32_bf16 v[92:95], v[132:135], v[204:207], v[92:95]
	v_mfma_f32_16x16x32_bf16 v[88:91], v[140:143], v[204:207], v[88:91]
	v_mfma_f32_16x16x32_bf16 v[76:79], v[132:135], v[212:215], v[76:79]
	v_mfma_f32_16x16x32_bf16 v[72:75], v[140:143], v[212:215], v[72:75]
	s_setprio 0
	s_setprio 1
	v_mfma_f32_16x16x32_bf16 v[116:119], v[144:147], v[176:179], v[116:119]
	v_mfma_f32_16x16x32_bf16 v[112:115], v[168:171], v[176:179], v[112:115]
	v_mfma_f32_16x16x32_bf16 v[100:103], v[144:147], v[192:195], v[100:103]
	v_mfma_f32_16x16x32_bf16 v[96:99], v[168:171], v[192:195], v[96:99]
	v_mfma_f32_16x16x32_bf16 v[84:87], v[144:147], v[200:203], v[84:87]
	v_mfma_f32_16x16x32_bf16 v[80:83], v[168:171], v[200:203], v[80:83]
	v_mfma_f32_16x16x32_bf16 v[68:71], v[144:147], v[208:211], v[68:71]
	v_mfma_f32_16x16x32_bf16 v[64:67], v[168:171], v[208:211], v[64:67]
	v_mfma_f32_16x16x32_bf16 v[116:119], v[148:151], v[180:183], v[116:119]
	v_mfma_f32_16x16x32_bf16 v[112:115], v[172:175], v[180:183], v[112:115]
	v_mfma_f32_16x16x32_bf16 v[100:103], v[148:151], v[196:199], v[100:103]
	v_mfma_f32_16x16x32_bf16 v[96:99], v[172:175], v[196:199], v[96:99]
	v_mfma_f32_16x16x32_bf16 v[84:87], v[148:151], v[204:207], v[84:87]
	v_mfma_f32_16x16x32_bf16 v[80:83], v[172:175], v[204:207], v[80:83]
	v_mfma_f32_16x16x32_bf16 v[68:71], v[148:151], v[212:215], v[68:71]
	v_mfma_f32_16x16x32_bf16 v[64:67], v[172:175], v[212:215], v[64:67]
	s_setprio 0
	s_barrier
	s_add_i32 s28, s52, s68
	v_lshl_add_u64 v[184:185], s[34:35], 0, v[154:155]
	s_mov_b32 m0, s28
	ds_read_b128 v[176:179], v191 offset:16384
	ds_read_b128 v[180:183], v191 offset:17408
	ds_read_b128 v[192:195], v191 offset:18432
	ds_read_b128 v[196:199], v191 offset:19456
	ds_read_b128 v[200:203], v191 offset:20480
	ds_read_b128 v[204:207], v191 offset:21504
	ds_read_b128 v[208:211], v191 offset:22528
	ds_read_b128 v[212:215], v191 offset:23552
	global_load_lds_dwordx4 v[184:185], off
	s_add_i32 m0, s28, 0x2000
	s_add_u32 s28, s34, 0xb0000
	v_lshl_add_u64 v[216:217], s[34:35], 0, v[158:159]
	s_addc_u32 s29, s35, 0
	s_add_i32 s61, s53, s68
	global_load_lds_dwordx4 v[216:217], off
	s_mov_b32 m0, s61
	v_lshl_add_u64 v[220:221], s[36:37], 0, v[156:157]
	global_load_lds_dwordx4 v154, s[28:29]
	s_add_i32 m0, s61, 0x2000
	s_nop 0
	global_load_lds_dwordx4 v158, s[28:29]
	v_lshl_add_u64 v[218:219], s[36:37], 0, v[152:153]
	s_mov_b32 m0, s74
	s_nop 0
	global_load_lds_dwordx4 v[218:219], off
	s_mov_b32 m0, s45
	s_nop 0
	global_load_lds_dwordx4 v[220:221], off
	s_waitcnt vmcnt(8)
	s_waitcnt lgkmcnt(0)
	s_barrier
; #define PG8_STAGE(bufoff, gbase, voff) do { _Pragma("unroll") for (int _i = 0; _i < 2; ++_i) \
;         __builtin_amdgcn_global_load_lds((const unsigned*)((const char*)(gbase) + (voff)[_i]), (PG8_LAS unsigned*)(lds + (bufoff) + ldsw + _i * 8192), 16, 0, 0); } while (0)
; #define PG8_LDA(dst, b, h) do { _Pragma("unroll") for (int m = 0; m < 4; ++m) _Pragma("unroll") for (int k = 0; k < 2; ++k) dst[m][k] = *(const PG8_LAS bf16x8*)(lds + PG8_SA(b, h) + aoff + m * 2048 + k * 1024); } while (0)
; #define PG8_LDB(dst, b, h) do { _Pragma("unroll") for (int n = 0; n < 2; ++n) _Pragma("unroll") for (int k = 0; k < 2; ++k) dst[n][k] = *(const PG8_LAS bf16x8*)(lds + PG8_SB(b, h) + boff + n * 2048 + k * 1024); } while (0)
; #define PG8_MMA(ai, bj, At, Bt) do { __builtin_amdgcn_s_setprio(1); _Pragma("unroll") for (int m = 0; m < 4; ++m) _Pragma("unroll") for (int n = 0; n < 2; ++n) _Pragma("unroll") for (int k = 0; k < 2; ++k) \
;         acc[ai][bj][m][n] = mma16<F16>(Bt[n][k], At[m][k], acc[ai][bj][m][n]); __builtin_amdgcn_s_setprio(0); } while (0)
; #define PG8_WAIT_V(n) asm volatile("s_waitcnt vmcnt(" #n ")" ::: "memory")
; #define PG8_WAIT_L(n) asm volatile("s_waitcnt lgkmcnt(" #n ")" ::: "memory")
; #define PG8_BAR __builtin_amdgcn_s_barrier()
; #define PG8_SCHED __builtin_amdgcn_sched_barrier(0)
; template <class Epi, class Sched, bool ALIGN_EPI = false, bool SP2 = false, bool F16 = false>
; __device__ __forceinline__ void gemm_phase(PG8_LAS unsigned char* lds, const Gemm g, const Sched& S, const Epi& E, const int wid_in) {
;     ...
;             PG8_LDA(At, 0, 1); PG8_STAGE(PG8_SB(0, 0), b2, voffB); PG8_STAGE(PG8_SB(0, 1), b2 + hstep, voffB); PG8_STAGE(PG8_SA(0, 0), a2, voffA);
;             PG8_WAIT_V(8); PG8_WAIT_L(0); PG8_BAR; PG8_MMA(1, 0, At, B0); PG8_MMA(1, 1, At, B1); PG8_BAR; PG8_SCHED;
;             PG8_LDB(B0, 1, 0); PG8_LDB(B1, 1, 1); PG8_SCHED; PG8_LDA(At, 1, 0); PG8_STAGE(PG8_SA(0, 1), a2 + hstep, voffA);
;             PG8_WAIT_V(8); PG8_WAIT_L(0); PG8_BAR; PG8_MMA(0, 0, At, B0); PG8_MMA(0, 1, At, B1); PG8_BAR; PG8_SCHED;
;             PG8_LDA(At, 1, 1); PG8_STAGE(PG8_SB(1, 0), b3, voffB); PG8_STAGE(PG8_SB(1, 1), b3 + hstep, voffB); PG8_STAGE(PG8_SA(1, 0), a3, voffA);
	s_setprio 1
	s_waitcnt lgkmcnt(0)
	v_mfma_f32_16x16x32_bf16 v[60:63], v[128:131], v[176:179], v[60:63]
	v_mfma_f32_16x16x32_bf16 v[56:59], v[136:139], v[176:179], v[56:59]
	v_mfma_f32_16x16x32_bf16 v[44:47], v[128:131], v[192:195], v[44:47]
	v_mfma_f32_16x16x32_bf16 v[40:43], v[136:139], v[192:195], v[40:43]
	v_mfma_f32_16x16x32_bf16 v[28:31], v[128:131], v[200:203], v[28:31]
	v_mfma_f32_16x16x32_bf16 v[24:27], v[136:139], v[200:203], v[24:27]
	v_mfma_f32_16x16x32_bf16 v[12:15], v[128:131], v[208:211], v[12:15]
	v_mfma_f32_16x16x32_bf16 v[8:11], v[136:139], v[208:211], v[8:11]
	v_mfma_f32_16x16x32_bf16 v[60:63], v[132:135], v[180:183], v[60:63]
	v_mfma_f32_16x16x32_bf16 v[56:59], v[140:143], v[180:183], v[56:59]
	v_mfma_f32_16x16x32_bf16 v[44:47], v[132:135], v[196:199], v[44:47]
	v_mfma_f32_16x16x32_bf16 v[40:43], v[140:143], v[196:199], v[40:43]
	v_mfma_f32_16x16x32_bf16 v[28:31], v[132:135], v[204:207], v[28:31]
	v_mfma_f32_16x16x32_bf16 v[24:27], v[140:143], v[204:207], v[24:27]
	v_mfma_f32_16x16x32_bf16 v[12:15], v[132:135], v[212:215], v[12:15]
	v_mfma_f32_16x16x32_bf16 v[8:11], v[140:143], v[212:215], v[8:11]
	s_setprio 0
	s_setprio 1
	v_mfma_f32_16x16x32_bf16 v[52:55], v[144:147], v[176:179], v[52:55]
	v_mfma_f32_16x16x32_bf16 v[48:51], v[168:171], v[176:179], v[48:51]
	v_mfma_f32_16x16x32_bf16 v[36:39], v[144:147], v[192:195], v[36:39]
	v_mfma_f32_16x16x32_bf16 v[32:35], v[168:171], v[192:195], v[32:35]
	v_mfma_f32_16x16x32_bf16 v[20:23], v[144:147], v[200:203], v[20:23]
	v_mfma_f32_16x16x32_bf16 v[16:19], v[168:171], v[200:203], v[16:19]
	v_mfma_f32_16x16x32_bf16 v[4:7], v[144:147], v[208:211], v[4:7]
	v_mfma_f32_16x16x32_bf16 v[0:3], v[168:171], v[208:211], v[0:3]
	v_mfma_f32_16x16x32_bf16 v[52:55], v[148:151], v[180:183], v[52:55]
	v_mfma_f32_16x16x32_bf16 v[48:51], v[172:175], v[180:183], v[48:51]
	v_mfma_f32_16x16x32_bf16 v[36:39], v[148:151], v[196:199], v[36:39]
	v_mfma_f32_16x16x32_bf16 v[32:35], v[172:175], v[196:199], v[32:35]
	v_mfma_f32_16x16x32_bf16 v[20:23], v[148:151], v[204:207], v[20:23]
	v_mfma_f32_16x16x32_bf16 v[16:19], v[172:175], v[204:207], v[16:19]
	v_mfma_f32_16x16x32_bf16 v[4:7], v[148:151], v[212:215], v[4:7]
	v_mfma_f32_16x16x32_bf16 v[0:3], v[172:175], v[212:215], v[0:3]
	s_setprio 0
	s_barrier
	s_add_i32 s61, 0, 0x18000
	s_add_i32 s62, 0, 0x1c000
	v_add_u32_e32 v140, s61, v188
	v_add_u32_e32 v172, s62, v188
	ds_read_b128 v[128:131], v140
	ds_read_b128 v[132:135], v140 offset:1024
	ds_read_b128 v[136:139], v140 offset:2048
	ds_read_b128 v[140:143], v140 offset:3072
	ds_read_b128 v[144:147], v172
	ds_read_b128 v[148:151], v172 offset:1024
	ds_read_b128 v[168:171], v172 offset:2048
	ds_read_b128 v[172:175], v172 offset:3072
	s_add_u32 s28, s36, 0xb0000
	s_addc_u32 s29, s37, 0
	s_mov_b32 m0, s46
	ds_read_b128 v[176:179], v191 offset:32768
	ds_read_b128 v[180:183], v191 offset:33792
	ds_read_b128 v[192:195], v191 offset:34816
	ds_read_b128 v[196:199], v191 offset:35840
	ds_read_b128 v[200:203], v191 offset:36864
	ds_read_b128 v[204:207], v191 offset:37888
	ds_read_b128 v[208:211], v191 offset:38912
	ds_read_b128 v[212:215], v191 offset:39936
	global_load_lds_dwordx4 v152, s[28:29]
	v_lshl_add_u64 v[222:223], s[28:29], 0, v[156:157]
	s_mov_b32 m0, s47
	s_nop 0
	global_load_lds_dwordx4 v[222:223], off
	s_waitcnt vmcnt(8)
	s_waitcnt lgkmcnt(0)
	s_barrier
	s_setprio 1
	s_waitcnt lgkmcnt(0)
	v_mfma_f32_16x16x32_bf16 v[124:127], v[128:131], v[176:179], v[124:127]
	v_mfma_f32_16x16x32_bf16 v[120:123], v[136:139], v[176:179], v[120:123]
	v_mfma_f32_16x16x32_bf16 v[108:111], v[128:131], v[192:195], v[108:111]
	v_mfma_f32_16x16x32_bf16 v[104:107], v[136:139], v[192:195], v[104:107]
	v_mfma_f32_16x16x32_bf16 v[92:95], v[128:131], v[200:203], v[92:95]
	v_mfma_f32_16x16x32_bf16 v[88:91], v[136:139], v[200:203], v[88:91]
	v_mfma_f32_16x16x32_bf16 v[76:79], v[128:131], v[208:211], v[76:79]
	v_mfma_f32_16x16x32_bf16 v[72:75], v[136:139], v[208:211], v[72:75]
	v_mfma_f32_16x16x32_bf16 v[124:127], v[132:135], v[180:183], v[124:127]
	v_mfma_f32_16x16x32_bf16 v[120:123], v[140:143], v[180:183], v[120:123]
	v_mfma_f32_16x16x32_bf16 v[108:111], v[132:135], v[196:199], v[108:111]
	v_mfma_f32_16x16x32_bf16 v[104:107], v[140:143], v[196:199], v[104:107]
	v_mfma_f32_16x16x32_bf16 v[92:95], v[132:135], v[204:207], v[92:95]
	v_mfma_f32_16x16x32_bf16 v[88:91], v[140:143], v[204:207], v[88:91]
	v_mfma_f32_16x16x32_bf16 v[76:79], v[132:135], v[212:215], v[76:79]
	v_mfma_f32_16x16x32_bf16 v[72:75], v[140:143], v[212:215], v[72:75]
	s_setprio 0
	s_setprio 1
	v_mfma_f32_16x16x32_bf16 v[116:119], v[144:147], v[176:179], v[116:119]
	v_mfma_f32_16x16x32_bf16 v[112:115], v[168:171], v[176:179], v[112:115]
	v_mfma_f32_16x16x32_bf16 v[100:103], v[144:147], v[192:195], v[100:103]
	v_mfma_f32_16x16x32_bf16 v[96:99], v[168:171], v[192:195], v[96:99]
	v_mfma_f32_16x16x32_bf16 v[84:87], v[144:147], v[200:203], v[84:87]
	v_mfma_f32_16x16x32_bf16 v[80:83], v[168:171], v[200:203], v[80:83]
	v_mfma_f32_16x16x32_bf16 v[68:71], v[144:147], v[208:211], v[68:71]
	v_mfma_f32_16x16x32_bf16 v[64:67], v[168:171], v[208:211], v[64:67]
	v_mfma_f32_16x16x32_bf16 v[116:119], v[148:151], v[180:183], v[116:119]
	v_mfma_f32_16x16x32_bf16 v[112:115], v[172:175], v[180:183], v[112:115]
	v_mfma_f32_16x16x32_bf16 v[100:103], v[148:151], v[196:199], v[100:103]
	v_mfma_f32_16x16x32_bf16 v[96:99], v[172:175], v[196:199], v[96:99]
	v_mfma_f32_16x16x32_bf16 v[84:87], v[148:151], v[204:207], v[84:87]
	v_mfma_f32_16x16x32_bf16 v[80:83], v[172:175], v[204:207], v[80:83]
	v_mfma_f32_16x16x32_bf16 v[68:71], v[148:151], v[212:215], v[68:71]
	v_mfma_f32_16x16x32_bf16 v[64:67], v[172:175], v[212:215], v[64:67]
	s_setprio 0
	s_barrier
; #define PG8_STAGE(bufoff, gbase, voff) do { _Pragma("unroll") for (int _i = 0; _i < 2; ++_i) \
;         __builtin_amdgcn_global_load_lds((const unsigned*)((const char*)(gbase) + (voff)[_i]), (PG8_LAS unsigned*)(lds + (bufoff) + ldsw + _i * 8192), 16, 0, 0); } while (0)
; #define PG8_LDA(dst, b, h) do { _Pragma("unroll") for (int m = 0; m < 4; ++m) _Pragma("unroll") for (int k = 0; k < 2; ++k) dst[m][k] = *(const PG8_LAS bf16x8*)(lds + PG8_SA(b, h) + aoff + m * 2048 + k * 1024); } while (0)
; #define PG8_MMA(ai, bj, At, Bt) do { __builtin_amdgcn_s_setprio(1); _Pragma("unroll") for (int m = 0; m < 4; ++m) _Pragma("unroll") for (int n = 0; n < 2; ++n) _Pragma("unroll") for (int k = 0; k < 2; ++k) \
;         acc[ai][bj][m][n] = mma16<F16>(Bt[n][k], At[m][k], acc[ai][bj][m][n]); __builtin_amdgcn_s_setprio(0); } while (0)
; #define PG8_WAIT_V(n) asm volatile("s_waitcnt vmcnt(" #n ")" ::: "memory")
; #define PG8_WAIT_L(n) asm volatile("s_waitcnt lgkmcnt(" #n ")" ::: "memory")
; #define PG8_BAR __builtin_amdgcn_s_barrier()
; #define PG8_SCHED __builtin_amdgcn_sched_barrier(0)
; template <class Epi, class Sched, bool ALIGN_EPI = false, bool SP2 = false, bool F16 = false>
; __device__ __forceinline__ void gemm_phase(PG8_LAS unsigned char* lds, const Gemm g, const Sched& S, const Epi& E, const int wid_in) {
;     ...
;             PG8_LDA(At, 1, 1); PG8_STAGE(PG8_SB(1, 0), b3, voffB); PG8_STAGE(PG8_SB(1, 1), b3 + hstep, voffB); PG8_STAGE(PG8_SA(1, 0), a3, voffA);
;             PG8_WAIT_V(8); PG8_WAIT_L(0); PG8_BAR; PG8_MMA(1, 0, At, B0); PG8_MMA(1, 1, At, B1); PG8_BAR; PG8_SCHED;
	s_add_i32 s28, s61, s68
	v_lshl_add_u64 v[184:185], v[184:185], 0, s[24:25]
	s_mov_b32 m0, s28
	ds_read_b128 v[176:179], v191 offset:49152
	ds_read_b128 v[180:183], v191 offset:50176
	ds_read_b128 v[192:195], v191 offset:51200
	ds_read_b128 v[196:199], v191 offset:52224
	ds_read_b128 v[200:203], v191 offset:53248
	ds_read_b128 v[204:207], v191 offset:54272
	ds_read_b128 v[208:211], v191 offset:55296
	ds_read_b128 v[212:215], v191 offset:56320
	global_load_lds_dwordx4 v[184:185], off
	s_add_i32 m0, s28, 0x2000
	s_add_u32 s28, s34, 0xb0080
	v_lshl_add_u64 v[184:185], v[216:217], 0, s[24:25]
	s_addc_u32 s29, s35, 0
	s_add_i32 s34, s62, s68
	global_load_lds_dwordx4 v[184:185], off
	s_mov_b32 m0, s34
	s_nop 0
	global_load_lds_dwordx4 v154, s[28:29]
	s_add_i32 m0, s34, 0x2000
	s_nop 0
	global_load_lds_dwordx4 v158, s[28:29]
	v_lshl_add_u64 v[184:185], v[218:219], 0, s[24:25]
	s_mov_b32 m0, s75
	s_nop 0
	global_load_lds_dwordx4 v[184:185], off
	v_lshl_add_u64 v[184:185], v[220:221], 0, s[24:25]
	s_mov_b32 m0, s48
	s_nop 0
	global_load_lds_dwordx4 v[184:185], off
	s_waitcnt vmcnt(8)
	s_waitcnt lgkmcnt(0)
	s_barrier
	s_setprio 1
	s_waitcnt lgkmcnt(0)
	v_mfma_f32_16x16x32_bf16 v[60:63], v[128:131], v[176:179], v[60:63]
	v_mfma_f32_16x16x32_bf16 v[56:59], v[136:139], v[176:179], v[56:59]
	v_mfma_f32_16x16x32_bf16 v[44:47], v[128:131], v[192:195], v[44:47]
	v_mfma_f32_16x16x32_bf16 v[40:43], v[136:139], v[192:195], v[40:43]
	v_mfma_f32_16x16x32_bf16 v[28:31], v[128:131], v[200:203], v[28:31]
	v_mfma_f32_16x16x32_bf16 v[24:27], v[136:139], v[200:203], v[24:27]
	v_mfma_f32_16x16x32_bf16 v[12:15], v[128:131], v[208:211], v[12:15]
	v_mfma_f32_16x16x32_bf16 v[8:11], v[136:139], v[208:211], v[8:11]
	v_mfma_f32_16x16x32_bf16 v[60:63], v[132:135], v[180:183], v[60:63]
	v_mfma_f32_16x16x32_bf16 v[56:59], v[140:143], v[180:183], v[56:59]
	v_mfma_f32_16x16x32_bf16 v[44:47], v[132:135], v[196:199], v[44:47]
	v_mfma_f32_16x16x32_bf16 v[40:43], v[140:143], v[196:199], v[40:43]
	v_mfma_f32_16x16x32_bf16 v[28:31], v[132:135], v[204:207], v[28:31]
	v_mfma_f32_16x16x32_bf16 v[24:27], v[140:143], v[204:207], v[24:27]
	v_mfma_f32_16x16x32_bf16 v[12:15], v[132:135], v[212:215], v[12:15]
	v_mfma_f32_16x16x32_bf16 v[8:11], v[140:143], v[212:215], v[8:11]
	s_setprio 0
	s_setprio 1
	v_mfma_f32_16x16x32_bf16 v[52:55], v[144:147], v[176:179], v[52:55]
	v_mfma_f32_16x16x32_bf16 v[48:51], v[168:171], v[176:179], v[48:51]
	v_mfma_f32_16x16x32_bf16 v[36:39], v[144:147], v[192:195], v[36:39]
	v_mfma_f32_16x16x32_bf16 v[32:35], v[168:171], v[192:195], v[32:35]
	v_mfma_f32_16x16x32_bf16 v[20:23], v[144:147], v[200:203], v[20:23]
	v_mfma_f32_16x16x32_bf16 v[16:19], v[168:171], v[200:203], v[16:19]
	v_mfma_f32_16x16x32_bf16 v[4:7], v[144:147], v[208:211], v[4:7]
	v_mfma_f32_16x16x32_bf16 v[0:3], v[168:171], v[208:211], v[0:3]
	v_mfma_f32_16x16x32_bf16 v[52:55], v[148:151], v[180:183], v[52:55]
	v_mfma_f32_16x16x32_bf16 v[48:51], v[172:175], v[180:183], v[48:51]
	v_mfma_f32_16x16x32_bf16 v[36:39], v[148:151], v[196:199], v[36:39]
	v_mfma_f32_16x16x32_bf16 v[32:35], v[172:175], v[196:199], v[32:35]
	v_mfma_f32_16x16x32_bf16 v[20:23], v[148:151], v[204:207], v[20:23]
	v_mfma_f32_16x16x32_bf16 v[16:19], v[172:175], v[204:207], v[16:19]
	v_mfma_f32_16x16x32_bf16 v[4:7], v[148:151], v[212:215], v[4:7]
	v_mfma_f32_16x16x32_bf16 v[0:3], v[172:175], v[212:215], v[0:3]
	s_setprio 0
	s_barrier
	s_add_i32 s60, s60, 2
	s_add_u32 s43, s43, 0x100
	s_addc_u32 s59, s59, 0
	s_cmp_gt_u32 s60, 41
	s_mov_b64 s[28:29], s[30:31]
	s_cbranch_scc0 .LBB0_716
	s_and_b64 vcc, exec, s[16:17]
	s_cbranch_vccz .LBB0_719
	s_barrier

; #define PG8_STAGE(bufoff, gbase, voff) do { _Pragma("unroll") for (int _i = 0; _i < 2; ++_i) \
;         __builtin_amdgcn_global_load_lds((const unsigned*)((const char*)(gbase) + (voff)[_i]), (PG8_LAS unsigned*)(lds + (bufoff) + ldsw + _i * 8192), 16, 0, 0); } while (0)
; #define PG8_WAIT_V(n) asm volatile("s_waitcnt vmcnt(" #n ")" ::: "memory")
; #define PG8_BAR __builtin_amdgcn_s_barrier()
; template <class Epi, class Sched, bool ALIGN_EPI = false, bool SP2 = false, bool F16 = false>
; __device__ __forceinline__ void gemm_phase(PG8_LAS unsigned char* lds, const Gemm g, const Sched& S, const Epi& E, const int wid_in) {
;     ...
;     const int wid = wid_in, lane = lane_, tid = wid * 64 + lane, wr = wid >> 2, wc = wid & 3, fr = lane & 15, fq = lane >> 4;
;     const int K = g.K, nt = K / BK;
;     unsigned voffA[2], voffB[2];
; #pragma unroll
;     for (int i = 0; i < 2; ++i) { int R, C; stage_rc(tid * 16 + i * 8192, R, C); const int Rb = Epi::PERM ? ((R & ~31) + perm32(R & 31)) : R;
;         voffA[i] = (unsigned)(R * K + C) * 2u; voffB[i] = (unsigned)(Rb * K + C) * 2u; }
;     const size_t kstep = (size_t)(BK * 2);
;     const size_t hstep = (size_t)HALF * K * 2;
;     const size_t tstep = 2 * hstep;
;     const unsigned ldsw = (unsigned)wid * 1024u;
;     const int aoff = lds_byte(wr * 64 + fr, fq * 8), boff = lds_byte(wc * 32 + fr, fq * 8);
;     ...
;         PG8_STAGE(PG8_SB(1, 0), cB + kstep, voffB); PG8_STAGE(PG8_SA(1, 0), cA + kstep, voffA); PG8_STAGE(PG8_SB(1, 1), cB + hstep + kstep, voffB);
;         PG8_WAIT_V(6); PG8_BAR;
.LBB0_802:
	s_add_u32 s18, s8, 0x7400000
	s_addc_u32 s19, s9, 0
	s_add_u32 s20, s8, 0xf400000
	s_addc_u32 s21, s9, 0
	s_add_u32 s22, s8, 0x15700000
	s_addc_u32 s23, s9, 0
	s_add_u32 s24, s8, 0x15600000
	s_mov_b64 s[26:27], 0x80
	s_addc_u32 s25, s9, 0
	s_add_i32 m0, s74, 0x18000
	v_lshl_add_u64 v[6:7], v[6:7], 0, s[26:27]
	s_waitcnt vmcnt(2)
	s_barrier
	global_load_lds_dwordx4 v[6:7], off
	v_lshl_add_u64 v[4:5], v[4:5], 0, s[26:27]
	s_add_i32 m0, s74, 0x1a000
	s_add_i32 s60, s74, 0xa000
	global_load_lds_dwordx4 v[4:5], off
	v_lshl_add_u64 v[0:1], v[0:1], 0, s[26:27]
	s_mov_b32 m0, s75
	s_add_u32 s8, s48, 0x40080
	global_load_lds_dwordx4 v[0:1], off
	v_lshl_add_u64 v[0:1], v[2:3], 0, s[26:27]
	s_mov_b32 m0, s60
	s_addc_u32 s9, s49, 0
	global_load_lds_dwordx4 v[0:1], off
	s_add_i32 m0, s74, 0x1c000
	s_nop 0
	global_load_lds_dwordx4 v198, s[8:9]
	s_add_i32 m0, s74, 0x1e000
	v_and_b32_e32 v232, 15, v8
	global_load_lds_dwordx4 v202, s[8:9]
	v_or_b32_e32 v0, s70, v232
	v_lshlrev_b32_e32 v1, 6, v0
	v_and_b32_e32 v2, 48, v8
	s_movk_i32 s8, 0x3c0
	v_and_b32_e32 v3, 0xfffffc00, v12
	v_lshlrev_b32_e32 v0, 2, v0
	v_and_or_b32 v1, v1, s8, v2
	v_add_u32_e32 v4, s73, v3
	v_and_b32_e32 v0, 32, v0
	v_bitop3_b32 v0, v1, v4, v0 bitop3:0xde
	v_lshl_or_b32 v1, v232, 6, v2
	v_add_u32_e32 v2, s72, v3
	v_lshlrev_b32_e32 v3, 2, v8
	v_and_b32_e32 v3, 32, v3
	v_bitop3_b32 v234, v1, v2, v3 bitop3:0xde
	v_lshlrev_b32_e32 v1, 14, v9
	v_and_b32_e32 v1, 0xffff8000, v1
	v_lshl_add_u32 v1, v10, 11, v1
	v_and_b32_e32 v2, 1, v9
	v_lshl_or_b32 v1, v2, 6, v1
	v_lshl_add_u32 v204, v11, 1, v1
	v_lshlrev_b32_e32 v1, 14, v13
	v_and_b32_e32 v1, 0xffff8000, v1
	s_waitcnt vmcnt(6)
	v_lshl_add_u32 v1, v14, 11, v1
	v_and_b32_e32 v2, 1, v13
	v_lshl_or_b32 v1, v2, 6, v1
	s_add_i32 s64, 0, 0x10000
	s_add_i32 s65, 0, 0x14000
	v_ashrrev_i32_e32 v233, 4, v8
	s_ashr_i32 s61, s38, 31
	s_mov_b32 s62, s38
	s_ashr_i32 s63, s52, 31
	v_mov_b32_e32 v205, v199
	v_lshl_add_u32 v206, v15, 1, v1
	v_mov_b32_e32 v207, v199
	v_mov_b64_e32 v[208:209], 0x100
	v_mov_b64_e32 v[210:211], 0xff
	v_add_u32_e32 v235, s64, v234
	v_add_u32_e32 v236, s65, v234
	v_add_u32_e32 v237, 0, v0
	v_mov_b32_e32 v238, 0x358637bd
	s_mov_b32 s66, 0
	s_barrier
	s_branch .LBB0_805

; #define PG8_STAGE(bufoff, gbase, voff) do { _Pragma("unroll") for (int _i = 0; _i < 2; ++_i) \
;         __builtin_amdgcn_global_load_lds((const unsigned*)((const char*)(gbase) + (voff)[_i]), (PG8_LAS unsigned*)(lds + (bufoff) + ldsw + _i * 8192), 16, 0, 0); } while (0)
; #define PG8_LDA(dst, b, h) do { _Pragma("unroll") for (int m = 0; m < 4; ++m) _Pragma("unroll") for (int k = 0; k < 2; ++k) dst[m][k] = *(const PG8_LAS bf16x8*)(lds + PG8_SA(b, h) + aoff + m * 2048 + k * 1024); } while (0)
; #define PG8_LDB(dst, b, h) do { _Pragma("unroll") for (int n = 0; n < 2; ++n) _Pragma("unroll") for (int k = 0; k < 2; ++k) dst[n][k] = *(const PG8_LAS bf16x8*)(lds + PG8_SB(b, h) + boff + n * 2048 + k * 1024); } while (0)
; #define PG8_MMA(ai, bj, At, Bt) do { __builtin_amdgcn_s_setprio(1); _Pragma("unroll") for (int m = 0; m < 4; ++m) _Pragma("unroll") for (int n = 0; n < 2; ++n) _Pragma("unroll") for (int k = 0; k < 2; ++k) \
;         acc[ai][bj][m][n] = mma16<F16>(Bt[n][k], At[m][k], acc[ai][bj][m][n]); __builtin_amdgcn_s_setprio(0); } while (0)
; #define PG8_WAIT_V(n) asm volatile("s_waitcnt vmcnt(" #n ")" ::: "memory")
; #define PG8_WAIT_L(n) asm volatile("s_waitcnt lgkmcnt(" #n ")" ::: "memory")
; #define PG8_BAR __builtin_amdgcn_s_barrier()
; #define PG8_SCHED __builtin_amdgcn_sched_barrier(0)
; template <class Epi, class Sched, bool ALIGN_EPI = false, bool SP2 = false, bool F16 = false>
; __device__ __forceinline__ void gemm_phase(PG8_LAS unsigned char* lds, const Gemm g, const Sched& S, const Epi& E, const int wid_in) {
;     ...
;         for (int t = 0; t < nt; t += 2) {
;             const bool last = (t == nt - 2);
;             const char* a1 = cA + (size_t)(t + 1) * kstep;
;             const char* a2 = last ? nA : cA + (size_t)(t + 2) * kstep; const char* b2 = last ? nB : cB + (size_t)(t + 2) * kstep;
;             const char* a3 = a2 + kstep; const char* b3 = b2 + kstep;
;             if (last && has_next) S.a_ready(nxt);
;             if constexpr (SP2) {
;             PG8_LDB(B0, 0, 0); PG8_LDB(B1, 0, 1); PG8_SCHED; PG8_LDA(At, 0, 0); PG8_STAGE(PG8_SA(1, 1), a1 + hstep, voffA);
;             PG8_WAIT_V(8); PG8_WAIT_L(0); PG8_BAR; PG8_MMA(0, 0, At, B0); PG8_MMA(0, 1, At, B1); PG8_BAR; PG8_SCHED;
;             PG8_LDA(At, 0, 1); PG8_STAGE(PG8_SB(0, 0), b2, voffB); PG8_STAGE(PG8_SB(0, 1), b2 + hstep, voffB); PG8_STAGE(PG8_SA(0, 0), a2, voffA);
.LBB0_812:
	ds_read_b128 v[112:115], v235
	ds_read_b128 v[116:119], v235 offset:1024
	ds_read_b128 v[128:131], v235 offset:2048
	ds_read_b128 v[132:135], v235 offset:3072
	ds_read_b128 v[144:147], v236
	ds_read_b128 v[148:151], v236 offset:1024
	ds_read_b128 v[152:155], v236 offset:2048
	ds_read_b128 v[156:159], v236 offset:3072
	s_add_u32 s43, s46, 0xfffc0080
	s_addc_u32 s45, s47, -1
	s_cmp_eq_u32 s42, 12
	s_cselect_b32 s51, s14, s45
	s_cselect_b32 s50, s15, s43
	s_cselect_b32 s49, s29, s41
	s_cselect_b32 s48, s31, s40
	s_add_i32 m0, s74, 0xc000
	ds_read_b128 v[160:163], v237
	ds_read_b128 v[164:167], v237 offset:1024
	ds_read_b128 v[168:171], v237 offset:2048
	ds_read_b128 v[172:175], v237 offset:3072
	ds_read_b128 v[176:179], v237 offset:4096
	ds_read_b128 v[180:183], v237 offset:5120
	ds_read_b128 v[184:187], v237 offset:6144
	ds_read_b128 v[188:191], v237 offset:7168
	global_load_lds_dwordx4 v204, s[46:47]
	s_add_i32 m0, s74, 0xe000
	s_nop 0
	global_load_lds_dwordx4 v206, s[46:47]
	s_waitcnt vmcnt(8)
	s_waitcnt lgkmcnt(0)
	s_barrier
	s_setprio 1
	s_waitcnt lgkmcnt(0)
	v_mfma_f32_16x16x32_f16 v[140:143], v[112:115], v[160:163], v[140:143]
	v_mfma_f32_16x16x32_f16 v[136:139], v[128:131], v[160:163], v[136:139]
	v_mfma_f32_16x16x32_f16 v[108:111], v[112:115], v[168:171], v[108:111]
	v_mfma_f32_16x16x32_f16 v[104:107], v[128:131], v[168:171], v[104:107]
	v_mfma_f32_16x16x32_f16 v[92:95], v[112:115], v[176:179], v[92:95]
	v_mfma_f32_16x16x32_f16 v[88:91], v[128:131], v[176:179], v[88:91]
	v_mfma_f32_16x16x32_f16 v[76:79], v[112:115], v[184:187], v[76:79]
	v_mfma_f32_16x16x32_f16 v[72:75], v[128:131], v[184:187], v[72:75]
	v_mfma_f32_16x16x32_f16 v[140:143], v[116:119], v[164:167], v[140:143]
	v_mfma_f32_16x16x32_f16 v[136:139], v[132:135], v[164:167], v[136:139]
	v_mfma_f32_16x16x32_f16 v[108:111], v[116:119], v[172:175], v[108:111]
	v_mfma_f32_16x16x32_f16 v[104:107], v[132:135], v[172:175], v[104:107]
	v_mfma_f32_16x16x32_f16 v[92:95], v[116:119], v[180:183], v[92:95]
	v_mfma_f32_16x16x32_f16 v[88:91], v[132:135], v[180:183], v[88:91]
	v_mfma_f32_16x16x32_f16 v[76:79], v[116:119], v[188:191], v[76:79]
	v_mfma_f32_16x16x32_f16 v[72:75], v[132:135], v[188:191], v[72:75]
	s_setprio 0
	s_setprio 1
	v_mfma_f32_16x16x32_f16 v[124:127], v[144:147], v[160:163], v[124:127]
	v_mfma_f32_16x16x32_f16 v[120:123], v[152:155], v[160:163], v[120:123]
	v_mfma_f32_16x16x32_f16 v[100:103], v[144:147], v[168:171], v[100:103]
	v_mfma_f32_16x16x32_f16 v[96:99], v[152:155], v[168:171], v[96:99]
	v_mfma_f32_16x16x32_f16 v[84:87], v[144:147], v[176:179], v[84:87]
	v_mfma_f32_16x16x32_f16 v[80:83], v[152:155], v[176:179], v[80:83]
	v_mfma_f32_16x16x32_f16 v[68:71], v[144:147], v[184:187], v[68:71]
	v_mfma_f32_16x16x32_f16 v[64:67], v[152:155], v[184:187], v[64:67]
	v_mfma_f32_16x16x32_f16 v[124:127], v[148:151], v[164:167], v[124:127]
	v_mfma_f32_16x16x32_f16 v[120:123], v[156:159], v[164:167], v[120:123]
	v_mfma_f32_16x16x32_f16 v[100:103], v[148:151], v[172:175], v[100:103]
	v_mfma_f32_16x16x32_f16 v[96:99], v[156:159], v[172:175], v[96:99]
	v_mfma_f32_16x16x32_f16 v[84:87], v[148:151], v[180:183], v[84:87]
	v_mfma_f32_16x16x32_f16 v[80:83], v[156:159], v[180:183], v[80:83]
	v_mfma_f32_16x16x32_f16 v[68:71], v[148:151], v[188:191], v[68:71]
	v_mfma_f32_16x16x32_f16 v[64:67], v[156:159], v[188:191], v[64:67]
	s_setprio 0
	s_barrier
	s_add_i32 s43, s64, s68
	v_lshl_add_u64 v[192:193], s[48:49], 0, v[198:199]
	s_mov_b32 m0, s43
	ds_read_b128 v[160:163], v237 offset:16384
	ds_read_b128 v[164:167], v237 offset:17408
	ds_read_b128 v[168:171], v237 offset:18432
	ds_read_b128 v[172:175], v237 offset:19456
	ds_read_b128 v[176:179], v237 offset:20480
	ds_read_b128 v[180:183], v237 offset:21504
	ds_read_b128 v[184:187], v237 offset:22528
	ds_read_b128 v[188:191], v237 offset:23552
	global_load_lds_dwordx4 v[192:193], off
	s_add_i32 m0, s43, 0x2000
	s_add_u32 s86, s48, 0x40000
	v_lshl_add_u64 v[194:195], s[48:49], 0, v[202:203]
	s_addc_u32 s87, s49, 0
	s_add_i32 s43, s65, s68
	global_load_lds_dwordx4 v[194:195], off
	s_mov_b32 m0, s43
	v_lshl_add_u64 v[214:215], s[50:51], 0, v[200:201]
	global_load_lds_dwordx4 v198, s[86:87]
	s_add_i32 m0, s43, 0x2000
	s_nop 0
	global_load_lds_dwordx4 v202, s[86:87]
	v_lshl_add_u64 v[212:213], s[50:51], 0, v[196:197]
	s_mov_b32 m0, s74
	s_nop 0
	global_load_lds_dwordx4 v[212:213], off
	s_mov_b32 m0, s55
	s_nop 0
	global_load_lds_dwordx4 v[214:215], off
	s_waitcnt vmcnt(8)
	s_waitcnt lgkmcnt(0)
	s_barrier
	s_setprio 1
	s_waitcnt lgkmcnt(0)
	v_mfma_f32_16x16x32_f16 v[60:63], v[112:115], v[160:163], v[60:63]
	v_mfma_f32_16x16x32_f16 v[56:59], v[128:131], v[160:163], v[56:59]
	v_mfma_f32_16x16x32_f16 v[44:47], v[112:115], v[168:171], v[44:47]
	v_mfma_f32_16x16x32_f16 v[40:43], v[128:131], v[168:171], v[40:43]
	v_mfma_f32_16x16x32_f16 v[28:31], v[112:115], v[176:179], v[28:31]
	v_mfma_f32_16x16x32_f16 v[24:27], v[128:131], v[176:179], v[24:27]
	v_mfma_f32_16x16x32_f16 v[12:15], v[112:115], v[184:187], v[12:15]
	v_mfma_f32_16x16x32_f16 v[8:11], v[128:131], v[184:187], v[8:11]
	v_mfma_f32_16x16x32_f16 v[60:63], v[116:119], v[164:167], v[60:63]
	v_mfma_f32_16x16x32_f16 v[56:59], v[132:135], v[164:167], v[56:59]
	v_mfma_f32_16x16x32_f16 v[44:47], v[116:119], v[172:175], v[44:47]
	v_mfma_f32_16x16x32_f16 v[40:43], v[132:135], v[172:175], v[40:43]
	v_mfma_f32_16x16x32_f16 v[28:31], v[116:119], v[180:183], v[28:31]
	v_mfma_f32_16x16x32_f16 v[24:27], v[132:135], v[180:183], v[24:27]
	v_mfma_f32_16x16x32_f16 v[12:15], v[116:119], v[188:191], v[12:15]
	v_mfma_f32_16x16x32_f16 v[8:11], v[132:135], v[188:191], v[8:11]
	s_setprio 0
	s_setprio 1
	v_mfma_f32_16x16x32_f16 v[52:55], v[144:147], v[160:163], v[52:55]
	v_mfma_f32_16x16x32_f16 v[48:51], v[152:155], v[160:163], v[48:51]
	v_mfma_f32_16x16x32_f16 v[36:39], v[144:147], v[168:171], v[36:39]
	v_mfma_f32_16x16x32_f16 v[32:35], v[152:155], v[168:171], v[32:35]
	v_mfma_f32_16x16x32_f16 v[20:23], v[144:147], v[176:179], v[20:23]
	v_mfma_f32_16x16x32_f16 v[16:19], v[152:155], v[176:179], v[16:19]
	v_mfma_f32_16x16x32_f16 v[4:7], v[144:147], v[184:187], v[4:7]
	v_mfma_f32_16x16x32_f16 v[0:3], v[152:155], v[184:187], v[0:3]
	v_mfma_f32_16x16x32_f16 v[52:55], v[148:151], v[164:167], v[52:55]
	v_mfma_f32_16x16x32_f16 v[48:51], v[156:159], v[164:167], v[48:51]
	v_mfma_f32_16x16x32_f16 v[36:39], v[148:151], v[172:175], v[36:39]
	v_mfma_f32_16x16x32_f16 v[32:35], v[156:159], v[172:175], v[32:35]
	v_mfma_f32_16x16x32_f16 v[20:23], v[148:151], v[180:183], v[20:23]
	v_mfma_f32_16x16x32_f16 v[16:19], v[156:159], v[180:183], v[16:19]
	v_mfma_f32_16x16x32_f16 v[4:7], v[148:151], v[188:191], v[4:7]
	v_mfma_f32_16x16x32_f16 v[0:3], v[156:159], v[188:191], v[0:3]
	s_setprio 0
	s_barrier
; #define PG8_STAGE(bufoff, gbase, voff) do { _Pragma("unroll") for (int _i = 0; _i < 2; ++_i) \
;         __builtin_amdgcn_global_load_lds((const unsigned*)((const char*)(gbase) + (voff)[_i]), (PG8_LAS unsigned*)(lds + (bufoff) + ldsw + _i * 8192), 16, 0, 0); } while (0)
; #define PG8_LDA(dst, b, h) do { _Pragma("unroll") for (int m = 0; m < 4; ++m) _Pragma("unroll") for (int k = 0; k < 2; ++k) dst[m][k] = *(const PG8_LAS bf16x8*)(lds + PG8_SA(b, h) + aoff + m * 2048 + k * 1024); } while (0)
; #define PG8_LDB(dst, b, h) do { _Pragma("unroll") for (int n = 0; n < 2; ++n) _Pragma("unroll") for (int k = 0; k < 2; ++k) dst[n][k] = *(const PG8_LAS bf16x8*)(lds + PG8_SB(b, h) + boff + n * 2048 + k * 1024); } while (0)
; #define PG8_MMA(ai, bj, At, Bt) do { __builtin_amdgcn_s_setprio(1); _Pragma("unroll") for (int m = 0; m < 4; ++m) _Pragma("unroll") for (int n = 0; n < 2; ++n) _Pragma("unroll") for (int k = 0; k < 2; ++k) \
;         acc[ai][bj][m][n] = mma16<F16>(Bt[n][k], At[m][k], acc[ai][bj][m][n]); __builtin_amdgcn_s_setprio(0); } while (0)
; #define PG8_WAIT_V(n) asm volatile("s_waitcnt vmcnt(" #n ")" ::: "memory")
; #define PG8_WAIT_L(n) asm volatile("s_waitcnt lgkmcnt(" #n ")" ::: "memory")
; #define PG8_BAR __builtin_amdgcn_s_barrier()
; #define PG8_SCHED __builtin_amdgcn_sched_barrier(0)
; template <class Epi, class Sched, bool ALIGN_EPI = false, bool SP2 = false, bool F16 = false>
; __device__ __forceinline__ void gemm_phase(PG8_LAS unsigned char* lds, const Gemm g, const Sched& S, const Epi& E, const int wid_in) {
;     ...
;         for (int t = 0; t < nt; t += 2) {
;     ...
;             PG8_LDB(B0, 1, 0); PG8_LDB(B1, 1, 1); PG8_SCHED; PG8_LDA(At, 1, 0); PG8_STAGE(PG8_SA(0, 1), a2 + hstep, voffA);
;             PG8_WAIT_V(8); PG8_WAIT_L(0); PG8_BAR; PG8_MMA(0, 0, At, B0); PG8_MMA(0, 1, At, B1); PG8_BAR; PG8_SCHED;
;             PG8_LDA(At, 1, 1); PG8_STAGE(PG8_SB(1, 0), b3, voffB); PG8_STAGE(PG8_SB(1, 1), b3 + hstep, voffB); PG8_STAGE(PG8_SA(1, 0), a3, voffA);
;             PG8_WAIT_V(8); PG8_WAIT_L(0); PG8_BAR; PG8_MMA(1, 0, At, B0); PG8_MMA(1, 1, At, B1); PG8_BAR; PG8_SCHED;
	s_add_i32 s43, 0, 0x18000
	s_add_i32 s45, 0, 0x1c000
	v_add_u32_e32 v132, s43, v234
	v_add_u32_e32 v156, s45, v234
	ds_read_b128 v[112:115], v132
	ds_read_b128 v[116:119], v132 offset:1024
	ds_read_b128 v[128:131], v132 offset:2048
	ds_read_b128 v[132:135], v132 offset:3072
	ds_read_b128 v[144:147], v156
	ds_read_b128 v[148:151], v156 offset:1024
	ds_read_b128 v[152:155], v156 offset:2048
	ds_read_b128 v[156:159], v156 offset:3072
	s_add_u32 s50, s50, 0x40000
	s_addc_u32 s51, s51, 0
	s_mov_b32 m0, s58
	ds_read_b128 v[160:163], v237 offset:32768
	ds_read_b128 v[164:167], v237 offset:33792
	ds_read_b128 v[168:171], v237 offset:34816
	ds_read_b128 v[172:175], v237 offset:35840
	ds_read_b128 v[176:179], v237 offset:36864
	ds_read_b128 v[180:183], v237 offset:37888
	ds_read_b128 v[184:187], v237 offset:38912
	ds_read_b128 v[188:191], v237 offset:39936
	global_load_lds_dwordx4 v196, s[50:51]
	s_mov_b32 m0, s59
	s_nop 0
	global_load_lds_dwordx4 v200, s[50:51]
	s_waitcnt vmcnt(8)
	s_waitcnt lgkmcnt(0)
	s_barrier
	s_setprio 1
	s_waitcnt lgkmcnt(0)
	v_mfma_f32_16x16x32_f16 v[140:143], v[112:115], v[160:163], v[140:143]
	v_mfma_f32_16x16x32_f16 v[136:139], v[128:131], v[160:163], v[136:139]
	v_mfma_f32_16x16x32_f16 v[108:111], v[112:115], v[168:171], v[108:111]
	v_mfma_f32_16x16x32_f16 v[104:107], v[128:131], v[168:171], v[104:107]
	v_mfma_f32_16x16x32_f16 v[92:95], v[112:115], v[176:179], v[92:95]
	v_mfma_f32_16x16x32_f16 v[88:91], v[128:131], v[176:179], v[88:91]
	v_mfma_f32_16x16x32_f16 v[76:79], v[112:115], v[184:187], v[76:79]
	v_mfma_f32_16x16x32_f16 v[72:75], v[128:131], v[184:187], v[72:75]
	v_mfma_f32_16x16x32_f16 v[140:143], v[116:119], v[164:167], v[140:143]
	v_mfma_f32_16x16x32_f16 v[136:139], v[132:135], v[164:167], v[136:139]
	v_mfma_f32_16x16x32_f16 v[108:111], v[116:119], v[172:175], v[108:111]
	v_mfma_f32_16x16x32_f16 v[104:107], v[132:135], v[172:175], v[104:107]
	v_mfma_f32_16x16x32_f16 v[92:95], v[116:119], v[180:183], v[92:95]
	v_mfma_f32_16x16x32_f16 v[88:91], v[132:135], v[180:183], v[88:91]
	v_mfma_f32_16x16x32_f16 v[76:79], v[116:119], v[188:191], v[76:79]
	v_mfma_f32_16x16x32_f16 v[72:75], v[132:135], v[188:191], v[72:75]
	s_setprio 0
	s_setprio 1
	v_mfma_f32_16x16x32_f16 v[124:127], v[144:147], v[160:163], v[124:127]
	v_mfma_f32_16x16x32_f16 v[120:123], v[152:155], v[160:163], v[120:123]
	v_mfma_f32_16x16x32_f16 v[100:103], v[144:147], v[168:171], v[100:103]
	v_mfma_f32_16x16x32_f16 v[96:99], v[152:155], v[168:171], v[96:99]
	v_mfma_f32_16x16x32_f16 v[84:87], v[144:147], v[176:179], v[84:87]
	v_mfma_f32_16x16x32_f16 v[80:83], v[152:155], v[176:179], v[80:83]
	v_mfma_f32_16x16x32_f16 v[68:71], v[144:147], v[184:187], v[68:71]
	v_mfma_f32_16x16x32_f16 v[64:67], v[152:155], v[184:187], v[64:67]
	v_mfma_f32_16x16x32_f16 v[124:127], v[148:151], v[164:167], v[124:127]
	v_mfma_f32_16x16x32_f16 v[120:123], v[156:159], v[164:167], v[120:123]
	v_mfma_f32_16x16x32_f16 v[100:103], v[148:151], v[172:175], v[100:103]
	v_mfma_f32_16x16x32_f16 v[96:99], v[156:159], v[172:175], v[96:99]
	v_mfma_f32_16x16x32_f16 v[84:87], v[148:151], v[180:183], v[84:87]
	v_mfma_f32_16x16x32_f16 v[80:83], v[156:159], v[180:183], v[80:83]
	v_mfma_f32_16x16x32_f16 v[68:71], v[148:151], v[188:191], v[68:71]
	v_mfma_f32_16x16x32_f16 v[64:67], v[156:159], v[188:191], v[64:67]
	s_setprio 0
	s_barrier
	s_add_i32 s43, s43, s68
	v_lshl_add_u64 v[192:193], v[192:193], 0, s[26:27]
	s_mov_b32 m0, s43
	ds_read_b128 v[160:163], v237 offset:49152
	ds_read_b128 v[164:167], v237 offset:50176
	ds_read_b128 v[168:171], v237 offset:51200
	ds_read_b128 v[172:175], v237 offset:52224
	ds_read_b128 v[176:179], v237 offset:53248
	ds_read_b128 v[180:183], v237 offset:54272
	ds_read_b128 v[184:187], v237 offset:55296
	ds_read_b128 v[188:191], v237 offset:56320
	global_load_lds_dwordx4 v[192:193], off
	s_add_i32 m0, s43, 0x2000
	s_add_u32 s48, s48, 0x40080
	v_lshl_add_u64 v[192:193], v[194:195], 0, s[26:27]
	s_addc_u32 s49, s49, 0
	s_add_i32 s43, s45, s68
	global_load_lds_dwordx4 v[192:193], off
	s_mov_b32 m0, s43
	s_nop 0
	global_load_lds_dwordx4 v198, s[48:49]
	s_add_i32 m0, s43, 0x2000
	s_nop 0
	global_load_lds_dwordx4 v202, s[48:49]
	v_lshl_add_u64 v[192:193], v[212:213], 0, s[26:27]
	s_mov_b32 m0, s75
	s_nop 0
	global_load_lds_dwordx4 v[192:193], off
	v_lshl_add_u64 v[192:193], v[214:215], 0, s[26:27]
	s_mov_b32 m0, s60
	s_nop 0
	global_load_lds_dwordx4 v[192:193], off
	s_waitcnt vmcnt(8)
	s_waitcnt lgkmcnt(0)
	s_barrier
	s_setprio 1
	s_waitcnt lgkmcnt(0)
	v_mfma_f32_16x16x32_f16 v[60:63], v[112:115], v[160:163], v[60:63]
	v_mfma_f32_16x16x32_f16 v[56:59], v[128:131], v[160:163], v[56:59]
	v_mfma_f32_16x16x32_f16 v[44:47], v[112:115], v[168:171], v[44:47]
	v_mfma_f32_16x16x32_f16 v[40:43], v[128:131], v[168:171], v[40:43]
	v_mfma_f32_16x16x32_f16 v[28:31], v[112:115], v[176:179], v[28:31]
	v_mfma_f32_16x16x32_f16 v[24:27], v[128:131], v[176:179], v[24:27]
	v_mfma_f32_16x16x32_f16 v[12:15], v[112:115], v[184:187], v[12:15]
	v_mfma_f32_16x16x32_f16 v[8:11], v[128:131], v[184:187], v[8:11]
	v_mfma_f32_16x16x32_f16 v[60:63], v[116:119], v[164:167], v[60:63]
	v_mfma_f32_16x16x32_f16 v[56:59], v[132:135], v[164:167], v[56:59]
	v_mfma_f32_16x16x32_f16 v[44:47], v[116:119], v[172:175], v[44:47]
	v_mfma_f32_16x16x32_f16 v[40:43], v[132:135], v[172:175], v[40:43]
	v_mfma_f32_16x16x32_f16 v[28:31], v[116:119], v[180:183], v[28:31]
	v_mfma_f32_16x16x32_f16 v[24:27], v[132:135], v[180:183], v[24:27]
	v_mfma_f32_16x16x32_f16 v[12:15], v[116:119], v[188:191], v[12:15]
	v_mfma_f32_16x16x32_f16 v[8:11], v[132:135], v[188:191], v[8:11]
	s_setprio 0
	s_setprio 1
	v_mfma_f32_16x16x32_f16 v[52:55], v[144:147], v[160:163], v[52:55]
	v_mfma_f32_16x16x32_f16 v[48:51], v[152:155], v[160:163], v[48:51]
	v_mfma_f32_16x16x32_f16 v[36:39], v[144:147], v[168:171], v[36:39]
	v_mfma_f32_16x16x32_f16 v[32:35], v[152:155], v[168:171], v[32:35]
	v_mfma_f32_16x16x32_f16 v[20:23], v[144:147], v[176:179], v[20:23]
	v_mfma_f32_16x16x32_f16 v[16:19], v[152:155], v[176:179], v[16:19]
	v_mfma_f32_16x16x32_f16 v[4:7], v[144:147], v[184:187], v[4:7]
	v_mfma_f32_16x16x32_f16 v[0:3], v[152:155], v[184:187], v[0:3]
	v_mfma_f32_16x16x32_f16 v[52:55], v[148:151], v[164:167], v[52:55]
	v_mfma_f32_16x16x32_f16 v[48:51], v[156:159], v[164:167], v[48:51]
	v_mfma_f32_16x16x32_f16 v[36:39], v[148:151], v[172:175], v[36:39]
	v_mfma_f32_16x16x32_f16 v[32:35], v[156:159], v[172:175], v[32:35]
	v_mfma_f32_16x16x32_f16 v[20:23], v[148:151], v[180:183], v[20:23]
	v_mfma_f32_16x16x32_f16 v[16:19], v[156:159], v[180:183], v[16:19]
	v_mfma_f32_16x16x32_f16 v[4:7], v[148:151], v[188:191], v[4:7]
	v_mfma_f32_16x16x32_f16 v[0:3], v[156:159], v[188:191], v[0:3]
	s_setprio 0
	s_barrier
	s_add_i32 s42, s42, 2
	s_add_u32 s46, s46, 0x100
	s_addc_u32 s47, s47, 0
	s_add_u32 s40, s40, 0x100
	s_addc_u32 s41, s41, 0
	s_cmp_gt_u32 s42, 13
	s_cbranch_scc0 .LBB0_812
	s_and_b64 vcc, exec, s[16:17]
	s_cbranch_vccz .LBB0_815
	s_barrier

; #define PG8_STAGE(bufoff, gbase, voff) do { _Pragma("unroll") for (int _i = 0; _i < 2; ++_i) \
;         __builtin_amdgcn_global_load_lds((const unsigned*)((const char*)(gbase) + (voff)[_i]), (PG8_LAS unsigned*)(lds + (bufoff) + ldsw + _i * 8192), 16, 0, 0); } while (0)
; #define PG8_WAIT_V(n) asm volatile("s_waitcnt vmcnt(" #n ")" ::: "memory")
; #define PG8_BAR __builtin_amdgcn_s_barrier()
; template <class Epi, class Sched, bool ALIGN_EPI = false, bool SP2 = false, bool F16 = false>
; __device__ __forceinline__ void gemm_phase(PG8_LAS unsigned char* lds, const Gemm g, const Sched& S, const Epi& E, const int wid_in) {
;     ...
;     const int wid = wid_in, lane = lane_, tid = wid * 64 + lane, wr = wid >> 2, wc = wid & 3, fr = lane & 15, fq = lane >> 4;
;     const int K = g.K, nt = K / BK;
;     unsigned voffA[2], voffB[2];
; #pragma unroll
;     for (int i = 0; i < 2; ++i) { int R, C; stage_rc(tid * 16 + i * 8192, R, C); const int Rb = Epi::PERM ? ((R & ~31) + perm32(R & 31)) : R;
;         voffA[i] = (unsigned)(R * K + C) * 2u; voffB[i] = (unsigned)(Rb * K + C) * 2u; }
;     const size_t kstep = (size_t)(BK * 2);
;     const size_t hstep = (size_t)HALF * K * 2;
;     const size_t tstep = 2 * hstep;
;     const unsigned ldsw = (unsigned)wid * 1024u;
;     const int aoff = lds_byte(wr * 64 + fr, fq * 8), boff = lds_byte(wc * 32 + fr, fq * 8);
;     ...
;         PG8_WAIT_V(2); PG8_BAR;
;         PG8_STAGE(PG8_SB(1, 0), cB + kstep, voffB); PG8_STAGE(PG8_SA(1, 0), cA + kstep, voffA); PG8_STAGE(PG8_SB(1, 1), cB + hstep + kstep, voffB);
;         PG8_WAIT_V(6); PG8_BAR;
.LBB0_896:
	s_add_u32 s18, s59, 0x15700000
	s_addc_u32 s19, s60, 0
	s_add_u32 s87, s59, 0x9400000
	s_mov_b64 s[20:21], 0x80
	s_addc_u32 s88, s60, 0
	s_add_i32 m0, s74, 0x18000
	v_lshl_add_u64 v[6:7], v[6:7], 0, s[20:21]
	s_waitcnt vmcnt(2)
	s_barrier
	global_load_lds_dwordx4 v[6:7], off
	v_lshl_add_u64 v[4:5], v[4:5], 0, s[20:21]
	s_add_i32 m0, s74, 0x1a000
	s_add_i32 s89, s74, 0xa000
	global_load_lds_dwordx4 v[4:5], off
	v_lshl_add_u64 v[0:1], v[0:1], 0, s[20:21]
	s_mov_b32 m0, s75
	s_add_u32 s8, s48, 0x40080
	global_load_lds_dwordx4 v[0:1], off
	v_lshl_add_u64 v[0:1], v[2:3], 0, s[20:21]
	s_mov_b32 m0, s89
	s_addc_u32 s9, s49, 0
	global_load_lds_dwordx4 v[0:1], off
	s_add_i32 m0, s74, 0x1c000
	s_nop 0
	global_load_lds_dwordx4 v158, s[8:9]
	s_add_i32 m0, s74, 0x1e000
	v_and_b32_e32 v180, 15, v8
	global_load_lds_dwordx4 v162, s[8:9]
	v_or_b32_e32 v0, s70, v180
	v_lshlrev_b32_e32 v1, 6, v0
	v_and_b32_e32 v2, 48, v8
	s_movk_i32 s8, 0x3c0
	v_and_b32_e32 v3, 0xfffffc00, v12
	v_lshlrev_b32_e32 v0, 2, v0
	v_and_or_b32 v1, v1, s8, v2
	v_add_u32_e32 v4, s73, v3
	v_and_b32_e32 v0, 32, v0
	v_bitop3_b32 v0, v1, v4, v0 bitop3:0xde
	v_lshl_or_b32 v1, v180, 6, v2
	v_add_u32_e32 v2, s72, v3
	v_lshlrev_b32_e32 v3, 2, v8
	v_and_b32_e32 v3, 32, v3
	v_bitop3_b32 v182, v1, v2, v3 bitop3:0xde
	v_lshlrev_b32_e32 v1, 14, v9
	v_and_b32_e32 v1, 0xffff8000, v1
	v_lshl_add_u32 v1, v10, 11, v1
	v_and_b32_e32 v2, 1, v9
	v_lshl_or_b32 v1, v2, 6, v1
	v_lshl_add_u32 v166, v11, 1, v1
	v_lshlrev_b32_e32 v1, 14, v13
	v_and_b32_e32 v1, 0xffff8000, v1
	s_waitcnt vmcnt(6)
	s_mul_i32 s8, s3, 0x210
	v_lshl_add_u32 v1, v14, 11, v1
	v_and_b32_e32 v2, 1, v13
	s_add_i32 s91, s8, 0
	v_lshl_or_b32 v1, v2, 6, v1
	s_add_i32 s40, 0, 0x10000
	s_add_i32 s41, 0, 0x14000
	v_ashrrev_i32_e32 v181, 4, v8
	s_bfe_u32 s14, s93, 0x10006
	s_ashr_i32 s15, s38, 31
	s_mov_b32 s76, s38
	s_ashr_i32 s83, s58, 31
	s_add_i32 s91, s91, 0x20400
	v_mov_b32_e32 v167, v164
	v_lshl_add_u32 v168, v15, 1, v1
	v_mov_b32_e32 v169, v164
	v_mov_b64_e32 v[170:171], 0x300
	v_mov_b64_e32 v[172:173], 0x2ff
	v_add_u32_e32 v183, s40, v182
	v_add_u32_e32 v184, s41, v182
	v_add_u32_e32 v185, 0, v0
	v_mov_b32_e32 v186, 0x358637bd
	s_mov_b64 s[22:23], 0x18000
	s_mov_b64 s[24:25], 0x48000
	s_mov_b64 s[26:27], 0x50000
	s_mov_b64 s[28:29], 0x58000
	v_mov_b32_e32 v187, 0x3e38aa3b
	s_barrier
	s_branch .LBB0_899

; #define PG8_STAGE(bufoff, gbase, voff) do { _Pragma("unroll") for (int _i = 0; _i < 2; ++_i) \
;         __builtin_amdgcn_global_load_lds((const unsigned*)((const char*)(gbase) + (voff)[_i]), (PG8_LAS unsigned*)(lds + (bufoff) + ldsw + _i * 8192), 16, 0, 0); } while (0)
; #define PG8_LDA(dst, b, h) do { _Pragma("unroll") for (int m = 0; m < 4; ++m) _Pragma("unroll") for (int k = 0; k < 2; ++k) dst[m][k] = *(const PG8_LAS bf16x8*)(lds + PG8_SA(b, h) + aoff + m * 2048 + k * 1024); } while (0)
; #define PG8_LDB(dst, b, h) do { _Pragma("unroll") for (int n = 0; n < 2; ++n) _Pragma("unroll") for (int k = 0; k < 2; ++k) dst[n][k] = *(const PG8_LAS bf16x8*)(lds + PG8_SB(b, h) + boff + n * 2048 + k * 1024); } while (0)
; #define PG8_MMA(ai, bj, At, Bt) do { __builtin_amdgcn_s_setprio(1); _Pragma("unroll") for (int m = 0; m < 4; ++m) _Pragma("unroll") for (int n = 0; n < 2; ++n) _Pragma("unroll") for (int k = 0; k < 2; ++k) \
;         acc[ai][bj][m][n] = mma16<F16>(Bt[n][k], At[m][k], acc[ai][bj][m][n]); __builtin_amdgcn_s_setprio(0); } while (0)
; #define PG8_WAIT_V(n) asm volatile("s_waitcnt vmcnt(" #n ")" ::: "memory")
; #define PG8_BAR __builtin_amdgcn_s_barrier()
; template <class Epi, class Sched, bool ALIGN_EPI = false, bool SP2 = false, bool F16 = false>
; __device__ __forceinline__ void gemm_phase(PG8_LAS unsigned char* lds, const Gemm g, const Sched& S, const Epi& E, const int wid_in) {
;     ...
;         for (int t = 0; t < nt; t += 2) {
;             const bool last = (t == nt - 2);
;             const char* a1 = cA + (size_t)(t + 1) * kstep;
;             const char* a2 = last ? nA : cA + (size_t)(t + 2) * kstep; const char* b2 = last ? nB : cB + (size_t)(t + 2) * kstep;
;             const char* a3 = a2 + kstep; const char* b3 = b2 + kstep;
;             if (last && has_next) S.a_ready(nxt);
;             if constexpr (SP2) {
;             PG8_LDB(B0, 0, 0); PG8_LDB(B1, 0, 1); PG8_SCHED; PG8_LDA(At, 0, 0); PG8_STAGE(PG8_SA(1, 1), a1 + hstep, voffA);
;             PG8_WAIT_V(8); PG8_WAIT_L(0); PG8_BAR; PG8_MMA(0, 0, At, B0); PG8_MMA(0, 1, At, B1); PG8_BAR; PG8_SCHED;
;             PG8_LDA(At, 0, 1); PG8_STAGE(PG8_SB(0, 0), b2, voffB); PG8_STAGE(PG8_SB(0, 1), b2 + hstep, voffB); PG8_STAGE(PG8_SA(0, 0), a2, voffA);
;             PG8_WAIT_V(8); PG8_WAIT_L(0); PG8_BAR; PG8_MMA(1, 0, At, B0); PG8_MMA(1, 1, At, B1); PG8_BAR; PG8_SCHED;
.LBB0_902:
	ds_read_b128 v[128:131], v183
	ds_read_b128 v[132:135], v183 offset:1024
	ds_read_b128 v[136:139], v183 offset:2048
	ds_read_b128 v[140:143], v183 offset:3072
	ds_read_b128 v[144:147], v184
	ds_read_b128 v[148:151], v184 offset:1024
	ds_read_b128 v[152:155], v184 offset:2048
	ds_read_b128 v[174:177], v184 offset:3072
	s_add_u32 s48, s46, 0xfffc0080
	s_addc_u32 s49, s47, -1
	s_cmp_eq_u32 s52, 12
	s_cselect_b32 s51, s11, s49
	s_cselect_b32 s50, s13, s48
	s_cselect_b32 s49, s31, s43
	s_cselect_b32 s48, s35, s42
	s_add_i32 m0, s74, 0xc000
	ds_read_b128 v[188:191], v185
	ds_read_b128 v[192:195], v185 offset:1024
	ds_read_b128 v[196:199], v185 offset:2048
	ds_read_b128 v[200:203], v185 offset:3072
	ds_read_b128 v[204:207], v185 offset:4096
	ds_read_b128 v[208:211], v185 offset:5120
	ds_read_b128 v[212:215], v185 offset:6144
	ds_read_b128 v[216:219], v185 offset:7168
	global_load_lds_dwordx4 v166, s[46:47]
	s_add_i32 m0, s74, 0xe000
	s_nop 0
	global_load_lds_dwordx4 v168, s[46:47]
	s_waitcnt vmcnt(8)
	s_waitcnt lgkmcnt(0)
	s_barrier
	s_setprio 1
	s_waitcnt lgkmcnt(0)
	v_mfma_f32_16x16x32_f16 v[124:127], v[128:131], v[188:191], v[124:127]
	v_mfma_f32_16x16x32_f16 v[120:123], v[136:139], v[188:191], v[120:123]
	v_mfma_f32_16x16x32_f16 v[108:111], v[128:131], v[196:199], v[108:111]
	v_mfma_f32_16x16x32_f16 v[104:107], v[136:139], v[196:199], v[104:107]
	v_mfma_f32_16x16x32_f16 v[92:95], v[128:131], v[204:207], v[92:95]
	v_mfma_f32_16x16x32_f16 v[88:91], v[136:139], v[204:207], v[88:91]
	v_mfma_f32_16x16x32_f16 v[76:79], v[128:131], v[212:215], v[76:79]
	v_mfma_f32_16x16x32_f16 v[72:75], v[136:139], v[212:215], v[72:75]
	v_mfma_f32_16x16x32_f16 v[124:127], v[132:135], v[192:195], v[124:127]
	v_mfma_f32_16x16x32_f16 v[120:123], v[140:143], v[192:195], v[120:123]
	v_mfma_f32_16x16x32_f16 v[108:111], v[132:135], v[200:203], v[108:111]
	v_mfma_f32_16x16x32_f16 v[104:107], v[140:143], v[200:203], v[104:107]
	v_mfma_f32_16x16x32_f16 v[92:95], v[132:135], v[208:211], v[92:95]
	v_mfma_f32_16x16x32_f16 v[88:91], v[140:143], v[208:211], v[88:91]
	v_mfma_f32_16x16x32_f16 v[76:79], v[132:135], v[216:219], v[76:79]
	v_mfma_f32_16x16x32_f16 v[72:75], v[140:143], v[216:219], v[72:75]
	s_setprio 0
	s_setprio 1
	v_mfma_f32_16x16x32_f16 v[116:119], v[144:147], v[188:191], v[116:119]
	v_mfma_f32_16x16x32_f16 v[112:115], v[152:155], v[188:191], v[112:115]
	v_mfma_f32_16x16x32_f16 v[100:103], v[144:147], v[196:199], v[100:103]
	v_mfma_f32_16x16x32_f16 v[96:99], v[152:155], v[196:199], v[96:99]
	v_mfma_f32_16x16x32_f16 v[84:87], v[144:147], v[204:207], v[84:87]
	v_mfma_f32_16x16x32_f16 v[80:83], v[152:155], v[204:207], v[80:83]
	v_mfma_f32_16x16x32_f16 v[68:71], v[144:147], v[212:215], v[68:71]
	v_mfma_f32_16x16x32_f16 v[64:67], v[152:155], v[212:215], v[64:67]
	v_mfma_f32_16x16x32_f16 v[116:119], v[148:151], v[192:195], v[116:119]
	v_mfma_f32_16x16x32_f16 v[112:115], v[174:177], v[192:195], v[112:115]
	v_mfma_f32_16x16x32_f16 v[100:103], v[148:151], v[200:203], v[100:103]
	v_mfma_f32_16x16x32_f16 v[96:99], v[174:177], v[200:203], v[96:99]
	v_mfma_f32_16x16x32_f16 v[84:87], v[148:151], v[208:211], v[84:87]
	v_mfma_f32_16x16x32_f16 v[80:83], v[174:177], v[208:211], v[80:83]
	v_mfma_f32_16x16x32_f16 v[68:71], v[148:151], v[216:219], v[68:71]
	v_mfma_f32_16x16x32_f16 v[64:67], v[174:177], v[216:219], v[64:67]
	s_setprio 0
	s_barrier
	s_add_i32 s53, s40, s68
	v_lshl_add_u64 v[178:179], s[48:49], 0, v[158:159]
	s_mov_b32 m0, s53
	ds_read_b128 v[188:191], v185 offset:16384
	ds_read_b128 v[192:195], v185 offset:17408
	ds_read_b128 v[196:199], v185 offset:18432
	ds_read_b128 v[200:203], v185 offset:19456
	ds_read_b128 v[204:207], v185 offset:20480
	ds_read_b128 v[208:211], v185 offset:21504
	ds_read_b128 v[212:215], v185 offset:22528
	ds_read_b128 v[216:219], v185 offset:23552
	global_load_lds_dwordx4 v[178:179], off
	s_add_i32 m0, s53, 0x2000
	s_add_u32 s54, s48, 0x40000
	v_lshl_add_u64 v[220:221], s[48:49], 0, v[162:163]
	s_addc_u32 s55, s49, 0
	s_add_i32 s53, s41, s68
	global_load_lds_dwordx4 v[220:221], off
	s_mov_b32 m0, s53
	v_lshl_add_u64 v[224:225], s[50:51], 0, v[160:161]
	global_load_lds_dwordx4 v158, s[54:55]
	s_add_i32 m0, s53, 0x2000
	s_nop 0
	global_load_lds_dwordx4 v162, s[54:55]
	v_lshl_add_u64 v[222:223], s[50:51], 0, v[156:157]
	s_mov_b32 m0, s74
	s_nop 0
	global_load_lds_dwordx4 v[222:223], off
	s_mov_b32 m0, s65
	s_nop 0
	global_load_lds_dwordx4 v[224:225], off
	s_waitcnt vmcnt(8)
	s_waitcnt lgkmcnt(0)
	s_barrier
	s_setprio 1
	s_waitcnt lgkmcnt(0)
	v_mfma_f32_16x16x32_f16 v[60:63], v[128:131], v[188:191], v[60:63]
	v_mfma_f32_16x16x32_f16 v[56:59], v[136:139], v[188:191], v[56:59]
	v_mfma_f32_16x16x32_f16 v[44:47], v[128:131], v[196:199], v[44:47]
	v_mfma_f32_16x16x32_f16 v[40:43], v[136:139], v[196:199], v[40:43]
	v_mfma_f32_16x16x32_f16 v[28:31], v[128:131], v[204:207], v[28:31]
	v_mfma_f32_16x16x32_f16 v[24:27], v[136:139], v[204:207], v[24:27]
	v_mfma_f32_16x16x32_f16 v[12:15], v[128:131], v[212:215], v[12:15]
	v_mfma_f32_16x16x32_f16 v[8:11], v[136:139], v[212:215], v[8:11]
	v_mfma_f32_16x16x32_f16 v[60:63], v[132:135], v[192:195], v[60:63]
	v_mfma_f32_16x16x32_f16 v[56:59], v[140:143], v[192:195], v[56:59]
	v_mfma_f32_16x16x32_f16 v[44:47], v[132:135], v[200:203], v[44:47]
	v_mfma_f32_16x16x32_f16 v[40:43], v[140:143], v[200:203], v[40:43]
	v_mfma_f32_16x16x32_f16 v[28:31], v[132:135], v[208:211], v[28:31]
	v_mfma_f32_16x16x32_f16 v[24:27], v[140:143], v[208:211], v[24:27]
	v_mfma_f32_16x16x32_f16 v[12:15], v[132:135], v[216:219], v[12:15]
	v_mfma_f32_16x16x32_f16 v[8:11], v[140:143], v[216:219], v[8:11]
	s_setprio 0
	s_setprio 1
	v_mfma_f32_16x16x32_f16 v[52:55], v[144:147], v[188:191], v[52:55]
	v_mfma_f32_16x16x32_f16 v[48:51], v[152:155], v[188:191], v[48:51]
	v_mfma_f32_16x16x32_f16 v[36:39], v[144:147], v[196:199], v[36:39]
	v_mfma_f32_16x16x32_f16 v[32:35], v[152:155], v[196:199], v[32:35]
	v_mfma_f32_16x16x32_f16 v[20:23], v[144:147], v[204:207], v[20:23]
	v_mfma_f32_16x16x32_f16 v[16:19], v[152:155], v[204:207], v[16:19]
	v_mfma_f32_16x16x32_f16 v[4:7], v[144:147], v[212:215], v[4:7]
	v_mfma_f32_16x16x32_f16 v[0:3], v[152:155], v[212:215], v[0:3]
	v_mfma_f32_16x16x32_f16 v[52:55], v[148:151], v[192:195], v[52:55]
	v_mfma_f32_16x16x32_f16 v[48:51], v[174:177], v[192:195], v[48:51]
	v_mfma_f32_16x16x32_f16 v[36:39], v[148:151], v[200:203], v[36:39]
	v_mfma_f32_16x16x32_f16 v[32:35], v[174:177], v[200:203], v[32:35]
	v_mfma_f32_16x16x32_f16 v[20:23], v[148:151], v[208:211], v[20:23]
	v_mfma_f32_16x16x32_f16 v[16:19], v[174:177], v[208:211], v[16:19]
	v_mfma_f32_16x16x32_f16 v[4:7], v[148:151], v[216:219], v[4:7]
	v_mfma_f32_16x16x32_f16 v[0:3], v[174:177], v[216:219], v[0:3]
	s_setprio 0
	s_barrier
; #define PG8_STAGE(bufoff, gbase, voff) do { _Pragma("unroll") for (int _i = 0; _i < 2; ++_i) \
;         __builtin_amdgcn_global_load_lds((const unsigned*)((const char*)(gbase) + (voff)[_i]), (PG8_LAS unsigned*)(lds + (bufoff) + ldsw + _i * 8192), 16, 0, 0); } while (0)
; #define PG8_LDA(dst, b, h) do { _Pragma("unroll") for (int m = 0; m < 4; ++m) _Pragma("unroll") for (int k = 0; k < 2; ++k) dst[m][k] = *(const PG8_LAS bf16x8*)(lds + PG8_SA(b, h) + aoff + m * 2048 + k * 1024); } while (0)
; #define PG8_LDB(dst, b, h) do { _Pragma("unroll") for (int n = 0; n < 2; ++n) _Pragma("unroll") for (int k = 0; k < 2; ++k) dst[n][k] = *(const PG8_LAS bf16x8*)(lds + PG8_SB(b, h) + boff + n * 2048 + k * 1024); } while (0)
; #define PG8_MMA(ai, bj, At, Bt) do { __builtin_amdgcn_s_setprio(1); _Pragma("unroll") for (int m = 0; m < 4; ++m) _Pragma("unroll") for (int n = 0; n < 2; ++n) _Pragma("unroll") for (int k = 0; k < 2; ++k) \
;         acc[ai][bj][m][n] = mma16<F16>(Bt[n][k], At[m][k], acc[ai][bj][m][n]); __builtin_amdgcn_s_setprio(0); } while (0)
; #define PG8_WAIT_V(n) asm volatile("s_waitcnt vmcnt(" #n ")" ::: "memory")
; #define PG8_WAIT_L(n) asm volatile("s_waitcnt lgkmcnt(" #n ")" ::: "memory")
; #define PG8_BAR __builtin_amdgcn_s_barrier()
; #define PG8_SCHED __builtin_amdgcn_sched_barrier(0)
; template <class Epi, class Sched, bool ALIGN_EPI = false, bool SP2 = false, bool F16 = false>
; __device__ __forceinline__ void gemm_phase(PG8_LAS unsigned char* lds, const Gemm g, const Sched& S, const Epi& E, const int wid_in) {
;     ...
;         for (int t = 0; t < nt; t += 2) {
;     ...
;             PG8_LDB(B0, 1, 0); PG8_LDB(B1, 1, 1); PG8_SCHED; PG8_LDA(At, 1, 0); PG8_STAGE(PG8_SA(0, 1), a2 + hstep, voffA);
;             PG8_WAIT_V(8); PG8_WAIT_L(0); PG8_BAR; PG8_MMA(0, 0, At, B0); PG8_MMA(0, 1, At, B1); PG8_BAR; PG8_SCHED;
;             PG8_LDA(At, 1, 1); PG8_STAGE(PG8_SB(1, 0), b3, voffB); PG8_STAGE(PG8_SB(1, 1), b3 + hstep, voffB); PG8_STAGE(PG8_SA(1, 0), a3, voffA);
;             PG8_WAIT_V(8); PG8_WAIT_L(0); PG8_BAR; PG8_MMA(1, 0, At, B0); PG8_MMA(1, 1, At, B1); PG8_BAR; PG8_SCHED;
	s_add_i32 s53, 0, 0x18000
	s_add_i32 s54, 0, 0x1c000
	v_add_u32_e32 v140, s53, v182
	v_add_u32_e32 v165, s54, v182
	ds_read_b128 v[128:131], v140
	ds_read_b128 v[132:135], v140 offset:1024
	ds_read_b128 v[136:139], v140 offset:2048
	ds_read_b128 v[140:143], v140 offset:3072
	ds_read_b128 v[144:147], v165
	ds_read_b128 v[148:151], v165 offset:1024
	ds_read_b128 v[152:155], v165 offset:2048
	ds_read_b128 v[174:177], v165 offset:3072
	s_add_u32 s50, s50, 0x40000
	s_addc_u32 s51, s51, 0
	s_mov_b32 m0, s66
	ds_read_b128 v[188:191], v185 offset:32768
	ds_read_b128 v[192:195], v185 offset:33792
	ds_read_b128 v[196:199], v185 offset:34816
	ds_read_b128 v[200:203], v185 offset:35840
	ds_read_b128 v[204:207], v185 offset:36864
	ds_read_b128 v[208:211], v185 offset:37888
	ds_read_b128 v[212:215], v185 offset:38912
	ds_read_b128 v[216:219], v185 offset:39936
	global_load_lds_dwordx4 v156, s[50:51]
	v_lshl_add_u64 v[226:227], s[50:51], 0, v[160:161]
	s_mov_b32 m0, s67
	s_nop 0
	global_load_lds_dwordx4 v[226:227], off
	s_waitcnt vmcnt(8)
	s_waitcnt lgkmcnt(0)
	s_barrier
	s_setprio 1
	s_waitcnt lgkmcnt(0)
	v_mfma_f32_16x16x32_f16 v[124:127], v[128:131], v[188:191], v[124:127]
	v_mfma_f32_16x16x32_f16 v[120:123], v[136:139], v[188:191], v[120:123]
	v_mfma_f32_16x16x32_f16 v[108:111], v[128:131], v[196:199], v[108:111]
	v_mfma_f32_16x16x32_f16 v[104:107], v[136:139], v[196:199], v[104:107]
	v_mfma_f32_16x16x32_f16 v[92:95], v[128:131], v[204:207], v[92:95]
	v_mfma_f32_16x16x32_f16 v[88:91], v[136:139], v[204:207], v[88:91]
	v_mfma_f32_16x16x32_f16 v[76:79], v[128:131], v[212:215], v[76:79]
	v_mfma_f32_16x16x32_f16 v[72:75], v[136:139], v[212:215], v[72:75]
	v_mfma_f32_16x16x32_f16 v[124:127], v[132:135], v[192:195], v[124:127]
	v_mfma_f32_16x16x32_f16 v[120:123], v[140:143], v[192:195], v[120:123]
	v_mfma_f32_16x16x32_f16 v[108:111], v[132:135], v[200:203], v[108:111]
	v_mfma_f32_16x16x32_f16 v[104:107], v[140:143], v[200:203], v[104:107]
	v_mfma_f32_16x16x32_f16 v[92:95], v[132:135], v[208:211], v[92:95]
	v_mfma_f32_16x16x32_f16 v[88:91], v[140:143], v[208:211], v[88:91]
	v_mfma_f32_16x16x32_f16 v[76:79], v[132:135], v[216:219], v[76:79]
	v_mfma_f32_16x16x32_f16 v[72:75], v[140:143], v[216:219], v[72:75]
	s_setprio 0
	s_setprio 1
	v_mfma_f32_16x16x32_f16 v[116:119], v[144:147], v[188:191], v[116:119]
	v_mfma_f32_16x16x32_f16 v[112:115], v[152:155], v[188:191], v[112:115]
	v_mfma_f32_16x16x32_f16 v[100:103], v[144:147], v[196:199], v[100:103]
	v_mfma_f32_16x16x32_f16 v[96:99], v[152:155], v[196:199], v[96:99]
	v_mfma_f32_16x16x32_f16 v[84:87], v[144:147], v[204:207], v[84:87]
	v_mfma_f32_16x16x32_f16 v[80:83], v[152:155], v[204:207], v[80:83]
	v_mfma_f32_16x16x32_f16 v[68:71], v[144:147], v[212:215], v[68:71]
	v_mfma_f32_16x16x32_f16 v[64:67], v[152:155], v[212:215], v[64:67]
	v_mfma_f32_16x16x32_f16 v[116:119], v[148:151], v[192:195], v[116:119]
	v_mfma_f32_16x16x32_f16 v[112:115], v[174:177], v[192:195], v[112:115]
	v_mfma_f32_16x16x32_f16 v[100:103], v[148:151], v[200:203], v[100:103]
	v_mfma_f32_16x16x32_f16 v[96:99], v[174:177], v[200:203], v[96:99]
	v_mfma_f32_16x16x32_f16 v[84:87], v[148:151], v[208:211], v[84:87]
	v_mfma_f32_16x16x32_f16 v[80:83], v[174:177], v[208:211], v[80:83]
	v_mfma_f32_16x16x32_f16 v[68:71], v[148:151], v[216:219], v[68:71]
	v_mfma_f32_16x16x32_f16 v[64:67], v[174:177], v[216:219], v[64:67]
	s_setprio 0
	s_barrier
	s_add_i32 s50, s53, s68
	v_lshl_add_u64 v[178:179], v[178:179], 0, s[20:21]
	s_mov_b32 m0, s50
	ds_read_b128 v[188:191], v185 offset:49152
	ds_read_b128 v[192:195], v185 offset:50176
	ds_read_b128 v[196:199], v185 offset:51200
	ds_read_b128 v[200:203], v185 offset:52224
	ds_read_b128 v[204:207], v185 offset:53248
	ds_read_b128 v[208:211], v185 offset:54272
	ds_read_b128 v[212:215], v185 offset:55296
	ds_read_b128 v[216:219], v185 offset:56320
	global_load_lds_dwordx4 v[178:179], off
	s_add_i32 m0, s50, 0x2000
	s_add_u32 s48, s48, 0x40080
	v_lshl_add_u64 v[178:179], v[220:221], 0, s[20:21]
	s_addc_u32 s49, s49, 0
	s_add_i32 s50, s54, s68
	global_load_lds_dwordx4 v[178:179], off
	s_mov_b32 m0, s50
	s_nop 0
	global_load_lds_dwordx4 v158, s[48:49]
	s_add_i32 m0, s50, 0x2000
	s_nop 0
	global_load_lds_dwordx4 v162, s[48:49]
	v_lshl_add_u64 v[178:179], v[222:223], 0, s[20:21]
	s_mov_b32 m0, s75
	s_nop 0
	global_load_lds_dwordx4 v[178:179], off
	v_lshl_add_u64 v[178:179], v[224:225], 0, s[20:21]
	s_mov_b32 m0, s89
	s_nop 0
	global_load_lds_dwordx4 v[178:179], off
	s_waitcnt vmcnt(8)
	s_waitcnt lgkmcnt(0)
	s_barrier
	s_setprio 1
	s_waitcnt lgkmcnt(0)
	v_mfma_f32_16x16x32_f16 v[60:63], v[128:131], v[188:191], v[60:63]
	v_mfma_f32_16x16x32_f16 v[56:59], v[136:139], v[188:191], v[56:59]
	v_mfma_f32_16x16x32_f16 v[44:47], v[128:131], v[196:199], v[44:47]
	v_mfma_f32_16x16x32_f16 v[40:43], v[136:139], v[196:199], v[40:43]
	v_mfma_f32_16x16x32_f16 v[28:31], v[128:131], v[204:207], v[28:31]
	v_mfma_f32_16x16x32_f16 v[24:27], v[136:139], v[204:207], v[24:27]
	v_mfma_f32_16x16x32_f16 v[12:15], v[128:131], v[212:215], v[12:15]
	v_mfma_f32_16x16x32_f16 v[8:11], v[136:139], v[212:215], v[8:11]
	v_mfma_f32_16x16x32_f16 v[60:63], v[132:135], v[192:195], v[60:63]
	v_mfma_f32_16x16x32_f16 v[56:59], v[140:143], v[192:195], v[56:59]
	v_mfma_f32_16x16x32_f16 v[44:47], v[132:135], v[200:203], v[44:47]
	v_mfma_f32_16x16x32_f16 v[40:43], v[140:143], v[200:203], v[40:43]
	v_mfma_f32_16x16x32_f16 v[28:31], v[132:135], v[208:211], v[28:31]
	v_mfma_f32_16x16x32_f16 v[24:27], v[140:143], v[208:211], v[24:27]
	v_mfma_f32_16x16x32_f16 v[12:15], v[132:135], v[216:219], v[12:15]
	v_mfma_f32_16x16x32_f16 v[8:11], v[140:143], v[216:219], v[8:11]
	s_setprio 0
	s_setprio 1
	v_mfma_f32_16x16x32_f16 v[52:55], v[144:147], v[188:191], v[52:55]
	v_mfma_f32_16x16x32_f16 v[48:51], v[152:155], v[188:191], v[48:51]
	v_mfma_f32_16x16x32_f16 v[36:39], v[144:147], v[196:199], v[36:39]
	v_mfma_f32_16x16x32_f16 v[32:35], v[152:155], v[196:199], v[32:35]
	v_mfma_f32_16x16x32_f16 v[20:23], v[144:147], v[204:207], v[20:23]
	v_mfma_f32_16x16x32_f16 v[16:19], v[152:155], v[204:207], v[16:19]
	v_mfma_f32_16x16x32_f16 v[4:7], v[144:147], v[212:215], v[4:7]
	v_mfma_f32_16x16x32_f16 v[0:3], v[152:155], v[212:215], v[0:3]
	v_mfma_f32_16x16x32_f16 v[52:55], v[148:151], v[192:195], v[52:55]
	v_mfma_f32_16x16x32_f16 v[48:51], v[174:177], v[192:195], v[48:51]
	v_mfma_f32_16x16x32_f16 v[36:39], v[148:151], v[200:203], v[36:39]
	v_mfma_f32_16x16x32_f16 v[32:35], v[174:177], v[200:203], v[32:35]
	v_mfma_f32_16x16x32_f16 v[20:23], v[148:151], v[208:211], v[20:23]
	v_mfma_f32_16x16x32_f16 v[16:19], v[174:177], v[208:211], v[16:19]
	v_mfma_f32_16x16x32_f16 v[4:7], v[148:151], v[216:219], v[4:7]
	v_mfma_f32_16x16x32_f16 v[0:3], v[174:177], v[216:219], v[0:3]
	s_setprio 0
	s_barrier
	s_add_i32 s52, s52, 2
	s_add_u32 s46, s46, 0x100
	s_addc_u32 s47, s47, 0
	s_add_u32 s42, s42, 0x100
	s_addc_u32 s43, s43, 0
	s_cmp_gt_u32 s52, 13
	s_cbranch_scc0 .LBB0_902
	s_and_b64 vcc, exec, s[16:17]
	s_cbranch_vccz .LBB0_905
	s_barrier

; #define PG8_STAGE(bufoff, gbase, voff) do { _Pragma("unroll") for (int _i = 0; _i < 2; ++_i) \
;         __builtin_amdgcn_global_load_lds((const unsigned*)((const char*)(gbase) + (voff)[_i]), (PG8_LAS unsigned*)(lds + (bufoff) + ldsw + _i * 8192), 16, 0, 0); } while (0)
; #define PG8_WAIT_V(n) asm volatile("s_waitcnt vmcnt(" #n ")" ::: "memory")
; #define PG8_BAR __builtin_amdgcn_s_barrier()
; template <class Epi, class Sched, bool ALIGN_EPI = false, bool SP2 = false, bool F16 = false>
; __device__ __forceinline__ void gemm_phase(PG8_LAS unsigned char* lds, const Gemm g, const Sched& S, const Epi& E, const int wid_in) {
;     ...
;     const int wid = wid_in, lane = lane_, tid = wid * 64 + lane, wr = wid >> 2, wc = wid & 3, fr = lane & 15, fq = lane >> 4;
;     const int K = g.K, nt = K / BK;
;     unsigned voffA[2], voffB[2];
; #pragma unroll
;     for (int i = 0; i < 2; ++i) { int R, C; stage_rc(tid * 16 + i * 8192, R, C); const int Rb = Epi::PERM ? ((R & ~31) + perm32(R & 31)) : R;
;         voffA[i] = (unsigned)(R * K + C) * 2u; voffB[i] = (unsigned)(Rb * K + C) * 2u; }
;     const size_t kstep = (size_t)(BK * 2);
;     const size_t hstep = (size_t)HALF * K * 2;
;     const size_t tstep = 2 * hstep;
;     const unsigned ldsw = (unsigned)wid * 1024u;
;     const int aoff = lds_byte(wr * 64 + fr, fq * 8), boff = lds_byte(wc * 32 + fr, fq * 8);
;     ...
;         PG8_WAIT_V(2); PG8_BAR;
;         PG8_STAGE(PG8_SB(1, 0), cB + kstep, voffB); PG8_STAGE(PG8_SA(1, 0), cA + kstep, voffA); PG8_STAGE(PG8_SB(1, 1), cB + hstep + kstep, voffB);
;         PG8_WAIT_V(6); PG8_BAR;
.LBB0_1155:
	s_add_u32 s22, s10, 0x15400000
	s_addc_u32 s23, s11, 0
	s_add_u32 s24, s10, 0x7400000
	s_addc_u32 s25, s11, 0
	s_add_u32 s26, s10, 0x13400000
	s_mov_b64 s[28:29], 0x80
	s_addc_u32 s27, s11, 0
	s_add_i32 m0, s74, 0x18000
	v_lshl_add_u64 v[6:7], v[6:7], 0, s[28:29]
	s_waitcnt vmcnt(2)
	s_barrier
	global_load_lds_dwordx4 v[6:7], off
	v_lshl_add_u64 v[4:5], v[4:5], 0, s[28:29]
	s_add_i32 m0, s74, 0x1a000
	s_add_i32 s56, s74, 0xa000
	global_load_lds_dwordx4 v[4:5], off
	v_lshl_add_u64 v[0:1], v[0:1], 0, s[28:29]
	s_mov_b32 m0, s75
	s_add_u32 s10, s50, 0x40080
	global_load_lds_dwordx4 v[0:1], off
	v_lshl_add_u64 v[0:1], v[2:3], 0, s[28:29]
	s_mov_b32 m0, s56
	s_addc_u32 s11, s51, 0
	global_load_lds_dwordx4 v[0:1], off
	s_add_i32 m0, s74, 0x1c000
	s_nop 0
	global_load_lds_dwordx4 v154, s[10:11]
	s_add_i32 m0, s74, 0x1e000
	v_and_b32_e32 v187, 15, v8
	global_load_lds_dwordx4 v158, s[10:11]
	v_or_b32_e32 v0, s70, v187
	v_lshlrev_b32_e32 v1, 6, v0
	v_and_b32_e32 v2, 48, v8
	s_movk_i32 s10, 0x3c0
	v_and_b32_e32 v3, 0xfffffc00, v12
	v_lshlrev_b32_e32 v0, 2, v0
	v_and_or_b32 v1, v1, s10, v2
	v_add_u32_e32 v4, s73, v3
	v_and_b32_e32 v0, 32, v0
	v_bitop3_b32 v0, v1, v4, v0 bitop3:0xde
	v_lshl_or_b32 v1, v187, 6, v2
	v_add_u32_e32 v2, s72, v3
	v_lshlrev_b32_e32 v3, 2, v8
	v_and_b32_e32 v3, 32, v3
	v_bitop3_b32 v188, v1, v2, v3 bitop3:0xde
	v_lshlrev_b32_e32 v1, 14, v9
	v_and_b32_e32 v1, 0xffff8000, v1
	v_lshl_add_u32 v1, v10, 11, v1
	v_and_b32_e32 v2, 1, v9
	v_lshl_or_b32 v1, v2, 6, v1
	v_lshl_add_u32 v160, v11, 1, v1
	v_lshlrev_b32_e32 v1, 14, v13
	v_and_b32_e32 v1, 0xffff8000, v1
	s_waitcnt vmcnt(6)
	v_lshl_add_u32 v1, v14, 11, v1
	v_and_b32_e32 v2, 1, v13
	v_lshl_or_b32 v1, v2, 6, v1
	s_add_i32 s60, 0, 0x10000
	s_add_i32 s61, 0, 0x14000
	v_ashrrev_i32_e32 v186, 4, v8
	s_ashr_i32 s57, s38, 31
	s_mov_b32 s58, s38
	s_ashr_i32 s59, s14, 31
	v_mov_b32_e32 v161, v155
	v_lshl_add_u32 v162, v15, 1, v1
	v_mov_b32_e32 v163, v155
	v_mov_b64_e32 v[164:165], 0x100
	v_mov_b64_e32 v[166:167], 0xff
	v_add_u32_e32 v189, s60, v188
	v_add_u32_e32 v190, s61, v188
	v_add_u32_e32 v191, 0, v0
	s_mov_b32 s62, 0
	s_barrier
	s_branch .LBB0_1158

; #define PG8_STAGE(bufoff, gbase, voff) do { _Pragma("unroll") for (int _i = 0; _i < 2; ++_i) \
;         __builtin_amdgcn_global_load_lds((const unsigned*)((const char*)(gbase) + (voff)[_i]), (PG8_LAS unsigned*)(lds + (bufoff) + ldsw + _i * 8192), 16, 0, 0); } while (0)
; #define PG8_LDA(dst, b, h) do { _Pragma("unroll") for (int m = 0; m < 4; ++m) _Pragma("unroll") for (int k = 0; k < 2; ++k) dst[m][k] = *(const PG8_LAS bf16x8*)(lds + PG8_SA(b, h) + aoff + m * 2048 + k * 1024); } while (0)
; #define PG8_LDB(dst, b, h) do { _Pragma("unroll") for (int n = 0; n < 2; ++n) _Pragma("unroll") for (int k = 0; k < 2; ++k) dst[n][k] = *(const PG8_LAS bf16x8*)(lds + PG8_SB(b, h) + boff + n * 2048 + k * 1024); } while (0)
; #define PG8_MMA(ai, bj, At, Bt) do { __builtin_amdgcn_s_setprio(1); _Pragma("unroll") for (int m = 0; m < 4; ++m) _Pragma("unroll") for (int n = 0; n < 2; ++n) _Pragma("unroll") for (int k = 0; k < 2; ++k) \
;         acc[ai][bj][m][n] = mma16<F16>(Bt[n][k], At[m][k], acc[ai][bj][m][n]); __builtin_amdgcn_s_setprio(0); } while (0)
; #define PG8_WAIT_V(n) asm volatile("s_waitcnt vmcnt(" #n ")" ::: "memory")
; #define PG8_BAR __builtin_amdgcn_s_barrier()
; template <class Epi, class Sched, bool ALIGN_EPI = false, bool SP2 = false, bool F16 = false>
; __device__ __forceinline__ void gemm_phase(PG8_LAS unsigned char* lds, const Gemm g, const Sched& S, const Epi& E, const int wid_in) {
;     ...
;         for (int t = 0; t < nt; t += 2) {
;             const bool last = (t == nt - 2);
;             const char* a1 = cA + (size_t)(t + 1) * kstep;
;             const char* a2 = last ? nA : cA + (size_t)(t + 2) * kstep; const char* b2 = last ? nB : cB + (size_t)(t + 2) * kstep;
;             const char* a3 = a2 + kstep; const char* b3 = b2 + kstep;
;             if (last && has_next) S.a_ready(nxt);
;             if constexpr (SP2) {
;             PG8_LDB(B0, 0, 0); PG8_LDB(B1, 0, 1); PG8_SCHED; PG8_LDA(At, 0, 0); PG8_STAGE(PG8_SA(1, 1), a1 + hstep, voffA);
;             PG8_WAIT_V(8); PG8_WAIT_L(0); PG8_BAR; PG8_MMA(0, 0, At, B0); PG8_MMA(0, 1, At, B1); PG8_BAR; PG8_SCHED;
;             PG8_LDA(At, 0, 1); PG8_STAGE(PG8_SB(0, 0), b2, voffB); PG8_STAGE(PG8_SB(0, 1), b2 + hstep, voffB); PG8_STAGE(PG8_SA(0, 0), a2, voffA);
;             PG8_WAIT_V(8); PG8_WAIT_L(0); PG8_BAR; PG8_MMA(1, 0, At, B0); PG8_MMA(1, 1, At, B1); PG8_BAR; PG8_SCHED;
.LBB0_1165:
	ds_read_b128 v[128:131], v189
	ds_read_b128 v[132:135], v189 offset:1024
	ds_read_b128 v[136:139], v189 offset:2048
	ds_read_b128 v[140:143], v189 offset:3072
	ds_read_b128 v[144:147], v190
	ds_read_b128 v[148:151], v190 offset:1024
	ds_read_b128 v[168:171], v190 offset:2048
	ds_read_b128 v[172:175], v190 offset:3072
	s_add_u32 s50, s48, 0xfffc0080
	s_addc_u32 s51, s49, -1
	s_cmp_eq_u32 s64, 12
	s_cselect_b32 s53, s35, s51
	s_cselect_b32 s52, s42, s50
	s_cselect_b32 s51, s31, s63
	s_cselect_b32 s50, s43, s47
	s_add_i32 m0, s74, 0xc000
	ds_read_b128 v[176:179], v191
	ds_read_b128 v[180:183], v191 offset:1024
	ds_read_b128 v[192:195], v191 offset:2048
	ds_read_b128 v[196:199], v191 offset:3072
	ds_read_b128 v[200:203], v191 offset:4096
	ds_read_b128 v[204:207], v191 offset:5120
	ds_read_b128 v[208:211], v191 offset:6144
	ds_read_b128 v[212:215], v191 offset:7168
	global_load_lds_dwordx4 v160, s[48:49]
	s_add_i32 m0, s74, 0xe000
	s_nop 0
	global_load_lds_dwordx4 v162, s[48:49]
	s_waitcnt vmcnt(8)
	s_waitcnt lgkmcnt(0)
	s_barrier
	s_setprio 1
	s_waitcnt lgkmcnt(0)
	v_mfma_f32_16x16x32_bf16 v[124:127], v[128:131], v[176:179], v[124:127]
	v_mfma_f32_16x16x32_bf16 v[120:123], v[136:139], v[176:179], v[120:123]
	v_mfma_f32_16x16x32_bf16 v[108:111], v[128:131], v[192:195], v[108:111]
	v_mfma_f32_16x16x32_bf16 v[104:107], v[136:139], v[192:195], v[104:107]
	v_mfma_f32_16x16x32_bf16 v[92:95], v[128:131], v[200:203], v[92:95]
	v_mfma_f32_16x16x32_bf16 v[88:91], v[136:139], v[200:203], v[88:91]
	v_mfma_f32_16x16x32_bf16 v[76:79], v[128:131], v[208:211], v[76:79]
	v_mfma_f32_16x16x32_bf16 v[72:75], v[136:139], v[208:211], v[72:75]
	v_mfma_f32_16x16x32_bf16 v[124:127], v[132:135], v[180:183], v[124:127]
	v_mfma_f32_16x16x32_bf16 v[120:123], v[140:143], v[180:183], v[120:123]
	v_mfma_f32_16x16x32_bf16 v[108:111], v[132:135], v[196:199], v[108:111]
	v_mfma_f32_16x16x32_bf16 v[104:107], v[140:143], v[196:199], v[104:107]
	v_mfma_f32_16x16x32_bf16 v[92:95], v[132:135], v[204:207], v[92:95]
	v_mfma_f32_16x16x32_bf16 v[88:91], v[140:143], v[204:207], v[88:91]
	v_mfma_f32_16x16x32_bf16 v[76:79], v[132:135], v[212:215], v[76:79]
	v_mfma_f32_16x16x32_bf16 v[72:75], v[140:143], v[212:215], v[72:75]
	s_setprio 0
	s_setprio 1
	v_mfma_f32_16x16x32_bf16 v[116:119], v[144:147], v[176:179], v[116:119]
	v_mfma_f32_16x16x32_bf16 v[112:115], v[168:171], v[176:179], v[112:115]
	v_mfma_f32_16x16x32_bf16 v[100:103], v[144:147], v[192:195], v[100:103]
	v_mfma_f32_16x16x32_bf16 v[96:99], v[168:171], v[192:195], v[96:99]
	v_mfma_f32_16x16x32_bf16 v[84:87], v[144:147], v[200:203], v[84:87]
	v_mfma_f32_16x16x32_bf16 v[80:83], v[168:171], v[200:203], v[80:83]
	v_mfma_f32_16x16x32_bf16 v[68:71], v[144:147], v[208:211], v[68:71]
	v_mfma_f32_16x16x32_bf16 v[64:67], v[168:171], v[208:211], v[64:67]
	v_mfma_f32_16x16x32_bf16 v[116:119], v[148:151], v[180:183], v[116:119]
	v_mfma_f32_16x16x32_bf16 v[112:115], v[172:175], v[180:183], v[112:115]
	v_mfma_f32_16x16x32_bf16 v[100:103], v[148:151], v[196:199], v[100:103]
	v_mfma_f32_16x16x32_bf16 v[96:99], v[172:175], v[196:199], v[96:99]
	v_mfma_f32_16x16x32_bf16 v[84:87], v[148:151], v[204:207], v[84:87]
	v_mfma_f32_16x16x32_bf16 v[80:83], v[172:175], v[204:207], v[80:83]
	v_mfma_f32_16x16x32_bf16 v[68:71], v[148:151], v[212:215], v[68:71]
	v_mfma_f32_16x16x32_bf16 v[64:67], v[172:175], v[212:215], v[64:67]
	s_setprio 0
	s_barrier
	s_add_i32 s65, s60, s68
	v_lshl_add_u64 v[184:185], s[50:51], 0, v[154:155]
	s_mov_b32 m0, s65
	ds_read_b128 v[176:179], v191 offset:16384
	ds_read_b128 v[180:183], v191 offset:17408
	ds_read_b128 v[192:195], v191 offset:18432
	ds_read_b128 v[196:199], v191 offset:19456
	ds_read_b128 v[200:203], v191 offset:20480
	ds_read_b128 v[204:207], v191 offset:21504
	ds_read_b128 v[208:211], v191 offset:22528
	ds_read_b128 v[212:215], v191 offset:23552
	global_load_lds_dwordx4 v[184:185], off
	s_add_i32 m0, s65, 0x2000
	s_add_u32 s66, s50, 0x40000
	v_lshl_add_u64 v[216:217], s[50:51], 0, v[158:159]
	s_addc_u32 s67, s51, 0
	s_add_i32 s65, s61, s68
	global_load_lds_dwordx4 v[216:217], off
	s_mov_b32 m0, s65
	v_lshl_add_u64 v[220:221], s[52:53], 0, v[156:157]
	global_load_lds_dwordx4 v154, s[66:67]
	s_add_i32 m0, s65, 0x2000
	s_nop 0
	global_load_lds_dwordx4 v158, s[66:67]
	v_lshl_add_u64 v[218:219], s[52:53], 0, v[152:153]
	s_mov_b32 m0, s74
	s_nop 0
	global_load_lds_dwordx4 v[218:219], off
	s_mov_b32 m0, s41
	s_nop 0
	global_load_lds_dwordx4 v[220:221], off
	s_waitcnt vmcnt(8)
	s_waitcnt lgkmcnt(0)
	s_barrier
; #define PG8_STAGE(bufoff, gbase, voff) do { _Pragma("unroll") for (int _i = 0; _i < 2; ++_i) \
;         __builtin_amdgcn_global_load_lds((const unsigned*)((const char*)(gbase) + (voff)[_i]), (PG8_LAS unsigned*)(lds + (bufoff) + ldsw + _i * 8192), 16, 0, 0); } while (0)
; #define PG8_LDA(dst, b, h) do { _Pragma("unroll") for (int m = 0; m < 4; ++m) _Pragma("unroll") for (int k = 0; k < 2; ++k) dst[m][k] = *(const PG8_LAS bf16x8*)(lds + PG8_SA(b, h) + aoff + m * 2048 + k * 1024); } while (0)
; #define PG8_LDB(dst, b, h) do { _Pragma("unroll") for (int n = 0; n < 2; ++n) _Pragma("unroll") for (int k = 0; k < 2; ++k) dst[n][k] = *(const PG8_LAS bf16x8*)(lds + PG8_SB(b, h) + boff + n * 2048 + k * 1024); } while (0)
; #define PG8_MMA(ai, bj, At, Bt) do { __builtin_amdgcn_s_setprio(1); _Pragma("unroll") for (int m = 0; m < 4; ++m) _Pragma("unroll") for (int n = 0; n < 2; ++n) _Pragma("unroll") for (int k = 0; k < 2; ++k) \
;         acc[ai][bj][m][n] = mma16<F16>(Bt[n][k], At[m][k], acc[ai][bj][m][n]); __builtin_amdgcn_s_setprio(0); } while (0)
; #define PG8_WAIT_V(n) asm volatile("s_waitcnt vmcnt(" #n ")" ::: "memory")
; #define PG8_WAIT_L(n) asm volatile("s_waitcnt lgkmcnt(" #n ")" ::: "memory")
; #define PG8_BAR __builtin_amdgcn_s_barrier()
; #define PG8_SCHED __builtin_amdgcn_sched_barrier(0)
; template <class Epi, class Sched, bool ALIGN_EPI = false, bool SP2 = false, bool F16 = false>
; __device__ __forceinline__ void gemm_phase(PG8_LAS unsigned char* lds, const Gemm g, const Sched& S, const Epi& E, const int wid_in) {
;     ...
;             PG8_WAIT_V(8); PG8_WAIT_L(0); PG8_BAR; PG8_MMA(1, 0, At, B0); PG8_MMA(1, 1, At, B1); PG8_BAR; PG8_SCHED;
;             PG8_LDB(B0, 1, 0); PG8_LDB(B1, 1, 1); PG8_SCHED; PG8_LDA(At, 1, 0); PG8_STAGE(PG8_SA(0, 1), a2 + hstep, voffA);
;             PG8_WAIT_V(8); PG8_WAIT_L(0); PG8_BAR; PG8_MMA(0, 0, At, B0); PG8_MMA(0, 1, At, B1); PG8_BAR; PG8_SCHED;
	s_setprio 1
	s_waitcnt lgkmcnt(0)
	v_mfma_f32_16x16x32_bf16 v[60:63], v[128:131], v[176:179], v[60:63]
	v_mfma_f32_16x16x32_bf16 v[56:59], v[136:139], v[176:179], v[56:59]
	v_mfma_f32_16x16x32_bf16 v[44:47], v[128:131], v[192:195], v[44:47]
	v_mfma_f32_16x16x32_bf16 v[40:43], v[136:139], v[192:195], v[40:43]
	v_mfma_f32_16x16x32_bf16 v[28:31], v[128:131], v[200:203], v[28:31]
	v_mfma_f32_16x16x32_bf16 v[24:27], v[136:139], v[200:203], v[24:27]
	v_mfma_f32_16x16x32_bf16 v[12:15], v[128:131], v[208:211], v[12:15]
	v_mfma_f32_16x16x32_bf16 v[8:11], v[136:139], v[208:211], v[8:11]
	v_mfma_f32_16x16x32_bf16 v[60:63], v[132:135], v[180:183], v[60:63]
	v_mfma_f32_16x16x32_bf16 v[56:59], v[140:143], v[180:183], v[56:59]
	v_mfma_f32_16x16x32_bf16 v[44:47], v[132:135], v[196:199], v[44:47]
	v_mfma_f32_16x16x32_bf16 v[40:43], v[140:143], v[196:199], v[40:43]
	v_mfma_f32_16x16x32_bf16 v[28:31], v[132:135], v[204:207], v[28:31]
	v_mfma_f32_16x16x32_bf16 v[24:27], v[140:143], v[204:207], v[24:27]
	v_mfma_f32_16x16x32_bf16 v[12:15], v[132:135], v[212:215], v[12:15]
	v_mfma_f32_16x16x32_bf16 v[8:11], v[140:143], v[212:215], v[8:11]
	s_setprio 0
	s_setprio 1
	v_mfma_f32_16x16x32_bf16 v[52:55], v[144:147], v[176:179], v[52:55]
	v_mfma_f32_16x16x32_bf16 v[48:51], v[168:171], v[176:179], v[48:51]
	v_mfma_f32_16x16x32_bf16 v[36:39], v[144:147], v[192:195], v[36:39]
	v_mfma_f32_16x16x32_bf16 v[32:35], v[168:171], v[192:195], v[32:35]
	v_mfma_f32_16x16x32_bf16 v[20:23], v[144:147], v[200:203], v[20:23]
	v_mfma_f32_16x16x32_bf16 v[16:19], v[168:171], v[200:203], v[16:19]
	v_mfma_f32_16x16x32_bf16 v[4:7], v[144:147], v[208:211], v[4:7]
	v_mfma_f32_16x16x32_bf16 v[0:3], v[168:171], v[208:211], v[0:3]
	v_mfma_f32_16x16x32_bf16 v[52:55], v[148:151], v[180:183], v[52:55]
	v_mfma_f32_16x16x32_bf16 v[48:51], v[172:175], v[180:183], v[48:51]
	v_mfma_f32_16x16x32_bf16 v[36:39], v[148:151], v[196:199], v[36:39]
	v_mfma_f32_16x16x32_bf16 v[32:35], v[172:175], v[196:199], v[32:35]
	v_mfma_f32_16x16x32_bf16 v[20:23], v[148:151], v[204:207], v[20:23]
	v_mfma_f32_16x16x32_bf16 v[16:19], v[172:175], v[204:207], v[16:19]
	v_mfma_f32_16x16x32_bf16 v[4:7], v[148:151], v[212:215], v[4:7]
	v_mfma_f32_16x16x32_bf16 v[0:3], v[172:175], v[212:215], v[0:3]
	s_setprio 0
	s_barrier
	s_add_i32 s65, 0, 0x18000
	s_add_i32 s66, 0, 0x1c000
	v_add_u32_e32 v140, s65, v188
	v_add_u32_e32 v172, s66, v188
	ds_read_b128 v[128:131], v140
	ds_read_b128 v[132:135], v140 offset:1024
	ds_read_b128 v[136:139], v140 offset:2048
	ds_read_b128 v[140:143], v140 offset:3072
	ds_read_b128 v[144:147], v172
	ds_read_b128 v[148:151], v172 offset:1024
	ds_read_b128 v[168:171], v172 offset:2048
	ds_read_b128 v[172:175], v172 offset:3072
	s_add_u32 s52, s52, 0x40000
	s_addc_u32 s53, s53, 0
	s_mov_b32 m0, s54
	ds_read_b128 v[176:179], v191 offset:32768
	ds_read_b128 v[180:183], v191 offset:33792
	ds_read_b128 v[192:195], v191 offset:34816
	ds_read_b128 v[196:199], v191 offset:35840
	ds_read_b128 v[200:203], v191 offset:36864
	ds_read_b128 v[204:207], v191 offset:37888
	ds_read_b128 v[208:211], v191 offset:38912
	ds_read_b128 v[212:215], v191 offset:39936
	global_load_lds_dwordx4 v152, s[52:53]
	v_lshl_add_u64 v[222:223], s[52:53], 0, v[156:157]
	s_mov_b32 m0, s55
	s_nop 0
	global_load_lds_dwordx4 v[222:223], off
	s_waitcnt vmcnt(8)
	s_waitcnt lgkmcnt(0)
	s_barrier
	s_setprio 1
	s_waitcnt lgkmcnt(0)
	v_mfma_f32_16x16x32_bf16 v[124:127], v[128:131], v[176:179], v[124:127]
	v_mfma_f32_16x16x32_bf16 v[120:123], v[136:139], v[176:179], v[120:123]
	v_mfma_f32_16x16x32_bf16 v[108:111], v[128:131], v[192:195], v[108:111]
	v_mfma_f32_16x16x32_bf16 v[104:107], v[136:139], v[192:195], v[104:107]
	v_mfma_f32_16x16x32_bf16 v[92:95], v[128:131], v[200:203], v[92:95]
	v_mfma_f32_16x16x32_bf16 v[88:91], v[136:139], v[200:203], v[88:91]
	v_mfma_f32_16x16x32_bf16 v[76:79], v[128:131], v[208:211], v[76:79]
	v_mfma_f32_16x16x32_bf16 v[72:75], v[136:139], v[208:211], v[72:75]
	v_mfma_f32_16x16x32_bf16 v[124:127], v[132:135], v[180:183], v[124:127]
	v_mfma_f32_16x16x32_bf16 v[120:123], v[140:143], v[180:183], v[120:123]
	v_mfma_f32_16x16x32_bf16 v[108:111], v[132:135], v[196:199], v[108:111]
	v_mfma_f32_16x16x32_bf16 v[104:107], v[140:143], v[196:199], v[104:107]
	v_mfma_f32_16x16x32_bf16 v[92:95], v[132:135], v[204:207], v[92:95]
	v_mfma_f32_16x16x32_bf16 v[88:91], v[140:143], v[204:207], v[88:91]
	v_mfma_f32_16x16x32_bf16 v[76:79], v[132:135], v[212:215], v[76:79]
	v_mfma_f32_16x16x32_bf16 v[72:75], v[140:143], v[212:215], v[72:75]
	s_setprio 0
	s_setprio 1
	v_mfma_f32_16x16x32_bf16 v[116:119], v[144:147], v[176:179], v[116:119]
	v_mfma_f32_16x16x32_bf16 v[112:115], v[168:171], v[176:179], v[112:115]
	v_mfma_f32_16x16x32_bf16 v[100:103], v[144:147], v[192:195], v[100:103]
	v_mfma_f32_16x16x32_bf16 v[96:99], v[168:171], v[192:195], v[96:99]
	v_mfma_f32_16x16x32_bf16 v[84:87], v[144:147], v[200:203], v[84:87]
	v_mfma_f32_16x16x32_bf16 v[80:83], v[168:171], v[200:203], v[80:83]
	v_mfma_f32_16x16x32_bf16 v[68:71], v[144:147], v[208:211], v[68:71]
	v_mfma_f32_16x16x32_bf16 v[64:67], v[168:171], v[208:211], v[64:67]
	v_mfma_f32_16x16x32_bf16 v[116:119], v[148:151], v[180:183], v[116:119]
	v_mfma_f32_16x16x32_bf16 v[112:115], v[172:175], v[180:183], v[112:115]
	v_mfma_f32_16x16x32_bf16 v[100:103], v[148:151], v[196:199], v[100:103]
	v_mfma_f32_16x16x32_bf16 v[96:99], v[172:175], v[196:199], v[96:99]
	v_mfma_f32_16x16x32_bf16 v[84:87], v[148:151], v[204:207], v[84:87]
	v_mfma_f32_16x16x32_bf16 v[80:83], v[172:175], v[204:207], v[80:83]
	v_mfma_f32_16x16x32_bf16 v[68:71], v[148:151], v[212:215], v[68:71]
	v_mfma_f32_16x16x32_bf16 v[64:67], v[172:175], v[212:215], v[64:67]
	s_setprio 0
	s_barrier
; #define PG8_STAGE(bufoff, gbase, voff) do { _Pragma("unroll") for (int _i = 0; _i < 2; ++_i) \
;         __builtin_amdgcn_global_load_lds((const unsigned*)((const char*)(gbase) + (voff)[_i]), (PG8_LAS unsigned*)(lds + (bufoff) + ldsw + _i * 8192), 16, 0, 0); } while (0)
; #define PG8_LDA(dst, b, h) do { _Pragma("unroll") for (int m = 0; m < 4; ++m) _Pragma("unroll") for (int k = 0; k < 2; ++k) dst[m][k] = *(const PG8_LAS bf16x8*)(lds + PG8_SA(b, h) + aoff + m * 2048 + k * 1024); } while (0)
; #define PG8_MMA(ai, bj, At, Bt) do { __builtin_amdgcn_s_setprio(1); _Pragma("unroll") for (int m = 0; m < 4; ++m) _Pragma("unroll") for (int n = 0; n < 2; ++n) _Pragma("unroll") for (int k = 0; k < 2; ++k) \
;         acc[ai][bj][m][n] = mma16<F16>(Bt[n][k], At[m][k], acc[ai][bj][m][n]); __builtin_amdgcn_s_setprio(0); } while (0)
; #define PG8_WAIT_V(n) asm volatile("s_waitcnt vmcnt(" #n ")" ::: "memory")
; #define PG8_WAIT_L(n) asm volatile("s_waitcnt lgkmcnt(" #n ")" ::: "memory")
; #define PG8_BAR __builtin_amdgcn_s_barrier()
; #define PG8_SCHED __builtin_amdgcn_sched_barrier(0)
; template <class Epi, class Sched, bool ALIGN_EPI = false, bool SP2 = false, bool F16 = false>
; __device__ __forceinline__ void gemm_phase(PG8_LAS unsigned char* lds, const Gemm g, const Sched& S, const Epi& E, const int wid_in) {
;     ...
;         for (int t = 0; t < nt; t += 2) {
;     ...
;             PG8_LDA(At, 1, 1); PG8_STAGE(PG8_SB(1, 0), b3, voffB); PG8_STAGE(PG8_SB(1, 1), b3 + hstep, voffB); PG8_STAGE(PG8_SA(1, 0), a3, voffA);
;             PG8_WAIT_V(8); PG8_WAIT_L(0); PG8_BAR; PG8_MMA(1, 0, At, B0); PG8_MMA(1, 1, At, B1); PG8_BAR; PG8_SCHED;
	s_add_i32 s52, s65, s68
	v_lshl_add_u64 v[184:185], v[184:185], 0, s[28:29]
	s_mov_b32 m0, s52
	ds_read_b128 v[176:179], v191 offset:49152
	ds_read_b128 v[180:183], v191 offset:50176
	ds_read_b128 v[192:195], v191 offset:51200
	ds_read_b128 v[196:199], v191 offset:52224
	ds_read_b128 v[200:203], v191 offset:53248
	ds_read_b128 v[204:207], v191 offset:54272
	ds_read_b128 v[208:211], v191 offset:55296
	ds_read_b128 v[212:215], v191 offset:56320
	global_load_lds_dwordx4 v[184:185], off
	s_add_i32 m0, s52, 0x2000
	s_add_u32 s50, s50, 0x40080
	v_lshl_add_u64 v[184:185], v[216:217], 0, s[28:29]
	s_addc_u32 s51, s51, 0
	s_add_i32 s52, s66, s68
	global_load_lds_dwordx4 v[184:185], off
	s_mov_b32 m0, s52
	s_nop 0
	global_load_lds_dwordx4 v154, s[50:51]
	s_add_i32 m0, s52, 0x2000
	s_nop 0
	global_load_lds_dwordx4 v158, s[50:51]
	v_lshl_add_u64 v[184:185], v[218:219], 0, s[28:29]
	s_mov_b32 m0, s75
	s_nop 0
	global_load_lds_dwordx4 v[184:185], off
	v_lshl_add_u64 v[184:185], v[220:221], 0, s[28:29]
	s_mov_b32 m0, s56
	s_nop 0
	global_load_lds_dwordx4 v[184:185], off
	s_waitcnt vmcnt(8)
	s_waitcnt lgkmcnt(0)
	s_barrier
	s_setprio 1
	s_waitcnt lgkmcnt(0)
	v_mfma_f32_16x16x32_bf16 v[60:63], v[128:131], v[176:179], v[60:63]
	v_mfma_f32_16x16x32_bf16 v[56:59], v[136:139], v[176:179], v[56:59]
	v_mfma_f32_16x16x32_bf16 v[44:47], v[128:131], v[192:195], v[44:47]
	v_mfma_f32_16x16x32_bf16 v[40:43], v[136:139], v[192:195], v[40:43]
	v_mfma_f32_16x16x32_bf16 v[28:31], v[128:131], v[200:203], v[28:31]
	v_mfma_f32_16x16x32_bf16 v[24:27], v[136:139], v[200:203], v[24:27]
	v_mfma_f32_16x16x32_bf16 v[12:15], v[128:131], v[208:211], v[12:15]
	v_mfma_f32_16x16x32_bf16 v[8:11], v[136:139], v[208:211], v[8:11]
	v_mfma_f32_16x16x32_bf16 v[60:63], v[132:135], v[180:183], v[60:63]
	v_mfma_f32_16x16x32_bf16 v[56:59], v[140:143], v[180:183], v[56:59]
	v_mfma_f32_16x16x32_bf16 v[44:47], v[132:135], v[196:199], v[44:47]
	v_mfma_f32_16x16x32_bf16 v[40:43], v[140:143], v[196:199], v[40:43]
	v_mfma_f32_16x16x32_bf16 v[28:31], v[132:135], v[204:207], v[28:31]
	v_mfma_f32_16x16x32_bf16 v[24:27], v[140:143], v[204:207], v[24:27]
	v_mfma_f32_16x16x32_bf16 v[12:15], v[132:135], v[212:215], v[12:15]
	v_mfma_f32_16x16x32_bf16 v[8:11], v[140:143], v[212:215], v[8:11]
	s_setprio 0
	s_setprio 1
	v_mfma_f32_16x16x32_bf16 v[52:55], v[144:147], v[176:179], v[52:55]
	v_mfma_f32_16x16x32_bf16 v[48:51], v[168:171], v[176:179], v[48:51]
	v_mfma_f32_16x16x32_bf16 v[36:39], v[144:147], v[192:195], v[36:39]
	v_mfma_f32_16x16x32_bf16 v[32:35], v[168:171], v[192:195], v[32:35]
	v_mfma_f32_16x16x32_bf16 v[20:23], v[144:147], v[200:203], v[20:23]
	v_mfma_f32_16x16x32_bf16 v[16:19], v[168:171], v[200:203], v[16:19]
	v_mfma_f32_16x16x32_bf16 v[4:7], v[144:147], v[208:211], v[4:7]
	v_mfma_f32_16x16x32_bf16 v[0:3], v[168:171], v[208:211], v[0:3]
	v_mfma_f32_16x16x32_bf16 v[52:55], v[148:151], v[180:183], v[52:55]
	v_mfma_f32_16x16x32_bf16 v[48:51], v[172:175], v[180:183], v[48:51]
	v_mfma_f32_16x16x32_bf16 v[36:39], v[148:151], v[196:199], v[36:39]
	v_mfma_f32_16x16x32_bf16 v[32:35], v[172:175], v[196:199], v[32:35]
	v_mfma_f32_16x16x32_bf16 v[20:23], v[148:151], v[204:207], v[20:23]
	v_mfma_f32_16x16x32_bf16 v[16:19], v[172:175], v[204:207], v[16:19]
	v_mfma_f32_16x16x32_bf16 v[4:7], v[148:151], v[212:215], v[4:7]
	v_mfma_f32_16x16x32_bf16 v[0:3], v[172:175], v[212:215], v[0:3]
	s_setprio 0
	s_barrier
	s_add_i32 s64, s64, 2
	s_add_u32 s48, s48, 0x100
	s_addc_u32 s49, s49, 0
	s_add_u32 s47, s47, 0x100
	s_addc_u32 s63, s63, 0
	s_cmp_gt_u32 s64, 13
	s_cbranch_scc0 .LBB0_1165
	s_and_b64 vcc, exec, s[16:17]
	s_cbranch_vccz .LBB0_1168
	s_barrier

; #define PG8_STAGE(bufoff, gbase, voff) do { _Pragma("unroll") for (int _i = 0; _i < 2; ++_i) \
;         __builtin_amdgcn_global_load_lds((const unsigned*)((const char*)(gbase) + (voff)[_i]), (PG8_LAS unsigned*)(lds + (bufoff) + ldsw + _i * 8192), 16, 0, 0); } while (0)
; #define PG8_WAIT_V(n) asm volatile("s_waitcnt vmcnt(" #n ")" ::: "memory")
; #define PG8_BAR __builtin_amdgcn_s_barrier()
; template <class Epi, class Sched, bool ALIGN_EPI = false, bool SP2 = false, bool F16 = false>
; __device__ __forceinline__ void gemm_phase(PG8_LAS unsigned char* lds, const Gemm g, const Sched& S, const Epi& E, const int wid_in) {
;     ...
;     const int wid = wid_in, lane = lane_, tid = wid * 64 + lane, wr = wid >> 2, wc = wid & 3, fr = lane & 15, fq = lane >> 4;
;     const int K = g.K, nt = K / BK;
;     unsigned voffA[2], voffB[2];
; #pragma unroll
;     for (int i = 0; i < 2; ++i) { int R, C; stage_rc(tid * 16 + i * 8192, R, C); const int Rb = Epi::PERM ? ((R & ~31) + perm32(R & 31)) : R;
;         voffA[i] = (unsigned)(R * K + C) * 2u; voffB[i] = (unsigned)(Rb * K + C) * 2u; }
;     const size_t kstep = (size_t)(BK * 2);
;     const size_t hstep = (size_t)HALF * K * 2;
;     const size_t tstep = 2 * hstep;
;     const unsigned ldsw = (unsigned)wid * 1024u;
;     const int aoff = lds_byte(wr * 64 + fr, fq * 8), boff = lds_byte(wc * 32 + fr, fq * 8);
;     ...
;         PG8_WAIT_V(2); PG8_BAR;
;         PG8_STAGE(PG8_SB(1, 0), cB + kstep, voffB); PG8_STAGE(PG8_SA(1, 0), cA + kstep, voffA); PG8_STAGE(PG8_SB(1, 1), cB + hstep + kstep, voffB);
;         PG8_WAIT_V(6); PG8_BAR;
.LBB0_1236:
	s_add_u32 s12, s14, 0x15400000
	s_addc_u32 s13, s15, 0
	s_add_u32 s22, s14, 0x9400000
	s_mov_b64 s[24:25], 0x80
	s_addc_u32 s23, s15, 0
	s_add_i32 m0, s74, 0x18000
	v_lshl_add_u64 v[6:7], v[6:7], 0, s[24:25]
	s_waitcnt vmcnt(2)
	s_barrier
	global_load_lds_dwordx4 v[6:7], off
	v_lshl_add_u64 v[4:5], v[4:5], 0, s[24:25]
	s_add_i32 m0, s74, 0x1a000
	s_add_i32 s57, s74, 0xa000
	global_load_lds_dwordx4 v[4:5], off
	v_lshl_add_u64 v[0:1], v[0:1], 0, s[24:25]
	s_mov_b32 m0, s75
	s_add_u32 s10, s48, 0x40080
	global_load_lds_dwordx4 v[0:1], off
	v_lshl_add_u64 v[0:1], v[2:3], 0, s[24:25]
	s_mov_b32 m0, s57
	s_addc_u32 s11, s49, 0
	global_load_lds_dwordx4 v[0:1], off
	s_add_i32 m0, s74, 0x1c000
	s_nop 0
	global_load_lds_dwordx4 v162, s[10:11]
	s_add_i32 m0, s74, 0x1e000
	v_and_b32_e32 v190, 15, v8
	global_load_lds_dwordx4 v166, s[10:11]
	v_or_b32_e32 v0, s70, v190
	v_lshlrev_b32_e32 v1, 6, v0
	v_and_b32_e32 v2, 48, v8
	s_movk_i32 s10, 0x3c0
	v_and_b32_e32 v3, 0xfffffc00, v12
	v_lshlrev_b32_e32 v0, 2, v0
	v_and_or_b32 v1, v1, s10, v2
	v_add_u32_e32 v4, s73, v3
	v_and_b32_e32 v0, 32, v0
	v_bitop3_b32 v0, v1, v4, v0 bitop3:0xde
	v_lshl_or_b32 v1, v190, 6, v2
	v_add_u32_e32 v2, s72, v3
	v_lshlrev_b32_e32 v3, 2, v8
	v_and_b32_e32 v3, 32, v3
	v_bitop3_b32 v192, v1, v2, v3 bitop3:0xde
	v_lshlrev_b32_e32 v1, 14, v9
	v_and_b32_e32 v1, 0xffff8000, v1
	v_lshl_add_u32 v1, v10, 11, v1
	v_and_b32_e32 v2, 1, v9
	v_lshl_or_b32 v1, v2, 6, v1
	v_lshl_add_u32 v168, v11, 1, v1
	v_lshlrev_b32_e32 v1, 14, v13
	v_and_b32_e32 v1, 0xffff8000, v1
	s_waitcnt vmcnt(6)
	s_mul_i32 s10, s3, 0x210
	v_lshl_add_u32 v1, v14, 11, v1
	v_and_b32_e32 v2, 1, v13
	s_add_i32 s61, s10, 0
	v_lshl_or_b32 v1, v2, 6, v1
	s_add_i32 s63, 0, 0x10000
	s_add_i32 s64, 0, 0x14000
	v_ashrrev_i32_e32 v191, 4, v8
	s_ashr_i32 s58, s38, 31
	s_mov_b32 s59, s38
	s_ashr_i32 s60, s19, 31
	s_add_i32 s61, s61, 0x20400
	v_mov_b32_e32 v169, v163
	v_lshl_add_u32 v170, v15, 1, v1
	v_mov_b32_e32 v171, v163
	v_mov_b64_e32 v[172:173], 0x580
	v_mov_b64_e32 v[174:175], 0x57f
	s_movk_i32 s62, 0xb1
	v_add_u32_e32 v193, s63, v192
	v_add_u32_e32 v194, s64, v192
	v_add_u32_e32 v195, 0, v0
	v_mov_b32_e32 v196, 0x358637bd
	s_movk_i32 s65, 0x1600
	s_barrier
	s_branch .LBB0_1239

; #define PG8_STAGE(bufoff, gbase, voff) do { _Pragma("unroll") for (int _i = 0; _i < 2; ++_i) \
;         __builtin_amdgcn_global_load_lds((const unsigned*)((const char*)(gbase) + (voff)[_i]), (PG8_LAS unsigned*)(lds + (bufoff) + ldsw + _i * 8192), 16, 0, 0); } while (0)
; #define PG8_LDA(dst, b, h) do { _Pragma("unroll") for (int m = 0; m < 4; ++m) _Pragma("unroll") for (int k = 0; k < 2; ++k) dst[m][k] = *(const PG8_LAS bf16x8*)(lds + PG8_SA(b, h) + aoff + m * 2048 + k * 1024); } while (0)
; #define PG8_LDB(dst, b, h) do { _Pragma("unroll") for (int n = 0; n < 2; ++n) _Pragma("unroll") for (int k = 0; k < 2; ++k) dst[n][k] = *(const PG8_LAS bf16x8*)(lds + PG8_SB(b, h) + boff + n * 2048 + k * 1024); } while (0)
; #define PG8_MMA(ai, bj, At, Bt) do { __builtin_amdgcn_s_setprio(1); _Pragma("unroll") for (int m = 0; m < 4; ++m) _Pragma("unroll") for (int n = 0; n < 2; ++n) _Pragma("unroll") for (int k = 0; k < 2; ++k) \
;         acc[ai][bj][m][n] = mma16<F16>(Bt[n][k], At[m][k], acc[ai][bj][m][n]); __builtin_amdgcn_s_setprio(0); } while (0)
; #define PG8_WAIT_V(n) asm volatile("s_waitcnt vmcnt(" #n ")" ::: "memory")
; #define PG8_BAR __builtin_amdgcn_s_barrier()
; template <class Epi, class Sched, bool ALIGN_EPI = false, bool SP2 = false, bool F16 = false>
; __device__ __forceinline__ void gemm_phase(PG8_LAS unsigned char* lds, const Gemm g, const Sched& S, const Epi& E, const int wid_in) {
;     ...
;         for (int t = 0; t < nt; t += 2) {
;             const bool last = (t == nt - 2);
;             const char* a1 = cA + (size_t)(t + 1) * kstep;
;             const char* a2 = last ? nA : cA + (size_t)(t + 2) * kstep; const char* b2 = last ? nB : cB + (size_t)(t + 2) * kstep;
;             const char* a3 = a2 + kstep; const char* b3 = b2 + kstep;
;             if (last && has_next) S.a_ready(nxt);
;             if constexpr (SP2) {
;             PG8_LDB(B0, 0, 0); PG8_LDB(B1, 0, 1); PG8_SCHED; PG8_LDA(At, 0, 0); PG8_STAGE(PG8_SA(1, 1), a1 + hstep, voffA);
;             PG8_WAIT_V(8); PG8_WAIT_L(0); PG8_BAR; PG8_MMA(0, 0, At, B0); PG8_MMA(0, 1, At, B1); PG8_BAR; PG8_SCHED;
;             PG8_LDA(At, 0, 1); PG8_STAGE(PG8_SB(0, 0), b2, voffB); PG8_STAGE(PG8_SB(0, 1), b2 + hstep, voffB); PG8_STAGE(PG8_SA(0, 0), a2, voffA);
;             PG8_WAIT_V(8); PG8_WAIT_L(0); PG8_BAR; PG8_MMA(1, 0, At, B0); PG8_MMA(1, 1, At, B1); PG8_BAR; PG8_SCHED;
.LBB0_1242:
	ds_read_b128 v[0:3], v193
	ds_read_b128 v[4:7], v193 offset:1024
	ds_read_b128 v[136:139], v193 offset:2048
	ds_read_b128 v[140:143], v193 offset:3072
	ds_read_b128 v[144:147], v194
	ds_read_b128 v[148:151], v194 offset:1024
	ds_read_b128 v[152:155], v194 offset:2048
	ds_read_b128 v[156:159], v194 offset:3072
	s_add_u32 s48, s46, 0xfffc0080
	s_addc_u32 s49, s47, -1
	s_cmp_eq_u32 s67, 12
	s_cselect_b32 s51, s29, s49
	s_cselect_b32 s50, s42, s48
	s_cselect_b32 s49, s27, s66
	s_cselect_b32 s48, s43, s45
	s_add_i32 m0, s74, 0xc000
	ds_read_b128 v[176:179], v195
	ds_read_b128 v[180:183], v195 offset:1024
	ds_read_b128 v[184:187], v195 offset:2048
	ds_read_b128 v[198:201], v195 offset:3072
	ds_read_b128 v[202:205], v195 offset:4096
	ds_read_b128 v[206:209], v195 offset:5120
	ds_read_b128 v[210:213], v195 offset:6144
	ds_read_b128 v[214:217], v195 offset:7168
	global_load_lds_dwordx4 v168, s[46:47]
	s_add_i32 m0, s74, 0xe000
	s_nop 0
	global_load_lds_dwordx4 v170, s[46:47]
	s_waitcnt vmcnt(8)
	s_waitcnt lgkmcnt(0)
	s_barrier
	s_setprio 1
	s_waitcnt lgkmcnt(0)
	v_mfma_f32_16x16x32_f16 v[132:135], v[0:3], v[176:179], v[132:135]
	v_mfma_f32_16x16x32_f16 v[128:131], v[136:139], v[176:179], v[128:131]
	v_mfma_f32_16x16x32_f16 v[116:119], v[0:3], v[184:187], v[116:119]
	v_mfma_f32_16x16x32_f16 v[112:115], v[136:139], v[184:187], v[112:115]
	v_mfma_f32_16x16x32_f16 v[100:103], v[0:3], v[202:205], v[100:103]
	v_mfma_f32_16x16x32_f16 v[96:99], v[136:139], v[202:205], v[96:99]
	v_mfma_f32_16x16x32_f16 v[84:87], v[0:3], v[210:213], v[84:87]
	v_mfma_f32_16x16x32_f16 v[80:83], v[136:139], v[210:213], v[80:83]
	v_mfma_f32_16x16x32_f16 v[132:135], v[4:7], v[180:183], v[132:135]
	v_mfma_f32_16x16x32_f16 v[128:131], v[140:143], v[180:183], v[128:131]
	v_mfma_f32_16x16x32_f16 v[116:119], v[4:7], v[198:201], v[116:119]
	v_mfma_f32_16x16x32_f16 v[112:115], v[140:143], v[198:201], v[112:115]
	v_mfma_f32_16x16x32_f16 v[100:103], v[4:7], v[206:209], v[100:103]
	v_mfma_f32_16x16x32_f16 v[96:99], v[140:143], v[206:209], v[96:99]
	v_mfma_f32_16x16x32_f16 v[84:87], v[4:7], v[214:217], v[84:87]
	v_mfma_f32_16x16x32_f16 v[80:83], v[140:143], v[214:217], v[80:83]
	s_setprio 0
	s_setprio 1
	v_mfma_f32_16x16x32_f16 v[124:127], v[144:147], v[176:179], v[124:127]
	v_mfma_f32_16x16x32_f16 v[120:123], v[152:155], v[176:179], v[120:123]
	v_mfma_f32_16x16x32_f16 v[108:111], v[144:147], v[184:187], v[108:111]
	v_mfma_f32_16x16x32_f16 v[104:107], v[152:155], v[184:187], v[104:107]
	v_mfma_f32_16x16x32_f16 v[92:95], v[144:147], v[202:205], v[92:95]
	v_mfma_f32_16x16x32_f16 v[88:91], v[152:155], v[202:205], v[88:91]
	v_mfma_f32_16x16x32_f16 v[76:79], v[144:147], v[210:213], v[76:79]
	v_mfma_f32_16x16x32_f16 v[72:75], v[152:155], v[210:213], v[72:75]
	v_mfma_f32_16x16x32_f16 v[124:127], v[148:151], v[180:183], v[124:127]
	v_mfma_f32_16x16x32_f16 v[120:123], v[156:159], v[180:183], v[120:123]
	v_mfma_f32_16x16x32_f16 v[108:111], v[148:151], v[198:201], v[108:111]
	v_mfma_f32_16x16x32_f16 v[104:107], v[156:159], v[198:201], v[104:107]
	v_mfma_f32_16x16x32_f16 v[92:95], v[148:151], v[206:209], v[92:95]
	v_mfma_f32_16x16x32_f16 v[88:91], v[156:159], v[206:209], v[88:91]
	v_mfma_f32_16x16x32_f16 v[76:79], v[148:151], v[214:217], v[76:79]
	v_mfma_f32_16x16x32_f16 v[72:75], v[156:159], v[214:217], v[72:75]
	s_setprio 0
	s_barrier
	s_add_i32 s76, s63, s68
	v_lshl_add_u64 v[188:189], s[48:49], 0, v[162:163]
	s_mov_b32 m0, s76
	ds_read_b128 v[176:179], v195 offset:16384
	ds_read_b128 v[180:183], v195 offset:17408
	ds_read_b128 v[184:187], v195 offset:18432
	ds_read_b128 v[198:201], v195 offset:19456
	ds_read_b128 v[202:205], v195 offset:20480
	ds_read_b128 v[206:209], v195 offset:21504
	ds_read_b128 v[210:213], v195 offset:22528
	ds_read_b128 v[214:217], v195 offset:23552
	global_load_lds_dwordx4 v[188:189], off
	s_add_i32 m0, s76, 0x2000
	s_add_u32 s90, s48, 0x40000
	v_lshl_add_u64 v[218:219], s[48:49], 0, v[166:167]
	s_addc_u32 s91, s49, 0
	s_add_i32 s76, s64, s68
	global_load_lds_dwordx4 v[218:219], off
	s_mov_b32 m0, s76
	v_lshl_add_u64 v[222:223], s[50:51], 0, v[164:165]
	global_load_lds_dwordx4 v162, s[90:91]
	s_add_i32 m0, s76, 0x2000
	s_nop 0
	global_load_lds_dwordx4 v166, s[90:91]
	v_lshl_add_u64 v[220:221], s[50:51], 0, v[160:161]
	s_mov_b32 m0, s74
	s_nop 0
	global_load_lds_dwordx4 v[220:221], off
	s_mov_b32 m0, s37
	s_nop 0
	global_load_lds_dwordx4 v[222:223], off
	s_waitcnt vmcnt(8)
	s_waitcnt lgkmcnt(0)
	s_barrier
	s_setprio 1
	s_waitcnt lgkmcnt(0)
	v_mfma_f32_16x16x32_f16 v[68:71], v[0:3], v[176:179], v[68:71]
	v_mfma_f32_16x16x32_f16 v[64:67], v[136:139], v[176:179], v[64:67]
	v_mfma_f32_16x16x32_f16 v[52:55], v[0:3], v[184:187], v[52:55]
	v_mfma_f32_16x16x32_f16 v[48:51], v[136:139], v[184:187], v[48:51]
	v_mfma_f32_16x16x32_f16 v[36:39], v[0:3], v[202:205], v[36:39]
	v_mfma_f32_16x16x32_f16 v[32:35], v[136:139], v[202:205], v[32:35]
	v_mfma_f32_16x16x32_f16 v[0:3], v[0:3], v[210:213], v[20:23]
	v_mfma_f32_16x16x32_f16 v[68:71], v[4:7], v[180:183], v[68:71]
	v_mfma_f32_16x16x32_f16 v[64:67], v[140:143], v[180:183], v[64:67]
	v_mfma_f32_16x16x32_f16 v[52:55], v[4:7], v[198:201], v[52:55]
	v_mfma_f32_16x16x32_f16 v[48:51], v[140:143], v[198:201], v[48:51]
	v_mfma_f32_16x16x32_f16 v[36:39], v[4:7], v[206:209], v[36:39]
	v_mfma_f32_16x16x32_f16 v[32:35], v[140:143], v[206:209], v[32:35]
	v_mfma_f32_16x16x32_f16 v[0:3], v[4:7], v[214:217], v[0:3]
	v_mfma_f32_16x16x32_f16 v[4:7], v[136:139], v[210:213], v[16:19]
	v_mfma_f32_16x16x32_f16 v[4:7], v[140:143], v[214:217], v[4:7]
	s_setprio 0
	s_setprio 1
	v_mfma_f32_16x16x32_f16 v[16:19], v[144:147], v[176:179], v[60:63]
	v_mfma_f32_16x16x32_f16 v[60:63], v[148:151], v[180:183], v[16:19]
	v_mfma_f32_16x16x32_f16 v[16:19], v[152:155], v[176:179], v[56:59]
	v_mfma_f32_16x16x32_f16 v[56:59], v[156:159], v[180:183], v[16:19]
	v_mfma_f32_16x16x32_f16 v[16:19], v[144:147], v[184:187], v[44:47]
	v_mfma_f32_16x16x32_f16 v[44:47], v[148:151], v[198:201], v[16:19]
	v_mfma_f32_16x16x32_f16 v[16:19], v[152:155], v[184:187], v[40:43]
	v_mfma_f32_16x16x32_f16 v[40:43], v[156:159], v[198:201], v[16:19]
	v_mfma_f32_16x16x32_f16 v[16:19], v[144:147], v[202:205], v[28:31]
	v_mfma_f32_16x16x32_f16 v[28:31], v[148:151], v[206:209], v[16:19]
	v_mfma_f32_16x16x32_f16 v[16:19], v[152:155], v[202:205], v[24:27]
	v_mfma_f32_16x16x32_f16 v[12:15], v[144:147], v[210:213], v[12:15]
	v_mfma_f32_16x16x32_f16 v[8:11], v[152:155], v[210:213], v[8:11]
	v_mfma_f32_16x16x32_f16 v[24:27], v[156:159], v[206:209], v[16:19]
	v_mfma_f32_16x16x32_f16 v[12:15], v[148:151], v[214:217], v[12:15]
	v_mfma_f32_16x16x32_f16 v[8:11], v[156:159], v[214:217], v[8:11]
	s_setprio 0
	s_barrier
; #define PG8_STAGE(bufoff, gbase, voff) do { _Pragma("unroll") for (int _i = 0; _i < 2; ++_i) \
;         __builtin_amdgcn_global_load_lds((const unsigned*)((const char*)(gbase) + (voff)[_i]), (PG8_LAS unsigned*)(lds + (bufoff) + ldsw + _i * 8192), 16, 0, 0); } while (0)
; #define PG8_LDA(dst, b, h) do { _Pragma("unroll") for (int m = 0; m < 4; ++m) _Pragma("unroll") for (int k = 0; k < 2; ++k) dst[m][k] = *(const PG8_LAS bf16x8*)(lds + PG8_SA(b, h) + aoff + m * 2048 + k * 1024); } while (0)
; #define PG8_LDB(dst, b, h) do { _Pragma("unroll") for (int n = 0; n < 2; ++n) _Pragma("unroll") for (int k = 0; k < 2; ++k) dst[n][k] = *(const PG8_LAS bf16x8*)(lds + PG8_SB(b, h) + boff + n * 2048 + k * 1024); } while (0)
; #define PG8_MMA(ai, bj, At, Bt) do { __builtin_amdgcn_s_setprio(1); _Pragma("unroll") for (int m = 0; m < 4; ++m) _Pragma("unroll") for (int n = 0; n < 2; ++n) _Pragma("unroll") for (int k = 0; k < 2; ++k) \
;         acc[ai][bj][m][n] = mma16<F16>(Bt[n][k], At[m][k], acc[ai][bj][m][n]); __builtin_amdgcn_s_setprio(0); } while (0)
; #define PG8_WAIT_V(n) asm volatile("s_waitcnt vmcnt(" #n ")" ::: "memory")
; #define PG8_WAIT_L(n) asm volatile("s_waitcnt lgkmcnt(" #n ")" ::: "memory")
; #define PG8_BAR __builtin_amdgcn_s_barrier()
; #define PG8_SCHED __builtin_amdgcn_sched_barrier(0)
; template <class Epi, class Sched, bool ALIGN_EPI = false, bool SP2 = false, bool F16 = false>
; __device__ __forceinline__ void gemm_phase(PG8_LAS unsigned char* lds, const Gemm g, const Sched& S, const Epi& E, const int wid_in) {
;     ...
;         for (int t = 0; t < nt; t += 2) {
;     ...
;             PG8_LDB(B0, 1, 0); PG8_LDB(B1, 1, 1); PG8_SCHED; PG8_LDA(At, 1, 0); PG8_STAGE(PG8_SA(0, 1), a2 + hstep, voffA);
;             PG8_WAIT_V(8); PG8_WAIT_L(0); PG8_BAR; PG8_MMA(0, 0, At, B0); PG8_MMA(0, 1, At, B1); PG8_BAR; PG8_SCHED;
;             PG8_LDA(At, 1, 1); PG8_STAGE(PG8_SB(1, 0), b3, voffB); PG8_STAGE(PG8_SB(1, 1), b3 + hstep, voffB); PG8_STAGE(PG8_SA(1, 0), a3, voffA);
;             PG8_WAIT_V(8); PG8_WAIT_L(0); PG8_BAR; PG8_MMA(1, 0, At, B0); PG8_MMA(1, 1, At, B1); PG8_BAR; PG8_SCHED;
	s_add_i32 s76, 0, 0x18000
	s_add_i32 s83, 0, 0x1c000
	v_add_u32_e32 v140, s76, v192
	v_add_u32_e32 v156, s83, v192
	ds_read_b128 v[16:19], v140
	ds_read_b128 v[20:23], v140 offset:1024
	ds_read_b128 v[136:139], v140 offset:2048
	ds_read_b128 v[140:143], v140 offset:3072
	ds_read_b128 v[144:147], v156
	ds_read_b128 v[148:151], v156 offset:1024
	ds_read_b128 v[152:155], v156 offset:2048
	ds_read_b128 v[156:159], v156 offset:3072
	s_add_u32 s50, s50, 0x40000
	s_addc_u32 s51, s51, 0
	s_mov_b32 m0, s53
	ds_read_b128 v[176:179], v195 offset:32768
	ds_read_b128 v[180:183], v195 offset:33792
	ds_read_b128 v[184:187], v195 offset:34816
	ds_read_b128 v[198:201], v195 offset:35840
	ds_read_b128 v[202:205], v195 offset:36864
	ds_read_b128 v[206:209], v195 offset:37888
	ds_read_b128 v[210:213], v195 offset:38912
	ds_read_b128 v[214:217], v195 offset:39936
	global_load_lds_dwordx4 v160, s[50:51]
	v_lshl_add_u64 v[224:225], s[50:51], 0, v[164:165]
	s_mov_b32 m0, s54
	s_nop 0
	global_load_lds_dwordx4 v[224:225], off
	s_waitcnt vmcnt(8)
	s_waitcnt lgkmcnt(0)
	s_barrier
	s_setprio 1
	s_waitcnt lgkmcnt(0)
	v_mfma_f32_16x16x32_f16 v[132:135], v[16:19], v[176:179], v[132:135]
	v_mfma_f32_16x16x32_f16 v[128:131], v[136:139], v[176:179], v[128:131]
	v_mfma_f32_16x16x32_f16 v[116:119], v[16:19], v[184:187], v[116:119]
	v_mfma_f32_16x16x32_f16 v[112:115], v[136:139], v[184:187], v[112:115]
	v_mfma_f32_16x16x32_f16 v[100:103], v[16:19], v[202:205], v[100:103]
	v_mfma_f32_16x16x32_f16 v[96:99], v[136:139], v[202:205], v[96:99]
	v_mfma_f32_16x16x32_f16 v[84:87], v[16:19], v[210:213], v[84:87]
	v_mfma_f32_16x16x32_f16 v[80:83], v[136:139], v[210:213], v[80:83]
	v_mfma_f32_16x16x32_f16 v[132:135], v[20:23], v[180:183], v[132:135]
	v_mfma_f32_16x16x32_f16 v[128:131], v[140:143], v[180:183], v[128:131]
	v_mfma_f32_16x16x32_f16 v[116:119], v[20:23], v[198:201], v[116:119]
	v_mfma_f32_16x16x32_f16 v[112:115], v[140:143], v[198:201], v[112:115]
	v_mfma_f32_16x16x32_f16 v[100:103], v[20:23], v[206:209], v[100:103]
	v_mfma_f32_16x16x32_f16 v[96:99], v[140:143], v[206:209], v[96:99]
	v_mfma_f32_16x16x32_f16 v[84:87], v[20:23], v[214:217], v[84:87]
	v_mfma_f32_16x16x32_f16 v[80:83], v[140:143], v[214:217], v[80:83]
	s_setprio 0
	s_setprio 1
	v_mfma_f32_16x16x32_f16 v[124:127], v[144:147], v[176:179], v[124:127]
	v_mfma_f32_16x16x32_f16 v[120:123], v[152:155], v[176:179], v[120:123]
	v_mfma_f32_16x16x32_f16 v[108:111], v[144:147], v[184:187], v[108:111]
	v_mfma_f32_16x16x32_f16 v[104:107], v[152:155], v[184:187], v[104:107]
	v_mfma_f32_16x16x32_f16 v[92:95], v[144:147], v[202:205], v[92:95]
	v_mfma_f32_16x16x32_f16 v[88:91], v[152:155], v[202:205], v[88:91]
	v_mfma_f32_16x16x32_f16 v[76:79], v[144:147], v[210:213], v[76:79]
	v_mfma_f32_16x16x32_f16 v[72:75], v[152:155], v[210:213], v[72:75]
	v_mfma_f32_16x16x32_f16 v[124:127], v[148:151], v[180:183], v[124:127]
	v_mfma_f32_16x16x32_f16 v[120:123], v[156:159], v[180:183], v[120:123]
	v_mfma_f32_16x16x32_f16 v[108:111], v[148:151], v[198:201], v[108:111]
	v_mfma_f32_16x16x32_f16 v[104:107], v[156:159], v[198:201], v[104:107]
	v_mfma_f32_16x16x32_f16 v[92:95], v[148:151], v[206:209], v[92:95]
	v_mfma_f32_16x16x32_f16 v[88:91], v[156:159], v[206:209], v[88:91]
	v_mfma_f32_16x16x32_f16 v[76:79], v[148:151], v[214:217], v[76:79]
	v_mfma_f32_16x16x32_f16 v[72:75], v[156:159], v[214:217], v[72:75]
	s_setprio 0
	s_barrier
	s_add_i32 s50, s76, s68
	v_lshl_add_u64 v[188:189], v[188:189], 0, s[24:25]
	s_mov_b32 m0, s50
	ds_read_b128 v[176:179], v195 offset:49152
	ds_read_b128 v[180:183], v195 offset:50176
	ds_read_b128 v[184:187], v195 offset:51200
	ds_read_b128 v[198:201], v195 offset:52224
	ds_read_b128 v[202:205], v195 offset:53248
	ds_read_b128 v[206:209], v195 offset:54272
	ds_read_b128 v[210:213], v195 offset:55296
	ds_read_b128 v[214:217], v195 offset:56320
	global_load_lds_dwordx4 v[188:189], off
	s_add_i32 m0, s50, 0x2000
	s_add_u32 s48, s48, 0x40080
	v_lshl_add_u64 v[188:189], v[218:219], 0, s[24:25]
	s_addc_u32 s49, s49, 0
	s_add_i32 s50, s83, s68
	global_load_lds_dwordx4 v[188:189], off
	s_mov_b32 m0, s50
	s_nop 0
	global_load_lds_dwordx4 v162, s[48:49]
	s_add_i32 m0, s50, 0x2000
	s_nop 0
	global_load_lds_dwordx4 v166, s[48:49]
	v_lshl_add_u64 v[188:189], v[220:221], 0, s[24:25]
	s_mov_b32 m0, s75
	s_nop 0
	global_load_lds_dwordx4 v[188:189], off
	v_lshl_add_u64 v[188:189], v[222:223], 0, s[24:25]
	s_mov_b32 m0, s57
	s_nop 0
	global_load_lds_dwordx4 v[188:189], off
	s_waitcnt vmcnt(8)
	s_waitcnt lgkmcnt(0)
	s_barrier
	s_setprio 1
	s_waitcnt lgkmcnt(0)
	v_mfma_f32_16x16x32_f16 v[68:71], v[16:19], v[176:179], v[68:71]
	v_mfma_f32_16x16x32_f16 v[52:55], v[16:19], v[184:187], v[52:55]
	v_mfma_f32_16x16x32_f16 v[36:39], v[16:19], v[202:205], v[36:39]
	v_mfma_f32_16x16x32_f16 v[0:3], v[16:19], v[210:213], v[0:3]
	v_mfma_f32_16x16x32_f16 v[68:71], v[20:23], v[180:183], v[68:71]
	v_mfma_f32_16x16x32_f16 v[64:67], v[136:139], v[176:179], v[64:67]
	v_mfma_f32_16x16x32_f16 v[52:55], v[20:23], v[198:201], v[52:55]
	v_mfma_f32_16x16x32_f16 v[48:51], v[136:139], v[184:187], v[48:51]
	v_mfma_f32_16x16x32_f16 v[36:39], v[20:23], v[206:209], v[36:39]
	v_mfma_f32_16x16x32_f16 v[32:35], v[136:139], v[202:205], v[32:35]
	v_mfma_f32_16x16x32_f16 v[20:23], v[20:23], v[214:217], v[0:3]
	v_mfma_f32_16x16x32_f16 v[0:3], v[136:139], v[210:213], v[4:7]
	v_mfma_f32_16x16x32_f16 v[64:67], v[140:143], v[180:183], v[64:67]
	v_mfma_f32_16x16x32_f16 v[48:51], v[140:143], v[198:201], v[48:51]
	v_mfma_f32_16x16x32_f16 v[32:35], v[140:143], v[206:209], v[32:35]
	v_mfma_f32_16x16x32_f16 v[16:19], v[140:143], v[214:217], v[0:3]
	s_setprio 0
	s_setprio 1
	v_mfma_f32_16x16x32_f16 v[0:3], v[144:147], v[176:179], v[60:63]
	v_mfma_f32_16x16x32_f16 v[60:63], v[148:151], v[180:183], v[0:3]
	v_mfma_f32_16x16x32_f16 v[0:3], v[152:155], v[176:179], v[56:59]
	v_mfma_f32_16x16x32_f16 v[56:59], v[156:159], v[180:183], v[0:3]
	v_mfma_f32_16x16x32_f16 v[0:3], v[144:147], v[184:187], v[44:47]
	v_mfma_f32_16x16x32_f16 v[44:47], v[148:151], v[198:201], v[0:3]
	v_mfma_f32_16x16x32_f16 v[0:3], v[152:155], v[184:187], v[40:43]
	v_mfma_f32_16x16x32_f16 v[40:43], v[156:159], v[198:201], v[0:3]
	v_mfma_f32_16x16x32_f16 v[0:3], v[144:147], v[202:205], v[28:31]
	v_mfma_f32_16x16x32_f16 v[28:31], v[148:151], v[206:209], v[0:3]
	v_mfma_f32_16x16x32_f16 v[0:3], v[152:155], v[202:205], v[24:27]
	v_mfma_f32_16x16x32_f16 v[24:27], v[156:159], v[206:209], v[0:3]
	v_mfma_f32_16x16x32_f16 v[0:3], v[144:147], v[210:213], v[12:15]
	v_mfma_f32_16x16x32_f16 v[12:15], v[148:151], v[214:217], v[0:3]
	v_mfma_f32_16x16x32_f16 v[0:3], v[152:155], v[210:213], v[8:11]
	v_mfma_f32_16x16x32_f16 v[8:11], v[156:159], v[214:217], v[0:3]
	s_setprio 0
	s_barrier
	s_add_i32 s67, s67, 2
	s_add_u32 s46, s46, 0x100
	s_addc_u32 s47, s47, 0
	s_add_u32 s45, s45, 0x100
	s_addc_u32 s66, s66, 0
	s_cmp_gt_u32 s67, 13
	s_cbranch_scc0 .LBB0_1242
	s_and_b64 vcc, exec, s[16:17]
	s_cbranch_vccz .LBB0_1245
	s_barrier

; #define PG8_STAGE(bufoff, gbase, voff) do { _Pragma("unroll") for (int _i = 0; _i < 2; ++_i) \
;         __builtin_amdgcn_global_load_lds((const unsigned*)((const char*)(gbase) + (voff)[_i]), (PG8_LAS unsigned*)(lds + (bufoff) + ldsw + _i * 8192), 16, 0, 0); } while (0)
; #define PG8_WAIT_V(n) asm volatile("s_waitcnt vmcnt(" #n ")" ::: "memory")
; #define PG8_BAR __builtin_amdgcn_s_barrier()
; template <class Epi, class Sched, bool ALIGN_EPI = false, bool SP2 = false, bool F16 = false>
; __device__ __forceinline__ void gemm_phase(PG8_LAS unsigned char* lds, const Gemm g, const Sched& S, const Epi& E, const int wid_in) {
;     ...
;     const int wid = wid_in, lane = lane_, tid = wid * 64 + lane, wr = wid >> 2, wc = wid & 3, fr = lane & 15, fq = lane >> 4;
;     const int K = g.K, nt = K / BK;
;     unsigned voffA[2], voffB[2];
; #pragma unroll
;     for (int i = 0; i < 2; ++i) { int R, C; stage_rc(tid * 16 + i * 8192, R, C); const int Rb = Epi::PERM ? ((R & ~31) + perm32(R & 31)) : R;
;         voffA[i] = (unsigned)(R * K + C) * 2u; voffB[i] = (unsigned)(Rb * K + C) * 2u; }
;     const size_t kstep = (size_t)(BK * 2);
;     const size_t hstep = (size_t)HALF * K * 2;
;     const size_t tstep = 2 * hstep;
;     const unsigned ldsw = (unsigned)wid * 1024u;
;     const int aoff = lds_byte(wr * 64 + fr, fq * 8), boff = lds_byte(wc * 32 + fr, fq * 8);
;     ...
;         PG8_WAIT_V(2); PG8_BAR;
;         PG8_STAGE(PG8_SB(1, 0), cB + kstep, voffB); PG8_STAGE(PG8_SA(1, 0), cA + kstep, voffA); PG8_STAGE(PG8_SB(1, 1), cB + hstep + kstep, voffB);
;         PG8_WAIT_V(6); PG8_BAR;
.LBB0_1274:
	s_add_u32 s22, s14, 0xf400000
	s_mov_b64 s[24:25], 0x80
	s_addc_u32 s23, s15, 0
	s_add_i32 m0, s74, 0x18000
	v_lshl_add_u64 v[6:7], v[6:7], 0, s[24:25]
	s_waitcnt vmcnt(2)
	s_barrier
	global_load_lds_dwordx4 v[6:7], off
	v_lshl_add_u64 v[4:5], v[4:5], 0, s[24:25]
	s_add_i32 m0, s74, 0x1a000
	s_add_i32 s14, s74, 0xa000
	global_load_lds_dwordx4 v[4:5], off
	v_lshl_add_u64 v[2:3], v[2:3], 0, s[24:25]
	s_mov_b32 m0, s75
	s_add_u32 s26, s10, 0x10080
	global_load_lds_dwordx4 v[2:3], off
	v_lshl_add_u64 v[0:1], v[0:1], 0, s[24:25]
	s_mov_b32 m0, s14
	s_addc_u32 s27, s11, 0
	global_load_lds_dwordx4 v[0:1], off
	s_add_i32 m0, s74, 0x1c000
	s_nop 0
	global_load_lds_dwordx4 v130, s[26:27]
	s_add_i32 m0, s74, 0x1e000
	v_and_b32_e32 v132, 15, v8
	global_load_lds_dwordx4 v128, s[26:27]
	v_or_b32_e32 v0, s70, v132
	v_ashrrev_i32_e32 v1, 6, v8
	v_lshlrev_b32_e32 v2, 6, v0
	v_and_b32_e32 v3, 48, v8
	s_movk_i32 s15, 0x3c0
	v_lshlrev_b32_e32 v0, 2, v0
	v_and_or_b32 v2, v2, s15, v3
	v_lshl_add_u32 v4, v1, 10, s73
	v_and_b32_e32 v0, 32, v0
	v_bitop3_b32 v0, v2, v4, v0 bitop3:0xde
	v_lshl_or_b32 v2, v132, 6, v3
	v_lshlrev_b32_e32 v3, 2, v8
	v_add_lshl_u32 v1, v1, s96, 10
	v_and_b32_e32 v3, 32, v3
	v_bitop3_b32 v1, v2, v1, v3 bitop3:0xde
	s_waitcnt vmcnt(6)
	s_add_i32 s53, 0, 0x10000
	s_add_i32 s55, 0, 0x14000
	s_add_i32 s57, 0, 0x18000
	s_add_i32 s59, 0, 0x1c000
	v_add_u32_e32 v134, s53, v1
	v_add_u32_e32 v135, s55, v1
	s_add_i32 s53, s53, s68
	s_add_i32 s55, s55, s68
	v_add_u32_e32 v137, s57, v1
	v_add_u32_e32 v138, s59, v1
	s_add_i32 s57, s57, s68
	s_add_i32 s59, s59, s68
	v_ashrrev_i32_e32 v133, 4, v8
	s_mov_b64 s[30:31], -1
	v_add_u32_e32 v136, 0, v0
	s_add_i32 s15, s74, 0xc000
	s_add_i32 s52, s74, 0xe000
	s_mov_b64 s[26:27], 0x100
	s_add_i32 s54, s53, 0x2000
	s_add_i32 s56, s55, 0x2000
	s_mov_b64 s[28:29], 0x180
	s_add_i32 s58, s57, 0x2000
	s_add_i32 s60, s59, 0x2000
	s_barrier
	s_branch .LBB0_1277

; #define PG8_STAGE(bufoff, gbase, voff) do { _Pragma("unroll") for (int _i = 0; _i < 2; ++_i) \
;         __builtin_amdgcn_global_load_lds((const unsigned*)((const char*)(gbase) + (voff)[_i]), (PG8_LAS unsigned*)(lds + (bufoff) + ldsw + _i * 8192), 16, 0, 0); } while (0)
; #define PG8_LDA(dst, b, h) do { _Pragma("unroll") for (int m = 0; m < 4; ++m) _Pragma("unroll") for (int k = 0; k < 2; ++k) dst[m][k] = *(const PG8_LAS bf16x8*)(lds + PG8_SA(b, h) + aoff + m * 2048 + k * 1024); } while (0)
; #define PG8_LDB(dst, b, h) do { _Pragma("unroll") for (int n = 0; n < 2; ++n) _Pragma("unroll") for (int k = 0; k < 2; ++k) dst[n][k] = *(const PG8_LAS bf16x8*)(lds + PG8_SB(b, h) + boff + n * 2048 + k * 1024); } while (0)
; #define PG8_MMA(ai, bj, At, Bt) do { __builtin_amdgcn_s_setprio(1); _Pragma("unroll") for (int m = 0; m < 4; ++m) _Pragma("unroll") for (int n = 0; n < 2; ++n) _Pragma("unroll") for (int k = 0; k < 2; ++k) \
;         acc[ai][bj][m][n] = mma16<F16>(Bt[n][k], At[m][k], acc[ai][bj][m][n]); __builtin_amdgcn_s_setprio(0); } while (0)
; #define PG8_BAR __builtin_amdgcn_s_barrier()
; template <class Epi, class Sched, bool ALIGN_EPI = false, bool SP2 = false, bool F16 = false>
; __device__ __forceinline__ void gemm_phase(PG8_LAS unsigned char* lds, const Gemm g, const Sched& S, const Epi& E, const int wid_in) {
;     ...
;         const bool has_next = S.next(ui + 1, nxt);
;         const char* nA = has_next ? (const char*)g.A + (size_t)nxt.pm * tstep : cA; const char* nB = has_next ? (const char*)g.Bt + (size_t)nxt.pn * tstep : cB;
;         for (int t = 0; t < nt; t += 2) {
;             const bool last = (t == nt - 2);
;             const char* a1 = cA + (size_t)(t + 1) * kstep;
;             const char* a2 = last ? nA : cA + (size_t)(t + 2) * kstep; const char* b2 = last ? nB : cB + (size_t)(t + 2) * kstep;
;             const char* a3 = a2 + kstep; const char* b3 = b2 + kstep;
;             if (last && has_next) S.a_ready(nxt);
;             if constexpr (SP2) {
;             PG8_LDB(B0, 0, 0); PG8_LDB(B1, 0, 1); PG8_SCHED; PG8_LDA(At, 0, 0); PG8_STAGE(PG8_SA(1, 1), a1 + hstep, voffA);
;             PG8_WAIT_V(8); PG8_WAIT_L(0); PG8_BAR; PG8_MMA(0, 0, At, B0); PG8_MMA(0, 1, At, B1); PG8_BAR; PG8_SCHED;
;             PG8_LDA(At, 0, 1); PG8_STAGE(PG8_SB(0, 0), b2, voffB); PG8_STAGE(PG8_SB(0, 1), b2 + hstep, voffB); PG8_STAGE(PG8_SA(0, 0), a2, voffA);
.LBB0_1277:
	s_mov_b64 s[48:49], s[10:11]
	s_add_i32 s10, s36, s19
	s_mov_b64 s[46:47], s[12:13]
	s_mov_b32 s12, s62
	s_mov_b32 s13, s61
	s_and_b32 s61, s10, 3
	s_ashr_i32 s62, s10, 2
	s_and_b64 s[10:11], s[30:31], exec
	s_cselect_b32 s12, s62, s12
	ds_read_b128 v[0:3], v134
	ds_read_b128 v[4:7], v134 offset:1024
	ds_read_b128 v[8:11], v134 offset:2048
	ds_read_b128 v[12:15], v134 offset:3072
	ds_read_b128 v[16:19], v135
	ds_read_b128 v[20:23], v135 offset:1024
	ds_read_b128 v[24:27], v135 offset:2048
	ds_read_b128 v[28:31], v135 offset:3072
	s_cselect_b32 s10, s61, s13
	s_ashr_i32 s13, s12, 31
	s_lshl_b64 s[12:13], s[12:13], 17
	s_add_u32 s12, s21, s12
	s_addc_u32 s13, s40, s13
	s_and_b64 s[36:37], s[30:31], exec
	s_cselect_b32 s45, s13, s47
	s_cselect_b32 s44, s12, s46
	s_ashr_i32 s11, s10, 31
	s_lshl_b64 s[10:11], s[10:11], 17
	s_add_u32 s10, s41, s10
	s_addc_u32 s11, s42, s11
	s_and_b64 s[36:37], s[30:31], exec
	s_cselect_b32 s37, s11, s49
	s_cselect_b32 s36, s10, s48
	s_add_u32 s64, s46, 0x10080
	s_addc_u32 s65, s47, 0
	s_mov_b32 m0, s15
	ds_read_b128 v[32:35], v136
	ds_read_b128 v[36:39], v136 offset:1024
	ds_read_b128 v[40:43], v136 offset:2048
	ds_read_b128 v[44:47], v136 offset:3072
	ds_read_b128 v[48:51], v136 offset:4096
	ds_read_b128 v[52:55], v136 offset:5120
	ds_read_b128 v[56:59], v136 offset:6144
	ds_read_b128 v[60:63], v136 offset:7168
	global_load_lds_dwordx4 v130, s[64:65]
	s_mov_b32 m0, s52
	s_nop 0
	global_load_lds_dwordx4 v128, s[64:65]
	s_waitcnt vmcnt(8)
	s_waitcnt lgkmcnt(0)
	s_barrier
	s_setprio 1
	s_waitcnt lgkmcnt(0)
	v_mfma_f32_16x16x32_bf16 v[64:67], v[0:3], v[32:35], 0
	v_mfma_f32_16x16x32_bf16 v[68:71], v[8:11], v[32:35], 0
	v_mfma_f32_16x16x32_bf16 v[72:75], v[0:3], v[40:43], 0
	v_mfma_f32_16x16x32_bf16 v[76:79], v[8:11], v[40:43], 0
	v_mfma_f32_16x16x32_bf16 v[80:83], v[0:3], v[48:51], 0
	v_mfma_f32_16x16x32_bf16 v[84:87], v[8:11], v[48:51], 0
	v_mfma_f32_16x16x32_bf16 v[88:91], v[0:3], v[56:59], 0
	v_mfma_f32_16x16x32_bf16 v[92:95], v[8:11], v[56:59], 0
	v_mfma_f32_16x16x32_bf16 v[64:67], v[4:7], v[36:39], v[64:67]
	v_mfma_f32_16x16x32_bf16 v[68:71], v[12:15], v[36:39], v[68:71]
	v_mfma_f32_16x16x32_bf16 v[72:75], v[4:7], v[44:47], v[72:75]
	v_mfma_f32_16x16x32_bf16 v[76:79], v[12:15], v[44:47], v[76:79]
	v_mfma_f32_16x16x32_bf16 v[80:83], v[4:7], v[52:55], v[80:83]
	v_mfma_f32_16x16x32_bf16 v[84:87], v[12:15], v[52:55], v[84:87]
	v_mfma_f32_16x16x32_bf16 v[88:91], v[4:7], v[60:63], v[88:91]
	v_mfma_f32_16x16x32_bf16 v[92:95], v[12:15], v[60:63], v[92:95]
	s_setprio 0
	s_setprio 1
	v_mfma_f32_16x16x32_bf16 v[96:99], v[16:19], v[32:35], 0
	v_mfma_f32_16x16x32_bf16 v[32:35], v[24:27], v[32:35], 0
	v_mfma_f32_16x16x32_bf16 v[96:99], v[20:23], v[36:39], v[96:99]
	v_mfma_f32_16x16x32_bf16 v[32:35], v[28:31], v[36:39], v[32:35]
	v_mfma_f32_16x16x32_bf16 v[36:39], v[16:19], v[40:43], 0
	v_mfma_f32_16x16x32_bf16 v[40:43], v[24:27], v[40:43], 0
	v_mfma_f32_16x16x32_bf16 v[36:39], v[20:23], v[44:47], v[36:39]
	v_mfma_f32_16x16x32_bf16 v[40:43], v[28:31], v[44:47], v[40:43]
	v_mfma_f32_16x16x32_bf16 v[44:47], v[16:19], v[48:51], 0
	v_mfma_f32_16x16x32_bf16 v[48:51], v[24:27], v[48:51], 0
	v_mfma_f32_16x16x32_bf16 v[44:47], v[20:23], v[52:55], v[44:47]
	v_mfma_f32_16x16x32_bf16 v[48:51], v[28:31], v[52:55], v[48:51]
	v_mfma_f32_16x16x32_bf16 v[52:55], v[16:19], v[56:59], 0
	v_mfma_f32_16x16x32_bf16 v[56:59], v[24:27], v[56:59], 0
	v_mfma_f32_16x16x32_bf16 v[52:55], v[20:23], v[60:63], v[52:55]
	v_mfma_f32_16x16x32_bf16 v[56:59], v[28:31], v[60:63], v[56:59]
	s_setprio 0
	s_barrier
	v_lshl_add_u64 v[204:205], s[48:49], 0, v[130:131]
	s_mov_b32 m0, s53
	v_lshl_add_u64 v[140:141], v[204:205], 0, s[26:27]
	v_lshl_add_u64 v[206:207], s[48:49], 0, v[128:129]
	s_add_u32 s64, s48, 0x10100
	ds_read_b128 v[60:63], v136 offset:16384
	ds_read_b128 v[100:103], v136 offset:17408
	ds_read_b128 v[104:107], v136 offset:18432
	ds_read_b128 v[108:111], v136 offset:19456
	ds_read_b128 v[112:115], v136 offset:20480
	ds_read_b128 v[116:119], v136 offset:21504
	ds_read_b128 v[120:123], v136 offset:22528
	ds_read_b128 v[124:127], v136 offset:23552
	global_load_lds_dwordx4 v[140:141], off
	v_lshl_add_u64 v[140:141], v[206:207], 0, s[26:27]
	s_mov_b32 m0, s54
	s_addc_u32 s65, s49, 0
	global_load_lds_dwordx4 v[140:141], off
	s_mov_b32 m0, s55
	v_lshl_add_u64 v[208:209], s[46:47], 0, v[130:131]
	global_load_lds_dwordx4 v130, s[64:65]
	s_mov_b32 m0, s56
	v_lshl_add_u64 v[210:211], s[46:47], 0, v[128:129]
	global_load_lds_dwordx4 v128, s[64:65]
	v_lshl_add_u64 v[140:141], v[208:209], 0, s[26:27]
	s_mov_b32 m0, s74
	s_nop 0
	global_load_lds_dwordx4 v[140:141], off
	v_lshl_add_u64 v[140:141], v[210:211], 0, s[26:27]
	s_mov_b32 m0, s43
	s_nop 0
	global_load_lds_dwordx4 v[140:141], off
	s_waitcnt vmcnt(8)
	s_waitcnt lgkmcnt(0)
	s_barrier
; #define PG8_STAGE(bufoff, gbase, voff) do { _Pragma("unroll") for (int _i = 0; _i < 2; ++_i) \
;         __builtin_amdgcn_global_load_lds((const unsigned*)((const char*)(gbase) + (voff)[_i]), (PG8_LAS unsigned*)(lds + (bufoff) + ldsw + _i * 8192), 16, 0, 0); } while (0)
; #define PG8_LDA(dst, b, h) do { _Pragma("unroll") for (int m = 0; m < 4; ++m) _Pragma("unroll") for (int k = 0; k < 2; ++k) dst[m][k] = *(const PG8_LAS bf16x8*)(lds + PG8_SA(b, h) + aoff + m * 2048 + k * 1024); } while (0)
; #define PG8_LDB(dst, b, h) do { _Pragma("unroll") for (int n = 0; n < 2; ++n) _Pragma("unroll") for (int k = 0; k < 2; ++k) dst[n][k] = *(const PG8_LAS bf16x8*)(lds + PG8_SB(b, h) + boff + n * 2048 + k * 1024); } while (0)
; #define PG8_MMA(ai, bj, At, Bt) do { __builtin_amdgcn_s_setprio(1); _Pragma("unroll") for (int m = 0; m < 4; ++m) _Pragma("unroll") for (int n = 0; n < 2; ++n) _Pragma("unroll") for (int k = 0; k < 2; ++k) \
;         acc[ai][bj][m][n] = mma16<F16>(Bt[n][k], At[m][k], acc[ai][bj][m][n]); __builtin_amdgcn_s_setprio(0); } while (0)
; #define PG8_WAIT_V(n) asm volatile("s_waitcnt vmcnt(" #n ")" ::: "memory")
; #define PG8_WAIT_L(n) asm volatile("s_waitcnt lgkmcnt(" #n ")" ::: "memory")
; #define PG8_BAR __builtin_amdgcn_s_barrier()
; #define PG8_SCHED __builtin_amdgcn_sched_barrier(0)
; template <class Epi, class Sched, bool ALIGN_EPI = false, bool SP2 = false, bool F16 = false>
; __device__ __forceinline__ void gemm_phase(PG8_LAS unsigned char* lds, const Gemm g, const Sched& S, const Epi& E, const int wid_in) {
;     ...
;             PG8_WAIT_V(8); PG8_WAIT_L(0); PG8_BAR; PG8_MMA(1, 0, At, B0); PG8_MMA(1, 1, At, B1); PG8_BAR; PG8_SCHED;
;             PG8_LDB(B0, 1, 0); PG8_LDB(B1, 1, 1); PG8_SCHED; PG8_LDA(At, 1, 0); PG8_STAGE(PG8_SA(0, 1), a2 + hstep, voffA);
;             PG8_WAIT_V(8); PG8_WAIT_L(0); PG8_BAR; PG8_MMA(0, 0, At, B0); PG8_MMA(0, 1, At, B1); PG8_BAR; PG8_SCHED;
	s_setprio 1
	s_waitcnt lgkmcnt(0)
	v_mfma_f32_16x16x32_bf16 v[140:143], v[0:3], v[60:63], 0
	v_mfma_f32_16x16x32_bf16 v[148:151], v[0:3], v[104:107], 0
	v_mfma_f32_16x16x32_bf16 v[156:159], v[0:3], v[112:115], 0
	v_mfma_f32_16x16x32_bf16 v[0:3], v[0:3], v[120:123], 0
	v_mfma_f32_16x16x32_bf16 v[140:143], v[4:7], v[100:103], v[140:143]
	v_mfma_f32_16x16x32_bf16 v[148:151], v[4:7], v[108:111], v[148:151]
	v_mfma_f32_16x16x32_bf16 v[156:159], v[4:7], v[116:119], v[156:159]
	v_mfma_f32_16x16x32_bf16 v[0:3], v[4:7], v[124:127], v[0:3]
	v_mfma_f32_16x16x32_bf16 v[4:7], v[8:11], v[120:123], 0
	v_mfma_f32_16x16x32_bf16 v[144:147], v[8:11], v[60:63], 0
	v_mfma_f32_16x16x32_bf16 v[152:155], v[8:11], v[104:107], 0
	v_mfma_f32_16x16x32_bf16 v[160:163], v[8:11], v[112:115], 0
	v_mfma_f32_16x16x32_bf16 v[4:7], v[12:15], v[124:127], v[4:7]
	v_mfma_f32_16x16x32_bf16 v[144:147], v[12:15], v[100:103], v[144:147]
	v_mfma_f32_16x16x32_bf16 v[152:155], v[12:15], v[108:111], v[152:155]
	v_mfma_f32_16x16x32_bf16 v[160:163], v[12:15], v[116:119], v[160:163]
	s_setprio 0
	s_setprio 1
	v_mfma_f32_16x16x32_bf16 v[8:11], v[16:19], v[60:63], 0
	v_mfma_f32_16x16x32_bf16 v[12:15], v[24:27], v[60:63], 0
	v_mfma_f32_16x16x32_bf16 v[8:11], v[20:23], v[100:103], v[8:11]
	v_mfma_f32_16x16x32_bf16 v[12:15], v[28:31], v[100:103], v[12:15]
	v_mfma_f32_16x16x32_bf16 v[60:63], v[16:19], v[104:107], 0
	v_mfma_f32_16x16x32_bf16 v[100:103], v[24:27], v[104:107], 0
	v_mfma_f32_16x16x32_bf16 v[104:107], v[16:19], v[112:115], 0
	v_mfma_f32_16x16x32_bf16 v[16:19], v[16:19], v[120:123], 0
	v_mfma_f32_16x16x32_bf16 v[60:63], v[20:23], v[108:111], v[60:63]
	v_mfma_f32_16x16x32_bf16 v[100:103], v[28:31], v[108:111], v[100:103]
	v_mfma_f32_16x16x32_bf16 v[104:107], v[20:23], v[116:119], v[104:107]
	v_mfma_f32_16x16x32_bf16 v[108:111], v[24:27], v[112:115], 0
	v_mfma_f32_16x16x32_bf16 v[16:19], v[20:23], v[124:127], v[16:19]
	v_mfma_f32_16x16x32_bf16 v[20:23], v[24:27], v[120:123], 0
	v_mfma_f32_16x16x32_bf16 v[108:111], v[28:31], v[116:119], v[108:111]
	v_mfma_f32_16x16x32_bf16 v[20:23], v[28:31], v[124:127], v[20:23]
	s_setprio 0
	s_barrier
	ds_read_b128 v[24:27], v137
	ds_read_b128 v[28:31], v137 offset:1024
	ds_read_b128 v[112:115], v137 offset:2048
	ds_read_b128 v[116:119], v137 offset:3072
	ds_read_b128 v[120:123], v138
	ds_read_b128 v[124:127], v138 offset:1024
	ds_read_b128 v[164:167], v138 offset:2048
	ds_read_b128 v[168:171], v138 offset:3072
	s_add_u32 s64, s46, 0x10100
	s_addc_u32 s65, s47, 0
	s_mov_b32 m0, s50
	ds_read_b128 v[172:175], v136 offset:32768
	ds_read_b128 v[176:179], v136 offset:33792
	ds_read_b128 v[180:183], v136 offset:34816
	ds_read_b128 v[184:187], v136 offset:35840
	ds_read_b128 v[188:191], v136 offset:36864
	ds_read_b128 v[192:195], v136 offset:37888
	ds_read_b128 v[196:199], v136 offset:38912
	ds_read_b128 v[200:203], v136 offset:39936
	global_load_lds_dwordx4 v130, s[64:65]
	s_mov_b32 m0, s51
	s_nop 0
	global_load_lds_dwordx4 v128, s[64:65]
	s_waitcnt vmcnt(8)
	s_waitcnt lgkmcnt(0)
	s_barrier
	s_setprio 1
	s_waitcnt lgkmcnt(0)
	v_mfma_f32_16x16x32_bf16 v[64:67], v[24:27], v[172:175], v[64:67]
	v_mfma_f32_16x16x32_bf16 v[68:71], v[112:115], v[172:175], v[68:71]
	v_mfma_f32_16x16x32_bf16 v[72:75], v[24:27], v[180:183], v[72:75]
	v_mfma_f32_16x16x32_bf16 v[76:79], v[112:115], v[180:183], v[76:79]
	v_mfma_f32_16x16x32_bf16 v[80:83], v[24:27], v[188:191], v[80:83]
	v_mfma_f32_16x16x32_bf16 v[84:87], v[112:115], v[188:191], v[84:87]
	v_mfma_f32_16x16x32_bf16 v[88:91], v[24:27], v[196:199], v[88:91]
	v_mfma_f32_16x16x32_bf16 v[92:95], v[112:115], v[196:199], v[92:95]
	v_mfma_f32_16x16x32_bf16 v[64:67], v[28:31], v[176:179], v[64:67]
	v_mfma_f32_16x16x32_bf16 v[68:71], v[116:119], v[176:179], v[68:71]
	v_mfma_f32_16x16x32_bf16 v[72:75], v[28:31], v[184:187], v[72:75]
	v_mfma_f32_16x16x32_bf16 v[76:79], v[116:119], v[184:187], v[76:79]
	v_mfma_f32_16x16x32_bf16 v[80:83], v[28:31], v[192:195], v[80:83]
	v_mfma_f32_16x16x32_bf16 v[84:87], v[116:119], v[192:195], v[84:87]
	v_mfma_f32_16x16x32_bf16 v[88:91], v[28:31], v[200:203], v[88:91]
	v_mfma_f32_16x16x32_bf16 v[92:95], v[116:119], v[200:203], v[92:95]
	s_setprio 0
	s_setprio 1
	v_mfma_f32_16x16x32_bf16 v[96:99], v[120:123], v[172:175], v[96:99]
	v_mfma_f32_16x16x32_bf16 v[32:35], v[164:167], v[172:175], v[32:35]
	v_mfma_f32_16x16x32_bf16 v[36:39], v[120:123], v[180:183], v[36:39]
	v_mfma_f32_16x16x32_bf16 v[40:43], v[164:167], v[180:183], v[40:43]
	v_mfma_f32_16x16x32_bf16 v[44:47], v[120:123], v[188:191], v[44:47]
	v_mfma_f32_16x16x32_bf16 v[48:51], v[164:167], v[188:191], v[48:51]
	v_mfma_f32_16x16x32_bf16 v[52:55], v[120:123], v[196:199], v[52:55]
	v_mfma_f32_16x16x32_bf16 v[56:59], v[164:167], v[196:199], v[56:59]
	v_mfma_f32_16x16x32_bf16 v[96:99], v[124:127], v[176:179], v[96:99]
	v_mfma_f32_16x16x32_bf16 v[32:35], v[168:171], v[176:179], v[32:35]
	v_mfma_f32_16x16x32_bf16 v[36:39], v[124:127], v[184:187], v[36:39]
	v_mfma_f32_16x16x32_bf16 v[40:43], v[168:171], v[184:187], v[40:43]
	v_mfma_f32_16x16x32_bf16 v[44:47], v[124:127], v[192:195], v[44:47]
	v_mfma_f32_16x16x32_bf16 v[48:51], v[168:171], v[192:195], v[48:51]
	v_mfma_f32_16x16x32_bf16 v[52:55], v[124:127], v[200:203], v[52:55]
	v_mfma_f32_16x16x32_bf16 v[56:59], v[168:171], v[200:203], v[56:59]
	s_setprio 0
	s_barrier
; #define PG8_STAGE(bufoff, gbase, voff) do { _Pragma("unroll") for (int _i = 0; _i < 2; ++_i) \
;         __builtin_amdgcn_global_load_lds((const unsigned*)((const char*)(gbase) + (voff)[_i]), (PG8_LAS unsigned*)(lds + (bufoff) + ldsw + _i * 8192), 16, 0, 0); } while (0)
; #define PG8_LDA(dst, b, h) do { _Pragma("unroll") for (int m = 0; m < 4; ++m) _Pragma("unroll") for (int k = 0; k < 2; ++k) dst[m][k] = *(const PG8_LAS bf16x8*)(lds + PG8_SA(b, h) + aoff + m * 2048 + k * 1024); } while (0)
; #define PG8_LDB(dst, b, h) do { _Pragma("unroll") for (int n = 0; n < 2; ++n) _Pragma("unroll") for (int k = 0; k < 2; ++k) dst[n][k] = *(const PG8_LAS bf16x8*)(lds + PG8_SB(b, h) + boff + n * 2048 + k * 1024); } while (0)
; #define PG8_MMA(ai, bj, At, Bt) do { __builtin_amdgcn_s_setprio(1); _Pragma("unroll") for (int m = 0; m < 4; ++m) _Pragma("unroll") for (int n = 0; n < 2; ++n) _Pragma("unroll") for (int k = 0; k < 2; ++k) \
;         acc[ai][bj][m][n] = mma16<F16>(Bt[n][k], At[m][k], acc[ai][bj][m][n]); __builtin_amdgcn_s_setprio(0); } while (0)
; #define PG8_WAIT_V(n) asm volatile("s_waitcnt vmcnt(" #n ")" ::: "memory")
; #define PG8_WAIT_L(n) asm volatile("s_waitcnt lgkmcnt(" #n ")" ::: "memory")
; #define PG8_BAR __builtin_amdgcn_s_barrier()
; #define PG8_SCHED __builtin_amdgcn_sched_barrier(0)
; template <class Epi, class Sched, bool ALIGN_EPI = false, bool SP2 = false, bool F16 = false>
; __device__ __forceinline__ void gemm_phase(PG8_LAS unsigned char* lds, const Gemm g, const Sched& S, const Epi& E, const int wid_in) {
;     ...
;             PG8_LDB(B0, 0, 0); PG8_LDB(B1, 0, 1); PG8_SCHED; PG8_LDA(At, 0, 0); PG8_STAGE(PG8_SA(1, 1), a1 + hstep, voffA);
;             PG8_WAIT_V(8); PG8_WAIT_L(0); PG8_BAR; PG8_MMA(0, 0, At, B0); PG8_MMA(0, 1, At, B1); PG8_BAR; PG8_SCHED;
;     ...
;             PG8_LDA(At, 1, 1); PG8_STAGE(PG8_SB(1, 0), b3, voffB); PG8_STAGE(PG8_SB(1, 1), b3 + hstep, voffB); PG8_STAGE(PG8_SA(1, 0), a3, voffA);
;             PG8_WAIT_V(8); PG8_WAIT_L(0); PG8_BAR; PG8_MMA(1, 0, At, B0); PG8_MMA(1, 1, At, B1); PG8_BAR; PG8_SCHED;
	s_mov_b32 m0, s57
	v_lshl_add_u64 v[204:205], v[204:205], 0, s[28:29]
	s_add_u32 s48, s48, 0x10180
	ds_read_b128 v[172:175], v136 offset:49152
	ds_read_b128 v[176:179], v136 offset:50176
	ds_read_b128 v[180:183], v136 offset:51200
	ds_read_b128 v[184:187], v136 offset:52224
	ds_read_b128 v[188:191], v136 offset:53248
	ds_read_b128 v[192:195], v136 offset:54272
	ds_read_b128 v[196:199], v136 offset:55296
	ds_read_b128 v[200:203], v136 offset:56320
	global_load_lds_dwordx4 v[204:205], off
	v_lshl_add_u64 v[204:205], v[206:207], 0, s[28:29]
	s_mov_b32 m0, s58
	s_addc_u32 s49, s49, 0
	global_load_lds_dwordx4 v[204:205], off
	s_mov_b32 m0, s59
	s_nop 0
	global_load_lds_dwordx4 v130, s[48:49]
	s_mov_b32 m0, s60
	s_nop 0
	global_load_lds_dwordx4 v128, s[48:49]
	v_lshl_add_u64 v[204:205], v[208:209], 0, s[28:29]
	s_mov_b32 m0, s75
	s_nop 0
	global_load_lds_dwordx4 v[204:205], off
	v_lshl_add_u64 v[204:205], v[210:211], 0, s[28:29]
	s_mov_b32 m0, s14
	s_nop 0
	global_load_lds_dwordx4 v[204:205], off
	s_waitcnt vmcnt(8)
	s_waitcnt lgkmcnt(0)
	s_barrier
	s_setprio 1
	s_waitcnt lgkmcnt(0)
	v_mfma_f32_16x16x32_bf16 v[0:3], v[24:27], v[196:199], v[0:3]
	v_mfma_f32_16x16x32_bf16 v[4:7], v[112:115], v[196:199], v[4:7]
	v_mfma_f32_16x16x32_bf16 v[140:143], v[24:27], v[172:175], v[140:143]
	v_mfma_f32_16x16x32_bf16 v[144:147], v[112:115], v[172:175], v[144:147]
	v_mfma_f32_16x16x32_bf16 v[148:151], v[24:27], v[180:183], v[148:151]
	v_mfma_f32_16x16x32_bf16 v[152:155], v[112:115], v[180:183], v[152:155]
	v_mfma_f32_16x16x32_bf16 v[156:159], v[24:27], v[188:191], v[156:159]
	v_mfma_f32_16x16x32_bf16 v[160:163], v[112:115], v[188:191], v[160:163]
	v_mfma_f32_16x16x32_bf16 v[0:3], v[28:31], v[200:203], v[0:3]
	v_mfma_f32_16x16x32_bf16 v[4:7], v[116:119], v[200:203], v[4:7]
	v_mfma_f32_16x16x32_bf16 v[140:143], v[28:31], v[176:179], v[140:143]
	v_mfma_f32_16x16x32_bf16 v[144:147], v[116:119], v[176:179], v[144:147]
	v_mfma_f32_16x16x32_bf16 v[148:151], v[28:31], v[184:187], v[148:151]
	v_mfma_f32_16x16x32_bf16 v[152:155], v[116:119], v[184:187], v[152:155]
	v_mfma_f32_16x16x32_bf16 v[156:159], v[28:31], v[192:195], v[156:159]
	v_mfma_f32_16x16x32_bf16 v[160:163], v[116:119], v[192:195], v[160:163]
	s_setprio 0
	s_setprio 1
	v_mfma_f32_16x16x32_bf16 v[8:11], v[120:123], v[172:175], v[8:11]
	v_mfma_f32_16x16x32_bf16 v[12:15], v[164:167], v[172:175], v[12:15]
	v_mfma_f32_16x16x32_bf16 v[24:27], v[120:123], v[180:183], v[60:63]
	v_mfma_f32_16x16x32_bf16 v[28:31], v[164:167], v[180:183], v[100:103]
	v_mfma_f32_16x16x32_bf16 v[60:63], v[120:123], v[188:191], v[104:107]
	v_mfma_f32_16x16x32_bf16 v[100:103], v[164:167], v[188:191], v[108:111]
	v_mfma_f32_16x16x32_bf16 v[16:19], v[120:123], v[196:199], v[16:19]
	v_mfma_f32_16x16x32_bf16 v[20:23], v[164:167], v[196:199], v[20:23]
	v_mfma_f32_16x16x32_bf16 v[8:11], v[124:127], v[176:179], v[8:11]
	v_mfma_f32_16x16x32_bf16 v[12:15], v[168:171], v[176:179], v[12:15]
	v_mfma_f32_16x16x32_bf16 v[24:27], v[124:127], v[184:187], v[24:27]
	v_mfma_f32_16x16x32_bf16 v[28:31], v[168:171], v[184:187], v[28:31]
	v_mfma_f32_16x16x32_bf16 v[60:63], v[124:127], v[192:195], v[60:63]
	v_mfma_f32_16x16x32_bf16 v[100:103], v[168:171], v[192:195], v[100:103]
	v_mfma_f32_16x16x32_bf16 v[16:19], v[124:127], v[200:203], v[16:19]
	v_mfma_f32_16x16x32_bf16 v[20:23], v[168:171], v[200:203], v[20:23]
	s_setprio 0
	s_barrier
	ds_read_b128 v[104:107], v134
	ds_read_b128 v[108:111], v134 offset:1024
	ds_read_b128 v[112:115], v134 offset:2048
	ds_read_b128 v[116:119], v134 offset:3072
	ds_read_b128 v[120:123], v135
	ds_read_b128 v[124:127], v135 offset:1024
	ds_read_b128 v[164:167], v135 offset:2048
	ds_read_b128 v[168:171], v135 offset:3072
	s_add_u32 s46, s46, 0x10180
	s_addc_u32 s47, s47, 0
	s_mov_b32 m0, s15
	ds_read_b128 v[172:175], v136
	ds_read_b128 v[176:179], v136 offset:1024
	ds_read_b128 v[180:183], v136 offset:2048
	ds_read_b128 v[184:187], v136 offset:3072
	ds_read_b128 v[188:191], v136 offset:4096
	ds_read_b128 v[192:195], v136 offset:5120
	ds_read_b128 v[196:199], v136 offset:6144
	ds_read_b128 v[200:203], v136 offset:7168
	global_load_lds_dwordx4 v130, s[46:47]
	s_mov_b32 m0, s52
	s_nop 0
	global_load_lds_dwordx4 v128, s[46:47]
	s_waitcnt vmcnt(8)
	s_waitcnt lgkmcnt(0)
	s_barrier
	s_setprio 1
	s_waitcnt lgkmcnt(0)
	v_mfma_f32_16x16x32_bf16 v[64:67], v[104:107], v[172:175], v[64:67]
	v_mfma_f32_16x16x32_bf16 v[68:71], v[112:115], v[172:175], v[68:71]
	v_mfma_f32_16x16x32_bf16 v[72:75], v[104:107], v[180:183], v[72:75]
	v_mfma_f32_16x16x32_bf16 v[76:79], v[112:115], v[180:183], v[76:79]
	v_mfma_f32_16x16x32_bf16 v[80:83], v[104:107], v[188:191], v[80:83]
	v_mfma_f32_16x16x32_bf16 v[84:87], v[112:115], v[188:191], v[84:87]
	v_mfma_f32_16x16x32_bf16 v[88:91], v[104:107], v[196:199], v[88:91]
	v_mfma_f32_16x16x32_bf16 v[92:95], v[112:115], v[196:199], v[92:95]
	v_mfma_f32_16x16x32_bf16 v[64:67], v[108:111], v[176:179], v[64:67]
	v_mfma_f32_16x16x32_bf16 v[68:71], v[116:119], v[176:179], v[68:71]
	v_mfma_f32_16x16x32_bf16 v[72:75], v[108:111], v[184:187], v[72:75]
	v_mfma_f32_16x16x32_bf16 v[76:79], v[116:119], v[184:187], v[76:79]
	v_mfma_f32_16x16x32_bf16 v[80:83], v[108:111], v[192:195], v[80:83]
	v_mfma_f32_16x16x32_bf16 v[84:87], v[116:119], v[192:195], v[84:87]
	v_mfma_f32_16x16x32_bf16 v[88:91], v[108:111], v[200:203], v[88:91]
	v_mfma_f32_16x16x32_bf16 v[92:95], v[116:119], v[200:203], v[92:95]
	s_setprio 0
	s_setprio 1
	v_mfma_f32_16x16x32_bf16 v[32:35], v[164:167], v[172:175], v[32:35]
	v_mfma_f32_16x16x32_bf16 v[96:99], v[120:123], v[172:175], v[96:99]
	v_mfma_f32_16x16x32_bf16 v[172:175], v[168:171], v[176:179], v[32:35]
	v_mfma_f32_16x16x32_bf16 v[32:35], v[120:123], v[180:183], v[36:39]
	v_mfma_f32_16x16x32_bf16 v[204:207], v[124:127], v[176:179], v[96:99]
	v_mfma_f32_16x16x32_bf16 v[176:179], v[124:127], v[184:187], v[32:35]
	v_mfma_f32_16x16x32_bf16 v[32:35], v[164:167], v[180:183], v[40:43]
	v_mfma_f32_16x16x32_bf16 v[40:43], v[168:171], v[184:187], v[32:35]
	v_mfma_f32_16x16x32_bf16 v[32:35], v[120:123], v[188:191], v[44:47]
	v_mfma_f32_16x16x32_bf16 v[44:47], v[124:127], v[192:195], v[32:35]
	v_mfma_f32_16x16x32_bf16 v[32:35], v[164:167], v[188:191], v[48:51]
	v_mfma_f32_16x16x32_bf16 v[48:51], v[168:171], v[192:195], v[32:35]
	v_mfma_f32_16x16x32_bf16 v[32:35], v[120:123], v[196:199], v[52:55]
	v_mfma_f32_16x16x32_bf16 v[52:55], v[124:127], v[200:203], v[32:35]
	v_mfma_f32_16x16x32_bf16 v[32:35], v[164:167], v[196:199], v[56:59]
	v_mfma_f32_16x16x32_bf16 v[56:59], v[168:171], v[200:203], v[32:35]
	s_setprio 0
	s_barrier
; #define PG8_STAGE(bufoff, gbase, voff) do { _Pragma("unroll") for (int _i = 0; _i < 2; ++_i) \
;         __builtin_amdgcn_global_load_lds((const unsigned*)((const char*)(gbase) + (voff)[_i]), (PG8_LAS unsigned*)(lds + (bufoff) + ldsw + _i * 8192), 16, 0, 0); } while (0)
; #define PG8_LDA(dst, b, h) do { _Pragma("unroll") for (int m = 0; m < 4; ++m) _Pragma("unroll") for (int k = 0; k < 2; ++k) dst[m][k] = *(const PG8_LAS bf16x8*)(lds + PG8_SA(b, h) + aoff + m * 2048 + k * 1024); } while (0)
; #define PG8_LDB(dst, b, h) do { _Pragma("unroll") for (int n = 0; n < 2; ++n) _Pragma("unroll") for (int k = 0; k < 2; ++k) dst[n][k] = *(const PG8_LAS bf16x8*)(lds + PG8_SB(b, h) + boff + n * 2048 + k * 1024); } while (0)
; #define PG8_MMA(ai, bj, At, Bt) do { __builtin_amdgcn_s_setprio(1); _Pragma("unroll") for (int m = 0; m < 4; ++m) _Pragma("unroll") for (int n = 0; n < 2; ++n) _Pragma("unroll") for (int k = 0; k < 2; ++k) \
;         acc[ai][bj][m][n] = mma16<F16>(Bt[n][k], At[m][k], acc[ai][bj][m][n]); __builtin_amdgcn_s_setprio(0); } while (0)
; #define PG8_WAIT_V(n) asm volatile("s_waitcnt vmcnt(" #n ")" ::: "memory")
; #define PG8_WAIT_L(n) asm volatile("s_waitcnt lgkmcnt(" #n ")" ::: "memory")
; #define PG8_BAR __builtin_amdgcn_s_barrier()
; #define PG8_SCHED __builtin_amdgcn_sched_barrier(0)
; template <class Epi, class Sched, bool ALIGN_EPI = false, bool SP2 = false, bool F16 = false>
; __device__ __forceinline__ void gemm_phase(PG8_LAS unsigned char* lds, const Gemm g, const Sched& S, const Epi& E, const int wid_in) {
;     ...
;         const char* nA = has_next ? (const char*)g.A + (size_t)nxt.pm * tstep : cA; const char* nB = has_next ? (const char*)g.Bt + (size_t)nxt.pn * tstep : cB;
;     ...
;             PG8_LDA(At, 0, 1); PG8_STAGE(PG8_SB(0, 0), b2, voffB); PG8_STAGE(PG8_SB(0, 1), b2 + hstep, voffB); PG8_STAGE(PG8_SA(0, 0), a2, voffA);
;             PG8_WAIT_V(8); PG8_WAIT_L(0); PG8_BAR; PG8_MMA(1, 0, At, B0); PG8_MMA(1, 1, At, B1); PG8_BAR; PG8_SCHED;
;             PG8_LDB(B0, 1, 0); PG8_LDB(B1, 1, 1); PG8_SCHED; PG8_LDA(At, 1, 0); PG8_STAGE(PG8_SA(0, 1), a2 + hstep, voffA);
;             PG8_WAIT_V(8); PG8_WAIT_L(0); PG8_BAR; PG8_MMA(0, 0, At, B0); PG8_MMA(0, 1, At, B1); PG8_BAR; PG8_SCHED;
	s_mov_b32 m0, s53
	v_lshl_add_u64 v[240:241], s[36:37], 0, v[130:131]
	s_add_u32 s46, s36, 0x10000
	s_nop 1
	ds_read_b128 v[32:35], v136 offset:16384
	ds_read_b128 v[36:39], v136 offset:17408
	ds_read_b128 v[96:99], v136 offset:18432
	ds_read_b128 v[180:183], v136 offset:19456
	ds_read_b128 v[184:187], v136 offset:20480
	ds_read_b128 v[188:191], v136 offset:21504
	ds_read_b128 v[192:195], v136 offset:22528
	ds_read_b128 v[196:199], v136 offset:23552
	global_load_lds_dwordx4 v[240:241], off
	v_lshl_add_u64 v[242:243], s[36:37], 0, v[128:129]
	s_mov_b32 m0, s54
	s_addc_u32 s47, s37, 0
	global_load_lds_dwordx4 v[242:243], off
	s_mov_b32 m0, s55
	v_lshl_add_u64 v[244:245], s[44:45], 0, v[130:131]
	global_load_lds_dwordx4 v130, s[46:47]
	s_mov_b32 m0, s56
	v_lshl_add_u64 v[246:247], s[44:45], 0, v[128:129]
	global_load_lds_dwordx4 v128, s[46:47]
	s_mov_b32 m0, s74
	s_nop 0
	global_load_lds_dwordx4 v[244:245], off
	s_mov_b32 m0, s43
	s_nop 0
	global_load_lds_dwordx4 v[246:247], off
	s_waitcnt vmcnt(8)
	s_waitcnt lgkmcnt(0)
	s_barrier
	s_setprio 1
	s_waitcnt lgkmcnt(0)
	v_mfma_f32_16x16x32_bf16 v[0:3], v[104:107], v[192:195], v[0:3]
	v_mfma_f32_16x16x32_bf16 v[140:143], v[104:107], v[32:35], v[140:143]
	v_mfma_f32_16x16x32_bf16 v[144:147], v[112:115], v[32:35], v[144:147]
	v_mfma_f32_16x16x32_bf16 v[148:151], v[104:107], v[96:99], v[148:151]
	v_mfma_f32_16x16x32_bf16 v[152:155], v[112:115], v[96:99], v[152:155]
	v_mfma_f32_16x16x32_bf16 v[156:159], v[104:107], v[184:187], v[156:159]
	v_mfma_f32_16x16x32_bf16 v[160:163], v[112:115], v[184:187], v[160:163]
	v_mfma_f32_16x16x32_bf16 v[0:3], v[108:111], v[196:199], v[0:3]
	v_mfma_f32_16x16x32_bf16 v[4:7], v[112:115], v[192:195], v[4:7]
	v_mfma_f32_16x16x32_bf16 v[140:143], v[108:111], v[36:39], v[140:143]
	v_mfma_f32_16x16x32_bf16 v[144:147], v[116:119], v[36:39], v[144:147]
	v_mfma_f32_16x16x32_bf16 v[148:151], v[108:111], v[180:183], v[148:151]
	v_mfma_f32_16x16x32_bf16 v[152:155], v[116:119], v[180:183], v[152:155]
	v_mfma_f32_16x16x32_bf16 v[156:159], v[108:111], v[188:191], v[156:159]
	v_mfma_f32_16x16x32_bf16 v[160:163], v[116:119], v[188:191], v[160:163]
	v_mfma_f32_16x16x32_bf16 v[200:203], v[116:119], v[196:199], v[4:7]
	s_setprio 0
	s_setprio 1
	v_mfma_f32_16x16x32_bf16 v[4:7], v[120:123], v[32:35], v[8:11]
	v_mfma_f32_16x16x32_bf16 v[8:11], v[124:127], v[36:39], v[4:7]
	v_mfma_f32_16x16x32_bf16 v[4:7], v[164:167], v[32:35], v[12:15]
	v_mfma_f32_16x16x32_bf16 v[12:15], v[168:171], v[36:39], v[4:7]
	v_mfma_f32_16x16x32_bf16 v[4:7], v[120:123], v[96:99], v[24:27]
	v_mfma_f32_16x16x32_bf16 v[24:27], v[124:127], v[180:183], v[4:7]
	v_mfma_f32_16x16x32_bf16 v[4:7], v[164:167], v[96:99], v[28:31]
	v_mfma_f32_16x16x32_bf16 v[28:31], v[168:171], v[180:183], v[4:7]
	v_mfma_f32_16x16x32_bf16 v[4:7], v[120:123], v[184:187], v[60:63]
	v_mfma_f32_16x16x32_bf16 v[180:183], v[124:127], v[188:191], v[4:7]
	v_mfma_f32_16x16x32_bf16 v[4:7], v[164:167], v[184:187], v[100:103]
	v_mfma_f32_16x16x32_bf16 v[184:187], v[168:171], v[188:191], v[4:7]
	v_mfma_f32_16x16x32_bf16 v[4:7], v[120:123], v[192:195], v[16:19]
	v_mfma_f32_16x16x32_bf16 v[188:191], v[124:127], v[196:199], v[4:7]
	v_mfma_f32_16x16x32_bf16 v[4:7], v[164:167], v[192:195], v[20:23]
	v_mfma_f32_16x16x32_bf16 v[164:167], v[168:171], v[196:199], v[4:7]
	s_setprio 0
	s_barrier
	s_nop 4
	ds_read_b128 v[4:7], v137
	ds_read_b128 v[60:63], v137 offset:1024
	ds_read_b128 v[168:171], v137 offset:2048
	ds_read_b128 v[192:195], v137 offset:3072
	ds_read_b128 v[196:199], v138
	ds_read_b128 v[208:211], v138 offset:1024
	ds_read_b128 v[212:215], v138 offset:2048
	ds_read_b128 v[216:219], v138 offset:3072
	s_add_u32 s44, s44, 0x10000
	s_addc_u32 s45, s45, 0
	s_mov_b32 m0, s50
	ds_read_b128 v[16:19], v136 offset:32768
	ds_read_b128 v[20:23], v136 offset:33792
	ds_read_b128 v[104:107], v136 offset:34816
	ds_read_b128 v[220:223], v136 offset:35840
	ds_read_b128 v[224:227], v136 offset:36864
	ds_read_b128 v[228:231], v136 offset:37888
	ds_read_b128 v[232:235], v136 offset:38912
	ds_read_b128 v[236:239], v136 offset:39936
	global_load_lds_dwordx4 v130, s[44:45]
	s_mov_b32 m0, s51
	s_nop 0
	global_load_lds_dwordx4 v128, s[44:45]
	s_waitcnt vmcnt(8)
	s_waitcnt lgkmcnt(0)
	s_barrier
; #define PG8_STAGE(bufoff, gbase, voff) do { _Pragma("unroll") for (int _i = 0; _i < 2; ++_i) \
;         __builtin_amdgcn_global_load_lds((const unsigned*)((const char*)(gbase) + (voff)[_i]), (PG8_LAS unsigned*)(lds + (bufoff) + ldsw + _i * 8192), 16, 0, 0); } while (0)
; #define PG8_LDA(dst, b, h) do { _Pragma("unroll") for (int m = 0; m < 4; ++m) _Pragma("unroll") for (int k = 0; k < 2; ++k) dst[m][k] = *(const PG8_LAS bf16x8*)(lds + PG8_SA(b, h) + aoff + m * 2048 + k * 1024); } while (0)
; #define PG8_MMA(ai, bj, At, Bt) do { __builtin_amdgcn_s_setprio(1); _Pragma("unroll") for (int m = 0; m < 4; ++m) _Pragma("unroll") for (int n = 0; n < 2; ++n) _Pragma("unroll") for (int k = 0; k < 2; ++k) \
;         acc[ai][bj][m][n] = mma16<F16>(Bt[n][k], At[m][k], acc[ai][bj][m][n]); __builtin_amdgcn_s_setprio(0); } while (0)
; #define PG8_WAIT_V(n) asm volatile("s_waitcnt vmcnt(" #n ")" ::: "memory")
; #define PG8_WAIT_L(n) asm volatile("s_waitcnt lgkmcnt(" #n ")" ::: "memory")
; #define PG8_BAR __builtin_amdgcn_s_barrier()
; #define PG8_SCHED __builtin_amdgcn_sched_barrier(0)
; template <class Epi, class Sched, bool ALIGN_EPI = false, bool SP2 = false, bool F16 = false>
; __device__ __forceinline__ void gemm_phase(PG8_LAS unsigned char* lds, const Gemm g, const Sched& S, const Epi& E, const int wid_in) {
;     ...
;             PG8_LDA(At, 1, 1); PG8_STAGE(PG8_SB(1, 0), b3, voffB); PG8_STAGE(PG8_SB(1, 1), b3 + hstep, voffB); PG8_STAGE(PG8_SA(1, 0), a3, voffA);
;             PG8_WAIT_V(8); PG8_WAIT_L(0); PG8_BAR; PG8_MMA(1, 0, At, B0); PG8_MMA(1, 1, At, B1); PG8_BAR; PG8_SCHED;
;     ...
;         if constexpr (!Epi::AFTER_DRAIN) { E(acc, cur, wr, wc, fr, fq); S.done(cur); }
	s_setprio 1
	s_waitcnt lgkmcnt(0)
	v_mfma_f32_16x16x32_bf16 v[32:35], v[4:7], v[16:19], v[64:67]
	v_mfma_f32_16x16x32_bf16 v[116:119], v[60:63], v[20:23], v[32:35]
	v_mfma_f32_16x16x32_bf16 v[32:35], v[168:171], v[16:19], v[68:71]
	v_mfma_f32_16x16x32_bf16 v[112:115], v[192:195], v[20:23], v[32:35]
	v_mfma_f32_16x16x32_bf16 v[32:35], v[4:7], v[104:107], v[72:75]
	v_mfma_f32_16x16x32_bf16 v[100:103], v[60:63], v[220:223], v[32:35]
	v_mfma_f32_16x16x32_bf16 v[32:35], v[168:171], v[104:107], v[76:79]
	v_mfma_f32_16x16x32_bf16 v[96:99], v[192:195], v[220:223], v[32:35]
	v_mfma_f32_16x16x32_bf16 v[32:35], v[4:7], v[224:227], v[80:83]
	v_mfma_f32_16x16x32_bf16 v[68:71], v[60:63], v[228:231], v[32:35]
	v_mfma_f32_16x16x32_bf16 v[32:35], v[168:171], v[224:227], v[84:87]
	v_mfma_f32_16x16x32_bf16 v[64:67], v[192:195], v[228:231], v[32:35]
	v_mfma_f32_16x16x32_bf16 v[32:35], v[4:7], v[232:235], v[88:91]
	v_mfma_f32_16x16x32_bf16 v[36:39], v[60:63], v[236:239], v[32:35]
	v_mfma_f32_16x16x32_bf16 v[32:35], v[168:171], v[232:235], v[92:95]
	v_mfma_f32_16x16x32_bf16 v[32:35], v[192:195], v[236:239], v[32:35]
	s_setprio 0
	s_setprio 1
	v_mfma_f32_16x16x32_bf16 v[72:75], v[196:199], v[16:19], v[204:207]
	v_mfma_f32_16x16x32_bf16 v[16:19], v[212:215], v[16:19], v[172:175]
	v_mfma_f32_16x16x32_bf16 v[120:123], v[216:219], v[20:23], v[16:19]
	v_mfma_f32_16x16x32_bf16 v[16:19], v[196:199], v[104:107], v[176:179]
	v_mfma_f32_16x16x32_bf16 v[108:111], v[208:211], v[220:223], v[16:19]
	v_mfma_f32_16x16x32_bf16 v[16:19], v[212:215], v[104:107], v[40:43]
	v_mfma_f32_16x16x32_bf16 v[104:107], v[216:219], v[220:223], v[16:19]
	v_mfma_f32_16x16x32_bf16 v[16:19], v[196:199], v[224:227], v[44:47]
	v_mfma_f32_16x16x32_bf16 v[80:83], v[208:211], v[228:231], v[16:19]
	v_mfma_f32_16x16x32_bf16 v[16:19], v[212:215], v[224:227], v[48:51]
	v_mfma_f32_16x16x32_bf16 v[124:127], v[208:211], v[20:23], v[72:75]
	v_mfma_f32_16x16x32_bf16 v[72:75], v[216:219], v[228:231], v[16:19]
	v_mfma_f32_16x16x32_bf16 v[16:19], v[196:199], v[232:235], v[52:55]
	v_mfma_f32_16x16x32_bf16 v[48:51], v[208:211], v[236:239], v[16:19]
	v_mfma_f32_16x16x32_bf16 v[16:19], v[212:215], v[232:235], v[56:59]
	v_mfma_f32_16x16x32_bf16 v[40:43], v[216:219], v[236:239], v[16:19]
	s_setprio 0
	s_barrier
	s_mov_b32 m0, s57
	s_nop 3
	v_lshl_add_u64 v[16:17], v[240:241], 0, s[24:25]
	s_add_u32 s36, s36, 0x10080
	ds_read_b128 v[56:59], v136 offset:49152
	ds_read_b128 v[88:91], v136 offset:50176
	ds_read_b128 v[172:175], v136 offset:51200
	ds_read_b128 v[176:179], v136 offset:52224
	ds_read_b128 v[204:207], v136 offset:53248
	ds_read_b128 v[220:223], v136 offset:54272
	ds_read_b128 v[224:227], v136 offset:55296
	ds_read_b128 v[228:231], v136 offset:56320
	global_load_lds_dwordx4 v[16:17], off
	v_lshl_add_u64 v[16:17], v[242:243], 0, s[24:25]
	s_mov_b32 m0, s58
	s_addc_u32 s37, s37, 0
	global_load_lds_dwordx4 v[16:17], off
	s_mov_b32 m0, s59
	s_nop 0
	global_load_lds_dwordx4 v130, s[36:37]
	s_mov_b32 m0, s60
	s_nop 0
	global_load_lds_dwordx4 v128, s[36:37]
	v_lshl_add_u64 v[16:17], v[244:245], 0, s[24:25]
	s_mov_b32 m0, s75
	s_nop 0
	global_load_lds_dwordx4 v[16:17], off
	v_lshl_add_u64 v[16:17], v[246:247], 0, s[24:25]
	s_mov_b32 m0, s14
	s_nop 0
	global_load_lds_dwordx4 v[16:17], off
	s_waitcnt vmcnt(8)
	s_waitcnt lgkmcnt(0)
	s_barrier
	s_setprio 1
	s_waitcnt lgkmcnt(0)
	v_mfma_f32_16x16x32_bf16 v[16:19], v[4:7], v[56:59], v[140:143]
	v_mfma_f32_16x16x32_bf16 v[84:87], v[60:63], v[88:91], v[16:19]
	v_mfma_f32_16x16x32_bf16 v[16:19], v[168:171], v[56:59], v[144:147]
	v_mfma_f32_16x16x32_bf16 v[76:79], v[192:195], v[88:91], v[16:19]
	v_mfma_f32_16x16x32_bf16 v[16:19], v[4:7], v[172:175], v[148:151]
	v_mfma_f32_16x16x32_bf16 v[52:55], v[60:63], v[176:179], v[16:19]
	v_mfma_f32_16x16x32_bf16 v[16:19], v[168:171], v[172:175], v[152:155]
	v_mfma_f32_16x16x32_bf16 v[44:47], v[192:195], v[176:179], v[16:19]
	v_mfma_f32_16x16x32_bf16 v[16:19], v[4:7], v[204:207], v[156:159]
	v_mfma_f32_16x16x32_bf16 v[0:3], v[4:7], v[224:227], v[0:3]
	v_mfma_f32_16x16x32_bf16 v[20:23], v[60:63], v[220:223], v[16:19]
	v_mfma_f32_16x16x32_bf16 v[16:19], v[168:171], v[204:207], v[160:163]
	v_mfma_f32_16x16x32_bf16 v[4:7], v[60:63], v[228:231], v[0:3]
	v_mfma_f32_16x16x32_bf16 v[0:3], v[168:171], v[224:227], v[200:203]
	v_mfma_f32_16x16x32_bf16 v[16:19], v[192:195], v[220:223], v[16:19]
	v_mfma_f32_16x16x32_bf16 v[0:3], v[192:195], v[228:231], v[0:3]
	s_setprio 0
	s_setprio 1
	v_mfma_f32_16x16x32_bf16 v[8:11], v[196:199], v[56:59], v[8:11]
	v_mfma_f32_16x16x32_bf16 v[92:95], v[208:211], v[88:91], v[8:11]
	v_mfma_f32_16x16x32_bf16 v[8:11], v[212:215], v[56:59], v[12:15]
	v_mfma_f32_16x16x32_bf16 v[88:91], v[216:219], v[88:91], v[8:11]
	v_mfma_f32_16x16x32_bf16 v[8:11], v[196:199], v[172:175], v[24:27]
	v_mfma_f32_16x16x32_bf16 v[60:63], v[208:211], v[176:179], v[8:11]
	v_mfma_f32_16x16x32_bf16 v[8:11], v[212:215], v[172:175], v[28:31]
	v_mfma_f32_16x16x32_bf16 v[56:59], v[216:219], v[176:179], v[8:11]
	v_mfma_f32_16x16x32_bf16 v[8:11], v[196:199], v[204:207], v[180:183]
	v_mfma_f32_16x16x32_bf16 v[28:31], v[208:211], v[220:223], v[8:11]
	v_mfma_f32_16x16x32_bf16 v[8:11], v[212:215], v[204:207], v[184:187]
	v_mfma_f32_16x16x32_bf16 v[24:27], v[216:219], v[220:223], v[8:11]
	v_mfma_f32_16x16x32_bf16 v[8:11], v[196:199], v[224:227], v[188:191]
	v_mfma_f32_16x16x32_bf16 v[12:15], v[208:211], v[228:231], v[8:11]
	v_mfma_f32_16x16x32_bf16 v[8:11], v[212:215], v[224:227], v[164:167]
	v_mfma_f32_16x16x32_bf16 v[8:11], v[216:219], v[228:231], v[8:11]
	s_setprio 0
	s_barrier
	s_and_b64 vcc, exec, s[8:9]
	s_cbranch_vccnz .LBB0_1279
	s_barrier

; #define PG8_STAGE(bufoff, gbase, voff) do { _Pragma("unroll") for (int _i = 0; _i < 2; ++_i) \
;         __builtin_amdgcn_global_load_lds((const unsigned*)((const char*)(gbase) + (voff)[_i]), (PG8_LAS unsigned*)(lds + (bufoff) + ldsw + _i * 8192), 16, 0, 0); } while (0)
; #define PG8_WAIT_V(n) asm volatile("s_waitcnt vmcnt(" #n ")" ::: "memory")
; #define PG8_BAR __builtin_amdgcn_s_barrier()
; template <class Epi, class Sched, bool ALIGN_EPI = false, bool SP2 = false, bool F16 = false>
; __device__ __forceinline__ void gemm_phase(PG8_LAS unsigned char* lds, const Gemm g, const Sched& S, const Epi& E, const int wid_in) {
;     ...
;     const int wid = wid_in, lane = lane_, tid = wid * 64 + lane, wr = wid >> 2, wc = wid & 3, fr = lane & 15, fq = lane >> 4;
;     const int K = g.K, nt = K / BK;
;     unsigned voffA[2], voffB[2];
; #pragma unroll
;     for (int i = 0; i < 2; ++i) { int R, C; stage_rc(tid * 16 + i * 8192, R, C); const int Rb = Epi::PERM ? ((R & ~31) + perm32(R & 31)) : R;
;         voffA[i] = (unsigned)(R * K + C) * 2u; voffB[i] = (unsigned)(Rb * K + C) * 2u; }
;     const size_t kstep = (size_t)(BK * 2);
;     const size_t hstep = (size_t)HALF * K * 2;
;     const size_t tstep = 2 * hstep;
;     const unsigned ldsw = (unsigned)wid * 1024u;
;     const int aoff = lds_byte(wr * 64 + fr, fq * 8), boff = lds_byte(wc * 32 + fr, fq * 8);
;     ...
;         PG8_WAIT_V(2); PG8_BAR;
;         PG8_STAGE(PG8_SB(1, 0), cB + kstep, voffB); PG8_STAGE(PG8_SA(1, 0), cA + kstep, voffA); PG8_STAGE(PG8_SB(1, 1), cB + hstep + kstep, voffB);
;         PG8_WAIT_V(6); PG8_BAR;
.LBB0_1359:
	s_add_u32 s24, s11, 0x7400000
	s_addc_u32 s25, s12, 0
	s_add_u32 s26, s11, 0x13400000
	s_addc_u32 s27, s12, 0
	s_add_u32 s28, s11, 0x15500000
	s_mov_b64 s[30:31], 0x80
	s_addc_u32 s29, s12, 0
	s_add_i32 m0, s74, 0x18000
	v_lshl_add_u64 v[6:7], v[6:7], 0, s[30:31]
	s_waitcnt vmcnt(2)
	s_barrier
	global_load_lds_dwordx4 v[6:7], off
	v_lshl_add_u64 v[4:5], v[4:5], 0, s[30:31]
	s_add_i32 m0, s74, 0x1a000
	s_add_i32 s52, s74, 0xa000
	global_load_lds_dwordx4 v[4:5], off
	v_lshl_add_u64 v[0:1], v[0:1], 0, s[30:31]
	s_mov_b32 m0, s75
	s_add_u32 s12, s44, 0xb0080
	global_load_lds_dwordx4 v[0:1], off
	v_lshl_add_u64 v[0:1], v[2:3], 0, s[30:31]
	s_mov_b32 m0, s52
	s_addc_u32 s13, s45, 0
	global_load_lds_dwordx4 v[0:1], off
	s_add_i32 m0, s74, 0x1c000
	s_nop 0
	global_load_lds_dwordx4 v154, s[12:13]
	s_add_i32 m0, s74, 0x1e000
	v_and_b32_e32 v187, 15, v8
	global_load_lds_dwordx4 v158, s[12:13]
	v_or_b32_e32 v0, s70, v187
	v_lshlrev_b32_e32 v1, 6, v0
	v_and_b32_e32 v2, 48, v8
	s_movk_i32 s11, 0x3c0
	v_and_b32_e32 v3, 0xfffffc00, v13
	v_lshlrev_b32_e32 v0, 2, v0
	v_and_or_b32 v1, v1, s11, v2
	v_add_u32_e32 v4, s73, v3
	v_and_b32_e32 v0, 32, v0
	v_bitop3_b32 v4, v1, v4, v0 bitop3:0xde
	v_lshl_or_b32 v0, v187, 6, v2
	v_lshlrev_b32_e32 v2, 2, v8
	v_add_u32_e32 v1, s72, v3
	v_and_b32_e32 v2, 32, v2
	v_bitop3_b32 v188, v0, v1, v2 bitop3:0xde
	v_lshrrev_b32_e32 v1, 1, v9
	v_mul_lo_u32 v0, v11, s10
	s_mov_b32 s11, 0xb000
	v_mad_u64_u32 v[0:1], s[34:35], v1, s11, v[0:1]
	v_or_b32_e32 v0, v0, v10
	s_mov_b64 s[12:13], 0xb0080
	v_add_lshl_u32 v0, v0, v12, 1
	v_mov_b32_e32 v1, v155
	v_lshl_add_u64 v[160:161], v[0:1], 0, s[12:13]
	v_lshrrev_b32_e32 v1, 1, v14
	v_mul_lo_u32 v0, v15, s10
	v_mad_u64_u32 v[0:1], s[10:11], v1, s11, v[0:1]
	s_waitcnt vmcnt(6)
	v_or_b32_e32 v0, v0, v16
	v_add_lshl_u32 v0, v0, v17, 1
	v_mov_b32_e32 v1, v155
	s_add_i32 s56, 0, 0x10000
	s_add_i32 s57, 0, 0x14000
	v_ashrrev_i32_e32 v186, 4, v8
	s_ashr_i32 s53, s38, 31
	s_mov_b32 s54, s38
	s_ashr_i32 s55, s14, 31
	v_lshl_add_u64 v[162:163], v[0:1], 0, s[12:13]
	v_mov_b64_e32 v[164:165], 0x100
	v_mov_b64_e32 v[166:167], 0xff
	v_add_u32_e32 v189, s56, v188
	v_add_u32_e32 v190, s57, v188
	v_add_u32_e32 v191, 0, v4
	s_mov_b32 s58, 0
	s_barrier
	s_branch .LBB0_1362

; #define PG8_STAGE(bufoff, gbase, voff) do { _Pragma("unroll") for (int _i = 0; _i < 2; ++_i) \
;         __builtin_amdgcn_global_load_lds((const unsigned*)((const char*)(gbase) + (voff)[_i]), (PG8_LAS unsigned*)(lds + (bufoff) + ldsw + _i * 8192), 16, 0, 0); } while (0)
; #define PG8_LDA(dst, b, h) do { _Pragma("unroll") for (int m = 0; m < 4; ++m) _Pragma("unroll") for (int k = 0; k < 2; ++k) dst[m][k] = *(const PG8_LAS bf16x8*)(lds + PG8_SA(b, h) + aoff + m * 2048 + k * 1024); } while (0)
; #define PG8_LDB(dst, b, h) do { _Pragma("unroll") for (int n = 0; n < 2; ++n) _Pragma("unroll") for (int k = 0; k < 2; ++k) dst[n][k] = *(const PG8_LAS bf16x8*)(lds + PG8_SB(b, h) + boff + n * 2048 + k * 1024); } while (0)
; #define PG8_MMA(ai, bj, At, Bt) do { __builtin_amdgcn_s_setprio(1); _Pragma("unroll") for (int m = 0; m < 4; ++m) _Pragma("unroll") for (int n = 0; n < 2; ++n) _Pragma("unroll") for (int k = 0; k < 2; ++k) \
;         acc[ai][bj][m][n] = mma16<F16>(Bt[n][k], At[m][k], acc[ai][bj][m][n]); __builtin_amdgcn_s_setprio(0); } while (0)
; #define PG8_WAIT_V(n) asm volatile("s_waitcnt vmcnt(" #n ")" ::: "memory")
; #define PG8_BAR __builtin_amdgcn_s_barrier()
; template <class Epi, class Sched, bool ALIGN_EPI = false, bool SP2 = false, bool F16 = false>
; __device__ __forceinline__ void gemm_phase(PG8_LAS unsigned char* lds, const Gemm g, const Sched& S, const Epi& E, const int wid_in) {
;     ...
;         for (int t = 0; t < nt; t += 2) {
;             const bool last = (t == nt - 2);
;             const char* a1 = cA + (size_t)(t + 1) * kstep;
;             const char* a2 = last ? nA : cA + (size_t)(t + 2) * kstep; const char* b2 = last ? nB : cB + (size_t)(t + 2) * kstep;
;             const char* a3 = a2 + kstep; const char* b3 = b2 + kstep;
;             if (last && has_next) S.a_ready(nxt);
;             if constexpr (SP2) {
;             PG8_LDB(B0, 0, 0); PG8_LDB(B1, 0, 1); PG8_SCHED; PG8_LDA(At, 0, 0); PG8_STAGE(PG8_SA(1, 1), a1 + hstep, voffA);
;             PG8_WAIT_V(8); PG8_WAIT_L(0); PG8_BAR; PG8_MMA(0, 0, At, B0); PG8_MMA(0, 1, At, B1); PG8_BAR; PG8_SCHED;
;             PG8_LDA(At, 0, 1); PG8_STAGE(PG8_SB(0, 0), b2, voffB); PG8_STAGE(PG8_SB(0, 1), b2 + hstep, voffB); PG8_STAGE(PG8_SA(0, 0), a2, voffA);
;             PG8_WAIT_V(8); PG8_WAIT_L(0); PG8_BAR; PG8_MMA(1, 0, At, B0); PG8_MMA(1, 1, At, B1); PG8_BAR; PG8_SCHED;
.LBB0_1373:
	ds_read_b128 v[128:131], v189
	ds_read_b128 v[132:135], v189 offset:1024
	ds_read_b128 v[136:139], v189 offset:2048
	ds_read_b128 v[140:143], v189 offset:3072
	ds_read_b128 v[144:147], v190
	ds_read_b128 v[148:151], v190 offset:1024
	ds_read_b128 v[168:171], v190 offset:2048
	ds_read_b128 v[172:175], v190 offset:3072
	s_add_u32 s44, s36, 0x100
	s_addc_u32 s45, s37, 0
	s_cmp_eq_u32 s62, 40
	s_cselect_b32 s49, s13, s45
	s_cselect_b32 s48, s12, s44
	s_cselect_b32 s47, s35, s61
	s_cselect_b32 s46, s34, s43
	v_lshl_add_u64 v[184:185], s[36:37], 0, v[160:161]
	s_add_i32 m0, s74, 0xc000
	ds_read_b128 v[176:179], v191
	ds_read_b128 v[180:183], v191 offset:1024
	ds_read_b128 v[192:195], v191 offset:2048
	ds_read_b128 v[196:199], v191 offset:3072
	ds_read_b128 v[200:203], v191 offset:4096
	ds_read_b128 v[204:207], v191 offset:5120
	ds_read_b128 v[208:211], v191 offset:6144
	ds_read_b128 v[212:215], v191 offset:7168
	global_load_lds_dwordx4 v[184:185], off
	v_lshl_add_u64 v[184:185], s[36:37], 0, v[162:163]
	s_add_i32 m0, s74, 0xe000
	s_nop 0
	global_load_lds_dwordx4 v[184:185], off
	s_waitcnt vmcnt(8)
	s_waitcnt lgkmcnt(0)
	s_barrier
	s_setprio 1
	s_waitcnt lgkmcnt(0)
	v_mfma_f32_16x16x32_bf16 v[124:127], v[128:131], v[176:179], v[124:127]
	v_mfma_f32_16x16x32_bf16 v[120:123], v[136:139], v[176:179], v[120:123]
	v_mfma_f32_16x16x32_bf16 v[108:111], v[128:131], v[192:195], v[108:111]
	v_mfma_f32_16x16x32_bf16 v[104:107], v[136:139], v[192:195], v[104:107]
	v_mfma_f32_16x16x32_bf16 v[92:95], v[128:131], v[200:203], v[92:95]
	v_mfma_f32_16x16x32_bf16 v[88:91], v[136:139], v[200:203], v[88:91]
	v_mfma_f32_16x16x32_bf16 v[76:79], v[128:131], v[208:211], v[76:79]
	v_mfma_f32_16x16x32_bf16 v[72:75], v[136:139], v[208:211], v[72:75]
	v_mfma_f32_16x16x32_bf16 v[124:127], v[132:135], v[180:183], v[124:127]
	v_mfma_f32_16x16x32_bf16 v[120:123], v[140:143], v[180:183], v[120:123]
	v_mfma_f32_16x16x32_bf16 v[108:111], v[132:135], v[196:199], v[108:111]
	v_mfma_f32_16x16x32_bf16 v[104:107], v[140:143], v[196:199], v[104:107]
	v_mfma_f32_16x16x32_bf16 v[92:95], v[132:135], v[204:207], v[92:95]
	v_mfma_f32_16x16x32_bf16 v[88:91], v[140:143], v[204:207], v[88:91]
	v_mfma_f32_16x16x32_bf16 v[76:79], v[132:135], v[212:215], v[76:79]
	v_mfma_f32_16x16x32_bf16 v[72:75], v[140:143], v[212:215], v[72:75]
	s_setprio 0
	s_setprio 1
	v_mfma_f32_16x16x32_bf16 v[116:119], v[144:147], v[176:179], v[116:119]
	v_mfma_f32_16x16x32_bf16 v[112:115], v[168:171], v[176:179], v[112:115]
	v_mfma_f32_16x16x32_bf16 v[100:103], v[144:147], v[192:195], v[100:103]
	v_mfma_f32_16x16x32_bf16 v[96:99], v[168:171], v[192:195], v[96:99]
	v_mfma_f32_16x16x32_bf16 v[84:87], v[144:147], v[200:203], v[84:87]
	v_mfma_f32_16x16x32_bf16 v[80:83], v[168:171], v[200:203], v[80:83]
	v_mfma_f32_16x16x32_bf16 v[68:71], v[144:147], v[208:211], v[68:71]
	v_mfma_f32_16x16x32_bf16 v[64:67], v[168:171], v[208:211], v[64:67]
	v_mfma_f32_16x16x32_bf16 v[116:119], v[148:151], v[180:183], v[116:119]
	v_mfma_f32_16x16x32_bf16 v[112:115], v[172:175], v[180:183], v[112:115]
	v_mfma_f32_16x16x32_bf16 v[100:103], v[148:151], v[196:199], v[100:103]
	v_mfma_f32_16x16x32_bf16 v[96:99], v[172:175], v[196:199], v[96:99]
	v_mfma_f32_16x16x32_bf16 v[84:87], v[148:151], v[204:207], v[84:87]
	v_mfma_f32_16x16x32_bf16 v[80:83], v[172:175], v[204:207], v[80:83]
	v_mfma_f32_16x16x32_bf16 v[68:71], v[148:151], v[212:215], v[68:71]
	v_mfma_f32_16x16x32_bf16 v[64:67], v[172:175], v[212:215], v[64:67]
	s_setprio 0
	s_barrier
	s_add_i32 s36, s56, s68
	v_lshl_add_u64 v[184:185], s[46:47], 0, v[154:155]
	s_mov_b32 m0, s36
	ds_read_b128 v[176:179], v191 offset:16384
	ds_read_b128 v[180:183], v191 offset:17408
	ds_read_b128 v[192:195], v191 offset:18432
	ds_read_b128 v[196:199], v191 offset:19456
	ds_read_b128 v[200:203], v191 offset:20480
	ds_read_b128 v[204:207], v191 offset:21504
	ds_read_b128 v[208:211], v191 offset:22528
	ds_read_b128 v[212:215], v191 offset:23552
	global_load_lds_dwordx4 v[184:185], off
	s_add_i32 m0, s36, 0x2000
	s_add_u32 s36, s46, 0xb0000
	v_lshl_add_u64 v[216:217], s[46:47], 0, v[158:159]
	s_addc_u32 s37, s47, 0
	s_add_i32 s63, s57, s68
	global_load_lds_dwordx4 v[216:217], off
	s_mov_b32 m0, s63
	v_lshl_add_u64 v[220:221], s[48:49], 0, v[156:157]
	global_load_lds_dwordx4 v154, s[36:37]
	s_add_i32 m0, s63, 0x2000
	s_nop 0
	global_load_lds_dwordx4 v158, s[36:37]
	v_lshl_add_u64 v[218:219], s[48:49], 0, v[152:153]
	s_mov_b32 m0, s74
	s_nop 0
	global_load_lds_dwordx4 v[218:219], off
	s_mov_b32 m0, s41
	s_nop 0
	global_load_lds_dwordx4 v[220:221], off
	s_waitcnt vmcnt(8)
	s_waitcnt lgkmcnt(0)
	s_barrier
; #define PG8_STAGE(bufoff, gbase, voff) do { _Pragma("unroll") for (int _i = 0; _i < 2; ++_i) \
;         __builtin_amdgcn_global_load_lds((const unsigned*)((const char*)(gbase) + (voff)[_i]), (PG8_LAS unsigned*)(lds + (bufoff) + ldsw + _i * 8192), 16, 0, 0); } while (0)
; #define PG8_LDA(dst, b, h) do { _Pragma("unroll") for (int m = 0; m < 4; ++m) _Pragma("unroll") for (int k = 0; k < 2; ++k) dst[m][k] = *(const PG8_LAS bf16x8*)(lds + PG8_SA(b, h) + aoff + m * 2048 + k * 1024); } while (0)
; #define PG8_LDB(dst, b, h) do { _Pragma("unroll") for (int n = 0; n < 2; ++n) _Pragma("unroll") for (int k = 0; k < 2; ++k) dst[n][k] = *(const PG8_LAS bf16x8*)(lds + PG8_SB(b, h) + boff + n * 2048 + k * 1024); } while (0)
; #define PG8_MMA(ai, bj, At, Bt) do { __builtin_amdgcn_s_setprio(1); _Pragma("unroll") for (int m = 0; m < 4; ++m) _Pragma("unroll") for (int n = 0; n < 2; ++n) _Pragma("unroll") for (int k = 0; k < 2; ++k) \
;         acc[ai][bj][m][n] = mma16<F16>(Bt[n][k], At[m][k], acc[ai][bj][m][n]); __builtin_amdgcn_s_setprio(0); } while (0)
; #define PG8_WAIT_V(n) asm volatile("s_waitcnt vmcnt(" #n ")" ::: "memory")
; #define PG8_WAIT_L(n) asm volatile("s_waitcnt lgkmcnt(" #n ")" ::: "memory")
; #define PG8_BAR __builtin_amdgcn_s_barrier()
; #define PG8_SCHED __builtin_amdgcn_sched_barrier(0)
; template <class Epi, class Sched, bool ALIGN_EPI = false, bool SP2 = false, bool F16 = false>
; __device__ __forceinline__ void gemm_phase(PG8_LAS unsigned char* lds, const Gemm g, const Sched& S, const Epi& E, const int wid_in) {
;     ...
;             PG8_WAIT_V(8); PG8_WAIT_L(0); PG8_BAR; PG8_MMA(1, 0, At, B0); PG8_MMA(1, 1, At, B1); PG8_BAR; PG8_SCHED;
;             PG8_LDB(B0, 1, 0); PG8_LDB(B1, 1, 1); PG8_SCHED; PG8_LDA(At, 1, 0); PG8_STAGE(PG8_SA(0, 1), a2 + hstep, voffA);
;             PG8_WAIT_V(8); PG8_WAIT_L(0); PG8_BAR; PG8_MMA(0, 0, At, B0); PG8_MMA(0, 1, At, B1); PG8_BAR; PG8_SCHED;
	s_setprio 1
	s_waitcnt lgkmcnt(0)
	v_mfma_f32_16x16x32_bf16 v[60:63], v[128:131], v[176:179], v[60:63]
	v_mfma_f32_16x16x32_bf16 v[56:59], v[136:139], v[176:179], v[56:59]
	v_mfma_f32_16x16x32_bf16 v[44:47], v[128:131], v[192:195], v[44:47]
	v_mfma_f32_16x16x32_bf16 v[40:43], v[136:139], v[192:195], v[40:43]
	v_mfma_f32_16x16x32_bf16 v[28:31], v[128:131], v[200:203], v[28:31]
	v_mfma_f32_16x16x32_bf16 v[24:27], v[136:139], v[200:203], v[24:27]
	v_mfma_f32_16x16x32_bf16 v[12:15], v[128:131], v[208:211], v[12:15]
	v_mfma_f32_16x16x32_bf16 v[8:11], v[136:139], v[208:211], v[8:11]
	v_mfma_f32_16x16x32_bf16 v[60:63], v[132:135], v[180:183], v[60:63]
	v_mfma_f32_16x16x32_bf16 v[56:59], v[140:143], v[180:183], v[56:59]
	v_mfma_f32_16x16x32_bf16 v[44:47], v[132:135], v[196:199], v[44:47]
	v_mfma_f32_16x16x32_bf16 v[40:43], v[140:143], v[196:199], v[40:43]
	v_mfma_f32_16x16x32_bf16 v[28:31], v[132:135], v[204:207], v[28:31]
	v_mfma_f32_16x16x32_bf16 v[24:27], v[140:143], v[204:207], v[24:27]
	v_mfma_f32_16x16x32_bf16 v[12:15], v[132:135], v[212:215], v[12:15]
	v_mfma_f32_16x16x32_bf16 v[8:11], v[140:143], v[212:215], v[8:11]
	s_setprio 0
	s_setprio 1
	v_mfma_f32_16x16x32_bf16 v[52:55], v[144:147], v[176:179], v[52:55]
	v_mfma_f32_16x16x32_bf16 v[48:51], v[168:171], v[176:179], v[48:51]
	v_mfma_f32_16x16x32_bf16 v[36:39], v[144:147], v[192:195], v[36:39]
	v_mfma_f32_16x16x32_bf16 v[32:35], v[168:171], v[192:195], v[32:35]
	v_mfma_f32_16x16x32_bf16 v[20:23], v[144:147], v[200:203], v[20:23]
	v_mfma_f32_16x16x32_bf16 v[16:19], v[168:171], v[200:203], v[16:19]
	v_mfma_f32_16x16x32_bf16 v[4:7], v[144:147], v[208:211], v[4:7]
	v_mfma_f32_16x16x32_bf16 v[0:3], v[168:171], v[208:211], v[0:3]
	v_mfma_f32_16x16x32_bf16 v[52:55], v[148:151], v[180:183], v[52:55]
	v_mfma_f32_16x16x32_bf16 v[48:51], v[172:175], v[180:183], v[48:51]
	v_mfma_f32_16x16x32_bf16 v[36:39], v[148:151], v[196:199], v[36:39]
	v_mfma_f32_16x16x32_bf16 v[32:35], v[172:175], v[196:199], v[32:35]
	v_mfma_f32_16x16x32_bf16 v[20:23], v[148:151], v[204:207], v[20:23]
	v_mfma_f32_16x16x32_bf16 v[16:19], v[172:175], v[204:207], v[16:19]
	v_mfma_f32_16x16x32_bf16 v[4:7], v[148:151], v[212:215], v[4:7]
	v_mfma_f32_16x16x32_bf16 v[0:3], v[172:175], v[212:215], v[0:3]
	s_setprio 0
	s_barrier
	s_add_i32 s63, 0, 0x18000
	s_add_i32 s64, 0, 0x1c000
	v_add_u32_e32 v140, s63, v188
	v_add_u32_e32 v172, s64, v188
	ds_read_b128 v[128:131], v140
	ds_read_b128 v[132:135], v140 offset:1024
	ds_read_b128 v[136:139], v140 offset:2048
	ds_read_b128 v[140:143], v140 offset:3072
	ds_read_b128 v[144:147], v172
	ds_read_b128 v[148:151], v172 offset:1024
	ds_read_b128 v[168:171], v172 offset:2048
	ds_read_b128 v[172:175], v172 offset:3072
	s_add_u32 s36, s48, 0xb0000
	s_addc_u32 s37, s49, 0
	s_mov_b32 m0, s50
	ds_read_b128 v[176:179], v191 offset:32768
	ds_read_b128 v[180:183], v191 offset:33792
	ds_read_b128 v[192:195], v191 offset:34816
	ds_read_b128 v[196:199], v191 offset:35840
	ds_read_b128 v[200:203], v191 offset:36864
	ds_read_b128 v[204:207], v191 offset:37888
	ds_read_b128 v[208:211], v191 offset:38912
	ds_read_b128 v[212:215], v191 offset:39936
	global_load_lds_dwordx4 v152, s[36:37]
	v_lshl_add_u64 v[222:223], s[36:37], 0, v[156:157]
	s_mov_b32 m0, s51
	s_nop 0
	global_load_lds_dwordx4 v[222:223], off
	s_waitcnt vmcnt(8)
	s_waitcnt lgkmcnt(0)
	s_barrier
	s_setprio 1
	s_waitcnt lgkmcnt(0)
	v_mfma_f32_16x16x32_bf16 v[124:127], v[128:131], v[176:179], v[124:127]
	v_mfma_f32_16x16x32_bf16 v[120:123], v[136:139], v[176:179], v[120:123]
	v_mfma_f32_16x16x32_bf16 v[108:111], v[128:131], v[192:195], v[108:111]
	v_mfma_f32_16x16x32_bf16 v[104:107], v[136:139], v[192:195], v[104:107]
	v_mfma_f32_16x16x32_bf16 v[92:95], v[128:131], v[200:203], v[92:95]
	v_mfma_f32_16x16x32_bf16 v[88:91], v[136:139], v[200:203], v[88:91]
	v_mfma_f32_16x16x32_bf16 v[76:79], v[128:131], v[208:211], v[76:79]
	v_mfma_f32_16x16x32_bf16 v[72:75], v[136:139], v[208:211], v[72:75]
	v_mfma_f32_16x16x32_bf16 v[124:127], v[132:135], v[180:183], v[124:127]
	v_mfma_f32_16x16x32_bf16 v[120:123], v[140:143], v[180:183], v[120:123]
	v_mfma_f32_16x16x32_bf16 v[108:111], v[132:135], v[196:199], v[108:111]
	v_mfma_f32_16x16x32_bf16 v[104:107], v[140:143], v[196:199], v[104:107]
	v_mfma_f32_16x16x32_bf16 v[92:95], v[132:135], v[204:207], v[92:95]
	v_mfma_f32_16x16x32_bf16 v[88:91], v[140:143], v[204:207], v[88:91]
	v_mfma_f32_16x16x32_bf16 v[76:79], v[132:135], v[212:215], v[76:79]
	v_mfma_f32_16x16x32_bf16 v[72:75], v[140:143], v[212:215], v[72:75]
	s_setprio 0
	s_setprio 1
	v_mfma_f32_16x16x32_bf16 v[116:119], v[144:147], v[176:179], v[116:119]
	v_mfma_f32_16x16x32_bf16 v[112:115], v[168:171], v[176:179], v[112:115]
	v_mfma_f32_16x16x32_bf16 v[100:103], v[144:147], v[192:195], v[100:103]
	v_mfma_f32_16x16x32_bf16 v[96:99], v[168:171], v[192:195], v[96:99]
	v_mfma_f32_16x16x32_bf16 v[84:87], v[144:147], v[200:203], v[84:87]
	v_mfma_f32_16x16x32_bf16 v[80:83], v[168:171], v[200:203], v[80:83]
	v_mfma_f32_16x16x32_bf16 v[68:71], v[144:147], v[208:211], v[68:71]
	v_mfma_f32_16x16x32_bf16 v[64:67], v[168:171], v[208:211], v[64:67]
	v_mfma_f32_16x16x32_bf16 v[116:119], v[148:151], v[180:183], v[116:119]
	v_mfma_f32_16x16x32_bf16 v[112:115], v[172:175], v[180:183], v[112:115]
	v_mfma_f32_16x16x32_bf16 v[100:103], v[148:151], v[196:199], v[100:103]
	v_mfma_f32_16x16x32_bf16 v[96:99], v[172:175], v[196:199], v[96:99]
	v_mfma_f32_16x16x32_bf16 v[84:87], v[148:151], v[204:207], v[84:87]
	v_mfma_f32_16x16x32_bf16 v[80:83], v[172:175], v[204:207], v[80:83]
	v_mfma_f32_16x16x32_bf16 v[68:71], v[148:151], v[212:215], v[68:71]
	v_mfma_f32_16x16x32_bf16 v[64:67], v[172:175], v[212:215], v[64:67]
	s_setprio 0
	s_barrier
; #define PG8_STAGE(bufoff, gbase, voff) do { _Pragma("unroll") for (int _i = 0; _i < 2; ++_i) \
;         __builtin_amdgcn_global_load_lds((const unsigned*)((const char*)(gbase) + (voff)[_i]), (PG8_LAS unsigned*)(lds + (bufoff) + ldsw + _i * 8192), 16, 0, 0); } while (0)
; #define PG8_LDA(dst, b, h) do { _Pragma("unroll") for (int m = 0; m < 4; ++m) _Pragma("unroll") for (int k = 0; k < 2; ++k) dst[m][k] = *(const PG8_LAS bf16x8*)(lds + PG8_SA(b, h) + aoff + m * 2048 + k * 1024); } while (0)
; #define PG8_MMA(ai, bj, At, Bt) do { __builtin_amdgcn_s_setprio(1); _Pragma("unroll") for (int m = 0; m < 4; ++m) _Pragma("unroll") for (int n = 0; n < 2; ++n) _Pragma("unroll") for (int k = 0; k < 2; ++k) \
;         acc[ai][bj][m][n] = mma16<F16>(Bt[n][k], At[m][k], acc[ai][bj][m][n]); __builtin_amdgcn_s_setprio(0); } while (0)
; #define PG8_WAIT_V(n) asm volatile("s_waitcnt vmcnt(" #n ")" ::: "memory")
; #define PG8_WAIT_L(n) asm volatile("s_waitcnt lgkmcnt(" #n ")" ::: "memory")
; #define PG8_BAR __builtin_amdgcn_s_barrier()
; #define PG8_SCHED __builtin_amdgcn_sched_barrier(0)
; template <class Epi, class Sched, bool ALIGN_EPI = false, bool SP2 = false, bool F16 = false>
; __device__ __forceinline__ void gemm_phase(PG8_LAS unsigned char* lds, const Gemm g, const Sched& S, const Epi& E, const int wid_in) {
;     ...
;         for (int t = 0; t < nt; t += 2) {
;     ...
;             PG8_LDA(At, 1, 1); PG8_STAGE(PG8_SB(1, 0), b3, voffB); PG8_STAGE(PG8_SB(1, 1), b3 + hstep, voffB); PG8_STAGE(PG8_SA(1, 0), a3, voffA);
;             PG8_WAIT_V(8); PG8_WAIT_L(0); PG8_BAR; PG8_MMA(1, 0, At, B0); PG8_MMA(1, 1, At, B1); PG8_BAR; PG8_SCHED;
	s_add_i32 s36, s63, s68
	v_lshl_add_u64 v[184:185], v[184:185], 0, s[30:31]
	s_mov_b32 m0, s36
	ds_read_b128 v[176:179], v191 offset:49152
	ds_read_b128 v[180:183], v191 offset:50176
	ds_read_b128 v[192:195], v191 offset:51200
	ds_read_b128 v[196:199], v191 offset:52224
	ds_read_b128 v[200:203], v191 offset:53248
	ds_read_b128 v[204:207], v191 offset:54272
	ds_read_b128 v[208:211], v191 offset:55296
	ds_read_b128 v[212:215], v191 offset:56320
	global_load_lds_dwordx4 v[184:185], off
	s_add_i32 m0, s36, 0x2000
	s_add_u32 s36, s46, 0xb0080
	v_lshl_add_u64 v[184:185], v[216:217], 0, s[30:31]
	s_addc_u32 s37, s47, 0
	s_add_i32 s46, s64, s68
	global_load_lds_dwordx4 v[184:185], off
	s_mov_b32 m0, s46
	s_nop 0
	global_load_lds_dwordx4 v154, s[36:37]
	s_add_i32 m0, s46, 0x2000
	s_nop 0
	global_load_lds_dwordx4 v158, s[36:37]
	v_lshl_add_u64 v[184:185], v[218:219], 0, s[30:31]
	s_mov_b32 m0, s75
	s_nop 0
	global_load_lds_dwordx4 v[184:185], off
	v_lshl_add_u64 v[184:185], v[220:221], 0, s[30:31]
	s_mov_b32 m0, s52
	s_nop 0
	global_load_lds_dwordx4 v[184:185], off
	s_waitcnt vmcnt(8)
	s_waitcnt lgkmcnt(0)
	s_barrier
	s_setprio 1
	s_waitcnt lgkmcnt(0)
	v_mfma_f32_16x16x32_bf16 v[60:63], v[128:131], v[176:179], v[60:63]
	v_mfma_f32_16x16x32_bf16 v[56:59], v[136:139], v[176:179], v[56:59]
	v_mfma_f32_16x16x32_bf16 v[44:47], v[128:131], v[192:195], v[44:47]
	v_mfma_f32_16x16x32_bf16 v[40:43], v[136:139], v[192:195], v[40:43]
	v_mfma_f32_16x16x32_bf16 v[28:31], v[128:131], v[200:203], v[28:31]
	v_mfma_f32_16x16x32_bf16 v[24:27], v[136:139], v[200:203], v[24:27]
	v_mfma_f32_16x16x32_bf16 v[12:15], v[128:131], v[208:211], v[12:15]
	v_mfma_f32_16x16x32_bf16 v[8:11], v[136:139], v[208:211], v[8:11]
	v_mfma_f32_16x16x32_bf16 v[60:63], v[132:135], v[180:183], v[60:63]
	v_mfma_f32_16x16x32_bf16 v[56:59], v[140:143], v[180:183], v[56:59]
	v_mfma_f32_16x16x32_bf16 v[44:47], v[132:135], v[196:199], v[44:47]
	v_mfma_f32_16x16x32_bf16 v[40:43], v[140:143], v[196:199], v[40:43]
	v_mfma_f32_16x16x32_bf16 v[28:31], v[132:135], v[204:207], v[28:31]
	v_mfma_f32_16x16x32_bf16 v[24:27], v[140:143], v[204:207], v[24:27]
	v_mfma_f32_16x16x32_bf16 v[12:15], v[132:135], v[212:215], v[12:15]
	v_mfma_f32_16x16x32_bf16 v[8:11], v[140:143], v[212:215], v[8:11]
	s_setprio 0
	s_setprio 1
	v_mfma_f32_16x16x32_bf16 v[52:55], v[144:147], v[176:179], v[52:55]
	v_mfma_f32_16x16x32_bf16 v[48:51], v[168:171], v[176:179], v[48:51]
	v_mfma_f32_16x16x32_bf16 v[36:39], v[144:147], v[192:195], v[36:39]
	v_mfma_f32_16x16x32_bf16 v[32:35], v[168:171], v[192:195], v[32:35]
	v_mfma_f32_16x16x32_bf16 v[20:23], v[144:147], v[200:203], v[20:23]
	v_mfma_f32_16x16x32_bf16 v[16:19], v[168:171], v[200:203], v[16:19]
	v_mfma_f32_16x16x32_bf16 v[4:7], v[144:147], v[208:211], v[4:7]
	v_mfma_f32_16x16x32_bf16 v[0:3], v[168:171], v[208:211], v[0:3]
	v_mfma_f32_16x16x32_bf16 v[52:55], v[148:151], v[180:183], v[52:55]
	v_mfma_f32_16x16x32_bf16 v[48:51], v[172:175], v[180:183], v[48:51]
	v_mfma_f32_16x16x32_bf16 v[36:39], v[148:151], v[196:199], v[36:39]
	v_mfma_f32_16x16x32_bf16 v[32:35], v[172:175], v[196:199], v[32:35]
	v_mfma_f32_16x16x32_bf16 v[20:23], v[148:151], v[204:207], v[20:23]
	v_mfma_f32_16x16x32_bf16 v[16:19], v[172:175], v[204:207], v[16:19]
	v_mfma_f32_16x16x32_bf16 v[4:7], v[148:151], v[212:215], v[4:7]
	v_mfma_f32_16x16x32_bf16 v[0:3], v[172:175], v[212:215], v[0:3]
	s_setprio 0
	s_barrier
	s_add_i32 s62, s62, 2
	s_add_u32 s43, s43, 0x100
	s_addc_u32 s61, s61, 0
	s_cmp_gt_u32 s62, 41
	s_mov_b64 s[36:37], s[44:45]
	s_cbranch_scc0 .LBB0_1373
	s_and_b64 vcc, exec, s[16:17]
	s_cbranch_vccz .LBB0_1376
	s_barrier

; #define PG8_STAGE(bufoff, gbase, voff) do { _Pragma("unroll") for (int _i = 0; _i < 2; ++_i) \
;         __builtin_amdgcn_global_load_lds((const unsigned*)((const char*)(gbase) + (voff)[_i]), (PG8_LAS unsigned*)(lds + (bufoff) + ldsw + _i * 8192), 16, 0, 0); } while (0)
; #define PG8_WAIT_V(n) asm volatile("s_waitcnt vmcnt(" #n ")" ::: "memory")
; #define PG8_BAR __builtin_amdgcn_s_barrier()
; template <class Epi, class Sched, bool ALIGN_EPI = false, bool SP2 = false, bool F16 = false>
; __device__ __forceinline__ void gemm_phase(PG8_LAS unsigned char* lds, const Gemm g, const Sched& S, const Epi& E, const int wid_in) {
;     ...
;     const int wid = wid_in, lane = lane_, tid = wid * 64 + lane, wr = wid >> 2, wc = wid & 3, fr = lane & 15, fq = lane >> 4;
;     const int K = g.K, nt = K / BK;
;     unsigned voffA[2], voffB[2];
; #pragma unroll
;     for (int i = 0; i < 2; ++i) { int R, C; stage_rc(tid * 16 + i * 8192, R, C); const int Rb = Epi::PERM ? ((R & ~31) + perm32(R & 31)) : R;
;         voffA[i] = (unsigned)(R * K + C) * 2u; voffB[i] = (unsigned)(Rb * K + C) * 2u; }
;     const size_t kstep = (size_t)(BK * 2);
;     const size_t hstep = (size_t)HALF * K * 2;
;     const size_t tstep = 2 * hstep;
;     const unsigned ldsw = (unsigned)wid * 1024u;
;     const int aoff = lds_byte(wr * 64 + fr, fq * 8), boff = lds_byte(wc * 32 + fr, fq * 8);
;     ...
;         PG8_WAIT_V(2); PG8_BAR;
;         PG8_STAGE(PG8_SB(1, 0), cB + kstep, voffB); PG8_STAGE(PG8_SA(1, 0), cA + kstep, voffA); PG8_STAGE(PG8_SB(1, 1), cB + hstep + kstep, voffB);
;         PG8_WAIT_V(6); PG8_BAR;
.LBB0_1459:
	s_add_u32 s24, s10, 0x13400000
	s_addc_u32 s25, s11, 0
	s_add_u32 s26, s10, 0xf400000
	s_addc_u32 s27, s11, 0
	s_add_u32 s28, s10, 0x15600000
	s_addc_u32 s29, s11, 0
	s_add_u32 s30, s10, 0x15500000
	s_mov_b64 s[34:35], 0x80
	s_addc_u32 s31, s11, 0
	s_add_i32 m0, s74, 0x18000
	v_lshl_add_u64 v[6:7], v[6:7], 0, s[34:35]
	s_waitcnt vmcnt(2)
	s_barrier
	global_load_lds_dwordx4 v[6:7], off
	v_lshl_add_u64 v[4:5], v[4:5], 0, s[34:35]
	s_add_i32 m0, s74, 0x1a000
	s_add_i32 s62, s74, 0xa000
	global_load_lds_dwordx4 v[4:5], off
	v_lshl_add_u64 v[0:1], v[0:1], 0, s[34:35]
	s_mov_b32 m0, s75
	s_add_u32 s10, s54, 0x40080
	global_load_lds_dwordx4 v[0:1], off
	v_lshl_add_u64 v[0:1], v[2:3], 0, s[34:35]
	s_mov_b32 m0, s62
	s_addc_u32 s11, s55, 0
	global_load_lds_dwordx4 v[0:1], off
	s_add_i32 m0, s74, 0x1c000
	s_nop 0
	global_load_lds_dwordx4 v198, s[10:11]
	s_add_i32 m0, s74, 0x1e000
	v_and_b32_e32 v232, 15, v8
	global_load_lds_dwordx4 v202, s[10:11]
	v_or_b32_e32 v0, s70, v232
	v_lshlrev_b32_e32 v1, 6, v0
	v_and_b32_e32 v2, 48, v8
	s_movk_i32 s10, 0x3c0
	v_and_b32_e32 v3, 0xfffffc00, v12
	v_lshlrev_b32_e32 v0, 2, v0
	v_and_or_b32 v1, v1, s10, v2
	v_add_u32_e32 v4, s73, v3
	v_and_b32_e32 v0, 32, v0
	v_bitop3_b32 v0, v1, v4, v0 bitop3:0xde
	v_lshl_or_b32 v1, v232, 6, v2
	v_add_u32_e32 v2, s72, v3
	v_lshlrev_b32_e32 v3, 2, v8
	v_and_b32_e32 v3, 32, v3
	v_bitop3_b32 v234, v1, v2, v3 bitop3:0xde
	v_lshlrev_b32_e32 v1, 14, v9
	v_and_b32_e32 v1, 0xffff8000, v1
	v_lshl_add_u32 v1, v10, 11, v1
	v_and_b32_e32 v2, 1, v9
	v_lshl_or_b32 v1, v2, 6, v1
	v_lshl_add_u32 v204, v11, 1, v1
	v_lshlrev_b32_e32 v1, 14, v13
	v_and_b32_e32 v1, 0xffff8000, v1
	s_waitcnt vmcnt(6)
	v_lshl_add_u32 v1, v14, 11, v1
	v_and_b32_e32 v2, 1, v13
	v_lshl_or_b32 v1, v2, 6, v1
	s_add_i32 s66, 0, 0x10000
	s_add_i32 s67, 0, 0x14000
	v_ashrrev_i32_e32 v233, 4, v8
	s_ashr_i32 s63, s38, 31
	s_mov_b32 s64, s38
	s_ashr_i32 s65, s19, 31
	v_mov_b32_e32 v205, v199
	v_lshl_add_u32 v206, v15, 1, v1
	v_mov_b32_e32 v207, v199
	v_mov_b64_e32 v[208:209], 0x100
	v_mov_b64_e32 v[210:211], 0xff
	v_add_u32_e32 v235, s66, v234
	v_add_u32_e32 v236, s67, v234
	v_add_u32_e32 v237, 0, v0
	v_mov_b32_e32 v238, 0x358637bd
	s_mov_b32 s91, 0
	s_barrier
	s_branch .LBB0_1462

; #define PG8_STAGE(bufoff, gbase, voff) do { _Pragma("unroll") for (int _i = 0; _i < 2; ++_i) \
;         __builtin_amdgcn_global_load_lds((const unsigned*)((const char*)(gbase) + (voff)[_i]), (PG8_LAS unsigned*)(lds + (bufoff) + ldsw + _i * 8192), 16, 0, 0); } while (0)
; #define PG8_LDA(dst, b, h) do { _Pragma("unroll") for (int m = 0; m < 4; ++m) _Pragma("unroll") for (int k = 0; k < 2; ++k) dst[m][k] = *(const PG8_LAS bf16x8*)(lds + PG8_SA(b, h) + aoff + m * 2048 + k * 1024); } while (0)
; #define PG8_LDB(dst, b, h) do { _Pragma("unroll") for (int n = 0; n < 2; ++n) _Pragma("unroll") for (int k = 0; k < 2; ++k) dst[n][k] = *(const PG8_LAS bf16x8*)(lds + PG8_SB(b, h) + boff + n * 2048 + k * 1024); } while (0)
; #define PG8_MMA(ai, bj, At, Bt) do { __builtin_amdgcn_s_setprio(1); _Pragma("unroll") for (int m = 0; m < 4; ++m) _Pragma("unroll") for (int n = 0; n < 2; ++n) _Pragma("unroll") for (int k = 0; k < 2; ++k) \
;         acc[ai][bj][m][n] = mma16<F16>(Bt[n][k], At[m][k], acc[ai][bj][m][n]); __builtin_amdgcn_s_setprio(0); } while (0)
; #define PG8_WAIT_V(n) asm volatile("s_waitcnt vmcnt(" #n ")" ::: "memory")
; #define PG8_BAR __builtin_amdgcn_s_barrier()
; template <class Epi, class Sched, bool ALIGN_EPI = false, bool SP2 = false, bool F16 = false>
; __device__ __forceinline__ void gemm_phase(PG8_LAS unsigned char* lds, const Gemm g, const Sched& S, const Epi& E, const int wid_in) {
;     ...
;         for (int t = 0; t < nt; t += 2) {
;             const bool last = (t == nt - 2);
;             const char* a1 = cA + (size_t)(t + 1) * kstep;
;             const char* a2 = last ? nA : cA + (size_t)(t + 2) * kstep; const char* b2 = last ? nB : cB + (size_t)(t + 2) * kstep;
;             const char* a3 = a2 + kstep; const char* b3 = b2 + kstep;
;             if (last && has_next) S.a_ready(nxt);
;             if constexpr (SP2) {
;             PG8_LDB(B0, 0, 0); PG8_LDB(B1, 0, 1); PG8_SCHED; PG8_LDA(At, 0, 0); PG8_STAGE(PG8_SA(1, 1), a1 + hstep, voffA);
;             PG8_WAIT_V(8); PG8_WAIT_L(0); PG8_BAR; PG8_MMA(0, 0, At, B0); PG8_MMA(0, 1, At, B1); PG8_BAR; PG8_SCHED;
;             PG8_LDA(At, 0, 1); PG8_STAGE(PG8_SB(0, 0), b2, voffB); PG8_STAGE(PG8_SB(0, 1), b2 + hstep, voffB); PG8_STAGE(PG8_SA(0, 0), a2, voffA);
;             PG8_WAIT_V(8); PG8_WAIT_L(0); PG8_BAR; PG8_MMA(1, 0, At, B0); PG8_MMA(1, 1, At, B1); PG8_BAR; PG8_SCHED;
.LBB0_1469:
	ds_read_b128 v[112:115], v235
	ds_read_b128 v[116:119], v235 offset:1024
	ds_read_b128 v[128:131], v235 offset:2048
	ds_read_b128 v[132:135], v235 offset:3072
	ds_read_b128 v[144:147], v236
	ds_read_b128 v[148:151], v236 offset:1024
	ds_read_b128 v[152:155], v236 offset:2048
	ds_read_b128 v[156:159], v236 offset:3072
	s_add_u32 s45, s52, 0xfffc0080
	s_addc_u32 s51, s53, -1
	s_cmp_eq_u32 s43, 12
	s_cselect_b32 s57, s14, s51
	s_cselect_b32 s56, s15, s45
	s_cselect_b32 s55, s37, s42
	s_cselect_b32 s54, s40, s41
	s_add_i32 m0, s74, 0xc000
	ds_read_b128 v[160:163], v237
	ds_read_b128 v[164:167], v237 offset:1024
	ds_read_b128 v[168:171], v237 offset:2048
	ds_read_b128 v[172:175], v237 offset:3072
	ds_read_b128 v[176:179], v237 offset:4096
	ds_read_b128 v[180:183], v237 offset:5120
	ds_read_b128 v[184:187], v237 offset:6144
	ds_read_b128 v[188:191], v237 offset:7168
	global_load_lds_dwordx4 v204, s[52:53]
	s_add_i32 m0, s74, 0xe000
	s_nop 0
	global_load_lds_dwordx4 v206, s[52:53]
	s_waitcnt vmcnt(8)
	s_waitcnt lgkmcnt(0)
	s_barrier
	s_setprio 1
	s_waitcnt lgkmcnt(0)
	v_mfma_f32_16x16x32_f16 v[140:143], v[112:115], v[160:163], v[140:143]
	v_mfma_f32_16x16x32_f16 v[136:139], v[128:131], v[160:163], v[136:139]
	v_mfma_f32_16x16x32_f16 v[108:111], v[112:115], v[168:171], v[108:111]
	v_mfma_f32_16x16x32_f16 v[104:107], v[128:131], v[168:171], v[104:107]
	v_mfma_f32_16x16x32_f16 v[92:95], v[112:115], v[176:179], v[92:95]
	v_mfma_f32_16x16x32_f16 v[88:91], v[128:131], v[176:179], v[88:91]
	v_mfma_f32_16x16x32_f16 v[76:79], v[112:115], v[184:187], v[76:79]
	v_mfma_f32_16x16x32_f16 v[72:75], v[128:131], v[184:187], v[72:75]
	v_mfma_f32_16x16x32_f16 v[140:143], v[116:119], v[164:167], v[140:143]
	v_mfma_f32_16x16x32_f16 v[136:139], v[132:135], v[164:167], v[136:139]
	v_mfma_f32_16x16x32_f16 v[108:111], v[116:119], v[172:175], v[108:111]
	v_mfma_f32_16x16x32_f16 v[104:107], v[132:135], v[172:175], v[104:107]
	v_mfma_f32_16x16x32_f16 v[92:95], v[116:119], v[180:183], v[92:95]
	v_mfma_f32_16x16x32_f16 v[88:91], v[132:135], v[180:183], v[88:91]
	v_mfma_f32_16x16x32_f16 v[76:79], v[116:119], v[188:191], v[76:79]
	v_mfma_f32_16x16x32_f16 v[72:75], v[132:135], v[188:191], v[72:75]
	s_setprio 0
	s_setprio 1
	v_mfma_f32_16x16x32_f16 v[124:127], v[144:147], v[160:163], v[124:127]
	v_mfma_f32_16x16x32_f16 v[120:123], v[152:155], v[160:163], v[120:123]
	v_mfma_f32_16x16x32_f16 v[100:103], v[144:147], v[168:171], v[100:103]
	v_mfma_f32_16x16x32_f16 v[96:99], v[152:155], v[168:171], v[96:99]
	v_mfma_f32_16x16x32_f16 v[84:87], v[144:147], v[176:179], v[84:87]
	v_mfma_f32_16x16x32_f16 v[80:83], v[152:155], v[176:179], v[80:83]
	v_mfma_f32_16x16x32_f16 v[68:71], v[144:147], v[184:187], v[68:71]
	v_mfma_f32_16x16x32_f16 v[64:67], v[152:155], v[184:187], v[64:67]
	v_mfma_f32_16x16x32_f16 v[124:127], v[148:151], v[164:167], v[124:127]
	v_mfma_f32_16x16x32_f16 v[120:123], v[156:159], v[164:167], v[120:123]
	v_mfma_f32_16x16x32_f16 v[100:103], v[148:151], v[172:175], v[100:103]
	v_mfma_f32_16x16x32_f16 v[96:99], v[156:159], v[172:175], v[96:99]
	v_mfma_f32_16x16x32_f16 v[84:87], v[148:151], v[180:183], v[84:87]
	v_mfma_f32_16x16x32_f16 v[80:83], v[156:159], v[180:183], v[80:83]
	v_mfma_f32_16x16x32_f16 v[68:71], v[148:151], v[188:191], v[68:71]
	v_mfma_f32_16x16x32_f16 v[64:67], v[156:159], v[188:191], v[64:67]
	s_setprio 0
	s_barrier
	s_add_i32 s45, s66, s68
	v_lshl_add_u64 v[192:193], s[54:55], 0, v[198:199]
	s_mov_b32 m0, s45
	ds_read_b128 v[160:163], v237 offset:16384
	ds_read_b128 v[164:167], v237 offset:17408
	ds_read_b128 v[168:171], v237 offset:18432
	ds_read_b128 v[172:175], v237 offset:19456
	ds_read_b128 v[176:179], v237 offset:20480
	ds_read_b128 v[180:183], v237 offset:21504
	ds_read_b128 v[184:187], v237 offset:22528
	ds_read_b128 v[188:191], v237 offset:23552
	global_load_lds_dwordx4 v[192:193], off
	s_add_i32 m0, s45, 0x2000
	s_add_u32 s94, s54, 0x40000
	v_lshl_add_u64 v[194:195], s[54:55], 0, v[202:203]
	s_addc_u32 s95, s55, 0
	s_add_i32 s45, s67, s68
	global_load_lds_dwordx4 v[194:195], off
	s_mov_b32 m0, s45
	v_lshl_add_u64 v[214:215], s[56:57], 0, v[200:201]
	global_load_lds_dwordx4 v198, s[94:95]
	s_add_i32 m0, s45, 0x2000
	s_nop 0
	global_load_lds_dwordx4 v202, s[94:95]
	v_lshl_add_u64 v[212:213], s[56:57], 0, v[196:197]
	s_mov_b32 m0, s74
	s_nop 0
	global_load_lds_dwordx4 v[212:213], off
	s_mov_b32 m0, s59
	s_nop 0
	global_load_lds_dwordx4 v[214:215], off
	s_waitcnt vmcnt(8)
	s_waitcnt lgkmcnt(0)
	s_barrier
	s_setprio 1
	s_waitcnt lgkmcnt(0)
	v_mfma_f32_16x16x32_f16 v[60:63], v[112:115], v[160:163], v[60:63]
	v_mfma_f32_16x16x32_f16 v[56:59], v[128:131], v[160:163], v[56:59]
	v_mfma_f32_16x16x32_f16 v[44:47], v[112:115], v[168:171], v[44:47]
	v_mfma_f32_16x16x32_f16 v[40:43], v[128:131], v[168:171], v[40:43]
	v_mfma_f32_16x16x32_f16 v[28:31], v[112:115], v[176:179], v[28:31]
	v_mfma_f32_16x16x32_f16 v[24:27], v[128:131], v[176:179], v[24:27]
	v_mfma_f32_16x16x32_f16 v[12:15], v[112:115], v[184:187], v[12:15]
	v_mfma_f32_16x16x32_f16 v[8:11], v[128:131], v[184:187], v[8:11]
	v_mfma_f32_16x16x32_f16 v[60:63], v[116:119], v[164:167], v[60:63]
	v_mfma_f32_16x16x32_f16 v[56:59], v[132:135], v[164:167], v[56:59]
	v_mfma_f32_16x16x32_f16 v[44:47], v[116:119], v[172:175], v[44:47]
	v_mfma_f32_16x16x32_f16 v[40:43], v[132:135], v[172:175], v[40:43]
	v_mfma_f32_16x16x32_f16 v[28:31], v[116:119], v[180:183], v[28:31]
	v_mfma_f32_16x16x32_f16 v[24:27], v[132:135], v[180:183], v[24:27]
	v_mfma_f32_16x16x32_f16 v[12:15], v[116:119], v[188:191], v[12:15]
	v_mfma_f32_16x16x32_f16 v[8:11], v[132:135], v[188:191], v[8:11]
	s_setprio 0
	s_setprio 1
	v_mfma_f32_16x16x32_f16 v[52:55], v[144:147], v[160:163], v[52:55]
	v_mfma_f32_16x16x32_f16 v[48:51], v[152:155], v[160:163], v[48:51]
	v_mfma_f32_16x16x32_f16 v[36:39], v[144:147], v[168:171], v[36:39]
	v_mfma_f32_16x16x32_f16 v[32:35], v[152:155], v[168:171], v[32:35]
	v_mfma_f32_16x16x32_f16 v[20:23], v[144:147], v[176:179], v[20:23]
	v_mfma_f32_16x16x32_f16 v[16:19], v[152:155], v[176:179], v[16:19]
	v_mfma_f32_16x16x32_f16 v[4:7], v[144:147], v[184:187], v[4:7]
	v_mfma_f32_16x16x32_f16 v[0:3], v[152:155], v[184:187], v[0:3]
	v_mfma_f32_16x16x32_f16 v[52:55], v[148:151], v[164:167], v[52:55]
	v_mfma_f32_16x16x32_f16 v[48:51], v[156:159], v[164:167], v[48:51]
	v_mfma_f32_16x16x32_f16 v[36:39], v[148:151], v[172:175], v[36:39]
	v_mfma_f32_16x16x32_f16 v[32:35], v[156:159], v[172:175], v[32:35]
	v_mfma_f32_16x16x32_f16 v[20:23], v[148:151], v[180:183], v[20:23]
	v_mfma_f32_16x16x32_f16 v[16:19], v[156:159], v[180:183], v[16:19]
	v_mfma_f32_16x16x32_f16 v[4:7], v[148:151], v[188:191], v[4:7]
	v_mfma_f32_16x16x32_f16 v[0:3], v[156:159], v[188:191], v[0:3]
	s_setprio 0
	s_barrier
; #define PG8_STAGE(bufoff, gbase, voff) do { _Pragma("unroll") for (int _i = 0; _i < 2; ++_i) \
;         __builtin_amdgcn_global_load_lds((const unsigned*)((const char*)(gbase) + (voff)[_i]), (PG8_LAS unsigned*)(lds + (bufoff) + ldsw + _i * 8192), 16, 0, 0); } while (0)
; #define PG8_LDA(dst, b, h) do { _Pragma("unroll") for (int m = 0; m < 4; ++m) _Pragma("unroll") for (int k = 0; k < 2; ++k) dst[m][k] = *(const PG8_LAS bf16x8*)(lds + PG8_SA(b, h) + aoff + m * 2048 + k * 1024); } while (0)
; #define PG8_LDB(dst, b, h) do { _Pragma("unroll") for (int n = 0; n < 2; ++n) _Pragma("unroll") for (int k = 0; k < 2; ++k) dst[n][k] = *(const PG8_LAS bf16x8*)(lds + PG8_SB(b, h) + boff + n * 2048 + k * 1024); } while (0)
; #define PG8_MMA(ai, bj, At, Bt) do { __builtin_amdgcn_s_setprio(1); _Pragma("unroll") for (int m = 0; m < 4; ++m) _Pragma("unroll") for (int n = 0; n < 2; ++n) _Pragma("unroll") for (int k = 0; k < 2; ++k) \
;         acc[ai][bj][m][n] = mma16<F16>(Bt[n][k], At[m][k], acc[ai][bj][m][n]); __builtin_amdgcn_s_setprio(0); } while (0)
; #define PG8_WAIT_V(n) asm volatile("s_waitcnt vmcnt(" #n ")" ::: "memory")
; #define PG8_WAIT_L(n) asm volatile("s_waitcnt lgkmcnt(" #n ")" ::: "memory")
; template <class Epi, class Sched, bool ALIGN_EPI = false, bool SP2 = false, bool F16 = false>
; __device__ __forceinline__ void gemm_phase(PG8_LAS unsigned char* lds, const Gemm g, const Sched& S, const Epi& E, const int wid_in) {
;     ...
;         for (int t = 0; t < nt; t += 2) {
;             const bool last = (t == nt - 2);
;             const char* a1 = cA + (size_t)(t + 1) * kstep;
;             const char* a2 = last ? nA : cA + (size_t)(t + 2) * kstep; const char* b2 = last ? nB : cB + (size_t)(t + 2) * kstep;
;             const char* a3 = a2 + kstep; const char* b3 = b2 + kstep;
;             if (last && has_next) S.a_ready(nxt);
;     ...
;             PG8_LDB(B0, 1, 0); PG8_LDB(B1, 1, 1); PG8_SCHED; PG8_LDA(At, 1, 0); PG8_STAGE(PG8_SA(0, 1), a2 + hstep, voffA);
;             PG8_WAIT_V(8); PG8_WAIT_L(0); PG8_BAR; PG8_MMA(0, 0, At, B0); PG8_MMA(0, 1, At, B1); PG8_BAR; PG8_SCHED;
;             PG8_LDA(At, 1, 1); PG8_STAGE(PG8_SB(1, 0), b3, voffB); PG8_STAGE(PG8_SB(1, 1), b3 + hstep, voffB); PG8_STAGE(PG8_SA(1, 0), a3, voffA);
;             PG8_WAIT_V(8); PG8_WAIT_L(0); PG8_BAR; PG8_MMA(1, 0, At, B0); PG8_MMA(1, 1, At, B1); PG8_BAR; PG8_SCHED;
	s_add_i32 s45, 0, 0x18000
	s_add_i32 s51, 0, 0x1c000
	v_add_u32_e32 v132, s45, v234
	v_add_u32_e32 v156, s51, v234
	ds_read_b128 v[112:115], v132
	ds_read_b128 v[116:119], v132 offset:1024
	ds_read_b128 v[128:131], v132 offset:2048
	ds_read_b128 v[132:135], v132 offset:3072
	ds_read_b128 v[144:147], v156
	ds_read_b128 v[148:151], v156 offset:1024
	ds_read_b128 v[152:155], v156 offset:2048
	ds_read_b128 v[156:159], v156 offset:3072
	s_add_u32 s56, s56, 0x40000
	s_addc_u32 s57, s57, 0
	s_mov_b32 m0, s60
	ds_read_b128 v[160:163], v237 offset:32768
	ds_read_b128 v[164:167], v237 offset:33792
	ds_read_b128 v[168:171], v237 offset:34816
	ds_read_b128 v[172:175], v237 offset:35840
	ds_read_b128 v[176:179], v237 offset:36864
	ds_read_b128 v[180:183], v237 offset:37888
	ds_read_b128 v[184:187], v237 offset:38912
	ds_read_b128 v[188:191], v237 offset:39936
	global_load_lds_dwordx4 v196, s[56:57]
	s_mov_b32 m0, s61
	s_nop 0
	global_load_lds_dwordx4 v200, s[56:57]
	s_waitcnt vmcnt(8)
	s_waitcnt lgkmcnt(0)
	s_barrier
	s_setprio 1
	s_waitcnt lgkmcnt(0)
	v_mfma_f32_16x16x32_f16 v[140:143], v[112:115], v[160:163], v[140:143]
	v_mfma_f32_16x16x32_f16 v[136:139], v[128:131], v[160:163], v[136:139]
	v_mfma_f32_16x16x32_f16 v[108:111], v[112:115], v[168:171], v[108:111]
	v_mfma_f32_16x16x32_f16 v[104:107], v[128:131], v[168:171], v[104:107]
	v_mfma_f32_16x16x32_f16 v[92:95], v[112:115], v[176:179], v[92:95]
	v_mfma_f32_16x16x32_f16 v[88:91], v[128:131], v[176:179], v[88:91]
	v_mfma_f32_16x16x32_f16 v[76:79], v[112:115], v[184:187], v[76:79]
	v_mfma_f32_16x16x32_f16 v[72:75], v[128:131], v[184:187], v[72:75]
	v_mfma_f32_16x16x32_f16 v[140:143], v[116:119], v[164:167], v[140:143]
	v_mfma_f32_16x16x32_f16 v[136:139], v[132:135], v[164:167], v[136:139]
	v_mfma_f32_16x16x32_f16 v[108:111], v[116:119], v[172:175], v[108:111]
	v_mfma_f32_16x16x32_f16 v[104:107], v[132:135], v[172:175], v[104:107]
	v_mfma_f32_16x16x32_f16 v[92:95], v[116:119], v[180:183], v[92:95]
	v_mfma_f32_16x16x32_f16 v[88:91], v[132:135], v[180:183], v[88:91]
	v_mfma_f32_16x16x32_f16 v[76:79], v[116:119], v[188:191], v[76:79]
	v_mfma_f32_16x16x32_f16 v[72:75], v[132:135], v[188:191], v[72:75]
	s_setprio 0
	s_setprio 1
	v_mfma_f32_16x16x32_f16 v[124:127], v[144:147], v[160:163], v[124:127]
	v_mfma_f32_16x16x32_f16 v[120:123], v[152:155], v[160:163], v[120:123]
	v_mfma_f32_16x16x32_f16 v[100:103], v[144:147], v[168:171], v[100:103]
	v_mfma_f32_16x16x32_f16 v[96:99], v[152:155], v[168:171], v[96:99]
	v_mfma_f32_16x16x32_f16 v[84:87], v[144:147], v[176:179], v[84:87]
	v_mfma_f32_16x16x32_f16 v[80:83], v[152:155], v[176:179], v[80:83]
	v_mfma_f32_16x16x32_f16 v[68:71], v[144:147], v[184:187], v[68:71]
	v_mfma_f32_16x16x32_f16 v[64:67], v[152:155], v[184:187], v[64:67]
	v_mfma_f32_16x16x32_f16 v[124:127], v[148:151], v[164:167], v[124:127]
	v_mfma_f32_16x16x32_f16 v[120:123], v[156:159], v[164:167], v[120:123]
	v_mfma_f32_16x16x32_f16 v[100:103], v[148:151], v[172:175], v[100:103]
	v_mfma_f32_16x16x32_f16 v[96:99], v[156:159], v[172:175], v[96:99]
	v_mfma_f32_16x16x32_f16 v[84:87], v[148:151], v[180:183], v[84:87]
	v_mfma_f32_16x16x32_f16 v[80:83], v[156:159], v[180:183], v[80:83]
	v_mfma_f32_16x16x32_f16 v[68:71], v[148:151], v[188:191], v[68:71]
	v_mfma_f32_16x16x32_f16 v[64:67], v[156:159], v[188:191], v[64:67]
	s_setprio 0
	s_barrier
	s_add_i32 s45, s45, s68
	v_lshl_add_u64 v[192:193], v[192:193], 0, s[34:35]
	s_mov_b32 m0, s45
	ds_read_b128 v[160:163], v237 offset:49152
	ds_read_b128 v[164:167], v237 offset:50176
	ds_read_b128 v[168:171], v237 offset:51200
	ds_read_b128 v[172:175], v237 offset:52224
	ds_read_b128 v[176:179], v237 offset:53248
	ds_read_b128 v[180:183], v237 offset:54272
	ds_read_b128 v[184:187], v237 offset:55296
	ds_read_b128 v[188:191], v237 offset:56320
	global_load_lds_dwordx4 v[192:193], off
	s_add_i32 m0, s45, 0x2000
	s_add_u32 s54, s54, 0x40080
	v_lshl_add_u64 v[192:193], v[194:195], 0, s[34:35]
	s_addc_u32 s55, s55, 0
	s_add_i32 s45, s51, s68
	global_load_lds_dwordx4 v[192:193], off
	s_mov_b32 m0, s45
	s_nop 0
	global_load_lds_dwordx4 v198, s[54:55]
	s_add_i32 m0, s45, 0x2000
	s_nop 0
	global_load_lds_dwordx4 v202, s[54:55]
	v_lshl_add_u64 v[192:193], v[212:213], 0, s[34:35]
	s_mov_b32 m0, s75
	s_nop 0
	global_load_lds_dwordx4 v[192:193], off
	v_lshl_add_u64 v[192:193], v[214:215], 0, s[34:35]
	s_mov_b32 m0, s62
	s_nop 0
	global_load_lds_dwordx4 v[192:193], off
	s_waitcnt vmcnt(8)
	s_waitcnt lgkmcnt(0)
	s_barrier
	s_setprio 1
	s_waitcnt lgkmcnt(0)
	v_mfma_f32_16x16x32_f16 v[60:63], v[112:115], v[160:163], v[60:63]
	v_mfma_f32_16x16x32_f16 v[56:59], v[128:131], v[160:163], v[56:59]
	v_mfma_f32_16x16x32_f16 v[44:47], v[112:115], v[168:171], v[44:47]
	v_mfma_f32_16x16x32_f16 v[40:43], v[128:131], v[168:171], v[40:43]
	v_mfma_f32_16x16x32_f16 v[28:31], v[112:115], v[176:179], v[28:31]
	v_mfma_f32_16x16x32_f16 v[24:27], v[128:131], v[176:179], v[24:27]
	v_mfma_f32_16x16x32_f16 v[12:15], v[112:115], v[184:187], v[12:15]
	v_mfma_f32_16x16x32_f16 v[8:11], v[128:131], v[184:187], v[8:11]
	v_mfma_f32_16x16x32_f16 v[60:63], v[116:119], v[164:167], v[60:63]
	v_mfma_f32_16x16x32_f16 v[56:59], v[132:135], v[164:167], v[56:59]
	v_mfma_f32_16x16x32_f16 v[44:47], v[116:119], v[172:175], v[44:47]
	v_mfma_f32_16x16x32_f16 v[40:43], v[132:135], v[172:175], v[40:43]
	v_mfma_f32_16x16x32_f16 v[28:31], v[116:119], v[180:183], v[28:31]
	v_mfma_f32_16x16x32_f16 v[24:27], v[132:135], v[180:183], v[24:27]
	v_mfma_f32_16x16x32_f16 v[12:15], v[116:119], v[188:191], v[12:15]
	v_mfma_f32_16x16x32_f16 v[8:11], v[132:135], v[188:191], v[8:11]
	s_setprio 0
	s_setprio 1
	v_mfma_f32_16x16x32_f16 v[52:55], v[144:147], v[160:163], v[52:55]
	v_mfma_f32_16x16x32_f16 v[48:51], v[152:155], v[160:163], v[48:51]
	v_mfma_f32_16x16x32_f16 v[36:39], v[144:147], v[168:171], v[36:39]
	v_mfma_f32_16x16x32_f16 v[32:35], v[152:155], v[168:171], v[32:35]
	v_mfma_f32_16x16x32_f16 v[20:23], v[144:147], v[176:179], v[20:23]
	v_mfma_f32_16x16x32_f16 v[16:19], v[152:155], v[176:179], v[16:19]
	v_mfma_f32_16x16x32_f16 v[4:7], v[144:147], v[184:187], v[4:7]
	v_mfma_f32_16x16x32_f16 v[0:3], v[152:155], v[184:187], v[0:3]
	v_mfma_f32_16x16x32_f16 v[52:55], v[148:151], v[164:167], v[52:55]
	v_mfma_f32_16x16x32_f16 v[48:51], v[156:159], v[164:167], v[48:51]
	v_mfma_f32_16x16x32_f16 v[36:39], v[148:151], v[172:175], v[36:39]
	v_mfma_f32_16x16x32_f16 v[32:35], v[156:159], v[172:175], v[32:35]
	v_mfma_f32_16x16x32_f16 v[20:23], v[148:151], v[180:183], v[20:23]
	v_mfma_f32_16x16x32_f16 v[16:19], v[156:159], v[180:183], v[16:19]
	v_mfma_f32_16x16x32_f16 v[4:7], v[148:151], v[188:191], v[4:7]
	v_mfma_f32_16x16x32_f16 v[0:3], v[156:159], v[188:191], v[0:3]
	s_setprio 0
	s_barrier
	s_add_i32 s43, s43, 2
	s_add_u32 s52, s52, 0x100
	s_addc_u32 s53, s53, 0
	s_add_u32 s41, s41, 0x100
	s_addc_u32 s42, s42, 0
	s_cmp_gt_u32 s43, 13
	s_cbranch_scc0 .LBB0_1469
	s_and_b64 vcc, exec, s[16:17]
	s_cbranch_vccz .LBB0_1472
	s_barrier

; #define PG8_STAGE(bufoff, gbase, voff) do { _Pragma("unroll") for (int _i = 0; _i < 2; ++_i) \
;         __builtin_amdgcn_global_load_lds((const unsigned*)((const char*)(gbase) + (voff)[_i]), (PG8_LAS unsigned*)(lds + (bufoff) + ldsw + _i * 8192), 16, 0, 0); } while (0)
; #define PG8_WAIT_V(n) asm volatile("s_waitcnt vmcnt(" #n ")" ::: "memory")
; #define PG8_BAR __builtin_amdgcn_s_barrier()
; template <class Epi, class Sched, bool ALIGN_EPI = false, bool SP2 = false, bool F16 = false>
; __device__ __forceinline__ void gemm_phase(PG8_LAS unsigned char* lds, const Gemm g, const Sched& S, const Epi& E, const int wid_in) {
;     ...
;     for (int i = 0; i < 2; ++i) { int R, C; stage_rc(tid * 16 + i * 8192, R, C); const int Rb = Epi::PERM ? ((R & ~31) + perm32(R & 31)) : R;
;         voffA[i] = (unsigned)(R * K + C) * 2u; voffB[i] = (unsigned)(Rb * K + C) * 2u; }
;     const size_t kstep = (size_t)(BK * 2);
;     const size_t hstep = (size_t)HALF * K * 2;
;     const size_t tstep = 2 * hstep;
;     const unsigned ldsw = (unsigned)wid * 1024u;
;     const int aoff = lds_byte(wr * 64 + fr, fq * 8), boff = lds_byte(wc * 32 + fr, fq * 8);
;     ...
;         PG8_STAGE(PG8_SB(1, 0), cB + kstep, voffB); PG8_STAGE(PG8_SA(1, 0), cA + kstep, voffA); PG8_STAGE(PG8_SB(1, 1), cB + hstep + kstep, voffB);
;         PG8_WAIT_V(6); PG8_BAR;
.LBB0_1542:
	s_add_u32 s95, s60, 0x9400000
	s_mov_b64 s[34:35], 0x80
	s_addc_u32 s96, s61, 0
	s_add_i32 m0, s74, 0x18000
	v_lshl_add_u64 v[6:7], v[6:7], 0, s[34:35]
	s_waitcnt vmcnt(2)
	s_barrier
	global_load_lds_dwordx4 v[6:7], off
	v_lshl_add_u64 v[4:5], v[4:5], 0, s[34:35]
	s_add_i32 m0, s74, 0x1a000
	s_add_i32 s97, s74, 0xa000
	global_load_lds_dwordx4 v[4:5], off
	v_lshl_add_u64 v[0:1], v[0:1], 0, s[34:35]
	s_mov_b32 m0, s75
	s_add_u32 s10, s52, 0x40080
	global_load_lds_dwordx4 v[0:1], off
	v_lshl_add_u64 v[0:1], v[2:3], 0, s[34:35]
	s_mov_b32 m0, s97
	s_addc_u32 s11, s53, 0
	global_load_lds_dwordx4 v[0:1], off
	s_add_i32 m0, s74, 0x1c000
	s_nop 0
	global_load_lds_dwordx4 v158, s[10:11]
	s_add_i32 m0, s74, 0x1e000
	v_and_b32_e32 v181, 15, v9
	global_load_lds_dwordx4 v162, s[10:11]
	v_or_b32_e32 v0, s70, v181
	v_lshlrev_b32_e32 v1, 6, v0
	v_and_b32_e32 v2, 48, v9
	s_movk_i32 s10, 0x3c0
	v_and_b32_e32 v3, 0xfffffc00, v15
	v_lshlrev_b32_e32 v0, 2, v0
	v_and_or_b32 v1, v1, s10, v2
	v_add_u32_e32 v4, s73, v3
	v_and_b32_e32 v0, 32, v0
	v_bitop3_b32 v0, v1, v4, v0 bitop3:0xde
	v_lshl_or_b32 v1, v181, 6, v2
	v_add_u32_e32 v2, s72, v3
	v_lshlrev_b32_e32 v3, 2, v9
	v_and_b32_e32 v3, 32, v3
	v_bitop3_b32 v183, v1, v2, v3 bitop3:0xde
	v_lshlrev_b32_e32 v1, 14, v8
	s_waitcnt vmcnt(6)
	s_barrier
	s_load_dwordx2 s[10:11], s[0:1], 0x90
	v_and_b32_e32 v1, 0xffff8000, v1
	v_lshl_add_u32 v1, v10, 11, v1
	v_and_b32_e32 v2, 1, v8
	v_lshl_or_b32 v1, v2, 6, v1
	v_lshl_add_u32 v166, v11, 1, v1
	v_lshlrev_b32_e32 v1, 14, v12
	v_and_b32_e32 v1, 0xffff8000, v1
	s_waitcnt lgkmcnt(0)
	s_ashr_i32 s83, s10, 31
	s_mov_b32 s14, s10
	s_mul_i32 s10, s3, 0x210
	v_lshl_add_u32 v1, v13, 11, v1
	v_and_b32_e32 v2, 1, v12
	s_add_i32 s76, s10, 0
	v_lshl_or_b32 v1, v2, 6, v1
	s_add_i32 s90, 0, 0x10000
	s_add_i32 s84, 0, 0x14000
	v_ashrrev_i32_e32 v182, 4, v9
	s_bfe_u32 s92, s93, 0x10006
	s_ashr_i32 s15, s21, 31
	s_add_i32 s76, s76, 0x20400
	v_mov_b32_e32 v167, v164
	v_lshl_add_u32 v168, v14, 1, v1
	v_mov_b32_e32 v169, v164
	v_mov_b64_e32 v[170:171], 0x300
	v_mov_b64_e32 v[172:173], 0x2ff
	v_add_u32_e32 v184, s90, v183
	v_add_u32_e32 v185, s84, v183
	v_add_u32_e32 v186, 0, v0
	v_mov_b32_e32 v187, 0x358637bd
	v_mov_b32_e32 v188, 0x3e38aa3b
	s_branch .LBB0_1545

; #define PG8_STAGE(bufoff, gbase, voff) do { _Pragma("unroll") for (int _i = 0; _i < 2; ++_i) \
;         __builtin_amdgcn_global_load_lds((const unsigned*)((const char*)(gbase) + (voff)[_i]), (PG8_LAS unsigned*)(lds + (bufoff) + ldsw + _i * 8192), 16, 0, 0); } while (0)
; #define PG8_LDA(dst, b, h) do { _Pragma("unroll") for (int m = 0; m < 4; ++m) _Pragma("unroll") for (int k = 0; k < 2; ++k) dst[m][k] = *(const PG8_LAS bf16x8*)(lds + PG8_SA(b, h) + aoff + m * 2048 + k * 1024); } while (0)
; #define PG8_LDB(dst, b, h) do { _Pragma("unroll") for (int n = 0; n < 2; ++n) _Pragma("unroll") for (int k = 0; k < 2; ++k) dst[n][k] = *(const PG8_LAS bf16x8*)(lds + PG8_SB(b, h) + boff + n * 2048 + k * 1024); } while (0)
; #define PG8_MMA(ai, bj, At, Bt) do { __builtin_amdgcn_s_setprio(1); _Pragma("unroll") for (int m = 0; m < 4; ++m) _Pragma("unroll") for (int n = 0; n < 2; ++n) _Pragma("unroll") for (int k = 0; k < 2; ++k) \
;         acc[ai][bj][m][n] = mma16<F16>(Bt[n][k], At[m][k], acc[ai][bj][m][n]); __builtin_amdgcn_s_setprio(0); } while (0)
; #define PG8_WAIT_V(n) asm volatile("s_waitcnt vmcnt(" #n ")" ::: "memory")
; #define PG8_WAIT_L(n) asm volatile("s_waitcnt lgkmcnt(" #n ")" ::: "memory")
; template <class Epi, class Sched, bool ALIGN_EPI = false, bool SP2 = false, bool F16 = false>
; __device__ __forceinline__ void gemm_phase(PG8_LAS unsigned char* lds, const Gemm g, const Sched& S, const Epi& E, const int wid_in) {
;     ...
;         for (int t = 0; t < nt; t += 2) {
;             const bool last = (t == nt - 2);
;             const char* a1 = cA + (size_t)(t + 1) * kstep;
;             const char* a2 = last ? nA : cA + (size_t)(t + 2) * kstep; const char* b2 = last ? nB : cB + (size_t)(t + 2) * kstep;
;             const char* a3 = a2 + kstep; const char* b3 = b2 + kstep;
;             if (last && has_next) S.a_ready(nxt);
;     ...
;             PG8_LDB(B0, 0, 0); PG8_LDB(B1, 0, 1); PG8_SCHED; PG8_LDA(At, 0, 0); PG8_STAGE(PG8_SA(1, 1), a1 + hstep, voffA);
;             PG8_WAIT_V(8); PG8_WAIT_L(0); PG8_BAR; PG8_MMA(0, 0, At, B0); PG8_MMA(0, 1, At, B1); PG8_BAR; PG8_SCHED;
;             PG8_LDA(At, 0, 1); PG8_STAGE(PG8_SB(0, 0), b2, voffB); PG8_STAGE(PG8_SB(0, 1), b2 + hstep, voffB); PG8_STAGE(PG8_SA(0, 0), a2, voffA);
;             PG8_WAIT_V(8); PG8_WAIT_L(0); PG8_BAR; PG8_MMA(1, 0, At, B0); PG8_MMA(1, 1, At, B1); PG8_BAR; PG8_SCHED;
.LBB0_1548:
	ds_read_b128 v[128:131], v184
	ds_read_b128 v[132:135], v184 offset:1024
	ds_read_b128 v[136:139], v184 offset:2048
	ds_read_b128 v[140:143], v184 offset:3072
	ds_read_b128 v[144:147], v185
	ds_read_b128 v[148:151], v185 offset:1024
	ds_read_b128 v[152:155], v185 offset:2048
	ds_read_b128 v[174:177], v185 offset:3072
	s_add_u32 s45, s50, 0xfffc0080
	s_addc_u32 s52, s51, -1
	s_cmp_eq_u32 s43, 12
	s_cselect_b32 s55, s13, s52
	s_cselect_b32 s54, s31, s45
	s_cselect_b32 s53, s37, s42
	s_cselect_b32 s52, s40, s41
	s_add_i32 m0, s74, 0xc000
	ds_read_b128 v[190:193], v186
	ds_read_b128 v[194:197], v186 offset:1024
	ds_read_b128 v[198:201], v186 offset:2048
	ds_read_b128 v[202:205], v186 offset:3072
	ds_read_b128 v[206:209], v186 offset:4096
	ds_read_b128 v[210:213], v186 offset:5120
	ds_read_b128 v[214:217], v186 offset:6144
	ds_read_b128 v[218:221], v186 offset:7168
	global_load_lds_dwordx4 v166, s[50:51]
	s_add_i32 m0, s74, 0xe000
	s_nop 0
	global_load_lds_dwordx4 v168, s[50:51]
	s_waitcnt vmcnt(8)
	s_waitcnt lgkmcnt(0)
	s_barrier
	s_setprio 1
	s_waitcnt lgkmcnt(0)
	v_mfma_f32_16x16x32_f16 v[124:127], v[128:131], v[190:193], v[124:127]
	v_mfma_f32_16x16x32_f16 v[120:123], v[136:139], v[190:193], v[120:123]
	v_mfma_f32_16x16x32_f16 v[108:111], v[128:131], v[198:201], v[108:111]
	v_mfma_f32_16x16x32_f16 v[104:107], v[136:139], v[198:201], v[104:107]
	v_mfma_f32_16x16x32_f16 v[92:95], v[128:131], v[206:209], v[92:95]
	v_mfma_f32_16x16x32_f16 v[88:91], v[136:139], v[206:209], v[88:91]
	v_mfma_f32_16x16x32_f16 v[76:79], v[128:131], v[214:217], v[76:79]
	v_mfma_f32_16x16x32_f16 v[72:75], v[136:139], v[214:217], v[72:75]
	v_mfma_f32_16x16x32_f16 v[124:127], v[132:135], v[194:197], v[124:127]
	v_mfma_f32_16x16x32_f16 v[120:123], v[140:143], v[194:197], v[120:123]
	v_mfma_f32_16x16x32_f16 v[108:111], v[132:135], v[202:205], v[108:111]
	v_mfma_f32_16x16x32_f16 v[104:107], v[140:143], v[202:205], v[104:107]
	v_mfma_f32_16x16x32_f16 v[92:95], v[132:135], v[210:213], v[92:95]
	v_mfma_f32_16x16x32_f16 v[88:91], v[140:143], v[210:213], v[88:91]
	v_mfma_f32_16x16x32_f16 v[76:79], v[132:135], v[218:221], v[76:79]
	v_mfma_f32_16x16x32_f16 v[72:75], v[140:143], v[218:221], v[72:75]
	s_setprio 0
	s_setprio 1
	v_mfma_f32_16x16x32_f16 v[116:119], v[144:147], v[190:193], v[116:119]
	v_mfma_f32_16x16x32_f16 v[112:115], v[152:155], v[190:193], v[112:115]
	v_mfma_f32_16x16x32_f16 v[100:103], v[144:147], v[198:201], v[100:103]
	v_mfma_f32_16x16x32_f16 v[96:99], v[152:155], v[198:201], v[96:99]
	v_mfma_f32_16x16x32_f16 v[84:87], v[144:147], v[206:209], v[84:87]
	v_mfma_f32_16x16x32_f16 v[80:83], v[152:155], v[206:209], v[80:83]
	v_mfma_f32_16x16x32_f16 v[68:71], v[144:147], v[214:217], v[68:71]
	v_mfma_f32_16x16x32_f16 v[64:67], v[152:155], v[214:217], v[64:67]
	v_mfma_f32_16x16x32_f16 v[116:119], v[148:151], v[194:197], v[116:119]
	v_mfma_f32_16x16x32_f16 v[112:115], v[174:177], v[194:197], v[112:115]
	v_mfma_f32_16x16x32_f16 v[100:103], v[148:151], v[202:205], v[100:103]
	v_mfma_f32_16x16x32_f16 v[96:99], v[174:177], v[202:205], v[96:99]
	v_mfma_f32_16x16x32_f16 v[84:87], v[148:151], v[210:213], v[84:87]
	v_mfma_f32_16x16x32_f16 v[80:83], v[174:177], v[210:213], v[80:83]
	v_mfma_f32_16x16x32_f16 v[68:71], v[148:151], v[218:221], v[68:71]
	v_mfma_f32_16x16x32_f16 v[64:67], v[174:177], v[218:221], v[64:67]
	s_setprio 0
	s_barrier
	s_add_i32 s45, s90, s68
	v_lshl_add_u64 v[178:179], s[52:53], 0, v[158:159]
	s_mov_b32 m0, s45
	ds_read_b128 v[190:193], v186 offset:16384
	ds_read_b128 v[194:197], v186 offset:17408
	ds_read_b128 v[198:201], v186 offset:18432
	ds_read_b128 v[202:205], v186 offset:19456
	ds_read_b128 v[206:209], v186 offset:20480
	ds_read_b128 v[210:213], v186 offset:21504
	ds_read_b128 v[214:217], v186 offset:22528
	ds_read_b128 v[218:221], v186 offset:23552
	global_load_lds_dwordx4 v[178:179], off
	s_add_i32 m0, s45, 0x2000
	s_add_u32 s56, s52, 0x40000
	v_lshl_add_u64 v[222:223], s[52:53], 0, v[162:163]
	s_addc_u32 s57, s53, 0
	s_add_i32 s45, s84, s68
	global_load_lds_dwordx4 v[222:223], off
	s_mov_b32 m0, s45
	v_lshl_add_u64 v[226:227], s[54:55], 0, v[160:161]
	global_load_lds_dwordx4 v158, s[56:57]
	s_add_i32 m0, s45, 0x2000
	s_nop 0
	global_load_lds_dwordx4 v162, s[56:57]
	v_lshl_add_u64 v[224:225], s[54:55], 0, v[156:157]
	s_mov_b32 m0, s74
	s_nop 0
	global_load_lds_dwordx4 v[224:225], off
	s_mov_b32 m0, s66
	s_nop 0
	global_load_lds_dwordx4 v[226:227], off
	s_waitcnt vmcnt(8)
	s_waitcnt lgkmcnt(0)
	s_barrier
	s_setprio 1
	s_waitcnt lgkmcnt(0)
	v_mfma_f32_16x16x32_f16 v[60:63], v[128:131], v[190:193], v[60:63]
	v_mfma_f32_16x16x32_f16 v[56:59], v[136:139], v[190:193], v[56:59]
	v_mfma_f32_16x16x32_f16 v[44:47], v[128:131], v[198:201], v[44:47]
	v_mfma_f32_16x16x32_f16 v[40:43], v[136:139], v[198:201], v[40:43]
	v_mfma_f32_16x16x32_f16 v[28:31], v[128:131], v[206:209], v[28:31]
	v_mfma_f32_16x16x32_f16 v[24:27], v[136:139], v[206:209], v[24:27]
	v_mfma_f32_16x16x32_f16 v[12:15], v[128:131], v[214:217], v[12:15]
	v_mfma_f32_16x16x32_f16 v[8:11], v[136:139], v[214:217], v[8:11]
	v_mfma_f32_16x16x32_f16 v[60:63], v[132:135], v[194:197], v[60:63]
	v_mfma_f32_16x16x32_f16 v[56:59], v[140:143], v[194:197], v[56:59]
	v_mfma_f32_16x16x32_f16 v[44:47], v[132:135], v[202:205], v[44:47]
	v_mfma_f32_16x16x32_f16 v[40:43], v[140:143], v[202:205], v[40:43]
	v_mfma_f32_16x16x32_f16 v[28:31], v[132:135], v[210:213], v[28:31]
	v_mfma_f32_16x16x32_f16 v[24:27], v[140:143], v[210:213], v[24:27]
	v_mfma_f32_16x16x32_f16 v[12:15], v[132:135], v[218:221], v[12:15]
	v_mfma_f32_16x16x32_f16 v[8:11], v[140:143], v[218:221], v[8:11]
	s_setprio 0
	s_setprio 1
	v_mfma_f32_16x16x32_f16 v[52:55], v[144:147], v[190:193], v[52:55]
	v_mfma_f32_16x16x32_f16 v[48:51], v[152:155], v[190:193], v[48:51]
	v_mfma_f32_16x16x32_f16 v[36:39], v[144:147], v[198:201], v[36:39]
	v_mfma_f32_16x16x32_f16 v[32:35], v[152:155], v[198:201], v[32:35]
	v_mfma_f32_16x16x32_f16 v[20:23], v[144:147], v[206:209], v[20:23]
	v_mfma_f32_16x16x32_f16 v[16:19], v[152:155], v[206:209], v[16:19]
	v_mfma_f32_16x16x32_f16 v[4:7], v[144:147], v[214:217], v[4:7]
	v_mfma_f32_16x16x32_f16 v[0:3], v[152:155], v[214:217], v[0:3]
	v_mfma_f32_16x16x32_f16 v[52:55], v[148:151], v[194:197], v[52:55]
	v_mfma_f32_16x16x32_f16 v[48:51], v[174:177], v[194:197], v[48:51]
	v_mfma_f32_16x16x32_f16 v[36:39], v[148:151], v[202:205], v[36:39]
	v_mfma_f32_16x16x32_f16 v[32:35], v[174:177], v[202:205], v[32:35]
	v_mfma_f32_16x16x32_f16 v[20:23], v[148:151], v[210:213], v[20:23]
	v_mfma_f32_16x16x32_f16 v[16:19], v[174:177], v[210:213], v[16:19]
	v_mfma_f32_16x16x32_f16 v[4:7], v[148:151], v[218:221], v[4:7]
	v_mfma_f32_16x16x32_f16 v[0:3], v[174:177], v[218:221], v[0:3]
	s_setprio 0
	s_barrier
; #define PG8_STAGE(bufoff, gbase, voff) do { _Pragma("unroll") for (int _i = 0; _i < 2; ++_i) \
;         __builtin_amdgcn_global_load_lds((const unsigned*)((const char*)(gbase) + (voff)[_i]), (PG8_LAS unsigned*)(lds + (bufoff) + ldsw + _i * 8192), 16, 0, 0); } while (0)
; #define PG8_LDA(dst, b, h) do { _Pragma("unroll") for (int m = 0; m < 4; ++m) _Pragma("unroll") for (int k = 0; k < 2; ++k) dst[m][k] = *(const PG8_LAS bf16x8*)(lds + PG8_SA(b, h) + aoff + m * 2048 + k * 1024); } while (0)
; #define PG8_LDB(dst, b, h) do { _Pragma("unroll") for (int n = 0; n < 2; ++n) _Pragma("unroll") for (int k = 0; k < 2; ++k) dst[n][k] = *(const PG8_LAS bf16x8*)(lds + PG8_SB(b, h) + boff + n * 2048 + k * 1024); } while (0)
; #define PG8_MMA(ai, bj, At, Bt) do { __builtin_amdgcn_s_setprio(1); _Pragma("unroll") for (int m = 0; m < 4; ++m) _Pragma("unroll") for (int n = 0; n < 2; ++n) _Pragma("unroll") for (int k = 0; k < 2; ++k) \
;         acc[ai][bj][m][n] = mma16<F16>(Bt[n][k], At[m][k], acc[ai][bj][m][n]); __builtin_amdgcn_s_setprio(0); } while (0)
; #define PG8_WAIT_V(n) asm volatile("s_waitcnt vmcnt(" #n ")" ::: "memory")
; #define PG8_WAIT_L(n) asm volatile("s_waitcnt lgkmcnt(" #n ")" ::: "memory")
; #define PG8_BAR __builtin_amdgcn_s_barrier()
; #define PG8_SCHED __builtin_amdgcn_sched_barrier(0)
; template <class Epi, class Sched, bool ALIGN_EPI = false, bool SP2 = false, bool F16 = false>
; __device__ __forceinline__ void gemm_phase(PG8_LAS unsigned char* lds, const Gemm g, const Sched& S, const Epi& E, const int wid_in) {
;     ...
;             PG8_LDB(B0, 1, 0); PG8_LDB(B1, 1, 1); PG8_SCHED; PG8_LDA(At, 1, 0); PG8_STAGE(PG8_SA(0, 1), a2 + hstep, voffA);
;             PG8_WAIT_V(8); PG8_WAIT_L(0); PG8_BAR; PG8_MMA(0, 0, At, B0); PG8_MMA(0, 1, At, B1); PG8_BAR; PG8_SCHED;
;             PG8_LDA(At, 1, 1); PG8_STAGE(PG8_SB(1, 0), b3, voffB); PG8_STAGE(PG8_SB(1, 1), b3 + hstep, voffB); PG8_STAGE(PG8_SA(1, 0), a3, voffA);
;             PG8_WAIT_V(8); PG8_WAIT_L(0); PG8_BAR; PG8_MMA(1, 0, At, B0); PG8_MMA(1, 1, At, B1); PG8_BAR; PG8_SCHED;
	s_add_i32 s45, 0, 0x18000
	s_add_i32 s56, 0, 0x1c000
	v_add_u32_e32 v140, s45, v183
	v_add_u32_e32 v165, s56, v183
	ds_read_b128 v[128:131], v140
	ds_read_b128 v[132:135], v140 offset:1024
	ds_read_b128 v[136:139], v140 offset:2048
	ds_read_b128 v[140:143], v140 offset:3072
	ds_read_b128 v[144:147], v165
	ds_read_b128 v[148:151], v165 offset:1024
	ds_read_b128 v[152:155], v165 offset:2048
	ds_read_b128 v[174:177], v165 offset:3072
	s_add_u32 s54, s54, 0x40000
	s_addc_u32 s55, s55, 0
	s_mov_b32 m0, s67
	ds_read_b128 v[190:193], v186 offset:32768
	ds_read_b128 v[194:197], v186 offset:33792
	ds_read_b128 v[198:201], v186 offset:34816
	ds_read_b128 v[202:205], v186 offset:35840
	ds_read_b128 v[206:209], v186 offset:36864
	ds_read_b128 v[210:213], v186 offset:37888
	ds_read_b128 v[214:217], v186 offset:38912
	ds_read_b128 v[218:221], v186 offset:39936
	global_load_lds_dwordx4 v156, s[54:55]
	v_lshl_add_u64 v[228:229], s[54:55], 0, v[160:161]
	s_mov_b32 m0, s91
	s_nop 0
	global_load_lds_dwordx4 v[228:229], off
	s_waitcnt vmcnt(8)
	s_waitcnt lgkmcnt(0)
	s_barrier
	s_setprio 1
	s_waitcnt lgkmcnt(0)
	v_mfma_f32_16x16x32_f16 v[124:127], v[128:131], v[190:193], v[124:127]
	v_mfma_f32_16x16x32_f16 v[120:123], v[136:139], v[190:193], v[120:123]
	v_mfma_f32_16x16x32_f16 v[108:111], v[128:131], v[198:201], v[108:111]
	v_mfma_f32_16x16x32_f16 v[104:107], v[136:139], v[198:201], v[104:107]
	v_mfma_f32_16x16x32_f16 v[92:95], v[128:131], v[206:209], v[92:95]
	v_mfma_f32_16x16x32_f16 v[88:91], v[136:139], v[206:209], v[88:91]
	v_mfma_f32_16x16x32_f16 v[76:79], v[128:131], v[214:217], v[76:79]
	v_mfma_f32_16x16x32_f16 v[72:75], v[136:139], v[214:217], v[72:75]
	v_mfma_f32_16x16x32_f16 v[124:127], v[132:135], v[194:197], v[124:127]
	v_mfma_f32_16x16x32_f16 v[120:123], v[140:143], v[194:197], v[120:123]
	v_mfma_f32_16x16x32_f16 v[108:111], v[132:135], v[202:205], v[108:111]
	v_mfma_f32_16x16x32_f16 v[104:107], v[140:143], v[202:205], v[104:107]
	v_mfma_f32_16x16x32_f16 v[92:95], v[132:135], v[210:213], v[92:95]
	v_mfma_f32_16x16x32_f16 v[88:91], v[140:143], v[210:213], v[88:91]
	v_mfma_f32_16x16x32_f16 v[76:79], v[132:135], v[218:221], v[76:79]
	v_mfma_f32_16x16x32_f16 v[72:75], v[140:143], v[218:221], v[72:75]
	s_setprio 0
	s_setprio 1
	v_mfma_f32_16x16x32_f16 v[116:119], v[144:147], v[190:193], v[116:119]
	v_mfma_f32_16x16x32_f16 v[112:115], v[152:155], v[190:193], v[112:115]
	v_mfma_f32_16x16x32_f16 v[100:103], v[144:147], v[198:201], v[100:103]
	v_mfma_f32_16x16x32_f16 v[96:99], v[152:155], v[198:201], v[96:99]
	v_mfma_f32_16x16x32_f16 v[84:87], v[144:147], v[206:209], v[84:87]
	v_mfma_f32_16x16x32_f16 v[80:83], v[152:155], v[206:209], v[80:83]
	v_mfma_f32_16x16x32_f16 v[68:71], v[144:147], v[214:217], v[68:71]
	v_mfma_f32_16x16x32_f16 v[64:67], v[152:155], v[214:217], v[64:67]
	v_mfma_f32_16x16x32_f16 v[116:119], v[148:151], v[194:197], v[116:119]
	v_mfma_f32_16x16x32_f16 v[112:115], v[174:177], v[194:197], v[112:115]
	v_mfma_f32_16x16x32_f16 v[100:103], v[148:151], v[202:205], v[100:103]
	v_mfma_f32_16x16x32_f16 v[96:99], v[174:177], v[202:205], v[96:99]
	v_mfma_f32_16x16x32_f16 v[84:87], v[148:151], v[210:213], v[84:87]
	v_mfma_f32_16x16x32_f16 v[80:83], v[174:177], v[210:213], v[80:83]
	v_mfma_f32_16x16x32_f16 v[68:71], v[148:151], v[218:221], v[68:71]
	v_mfma_f32_16x16x32_f16 v[64:67], v[174:177], v[218:221], v[64:67]
	s_setprio 0
	s_barrier
	s_add_i32 s45, s45, s68
	v_lshl_add_u64 v[178:179], v[178:179], 0, s[34:35]
	s_mov_b32 m0, s45
	ds_read_b128 v[190:193], v186 offset:49152
	ds_read_b128 v[194:197], v186 offset:50176
	ds_read_b128 v[198:201], v186 offset:51200
	ds_read_b128 v[202:205], v186 offset:52224
	ds_read_b128 v[206:209], v186 offset:53248
	ds_read_b128 v[210:213], v186 offset:54272
	ds_read_b128 v[214:217], v186 offset:55296
	ds_read_b128 v[218:221], v186 offset:56320
	global_load_lds_dwordx4 v[178:179], off
	s_add_i32 m0, s45, 0x2000
	s_add_u32 s52, s52, 0x40080
	v_lshl_add_u64 v[178:179], v[222:223], 0, s[34:35]
	s_addc_u32 s53, s53, 0
	s_add_i32 s45, s56, s68
	global_load_lds_dwordx4 v[178:179], off
	s_mov_b32 m0, s45
	s_nop 0
	global_load_lds_dwordx4 v158, s[52:53]
	s_add_i32 m0, s45, 0x2000
	s_nop 0
	global_load_lds_dwordx4 v162, s[52:53]
	v_lshl_add_u64 v[178:179], v[224:225], 0, s[34:35]
	s_mov_b32 m0, s75
	s_nop 0
	global_load_lds_dwordx4 v[178:179], off
	v_lshl_add_u64 v[178:179], v[226:227], 0, s[34:35]
	s_mov_b32 m0, s97
	s_nop 0
	global_load_lds_dwordx4 v[178:179], off
	s_waitcnt vmcnt(8)
	s_waitcnt lgkmcnt(0)
	s_barrier
	s_setprio 1
	s_waitcnt lgkmcnt(0)
	v_mfma_f32_16x16x32_f16 v[60:63], v[128:131], v[190:193], v[60:63]
	v_mfma_f32_16x16x32_f16 v[56:59], v[136:139], v[190:193], v[56:59]
	v_mfma_f32_16x16x32_f16 v[44:47], v[128:131], v[198:201], v[44:47]
	v_mfma_f32_16x16x32_f16 v[40:43], v[136:139], v[198:201], v[40:43]
	v_mfma_f32_16x16x32_f16 v[28:31], v[128:131], v[206:209], v[28:31]
	v_mfma_f32_16x16x32_f16 v[24:27], v[136:139], v[206:209], v[24:27]
	v_mfma_f32_16x16x32_f16 v[12:15], v[128:131], v[214:217], v[12:15]
	v_mfma_f32_16x16x32_f16 v[8:11], v[136:139], v[214:217], v[8:11]
	v_mfma_f32_16x16x32_f16 v[60:63], v[132:135], v[194:197], v[60:63]
	v_mfma_f32_16x16x32_f16 v[56:59], v[140:143], v[194:197], v[56:59]
	v_mfma_f32_16x16x32_f16 v[44:47], v[132:135], v[202:205], v[44:47]
	v_mfma_f32_16x16x32_f16 v[40:43], v[140:143], v[202:205], v[40:43]
	v_mfma_f32_16x16x32_f16 v[28:31], v[132:135], v[210:213], v[28:31]
	v_mfma_f32_16x16x32_f16 v[24:27], v[140:143], v[210:213], v[24:27]
	v_mfma_f32_16x16x32_f16 v[12:15], v[132:135], v[218:221], v[12:15]
	v_mfma_f32_16x16x32_f16 v[8:11], v[140:143], v[218:221], v[8:11]
	s_setprio 0
	s_setprio 1
	v_mfma_f32_16x16x32_f16 v[52:55], v[144:147], v[190:193], v[52:55]
	v_mfma_f32_16x16x32_f16 v[48:51], v[152:155], v[190:193], v[48:51]
	v_mfma_f32_16x16x32_f16 v[36:39], v[144:147], v[198:201], v[36:39]
	v_mfma_f32_16x16x32_f16 v[32:35], v[152:155], v[198:201], v[32:35]
	v_mfma_f32_16x16x32_f16 v[20:23], v[144:147], v[206:209], v[20:23]
	v_mfma_f32_16x16x32_f16 v[16:19], v[152:155], v[206:209], v[16:19]
	v_mfma_f32_16x16x32_f16 v[4:7], v[144:147], v[214:217], v[4:7]
	v_mfma_f32_16x16x32_f16 v[0:3], v[152:155], v[214:217], v[0:3]
	v_mfma_f32_16x16x32_f16 v[52:55], v[148:151], v[194:197], v[52:55]
	v_mfma_f32_16x16x32_f16 v[48:51], v[174:177], v[194:197], v[48:51]
	v_mfma_f32_16x16x32_f16 v[36:39], v[148:151], v[202:205], v[36:39]
	v_mfma_f32_16x16x32_f16 v[32:35], v[174:177], v[202:205], v[32:35]
	v_mfma_f32_16x16x32_f16 v[20:23], v[148:151], v[210:213], v[20:23]
	v_mfma_f32_16x16x32_f16 v[16:19], v[174:177], v[210:213], v[16:19]
	v_mfma_f32_16x16x32_f16 v[4:7], v[148:151], v[218:221], v[4:7]
	v_mfma_f32_16x16x32_f16 v[0:3], v[174:177], v[218:221], v[0:3]
	s_setprio 0
	s_barrier
	s_add_i32 s43, s43, 2
	s_add_u32 s50, s50, 0x100
	s_addc_u32 s51, s51, 0
	s_add_u32 s41, s41, 0x100
	s_addc_u32 s42, s42, 0
	s_cmp_gt_u32 s43, 13
	s_cbranch_scc0 .LBB0_1548
	s_and_b64 vcc, exec, s[16:17]
	s_cbranch_vccz .LBB0_1551
	s_barrier

; #define PG8_STAGE(bufoff, gbase, voff) do { _Pragma("unroll") for (int _i = 0; _i < 2; ++_i) \
;         __builtin_amdgcn_global_load_lds((const unsigned*)((const char*)(gbase) + (voff)[_i]), (PG8_LAS unsigned*)(lds + (bufoff) + ldsw + _i * 8192), 16, 0, 0); } while (0)
; #define PG8_WAIT_V(n) asm volatile("s_waitcnt vmcnt(" #n ")" ::: "memory")
; #define PG8_BAR __builtin_amdgcn_s_barrier()
; template <class Epi, class Sched, bool ALIGN_EPI = false, bool SP2 = false, bool F16 = false>
; __device__ __forceinline__ void gemm_phase(PG8_LAS unsigned char* lds, const Gemm g, const Sched& S, const Epi& E, const int wid_in) {
;     ...
;     for (int i = 0; i < 2; ++i) { int R, C; stage_rc(tid * 16 + i * 8192, R, C); const int Rb = Epi::PERM ? ((R & ~31) + perm32(R & 31)) : R;
;         voffA[i] = (unsigned)(R * K + C) * 2u; voffB[i] = (unsigned)(Rb * K + C) * 2u; }
;     const size_t kstep = (size_t)(BK * 2);
;     const size_t hstep = (size_t)HALF * K * 2;
;     const size_t tstep = 2 * hstep;
;     const unsigned ldsw = (unsigned)wid * 1024u;
;     const int aoff = lds_byte(wr * 64 + fr, fq * 8), boff = lds_byte(wc * 32 + fr, fq * 8);
;     ...
;         PG8_STAGE(PG8_SB(1, 0), cB + kstep, voffB); PG8_STAGE(PG8_SA(1, 0), cA + kstep, voffA); PG8_STAGE(PG8_SB(1, 1), cB + hstep + kstep, voffB);
;         PG8_WAIT_V(6); PG8_BAR;
.LBB0_1822:
	s_add_u32 s22, s10, 0x7400000
	s_addc_u32 s23, s11, 0
	s_add_u32 s24, s10, 0x13400000
	s_addc_u32 s25, s11, 0
	s_add_u32 s26, s10, 0x15700000
	s_mov_b64 s[28:29], 0x80
	s_addc_u32 s27, s11, 0
	s_add_i32 m0, s74, 0x18000
	v_lshl_add_u64 v[6:7], v[6:7], 0, s[28:29]
	s_waitcnt vmcnt(2)
	s_barrier
	global_load_lds_dwordx4 v[6:7], off
	v_lshl_add_u64 v[4:5], v[4:5], 0, s[28:29]
	s_add_i32 m0, s74, 0x1a000
	v_lshl_add_u64 v[0:1], v[0:1], 0, s[28:29]
	global_load_lds_dwordx4 v[4:5], off
	s_mov_b32 m0, s75
	s_add_u32 s10, s50, 0x40080
	global_load_lds_dwordx4 v[0:1], off
	v_lshl_add_u64 v[0:1], v[2:3], 0, s[28:29]
	s_mov_b32 m0, s67
	s_addc_u32 s11, s51, 0
	global_load_lds_dwordx4 v[0:1], off
	s_add_i32 m0, s74, 0x1c000
	s_nop 0
	global_load_lds_dwordx4 v154, s[10:11]
	s_add_i32 m0, s74, 0x1e000
	v_and_b32_e32 v187, 15, v8
	global_load_lds_dwordx4 v158, s[10:11]
	v_or_b32_e32 v0, s70, v187
	v_lshlrev_b32_e32 v1, 6, v0
	v_and_b32_e32 v2, 48, v8
	s_movk_i32 s10, 0x3c0
	v_and_b32_e32 v3, 0xfffffc00, v12
	v_lshlrev_b32_e32 v0, 2, v0
	v_and_or_b32 v1, v1, s10, v2
	v_add_u32_e32 v4, s73, v3
	v_and_b32_e32 v0, 32, v0
	v_bitop3_b32 v0, v1, v4, v0 bitop3:0xde
	v_lshl_or_b32 v1, v187, 6, v2
	v_add_u32_e32 v2, s72, v3
	v_lshlrev_b32_e32 v3, 2, v8
	v_and_b32_e32 v3, 32, v3
	v_bitop3_b32 v188, v1, v2, v3 bitop3:0xde
	v_lshlrev_b32_e32 v1, 14, v9
	v_and_b32_e32 v1, 0xffff8000, v1
	v_lshl_add_u32 v1, v10, 11, v1
	v_and_b32_e32 v2, 1, v9
	v_lshl_or_b32 v1, v2, 6, v1
	v_lshl_add_u32 v160, v11, 1, v1
	v_lshlrev_b32_e32 v1, 14, v13
	v_and_b32_e32 v1, 0xffff8000, v1
	s_waitcnt vmcnt(6)
	v_lshl_add_u32 v1, v14, 11, v1
	v_and_b32_e32 v2, 1, v13
	v_lshl_or_b32 v1, v2, 6, v1
	s_add_i32 s57, 0, 0x10000
	s_add_i32 s58, 0, 0x14000
	v_ashrrev_i32_e32 v186, 4, v8
	s_ashr_i32 s54, s38, 31
	s_mov_b32 s55, s38
	s_ashr_i32 s56, s14, 31
	v_mov_b32_e32 v161, v155
	v_lshl_add_u32 v162, v15, 1, v1
	v_mov_b32_e32 v163, v155
	v_mov_b64_e32 v[164:165], 0x100
	v_mov_b64_e32 v[166:167], 0xff
	v_add_u32_e32 v189, s57, v188
	v_add_u32_e32 v190, s58, v188
	v_add_u32_e32 v191, 0, v0
	s_mov_b32 s59, 0
	s_barrier
	s_branch .LBB0_1825

; #define PG8_STAGE(bufoff, gbase, voff) do { _Pragma("unroll") for (int _i = 0; _i < 2; ++_i) \
;         __builtin_amdgcn_global_load_lds((const unsigned*)((const char*)(gbase) + (voff)[_i]), (PG8_LAS unsigned*)(lds + (bufoff) + ldsw + _i * 8192), 16, 0, 0); } while (0)
; #define PG8_LDA(dst, b, h) do { _Pragma("unroll") for (int m = 0; m < 4; ++m) _Pragma("unroll") for (int k = 0; k < 2; ++k) dst[m][k] = *(const PG8_LAS bf16x8*)(lds + PG8_SA(b, h) + aoff + m * 2048 + k * 1024); } while (0)
; #define PG8_LDB(dst, b, h) do { _Pragma("unroll") for (int n = 0; n < 2; ++n) _Pragma("unroll") for (int k = 0; k < 2; ++k) dst[n][k] = *(const PG8_LAS bf16x8*)(lds + PG8_SB(b, h) + boff + n * 2048 + k * 1024); } while (0)
; #define PG8_MMA(ai, bj, At, Bt) do { __builtin_amdgcn_s_setprio(1); _Pragma("unroll") for (int m = 0; m < 4; ++m) _Pragma("unroll") for (int n = 0; n < 2; ++n) _Pragma("unroll") for (int k = 0; k < 2; ++k) \
;         acc[ai][bj][m][n] = mma16<F16>(Bt[n][k], At[m][k], acc[ai][bj][m][n]); __builtin_amdgcn_s_setprio(0); } while (0)
; #define PG8_WAIT_V(n) asm volatile("s_waitcnt vmcnt(" #n ")" ::: "memory")
; #define PG8_WAIT_L(n) asm volatile("s_waitcnt lgkmcnt(" #n ")" ::: "memory")
; #define PG8_BAR __builtin_amdgcn_s_barrier()
; #define PG8_SCHED __builtin_amdgcn_sched_barrier(0)
; template <class Epi, class Sched, bool ALIGN_EPI = false, bool SP2 = false, bool F16 = false>
; __device__ __forceinline__ void gemm_phase(PG8_LAS unsigned char* lds, const Gemm g, const Sched& S, const Epi& E, const int wid_in) {
;     ...
;             PG8_LDB(B0, 0, 0); PG8_LDB(B1, 0, 1); PG8_SCHED; PG8_LDA(At, 0, 0); PG8_STAGE(PG8_SA(1, 1), a1 + hstep, voffA);
;             PG8_WAIT_V(8); PG8_WAIT_L(0); PG8_BAR; PG8_MMA(0, 0, At, B0); PG8_MMA(0, 1, At, B1); PG8_BAR; PG8_SCHED;
;             PG8_LDA(At, 0, 1); PG8_STAGE(PG8_SB(0, 0), b2, voffB); PG8_STAGE(PG8_SB(0, 1), b2 + hstep, voffB); PG8_STAGE(PG8_SA(0, 0), a2, voffA);
;             PG8_WAIT_V(8); PG8_WAIT_L(0); PG8_BAR; PG8_MMA(1, 0, At, B0); PG8_MMA(1, 1, At, B1); PG8_BAR; PG8_SCHED;
.LBB0_1832:
	ds_read_b128 v[128:131], v189
	ds_read_b128 v[132:135], v189 offset:1024
	ds_read_b128 v[136:139], v189 offset:2048
	ds_read_b128 v[140:143], v189 offset:3072
	ds_read_b128 v[144:147], v190
	ds_read_b128 v[148:151], v190 offset:1024
	ds_read_b128 v[168:171], v190 offset:2048
	ds_read_b128 v[172:175], v190 offset:3072
	s_add_u32 s50, s48, 0xfffc0080
	s_addc_u32 s51, s49, -1
	s_cmp_eq_u32 s61, 12
	s_cselect_b32 s53, s35, s51
	s_cselect_b32 s52, s42, s50
	s_cselect_b32 s51, s31, s60
	s_cselect_b32 s50, s43, s47
	s_mov_b32 m0, s91
	ds_read_b128 v[176:179], v191
	ds_read_b128 v[180:183], v191 offset:1024
	ds_read_b128 v[192:195], v191 offset:2048
	ds_read_b128 v[196:199], v191 offset:3072
	ds_read_b128 v[200:203], v191 offset:4096
	ds_read_b128 v[204:207], v191 offset:5120
	ds_read_b128 v[208:211], v191 offset:6144
	ds_read_b128 v[212:215], v191 offset:7168
	global_load_lds_dwordx4 v160, s[48:49]
	s_add_i32 m0, s74, 0xe000
	s_nop 0
	global_load_lds_dwordx4 v162, s[48:49]
	s_waitcnt vmcnt(8)
	s_waitcnt lgkmcnt(0)
	s_barrier
	s_setprio 1
	s_waitcnt lgkmcnt(0)
	v_mfma_f32_16x16x32_bf16 v[124:127], v[128:131], v[176:179], v[124:127]
	v_mfma_f32_16x16x32_bf16 v[120:123], v[136:139], v[176:179], v[120:123]
	v_mfma_f32_16x16x32_bf16 v[108:111], v[128:131], v[192:195], v[108:111]
	v_mfma_f32_16x16x32_bf16 v[104:107], v[136:139], v[192:195], v[104:107]
	v_mfma_f32_16x16x32_bf16 v[92:95], v[128:131], v[200:203], v[92:95]
	v_mfma_f32_16x16x32_bf16 v[88:91], v[136:139], v[200:203], v[88:91]
	v_mfma_f32_16x16x32_bf16 v[76:79], v[128:131], v[208:211], v[76:79]
	v_mfma_f32_16x16x32_bf16 v[72:75], v[136:139], v[208:211], v[72:75]
	v_mfma_f32_16x16x32_bf16 v[124:127], v[132:135], v[180:183], v[124:127]
	v_mfma_f32_16x16x32_bf16 v[120:123], v[140:143], v[180:183], v[120:123]
	v_mfma_f32_16x16x32_bf16 v[108:111], v[132:135], v[196:199], v[108:111]
	v_mfma_f32_16x16x32_bf16 v[104:107], v[140:143], v[196:199], v[104:107]
	v_mfma_f32_16x16x32_bf16 v[92:95], v[132:135], v[204:207], v[92:95]
	v_mfma_f32_16x16x32_bf16 v[88:91], v[140:143], v[204:207], v[88:91]
	v_mfma_f32_16x16x32_bf16 v[76:79], v[132:135], v[212:215], v[76:79]
	v_mfma_f32_16x16x32_bf16 v[72:75], v[140:143], v[212:215], v[72:75]
	s_setprio 0
	s_setprio 1
	v_mfma_f32_16x16x32_bf16 v[116:119], v[144:147], v[176:179], v[116:119]
	v_mfma_f32_16x16x32_bf16 v[112:115], v[168:171], v[176:179], v[112:115]
	v_mfma_f32_16x16x32_bf16 v[100:103], v[144:147], v[192:195], v[100:103]
	v_mfma_f32_16x16x32_bf16 v[96:99], v[168:171], v[192:195], v[96:99]
	v_mfma_f32_16x16x32_bf16 v[84:87], v[144:147], v[200:203], v[84:87]
	v_mfma_f32_16x16x32_bf16 v[80:83], v[168:171], v[200:203], v[80:83]
	v_mfma_f32_16x16x32_bf16 v[68:71], v[144:147], v[208:211], v[68:71]
	v_mfma_f32_16x16x32_bf16 v[64:67], v[168:171], v[208:211], v[64:67]
	v_mfma_f32_16x16x32_bf16 v[116:119], v[148:151], v[180:183], v[116:119]
	v_mfma_f32_16x16x32_bf16 v[112:115], v[172:175], v[180:183], v[112:115]
	v_mfma_f32_16x16x32_bf16 v[100:103], v[148:151], v[196:199], v[100:103]
	v_mfma_f32_16x16x32_bf16 v[96:99], v[172:175], v[196:199], v[96:99]
	v_mfma_f32_16x16x32_bf16 v[84:87], v[148:151], v[204:207], v[84:87]
	v_mfma_f32_16x16x32_bf16 v[80:83], v[172:175], v[204:207], v[80:83]
	v_mfma_f32_16x16x32_bf16 v[68:71], v[148:151], v[212:215], v[68:71]
	v_mfma_f32_16x16x32_bf16 v[64:67], v[172:175], v[212:215], v[64:67]
	s_setprio 0
	s_barrier
	s_add_i32 s62, s57, s68
	v_lshl_add_u64 v[184:185], s[50:51], 0, v[154:155]
	s_mov_b32 m0, s62
	ds_read_b128 v[176:179], v191 offset:16384
	ds_read_b128 v[180:183], v191 offset:17408
	ds_read_b128 v[192:195], v191 offset:18432
	ds_read_b128 v[196:199], v191 offset:19456
	ds_read_b128 v[200:203], v191 offset:20480
	ds_read_b128 v[204:207], v191 offset:21504
	ds_read_b128 v[208:211], v191 offset:22528
	ds_read_b128 v[212:215], v191 offset:23552
	global_load_lds_dwordx4 v[184:185], off
	s_add_i32 m0, s62, 0x2000
	s_add_u32 s62, s50, 0x40000
	v_lshl_add_u64 v[216:217], s[50:51], 0, v[158:159]
	s_addc_u32 s63, s51, 0
	s_add_i32 s64, s58, s68
	global_load_lds_dwordx4 v[216:217], off
	s_mov_b32 m0, s64
	v_lshl_add_u64 v[220:221], s[52:53], 0, v[156:157]
	global_load_lds_dwordx4 v154, s[62:63]
	s_add_i32 m0, s64, 0x2000
	s_nop 0
	global_load_lds_dwordx4 v158, s[62:63]
	v_lshl_add_u64 v[218:219], s[52:53], 0, v[152:153]
	s_mov_b32 m0, s74
	s_nop 0
	global_load_lds_dwordx4 v[218:219], off
	s_mov_b32 m0, s66
	s_nop 0
	global_load_lds_dwordx4 v[220:221], off
	s_waitcnt vmcnt(8)
	s_waitcnt lgkmcnt(0)
	s_barrier
; #define PG8_STAGE(bufoff, gbase, voff) do { _Pragma("unroll") for (int _i = 0; _i < 2; ++_i) \
;         __builtin_amdgcn_global_load_lds((const unsigned*)((const char*)(gbase) + (voff)[_i]), (PG8_LAS unsigned*)(lds + (bufoff) + ldsw + _i * 8192), 16, 0, 0); } while (0)
; #define PG8_LDA(dst, b, h) do { _Pragma("unroll") for (int m = 0; m < 4; ++m) _Pragma("unroll") for (int k = 0; k < 2; ++k) dst[m][k] = *(const PG8_LAS bf16x8*)(lds + PG8_SA(b, h) + aoff + m * 2048 + k * 1024); } while (0)
; #define PG8_LDB(dst, b, h) do { _Pragma("unroll") for (int n = 0; n < 2; ++n) _Pragma("unroll") for (int k = 0; k < 2; ++k) dst[n][k] = *(const PG8_LAS bf16x8*)(lds + PG8_SB(b, h) + boff + n * 2048 + k * 1024); } while (0)
; #define PG8_MMA(ai, bj, At, Bt) do { __builtin_amdgcn_s_setprio(1); _Pragma("unroll") for (int m = 0; m < 4; ++m) _Pragma("unroll") for (int n = 0; n < 2; ++n) _Pragma("unroll") for (int k = 0; k < 2; ++k) \
;         acc[ai][bj][m][n] = mma16<F16>(Bt[n][k], At[m][k], acc[ai][bj][m][n]); __builtin_amdgcn_s_setprio(0); } while (0)
; #define PG8_WAIT_V(n) asm volatile("s_waitcnt vmcnt(" #n ")" ::: "memory")
; #define PG8_WAIT_L(n) asm volatile("s_waitcnt lgkmcnt(" #n ")" ::: "memory")
; #define PG8_BAR __builtin_amdgcn_s_barrier()
; #define PG8_SCHED __builtin_amdgcn_sched_barrier(0)
; template <class Epi, class Sched, bool ALIGN_EPI = false, bool SP2 = false, bool F16 = false>
; __device__ __forceinline__ void gemm_phase(PG8_LAS unsigned char* lds, const Gemm g, const Sched& S, const Epi& E, const int wid_in) {
;     ...
;             PG8_WAIT_V(8); PG8_WAIT_L(0); PG8_BAR; PG8_MMA(0, 0, At, B0); PG8_MMA(0, 1, At, B1); PG8_BAR; PG8_SCHED;
;             PG8_LDA(At, 0, 1); PG8_STAGE(PG8_SB(0, 0), b2, voffB); PG8_STAGE(PG8_SB(0, 1), b2 + hstep, voffB); PG8_STAGE(PG8_SA(0, 0), a2, voffA);
;             PG8_WAIT_V(8); PG8_WAIT_L(0); PG8_BAR; PG8_MMA(1, 0, At, B0); PG8_MMA(1, 1, At, B1); PG8_BAR; PG8_SCHED;
;             PG8_LDB(B0, 1, 0); PG8_LDB(B1, 1, 1); PG8_SCHED; PG8_LDA(At, 1, 0); PG8_STAGE(PG8_SA(0, 1), a2 + hstep, voffA);
;             PG8_WAIT_V(8); PG8_WAIT_L(0); PG8_BAR; PG8_MMA(0, 0, At, B0); PG8_MMA(0, 1, At, B1); PG8_BAR; PG8_SCHED;
	s_setprio 1
	s_waitcnt lgkmcnt(0)
	v_mfma_f32_16x16x32_bf16 v[60:63], v[128:131], v[176:179], v[60:63]
	v_mfma_f32_16x16x32_bf16 v[56:59], v[136:139], v[176:179], v[56:59]
	v_mfma_f32_16x16x32_bf16 v[44:47], v[128:131], v[192:195], v[44:47]
	v_mfma_f32_16x16x32_bf16 v[40:43], v[136:139], v[192:195], v[40:43]
	v_mfma_f32_16x16x32_bf16 v[28:31], v[128:131], v[200:203], v[28:31]
	v_mfma_f32_16x16x32_bf16 v[24:27], v[136:139], v[200:203], v[24:27]
	v_mfma_f32_16x16x32_bf16 v[12:15], v[128:131], v[208:211], v[12:15]
	v_mfma_f32_16x16x32_bf16 v[8:11], v[136:139], v[208:211], v[8:11]
	v_mfma_f32_16x16x32_bf16 v[60:63], v[132:135], v[180:183], v[60:63]
	v_mfma_f32_16x16x32_bf16 v[56:59], v[140:143], v[180:183], v[56:59]
	v_mfma_f32_16x16x32_bf16 v[44:47], v[132:135], v[196:199], v[44:47]
	v_mfma_f32_16x16x32_bf16 v[40:43], v[140:143], v[196:199], v[40:43]
	v_mfma_f32_16x16x32_bf16 v[28:31], v[132:135], v[204:207], v[28:31]
	v_mfma_f32_16x16x32_bf16 v[24:27], v[140:143], v[204:207], v[24:27]
	v_mfma_f32_16x16x32_bf16 v[12:15], v[132:135], v[212:215], v[12:15]
	v_mfma_f32_16x16x32_bf16 v[8:11], v[140:143], v[212:215], v[8:11]
	s_setprio 0
	s_setprio 1
	v_mfma_f32_16x16x32_bf16 v[52:55], v[144:147], v[176:179], v[52:55]
	v_mfma_f32_16x16x32_bf16 v[48:51], v[168:171], v[176:179], v[48:51]
	v_mfma_f32_16x16x32_bf16 v[36:39], v[144:147], v[192:195], v[36:39]
	v_mfma_f32_16x16x32_bf16 v[32:35], v[168:171], v[192:195], v[32:35]
	v_mfma_f32_16x16x32_bf16 v[20:23], v[144:147], v[200:203], v[20:23]
	v_mfma_f32_16x16x32_bf16 v[16:19], v[168:171], v[200:203], v[16:19]
	v_mfma_f32_16x16x32_bf16 v[4:7], v[144:147], v[208:211], v[4:7]
	v_mfma_f32_16x16x32_bf16 v[0:3], v[168:171], v[208:211], v[0:3]
	v_mfma_f32_16x16x32_bf16 v[52:55], v[148:151], v[180:183], v[52:55]
	v_mfma_f32_16x16x32_bf16 v[48:51], v[172:175], v[180:183], v[48:51]
	v_mfma_f32_16x16x32_bf16 v[36:39], v[148:151], v[196:199], v[36:39]
	v_mfma_f32_16x16x32_bf16 v[32:35], v[172:175], v[196:199], v[32:35]
	v_mfma_f32_16x16x32_bf16 v[20:23], v[148:151], v[204:207], v[20:23]
	v_mfma_f32_16x16x32_bf16 v[16:19], v[172:175], v[204:207], v[16:19]
	v_mfma_f32_16x16x32_bf16 v[4:7], v[148:151], v[212:215], v[4:7]
	v_mfma_f32_16x16x32_bf16 v[0:3], v[172:175], v[212:215], v[0:3]
	s_setprio 0
	s_barrier
	s_add_i32 s62, 0, 0x18000
	s_add_i32 s63, 0, 0x1c000
	v_add_u32_e32 v140, s62, v188
	v_add_u32_e32 v172, s63, v188
	ds_read_b128 v[128:131], v140
	ds_read_b128 v[132:135], v140 offset:1024
	ds_read_b128 v[136:139], v140 offset:2048
	ds_read_b128 v[140:143], v140 offset:3072
	ds_read_b128 v[144:147], v172
	ds_read_b128 v[148:151], v172 offset:1024
	ds_read_b128 v[168:171], v172 offset:2048
	ds_read_b128 v[172:175], v172 offset:3072
	s_add_u32 s52, s52, 0x40000
	s_addc_u32 s53, s53, 0
	s_mov_b32 m0, s90
	ds_read_b128 v[176:179], v191 offset:32768
	ds_read_b128 v[180:183], v191 offset:33792
	ds_read_b128 v[192:195], v191 offset:34816
	ds_read_b128 v[196:199], v191 offset:35840
	ds_read_b128 v[200:203], v191 offset:36864
	ds_read_b128 v[204:207], v191 offset:37888
	ds_read_b128 v[208:211], v191 offset:38912
	ds_read_b128 v[212:215], v191 offset:39936
	global_load_lds_dwordx4 v152, s[52:53]
	v_lshl_add_u64 v[222:223], s[52:53], 0, v[156:157]
	s_mov_b32 m0, s41
	s_nop 0
	global_load_lds_dwordx4 v[222:223], off
	s_waitcnt vmcnt(8)
	s_waitcnt lgkmcnt(0)
	s_barrier
	s_setprio 1
	s_waitcnt lgkmcnt(0)
	v_mfma_f32_16x16x32_bf16 v[124:127], v[128:131], v[176:179], v[124:127]
	v_mfma_f32_16x16x32_bf16 v[120:123], v[136:139], v[176:179], v[120:123]
	v_mfma_f32_16x16x32_bf16 v[108:111], v[128:131], v[192:195], v[108:111]
	v_mfma_f32_16x16x32_bf16 v[104:107], v[136:139], v[192:195], v[104:107]
	v_mfma_f32_16x16x32_bf16 v[92:95], v[128:131], v[200:203], v[92:95]
	v_mfma_f32_16x16x32_bf16 v[88:91], v[136:139], v[200:203], v[88:91]
	v_mfma_f32_16x16x32_bf16 v[76:79], v[128:131], v[208:211], v[76:79]
	v_mfma_f32_16x16x32_bf16 v[72:75], v[136:139], v[208:211], v[72:75]
	v_mfma_f32_16x16x32_bf16 v[124:127], v[132:135], v[180:183], v[124:127]
	v_mfma_f32_16x16x32_bf16 v[120:123], v[140:143], v[180:183], v[120:123]
	v_mfma_f32_16x16x32_bf16 v[108:111], v[132:135], v[196:199], v[108:111]
	v_mfma_f32_16x16x32_bf16 v[104:107], v[140:143], v[196:199], v[104:107]
	v_mfma_f32_16x16x32_bf16 v[92:95], v[132:135], v[204:207], v[92:95]
	v_mfma_f32_16x16x32_bf16 v[88:91], v[140:143], v[204:207], v[88:91]
	v_mfma_f32_16x16x32_bf16 v[76:79], v[132:135], v[212:215], v[76:79]
	v_mfma_f32_16x16x32_bf16 v[72:75], v[140:143], v[212:215], v[72:75]
	s_setprio 0
	s_setprio 1
	v_mfma_f32_16x16x32_bf16 v[116:119], v[144:147], v[176:179], v[116:119]
	v_mfma_f32_16x16x32_bf16 v[112:115], v[168:171], v[176:179], v[112:115]
	v_mfma_f32_16x16x32_bf16 v[100:103], v[144:147], v[192:195], v[100:103]
	v_mfma_f32_16x16x32_bf16 v[96:99], v[168:171], v[192:195], v[96:99]
	v_mfma_f32_16x16x32_bf16 v[84:87], v[144:147], v[200:203], v[84:87]
	v_mfma_f32_16x16x32_bf16 v[80:83], v[168:171], v[200:203], v[80:83]
	v_mfma_f32_16x16x32_bf16 v[68:71], v[144:147], v[208:211], v[68:71]
	v_mfma_f32_16x16x32_bf16 v[64:67], v[168:171], v[208:211], v[64:67]
	v_mfma_f32_16x16x32_bf16 v[116:119], v[148:151], v[180:183], v[116:119]
	v_mfma_f32_16x16x32_bf16 v[112:115], v[172:175], v[180:183], v[112:115]
	v_mfma_f32_16x16x32_bf16 v[100:103], v[148:151], v[196:199], v[100:103]
	v_mfma_f32_16x16x32_bf16 v[96:99], v[172:175], v[196:199], v[96:99]
	v_mfma_f32_16x16x32_bf16 v[84:87], v[148:151], v[204:207], v[84:87]
	v_mfma_f32_16x16x32_bf16 v[80:83], v[172:175], v[204:207], v[80:83]
	v_mfma_f32_16x16x32_bf16 v[68:71], v[148:151], v[212:215], v[68:71]
	v_mfma_f32_16x16x32_bf16 v[64:67], v[172:175], v[212:215], v[64:67]
	s_setprio 0
	s_barrier
; #define PG8_STAGE(bufoff, gbase, voff) do { _Pragma("unroll") for (int _i = 0; _i < 2; ++_i) \
;         __builtin_amdgcn_global_load_lds((const unsigned*)((const char*)(gbase) + (voff)[_i]), (PG8_LAS unsigned*)(lds + (bufoff) + ldsw + _i * 8192), 16, 0, 0); } while (0)
; #define PG8_LDA(dst, b, h) do { _Pragma("unroll") for (int m = 0; m < 4; ++m) _Pragma("unroll") for (int k = 0; k < 2; ++k) dst[m][k] = *(const PG8_LAS bf16x8*)(lds + PG8_SA(b, h) + aoff + m * 2048 + k * 1024); } while (0)
; #define PG8_MMA(ai, bj, At, Bt) do { __builtin_amdgcn_s_setprio(1); _Pragma("unroll") for (int m = 0; m < 4; ++m) _Pragma("unroll") for (int n = 0; n < 2; ++n) _Pragma("unroll") for (int k = 0; k < 2; ++k) \
;         acc[ai][bj][m][n] = mma16<F16>(Bt[n][k], At[m][k], acc[ai][bj][m][n]); __builtin_amdgcn_s_setprio(0); } while (0)
; #define PG8_WAIT_V(n) asm volatile("s_waitcnt vmcnt(" #n ")" ::: "memory")
; #define PG8_WAIT_L(n) asm volatile("s_waitcnt lgkmcnt(" #n ")" ::: "memory")
; #define PG8_BAR __builtin_amdgcn_s_barrier()
; #define PG8_SCHED __builtin_amdgcn_sched_barrier(0)
; template <class Epi, class Sched, bool ALIGN_EPI = false, bool SP2 = false, bool F16 = false>
; __device__ __forceinline__ void gemm_phase(PG8_LAS unsigned char* lds, const Gemm g, const Sched& S, const Epi& E, const int wid_in) {
;     ...
;             PG8_LDA(At, 1, 1); PG8_STAGE(PG8_SB(1, 0), b3, voffB); PG8_STAGE(PG8_SB(1, 1), b3 + hstep, voffB); PG8_STAGE(PG8_SA(1, 0), a3, voffA);
;             PG8_WAIT_V(8); PG8_WAIT_L(0); PG8_BAR; PG8_MMA(1, 0, At, B0); PG8_MMA(1, 1, At, B1); PG8_BAR; PG8_SCHED;
	s_add_i32 s52, s62, s68
	v_lshl_add_u64 v[184:185], v[184:185], 0, s[28:29]
	s_mov_b32 m0, s52
	ds_read_b128 v[176:179], v191 offset:49152
	ds_read_b128 v[180:183], v191 offset:50176
	ds_read_b128 v[192:195], v191 offset:51200
	ds_read_b128 v[196:199], v191 offset:52224
	ds_read_b128 v[200:203], v191 offset:53248
	ds_read_b128 v[204:207], v191 offset:54272
	ds_read_b128 v[208:211], v191 offset:55296
	ds_read_b128 v[212:215], v191 offset:56320
	global_load_lds_dwordx4 v[184:185], off
	s_add_i32 m0, s52, 0x2000
	s_add_u32 s50, s50, 0x40080
	v_lshl_add_u64 v[184:185], v[216:217], 0, s[28:29]
	s_addc_u32 s51, s51, 0
	s_add_i32 s52, s63, s68
	global_load_lds_dwordx4 v[184:185], off
	s_mov_b32 m0, s52
	s_nop 0
	global_load_lds_dwordx4 v154, s[50:51]
	s_add_i32 m0, s52, 0x2000
	s_nop 0
	global_load_lds_dwordx4 v158, s[50:51]
	v_lshl_add_u64 v[184:185], v[218:219], 0, s[28:29]
	s_mov_b32 m0, s75
	s_nop 0
	global_load_lds_dwordx4 v[184:185], off
	v_lshl_add_u64 v[184:185], v[220:221], 0, s[28:29]
	s_mov_b32 m0, s67
	s_nop 0
	global_load_lds_dwordx4 v[184:185], off
	s_waitcnt vmcnt(8)
	s_waitcnt lgkmcnt(0)
	s_barrier
	s_setprio 1
	s_waitcnt lgkmcnt(0)
	v_mfma_f32_16x16x32_bf16 v[60:63], v[128:131], v[176:179], v[60:63]
	v_mfma_f32_16x16x32_bf16 v[56:59], v[136:139], v[176:179], v[56:59]
	v_mfma_f32_16x16x32_bf16 v[44:47], v[128:131], v[192:195], v[44:47]
	v_mfma_f32_16x16x32_bf16 v[40:43], v[136:139], v[192:195], v[40:43]
	v_mfma_f32_16x16x32_bf16 v[28:31], v[128:131], v[200:203], v[28:31]
	v_mfma_f32_16x16x32_bf16 v[24:27], v[136:139], v[200:203], v[24:27]
	v_mfma_f32_16x16x32_bf16 v[12:15], v[128:131], v[208:211], v[12:15]
	v_mfma_f32_16x16x32_bf16 v[8:11], v[136:139], v[208:211], v[8:11]
	v_mfma_f32_16x16x32_bf16 v[60:63], v[132:135], v[180:183], v[60:63]
	v_mfma_f32_16x16x32_bf16 v[56:59], v[140:143], v[180:183], v[56:59]
	v_mfma_f32_16x16x32_bf16 v[44:47], v[132:135], v[196:199], v[44:47]
	v_mfma_f32_16x16x32_bf16 v[40:43], v[140:143], v[196:199], v[40:43]
	v_mfma_f32_16x16x32_bf16 v[28:31], v[132:135], v[204:207], v[28:31]
	v_mfma_f32_16x16x32_bf16 v[24:27], v[140:143], v[204:207], v[24:27]
	v_mfma_f32_16x16x32_bf16 v[12:15], v[132:135], v[212:215], v[12:15]
	v_mfma_f32_16x16x32_bf16 v[8:11], v[140:143], v[212:215], v[8:11]
	s_setprio 0
	s_setprio 1
	v_mfma_f32_16x16x32_bf16 v[52:55], v[144:147], v[176:179], v[52:55]
	v_mfma_f32_16x16x32_bf16 v[48:51], v[168:171], v[176:179], v[48:51]
	v_mfma_f32_16x16x32_bf16 v[36:39], v[144:147], v[192:195], v[36:39]
	v_mfma_f32_16x16x32_bf16 v[32:35], v[168:171], v[192:195], v[32:35]
	v_mfma_f32_16x16x32_bf16 v[20:23], v[144:147], v[200:203], v[20:23]
	v_mfma_f32_16x16x32_bf16 v[16:19], v[168:171], v[200:203], v[16:19]
	v_mfma_f32_16x16x32_bf16 v[4:7], v[144:147], v[208:211], v[4:7]
	v_mfma_f32_16x16x32_bf16 v[0:3], v[168:171], v[208:211], v[0:3]
	v_mfma_f32_16x16x32_bf16 v[52:55], v[148:151], v[180:183], v[52:55]
	v_mfma_f32_16x16x32_bf16 v[48:51], v[172:175], v[180:183], v[48:51]
	v_mfma_f32_16x16x32_bf16 v[36:39], v[148:151], v[196:199], v[36:39]
	v_mfma_f32_16x16x32_bf16 v[32:35], v[172:175], v[196:199], v[32:35]
	v_mfma_f32_16x16x32_bf16 v[20:23], v[148:151], v[204:207], v[20:23]
	v_mfma_f32_16x16x32_bf16 v[16:19], v[172:175], v[204:207], v[16:19]
	v_mfma_f32_16x16x32_bf16 v[4:7], v[148:151], v[212:215], v[4:7]
	v_mfma_f32_16x16x32_bf16 v[0:3], v[172:175], v[212:215], v[0:3]
	s_setprio 0
	s_barrier
	s_add_i32 s61, s61, 2
	s_add_u32 s48, s48, 0x100
	s_addc_u32 s49, s49, 0
	s_add_u32 s47, s47, 0x100
	s_addc_u32 s60, s60, 0
	s_cmp_gt_u32 s61, 13
	s_cbranch_scc0 .LBB0_1832
	s_and_b64 vcc, exec, s[16:17]
	s_cbranch_vccz .LBB0_1835
	s_barrier

; #define PG8_STAGE(bufoff, gbase, voff) do { _Pragma("unroll") for (int _i = 0; _i < 2; ++_i) \
;         __builtin_amdgcn_global_load_lds((const unsigned*)((const char*)(gbase) + (voff)[_i]), (PG8_LAS unsigned*)(lds + (bufoff) + ldsw + _i * 8192), 16, 0, 0); } while (0)
; #define PG8_WAIT_V(n) asm volatile("s_waitcnt vmcnt(" #n ")" ::: "memory")
; #define PG8_BAR __builtin_amdgcn_s_barrier()
; template <class Epi, class Sched, bool ALIGN_EPI = false, bool SP2 = false, bool F16 = false>
; __device__ __forceinline__ void gemm_phase(PG8_LAS unsigned char* lds, const Gemm g, const Sched& S, const Epi& E, const int wid_in) {
;     ...
;     for (int i = 0; i < 2; ++i) { int R, C; stage_rc(tid * 16 + i * 8192, R, C); const int Rb = Epi::PERM ? ((R & ~31) + perm32(R & 31)) : R;
;         voffA[i] = (unsigned)(R * K + C) * 2u; voffB[i] = (unsigned)(Rb * K + C) * 2u; }
;     const size_t kstep = (size_t)(BK * 2);
;     const size_t hstep = (size_t)HALF * K * 2;
;     const size_t tstep = 2 * hstep;
;     const unsigned ldsw = (unsigned)wid * 1024u;
;     const int aoff = lds_byte(wr * 64 + fr, fq * 8), boff = lds_byte(wc * 32 + fr, fq * 8);
;     ...
;         PG8_STAGE(PG8_SB(1, 0), cB + kstep, voffB); PG8_STAGE(PG8_SA(1, 0), cA + kstep, voffA); PG8_STAGE(PG8_SB(1, 1), cB + hstep + kstep, voffB);
;         PG8_WAIT_V(6); PG8_BAR;
.LBB0_1903:
	s_add_u32 s12, s14, 0x15700000
	s_addc_u32 s13, s15, 0
	s_add_u32 s22, s14, 0x9400000
	s_mov_b64 s[24:25], 0x80
	s_addc_u32 s23, s15, 0
	s_add_i32 m0, s74, 0x18000
	v_lshl_add_u64 v[6:7], v[6:7], 0, s[24:25]
	s_waitcnt vmcnt(2)
	s_barrier
	global_load_lds_dwordx4 v[6:7], off
	v_lshl_add_u64 v[4:5], v[4:5], 0, s[24:25]
	s_add_i32 m0, s74, 0x1a000
	v_lshl_add_u64 v[0:1], v[0:1], 0, s[24:25]
	global_load_lds_dwordx4 v[4:5], off
	s_mov_b32 m0, s75
	s_add_u32 s10, s48, 0x40080
	global_load_lds_dwordx4 v[0:1], off
	v_lshl_add_u64 v[0:1], v[2:3], 0, s[24:25]
	s_mov_b32 m0, s67
	s_addc_u32 s11, s49, 0
	global_load_lds_dwordx4 v[0:1], off
	s_add_i32 m0, s74, 0x1c000
	s_nop 0
	global_load_lds_dwordx4 v162, s[10:11]
	s_add_i32 m0, s74, 0x1e000
	v_and_b32_e32 v190, 15, v8
	global_load_lds_dwordx4 v166, s[10:11]
	v_or_b32_e32 v0, s70, v190
	v_lshlrev_b32_e32 v1, 6, v0
	v_and_b32_e32 v2, 48, v8
	s_movk_i32 s10, 0x3c0
	v_and_b32_e32 v3, 0xfffffc00, v12
	v_lshlrev_b32_e32 v0, 2, v0
	v_and_or_b32 v1, v1, s10, v2
	v_add_u32_e32 v4, s73, v3
	v_and_b32_e32 v0, 32, v0
	v_bitop3_b32 v0, v1, v4, v0 bitop3:0xde
	v_lshl_or_b32 v1, v190, 6, v2
	v_add_u32_e32 v2, s72, v3
	v_lshlrev_b32_e32 v3, 2, v8
	v_and_b32_e32 v3, 32, v3
	v_bitop3_b32 v192, v1, v2, v3 bitop3:0xde
	v_lshlrev_b32_e32 v1, 14, v9
	v_and_b32_e32 v1, 0xffff8000, v1
	v_lshl_add_u32 v1, v10, 11, v1
	v_and_b32_e32 v2, 1, v9
	v_lshl_or_b32 v1, v2, 6, v1
	v_lshl_add_u32 v168, v11, 1, v1
	v_lshlrev_b32_e32 v1, 14, v13
	v_and_b32_e32 v1, 0xffff8000, v1
	s_waitcnt vmcnt(6)
	s_mul_i32 s10, s3, 0x210
	v_lshl_add_u32 v1, v14, 11, v1
	v_and_b32_e32 v2, 1, v13
	s_add_i32 s58, s10, 0
	v_lshl_or_b32 v1, v2, 6, v1
	s_add_i32 s60, 0, 0x10000
	s_add_i32 s61, 0, 0x14000
	v_ashrrev_i32_e32 v191, 4, v8
	s_ashr_i32 s55, s38, 31
	s_mov_b32 s56, s38
	s_ashr_i32 s57, s19, 31
	s_add_i32 s58, s58, 0x20400
	v_mov_b32_e32 v169, v163
	v_lshl_add_u32 v170, v15, 1, v1
	v_mov_b32_e32 v171, v163
	v_mov_b64_e32 v[172:173], 0x580
	v_mov_b64_e32 v[174:175], 0x57f
	s_movk_i32 s59, 0xb1
	v_add_u32_e32 v193, s60, v192
	v_add_u32_e32 v194, s61, v192
	v_add_u32_e32 v195, 0, v0
	v_mov_b32_e32 v196, 0x358637bd
	s_movk_i32 s62, 0x1600
	s_barrier
	s_branch .LBB0_1906

; #define PG8_STAGE(bufoff, gbase, voff) do { _Pragma("unroll") for (int _i = 0; _i < 2; ++_i) \
;         __builtin_amdgcn_global_load_lds((const unsigned*)((const char*)(gbase) + (voff)[_i]), (PG8_LAS unsigned*)(lds + (bufoff) + ldsw + _i * 8192), 16, 0, 0); } while (0)
; #define PG8_LDA(dst, b, h) do { _Pragma("unroll") for (int m = 0; m < 4; ++m) _Pragma("unroll") for (int k = 0; k < 2; ++k) dst[m][k] = *(const PG8_LAS bf16x8*)(lds + PG8_SA(b, h) + aoff + m * 2048 + k * 1024); } while (0)
; #define PG8_LDB(dst, b, h) do { _Pragma("unroll") for (int n = 0; n < 2; ++n) _Pragma("unroll") for (int k = 0; k < 2; ++k) dst[n][k] = *(const PG8_LAS bf16x8*)(lds + PG8_SB(b, h) + boff + n * 2048 + k * 1024); } while (0)
; #define PG8_MMA(ai, bj, At, Bt) do { __builtin_amdgcn_s_setprio(1); _Pragma("unroll") for (int m = 0; m < 4; ++m) _Pragma("unroll") for (int n = 0; n < 2; ++n) _Pragma("unroll") for (int k = 0; k < 2; ++k) \
;         acc[ai][bj][m][n] = mma16<F16>(Bt[n][k], At[m][k], acc[ai][bj][m][n]); __builtin_amdgcn_s_setprio(0); } while (0)
; #define PG8_WAIT_V(n) asm volatile("s_waitcnt vmcnt(" #n ")" ::: "memory")
; #define PG8_WAIT_L(n) asm volatile("s_waitcnt lgkmcnt(" #n ")" ::: "memory")
; #define PG8_BAR __builtin_amdgcn_s_barrier()
; #define PG8_SCHED __builtin_amdgcn_sched_barrier(0)
; template <class Epi, class Sched, bool ALIGN_EPI = false, bool SP2 = false, bool F16 = false>
; __device__ __forceinline__ void gemm_phase(PG8_LAS unsigned char* lds, const Gemm g, const Sched& S, const Epi& E, const int wid_in) {
;     ...
;             PG8_LDB(B0, 0, 0); PG8_LDB(B1, 0, 1); PG8_SCHED; PG8_LDA(At, 0, 0); PG8_STAGE(PG8_SA(1, 1), a1 + hstep, voffA);
;             PG8_WAIT_V(8); PG8_WAIT_L(0); PG8_BAR; PG8_MMA(0, 0, At, B0); PG8_MMA(0, 1, At, B1); PG8_BAR; PG8_SCHED;
;             PG8_LDA(At, 0, 1); PG8_STAGE(PG8_SB(0, 0), b2, voffB); PG8_STAGE(PG8_SB(0, 1), b2 + hstep, voffB); PG8_STAGE(PG8_SA(0, 0), a2, voffA);
;             PG8_WAIT_V(8); PG8_WAIT_L(0); PG8_BAR; PG8_MMA(1, 0, At, B0); PG8_MMA(1, 1, At, B1); PG8_BAR; PG8_SCHED;
.LBB0_1909:
	ds_read_b128 v[0:3], v193
	ds_read_b128 v[4:7], v193 offset:1024
	ds_read_b128 v[136:139], v193 offset:2048
	ds_read_b128 v[140:143], v193 offset:3072
	ds_read_b128 v[144:147], v194
	ds_read_b128 v[148:151], v194 offset:1024
	ds_read_b128 v[152:155], v194 offset:2048
	ds_read_b128 v[156:159], v194 offset:3072
	s_add_u32 s48, s46, 0xfffc0080
	s_addc_u32 s49, s47, -1
	s_cmp_eq_u32 s64, 12
	s_cselect_b32 s51, s29, s49
	s_cselect_b32 s50, s42, s48
	s_cselect_b32 s49, s27, s63
	s_cselect_b32 s48, s43, s45
	s_mov_b32 m0, s91
	ds_read_b128 v[176:179], v195
	ds_read_b128 v[180:183], v195 offset:1024
	ds_read_b128 v[184:187], v195 offset:2048
	ds_read_b128 v[198:201], v195 offset:3072
	ds_read_b128 v[202:205], v195 offset:4096
	ds_read_b128 v[206:209], v195 offset:5120
	ds_read_b128 v[210:213], v195 offset:6144
	ds_read_b128 v[214:217], v195 offset:7168
	global_load_lds_dwordx4 v168, s[46:47]
	s_add_i32 m0, s74, 0xe000
	s_nop 0
	global_load_lds_dwordx4 v170, s[46:47]
	s_waitcnt vmcnt(8)
	s_waitcnt lgkmcnt(0)
	s_barrier
	s_setprio 1
	s_waitcnt lgkmcnt(0)
	v_mfma_f32_16x16x32_f16 v[132:135], v[0:3], v[176:179], v[132:135]
	v_mfma_f32_16x16x32_f16 v[128:131], v[136:139], v[176:179], v[128:131]
	v_mfma_f32_16x16x32_f16 v[116:119], v[0:3], v[184:187], v[116:119]
	v_mfma_f32_16x16x32_f16 v[112:115], v[136:139], v[184:187], v[112:115]
	v_mfma_f32_16x16x32_f16 v[100:103], v[0:3], v[202:205], v[100:103]
	v_mfma_f32_16x16x32_f16 v[96:99], v[136:139], v[202:205], v[96:99]
	v_mfma_f32_16x16x32_f16 v[84:87], v[0:3], v[210:213], v[84:87]
	v_mfma_f32_16x16x32_f16 v[80:83], v[136:139], v[210:213], v[80:83]
	v_mfma_f32_16x16x32_f16 v[132:135], v[4:7], v[180:183], v[132:135]
	v_mfma_f32_16x16x32_f16 v[128:131], v[140:143], v[180:183], v[128:131]
	v_mfma_f32_16x16x32_f16 v[116:119], v[4:7], v[198:201], v[116:119]
	v_mfma_f32_16x16x32_f16 v[112:115], v[140:143], v[198:201], v[112:115]
	v_mfma_f32_16x16x32_f16 v[100:103], v[4:7], v[206:209], v[100:103]
	v_mfma_f32_16x16x32_f16 v[96:99], v[140:143], v[206:209], v[96:99]
	v_mfma_f32_16x16x32_f16 v[84:87], v[4:7], v[214:217], v[84:87]
	v_mfma_f32_16x16x32_f16 v[80:83], v[140:143], v[214:217], v[80:83]
	s_setprio 0
	s_setprio 1
	v_mfma_f32_16x16x32_f16 v[124:127], v[144:147], v[176:179], v[124:127]
	v_mfma_f32_16x16x32_f16 v[120:123], v[152:155], v[176:179], v[120:123]
	v_mfma_f32_16x16x32_f16 v[108:111], v[144:147], v[184:187], v[108:111]
	v_mfma_f32_16x16x32_f16 v[104:107], v[152:155], v[184:187], v[104:107]
	v_mfma_f32_16x16x32_f16 v[92:95], v[144:147], v[202:205], v[92:95]
	v_mfma_f32_16x16x32_f16 v[88:91], v[152:155], v[202:205], v[88:91]
	v_mfma_f32_16x16x32_f16 v[76:79], v[144:147], v[210:213], v[76:79]
	v_mfma_f32_16x16x32_f16 v[72:75], v[152:155], v[210:213], v[72:75]
	v_mfma_f32_16x16x32_f16 v[124:127], v[148:151], v[180:183], v[124:127]
	v_mfma_f32_16x16x32_f16 v[120:123], v[156:159], v[180:183], v[120:123]
	v_mfma_f32_16x16x32_f16 v[108:111], v[148:151], v[198:201], v[108:111]
	v_mfma_f32_16x16x32_f16 v[104:107], v[156:159], v[198:201], v[104:107]
	v_mfma_f32_16x16x32_f16 v[92:95], v[148:151], v[206:209], v[92:95]
	v_mfma_f32_16x16x32_f16 v[88:91], v[156:159], v[206:209], v[88:91]
	v_mfma_f32_16x16x32_f16 v[76:79], v[148:151], v[214:217], v[76:79]
	v_mfma_f32_16x16x32_f16 v[72:75], v[156:159], v[214:217], v[72:75]
	s_setprio 0
	s_barrier
	s_add_i32 s65, s60, s68
	v_lshl_add_u64 v[188:189], s[48:49], 0, v[162:163]
	s_mov_b32 m0, s65
	ds_read_b128 v[176:179], v195 offset:16384
	ds_read_b128 v[180:183], v195 offset:17408
	ds_read_b128 v[184:187], v195 offset:18432
	ds_read_b128 v[198:201], v195 offset:19456
	ds_read_b128 v[202:205], v195 offset:20480
	ds_read_b128 v[206:209], v195 offset:21504
	ds_read_b128 v[210:213], v195 offset:22528
	ds_read_b128 v[214:217], v195 offset:23552
	global_load_lds_dwordx4 v[188:189], off
	s_add_i32 m0, s65, 0x2000
	s_add_u32 s84, s48, 0x40000
	v_lshl_add_u64 v[218:219], s[48:49], 0, v[166:167]
	s_addc_u32 s85, s49, 0
	s_add_i32 s65, s61, s68
	global_load_lds_dwordx4 v[218:219], off
	s_mov_b32 m0, s65
	v_lshl_add_u64 v[222:223], s[50:51], 0, v[164:165]
	global_load_lds_dwordx4 v162, s[84:85]
	s_add_i32 m0, s65, 0x2000
	s_nop 0
	global_load_lds_dwordx4 v166, s[84:85]
	v_lshl_add_u64 v[220:221], s[50:51], 0, v[160:161]
	s_mov_b32 m0, s74
	s_nop 0
	global_load_lds_dwordx4 v[220:221], off
	s_mov_b32 m0, s66
	s_nop 0
	global_load_lds_dwordx4 v[222:223], off
	s_waitcnt vmcnt(8)
	s_waitcnt lgkmcnt(0)
	s_barrier
	s_setprio 1
	s_waitcnt lgkmcnt(0)
	v_mfma_f32_16x16x32_f16 v[68:71], v[0:3], v[176:179], v[68:71]
	v_mfma_f32_16x16x32_f16 v[64:67], v[136:139], v[176:179], v[64:67]
	v_mfma_f32_16x16x32_f16 v[52:55], v[0:3], v[184:187], v[52:55]
	v_mfma_f32_16x16x32_f16 v[48:51], v[136:139], v[184:187], v[48:51]
	v_mfma_f32_16x16x32_f16 v[36:39], v[0:3], v[202:205], v[36:39]
	v_mfma_f32_16x16x32_f16 v[32:35], v[136:139], v[202:205], v[32:35]
	v_mfma_f32_16x16x32_f16 v[0:3], v[0:3], v[210:213], v[20:23]
	v_mfma_f32_16x16x32_f16 v[68:71], v[4:7], v[180:183], v[68:71]
	v_mfma_f32_16x16x32_f16 v[64:67], v[140:143], v[180:183], v[64:67]
	v_mfma_f32_16x16x32_f16 v[52:55], v[4:7], v[198:201], v[52:55]
	v_mfma_f32_16x16x32_f16 v[48:51], v[140:143], v[198:201], v[48:51]
	v_mfma_f32_16x16x32_f16 v[36:39], v[4:7], v[206:209], v[36:39]
	v_mfma_f32_16x16x32_f16 v[32:35], v[140:143], v[206:209], v[32:35]
	v_mfma_f32_16x16x32_f16 v[0:3], v[4:7], v[214:217], v[0:3]
	v_mfma_f32_16x16x32_f16 v[4:7], v[136:139], v[210:213], v[16:19]
	v_mfma_f32_16x16x32_f16 v[4:7], v[140:143], v[214:217], v[4:7]
	s_setprio 0
	s_setprio 1
	v_mfma_f32_16x16x32_f16 v[16:19], v[144:147], v[176:179], v[60:63]
	v_mfma_f32_16x16x32_f16 v[60:63], v[148:151], v[180:183], v[16:19]
	v_mfma_f32_16x16x32_f16 v[16:19], v[152:155], v[176:179], v[56:59]
	v_mfma_f32_16x16x32_f16 v[56:59], v[156:159], v[180:183], v[16:19]
	v_mfma_f32_16x16x32_f16 v[16:19], v[144:147], v[184:187], v[44:47]
	v_mfma_f32_16x16x32_f16 v[44:47], v[148:151], v[198:201], v[16:19]
	v_mfma_f32_16x16x32_f16 v[16:19], v[152:155], v[184:187], v[40:43]
	v_mfma_f32_16x16x32_f16 v[40:43], v[156:159], v[198:201], v[16:19]
	v_mfma_f32_16x16x32_f16 v[16:19], v[144:147], v[202:205], v[28:31]
	v_mfma_f32_16x16x32_f16 v[28:31], v[148:151], v[206:209], v[16:19]
	v_mfma_f32_16x16x32_f16 v[16:19], v[152:155], v[202:205], v[24:27]
	v_mfma_f32_16x16x32_f16 v[12:15], v[144:147], v[210:213], v[12:15]
	v_mfma_f32_16x16x32_f16 v[8:11], v[152:155], v[210:213], v[8:11]
	v_mfma_f32_16x16x32_f16 v[24:27], v[156:159], v[206:209], v[16:19]
	v_mfma_f32_16x16x32_f16 v[12:15], v[148:151], v[214:217], v[12:15]
	v_mfma_f32_16x16x32_f16 v[8:11], v[156:159], v[214:217], v[8:11]
	s_setprio 0
	s_barrier
; #define PG8_STAGE(bufoff, gbase, voff) do { _Pragma("unroll") for (int _i = 0; _i < 2; ++_i) \
;         __builtin_amdgcn_global_load_lds((const unsigned*)((const char*)(gbase) + (voff)[_i]), (PG8_LAS unsigned*)(lds + (bufoff) + ldsw + _i * 8192), 16, 0, 0); } while (0)
; #define PG8_LDA(dst, b, h) do { _Pragma("unroll") for (int m = 0; m < 4; ++m) _Pragma("unroll") for (int k = 0; k < 2; ++k) dst[m][k] = *(const PG8_LAS bf16x8*)(lds + PG8_SA(b, h) + aoff + m * 2048 + k * 1024); } while (0)
; #define PG8_LDB(dst, b, h) do { _Pragma("unroll") for (int n = 0; n < 2; ++n) _Pragma("unroll") for (int k = 0; k < 2; ++k) dst[n][k] = *(const PG8_LAS bf16x8*)(lds + PG8_SB(b, h) + boff + n * 2048 + k * 1024); } while (0)
; #define PG8_MMA(ai, bj, At, Bt) do { __builtin_amdgcn_s_setprio(1); _Pragma("unroll") for (int m = 0; m < 4; ++m) _Pragma("unroll") for (int n = 0; n < 2; ++n) _Pragma("unroll") for (int k = 0; k < 2; ++k) \
;         acc[ai][bj][m][n] = mma16<F16>(Bt[n][k], At[m][k], acc[ai][bj][m][n]); __builtin_amdgcn_s_setprio(0); } while (0)
; #define PG8_WAIT_V(n) asm volatile("s_waitcnt vmcnt(" #n ")" ::: "memory")
; #define PG8_WAIT_L(n) asm volatile("s_waitcnt lgkmcnt(" #n ")" ::: "memory")
; #define PG8_BAR __builtin_amdgcn_s_barrier()
; #define PG8_SCHED __builtin_amdgcn_sched_barrier(0)
; template <class Epi, class Sched, bool ALIGN_EPI = false, bool SP2 = false, bool F16 = false>
; __device__ __forceinline__ void gemm_phase(PG8_LAS unsigned char* lds, const Gemm g, const Sched& S, const Epi& E, const int wid_in) {
;     ...
;             PG8_LDB(B0, 1, 0); PG8_LDB(B1, 1, 1); PG8_SCHED; PG8_LDA(At, 1, 0); PG8_STAGE(PG8_SA(0, 1), a2 + hstep, voffA);
;             PG8_WAIT_V(8); PG8_WAIT_L(0); PG8_BAR; PG8_MMA(0, 0, At, B0); PG8_MMA(0, 1, At, B1); PG8_BAR; PG8_SCHED;
;             PG8_LDA(At, 1, 1); PG8_STAGE(PG8_SB(1, 0), b3, voffB); PG8_STAGE(PG8_SB(1, 1), b3 + hstep, voffB); PG8_STAGE(PG8_SA(1, 0), a3, voffA);
;             PG8_WAIT_V(8); PG8_WAIT_L(0); PG8_BAR; PG8_MMA(1, 0, At, B0); PG8_MMA(1, 1, At, B1); PG8_BAR; PG8_SCHED;
	s_add_i32 s65, 0, 0x18000
	s_add_i32 s76, 0, 0x1c000
	v_add_u32_e32 v140, s65, v192
	v_add_u32_e32 v156, s76, v192
	ds_read_b128 v[16:19], v140
	ds_read_b128 v[20:23], v140 offset:1024
	ds_read_b128 v[136:139], v140 offset:2048
	ds_read_b128 v[140:143], v140 offset:3072
	ds_read_b128 v[144:147], v156
	ds_read_b128 v[148:151], v156 offset:1024
	ds_read_b128 v[152:155], v156 offset:2048
	ds_read_b128 v[156:159], v156 offset:3072
	s_add_u32 s50, s50, 0x40000
	s_addc_u32 s51, s51, 0
	s_mov_b32 m0, s90
	ds_read_b128 v[176:179], v195 offset:32768
	ds_read_b128 v[180:183], v195 offset:33792
	ds_read_b128 v[184:187], v195 offset:34816
	ds_read_b128 v[198:201], v195 offset:35840
	ds_read_b128 v[202:205], v195 offset:36864
	ds_read_b128 v[206:209], v195 offset:37888
	ds_read_b128 v[210:213], v195 offset:38912
	ds_read_b128 v[214:217], v195 offset:39936
	global_load_lds_dwordx4 v160, s[50:51]
	v_lshl_add_u64 v[224:225], s[50:51], 0, v[164:165]
	s_mov_b32 m0, s37
	s_nop 0
	global_load_lds_dwordx4 v[224:225], off
	s_waitcnt vmcnt(8)
	s_waitcnt lgkmcnt(0)
	s_barrier
	s_setprio 1
	s_waitcnt lgkmcnt(0)
	v_mfma_f32_16x16x32_f16 v[132:135], v[16:19], v[176:179], v[132:135]
	v_mfma_f32_16x16x32_f16 v[128:131], v[136:139], v[176:179], v[128:131]
	v_mfma_f32_16x16x32_f16 v[116:119], v[16:19], v[184:187], v[116:119]
	v_mfma_f32_16x16x32_f16 v[112:115], v[136:139], v[184:187], v[112:115]
	v_mfma_f32_16x16x32_f16 v[100:103], v[16:19], v[202:205], v[100:103]
	v_mfma_f32_16x16x32_f16 v[96:99], v[136:139], v[202:205], v[96:99]
	v_mfma_f32_16x16x32_f16 v[84:87], v[16:19], v[210:213], v[84:87]
	v_mfma_f32_16x16x32_f16 v[80:83], v[136:139], v[210:213], v[80:83]
	v_mfma_f32_16x16x32_f16 v[132:135], v[20:23], v[180:183], v[132:135]
	v_mfma_f32_16x16x32_f16 v[128:131], v[140:143], v[180:183], v[128:131]
	v_mfma_f32_16x16x32_f16 v[116:119], v[20:23], v[198:201], v[116:119]
	v_mfma_f32_16x16x32_f16 v[112:115], v[140:143], v[198:201], v[112:115]
	v_mfma_f32_16x16x32_f16 v[100:103], v[20:23], v[206:209], v[100:103]
	v_mfma_f32_16x16x32_f16 v[96:99], v[140:143], v[206:209], v[96:99]
	v_mfma_f32_16x16x32_f16 v[84:87], v[20:23], v[214:217], v[84:87]
	v_mfma_f32_16x16x32_f16 v[80:83], v[140:143], v[214:217], v[80:83]
	s_setprio 0
	s_setprio 1
	v_mfma_f32_16x16x32_f16 v[124:127], v[144:147], v[176:179], v[124:127]
	v_mfma_f32_16x16x32_f16 v[120:123], v[152:155], v[176:179], v[120:123]
	v_mfma_f32_16x16x32_f16 v[108:111], v[144:147], v[184:187], v[108:111]
	v_mfma_f32_16x16x32_f16 v[104:107], v[152:155], v[184:187], v[104:107]
	v_mfma_f32_16x16x32_f16 v[92:95], v[144:147], v[202:205], v[92:95]
	v_mfma_f32_16x16x32_f16 v[88:91], v[152:155], v[202:205], v[88:91]
	v_mfma_f32_16x16x32_f16 v[76:79], v[144:147], v[210:213], v[76:79]
	v_mfma_f32_16x16x32_f16 v[72:75], v[152:155], v[210:213], v[72:75]
	v_mfma_f32_16x16x32_f16 v[124:127], v[148:151], v[180:183], v[124:127]
	v_mfma_f32_16x16x32_f16 v[120:123], v[156:159], v[180:183], v[120:123]
	v_mfma_f32_16x16x32_f16 v[108:111], v[148:151], v[198:201], v[108:111]
	v_mfma_f32_16x16x32_f16 v[104:107], v[156:159], v[198:201], v[104:107]
	v_mfma_f32_16x16x32_f16 v[92:95], v[148:151], v[206:209], v[92:95]
	v_mfma_f32_16x16x32_f16 v[88:91], v[156:159], v[206:209], v[88:91]
	v_mfma_f32_16x16x32_f16 v[76:79], v[148:151], v[214:217], v[76:79]
	v_mfma_f32_16x16x32_f16 v[72:75], v[156:159], v[214:217], v[72:75]
	s_setprio 0
	s_barrier
	s_add_i32 s50, s65, s68
	v_lshl_add_u64 v[188:189], v[188:189], 0, s[24:25]
	s_mov_b32 m0, s50
	ds_read_b128 v[176:179], v195 offset:49152
	ds_read_b128 v[180:183], v195 offset:50176
	ds_read_b128 v[184:187], v195 offset:51200
	ds_read_b128 v[198:201], v195 offset:52224
	ds_read_b128 v[202:205], v195 offset:53248
	ds_read_b128 v[206:209], v195 offset:54272
	ds_read_b128 v[210:213], v195 offset:55296
	ds_read_b128 v[214:217], v195 offset:56320
	global_load_lds_dwordx4 v[188:189], off
	s_add_i32 m0, s50, 0x2000
	s_add_u32 s48, s48, 0x40080
	v_lshl_add_u64 v[188:189], v[218:219], 0, s[24:25]
	s_addc_u32 s49, s49, 0
	s_add_i32 s50, s76, s68
	global_load_lds_dwordx4 v[188:189], off
	s_mov_b32 m0, s50
	s_nop 0
	global_load_lds_dwordx4 v162, s[48:49]
	s_add_i32 m0, s50, 0x2000
	s_nop 0
	global_load_lds_dwordx4 v166, s[48:49]
	v_lshl_add_u64 v[188:189], v[220:221], 0, s[24:25]
	s_mov_b32 m0, s75
	s_nop 0
	global_load_lds_dwordx4 v[188:189], off
	v_lshl_add_u64 v[188:189], v[222:223], 0, s[24:25]
	s_mov_b32 m0, s67
	s_nop 0
	global_load_lds_dwordx4 v[188:189], off
	s_waitcnt vmcnt(8)
	s_waitcnt lgkmcnt(0)
	s_barrier
	s_setprio 1
	s_waitcnt lgkmcnt(0)
	v_mfma_f32_16x16x32_f16 v[68:71], v[16:19], v[176:179], v[68:71]
	v_mfma_f32_16x16x32_f16 v[52:55], v[16:19], v[184:187], v[52:55]
	v_mfma_f32_16x16x32_f16 v[36:39], v[16:19], v[202:205], v[36:39]
	v_mfma_f32_16x16x32_f16 v[0:3], v[16:19], v[210:213], v[0:3]
	v_mfma_f32_16x16x32_f16 v[68:71], v[20:23], v[180:183], v[68:71]
	v_mfma_f32_16x16x32_f16 v[64:67], v[136:139], v[176:179], v[64:67]
	v_mfma_f32_16x16x32_f16 v[52:55], v[20:23], v[198:201], v[52:55]
	v_mfma_f32_16x16x32_f16 v[48:51], v[136:139], v[184:187], v[48:51]
	v_mfma_f32_16x16x32_f16 v[36:39], v[20:23], v[206:209], v[36:39]
	v_mfma_f32_16x16x32_f16 v[32:35], v[136:139], v[202:205], v[32:35]
	v_mfma_f32_16x16x32_f16 v[20:23], v[20:23], v[214:217], v[0:3]
	v_mfma_f32_16x16x32_f16 v[0:3], v[136:139], v[210:213], v[4:7]
	v_mfma_f32_16x16x32_f16 v[64:67], v[140:143], v[180:183], v[64:67]
	v_mfma_f32_16x16x32_f16 v[48:51], v[140:143], v[198:201], v[48:51]
	v_mfma_f32_16x16x32_f16 v[32:35], v[140:143], v[206:209], v[32:35]
	v_mfma_f32_16x16x32_f16 v[16:19], v[140:143], v[214:217], v[0:3]
	s_setprio 0
	s_setprio 1
	v_mfma_f32_16x16x32_f16 v[0:3], v[144:147], v[176:179], v[60:63]
	v_mfma_f32_16x16x32_f16 v[60:63], v[148:151], v[180:183], v[0:3]
	v_mfma_f32_16x16x32_f16 v[0:3], v[152:155], v[176:179], v[56:59]
	v_mfma_f32_16x16x32_f16 v[56:59], v[156:159], v[180:183], v[0:3]
	v_mfma_f32_16x16x32_f16 v[0:3], v[144:147], v[184:187], v[44:47]
	v_mfma_f32_16x16x32_f16 v[44:47], v[148:151], v[198:201], v[0:3]
	v_mfma_f32_16x16x32_f16 v[0:3], v[152:155], v[184:187], v[40:43]
	v_mfma_f32_16x16x32_f16 v[40:43], v[156:159], v[198:201], v[0:3]
	v_mfma_f32_16x16x32_f16 v[0:3], v[144:147], v[202:205], v[28:31]
	v_mfma_f32_16x16x32_f16 v[28:31], v[148:151], v[206:209], v[0:3]
	v_mfma_f32_16x16x32_f16 v[0:3], v[152:155], v[202:205], v[24:27]
	v_mfma_f32_16x16x32_f16 v[24:27], v[156:159], v[206:209], v[0:3]
	v_mfma_f32_16x16x32_f16 v[0:3], v[144:147], v[210:213], v[12:15]
	v_mfma_f32_16x16x32_f16 v[12:15], v[148:151], v[214:217], v[0:3]
	v_mfma_f32_16x16x32_f16 v[0:3], v[152:155], v[210:213], v[8:11]
	v_mfma_f32_16x16x32_f16 v[8:11], v[156:159], v[214:217], v[0:3]
	s_setprio 0
	s_barrier
	s_add_i32 s64, s64, 2
	s_add_u32 s46, s46, 0x100
	s_addc_u32 s47, s47, 0
	s_add_u32 s45, s45, 0x100
	s_addc_u32 s63, s63, 0
	s_cmp_gt_u32 s64, 13
	s_cbranch_scc0 .LBB0_1909
	s_and_b64 vcc, exec, s[16:17]
	s_cbranch_vccz .LBB0_1912
	s_barrier

; #define PG8_STAGE(bufoff, gbase, voff) do { _Pragma("unroll") for (int _i = 0; _i < 2; ++_i) \
;         __builtin_amdgcn_global_load_lds((const unsigned*)((const char*)(gbase) + (voff)[_i]), (PG8_LAS unsigned*)(lds + (bufoff) + ldsw + _i * 8192), 16, 0, 0); } while (0)
; #define PG8_WAIT_V(n) asm volatile("s_waitcnt vmcnt(" #n ")" ::: "memory")
; #define PG8_BAR __builtin_amdgcn_s_barrier()
; template <class Epi, class Sched, bool ALIGN_EPI = false, bool SP2 = false, bool F16 = false>
; __device__ __forceinline__ void gemm_phase(PG8_LAS unsigned char* lds, const Gemm g, const Sched& S, const Epi& E, const int wid_in) {
;     ...
;     for (int i = 0; i < 2; ++i) { int R, C; stage_rc(tid * 16 + i * 8192, R, C); const int Rb = Epi::PERM ? ((R & ~31) + perm32(R & 31)) : R;
;         voffA[i] = (unsigned)(R * K + C) * 2u; voffB[i] = (unsigned)(Rb * K + C) * 2u; }
;     const size_t kstep = (size_t)(BK * 2);
;     const size_t hstep = (size_t)HALF * K * 2;
;     const size_t tstep = 2 * hstep;
;     const unsigned ldsw = (unsigned)wid * 1024u;
;     const int aoff = lds_byte(wr * 64 + fr, fq * 8), boff = lds_byte(wc * 32 + fr, fq * 8);
;     ...
;         PG8_STAGE(PG8_SB(1, 0), cB + kstep, voffB); PG8_STAGE(PG8_SA(1, 0), cA + kstep, voffA); PG8_STAGE(PG8_SB(1, 1), cB + hstep + kstep, voffB);
;         PG8_WAIT_V(6); PG8_BAR;
.LBB0_1941:
	s_add_u32 s22, s14, 0xf400000
	s_mov_b64 s[24:25], 0x80
	s_addc_u32 s23, s15, 0
	s_add_i32 m0, s74, 0x18000
	v_lshl_add_u64 v[6:7], v[6:7], 0, s[24:25]
	s_waitcnt vmcnt(2)
	s_barrier
	global_load_lds_dwordx4 v[6:7], off
	v_lshl_add_u64 v[4:5], v[4:5], 0, s[24:25]
	s_add_i32 m0, s74, 0x1a000
	v_lshl_add_u64 v[2:3], v[2:3], 0, s[24:25]
	global_load_lds_dwordx4 v[4:5], off
	s_mov_b32 m0, s75
	s_add_u32 s14, s10, 0x10080
	global_load_lds_dwordx4 v[2:3], off
	v_lshl_add_u64 v[0:1], v[0:1], 0, s[24:25]
	s_mov_b32 m0, s67
	s_addc_u32 s15, s11, 0
	global_load_lds_dwordx4 v[0:1], off
	s_add_i32 m0, s74, 0x1c000
	s_nop 0
	global_load_lds_dwordx4 v130, s[14:15]
	s_add_i32 m0, s74, 0x1e000
	v_and_b32_e32 v132, 15, v8
	global_load_lds_dwordx4 v128, s[14:15]
	v_or_b32_e32 v0, s70, v132
	v_ashrrev_i32_e32 v1, 6, v8
	v_lshlrev_b32_e32 v2, 6, v0
	v_and_b32_e32 v3, 48, v8
	s_movk_i32 s14, 0x3c0
	v_lshlrev_b32_e32 v0, 2, v0
	v_and_or_b32 v2, v2, s14, v3
	v_lshl_add_u32 v4, v1, 10, s73
	v_and_b32_e32 v0, 32, v0
	v_bitop3_b32 v0, v2, v4, v0 bitop3:0xde
	v_lshl_or_b32 v2, v132, 6, v3
	v_lshlrev_b32_e32 v3, 2, v8
	v_add_lshl_u32 v1, v1, s96, 10
	v_and_b32_e32 v3, 32, v3
	v_bitop3_b32 v1, v2, v1, v3 bitop3:0xde
	s_waitcnt vmcnt(6)
	s_add_i32 s15, 0, 0x10000
	s_add_i32 s51, 0, 0x14000
	s_add_i32 s53, 0, 0x18000
	s_add_i32 s55, 0, 0x1c000
	v_add_u32_e32 v134, s15, v1
	v_add_u32_e32 v135, s51, v1
	s_add_i32 s15, s15, s68
	s_add_i32 s51, s51, s68
	v_add_u32_e32 v137, s53, v1
	v_add_u32_e32 v138, s55, v1
	s_add_i32 s53, s53, s68
	s_add_i32 s55, s55, s68
	v_ashrrev_i32_e32 v133, 4, v8
	s_mov_b64 s[30:31], -1
	v_add_u32_e32 v136, 0, v0
	s_add_i32 s14, s74, 0xe000
	s_mov_b64 s[26:27], 0x100
	s_add_i32 s50, s15, 0x2000
	s_add_i32 s52, s51, 0x2000
	s_mov_b64 s[28:29], 0x180
	s_add_i32 s54, s53, 0x2000
	s_add_i32 s56, s55, 0x2000
	s_barrier
	s_branch .LBB0_1944

; #define PG8_STAGE(bufoff, gbase, voff) do { _Pragma("unroll") for (int _i = 0; _i < 2; ++_i) \
;         __builtin_amdgcn_global_load_lds((const unsigned*)((const char*)(gbase) + (voff)[_i]), (PG8_LAS unsigned*)(lds + (bufoff) + ldsw + _i * 8192), 16, 0, 0); } while (0)
; #define PG8_LDA(dst, b, h) do { _Pragma("unroll") for (int m = 0; m < 4; ++m) _Pragma("unroll") for (int k = 0; k < 2; ++k) dst[m][k] = *(const PG8_LAS bf16x8*)(lds + PG8_SA(b, h) + aoff + m * 2048 + k * 1024); } while (0)
; #define PG8_LDB(dst, b, h) do { _Pragma("unroll") for (int n = 0; n < 2; ++n) _Pragma("unroll") for (int k = 0; k < 2; ++k) dst[n][k] = *(const PG8_LAS bf16x8*)(lds + PG8_SB(b, h) + boff + n * 2048 + k * 1024); } while (0)
; #define PG8_WAIT_V(n) asm volatile("s_waitcnt vmcnt(" #n ")" ::: "memory")
; #define PG8_WAIT_L(n) asm volatile("s_waitcnt lgkmcnt(" #n ")" ::: "memory")
; #define PG8_BAR __builtin_amdgcn_s_barrier()
; #define PG8_SCHED __builtin_amdgcn_sched_barrier(0)
; template <class Epi, class Sched, bool ALIGN_EPI = false, bool SP2 = false, bool F16 = false>
; __device__ __forceinline__ void gemm_phase(PG8_LAS unsigned char* lds, const Gemm g, const Sched& S, const Epi& E, const int wid_in) {
;     ...
;         const bool has_next = S.next(ui + 1, nxt);
;         const char* nA = has_next ? (const char*)g.A + (size_t)nxt.pm * tstep : cA; const char* nB = has_next ? (const char*)g.Bt + (size_t)nxt.pn * tstep : cB;
;         for (int t = 0; t < nt; t += 2) {
;             const bool last = (t == nt - 2);
;             const char* a1 = cA + (size_t)(t + 1) * kstep;
;             const char* a2 = last ? nA : cA + (size_t)(t + 2) * kstep; const char* b2 = last ? nB : cB + (size_t)(t + 2) * kstep;
;             const char* a3 = a2 + kstep; const char* b3 = b2 + kstep;
;             if (last && has_next) S.a_ready(nxt);
;             if constexpr (SP2) {
;             PG8_LDB(B0, 0, 0); PG8_LDB(B1, 0, 1); PG8_SCHED; PG8_LDA(At, 0, 0); PG8_STAGE(PG8_SA(1, 1), a1 + hstep, voffA);
;             PG8_WAIT_V(8); PG8_WAIT_L(0); PG8_BAR; PG8_MMA(0, 0, At, B0); PG8_MMA(0, 1, At, B1); PG8_BAR; PG8_SCHED;
;             PG8_LDA(At, 0, 1); PG8_STAGE(PG8_SB(0, 0), b2, voffB); PG8_STAGE(PG8_SB(0, 1), b2 + hstep, voffB); PG8_STAGE(PG8_SA(0, 0), a2, voffA);
;             PG8_WAIT_V(8); PG8_WAIT_L(0); PG8_BAR; PG8_MMA(1, 0, At, B0); PG8_MMA(1, 1, At, B1); PG8_BAR; PG8_SCHED;
.LBB0_1944:
	s_mov_b64 s[48:49], s[10:11]
	s_add_i32 s10, s36, s19
	s_mov_b64 s[46:47], s[12:13]
	s_mov_b32 s12, s58
	s_mov_b32 s13, s57
	s_and_b32 s57, s10, 3
	s_ashr_i32 s58, s10, 2
	s_and_b64 s[10:11], s[30:31], exec
	s_cselect_b32 s12, s58, s12
	ds_read_b128 v[0:3], v134
	ds_read_b128 v[4:7], v134 offset:1024
	ds_read_b128 v[8:11], v134 offset:2048
	ds_read_b128 v[12:15], v134 offset:3072
	ds_read_b128 v[16:19], v135
	ds_read_b128 v[20:23], v135 offset:1024
	ds_read_b128 v[24:27], v135 offset:2048
	ds_read_b128 v[28:31], v135 offset:3072
	s_cselect_b32 s10, s57, s13
	s_ashr_i32 s13, s12, 31
	s_lshl_b64 s[12:13], s[12:13], 17
	s_add_u32 s12, s21, s12
	s_addc_u32 s13, s40, s13
	s_and_b64 s[36:37], s[30:31], exec
	s_cselect_b32 s45, s13, s47
	s_cselect_b32 s44, s12, s46
	s_ashr_i32 s11, s10, 31
	s_lshl_b64 s[10:11], s[10:11], 17
	s_add_u32 s10, s41, s10
	s_addc_u32 s11, s42, s11
	s_and_b64 s[36:37], s[30:31], exec
	s_cselect_b32 s37, s11, s49
	s_cselect_b32 s36, s10, s48
	s_add_u32 s60, s46, 0x10080
	s_addc_u32 s61, s47, 0
	s_mov_b32 m0, s91
	ds_read_b128 v[32:35], v136
	ds_read_b128 v[36:39], v136 offset:1024
	ds_read_b128 v[40:43], v136 offset:2048
	ds_read_b128 v[44:47], v136 offset:3072
	ds_read_b128 v[48:51], v136 offset:4096
	ds_read_b128 v[52:55], v136 offset:5120
	ds_read_b128 v[56:59], v136 offset:6144
	ds_read_b128 v[60:63], v136 offset:7168
	global_load_lds_dwordx4 v130, s[60:61]
	s_mov_b32 m0, s14
	s_nop 0
	global_load_lds_dwordx4 v128, s[60:61]
	s_waitcnt vmcnt(8)
	s_waitcnt lgkmcnt(0)
	s_barrier
	s_setprio 1
	s_waitcnt lgkmcnt(0)
	v_mfma_f32_16x16x32_bf16 v[64:67], v[0:3], v[32:35], 0
	v_mfma_f32_16x16x32_bf16 v[68:71], v[8:11], v[32:35], 0
	v_mfma_f32_16x16x32_bf16 v[72:75], v[0:3], v[40:43], 0
	v_mfma_f32_16x16x32_bf16 v[76:79], v[8:11], v[40:43], 0
	v_mfma_f32_16x16x32_bf16 v[80:83], v[0:3], v[48:51], 0
	v_mfma_f32_16x16x32_bf16 v[84:87], v[8:11], v[48:51], 0
	v_mfma_f32_16x16x32_bf16 v[88:91], v[0:3], v[56:59], 0
	v_mfma_f32_16x16x32_bf16 v[92:95], v[8:11], v[56:59], 0
	v_mfma_f32_16x16x32_bf16 v[64:67], v[4:7], v[36:39], v[64:67]
	v_mfma_f32_16x16x32_bf16 v[68:71], v[12:15], v[36:39], v[68:71]
	v_mfma_f32_16x16x32_bf16 v[72:75], v[4:7], v[44:47], v[72:75]
	v_mfma_f32_16x16x32_bf16 v[76:79], v[12:15], v[44:47], v[76:79]
	v_mfma_f32_16x16x32_bf16 v[80:83], v[4:7], v[52:55], v[80:83]
	v_mfma_f32_16x16x32_bf16 v[84:87], v[12:15], v[52:55], v[84:87]
	v_mfma_f32_16x16x32_bf16 v[88:91], v[4:7], v[60:63], v[88:91]
	v_mfma_f32_16x16x32_bf16 v[92:95], v[12:15], v[60:63], v[92:95]
	s_setprio 0
	s_setprio 1
	v_mfma_f32_16x16x32_bf16 v[96:99], v[16:19], v[32:35], 0
	v_mfma_f32_16x16x32_bf16 v[32:35], v[24:27], v[32:35], 0
	v_mfma_f32_16x16x32_bf16 v[96:99], v[20:23], v[36:39], v[96:99]
	v_mfma_f32_16x16x32_bf16 v[32:35], v[28:31], v[36:39], v[32:35]
	v_mfma_f32_16x16x32_bf16 v[36:39], v[16:19], v[40:43], 0
	v_mfma_f32_16x16x32_bf16 v[40:43], v[24:27], v[40:43], 0
	v_mfma_f32_16x16x32_bf16 v[36:39], v[20:23], v[44:47], v[36:39]
	v_mfma_f32_16x16x32_bf16 v[40:43], v[28:31], v[44:47], v[40:43]
	v_mfma_f32_16x16x32_bf16 v[44:47], v[16:19], v[48:51], 0
	v_mfma_f32_16x16x32_bf16 v[48:51], v[24:27], v[48:51], 0
	v_mfma_f32_16x16x32_bf16 v[44:47], v[20:23], v[52:55], v[44:47]
	v_mfma_f32_16x16x32_bf16 v[48:51], v[28:31], v[52:55], v[48:51]
	v_mfma_f32_16x16x32_bf16 v[52:55], v[16:19], v[56:59], 0
	v_mfma_f32_16x16x32_bf16 v[56:59], v[24:27], v[56:59], 0
	v_mfma_f32_16x16x32_bf16 v[52:55], v[20:23], v[60:63], v[52:55]
	v_mfma_f32_16x16x32_bf16 v[56:59], v[28:31], v[60:63], v[56:59]
	s_setprio 0
	s_barrier
	v_lshl_add_u64 v[204:205], s[48:49], 0, v[130:131]
	s_mov_b32 m0, s15
	v_lshl_add_u64 v[140:141], v[204:205], 0, s[26:27]
	v_lshl_add_u64 v[206:207], s[48:49], 0, v[128:129]
	s_add_u32 s60, s48, 0x10100
	ds_read_b128 v[60:63], v136 offset:16384
	ds_read_b128 v[100:103], v136 offset:17408
	ds_read_b128 v[104:107], v136 offset:18432
	ds_read_b128 v[108:111], v136 offset:19456
	ds_read_b128 v[112:115], v136 offset:20480
	ds_read_b128 v[116:119], v136 offset:21504
	ds_read_b128 v[120:123], v136 offset:22528
	ds_read_b128 v[124:127], v136 offset:23552
	global_load_lds_dwordx4 v[140:141], off
	v_lshl_add_u64 v[140:141], v[206:207], 0, s[26:27]
	s_mov_b32 m0, s50
	s_addc_u32 s61, s49, 0
	global_load_lds_dwordx4 v[140:141], off
	s_mov_b32 m0, s51
	v_lshl_add_u64 v[208:209], s[46:47], 0, v[130:131]
	global_load_lds_dwordx4 v130, s[60:61]
	s_mov_b32 m0, s52
	v_lshl_add_u64 v[210:211], s[46:47], 0, v[128:129]
	global_load_lds_dwordx4 v128, s[60:61]
	v_lshl_add_u64 v[140:141], v[208:209], 0, s[26:27]
	s_mov_b32 m0, s74
	s_nop 0
	global_load_lds_dwordx4 v[140:141], off
	v_lshl_add_u64 v[140:141], v[210:211], 0, s[26:27]
	s_mov_b32 m0, s66
	s_nop 0
	global_load_lds_dwordx4 v[140:141], off
	s_waitcnt vmcnt(8)
	s_waitcnt lgkmcnt(0)
	s_barrier
; #define PG8_STAGE(bufoff, gbase, voff) do { _Pragma("unroll") for (int _i = 0; _i < 2; ++_i) \
;         __builtin_amdgcn_global_load_lds((const unsigned*)((const char*)(gbase) + (voff)[_i]), (PG8_LAS unsigned*)(lds + (bufoff) + ldsw + _i * 8192), 16, 0, 0); } while (0)
; #define PG8_LDA(dst, b, h) do { _Pragma("unroll") for (int m = 0; m < 4; ++m) _Pragma("unroll") for (int k = 0; k < 2; ++k) dst[m][k] = *(const PG8_LAS bf16x8*)(lds + PG8_SA(b, h) + aoff + m * 2048 + k * 1024); } while (0)
; #define PG8_LDB(dst, b, h) do { _Pragma("unroll") for (int n = 0; n < 2; ++n) _Pragma("unroll") for (int k = 0; k < 2; ++k) dst[n][k] = *(const PG8_LAS bf16x8*)(lds + PG8_SB(b, h) + boff + n * 2048 + k * 1024); } while (0)
; #define PG8_MMA(ai, bj, At, Bt) do { __builtin_amdgcn_s_setprio(1); _Pragma("unroll") for (int m = 0; m < 4; ++m) _Pragma("unroll") for (int n = 0; n < 2; ++n) _Pragma("unroll") for (int k = 0; k < 2; ++k) \
;         acc[ai][bj][m][n] = mma16<F16>(Bt[n][k], At[m][k], acc[ai][bj][m][n]); __builtin_amdgcn_s_setprio(0); } while (0)
; #define PG8_WAIT_V(n) asm volatile("s_waitcnt vmcnt(" #n ")" ::: "memory")
; #define PG8_WAIT_L(n) asm volatile("s_waitcnt lgkmcnt(" #n ")" ::: "memory")
; #define PG8_BAR __builtin_amdgcn_s_barrier()
; #define PG8_SCHED __builtin_amdgcn_sched_barrier(0)
; template <class Epi, class Sched, bool ALIGN_EPI = false, bool SP2 = false, bool F16 = false>
; __device__ __forceinline__ void gemm_phase(PG8_LAS unsigned char* lds, const Gemm g, const Sched& S, const Epi& E, const int wid_in) {
;     ...
;             PG8_WAIT_V(8); PG8_WAIT_L(0); PG8_BAR; PG8_MMA(0, 0, At, B0); PG8_MMA(0, 1, At, B1); PG8_BAR; PG8_SCHED;
;             PG8_LDA(At, 0, 1); PG8_STAGE(PG8_SB(0, 0), b2, voffB); PG8_STAGE(PG8_SB(0, 1), b2 + hstep, voffB); PG8_STAGE(PG8_SA(0, 0), a2, voffA);
;             PG8_WAIT_V(8); PG8_WAIT_L(0); PG8_BAR; PG8_MMA(1, 0, At, B0); PG8_MMA(1, 1, At, B1); PG8_BAR; PG8_SCHED;
;             PG8_LDB(B0, 1, 0); PG8_LDB(B1, 1, 1); PG8_SCHED; PG8_LDA(At, 1, 0); PG8_STAGE(PG8_SA(0, 1), a2 + hstep, voffA);
;             PG8_WAIT_V(8); PG8_WAIT_L(0); PG8_BAR; PG8_MMA(0, 0, At, B0); PG8_MMA(0, 1, At, B1); PG8_BAR; PG8_SCHED;
	s_setprio 1
	s_waitcnt lgkmcnt(0)
	v_mfma_f32_16x16x32_bf16 v[140:143], v[0:3], v[60:63], 0
	v_mfma_f32_16x16x32_bf16 v[148:151], v[0:3], v[104:107], 0
	v_mfma_f32_16x16x32_bf16 v[156:159], v[0:3], v[112:115], 0
	v_mfma_f32_16x16x32_bf16 v[0:3], v[0:3], v[120:123], 0
	v_mfma_f32_16x16x32_bf16 v[140:143], v[4:7], v[100:103], v[140:143]
	v_mfma_f32_16x16x32_bf16 v[148:151], v[4:7], v[108:111], v[148:151]
	v_mfma_f32_16x16x32_bf16 v[156:159], v[4:7], v[116:119], v[156:159]
	v_mfma_f32_16x16x32_bf16 v[0:3], v[4:7], v[124:127], v[0:3]
	v_mfma_f32_16x16x32_bf16 v[4:7], v[8:11], v[120:123], 0
	v_mfma_f32_16x16x32_bf16 v[144:147], v[8:11], v[60:63], 0
	v_mfma_f32_16x16x32_bf16 v[152:155], v[8:11], v[104:107], 0
	v_mfma_f32_16x16x32_bf16 v[160:163], v[8:11], v[112:115], 0
	v_mfma_f32_16x16x32_bf16 v[4:7], v[12:15], v[124:127], v[4:7]
	v_mfma_f32_16x16x32_bf16 v[144:147], v[12:15], v[100:103], v[144:147]
	v_mfma_f32_16x16x32_bf16 v[152:155], v[12:15], v[108:111], v[152:155]
	v_mfma_f32_16x16x32_bf16 v[160:163], v[12:15], v[116:119], v[160:163]
	s_setprio 0
	s_setprio 1
	v_mfma_f32_16x16x32_bf16 v[8:11], v[16:19], v[60:63], 0
	v_mfma_f32_16x16x32_bf16 v[12:15], v[24:27], v[60:63], 0
	v_mfma_f32_16x16x32_bf16 v[8:11], v[20:23], v[100:103], v[8:11]
	v_mfma_f32_16x16x32_bf16 v[12:15], v[28:31], v[100:103], v[12:15]
	v_mfma_f32_16x16x32_bf16 v[60:63], v[16:19], v[104:107], 0
	v_mfma_f32_16x16x32_bf16 v[100:103], v[24:27], v[104:107], 0
	v_mfma_f32_16x16x32_bf16 v[104:107], v[16:19], v[112:115], 0
	v_mfma_f32_16x16x32_bf16 v[16:19], v[16:19], v[120:123], 0
	v_mfma_f32_16x16x32_bf16 v[60:63], v[20:23], v[108:111], v[60:63]
	v_mfma_f32_16x16x32_bf16 v[100:103], v[28:31], v[108:111], v[100:103]
	v_mfma_f32_16x16x32_bf16 v[104:107], v[20:23], v[116:119], v[104:107]
	v_mfma_f32_16x16x32_bf16 v[108:111], v[24:27], v[112:115], 0
	v_mfma_f32_16x16x32_bf16 v[16:19], v[20:23], v[124:127], v[16:19]
	v_mfma_f32_16x16x32_bf16 v[20:23], v[24:27], v[120:123], 0
	v_mfma_f32_16x16x32_bf16 v[108:111], v[28:31], v[116:119], v[108:111]
	v_mfma_f32_16x16x32_bf16 v[20:23], v[28:31], v[124:127], v[20:23]
	s_setprio 0
	s_barrier
	ds_read_b128 v[24:27], v137
	ds_read_b128 v[28:31], v137 offset:1024
	ds_read_b128 v[112:115], v137 offset:2048
	ds_read_b128 v[116:119], v137 offset:3072
	ds_read_b128 v[120:123], v138
	ds_read_b128 v[124:127], v138 offset:1024
	ds_read_b128 v[164:167], v138 offset:2048
	ds_read_b128 v[168:171], v138 offset:3072
	s_add_u32 s60, s46, 0x10100
	s_addc_u32 s61, s47, 0
	s_mov_b32 m0, s90
	ds_read_b128 v[172:175], v136 offset:32768
	ds_read_b128 v[176:179], v136 offset:33792
	ds_read_b128 v[180:183], v136 offset:34816
	ds_read_b128 v[184:187], v136 offset:35840
	ds_read_b128 v[188:191], v136 offset:36864
	ds_read_b128 v[192:195], v136 offset:37888
	ds_read_b128 v[196:199], v136 offset:38912
	ds_read_b128 v[200:203], v136 offset:39936
	global_load_lds_dwordx4 v130, s[60:61]
	s_mov_b32 m0, s43
	s_nop 0
	global_load_lds_dwordx4 v128, s[60:61]
	s_waitcnt vmcnt(8)
	s_waitcnt lgkmcnt(0)
	s_barrier
	s_setprio 1
	s_waitcnt lgkmcnt(0)
	v_mfma_f32_16x16x32_bf16 v[64:67], v[24:27], v[172:175], v[64:67]
	v_mfma_f32_16x16x32_bf16 v[68:71], v[112:115], v[172:175], v[68:71]
	v_mfma_f32_16x16x32_bf16 v[72:75], v[24:27], v[180:183], v[72:75]
	v_mfma_f32_16x16x32_bf16 v[76:79], v[112:115], v[180:183], v[76:79]
	v_mfma_f32_16x16x32_bf16 v[80:83], v[24:27], v[188:191], v[80:83]
	v_mfma_f32_16x16x32_bf16 v[84:87], v[112:115], v[188:191], v[84:87]
	v_mfma_f32_16x16x32_bf16 v[88:91], v[24:27], v[196:199], v[88:91]
	v_mfma_f32_16x16x32_bf16 v[92:95], v[112:115], v[196:199], v[92:95]
	v_mfma_f32_16x16x32_bf16 v[64:67], v[28:31], v[176:179], v[64:67]
	v_mfma_f32_16x16x32_bf16 v[68:71], v[116:119], v[176:179], v[68:71]
	v_mfma_f32_16x16x32_bf16 v[72:75], v[28:31], v[184:187], v[72:75]
	v_mfma_f32_16x16x32_bf16 v[76:79], v[116:119], v[184:187], v[76:79]
	v_mfma_f32_16x16x32_bf16 v[80:83], v[28:31], v[192:195], v[80:83]
	v_mfma_f32_16x16x32_bf16 v[84:87], v[116:119], v[192:195], v[84:87]
	v_mfma_f32_16x16x32_bf16 v[88:91], v[28:31], v[200:203], v[88:91]
	v_mfma_f32_16x16x32_bf16 v[92:95], v[116:119], v[200:203], v[92:95]
	s_setprio 0
	s_setprio 1
	v_mfma_f32_16x16x32_bf16 v[96:99], v[120:123], v[172:175], v[96:99]
	v_mfma_f32_16x16x32_bf16 v[32:35], v[164:167], v[172:175], v[32:35]
	v_mfma_f32_16x16x32_bf16 v[36:39], v[120:123], v[180:183], v[36:39]
	v_mfma_f32_16x16x32_bf16 v[40:43], v[164:167], v[180:183], v[40:43]
	v_mfma_f32_16x16x32_bf16 v[44:47], v[120:123], v[188:191], v[44:47]
	v_mfma_f32_16x16x32_bf16 v[48:51], v[164:167], v[188:191], v[48:51]
	v_mfma_f32_16x16x32_bf16 v[52:55], v[120:123], v[196:199], v[52:55]
	v_mfma_f32_16x16x32_bf16 v[56:59], v[164:167], v[196:199], v[56:59]
	v_mfma_f32_16x16x32_bf16 v[96:99], v[124:127], v[176:179], v[96:99]
	v_mfma_f32_16x16x32_bf16 v[32:35], v[168:171], v[176:179], v[32:35]
	v_mfma_f32_16x16x32_bf16 v[36:39], v[124:127], v[184:187], v[36:39]
	v_mfma_f32_16x16x32_bf16 v[40:43], v[168:171], v[184:187], v[40:43]
	v_mfma_f32_16x16x32_bf16 v[44:47], v[124:127], v[192:195], v[44:47]
	v_mfma_f32_16x16x32_bf16 v[48:51], v[168:171], v[192:195], v[48:51]
	v_mfma_f32_16x16x32_bf16 v[52:55], v[124:127], v[200:203], v[52:55]
	v_mfma_f32_16x16x32_bf16 v[56:59], v[168:171], v[200:203], v[56:59]
	s_setprio 0
	s_barrier
; #define PG8_STAGE(bufoff, gbase, voff) do { _Pragma("unroll") for (int _i = 0; _i < 2; ++_i) \
;         __builtin_amdgcn_global_load_lds((const unsigned*)((const char*)(gbase) + (voff)[_i]), (PG8_LAS unsigned*)(lds + (bufoff) + ldsw + _i * 8192), 16, 0, 0); } while (0)
; #define PG8_LDA(dst, b, h) do { _Pragma("unroll") for (int m = 0; m < 4; ++m) _Pragma("unroll") for (int k = 0; k < 2; ++k) dst[m][k] = *(const PG8_LAS bf16x8*)(lds + PG8_SA(b, h) + aoff + m * 2048 + k * 1024); } while (0)
; #define PG8_LDB(dst, b, h) do { _Pragma("unroll") for (int n = 0; n < 2; ++n) _Pragma("unroll") for (int k = 0; k < 2; ++k) dst[n][k] = *(const PG8_LAS bf16x8*)(lds + PG8_SB(b, h) + boff + n * 2048 + k * 1024); } while (0)
; #define PG8_MMA(ai, bj, At, Bt) do { __builtin_amdgcn_s_setprio(1); _Pragma("unroll") for (int m = 0; m < 4; ++m) _Pragma("unroll") for (int n = 0; n < 2; ++n) _Pragma("unroll") for (int k = 0; k < 2; ++k) \
;         acc[ai][bj][m][n] = mma16<F16>(Bt[n][k], At[m][k], acc[ai][bj][m][n]); __builtin_amdgcn_s_setprio(0); } while (0)
; #define PG8_WAIT_V(n) asm volatile("s_waitcnt vmcnt(" #n ")" ::: "memory")
; #define PG8_WAIT_L(n) asm volatile("s_waitcnt lgkmcnt(" #n ")" ::: "memory")
; #define PG8_BAR __builtin_amdgcn_s_barrier()
; #define PG8_SCHED __builtin_amdgcn_sched_barrier(0)
; template <class Epi, class Sched, bool ALIGN_EPI = false, bool SP2 = false, bool F16 = false>
; __device__ __forceinline__ void gemm_phase(PG8_LAS unsigned char* lds, const Gemm g, const Sched& S, const Epi& E, const int wid_in) {
;     ...
;             PG8_LDA(At, 1, 1); PG8_STAGE(PG8_SB(1, 0), b3, voffB); PG8_STAGE(PG8_SB(1, 1), b3 + hstep, voffB); PG8_STAGE(PG8_SA(1, 0), a3, voffA);
;             PG8_WAIT_V(8); PG8_WAIT_L(0); PG8_BAR; PG8_MMA(1, 0, At, B0); PG8_MMA(1, 1, At, B1); PG8_BAR; PG8_SCHED;
;             } else {
;             PG8_LDB(B0, 0, 0); PG8_SCHED; PG8_LDA(At, 0, 0); PG8_STAGE(PG8_SA(1, 1), a1 + hstep, voffA);
	s_mov_b32 m0, s53
	v_lshl_add_u64 v[204:205], v[204:205], 0, s[28:29]
	s_add_u32 s48, s48, 0x10180
	ds_read_b128 v[172:175], v136 offset:49152
	ds_read_b128 v[176:179], v136 offset:50176
	ds_read_b128 v[180:183], v136 offset:51200
	ds_read_b128 v[184:187], v136 offset:52224
	ds_read_b128 v[188:191], v136 offset:53248
	ds_read_b128 v[192:195], v136 offset:54272
	ds_read_b128 v[196:199], v136 offset:55296
	ds_read_b128 v[200:203], v136 offset:56320
	global_load_lds_dwordx4 v[204:205], off
	v_lshl_add_u64 v[204:205], v[206:207], 0, s[28:29]
	s_mov_b32 m0, s54
	s_addc_u32 s49, s49, 0
	global_load_lds_dwordx4 v[204:205], off
	s_mov_b32 m0, s55
	s_nop 0
	global_load_lds_dwordx4 v130, s[48:49]
	s_mov_b32 m0, s56
	s_nop 0
	global_load_lds_dwordx4 v128, s[48:49]
	v_lshl_add_u64 v[204:205], v[208:209], 0, s[28:29]
	s_mov_b32 m0, s75
	s_nop 0
	global_load_lds_dwordx4 v[204:205], off
	v_lshl_add_u64 v[204:205], v[210:211], 0, s[28:29]
	s_mov_b32 m0, s67
	s_nop 0
	global_load_lds_dwordx4 v[204:205], off
	s_waitcnt vmcnt(8)
	s_waitcnt lgkmcnt(0)
	s_barrier
	s_setprio 1
	s_waitcnt lgkmcnt(0)
	v_mfma_f32_16x16x32_bf16 v[0:3], v[24:27], v[196:199], v[0:3]
	v_mfma_f32_16x16x32_bf16 v[4:7], v[112:115], v[196:199], v[4:7]
	v_mfma_f32_16x16x32_bf16 v[140:143], v[24:27], v[172:175], v[140:143]
	v_mfma_f32_16x16x32_bf16 v[144:147], v[112:115], v[172:175], v[144:147]
	v_mfma_f32_16x16x32_bf16 v[148:151], v[24:27], v[180:183], v[148:151]
	v_mfma_f32_16x16x32_bf16 v[152:155], v[112:115], v[180:183], v[152:155]
	v_mfma_f32_16x16x32_bf16 v[156:159], v[24:27], v[188:191], v[156:159]
	v_mfma_f32_16x16x32_bf16 v[160:163], v[112:115], v[188:191], v[160:163]
	v_mfma_f32_16x16x32_bf16 v[0:3], v[28:31], v[200:203], v[0:3]
	v_mfma_f32_16x16x32_bf16 v[4:7], v[116:119], v[200:203], v[4:7]
	v_mfma_f32_16x16x32_bf16 v[140:143], v[28:31], v[176:179], v[140:143]
	v_mfma_f32_16x16x32_bf16 v[144:147], v[116:119], v[176:179], v[144:147]
	v_mfma_f32_16x16x32_bf16 v[148:151], v[28:31], v[184:187], v[148:151]
	v_mfma_f32_16x16x32_bf16 v[152:155], v[116:119], v[184:187], v[152:155]
	v_mfma_f32_16x16x32_bf16 v[156:159], v[28:31], v[192:195], v[156:159]
	v_mfma_f32_16x16x32_bf16 v[160:163], v[116:119], v[192:195], v[160:163]
	s_setprio 0
	s_setprio 1
	v_mfma_f32_16x16x32_bf16 v[8:11], v[120:123], v[172:175], v[8:11]
	v_mfma_f32_16x16x32_bf16 v[12:15], v[164:167], v[172:175], v[12:15]
	v_mfma_f32_16x16x32_bf16 v[24:27], v[120:123], v[180:183], v[60:63]
	v_mfma_f32_16x16x32_bf16 v[28:31], v[164:167], v[180:183], v[100:103]
	v_mfma_f32_16x16x32_bf16 v[60:63], v[120:123], v[188:191], v[104:107]
	v_mfma_f32_16x16x32_bf16 v[100:103], v[164:167], v[188:191], v[108:111]
	v_mfma_f32_16x16x32_bf16 v[16:19], v[120:123], v[196:199], v[16:19]
	v_mfma_f32_16x16x32_bf16 v[20:23], v[164:167], v[196:199], v[20:23]
	v_mfma_f32_16x16x32_bf16 v[8:11], v[124:127], v[176:179], v[8:11]
	v_mfma_f32_16x16x32_bf16 v[12:15], v[168:171], v[176:179], v[12:15]
	v_mfma_f32_16x16x32_bf16 v[24:27], v[124:127], v[184:187], v[24:27]
	v_mfma_f32_16x16x32_bf16 v[28:31], v[168:171], v[184:187], v[28:31]
	v_mfma_f32_16x16x32_bf16 v[60:63], v[124:127], v[192:195], v[60:63]
	v_mfma_f32_16x16x32_bf16 v[100:103], v[168:171], v[192:195], v[100:103]
	v_mfma_f32_16x16x32_bf16 v[16:19], v[124:127], v[200:203], v[16:19]
	v_mfma_f32_16x16x32_bf16 v[20:23], v[168:171], v[200:203], v[20:23]
	s_setprio 0
	s_barrier
	ds_read_b128 v[104:107], v134
	ds_read_b128 v[108:111], v134 offset:1024
	ds_read_b128 v[112:115], v134 offset:2048
	ds_read_b128 v[116:119], v134 offset:3072
	ds_read_b128 v[120:123], v135
	ds_read_b128 v[124:127], v135 offset:1024
	ds_read_b128 v[164:167], v135 offset:2048
	ds_read_b128 v[168:171], v135 offset:3072
	s_add_u32 s46, s46, 0x10180
	s_addc_u32 s47, s47, 0
	s_mov_b32 m0, s91
	ds_read_b128 v[172:175], v136
	ds_read_b128 v[176:179], v136 offset:1024
	ds_read_b128 v[180:183], v136 offset:2048
	ds_read_b128 v[184:187], v136 offset:3072
	ds_read_b128 v[188:191], v136 offset:4096
	ds_read_b128 v[192:195], v136 offset:5120
	ds_read_b128 v[196:199], v136 offset:6144
	ds_read_b128 v[200:203], v136 offset:7168
	global_load_lds_dwordx4 v130, s[46:47]
	s_mov_b32 m0, s14
	s_nop 0
	global_load_lds_dwordx4 v128, s[46:47]
	s_waitcnt vmcnt(8)
	s_waitcnt lgkmcnt(0)
	s_barrier
	s_setprio 1
	s_waitcnt lgkmcnt(0)
	v_mfma_f32_16x16x32_bf16 v[64:67], v[104:107], v[172:175], v[64:67]
	v_mfma_f32_16x16x32_bf16 v[68:71], v[112:115], v[172:175], v[68:71]
	v_mfma_f32_16x16x32_bf16 v[72:75], v[104:107], v[180:183], v[72:75]
	v_mfma_f32_16x16x32_bf16 v[76:79], v[112:115], v[180:183], v[76:79]
	v_mfma_f32_16x16x32_bf16 v[80:83], v[104:107], v[188:191], v[80:83]
	v_mfma_f32_16x16x32_bf16 v[84:87], v[112:115], v[188:191], v[84:87]
	v_mfma_f32_16x16x32_bf16 v[88:91], v[104:107], v[196:199], v[88:91]
	v_mfma_f32_16x16x32_bf16 v[92:95], v[112:115], v[196:199], v[92:95]
	v_mfma_f32_16x16x32_bf16 v[64:67], v[108:111], v[176:179], v[64:67]
	v_mfma_f32_16x16x32_bf16 v[68:71], v[116:119], v[176:179], v[68:71]
	v_mfma_f32_16x16x32_bf16 v[72:75], v[108:111], v[184:187], v[72:75]
	v_mfma_f32_16x16x32_bf16 v[76:79], v[116:119], v[184:187], v[76:79]
	v_mfma_f32_16x16x32_bf16 v[80:83], v[108:111], v[192:195], v[80:83]
	v_mfma_f32_16x16x32_bf16 v[84:87], v[116:119], v[192:195], v[84:87]
	v_mfma_f32_16x16x32_bf16 v[88:91], v[108:111], v[200:203], v[88:91]
	v_mfma_f32_16x16x32_bf16 v[92:95], v[116:119], v[200:203], v[92:95]
	s_setprio 0
	s_setprio 1
	v_mfma_f32_16x16x32_bf16 v[32:35], v[164:167], v[172:175], v[32:35]
	v_mfma_f32_16x16x32_bf16 v[96:99], v[120:123], v[172:175], v[96:99]
	v_mfma_f32_16x16x32_bf16 v[172:175], v[168:171], v[176:179], v[32:35]
	v_mfma_f32_16x16x32_bf16 v[32:35], v[120:123], v[180:183], v[36:39]
	v_mfma_f32_16x16x32_bf16 v[204:207], v[124:127], v[176:179], v[96:99]
	v_mfma_f32_16x16x32_bf16 v[176:179], v[124:127], v[184:187], v[32:35]
	v_mfma_f32_16x16x32_bf16 v[32:35], v[164:167], v[180:183], v[40:43]
	v_mfma_f32_16x16x32_bf16 v[40:43], v[168:171], v[184:187], v[32:35]
	v_mfma_f32_16x16x32_bf16 v[32:35], v[120:123], v[188:191], v[44:47]
	v_mfma_f32_16x16x32_bf16 v[44:47], v[124:127], v[192:195], v[32:35]
	v_mfma_f32_16x16x32_bf16 v[32:35], v[164:167], v[188:191], v[48:51]
	v_mfma_f32_16x16x32_bf16 v[48:51], v[168:171], v[192:195], v[32:35]
	v_mfma_f32_16x16x32_bf16 v[32:35], v[120:123], v[196:199], v[52:55]
	v_mfma_f32_16x16x32_bf16 v[52:55], v[124:127], v[200:203], v[32:35]
	v_mfma_f32_16x16x32_bf16 v[32:35], v[164:167], v[196:199], v[56:59]
	v_mfma_f32_16x16x32_bf16 v[56:59], v[168:171], v[200:203], v[32:35]
	s_setprio 0
	s_barrier
; #define PG8_STAGE(bufoff, gbase, voff) do { _Pragma("unroll") for (int _i = 0; _i < 2; ++_i) \
;         __builtin_amdgcn_global_load_lds((const unsigned*)((const char*)(gbase) + (voff)[_i]), (PG8_LAS unsigned*)(lds + (bufoff) + ldsw + _i * 8192), 16, 0, 0); } while (0)
; #define PG8_LDA(dst, b, h) do { _Pragma("unroll") for (int m = 0; m < 4; ++m) _Pragma("unroll") for (int k = 0; k < 2; ++k) dst[m][k] = *(const PG8_LAS bf16x8*)(lds + PG8_SA(b, h) + aoff + m * 2048 + k * 1024); } while (0)
; #define PG8_LDB(dst, b, h) do { _Pragma("unroll") for (int n = 0; n < 2; ++n) _Pragma("unroll") for (int k = 0; k < 2; ++k) dst[n][k] = *(const PG8_LAS bf16x8*)(lds + PG8_SB(b, h) + boff + n * 2048 + k * 1024); } while (0)
; #define PG8_MMA(ai, bj, At, Bt) do { __builtin_amdgcn_s_setprio(1); _Pragma("unroll") for (int m = 0; m < 4; ++m) _Pragma("unroll") for (int n = 0; n < 2; ++n) _Pragma("unroll") for (int k = 0; k < 2; ++k) \
;         acc[ai][bj][m][n] = mma16<F16>(Bt[n][k], At[m][k], acc[ai][bj][m][n]); __builtin_amdgcn_s_setprio(0); } while (0)
; #define PG8_WAIT_V(n) asm volatile("s_waitcnt vmcnt(" #n ")" ::: "memory")
; #define PG8_WAIT_L(n) asm volatile("s_waitcnt lgkmcnt(" #n ")" ::: "memory")
; #define PG8_BAR __builtin_amdgcn_s_barrier()
; #define PG8_SCHED __builtin_amdgcn_sched_barrier(0)
; template <class Epi, class Sched, bool ALIGN_EPI = false, bool SP2 = false, bool F16 = false>
; __device__ __forceinline__ void gemm_phase(PG8_LAS unsigned char* lds, const Gemm g, const Sched& S, const Epi& E, const int wid_in) {
;     ...
;             PG8_WAIT_L(8); PG8_BAR; PG8_WAIT_L(0); PG8_MMA(0, 0, At, B0); PG8_BAR; PG8_SCHED;
;             PG8_LDB(B1, 0, 1); PG8_STAGE(PG8_SB(0, 0), b2, voffB);
;             PG8_BAR; PG8_WAIT_L(0); PG8_MMA(0, 1, At, B1); PG8_BAR;
;             PG8_LDA(At, 0, 1); PG8_STAGE(PG8_SA(0, 0), a2, voffA);
;             PG8_BAR; PG8_WAIT_L(0); PG8_MMA(1, 0, At, B0); PG8_BAR; PG8_SCHED;
;             PG8_STAGE(PG8_SB(0, 1), b2 + hstep, voffB);
;             PG8_WAIT_V(6); PG8_BAR; PG8_MMA(1, 1, At, B1); PG8_BAR;
;             PG8_LDB(B0, 1, 0); PG8_SCHED; PG8_LDA(At, 1, 0); PG8_STAGE(PG8_SA(0, 1), a2 + hstep, voffA);
	s_mov_b32 m0, s15
	v_lshl_add_u64 v[240:241], s[36:37], 0, v[130:131]
	s_add_u32 s46, s36, 0x10000
	s_nop 1
	ds_read_b128 v[32:35], v136 offset:16384
	ds_read_b128 v[36:39], v136 offset:17408
	ds_read_b128 v[96:99], v136 offset:18432
	ds_read_b128 v[180:183], v136 offset:19456
	ds_read_b128 v[184:187], v136 offset:20480
	ds_read_b128 v[188:191], v136 offset:21504
	ds_read_b128 v[192:195], v136 offset:22528
	ds_read_b128 v[196:199], v136 offset:23552
	global_load_lds_dwordx4 v[240:241], off
	v_lshl_add_u64 v[242:243], s[36:37], 0, v[128:129]
	s_mov_b32 m0, s50
	s_addc_u32 s47, s37, 0
	global_load_lds_dwordx4 v[242:243], off
	s_mov_b32 m0, s51
	v_lshl_add_u64 v[244:245], s[44:45], 0, v[130:131]
	global_load_lds_dwordx4 v130, s[46:47]
	s_mov_b32 m0, s52
	v_lshl_add_u64 v[246:247], s[44:45], 0, v[128:129]
	global_load_lds_dwordx4 v128, s[46:47]
	s_mov_b32 m0, s74
	s_nop 0
	global_load_lds_dwordx4 v[244:245], off
	s_mov_b32 m0, s66
	s_nop 0
	global_load_lds_dwordx4 v[246:247], off
	s_waitcnt vmcnt(8)
	s_waitcnt lgkmcnt(0)
	s_barrier
	s_setprio 1
	s_waitcnt lgkmcnt(0)
	v_mfma_f32_16x16x32_bf16 v[0:3], v[104:107], v[192:195], v[0:3]
	v_mfma_f32_16x16x32_bf16 v[140:143], v[104:107], v[32:35], v[140:143]
	v_mfma_f32_16x16x32_bf16 v[144:147], v[112:115], v[32:35], v[144:147]
	v_mfma_f32_16x16x32_bf16 v[148:151], v[104:107], v[96:99], v[148:151]
	v_mfma_f32_16x16x32_bf16 v[152:155], v[112:115], v[96:99], v[152:155]
	v_mfma_f32_16x16x32_bf16 v[156:159], v[104:107], v[184:187], v[156:159]
	v_mfma_f32_16x16x32_bf16 v[160:163], v[112:115], v[184:187], v[160:163]
	v_mfma_f32_16x16x32_bf16 v[0:3], v[108:111], v[196:199], v[0:3]
	v_mfma_f32_16x16x32_bf16 v[4:7], v[112:115], v[192:195], v[4:7]
	v_mfma_f32_16x16x32_bf16 v[140:143], v[108:111], v[36:39], v[140:143]
	v_mfma_f32_16x16x32_bf16 v[144:147], v[116:119], v[36:39], v[144:147]
	v_mfma_f32_16x16x32_bf16 v[148:151], v[108:111], v[180:183], v[148:151]
	v_mfma_f32_16x16x32_bf16 v[152:155], v[116:119], v[180:183], v[152:155]
	v_mfma_f32_16x16x32_bf16 v[156:159], v[108:111], v[188:191], v[156:159]
	v_mfma_f32_16x16x32_bf16 v[160:163], v[116:119], v[188:191], v[160:163]
	v_mfma_f32_16x16x32_bf16 v[200:203], v[116:119], v[196:199], v[4:7]
	s_setprio 0
	s_setprio 1
	v_mfma_f32_16x16x32_bf16 v[4:7], v[120:123], v[32:35], v[8:11]
	v_mfma_f32_16x16x32_bf16 v[8:11], v[124:127], v[36:39], v[4:7]
	v_mfma_f32_16x16x32_bf16 v[4:7], v[164:167], v[32:35], v[12:15]
	v_mfma_f32_16x16x32_bf16 v[12:15], v[168:171], v[36:39], v[4:7]
	v_mfma_f32_16x16x32_bf16 v[4:7], v[120:123], v[96:99], v[24:27]
	v_mfma_f32_16x16x32_bf16 v[24:27], v[124:127], v[180:183], v[4:7]
	v_mfma_f32_16x16x32_bf16 v[4:7], v[164:167], v[96:99], v[28:31]
	v_mfma_f32_16x16x32_bf16 v[28:31], v[168:171], v[180:183], v[4:7]
	v_mfma_f32_16x16x32_bf16 v[4:7], v[120:123], v[184:187], v[60:63]
	v_mfma_f32_16x16x32_bf16 v[180:183], v[124:127], v[188:191], v[4:7]
	v_mfma_f32_16x16x32_bf16 v[4:7], v[164:167], v[184:187], v[100:103]
	v_mfma_f32_16x16x32_bf16 v[184:187], v[168:171], v[188:191], v[4:7]
	v_mfma_f32_16x16x32_bf16 v[4:7], v[120:123], v[192:195], v[16:19]
	v_mfma_f32_16x16x32_bf16 v[188:191], v[124:127], v[196:199], v[4:7]
	v_mfma_f32_16x16x32_bf16 v[4:7], v[164:167], v[192:195], v[20:23]
	v_mfma_f32_16x16x32_bf16 v[164:167], v[168:171], v[196:199], v[4:7]
	s_setprio 0
	s_barrier
	s_nop 4
	ds_read_b128 v[4:7], v137
	ds_read_b128 v[60:63], v137 offset:1024
	ds_read_b128 v[168:171], v137 offset:2048
	ds_read_b128 v[192:195], v137 offset:3072
	ds_read_b128 v[196:199], v138
	ds_read_b128 v[208:211], v138 offset:1024
	ds_read_b128 v[212:215], v138 offset:2048
	ds_read_b128 v[216:219], v138 offset:3072
	s_add_u32 s44, s44, 0x10000
	s_addc_u32 s45, s45, 0
	s_mov_b32 m0, s90
	ds_read_b128 v[16:19], v136 offset:32768
	ds_read_b128 v[20:23], v136 offset:33792
	ds_read_b128 v[104:107], v136 offset:34816
	ds_read_b128 v[220:223], v136 offset:35840
	ds_read_b128 v[224:227], v136 offset:36864
	ds_read_b128 v[228:231], v136 offset:37888
	ds_read_b128 v[232:235], v136 offset:38912
	ds_read_b128 v[236:239], v136 offset:39936
	global_load_lds_dwordx4 v130, s[44:45]
	s_mov_b32 m0, s43
	s_nop 0
	global_load_lds_dwordx4 v128, s[44:45]
	s_waitcnt vmcnt(8)
	s_waitcnt lgkmcnt(0)
	s_barrier
; #define PG8_STAGE(bufoff, gbase, voff) do { _Pragma("unroll") for (int _i = 0; _i < 2; ++_i) \
;         __builtin_amdgcn_global_load_lds((const unsigned*)((const char*)(gbase) + (voff)[_i]), (PG8_LAS unsigned*)(lds + (bufoff) + ldsw + _i * 8192), 16, 0, 0); } while (0)
; #define PG8_LDA(dst, b, h) do { _Pragma("unroll") for (int m = 0; m < 4; ++m) _Pragma("unroll") for (int k = 0; k < 2; ++k) dst[m][k] = *(const PG8_LAS bf16x8*)(lds + PG8_SA(b, h) + aoff + m * 2048 + k * 1024); } while (0)
; #define PG8_LDB(dst, b, h) do { _Pragma("unroll") for (int n = 0; n < 2; ++n) _Pragma("unroll") for (int k = 0; k < 2; ++k) dst[n][k] = *(const PG8_LAS bf16x8*)(lds + PG8_SB(b, h) + boff + n * 2048 + k * 1024); } while (0)
; #define PG8_MMA(ai, bj, At, Bt) do { __builtin_amdgcn_s_setprio(1); _Pragma("unroll") for (int m = 0; m < 4; ++m) _Pragma("unroll") for (int n = 0; n < 2; ++n) _Pragma("unroll") for (int k = 0; k < 2; ++k) \
;         acc[ai][bj][m][n] = mma16<F16>(Bt[n][k], At[m][k], acc[ai][bj][m][n]); __builtin_amdgcn_s_setprio(0); } while (0)
; #define PG8_WAIT_V(n) asm volatile("s_waitcnt vmcnt(" #n ")" ::: "memory")
; #define PG8_WAIT_L(n) asm volatile("s_waitcnt lgkmcnt(" #n ")" ::: "memory")
; #define PG8_BAR __builtin_amdgcn_s_barrier()
; #define PG8_SCHED __builtin_amdgcn_sched_barrier(0)
; template <class Epi, class Sched, bool ALIGN_EPI = false, bool SP2 = false, bool F16 = false>
; __device__ __forceinline__ void gemm_phase(PG8_LAS unsigned char* lds, const Gemm g, const Sched& S, const Epi& E, const int wid_in) {
;     ...
;             PG8_LDB(B0, 1, 0); PG8_SCHED; PG8_LDA(At, 1, 0); PG8_STAGE(PG8_SA(0, 1), a2 + hstep, voffA);
;             PG8_WAIT_L(8); PG8_BAR; PG8_WAIT_L(0); PG8_MMA(0, 0, At, B0); PG8_BAR; PG8_SCHED;
;             PG8_LDB(B1, 1, 1); PG8_STAGE(PG8_SB(1, 0), b3, voffB);
;             PG8_BAR; PG8_WAIT_L(0); PG8_MMA(0, 1, At, B1); PG8_BAR;
;             PG8_LDA(At, 1, 1); PG8_STAGE(PG8_SA(1, 0), a3, voffA);
;             PG8_BAR; PG8_WAIT_L(0); PG8_MMA(1, 0, At, B0); PG8_BAR; PG8_SCHED;
;             PG8_STAGE(PG8_SB(1, 1), b3 + hstep, voffB);
;             PG8_WAIT_V(6); PG8_BAR; PG8_MMA(1, 1, At, B1); PG8_BAR;
;             }
;         }
;         if constexpr (ALIGN_EPI) { if (wr == 0) PG8_BAR; }
;         if constexpr (!Epi::AFTER_DRAIN) { E(acc, cur, wr, wc, fr, fq); S.done(cur); }
;         if (!has_next) break;
	s_setprio 1
	s_waitcnt lgkmcnt(0)
	v_mfma_f32_16x16x32_bf16 v[32:35], v[4:7], v[16:19], v[64:67]
	v_mfma_f32_16x16x32_bf16 v[116:119], v[60:63], v[20:23], v[32:35]
	v_mfma_f32_16x16x32_bf16 v[32:35], v[168:171], v[16:19], v[68:71]
	v_mfma_f32_16x16x32_bf16 v[112:115], v[192:195], v[20:23], v[32:35]
	v_mfma_f32_16x16x32_bf16 v[32:35], v[4:7], v[104:107], v[72:75]
	v_mfma_f32_16x16x32_bf16 v[100:103], v[60:63], v[220:223], v[32:35]
	v_mfma_f32_16x16x32_bf16 v[32:35], v[168:171], v[104:107], v[76:79]
	v_mfma_f32_16x16x32_bf16 v[96:99], v[192:195], v[220:223], v[32:35]
	v_mfma_f32_16x16x32_bf16 v[32:35], v[4:7], v[224:227], v[80:83]
	v_mfma_f32_16x16x32_bf16 v[68:71], v[60:63], v[228:231], v[32:35]
	v_mfma_f32_16x16x32_bf16 v[32:35], v[168:171], v[224:227], v[84:87]
	v_mfma_f32_16x16x32_bf16 v[64:67], v[192:195], v[228:231], v[32:35]
	v_mfma_f32_16x16x32_bf16 v[32:35], v[4:7], v[232:235], v[88:91]
	v_mfma_f32_16x16x32_bf16 v[36:39], v[60:63], v[236:239], v[32:35]
	v_mfma_f32_16x16x32_bf16 v[32:35], v[168:171], v[232:235], v[92:95]
	v_mfma_f32_16x16x32_bf16 v[32:35], v[192:195], v[236:239], v[32:35]
	s_setprio 0
	s_setprio 1
	v_mfma_f32_16x16x32_bf16 v[72:75], v[196:199], v[16:19], v[204:207]
	v_mfma_f32_16x16x32_bf16 v[16:19], v[212:215], v[16:19], v[172:175]
	v_mfma_f32_16x16x32_bf16 v[120:123], v[216:219], v[20:23], v[16:19]
	v_mfma_f32_16x16x32_bf16 v[16:19], v[196:199], v[104:107], v[176:179]
	v_mfma_f32_16x16x32_bf16 v[108:111], v[208:211], v[220:223], v[16:19]
	v_mfma_f32_16x16x32_bf16 v[16:19], v[212:215], v[104:107], v[40:43]
	v_mfma_f32_16x16x32_bf16 v[104:107], v[216:219], v[220:223], v[16:19]
	v_mfma_f32_16x16x32_bf16 v[16:19], v[196:199], v[224:227], v[44:47]
	v_mfma_f32_16x16x32_bf16 v[80:83], v[208:211], v[228:231], v[16:19]
	v_mfma_f32_16x16x32_bf16 v[16:19], v[212:215], v[224:227], v[48:51]
	v_mfma_f32_16x16x32_bf16 v[124:127], v[208:211], v[20:23], v[72:75]
	v_mfma_f32_16x16x32_bf16 v[72:75], v[216:219], v[228:231], v[16:19]
	v_mfma_f32_16x16x32_bf16 v[16:19], v[196:199], v[232:235], v[52:55]
	v_mfma_f32_16x16x32_bf16 v[48:51], v[208:211], v[236:239], v[16:19]
	v_mfma_f32_16x16x32_bf16 v[16:19], v[212:215], v[232:235], v[56:59]
	v_mfma_f32_16x16x32_bf16 v[40:43], v[216:219], v[236:239], v[16:19]
	s_setprio 0
	s_barrier
	s_mov_b32 m0, s53
	s_nop 3
	v_lshl_add_u64 v[16:17], v[240:241], 0, s[24:25]
	s_add_u32 s36, s36, 0x10080
	ds_read_b128 v[56:59], v136 offset:49152
	ds_read_b128 v[88:91], v136 offset:50176
	ds_read_b128 v[172:175], v136 offset:51200
	ds_read_b128 v[176:179], v136 offset:52224
	ds_read_b128 v[204:207], v136 offset:53248
	ds_read_b128 v[220:223], v136 offset:54272
	ds_read_b128 v[224:227], v136 offset:55296
	ds_read_b128 v[228:231], v136 offset:56320
	global_load_lds_dwordx4 v[16:17], off
	v_lshl_add_u64 v[16:17], v[242:243], 0, s[24:25]
	s_mov_b32 m0, s54
	s_addc_u32 s37, s37, 0
	global_load_lds_dwordx4 v[16:17], off
	s_mov_b32 m0, s55
	s_nop 0
	global_load_lds_dwordx4 v130, s[36:37]
	s_mov_b32 m0, s56
	s_nop 0
	global_load_lds_dwordx4 v128, s[36:37]
	v_lshl_add_u64 v[16:17], v[244:245], 0, s[24:25]
	s_mov_b32 m0, s75
	s_nop 0
	global_load_lds_dwordx4 v[16:17], off
	v_lshl_add_u64 v[16:17], v[246:247], 0, s[24:25]
	s_mov_b32 m0, s67
	s_nop 0
	global_load_lds_dwordx4 v[16:17], off
	s_waitcnt vmcnt(8)
	s_waitcnt lgkmcnt(0)
	s_barrier
	s_setprio 1
	s_waitcnt lgkmcnt(0)
	v_mfma_f32_16x16x32_bf16 v[16:19], v[4:7], v[56:59], v[140:143]
	v_mfma_f32_16x16x32_bf16 v[84:87], v[60:63], v[88:91], v[16:19]
	v_mfma_f32_16x16x32_bf16 v[16:19], v[168:171], v[56:59], v[144:147]
	v_mfma_f32_16x16x32_bf16 v[76:79], v[192:195], v[88:91], v[16:19]
	v_mfma_f32_16x16x32_bf16 v[16:19], v[4:7], v[172:175], v[148:151]
	v_mfma_f32_16x16x32_bf16 v[52:55], v[60:63], v[176:179], v[16:19]
	v_mfma_f32_16x16x32_bf16 v[16:19], v[168:171], v[172:175], v[152:155]
	v_mfma_f32_16x16x32_bf16 v[44:47], v[192:195], v[176:179], v[16:19]
	v_mfma_f32_16x16x32_bf16 v[16:19], v[4:7], v[204:207], v[156:159]
	v_mfma_f32_16x16x32_bf16 v[0:3], v[4:7], v[224:227], v[0:3]
	v_mfma_f32_16x16x32_bf16 v[20:23], v[60:63], v[220:223], v[16:19]
	v_mfma_f32_16x16x32_bf16 v[16:19], v[168:171], v[204:207], v[160:163]
	v_mfma_f32_16x16x32_bf16 v[4:7], v[60:63], v[228:231], v[0:3]
	v_mfma_f32_16x16x32_bf16 v[0:3], v[168:171], v[224:227], v[200:203]
	v_mfma_f32_16x16x32_bf16 v[16:19], v[192:195], v[220:223], v[16:19]
	v_mfma_f32_16x16x32_bf16 v[0:3], v[192:195], v[228:231], v[0:3]
	s_setprio 0
	s_setprio 1
	v_mfma_f32_16x16x32_bf16 v[8:11], v[196:199], v[56:59], v[8:11]
	v_mfma_f32_16x16x32_bf16 v[92:95], v[208:211], v[88:91], v[8:11]
	v_mfma_f32_16x16x32_bf16 v[8:11], v[212:215], v[56:59], v[12:15]
	v_mfma_f32_16x16x32_bf16 v[88:91], v[216:219], v[88:91], v[8:11]
	v_mfma_f32_16x16x32_bf16 v[8:11], v[196:199], v[172:175], v[24:27]
	v_mfma_f32_16x16x32_bf16 v[60:63], v[208:211], v[176:179], v[8:11]
	v_mfma_f32_16x16x32_bf16 v[8:11], v[212:215], v[172:175], v[28:31]
	v_mfma_f32_16x16x32_bf16 v[56:59], v[216:219], v[176:179], v[8:11]
	v_mfma_f32_16x16x32_bf16 v[8:11], v[196:199], v[204:207], v[180:183]
	v_mfma_f32_16x16x32_bf16 v[28:31], v[208:211], v[220:223], v[8:11]
	v_mfma_f32_16x16x32_bf16 v[8:11], v[212:215], v[204:207], v[184:187]
	v_mfma_f32_16x16x32_bf16 v[24:27], v[216:219], v[220:223], v[8:11]
	v_mfma_f32_16x16x32_bf16 v[8:11], v[196:199], v[224:227], v[188:191]
	v_mfma_f32_16x16x32_bf16 v[12:15], v[208:211], v[228:231], v[8:11]
	v_mfma_f32_16x16x32_bf16 v[8:11], v[212:215], v[224:227], v[164:167]
	v_mfma_f32_16x16x32_bf16 v[8:11], v[216:219], v[228:231], v[8:11]
	s_setprio 0
	s_barrier
	s_and_b64 vcc, exec, s[8:9]
	s_cbranch_vccnz .LBB0_1946
	s_barrier

; #define PG8_STAGE(bufoff, gbase, voff) do { _Pragma("unroll") for (int _i = 0; _i < 2; ++_i) \
;         __builtin_amdgcn_global_load_lds((const unsigned*)((const char*)(gbase) + (voff)[_i]), (PG8_LAS unsigned*)(lds + (bufoff) + ldsw + _i * 8192), 16, 0, 0); } while (0)
; #define PG8_WAIT_V(n) asm volatile("s_waitcnt vmcnt(" #n ")" ::: "memory")
; #define PG8_BAR __builtin_amdgcn_s_barrier()
; template <class Epi, class Sched, bool ALIGN_EPI = false, bool SP2 = false, bool F16 = false>
; __device__ __forceinline__ void gemm_phase(PG8_LAS unsigned char* lds, const Gemm g, const Sched& S, const Epi& E, const int wid_in) {
;     ...
;     const int K = g.K, nt = K / BK;
;     unsigned voffA[2], voffB[2];
; #pragma unroll
;     for (int i = 0; i < 2; ++i) { int R, C; stage_rc(tid * 16 + i * 8192, R, C); const int Rb = Epi::PERM ? ((R & ~31) + perm32(R & 31)) : R;
;         voffA[i] = (unsigned)(R * K + C) * 2u; voffB[i] = (unsigned)(Rb * K + C) * 2u; }
;     const size_t kstep = (size_t)(BK * 2);
;     const size_t hstep = (size_t)HALF * K * 2;
;     const size_t tstep = 2 * hstep;
;     const unsigned ldsw = (unsigned)wid * 1024u;
;     const int aoff = lds_byte(wr * 64 + fr, fq * 8), boff = lds_byte(wc * 32 + fr, fq * 8);
;     ...
;         PG8_STAGE(PG8_SB(1, 0), cB + kstep, voffB); PG8_STAGE(PG8_SA(1, 0), cA + kstep, voffA); PG8_STAGE(PG8_SB(1, 1), cB + hstep + kstep, voffB);
;         PG8_WAIT_V(6); PG8_BAR;
.LBB0_2026:
	s_add_u32 s24, s11, 0x15400000
	s_addc_u32 s25, s12, 0
	s_add_u32 s26, s11, 0x7400000
	s_addc_u32 s27, s12, 0
	s_add_u32 s28, s11, 0x13400000
	s_mov_b64 s[30:31], 0x80
	s_addc_u32 s29, s12, 0
	s_add_i32 m0, s74, 0x18000
	v_lshl_add_u64 v[6:7], v[6:7], 0, s[30:31]
	s_waitcnt vmcnt(2)
	s_barrier
	global_load_lds_dwordx4 v[6:7], off
	v_lshl_add_u64 v[4:5], v[4:5], 0, s[30:31]
	s_add_i32 m0, s74, 0x1a000
	v_lshl_add_u64 v[0:1], v[0:1], 0, s[30:31]
	global_load_lds_dwordx4 v[4:5], off
	s_mov_b32 m0, s75
	s_add_u32 s12, s44, 0xb0080
	global_load_lds_dwordx4 v[0:1], off
	v_lshl_add_u64 v[0:1], v[2:3], 0, s[30:31]
	s_mov_b32 m0, s67
	s_addc_u32 s13, s45, 0
	global_load_lds_dwordx4 v[0:1], off
	s_add_i32 m0, s74, 0x1c000
	s_nop 0
	global_load_lds_dwordx4 v154, s[12:13]
	s_add_i32 m0, s74, 0x1e000
	v_and_b32_e32 v187, 15, v8
	global_load_lds_dwordx4 v158, s[12:13]
	v_or_b32_e32 v0, s70, v187
	v_lshlrev_b32_e32 v1, 6, v0
	v_and_b32_e32 v2, 48, v8
	s_movk_i32 s11, 0x3c0
	v_and_b32_e32 v3, 0xfffffc00, v13
	v_lshlrev_b32_e32 v0, 2, v0
	v_and_or_b32 v1, v1, s11, v2
	v_add_u32_e32 v4, s73, v3
	v_and_b32_e32 v0, 32, v0
	v_bitop3_b32 v4, v1, v4, v0 bitop3:0xde
	v_lshl_or_b32 v0, v187, 6, v2
	v_lshlrev_b32_e32 v2, 2, v8
	v_add_u32_e32 v1, s72, v3
	v_and_b32_e32 v2, 32, v2
	v_bitop3_b32 v188, v0, v1, v2 bitop3:0xde
	v_lshrrev_b32_e32 v1, 1, v9
	v_mul_lo_u32 v0, v11, s10
	s_mov_b32 s11, 0xb000
	v_mad_u64_u32 v[0:1], s[34:35], v1, s11, v[0:1]
	v_or_b32_e32 v0, v0, v10
	s_mov_b64 s[12:13], 0xb0080
	v_add_lshl_u32 v0, v0, v12, 1
	v_mov_b32_e32 v1, v155
	v_lshl_add_u64 v[160:161], v[0:1], 0, s[12:13]
	v_lshrrev_b32_e32 v1, 1, v14
	v_mul_lo_u32 v0, v15, s10
	v_mad_u64_u32 v[0:1], s[10:11], v1, s11, v[0:1]
	s_waitcnt vmcnt(6)
	v_or_b32_e32 v0, v0, v16
	v_add_lshl_u32 v0, v0, v17, 1
	v_mov_b32_e32 v1, v155
	s_add_i32 s53, 0, 0x10000
	s_add_i32 s54, 0, 0x14000
	v_ashrrev_i32_e32 v186, 4, v8
	s_ashr_i32 s50, s38, 31
	s_mov_b32 s51, s38
	s_ashr_i32 s52, s14, 31
	v_lshl_add_u64 v[162:163], v[0:1], 0, s[12:13]
	v_mov_b64_e32 v[164:165], 0x100
	v_mov_b64_e32 v[166:167], 0xff
	v_add_u32_e32 v189, s53, v188
	v_add_u32_e32 v190, s54, v188
	v_add_u32_e32 v191, 0, v4
	s_mov_b32 s55, 0
	s_barrier
	s_branch .LBB0_2029

; #define PG8_STAGE(bufoff, gbase, voff) do { _Pragma("unroll") for (int _i = 0; _i < 2; ++_i) \
;         __builtin_amdgcn_global_load_lds((const unsigned*)((const char*)(gbase) + (voff)[_i]), (PG8_LAS unsigned*)(lds + (bufoff) + ldsw + _i * 8192), 16, 0, 0); } while (0)
; #define PG8_LDA(dst, b, h) do { _Pragma("unroll") for (int m = 0; m < 4; ++m) _Pragma("unroll") for (int k = 0; k < 2; ++k) dst[m][k] = *(const PG8_LAS bf16x8*)(lds + PG8_SA(b, h) + aoff + m * 2048 + k * 1024); } while (0)
; #define PG8_LDB(dst, b, h) do { _Pragma("unroll") for (int n = 0; n < 2; ++n) _Pragma("unroll") for (int k = 0; k < 2; ++k) dst[n][k] = *(const PG8_LAS bf16x8*)(lds + PG8_SB(b, h) + boff + n * 2048 + k * 1024); } while (0)
; #define PG8_MMA(ai, bj, At, Bt) do { __builtin_amdgcn_s_setprio(1); _Pragma("unroll") for (int m = 0; m < 4; ++m) _Pragma("unroll") for (int n = 0; n < 2; ++n) _Pragma("unroll") for (int k = 0; k < 2; ++k) \
;         acc[ai][bj][m][n] = mma16<F16>(Bt[n][k], At[m][k], acc[ai][bj][m][n]); __builtin_amdgcn_s_setprio(0); } while (0)
; #define PG8_WAIT_V(n) asm volatile("s_waitcnt vmcnt(" #n ")" ::: "memory")
; #define PG8_WAIT_L(n) asm volatile("s_waitcnt lgkmcnt(" #n ")" ::: "memory")
; #define PG8_BAR __builtin_amdgcn_s_barrier()
; #define PG8_SCHED __builtin_amdgcn_sched_barrier(0)
; template <class Epi, class Sched, bool ALIGN_EPI = false, bool SP2 = false, bool F16 = false>
; __device__ __forceinline__ void gemm_phase(PG8_LAS unsigned char* lds, const Gemm g, const Sched& S, const Epi& E, const int wid_in) {
;     ...
;             PG8_LDB(B0, 0, 0); PG8_LDB(B1, 0, 1); PG8_SCHED; PG8_LDA(At, 0, 0); PG8_STAGE(PG8_SA(1, 1), a1 + hstep, voffA);
;             PG8_WAIT_V(8); PG8_WAIT_L(0); PG8_BAR; PG8_MMA(0, 0, At, B0); PG8_MMA(0, 1, At, B1); PG8_BAR; PG8_SCHED;
;             PG8_LDA(At, 0, 1); PG8_STAGE(PG8_SB(0, 0), b2, voffB); PG8_STAGE(PG8_SB(0, 1), b2 + hstep, voffB); PG8_STAGE(PG8_SA(0, 0), a2, voffA);
;             PG8_WAIT_V(8); PG8_WAIT_L(0); PG8_BAR; PG8_MMA(1, 0, At, B0); PG8_MMA(1, 1, At, B1); PG8_BAR; PG8_SCHED;
.LBB0_2040:
	ds_read_b128 v[128:131], v189
	ds_read_b128 v[132:135], v189 offset:1024
	ds_read_b128 v[136:139], v189 offset:2048
	ds_read_b128 v[140:143], v189 offset:3072
	ds_read_b128 v[144:147], v190
	ds_read_b128 v[148:151], v190 offset:1024
	ds_read_b128 v[168:171], v190 offset:2048
	ds_read_b128 v[172:175], v190 offset:3072
	s_add_u32 s44, s36, 0x100
	s_addc_u32 s45, s37, 0
	s_cmp_eq_u32 s59, 40
	s_cselect_b32 s49, s13, s45
	s_cselect_b32 s48, s12, s44
	s_cselect_b32 s47, s35, s58
	s_cselect_b32 s46, s34, s43
	s_mov_b32 m0, s91
	v_lshl_add_u64 v[184:185], s[36:37], 0, v[160:161]
	ds_read_b128 v[176:179], v191
	ds_read_b128 v[180:183], v191 offset:1024
	ds_read_b128 v[192:195], v191 offset:2048
	ds_read_b128 v[196:199], v191 offset:3072
	ds_read_b128 v[200:203], v191 offset:4096
	ds_read_b128 v[204:207], v191 offset:5120
	ds_read_b128 v[208:211], v191 offset:6144
	ds_read_b128 v[212:215], v191 offset:7168
	global_load_lds_dwordx4 v[184:185], off
	v_lshl_add_u64 v[184:185], s[36:37], 0, v[162:163]
	s_add_i32 m0, s74, 0xe000
	s_nop 0
	global_load_lds_dwordx4 v[184:185], off
	s_waitcnt vmcnt(8)
	s_waitcnt lgkmcnt(0)
	s_barrier
	s_setprio 1
	s_waitcnt lgkmcnt(0)
	v_mfma_f32_16x16x32_bf16 v[124:127], v[128:131], v[176:179], v[124:127]
	v_mfma_f32_16x16x32_bf16 v[120:123], v[136:139], v[176:179], v[120:123]
	v_mfma_f32_16x16x32_bf16 v[108:111], v[128:131], v[192:195], v[108:111]
	v_mfma_f32_16x16x32_bf16 v[104:107], v[136:139], v[192:195], v[104:107]
	v_mfma_f32_16x16x32_bf16 v[92:95], v[128:131], v[200:203], v[92:95]
	v_mfma_f32_16x16x32_bf16 v[88:91], v[136:139], v[200:203], v[88:91]
	v_mfma_f32_16x16x32_bf16 v[76:79], v[128:131], v[208:211], v[76:79]
	v_mfma_f32_16x16x32_bf16 v[72:75], v[136:139], v[208:211], v[72:75]
	v_mfma_f32_16x16x32_bf16 v[124:127], v[132:135], v[180:183], v[124:127]
	v_mfma_f32_16x16x32_bf16 v[120:123], v[140:143], v[180:183], v[120:123]
	v_mfma_f32_16x16x32_bf16 v[108:111], v[132:135], v[196:199], v[108:111]
	v_mfma_f32_16x16x32_bf16 v[104:107], v[140:143], v[196:199], v[104:107]
	v_mfma_f32_16x16x32_bf16 v[92:95], v[132:135], v[204:207], v[92:95]
	v_mfma_f32_16x16x32_bf16 v[88:91], v[140:143], v[204:207], v[88:91]
	v_mfma_f32_16x16x32_bf16 v[76:79], v[132:135], v[212:215], v[76:79]
	v_mfma_f32_16x16x32_bf16 v[72:75], v[140:143], v[212:215], v[72:75]
	s_setprio 0
	s_setprio 1
	v_mfma_f32_16x16x32_bf16 v[116:119], v[144:147], v[176:179], v[116:119]
	v_mfma_f32_16x16x32_bf16 v[112:115], v[168:171], v[176:179], v[112:115]
	v_mfma_f32_16x16x32_bf16 v[100:103], v[144:147], v[192:195], v[100:103]
	v_mfma_f32_16x16x32_bf16 v[96:99], v[168:171], v[192:195], v[96:99]
	v_mfma_f32_16x16x32_bf16 v[84:87], v[144:147], v[200:203], v[84:87]
	v_mfma_f32_16x16x32_bf16 v[80:83], v[168:171], v[200:203], v[80:83]
	v_mfma_f32_16x16x32_bf16 v[68:71], v[144:147], v[208:211], v[68:71]
	v_mfma_f32_16x16x32_bf16 v[64:67], v[168:171], v[208:211], v[64:67]
	v_mfma_f32_16x16x32_bf16 v[116:119], v[148:151], v[180:183], v[116:119]
	v_mfma_f32_16x16x32_bf16 v[112:115], v[172:175], v[180:183], v[112:115]
	v_mfma_f32_16x16x32_bf16 v[100:103], v[148:151], v[196:199], v[100:103]
	v_mfma_f32_16x16x32_bf16 v[96:99], v[172:175], v[196:199], v[96:99]
	v_mfma_f32_16x16x32_bf16 v[84:87], v[148:151], v[204:207], v[84:87]
	v_mfma_f32_16x16x32_bf16 v[80:83], v[172:175], v[204:207], v[80:83]
	v_mfma_f32_16x16x32_bf16 v[68:71], v[148:151], v[212:215], v[68:71]
	v_mfma_f32_16x16x32_bf16 v[64:67], v[172:175], v[212:215], v[64:67]
	s_setprio 0
	s_barrier
	s_add_i32 s36, s53, s68
	v_lshl_add_u64 v[184:185], s[46:47], 0, v[154:155]
	s_mov_b32 m0, s36
	ds_read_b128 v[176:179], v191 offset:16384
	ds_read_b128 v[180:183], v191 offset:17408
	ds_read_b128 v[192:195], v191 offset:18432
	ds_read_b128 v[196:199], v191 offset:19456
	ds_read_b128 v[200:203], v191 offset:20480
	ds_read_b128 v[204:207], v191 offset:21504
	ds_read_b128 v[208:211], v191 offset:22528
	ds_read_b128 v[212:215], v191 offset:23552
	global_load_lds_dwordx4 v[184:185], off
	s_add_i32 m0, s36, 0x2000
	s_add_u32 s36, s46, 0xb0000
	v_lshl_add_u64 v[216:217], s[46:47], 0, v[158:159]
	s_addc_u32 s37, s47, 0
	s_add_i32 s60, s54, s68
	global_load_lds_dwordx4 v[216:217], off
	s_mov_b32 m0, s60
	v_lshl_add_u64 v[220:221], s[48:49], 0, v[156:157]
	global_load_lds_dwordx4 v154, s[36:37]
	s_add_i32 m0, s60, 0x2000
	s_nop 0
	global_load_lds_dwordx4 v158, s[36:37]
	v_lshl_add_u64 v[218:219], s[48:49], 0, v[152:153]
	s_mov_b32 m0, s74
	s_nop 0
	global_load_lds_dwordx4 v[218:219], off
	s_mov_b32 m0, s66
	s_nop 0
	global_load_lds_dwordx4 v[220:221], off
	s_waitcnt vmcnt(8)
	s_waitcnt lgkmcnt(0)
	s_barrier
; #define PG8_STAGE(bufoff, gbase, voff) do { _Pragma("unroll") for (int _i = 0; _i < 2; ++_i) \
;         __builtin_amdgcn_global_load_lds((const unsigned*)((const char*)(gbase) + (voff)[_i]), (PG8_LAS unsigned*)(lds + (bufoff) + ldsw + _i * 8192), 16, 0, 0); } while (0)
; #define PG8_LDA(dst, b, h) do { _Pragma("unroll") for (int m = 0; m < 4; ++m) _Pragma("unroll") for (int k = 0; k < 2; ++k) dst[m][k] = *(const PG8_LAS bf16x8*)(lds + PG8_SA(b, h) + aoff + m * 2048 + k * 1024); } while (0)
; #define PG8_LDB(dst, b, h) do { _Pragma("unroll") for (int n = 0; n < 2; ++n) _Pragma("unroll") for (int k = 0; k < 2; ++k) dst[n][k] = *(const PG8_LAS bf16x8*)(lds + PG8_SB(b, h) + boff + n * 2048 + k * 1024); } while (0)
; #define PG8_MMA(ai, bj, At, Bt) do { __builtin_amdgcn_s_setprio(1); _Pragma("unroll") for (int m = 0; m < 4; ++m) _Pragma("unroll") for (int n = 0; n < 2; ++n) _Pragma("unroll") for (int k = 0; k < 2; ++k) \
;         acc[ai][bj][m][n] = mma16<F16>(Bt[n][k], At[m][k], acc[ai][bj][m][n]); __builtin_amdgcn_s_setprio(0); } while (0)
; #define PG8_WAIT_V(n) asm volatile("s_waitcnt vmcnt(" #n ")" ::: "memory")
; #define PG8_WAIT_L(n) asm volatile("s_waitcnt lgkmcnt(" #n ")" ::: "memory")
; #define PG8_BAR __builtin_amdgcn_s_barrier()
; #define PG8_SCHED __builtin_amdgcn_sched_barrier(0)
; template <class Epi, class Sched, bool ALIGN_EPI = false, bool SP2 = false, bool F16 = false>
; __device__ __forceinline__ void gemm_phase(PG8_LAS unsigned char* lds, const Gemm g, const Sched& S, const Epi& E, const int wid_in) {
;     ...
;             PG8_WAIT_V(8); PG8_WAIT_L(0); PG8_BAR; PG8_MMA(1, 0, At, B0); PG8_MMA(1, 1, At, B1); PG8_BAR; PG8_SCHED;
;             PG8_LDB(B0, 1, 0); PG8_LDB(B1, 1, 1); PG8_SCHED; PG8_LDA(At, 1, 0); PG8_STAGE(PG8_SA(0, 1), a2 + hstep, voffA);
;             PG8_WAIT_V(8); PG8_WAIT_L(0); PG8_BAR; PG8_MMA(0, 0, At, B0); PG8_MMA(0, 1, At, B1); PG8_BAR; PG8_SCHED;
	s_setprio 1
	s_waitcnt lgkmcnt(0)
	v_mfma_f32_16x16x32_bf16 v[60:63], v[128:131], v[176:179], v[60:63]
	v_mfma_f32_16x16x32_bf16 v[56:59], v[136:139], v[176:179], v[56:59]
	v_mfma_f32_16x16x32_bf16 v[44:47], v[128:131], v[192:195], v[44:47]
	v_mfma_f32_16x16x32_bf16 v[40:43], v[136:139], v[192:195], v[40:43]
	v_mfma_f32_16x16x32_bf16 v[28:31], v[128:131], v[200:203], v[28:31]
	v_mfma_f32_16x16x32_bf16 v[24:27], v[136:139], v[200:203], v[24:27]
	v_mfma_f32_16x16x32_bf16 v[12:15], v[128:131], v[208:211], v[12:15]
	v_mfma_f32_16x16x32_bf16 v[8:11], v[136:139], v[208:211], v[8:11]
	v_mfma_f32_16x16x32_bf16 v[60:63], v[132:135], v[180:183], v[60:63]
	v_mfma_f32_16x16x32_bf16 v[56:59], v[140:143], v[180:183], v[56:59]
	v_mfma_f32_16x16x32_bf16 v[44:47], v[132:135], v[196:199], v[44:47]
	v_mfma_f32_16x16x32_bf16 v[40:43], v[140:143], v[196:199], v[40:43]
	v_mfma_f32_16x16x32_bf16 v[28:31], v[132:135], v[204:207], v[28:31]
	v_mfma_f32_16x16x32_bf16 v[24:27], v[140:143], v[204:207], v[24:27]
	v_mfma_f32_16x16x32_bf16 v[12:15], v[132:135], v[212:215], v[12:15]
	v_mfma_f32_16x16x32_bf16 v[8:11], v[140:143], v[212:215], v[8:11]
	s_setprio 0
	s_setprio 1
	v_mfma_f32_16x16x32_bf16 v[52:55], v[144:147], v[176:179], v[52:55]
	v_mfma_f32_16x16x32_bf16 v[48:51], v[168:171], v[176:179], v[48:51]
	v_mfma_f32_16x16x32_bf16 v[36:39], v[144:147], v[192:195], v[36:39]
	v_mfma_f32_16x16x32_bf16 v[32:35], v[168:171], v[192:195], v[32:35]
	v_mfma_f32_16x16x32_bf16 v[20:23], v[144:147], v[200:203], v[20:23]
	v_mfma_f32_16x16x32_bf16 v[16:19], v[168:171], v[200:203], v[16:19]
	v_mfma_f32_16x16x32_bf16 v[4:7], v[144:147], v[208:211], v[4:7]
	v_mfma_f32_16x16x32_bf16 v[0:3], v[168:171], v[208:211], v[0:3]
	v_mfma_f32_16x16x32_bf16 v[52:55], v[148:151], v[180:183], v[52:55]
	v_mfma_f32_16x16x32_bf16 v[48:51], v[172:175], v[180:183], v[48:51]
	v_mfma_f32_16x16x32_bf16 v[36:39], v[148:151], v[196:199], v[36:39]
	v_mfma_f32_16x16x32_bf16 v[32:35], v[172:175], v[196:199], v[32:35]
	v_mfma_f32_16x16x32_bf16 v[20:23], v[148:151], v[204:207], v[20:23]
	v_mfma_f32_16x16x32_bf16 v[16:19], v[172:175], v[204:207], v[16:19]
	v_mfma_f32_16x16x32_bf16 v[4:7], v[148:151], v[212:215], v[4:7]
	v_mfma_f32_16x16x32_bf16 v[0:3], v[172:175], v[212:215], v[0:3]
	s_setprio 0
	s_barrier
	s_add_i32 s60, 0, 0x18000
	s_add_i32 s61, 0, 0x1c000
	v_add_u32_e32 v140, s60, v188
	v_add_u32_e32 v172, s61, v188
	ds_read_b128 v[128:131], v140
	ds_read_b128 v[132:135], v140 offset:1024
	ds_read_b128 v[136:139], v140 offset:2048
	ds_read_b128 v[140:143], v140 offset:3072
	ds_read_b128 v[144:147], v172
	ds_read_b128 v[148:151], v172 offset:1024
	ds_read_b128 v[168:171], v172 offset:2048
	ds_read_b128 v[172:175], v172 offset:3072
	s_add_u32 s36, s48, 0xb0000
	s_addc_u32 s37, s49, 0
	s_mov_b32 m0, s90
	ds_read_b128 v[176:179], v191 offset:32768
	ds_read_b128 v[180:183], v191 offset:33792
	ds_read_b128 v[192:195], v191 offset:34816
	ds_read_b128 v[196:199], v191 offset:35840
	ds_read_b128 v[200:203], v191 offset:36864
	ds_read_b128 v[204:207], v191 offset:37888
	ds_read_b128 v[208:211], v191 offset:38912
	ds_read_b128 v[212:215], v191 offset:39936
	global_load_lds_dwordx4 v152, s[36:37]
	v_lshl_add_u64 v[222:223], s[36:37], 0, v[156:157]
	s_mov_b32 m0, s41
	s_nop 0
	global_load_lds_dwordx4 v[222:223], off
	s_waitcnt vmcnt(8)
	s_waitcnt lgkmcnt(0)
	s_barrier
	s_setprio 1
	s_waitcnt lgkmcnt(0)
	v_mfma_f32_16x16x32_bf16 v[124:127], v[128:131], v[176:179], v[124:127]
	v_mfma_f32_16x16x32_bf16 v[120:123], v[136:139], v[176:179], v[120:123]
	v_mfma_f32_16x16x32_bf16 v[108:111], v[128:131], v[192:195], v[108:111]
	v_mfma_f32_16x16x32_bf16 v[104:107], v[136:139], v[192:195], v[104:107]
	v_mfma_f32_16x16x32_bf16 v[92:95], v[128:131], v[200:203], v[92:95]
	v_mfma_f32_16x16x32_bf16 v[88:91], v[136:139], v[200:203], v[88:91]
	v_mfma_f32_16x16x32_bf16 v[76:79], v[128:131], v[208:211], v[76:79]
	v_mfma_f32_16x16x32_bf16 v[72:75], v[136:139], v[208:211], v[72:75]
	v_mfma_f32_16x16x32_bf16 v[124:127], v[132:135], v[180:183], v[124:127]
	v_mfma_f32_16x16x32_bf16 v[120:123], v[140:143], v[180:183], v[120:123]
	v_mfma_f32_16x16x32_bf16 v[108:111], v[132:135], v[196:199], v[108:111]
	v_mfma_f32_16x16x32_bf16 v[104:107], v[140:143], v[196:199], v[104:107]
	v_mfma_f32_16x16x32_bf16 v[92:95], v[132:135], v[204:207], v[92:95]
	v_mfma_f32_16x16x32_bf16 v[88:91], v[140:143], v[204:207], v[88:91]
	v_mfma_f32_16x16x32_bf16 v[76:79], v[132:135], v[212:215], v[76:79]
	v_mfma_f32_16x16x32_bf16 v[72:75], v[140:143], v[212:215], v[72:75]
	s_setprio 0
	s_setprio 1
	v_mfma_f32_16x16x32_bf16 v[116:119], v[144:147], v[176:179], v[116:119]
	v_mfma_f32_16x16x32_bf16 v[112:115], v[168:171], v[176:179], v[112:115]
	v_mfma_f32_16x16x32_bf16 v[100:103], v[144:147], v[192:195], v[100:103]
	v_mfma_f32_16x16x32_bf16 v[96:99], v[168:171], v[192:195], v[96:99]
	v_mfma_f32_16x16x32_bf16 v[84:87], v[144:147], v[200:203], v[84:87]
	v_mfma_f32_16x16x32_bf16 v[80:83], v[168:171], v[200:203], v[80:83]
	v_mfma_f32_16x16x32_bf16 v[68:71], v[144:147], v[208:211], v[68:71]
	v_mfma_f32_16x16x32_bf16 v[64:67], v[168:171], v[208:211], v[64:67]
	v_mfma_f32_16x16x32_bf16 v[116:119], v[148:151], v[180:183], v[116:119]
	v_mfma_f32_16x16x32_bf16 v[112:115], v[172:175], v[180:183], v[112:115]
	v_mfma_f32_16x16x32_bf16 v[100:103], v[148:151], v[196:199], v[100:103]
	v_mfma_f32_16x16x32_bf16 v[96:99], v[172:175], v[196:199], v[96:99]
	v_mfma_f32_16x16x32_bf16 v[84:87], v[148:151], v[204:207], v[84:87]
	v_mfma_f32_16x16x32_bf16 v[80:83], v[172:175], v[204:207], v[80:83]
	v_mfma_f32_16x16x32_bf16 v[68:71], v[148:151], v[212:215], v[68:71]
	v_mfma_f32_16x16x32_bf16 v[64:67], v[172:175], v[212:215], v[64:67]
	s_setprio 0
	s_barrier
; #define PG8_STAGE(bufoff, gbase, voff) do { _Pragma("unroll") for (int _i = 0; _i < 2; ++_i) \
;         __builtin_amdgcn_global_load_lds((const unsigned*)((const char*)(gbase) + (voff)[_i]), (PG8_LAS unsigned*)(lds + (bufoff) + ldsw + _i * 8192), 16, 0, 0); } while (0)
; #define PG8_LDA(dst, b, h) do { _Pragma("unroll") for (int m = 0; m < 4; ++m) _Pragma("unroll") for (int k = 0; k < 2; ++k) dst[m][k] = *(const PG8_LAS bf16x8*)(lds + PG8_SA(b, h) + aoff + m * 2048 + k * 1024); } while (0)
; #define PG8_MMA(ai, bj, At, Bt) do { __builtin_amdgcn_s_setprio(1); _Pragma("unroll") for (int m = 0; m < 4; ++m) _Pragma("unroll") for (int n = 0; n < 2; ++n) _Pragma("unroll") for (int k = 0; k < 2; ++k) \
;         acc[ai][bj][m][n] = mma16<F16>(Bt[n][k], At[m][k], acc[ai][bj][m][n]); __builtin_amdgcn_s_setprio(0); } while (0)
; #define PG8_WAIT_V(n) asm volatile("s_waitcnt vmcnt(" #n ")" ::: "memory")
; #define PG8_WAIT_L(n) asm volatile("s_waitcnt lgkmcnt(" #n ")" ::: "memory")
; #define PG8_BAR __builtin_amdgcn_s_barrier()
; #define PG8_SCHED __builtin_amdgcn_sched_barrier(0)
; template <class Epi, class Sched, bool ALIGN_EPI = false, bool SP2 = false, bool F16 = false>
; __device__ __forceinline__ void gemm_phase(PG8_LAS unsigned char* lds, const Gemm g, const Sched& S, const Epi& E, const int wid_in) {
;     ...
;             PG8_LDA(At, 1, 1); PG8_STAGE(PG8_SB(1, 0), b3, voffB); PG8_STAGE(PG8_SB(1, 1), b3 + hstep, voffB); PG8_STAGE(PG8_SA(1, 0), a3, voffA);
;             PG8_WAIT_V(8); PG8_WAIT_L(0); PG8_BAR; PG8_MMA(1, 0, At, B0); PG8_MMA(1, 1, At, B1); PG8_BAR; PG8_SCHED;
	s_add_i32 s36, s60, s68
	v_lshl_add_u64 v[184:185], v[184:185], 0, s[30:31]
	s_mov_b32 m0, s36
	ds_read_b128 v[176:179], v191 offset:49152
	ds_read_b128 v[180:183], v191 offset:50176
	ds_read_b128 v[192:195], v191 offset:51200
	ds_read_b128 v[196:199], v191 offset:52224
	ds_read_b128 v[200:203], v191 offset:53248
	ds_read_b128 v[204:207], v191 offset:54272
	ds_read_b128 v[208:211], v191 offset:55296
	ds_read_b128 v[212:215], v191 offset:56320
	global_load_lds_dwordx4 v[184:185], off
	s_add_i32 m0, s36, 0x2000
	s_add_u32 s36, s46, 0xb0080
	v_lshl_add_u64 v[184:185], v[216:217], 0, s[30:31]
	s_addc_u32 s37, s47, 0
	s_add_i32 s46, s61, s68
	global_load_lds_dwordx4 v[184:185], off
	s_mov_b32 m0, s46
	s_nop 0
	global_load_lds_dwordx4 v154, s[36:37]
	s_add_i32 m0, s46, 0x2000
	s_nop 0
	global_load_lds_dwordx4 v158, s[36:37]
	v_lshl_add_u64 v[184:185], v[218:219], 0, s[30:31]
	s_mov_b32 m0, s75
	s_nop 0
	global_load_lds_dwordx4 v[184:185], off
	v_lshl_add_u64 v[184:185], v[220:221], 0, s[30:31]
	s_mov_b32 m0, s67
	s_nop 0
	global_load_lds_dwordx4 v[184:185], off
	s_waitcnt vmcnt(8)
	s_waitcnt lgkmcnt(0)
	s_barrier
	s_setprio 1
	s_waitcnt lgkmcnt(0)
	v_mfma_f32_16x16x32_bf16 v[60:63], v[128:131], v[176:179], v[60:63]
	v_mfma_f32_16x16x32_bf16 v[56:59], v[136:139], v[176:179], v[56:59]
	v_mfma_f32_16x16x32_bf16 v[44:47], v[128:131], v[192:195], v[44:47]
	v_mfma_f32_16x16x32_bf16 v[40:43], v[136:139], v[192:195], v[40:43]
	v_mfma_f32_16x16x32_bf16 v[28:31], v[128:131], v[200:203], v[28:31]
	v_mfma_f32_16x16x32_bf16 v[24:27], v[136:139], v[200:203], v[24:27]
	v_mfma_f32_16x16x32_bf16 v[12:15], v[128:131], v[208:211], v[12:15]
	v_mfma_f32_16x16x32_bf16 v[8:11], v[136:139], v[208:211], v[8:11]
	v_mfma_f32_16x16x32_bf16 v[60:63], v[132:135], v[180:183], v[60:63]
	v_mfma_f32_16x16x32_bf16 v[56:59], v[140:143], v[180:183], v[56:59]
	v_mfma_f32_16x16x32_bf16 v[44:47], v[132:135], v[196:199], v[44:47]
	v_mfma_f32_16x16x32_bf16 v[40:43], v[140:143], v[196:199], v[40:43]
	v_mfma_f32_16x16x32_bf16 v[28:31], v[132:135], v[204:207], v[28:31]
	v_mfma_f32_16x16x32_bf16 v[24:27], v[140:143], v[204:207], v[24:27]
	v_mfma_f32_16x16x32_bf16 v[12:15], v[132:135], v[212:215], v[12:15]
	v_mfma_f32_16x16x32_bf16 v[8:11], v[140:143], v[212:215], v[8:11]
	s_setprio 0
	s_setprio 1
	v_mfma_f32_16x16x32_bf16 v[52:55], v[144:147], v[176:179], v[52:55]
	v_mfma_f32_16x16x32_bf16 v[48:51], v[168:171], v[176:179], v[48:51]
	v_mfma_f32_16x16x32_bf16 v[36:39], v[144:147], v[192:195], v[36:39]
	v_mfma_f32_16x16x32_bf16 v[32:35], v[168:171], v[192:195], v[32:35]
	v_mfma_f32_16x16x32_bf16 v[20:23], v[144:147], v[200:203], v[20:23]
	v_mfma_f32_16x16x32_bf16 v[16:19], v[168:171], v[200:203], v[16:19]
	v_mfma_f32_16x16x32_bf16 v[4:7], v[144:147], v[208:211], v[4:7]
	v_mfma_f32_16x16x32_bf16 v[0:3], v[168:171], v[208:211], v[0:3]
	v_mfma_f32_16x16x32_bf16 v[52:55], v[148:151], v[180:183], v[52:55]
	v_mfma_f32_16x16x32_bf16 v[48:51], v[172:175], v[180:183], v[48:51]
	v_mfma_f32_16x16x32_bf16 v[36:39], v[148:151], v[196:199], v[36:39]
	v_mfma_f32_16x16x32_bf16 v[32:35], v[172:175], v[196:199], v[32:35]
	v_mfma_f32_16x16x32_bf16 v[20:23], v[148:151], v[204:207], v[20:23]
	v_mfma_f32_16x16x32_bf16 v[16:19], v[172:175], v[204:207], v[16:19]
	v_mfma_f32_16x16x32_bf16 v[4:7], v[148:151], v[212:215], v[4:7]
	v_mfma_f32_16x16x32_bf16 v[0:3], v[172:175], v[212:215], v[0:3]
	s_setprio 0
	s_barrier
	s_add_i32 s59, s59, 2
	s_add_u32 s43, s43, 0x100
	s_addc_u32 s58, s58, 0
	s_cmp_gt_u32 s59, 41
	s_mov_b64 s[36:37], s[44:45]
	s_cbranch_scc0 .LBB0_2040
	s_and_b64 vcc, exec, s[16:17]
	s_cbranch_vccz .LBB0_2043
	s_barrier

; #define PG8_STAGE(bufoff, gbase, voff) do { _Pragma("unroll") for (int _i = 0; _i < 2; ++_i) \
;         __builtin_amdgcn_global_load_lds((const unsigned*)((const char*)(gbase) + (voff)[_i]), (PG8_LAS unsigned*)(lds + (bufoff) + ldsw + _i * 8192), 16, 0, 0); } while (0)
; #define PG8_WAIT_V(n) asm volatile("s_waitcnt vmcnt(" #n ")" ::: "memory")
; #define PG8_BAR __builtin_amdgcn_s_barrier()
; template <class Epi, class Sched, bool ALIGN_EPI = false, bool SP2 = false, bool F16 = false>
; __device__ __forceinline__ void gemm_phase(PG8_LAS unsigned char* lds, const Gemm g, const Sched& S, const Epi& E, const int wid_in) {
;     ...
;     for (int i = 0; i < 2; ++i) { int R, C; stage_rc(tid * 16 + i * 8192, R, C); const int Rb = Epi::PERM ? ((R & ~31) + perm32(R & 31)) : R;
;         voffA[i] = (unsigned)(R * K + C) * 2u; voffB[i] = (unsigned)(Rb * K + C) * 2u; }
;     const size_t kstep = (size_t)(BK * 2);
;     const size_t hstep = (size_t)HALF * K * 2;
;     const size_t tstep = 2 * hstep;
;     const unsigned ldsw = (unsigned)wid * 1024u;
;     const int aoff = lds_byte(wr * 64 + fr, fq * 8), boff = lds_byte(wc * 32 + fr, fq * 8);
;     ...
;         PG8_STAGE(PG8_SB(1, 0), cB + kstep, voffB); PG8_STAGE(PG8_SA(1, 0), cA + kstep, voffA); PG8_STAGE(PG8_SB(1, 1), cB + hstep + kstep, voffB);
;         PG8_WAIT_V(6); PG8_BAR;
.LBB0_2126:
	s_add_u32 s24, s10, 0x15400000
	s_addc_u32 s25, s11, 0
	s_add_u32 s26, s10, 0x7400000
	s_addc_u32 s27, s11, 0
	s_add_u32 s28, s10, 0xf400000
	s_addc_u32 s29, s11, 0
	s_add_u32 s30, s10, 0x15500000
	s_mov_b64 s[34:35], 0x80
	s_addc_u32 s31, s11, 0
	s_add_i32 m0, s74, 0x18000
	v_lshl_add_u64 v[6:7], v[6:7], 0, s[34:35]
	s_waitcnt vmcnt(2)
	s_barrier
	global_load_lds_dwordx4 v[6:7], off
	v_lshl_add_u64 v[4:5], v[4:5], 0, s[34:35]
	s_add_i32 m0, s74, 0x1a000
	v_lshl_add_u64 v[0:1], v[0:1], 0, s[34:35]
	global_load_lds_dwordx4 v[4:5], off
	s_mov_b32 m0, s75
	s_add_u32 s10, s54, 0x40080
	global_load_lds_dwordx4 v[0:1], off
	v_lshl_add_u64 v[0:1], v[2:3], 0, s[34:35]
	s_mov_b32 m0, s67
	s_addc_u32 s11, s55, 0
	global_load_lds_dwordx4 v[0:1], off
	s_add_i32 m0, s74, 0x1c000
	s_nop 0
	global_load_lds_dwordx4 v198, s[10:11]
	s_add_i32 m0, s74, 0x1e000
	v_and_b32_e32 v232, 15, v8
	global_load_lds_dwordx4 v202, s[10:11]
	v_or_b32_e32 v0, s70, v232
	v_lshlrev_b32_e32 v1, 6, v0
	v_and_b32_e32 v2, 48, v8
	s_movk_i32 s10, 0x3c0
	v_and_b32_e32 v3, 0xfffffc00, v12
	v_lshlrev_b32_e32 v0, 2, v0
	v_and_or_b32 v1, v1, s10, v2
	v_add_u32_e32 v4, s73, v3
	v_and_b32_e32 v0, 32, v0
	v_bitop3_b32 v0, v1, v4, v0 bitop3:0xde
	v_lshl_or_b32 v1, v232, 6, v2
	v_add_u32_e32 v2, s72, v3
	v_lshlrev_b32_e32 v3, 2, v8
	v_and_b32_e32 v3, 32, v3
	v_bitop3_b32 v234, v1, v2, v3 bitop3:0xde
	v_lshlrev_b32_e32 v1, 14, v9
	v_and_b32_e32 v1, 0xffff8000, v1
	v_lshl_add_u32 v1, v10, 11, v1
	v_and_b32_e32 v2, 1, v9
	v_lshl_or_b32 v1, v2, 6, v1
	v_lshl_add_u32 v204, v11, 1, v1
	v_lshlrev_b32_e32 v1, 14, v13
	v_and_b32_e32 v1, 0xffff8000, v1
	s_waitcnt vmcnt(6)
	v_lshl_add_u32 v1, v14, 11, v1
	v_and_b32_e32 v2, 1, v13
	v_lshl_or_b32 v1, v2, 6, v1
	s_add_i32 s63, 0, 0x10000
	s_add_i32 s64, 0, 0x14000
	v_ashrrev_i32_e32 v233, 4, v8
	s_ashr_i32 s60, s38, 31
	s_mov_b32 s61, s38
	s_ashr_i32 s62, s19, 31
	v_mov_b32_e32 v205, v199
	v_lshl_add_u32 v206, v15, 1, v1
	v_mov_b32_e32 v207, v199
	v_mov_b64_e32 v[208:209], 0x100
	v_mov_b64_e32 v[210:211], 0xff
	v_add_u32_e32 v235, s63, v234
	v_add_u32_e32 v236, s64, v234
	v_add_u32_e32 v237, 0, v0
	v_mov_b32_e32 v238, 0x358637bd
	s_mov_b32 s65, 0
	s_barrier
	s_branch .LBB0_2129

; #define PG8_STAGE(bufoff, gbase, voff) do { _Pragma("unroll") for (int _i = 0; _i < 2; ++_i) \
;         __builtin_amdgcn_global_load_lds((const unsigned*)((const char*)(gbase) + (voff)[_i]), (PG8_LAS unsigned*)(lds + (bufoff) + ldsw + _i * 8192), 16, 0, 0); } while (0)
; #define PG8_LDA(dst, b, h) do { _Pragma("unroll") for (int m = 0; m < 4; ++m) _Pragma("unroll") for (int k = 0; k < 2; ++k) dst[m][k] = *(const PG8_LAS bf16x8*)(lds + PG8_SA(b, h) + aoff + m * 2048 + k * 1024); } while (0)
; #define PG8_LDB(dst, b, h) do { _Pragma("unroll") for (int n = 0; n < 2; ++n) _Pragma("unroll") for (int k = 0; k < 2; ++k) dst[n][k] = *(const PG8_LAS bf16x8*)(lds + PG8_SB(b, h) + boff + n * 2048 + k * 1024); } while (0)
; #define PG8_MMA(ai, bj, At, Bt) do { __builtin_amdgcn_s_setprio(1); _Pragma("unroll") for (int m = 0; m < 4; ++m) _Pragma("unroll") for (int n = 0; n < 2; ++n) _Pragma("unroll") for (int k = 0; k < 2; ++k) \
;         acc[ai][bj][m][n] = mma16<F16>(Bt[n][k], At[m][k], acc[ai][bj][m][n]); __builtin_amdgcn_s_setprio(0); } while (0)
; #define PG8_WAIT_V(n) asm volatile("s_waitcnt vmcnt(" #n ")" ::: "memory")
; #define PG8_WAIT_L(n) asm volatile("s_waitcnt lgkmcnt(" #n ")" ::: "memory")
; #define PG8_BAR __builtin_amdgcn_s_barrier()
; #define PG8_SCHED __builtin_amdgcn_sched_barrier(0)
; template <class Epi, class Sched, bool ALIGN_EPI = false, bool SP2 = false, bool F16 = false>
; __device__ __forceinline__ void gemm_phase(PG8_LAS unsigned char* lds, const Gemm g, const Sched& S, const Epi& E, const int wid_in) {
;     ...
;             PG8_LDB(B0, 0, 0); PG8_LDB(B1, 0, 1); PG8_SCHED; PG8_LDA(At, 0, 0); PG8_STAGE(PG8_SA(1, 1), a1 + hstep, voffA);
;             PG8_WAIT_V(8); PG8_WAIT_L(0); PG8_BAR; PG8_MMA(0, 0, At, B0); PG8_MMA(0, 1, At, B1); PG8_BAR; PG8_SCHED;
;             PG8_LDA(At, 0, 1); PG8_STAGE(PG8_SB(0, 0), b2, voffB); PG8_STAGE(PG8_SB(0, 1), b2 + hstep, voffB); PG8_STAGE(PG8_SA(0, 0), a2, voffA);
;             PG8_WAIT_V(8); PG8_WAIT_L(0); PG8_BAR; PG8_MMA(1, 0, At, B0); PG8_MMA(1, 1, At, B1); PG8_BAR; PG8_SCHED;
.LBB0_2136:
	ds_read_b128 v[112:115], v235
	ds_read_b128 v[116:119], v235 offset:1024
	ds_read_b128 v[128:131], v235 offset:2048
	ds_read_b128 v[132:135], v235 offset:3072
	ds_read_b128 v[144:147], v236
	ds_read_b128 v[148:151], v236 offset:1024
	ds_read_b128 v[152:155], v236 offset:2048
	ds_read_b128 v[156:159], v236 offset:3072
	s_add_u32 s45, s52, 0xfffc0080
	s_addc_u32 s51, s53, -1
	s_cmp_eq_u32 s43, 12
	s_cselect_b32 s57, s14, s51
	s_cselect_b32 s56, s15, s45
	s_cselect_b32 s55, s37, s42
	s_cselect_b32 s54, s40, s41
	s_mov_b32 m0, s91
	ds_read_b128 v[160:163], v237
	ds_read_b128 v[164:167], v237 offset:1024
	ds_read_b128 v[168:171], v237 offset:2048
	ds_read_b128 v[172:175], v237 offset:3072
	ds_read_b128 v[176:179], v237 offset:4096
	ds_read_b128 v[180:183], v237 offset:5120
	ds_read_b128 v[184:187], v237 offset:6144
	ds_read_b128 v[188:191], v237 offset:7168
	global_load_lds_dwordx4 v204, s[52:53]
	s_add_i32 m0, s74, 0xe000
	s_nop 0
	global_load_lds_dwordx4 v206, s[52:53]
	s_waitcnt vmcnt(8)
	s_waitcnt lgkmcnt(0)
	s_barrier
	s_setprio 1
	s_waitcnt lgkmcnt(0)
	v_mfma_f32_16x16x32_f16 v[140:143], v[112:115], v[160:163], v[140:143]
	v_mfma_f32_16x16x32_f16 v[136:139], v[128:131], v[160:163], v[136:139]
	v_mfma_f32_16x16x32_f16 v[108:111], v[112:115], v[168:171], v[108:111]
	v_mfma_f32_16x16x32_f16 v[104:107], v[128:131], v[168:171], v[104:107]
	v_mfma_f32_16x16x32_f16 v[92:95], v[112:115], v[176:179], v[92:95]
	v_mfma_f32_16x16x32_f16 v[88:91], v[128:131], v[176:179], v[88:91]
	v_mfma_f32_16x16x32_f16 v[76:79], v[112:115], v[184:187], v[76:79]
	v_mfma_f32_16x16x32_f16 v[72:75], v[128:131], v[184:187], v[72:75]
	v_mfma_f32_16x16x32_f16 v[140:143], v[116:119], v[164:167], v[140:143]
	v_mfma_f32_16x16x32_f16 v[136:139], v[132:135], v[164:167], v[136:139]
	v_mfma_f32_16x16x32_f16 v[108:111], v[116:119], v[172:175], v[108:111]
	v_mfma_f32_16x16x32_f16 v[104:107], v[132:135], v[172:175], v[104:107]
	v_mfma_f32_16x16x32_f16 v[92:95], v[116:119], v[180:183], v[92:95]
	v_mfma_f32_16x16x32_f16 v[88:91], v[132:135], v[180:183], v[88:91]
	v_mfma_f32_16x16x32_f16 v[76:79], v[116:119], v[188:191], v[76:79]
	v_mfma_f32_16x16x32_f16 v[72:75], v[132:135], v[188:191], v[72:75]
	s_setprio 0
	s_setprio 1
	v_mfma_f32_16x16x32_f16 v[124:127], v[144:147], v[160:163], v[124:127]
	v_mfma_f32_16x16x32_f16 v[120:123], v[152:155], v[160:163], v[120:123]
	v_mfma_f32_16x16x32_f16 v[100:103], v[144:147], v[168:171], v[100:103]
	v_mfma_f32_16x16x32_f16 v[96:99], v[152:155], v[168:171], v[96:99]
	v_mfma_f32_16x16x32_f16 v[84:87], v[144:147], v[176:179], v[84:87]
	v_mfma_f32_16x16x32_f16 v[80:83], v[152:155], v[176:179], v[80:83]
	v_mfma_f32_16x16x32_f16 v[68:71], v[144:147], v[184:187], v[68:71]
	v_mfma_f32_16x16x32_f16 v[64:67], v[152:155], v[184:187], v[64:67]
	v_mfma_f32_16x16x32_f16 v[124:127], v[148:151], v[164:167], v[124:127]
	v_mfma_f32_16x16x32_f16 v[120:123], v[156:159], v[164:167], v[120:123]
	v_mfma_f32_16x16x32_f16 v[100:103], v[148:151], v[172:175], v[100:103]
	v_mfma_f32_16x16x32_f16 v[96:99], v[156:159], v[172:175], v[96:99]
	v_mfma_f32_16x16x32_f16 v[84:87], v[148:151], v[180:183], v[84:87]
	v_mfma_f32_16x16x32_f16 v[80:83], v[156:159], v[180:183], v[80:83]
	v_mfma_f32_16x16x32_f16 v[68:71], v[148:151], v[188:191], v[68:71]
	v_mfma_f32_16x16x32_f16 v[64:67], v[156:159], v[188:191], v[64:67]
	s_setprio 0
	s_barrier
	s_add_i32 s45, s63, s68
	v_lshl_add_u64 v[192:193], s[54:55], 0, v[198:199]
	s_mov_b32 m0, s45
	ds_read_b128 v[160:163], v237 offset:16384
	ds_read_b128 v[164:167], v237 offset:17408
	ds_read_b128 v[168:171], v237 offset:18432
	ds_read_b128 v[172:175], v237 offset:19456
	ds_read_b128 v[176:179], v237 offset:20480
	ds_read_b128 v[180:183], v237 offset:21504
	ds_read_b128 v[184:187], v237 offset:22528
	ds_read_b128 v[188:191], v237 offset:23552
	global_load_lds_dwordx4 v[192:193], off
	s_add_i32 m0, s45, 0x2000
	s_add_u32 s84, s54, 0x40000
	v_lshl_add_u64 v[194:195], s[54:55], 0, v[202:203]
	s_addc_u32 s85, s55, 0
	s_add_i32 s45, s64, s68
	global_load_lds_dwordx4 v[194:195], off
	s_mov_b32 m0, s45
	v_lshl_add_u64 v[214:215], s[56:57], 0, v[200:201]
	global_load_lds_dwordx4 v198, s[84:85]
	s_add_i32 m0, s45, 0x2000
	s_nop 0
	global_load_lds_dwordx4 v202, s[84:85]
	v_lshl_add_u64 v[212:213], s[56:57], 0, v[196:197]
	s_mov_b32 m0, s74
	s_nop 0
	global_load_lds_dwordx4 v[212:213], off
	s_mov_b32 m0, s66
	s_nop 0
	global_load_lds_dwordx4 v[214:215], off
	s_waitcnt vmcnt(8)
	s_waitcnt lgkmcnt(0)
	s_barrier
	s_setprio 1
	s_waitcnt lgkmcnt(0)
	v_mfma_f32_16x16x32_f16 v[60:63], v[112:115], v[160:163], v[60:63]
	v_mfma_f32_16x16x32_f16 v[56:59], v[128:131], v[160:163], v[56:59]
	v_mfma_f32_16x16x32_f16 v[44:47], v[112:115], v[168:171], v[44:47]
	v_mfma_f32_16x16x32_f16 v[40:43], v[128:131], v[168:171], v[40:43]
	v_mfma_f32_16x16x32_f16 v[28:31], v[112:115], v[176:179], v[28:31]
	v_mfma_f32_16x16x32_f16 v[24:27], v[128:131], v[176:179], v[24:27]
	v_mfma_f32_16x16x32_f16 v[12:15], v[112:115], v[184:187], v[12:15]
	v_mfma_f32_16x16x32_f16 v[8:11], v[128:131], v[184:187], v[8:11]
	v_mfma_f32_16x16x32_f16 v[60:63], v[116:119], v[164:167], v[60:63]
	v_mfma_f32_16x16x32_f16 v[56:59], v[132:135], v[164:167], v[56:59]
	v_mfma_f32_16x16x32_f16 v[44:47], v[116:119], v[172:175], v[44:47]
	v_mfma_f32_16x16x32_f16 v[40:43], v[132:135], v[172:175], v[40:43]
	v_mfma_f32_16x16x32_f16 v[28:31], v[116:119], v[180:183], v[28:31]
	v_mfma_f32_16x16x32_f16 v[24:27], v[132:135], v[180:183], v[24:27]
	v_mfma_f32_16x16x32_f16 v[12:15], v[116:119], v[188:191], v[12:15]
	v_mfma_f32_16x16x32_f16 v[8:11], v[132:135], v[188:191], v[8:11]
	s_setprio 0
	s_setprio 1
	v_mfma_f32_16x16x32_f16 v[52:55], v[144:147], v[160:163], v[52:55]
	v_mfma_f32_16x16x32_f16 v[48:51], v[152:155], v[160:163], v[48:51]
	v_mfma_f32_16x16x32_f16 v[36:39], v[144:147], v[168:171], v[36:39]
	v_mfma_f32_16x16x32_f16 v[32:35], v[152:155], v[168:171], v[32:35]
	v_mfma_f32_16x16x32_f16 v[20:23], v[144:147], v[176:179], v[20:23]
	v_mfma_f32_16x16x32_f16 v[16:19], v[152:155], v[176:179], v[16:19]
	v_mfma_f32_16x16x32_f16 v[4:7], v[144:147], v[184:187], v[4:7]
	v_mfma_f32_16x16x32_f16 v[0:3], v[152:155], v[184:187], v[0:3]
	v_mfma_f32_16x16x32_f16 v[52:55], v[148:151], v[164:167], v[52:55]
	v_mfma_f32_16x16x32_f16 v[48:51], v[156:159], v[164:167], v[48:51]
	v_mfma_f32_16x16x32_f16 v[36:39], v[148:151], v[172:175], v[36:39]
	v_mfma_f32_16x16x32_f16 v[32:35], v[156:159], v[172:175], v[32:35]
	v_mfma_f32_16x16x32_f16 v[20:23], v[148:151], v[180:183], v[20:23]
	v_mfma_f32_16x16x32_f16 v[16:19], v[156:159], v[180:183], v[16:19]
	v_mfma_f32_16x16x32_f16 v[4:7], v[148:151], v[188:191], v[4:7]
	v_mfma_f32_16x16x32_f16 v[0:3], v[156:159], v[188:191], v[0:3]
	s_setprio 0
	s_barrier
; #define PG8_STAGE(bufoff, gbase, voff) do { _Pragma("unroll") for (int _i = 0; _i < 2; ++_i) \
;         __builtin_amdgcn_global_load_lds((const unsigned*)((const char*)(gbase) + (voff)[_i]), (PG8_LAS unsigned*)(lds + (bufoff) + ldsw + _i * 8192), 16, 0, 0); } while (0)
; #define PG8_LDA(dst, b, h) do { _Pragma("unroll") for (int m = 0; m < 4; ++m) _Pragma("unroll") for (int k = 0; k < 2; ++k) dst[m][k] = *(const PG8_LAS bf16x8*)(lds + PG8_SA(b, h) + aoff + m * 2048 + k * 1024); } while (0)
; #define PG8_LDB(dst, b, h) do { _Pragma("unroll") for (int n = 0; n < 2; ++n) _Pragma("unroll") for (int k = 0; k < 2; ++k) dst[n][k] = *(const PG8_LAS bf16x8*)(lds + PG8_SB(b, h) + boff + n * 2048 + k * 1024); } while (0)
; #define PG8_MMA(ai, bj, At, Bt) do { __builtin_amdgcn_s_setprio(1); _Pragma("unroll") for (int m = 0; m < 4; ++m) _Pragma("unroll") for (int n = 0; n < 2; ++n) _Pragma("unroll") for (int k = 0; k < 2; ++k) \
;         acc[ai][bj][m][n] = mma16<F16>(Bt[n][k], At[m][k], acc[ai][bj][m][n]); __builtin_amdgcn_s_setprio(0); } while (0)
; #define PG8_WAIT_V(n) asm volatile("s_waitcnt vmcnt(" #n ")" ::: "memory")
; #define PG8_WAIT_L(n) asm volatile("s_waitcnt lgkmcnt(" #n ")" ::: "memory")
; #define PG8_BAR __builtin_amdgcn_s_barrier()
; #define PG8_SCHED __builtin_amdgcn_sched_barrier(0)
; template <class Epi, class Sched, bool ALIGN_EPI = false, bool SP2 = false, bool F16 = false>
; __device__ __forceinline__ void gemm_phase(PG8_LAS unsigned char* lds, const Gemm g, const Sched& S, const Epi& E, const int wid_in) {
;     ...
;             PG8_LDB(B0, 1, 0); PG8_LDB(B1, 1, 1); PG8_SCHED; PG8_LDA(At, 1, 0); PG8_STAGE(PG8_SA(0, 1), a2 + hstep, voffA);
;             PG8_WAIT_V(8); PG8_WAIT_L(0); PG8_BAR; PG8_MMA(0, 0, At, B0); PG8_MMA(0, 1, At, B1); PG8_BAR; PG8_SCHED;
;             PG8_LDA(At, 1, 1); PG8_STAGE(PG8_SB(1, 0), b3, voffB); PG8_STAGE(PG8_SB(1, 1), b3 + hstep, voffB); PG8_STAGE(PG8_SA(1, 0), a3, voffA);
;             PG8_WAIT_V(8); PG8_WAIT_L(0); PG8_BAR; PG8_MMA(1, 0, At, B0); PG8_MMA(1, 1, At, B1); PG8_BAR; PG8_SCHED;
	s_add_i32 s45, 0, 0x18000
	s_add_i32 s51, 0, 0x1c000
	v_add_u32_e32 v132, s45, v234
	v_add_u32_e32 v156, s51, v234
	ds_read_b128 v[112:115], v132
	ds_read_b128 v[116:119], v132 offset:1024
	ds_read_b128 v[128:131], v132 offset:2048
	ds_read_b128 v[132:135], v132 offset:3072
	ds_read_b128 v[144:147], v156
	ds_read_b128 v[148:151], v156 offset:1024
	ds_read_b128 v[152:155], v156 offset:2048
	ds_read_b128 v[156:159], v156 offset:3072
	s_add_u32 s56, s56, 0x40000
	s_addc_u32 s57, s57, 0
	s_mov_b32 m0, s90
	ds_read_b128 v[160:163], v237 offset:32768
	ds_read_b128 v[164:167], v237 offset:33792
	ds_read_b128 v[168:171], v237 offset:34816
	ds_read_b128 v[172:175], v237 offset:35840
	ds_read_b128 v[176:179], v237 offset:36864
	ds_read_b128 v[180:183], v237 offset:37888
	ds_read_b128 v[184:187], v237 offset:38912
	ds_read_b128 v[188:191], v237 offset:39936
	global_load_lds_dwordx4 v196, s[56:57]
	s_mov_b32 m0, s59
	s_nop 0
	global_load_lds_dwordx4 v200, s[56:57]
	s_waitcnt vmcnt(8)
	s_waitcnt lgkmcnt(0)
	s_barrier
	s_setprio 1
	s_waitcnt lgkmcnt(0)
	v_mfma_f32_16x16x32_f16 v[140:143], v[112:115], v[160:163], v[140:143]
	v_mfma_f32_16x16x32_f16 v[136:139], v[128:131], v[160:163], v[136:139]
	v_mfma_f32_16x16x32_f16 v[108:111], v[112:115], v[168:171], v[108:111]
	v_mfma_f32_16x16x32_f16 v[104:107], v[128:131], v[168:171], v[104:107]
	v_mfma_f32_16x16x32_f16 v[92:95], v[112:115], v[176:179], v[92:95]
	v_mfma_f32_16x16x32_f16 v[88:91], v[128:131], v[176:179], v[88:91]
	v_mfma_f32_16x16x32_f16 v[76:79], v[112:115], v[184:187], v[76:79]
	v_mfma_f32_16x16x32_f16 v[72:75], v[128:131], v[184:187], v[72:75]
	v_mfma_f32_16x16x32_f16 v[140:143], v[116:119], v[164:167], v[140:143]
	v_mfma_f32_16x16x32_f16 v[136:139], v[132:135], v[164:167], v[136:139]
	v_mfma_f32_16x16x32_f16 v[108:111], v[116:119], v[172:175], v[108:111]
	v_mfma_f32_16x16x32_f16 v[104:107], v[132:135], v[172:175], v[104:107]
	v_mfma_f32_16x16x32_f16 v[92:95], v[116:119], v[180:183], v[92:95]
	v_mfma_f32_16x16x32_f16 v[88:91], v[132:135], v[180:183], v[88:91]
	v_mfma_f32_16x16x32_f16 v[76:79], v[116:119], v[188:191], v[76:79]
	v_mfma_f32_16x16x32_f16 v[72:75], v[132:135], v[188:191], v[72:75]
	s_setprio 0
	s_setprio 1
	v_mfma_f32_16x16x32_f16 v[124:127], v[144:147], v[160:163], v[124:127]
	v_mfma_f32_16x16x32_f16 v[120:123], v[152:155], v[160:163], v[120:123]
	v_mfma_f32_16x16x32_f16 v[100:103], v[144:147], v[168:171], v[100:103]
	v_mfma_f32_16x16x32_f16 v[96:99], v[152:155], v[168:171], v[96:99]
	v_mfma_f32_16x16x32_f16 v[84:87], v[144:147], v[176:179], v[84:87]
	v_mfma_f32_16x16x32_f16 v[80:83], v[152:155], v[176:179], v[80:83]
	v_mfma_f32_16x16x32_f16 v[68:71], v[144:147], v[184:187], v[68:71]
	v_mfma_f32_16x16x32_f16 v[64:67], v[152:155], v[184:187], v[64:67]
	v_mfma_f32_16x16x32_f16 v[124:127], v[148:151], v[164:167], v[124:127]
	v_mfma_f32_16x16x32_f16 v[120:123], v[156:159], v[164:167], v[120:123]
	v_mfma_f32_16x16x32_f16 v[100:103], v[148:151], v[172:175], v[100:103]
	v_mfma_f32_16x16x32_f16 v[96:99], v[156:159], v[172:175], v[96:99]
	v_mfma_f32_16x16x32_f16 v[84:87], v[148:151], v[180:183], v[84:87]
	v_mfma_f32_16x16x32_f16 v[80:83], v[156:159], v[180:183], v[80:83]
	v_mfma_f32_16x16x32_f16 v[68:71], v[148:151], v[188:191], v[68:71]
	v_mfma_f32_16x16x32_f16 v[64:67], v[156:159], v[188:191], v[64:67]
	s_setprio 0
	s_barrier
	s_add_i32 s45, s45, s68
	v_lshl_add_u64 v[192:193], v[192:193], 0, s[34:35]
	s_mov_b32 m0, s45
	ds_read_b128 v[160:163], v237 offset:49152
	ds_read_b128 v[164:167], v237 offset:50176
	ds_read_b128 v[168:171], v237 offset:51200
	ds_read_b128 v[172:175], v237 offset:52224
	ds_read_b128 v[176:179], v237 offset:53248
	ds_read_b128 v[180:183], v237 offset:54272
	ds_read_b128 v[184:187], v237 offset:55296
	ds_read_b128 v[188:191], v237 offset:56320
	global_load_lds_dwordx4 v[192:193], off
	s_add_i32 m0, s45, 0x2000
	s_add_u32 s54, s54, 0x40080
	v_lshl_add_u64 v[192:193], v[194:195], 0, s[34:35]
	s_addc_u32 s55, s55, 0
	s_add_i32 s45, s51, s68
	global_load_lds_dwordx4 v[192:193], off
	s_mov_b32 m0, s45
	s_nop 0
	global_load_lds_dwordx4 v198, s[54:55]
	s_add_i32 m0, s45, 0x2000
	s_nop 0
	global_load_lds_dwordx4 v202, s[54:55]
	v_lshl_add_u64 v[192:193], v[212:213], 0, s[34:35]
	s_mov_b32 m0, s75
	s_nop 0
	global_load_lds_dwordx4 v[192:193], off
	v_lshl_add_u64 v[192:193], v[214:215], 0, s[34:35]
	s_mov_b32 m0, s67
	s_nop 0
	global_load_lds_dwordx4 v[192:193], off
	s_waitcnt vmcnt(8)
	s_waitcnt lgkmcnt(0)
	s_barrier
	s_setprio 1
	s_waitcnt lgkmcnt(0)
	v_mfma_f32_16x16x32_f16 v[60:63], v[112:115], v[160:163], v[60:63]
	v_mfma_f32_16x16x32_f16 v[56:59], v[128:131], v[160:163], v[56:59]
	v_mfma_f32_16x16x32_f16 v[44:47], v[112:115], v[168:171], v[44:47]
	v_mfma_f32_16x16x32_f16 v[40:43], v[128:131], v[168:171], v[40:43]
	v_mfma_f32_16x16x32_f16 v[28:31], v[112:115], v[176:179], v[28:31]
	v_mfma_f32_16x16x32_f16 v[24:27], v[128:131], v[176:179], v[24:27]
	v_mfma_f32_16x16x32_f16 v[12:15], v[112:115], v[184:187], v[12:15]
	v_mfma_f32_16x16x32_f16 v[8:11], v[128:131], v[184:187], v[8:11]
	v_mfma_f32_16x16x32_f16 v[60:63], v[116:119], v[164:167], v[60:63]
	v_mfma_f32_16x16x32_f16 v[56:59], v[132:135], v[164:167], v[56:59]
	v_mfma_f32_16x16x32_f16 v[44:47], v[116:119], v[172:175], v[44:47]
	v_mfma_f32_16x16x32_f16 v[40:43], v[132:135], v[172:175], v[40:43]
	v_mfma_f32_16x16x32_f16 v[28:31], v[116:119], v[180:183], v[28:31]
	v_mfma_f32_16x16x32_f16 v[24:27], v[132:135], v[180:183], v[24:27]
	v_mfma_f32_16x16x32_f16 v[12:15], v[116:119], v[188:191], v[12:15]
	v_mfma_f32_16x16x32_f16 v[8:11], v[132:135], v[188:191], v[8:11]
	s_setprio 0
	s_setprio 1
	v_mfma_f32_16x16x32_f16 v[52:55], v[144:147], v[160:163], v[52:55]
	v_mfma_f32_16x16x32_f16 v[48:51], v[152:155], v[160:163], v[48:51]
	v_mfma_f32_16x16x32_f16 v[36:39], v[144:147], v[168:171], v[36:39]
	v_mfma_f32_16x16x32_f16 v[32:35], v[152:155], v[168:171], v[32:35]
	v_mfma_f32_16x16x32_f16 v[20:23], v[144:147], v[176:179], v[20:23]
	v_mfma_f32_16x16x32_f16 v[16:19], v[152:155], v[176:179], v[16:19]
	v_mfma_f32_16x16x32_f16 v[4:7], v[144:147], v[184:187], v[4:7]
	v_mfma_f32_16x16x32_f16 v[0:3], v[152:155], v[184:187], v[0:3]
	v_mfma_f32_16x16x32_f16 v[52:55], v[148:151], v[164:167], v[52:55]
	v_mfma_f32_16x16x32_f16 v[48:51], v[156:159], v[164:167], v[48:51]
	v_mfma_f32_16x16x32_f16 v[36:39], v[148:151], v[172:175], v[36:39]
	v_mfma_f32_16x16x32_f16 v[32:35], v[156:159], v[172:175], v[32:35]
	v_mfma_f32_16x16x32_f16 v[20:23], v[148:151], v[180:183], v[20:23]
	v_mfma_f32_16x16x32_f16 v[16:19], v[156:159], v[180:183], v[16:19]
	v_mfma_f32_16x16x32_f16 v[4:7], v[148:151], v[188:191], v[4:7]
	v_mfma_f32_16x16x32_f16 v[0:3], v[156:159], v[188:191], v[0:3]
	s_setprio 0
	s_barrier
	s_add_i32 s43, s43, 2
	s_add_u32 s52, s52, 0x100
	s_addc_u32 s53, s53, 0
	s_add_u32 s41, s41, 0x100
	s_addc_u32 s42, s42, 0
	s_cmp_gt_u32 s43, 13
	s_cbranch_scc0 .LBB0_2136
	s_and_b64 vcc, exec, s[16:17]
	s_cbranch_vccz .LBB0_2139
	s_barrier

; #define PG8_STAGE(bufoff, gbase, voff) do { _Pragma("unroll") for (int _i = 0; _i < 2; ++_i) \
;         __builtin_amdgcn_global_load_lds((const unsigned*)((const char*)(gbase) + (voff)[_i]), (PG8_LAS unsigned*)(lds + (bufoff) + ldsw + _i * 8192), 16, 0, 0); } while (0)
; #define PG8_WAIT_V(n) asm volatile("s_waitcnt vmcnt(" #n ")" ::: "memory")
; #define PG8_BAR __builtin_amdgcn_s_barrier()
; template <class Epi, class Sched, bool ALIGN_EPI = false, bool SP2 = false, bool F16 = false>
; __device__ __forceinline__ void gemm_phase(PG8_LAS unsigned char* lds, const Gemm g, const Sched& S, const Epi& E, const int wid_in) {
;     ...
;     for (int i = 0; i < 2; ++i) { int R, C; stage_rc(tid * 16 + i * 8192, R, C); const int Rb = Epi::PERM ? ((R & ~31) + perm32(R & 31)) : R;
;         voffA[i] = (unsigned)(R * K + C) * 2u; voffB[i] = (unsigned)(Rb * K + C) * 2u; }
;     const size_t kstep = (size_t)(BK * 2);
;     const size_t hstep = (size_t)HALF * K * 2;
;     const size_t tstep = 2 * hstep;
;     const unsigned ldsw = (unsigned)wid * 1024u;
;     const int aoff = lds_byte(wr * 64 + fr, fq * 8), boff = lds_byte(wc * 32 + fr, fq * 8);
;     ...
;         PG8_STAGE(PG8_SB(1, 0), cB + kstep, voffB); PG8_STAGE(PG8_SA(1, 0), cA + kstep, voffA); PG8_STAGE(PG8_SB(1, 1), cB + hstep + kstep, voffB);
;         PG8_WAIT_V(6); PG8_BAR;
.LBB0_2220:
	s_add_u32 s24, s21, 0x15500000
	s_addc_u32 s25, s58, 0
	s_add_u32 s65, s21, 0x9400000
	s_mov_b64 s[26:27], 0x80
	s_addc_u32 s85, s58, 0
	s_add_i32 m0, s74, 0x18000
	v_lshl_add_u64 v[6:7], v[6:7], 0, s[26:27]
	s_waitcnt vmcnt(2)
	s_barrier
	global_load_lds_dwordx4 v[6:7], off
	v_lshl_add_u64 v[4:5], v[4:5], 0, s[26:27]
	s_add_i32 m0, s74, 0x1a000
	v_lshl_add_u64 v[0:1], v[0:1], 0, s[26:27]
	global_load_lds_dwordx4 v[4:5], off
	s_mov_b32 m0, s75
	s_add_u32 s10, s50, 0x40080
	global_load_lds_dwordx4 v[0:1], off
	v_lshl_add_u64 v[0:1], v[2:3], 0, s[26:27]
	s_mov_b32 m0, s67
	s_addc_u32 s11, s51, 0
	global_load_lds_dwordx4 v[0:1], off
	s_add_i32 m0, s74, 0x1c000
	s_nop 0
	global_load_lds_dwordx4 v158, s[10:11]
	s_add_i32 m0, s74, 0x1e000
	v_and_b32_e32 v180, 15, v8
	global_load_lds_dwordx4 v162, s[10:11]
	v_or_b32_e32 v0, s70, v180
	v_lshlrev_b32_e32 v1, 6, v0
	v_and_b32_e32 v2, 48, v8
	s_movk_i32 s10, 0x3c0
	v_and_b32_e32 v3, 0xfffffc00, v12
	v_lshlrev_b32_e32 v0, 2, v0
	v_and_or_b32 v1, v1, s10, v2
	v_add_u32_e32 v4, s73, v3
	v_and_b32_e32 v0, 32, v0
	v_bitop3_b32 v0, v1, v4, v0 bitop3:0xde
	v_lshl_or_b32 v1, v180, 6, v2
	v_add_u32_e32 v2, s72, v3
	v_lshlrev_b32_e32 v3, 2, v8
	v_and_b32_e32 v3, 32, v3
	v_bitop3_b32 v182, v1, v2, v3 bitop3:0xde
	v_lshlrev_b32_e32 v1, 14, v9
	v_and_b32_e32 v1, 0xffff8000, v1
	v_lshl_add_u32 v1, v10, 11, v1
	v_and_b32_e32 v2, 1, v9
	v_lshl_or_b32 v1, v2, 6, v1
	v_lshl_add_u32 v166, v11, 1, v1
	v_lshlrev_b32_e32 v1, 14, v13
	v_and_b32_e32 v1, 0xffff8000, v1
	s_waitcnt vmcnt(6)
	s_mul_i32 s10, s3, 0x210
	v_lshl_add_u32 v1, v14, 11, v1
	v_and_b32_e32 v2, 1, v13
	s_bfe_u32 s14, s93, 0x10006
	s_add_i32 s92, s10, 0
	v_lshl_or_b32 v1, v2, 6, v1
	s_add_i32 s84, 0, 0x10000
	s_add_i32 s93, 0, 0x14000
	v_ashrrev_i32_e32 v181, 4, v8
	s_ashr_i32 s15, s38, 31
	s_mov_b32 s83, s38
	s_ashr_i32 s76, s19, 31
	s_add_i32 s92, s92, 0x20400
	v_mov_b32_e32 v167, v164
	v_lshl_add_u32 v168, v15, 1, v1
	v_mov_b32_e32 v169, v164
	v_mov_b64_e32 v[170:171], 0x300
	v_mov_b64_e32 v[172:173], 0x2ff
	v_add_u32_e32 v183, s84, v182
	v_add_u32_e32 v184, s93, v182
	v_add_u32_e32 v185, 0, v0
	v_mov_b32_e32 v186, 0x358637bd
	s_mov_b64 s[28:29], 0x50000
	s_mov_b64 s[30:31], 0x58000
	v_mov_b32_e32 v187, 0x3e38aa3b
	s_barrier
	s_branch .LBB0_2223

; #define PG8_STAGE(bufoff, gbase, voff) do { _Pragma("unroll") for (int _i = 0; _i < 2; ++_i) \
;         __builtin_amdgcn_global_load_lds((const unsigned*)((const char*)(gbase) + (voff)[_i]), (PG8_LAS unsigned*)(lds + (bufoff) + ldsw + _i * 8192), 16, 0, 0); } while (0)
; #define PG8_LDA(dst, b, h) do { _Pragma("unroll") for (int m = 0; m < 4; ++m) _Pragma("unroll") for (int k = 0; k < 2; ++k) dst[m][k] = *(const PG8_LAS bf16x8*)(lds + PG8_SA(b, h) + aoff + m * 2048 + k * 1024); } while (0)
; #define PG8_LDB(dst, b, h) do { _Pragma("unroll") for (int n = 0; n < 2; ++n) _Pragma("unroll") for (int k = 0; k < 2; ++k) dst[n][k] = *(const PG8_LAS bf16x8*)(lds + PG8_SB(b, h) + boff + n * 2048 + k * 1024); } while (0)
; #define PG8_MMA(ai, bj, At, Bt) do { __builtin_amdgcn_s_setprio(1); _Pragma("unroll") for (int m = 0; m < 4; ++m) _Pragma("unroll") for (int n = 0; n < 2; ++n) _Pragma("unroll") for (int k = 0; k < 2; ++k) \
;         acc[ai][bj][m][n] = mma16<F16>(Bt[n][k], At[m][k], acc[ai][bj][m][n]); __builtin_amdgcn_s_setprio(0); } while (0)
; #define PG8_WAIT_V(n) asm volatile("s_waitcnt vmcnt(" #n ")" ::: "memory")
; #define PG8_WAIT_L(n) asm volatile("s_waitcnt lgkmcnt(" #n ")" ::: "memory")
; template <class Epi, class Sched, bool ALIGN_EPI = false, bool SP2 = false, bool F16 = false>
; __device__ __forceinline__ void gemm_phase(PG8_LAS unsigned char* lds, const Gemm g, const Sched& S, const Epi& E, const int wid_in) {
;     ...
;             const bool last = (t == nt - 2);
;             const char* a1 = cA + (size_t)(t + 1) * kstep;
;             const char* a2 = last ? nA : cA + (size_t)(t + 2) * kstep; const char* b2 = last ? nB : cB + (size_t)(t + 2) * kstep;
;             const char* a3 = a2 + kstep; const char* b3 = b2 + kstep;
;             if (last && has_next) S.a_ready(nxt);
;             if constexpr (SP2) {
;             PG8_LDB(B0, 0, 0); PG8_LDB(B1, 0, 1); PG8_SCHED; PG8_LDA(At, 0, 0); PG8_STAGE(PG8_SA(1, 1), a1 + hstep, voffA);
;             PG8_WAIT_V(8); PG8_WAIT_L(0); PG8_BAR; PG8_MMA(0, 0, At, B0); PG8_MMA(0, 1, At, B1); PG8_BAR; PG8_SCHED;
;             PG8_LDA(At, 0, 1); PG8_STAGE(PG8_SB(0, 0), b2, voffB); PG8_STAGE(PG8_SB(0, 1), b2 + hstep, voffB); PG8_STAGE(PG8_SA(0, 0), a2, voffA);
;             PG8_WAIT_V(8); PG8_WAIT_L(0); PG8_BAR; PG8_MMA(1, 0, At, B0); PG8_MMA(1, 1, At, B1); PG8_BAR; PG8_SCHED;
.LBB0_2226:
	ds_read_b128 v[128:131], v183
	ds_read_b128 v[132:135], v183 offset:1024
	ds_read_b128 v[136:139], v183 offset:2048
	ds_read_b128 v[140:143], v183 offset:3072
	ds_read_b128 v[144:147], v184
	ds_read_b128 v[148:151], v184 offset:1024
	ds_read_b128 v[152:155], v184 offset:2048
	ds_read_b128 v[174:177], v184 offset:3072
	s_add_u32 s43, s48, 0xfffc0080
	s_addc_u32 s50, s49, -1
	s_cmp_eq_u32 s42, 12
	s_cselect_b32 s53, s13, s50
	s_cselect_b32 s52, s23, s43
	s_cselect_b32 s51, s35, s41
	s_cselect_b32 s50, s37, s40
	s_mov_b32 m0, s91
	ds_read_b128 v[188:191], v185
	ds_read_b128 v[192:195], v185 offset:1024
	ds_read_b128 v[196:199], v185 offset:2048
	ds_read_b128 v[200:203], v185 offset:3072
	ds_read_b128 v[204:207], v185 offset:4096
	ds_read_b128 v[208:211], v185 offset:5120
	ds_read_b128 v[212:215], v185 offset:6144
	ds_read_b128 v[216:219], v185 offset:7168
	global_load_lds_dwordx4 v166, s[48:49]
	s_add_i32 m0, s74, 0xe000
	s_nop 0
	global_load_lds_dwordx4 v168, s[48:49]
	s_waitcnt vmcnt(8)
	s_waitcnt lgkmcnt(0)
	s_barrier
	s_setprio 1
	s_waitcnt lgkmcnt(0)
	v_mfma_f32_16x16x32_f16 v[124:127], v[128:131], v[188:191], v[124:127]
	v_mfma_f32_16x16x32_f16 v[120:123], v[136:139], v[188:191], v[120:123]
	v_mfma_f32_16x16x32_f16 v[108:111], v[128:131], v[196:199], v[108:111]
	v_mfma_f32_16x16x32_f16 v[104:107], v[136:139], v[196:199], v[104:107]
	v_mfma_f32_16x16x32_f16 v[92:95], v[128:131], v[204:207], v[92:95]
	v_mfma_f32_16x16x32_f16 v[88:91], v[136:139], v[204:207], v[88:91]
	v_mfma_f32_16x16x32_f16 v[76:79], v[128:131], v[212:215], v[76:79]
	v_mfma_f32_16x16x32_f16 v[72:75], v[136:139], v[212:215], v[72:75]
	v_mfma_f32_16x16x32_f16 v[124:127], v[132:135], v[192:195], v[124:127]
	v_mfma_f32_16x16x32_f16 v[120:123], v[140:143], v[192:195], v[120:123]
	v_mfma_f32_16x16x32_f16 v[108:111], v[132:135], v[200:203], v[108:111]
	v_mfma_f32_16x16x32_f16 v[104:107], v[140:143], v[200:203], v[104:107]
	v_mfma_f32_16x16x32_f16 v[92:95], v[132:135], v[208:211], v[92:95]
	v_mfma_f32_16x16x32_f16 v[88:91], v[140:143], v[208:211], v[88:91]
	v_mfma_f32_16x16x32_f16 v[76:79], v[132:135], v[216:219], v[76:79]
	v_mfma_f32_16x16x32_f16 v[72:75], v[140:143], v[216:219], v[72:75]
	s_setprio 0
	s_setprio 1
	v_mfma_f32_16x16x32_f16 v[116:119], v[144:147], v[188:191], v[116:119]
	v_mfma_f32_16x16x32_f16 v[112:115], v[152:155], v[188:191], v[112:115]
	v_mfma_f32_16x16x32_f16 v[100:103], v[144:147], v[196:199], v[100:103]
	v_mfma_f32_16x16x32_f16 v[96:99], v[152:155], v[196:199], v[96:99]
	v_mfma_f32_16x16x32_f16 v[84:87], v[144:147], v[204:207], v[84:87]
	v_mfma_f32_16x16x32_f16 v[80:83], v[152:155], v[204:207], v[80:83]
	v_mfma_f32_16x16x32_f16 v[68:71], v[144:147], v[212:215], v[68:71]
	v_mfma_f32_16x16x32_f16 v[64:67], v[152:155], v[212:215], v[64:67]
	v_mfma_f32_16x16x32_f16 v[116:119], v[148:151], v[192:195], v[116:119]
	v_mfma_f32_16x16x32_f16 v[112:115], v[174:177], v[192:195], v[112:115]
	v_mfma_f32_16x16x32_f16 v[100:103], v[148:151], v[200:203], v[100:103]
	v_mfma_f32_16x16x32_f16 v[96:99], v[174:177], v[200:203], v[96:99]
	v_mfma_f32_16x16x32_f16 v[84:87], v[148:151], v[208:211], v[84:87]
	v_mfma_f32_16x16x32_f16 v[80:83], v[174:177], v[208:211], v[80:83]
	v_mfma_f32_16x16x32_f16 v[68:71], v[148:151], v[216:219], v[68:71]
	v_mfma_f32_16x16x32_f16 v[64:67], v[174:177], v[216:219], v[64:67]
	s_setprio 0
	s_barrier
	s_add_i32 s43, s84, s68
	v_lshl_add_u64 v[178:179], s[50:51], 0, v[158:159]
	s_mov_b32 m0, s43
	ds_read_b128 v[188:191], v185 offset:16384
	ds_read_b128 v[192:195], v185 offset:17408
	ds_read_b128 v[196:199], v185 offset:18432
	ds_read_b128 v[200:203], v185 offset:19456
	ds_read_b128 v[204:207], v185 offset:20480
	ds_read_b128 v[208:211], v185 offset:21504
	ds_read_b128 v[212:215], v185 offset:22528
	ds_read_b128 v[216:219], v185 offset:23552
	global_load_lds_dwordx4 v[178:179], off
	s_add_i32 m0, s43, 0x2000
	s_add_u32 s54, s50, 0x40000
	v_lshl_add_u64 v[220:221], s[50:51], 0, v[162:163]
	s_addc_u32 s55, s51, 0
	s_add_i32 s43, s93, s68
	global_load_lds_dwordx4 v[220:221], off
	s_mov_b32 m0, s43
	v_lshl_add_u64 v[224:225], s[52:53], 0, v[160:161]
	global_load_lds_dwordx4 v158, s[54:55]
	s_add_i32 m0, s43, 0x2000
	s_nop 0
	global_load_lds_dwordx4 v162, s[54:55]
	v_lshl_add_u64 v[222:223], s[52:53], 0, v[156:157]
	s_mov_b32 m0, s74
	s_nop 0
	global_load_lds_dwordx4 v[222:223], off
	s_mov_b32 m0, s66
	s_nop 0
	global_load_lds_dwordx4 v[224:225], off
	s_waitcnt vmcnt(8)
	s_waitcnt lgkmcnt(0)
	s_barrier
	s_setprio 1
	s_waitcnt lgkmcnt(0)
	v_mfma_f32_16x16x32_f16 v[60:63], v[128:131], v[188:191], v[60:63]
	v_mfma_f32_16x16x32_f16 v[56:59], v[136:139], v[188:191], v[56:59]
	v_mfma_f32_16x16x32_f16 v[44:47], v[128:131], v[196:199], v[44:47]
	v_mfma_f32_16x16x32_f16 v[40:43], v[136:139], v[196:199], v[40:43]
	v_mfma_f32_16x16x32_f16 v[28:31], v[128:131], v[204:207], v[28:31]
	v_mfma_f32_16x16x32_f16 v[24:27], v[136:139], v[204:207], v[24:27]
	v_mfma_f32_16x16x32_f16 v[12:15], v[128:131], v[212:215], v[12:15]
	v_mfma_f32_16x16x32_f16 v[8:11], v[136:139], v[212:215], v[8:11]
	v_mfma_f32_16x16x32_f16 v[60:63], v[132:135], v[192:195], v[60:63]
	v_mfma_f32_16x16x32_f16 v[56:59], v[140:143], v[192:195], v[56:59]
	v_mfma_f32_16x16x32_f16 v[44:47], v[132:135], v[200:203], v[44:47]
	v_mfma_f32_16x16x32_f16 v[40:43], v[140:143], v[200:203], v[40:43]
	v_mfma_f32_16x16x32_f16 v[28:31], v[132:135], v[208:211], v[28:31]
	v_mfma_f32_16x16x32_f16 v[24:27], v[140:143], v[208:211], v[24:27]
	v_mfma_f32_16x16x32_f16 v[12:15], v[132:135], v[216:219], v[12:15]
	v_mfma_f32_16x16x32_f16 v[8:11], v[140:143], v[216:219], v[8:11]
	s_setprio 0
	s_setprio 1
	v_mfma_f32_16x16x32_f16 v[52:55], v[144:147], v[188:191], v[52:55]
	v_mfma_f32_16x16x32_f16 v[48:51], v[152:155], v[188:191], v[48:51]
	v_mfma_f32_16x16x32_f16 v[36:39], v[144:147], v[196:199], v[36:39]
	v_mfma_f32_16x16x32_f16 v[32:35], v[152:155], v[196:199], v[32:35]
	v_mfma_f32_16x16x32_f16 v[20:23], v[144:147], v[204:207], v[20:23]
	v_mfma_f32_16x16x32_f16 v[16:19], v[152:155], v[204:207], v[16:19]
	v_mfma_f32_16x16x32_f16 v[4:7], v[144:147], v[212:215], v[4:7]
	v_mfma_f32_16x16x32_f16 v[0:3], v[152:155], v[212:215], v[0:3]
	v_mfma_f32_16x16x32_f16 v[52:55], v[148:151], v[192:195], v[52:55]
	v_mfma_f32_16x16x32_f16 v[48:51], v[174:177], v[192:195], v[48:51]
	v_mfma_f32_16x16x32_f16 v[36:39], v[148:151], v[200:203], v[36:39]
	v_mfma_f32_16x16x32_f16 v[32:35], v[174:177], v[200:203], v[32:35]
	v_mfma_f32_16x16x32_f16 v[20:23], v[148:151], v[208:211], v[20:23]
	v_mfma_f32_16x16x32_f16 v[16:19], v[174:177], v[208:211], v[16:19]
	v_mfma_f32_16x16x32_f16 v[4:7], v[148:151], v[216:219], v[4:7]
	v_mfma_f32_16x16x32_f16 v[0:3], v[174:177], v[216:219], v[0:3]
	s_setprio 0
	s_barrier
; #define PG8_STAGE(bufoff, gbase, voff) do { _Pragma("unroll") for (int _i = 0; _i < 2; ++_i) \
;         __builtin_amdgcn_global_load_lds((const unsigned*)((const char*)(gbase) + (voff)[_i]), (PG8_LAS unsigned*)(lds + (bufoff) + ldsw + _i * 8192), 16, 0, 0); } while (0)
; #define PG8_LDA(dst, b, h) do { _Pragma("unroll") for (int m = 0; m < 4; ++m) _Pragma("unroll") for (int k = 0; k < 2; ++k) dst[m][k] = *(const PG8_LAS bf16x8*)(lds + PG8_SA(b, h) + aoff + m * 2048 + k * 1024); } while (0)
; #define PG8_LDB(dst, b, h) do { _Pragma("unroll") for (int n = 0; n < 2; ++n) _Pragma("unroll") for (int k = 0; k < 2; ++k) dst[n][k] = *(const PG8_LAS bf16x8*)(lds + PG8_SB(b, h) + boff + n * 2048 + k * 1024); } while (0)
; #define PG8_MMA(ai, bj, At, Bt) do { __builtin_amdgcn_s_setprio(1); _Pragma("unroll") for (int m = 0; m < 4; ++m) _Pragma("unroll") for (int n = 0; n < 2; ++n) _Pragma("unroll") for (int k = 0; k < 2; ++k) \
;         acc[ai][bj][m][n] = mma16<F16>(Bt[n][k], At[m][k], acc[ai][bj][m][n]); __builtin_amdgcn_s_setprio(0); } while (0)
; #define PG8_WAIT_V(n) asm volatile("s_waitcnt vmcnt(" #n ")" ::: "memory")
; #define PG8_WAIT_L(n) asm volatile("s_waitcnt lgkmcnt(" #n ")" ::: "memory")
; #define PG8_BAR __builtin_amdgcn_s_barrier()
; #define PG8_SCHED __builtin_amdgcn_sched_barrier(0)
; template <class Epi, class Sched, bool ALIGN_EPI = false, bool SP2 = false, bool F16 = false>
; __device__ __forceinline__ void gemm_phase(PG8_LAS unsigned char* lds, const Gemm g, const Sched& S, const Epi& E, const int wid_in) {
;     ...
;             PG8_LDB(B0, 1, 0); PG8_LDB(B1, 1, 1); PG8_SCHED; PG8_LDA(At, 1, 0); PG8_STAGE(PG8_SA(0, 1), a2 + hstep, voffA);
;             PG8_WAIT_V(8); PG8_WAIT_L(0); PG8_BAR; PG8_MMA(0, 0, At, B0); PG8_MMA(0, 1, At, B1); PG8_BAR; PG8_SCHED;
;             PG8_LDA(At, 1, 1); PG8_STAGE(PG8_SB(1, 0), b3, voffB); PG8_STAGE(PG8_SB(1, 1), b3 + hstep, voffB); PG8_STAGE(PG8_SA(1, 0), a3, voffA);
;             PG8_WAIT_V(8); PG8_WAIT_L(0); PG8_BAR; PG8_MMA(1, 0, At, B0); PG8_MMA(1, 1, At, B1); PG8_BAR; PG8_SCHED;
	s_add_i32 s43, 0, 0x18000
	s_add_i32 s54, 0, 0x1c000
	v_add_u32_e32 v140, s43, v182
	v_add_u32_e32 v165, s54, v182
	ds_read_b128 v[128:131], v140
	ds_read_b128 v[132:135], v140 offset:1024
	ds_read_b128 v[136:139], v140 offset:2048
	ds_read_b128 v[140:143], v140 offset:3072
	ds_read_b128 v[144:147], v165
	ds_read_b128 v[148:151], v165 offset:1024
	ds_read_b128 v[152:155], v165 offset:2048
	ds_read_b128 v[174:177], v165 offset:3072
	s_add_u32 s52, s52, 0x40000
	s_addc_u32 s53, s53, 0
	s_mov_b32 m0, s90
	ds_read_b128 v[188:191], v185 offset:32768
	ds_read_b128 v[192:195], v185 offset:33792
	ds_read_b128 v[196:199], v185 offset:34816
	ds_read_b128 v[200:203], v185 offset:35840
	ds_read_b128 v[204:207], v185 offset:36864
	ds_read_b128 v[208:211], v185 offset:37888
	ds_read_b128 v[212:215], v185 offset:38912
	ds_read_b128 v[216:219], v185 offset:39936
	global_load_lds_dwordx4 v156, s[52:53]
	v_lshl_add_u64 v[226:227], s[52:53], 0, v[160:161]
	s_mov_b32 m0, s63
	s_nop 0
	global_load_lds_dwordx4 v[226:227], off
	s_waitcnt vmcnt(8)
	s_waitcnt lgkmcnt(0)
	s_barrier
	s_setprio 1
	s_waitcnt lgkmcnt(0)
	v_mfma_f32_16x16x32_f16 v[124:127], v[128:131], v[188:191], v[124:127]
	v_mfma_f32_16x16x32_f16 v[120:123], v[136:139], v[188:191], v[120:123]
	v_mfma_f32_16x16x32_f16 v[108:111], v[128:131], v[196:199], v[108:111]
	v_mfma_f32_16x16x32_f16 v[104:107], v[136:139], v[196:199], v[104:107]
	v_mfma_f32_16x16x32_f16 v[92:95], v[128:131], v[204:207], v[92:95]
	v_mfma_f32_16x16x32_f16 v[88:91], v[136:139], v[204:207], v[88:91]
	v_mfma_f32_16x16x32_f16 v[76:79], v[128:131], v[212:215], v[76:79]
	v_mfma_f32_16x16x32_f16 v[72:75], v[136:139], v[212:215], v[72:75]
	v_mfma_f32_16x16x32_f16 v[124:127], v[132:135], v[192:195], v[124:127]
	v_mfma_f32_16x16x32_f16 v[120:123], v[140:143], v[192:195], v[120:123]
	v_mfma_f32_16x16x32_f16 v[108:111], v[132:135], v[200:203], v[108:111]
	v_mfma_f32_16x16x32_f16 v[104:107], v[140:143], v[200:203], v[104:107]
	v_mfma_f32_16x16x32_f16 v[92:95], v[132:135], v[208:211], v[92:95]
	v_mfma_f32_16x16x32_f16 v[88:91], v[140:143], v[208:211], v[88:91]
	v_mfma_f32_16x16x32_f16 v[76:79], v[132:135], v[216:219], v[76:79]
	v_mfma_f32_16x16x32_f16 v[72:75], v[140:143], v[216:219], v[72:75]
	s_setprio 0
	s_setprio 1
	v_mfma_f32_16x16x32_f16 v[116:119], v[144:147], v[188:191], v[116:119]
	v_mfma_f32_16x16x32_f16 v[112:115], v[152:155], v[188:191], v[112:115]
	v_mfma_f32_16x16x32_f16 v[100:103], v[144:147], v[196:199], v[100:103]
	v_mfma_f32_16x16x32_f16 v[96:99], v[152:155], v[196:199], v[96:99]
	v_mfma_f32_16x16x32_f16 v[84:87], v[144:147], v[204:207], v[84:87]
	v_mfma_f32_16x16x32_f16 v[80:83], v[152:155], v[204:207], v[80:83]
	v_mfma_f32_16x16x32_f16 v[68:71], v[144:147], v[212:215], v[68:71]
	v_mfma_f32_16x16x32_f16 v[64:67], v[152:155], v[212:215], v[64:67]
	v_mfma_f32_16x16x32_f16 v[116:119], v[148:151], v[192:195], v[116:119]
	v_mfma_f32_16x16x32_f16 v[112:115], v[174:177], v[192:195], v[112:115]
	v_mfma_f32_16x16x32_f16 v[100:103], v[148:151], v[200:203], v[100:103]
	v_mfma_f32_16x16x32_f16 v[96:99], v[174:177], v[200:203], v[96:99]
	v_mfma_f32_16x16x32_f16 v[84:87], v[148:151], v[208:211], v[84:87]
	v_mfma_f32_16x16x32_f16 v[80:83], v[174:177], v[208:211], v[80:83]
	v_mfma_f32_16x16x32_f16 v[68:71], v[148:151], v[216:219], v[68:71]
	v_mfma_f32_16x16x32_f16 v[64:67], v[174:177], v[216:219], v[64:67]
	s_setprio 0
	s_barrier
	s_add_i32 s43, s43, s68
	v_lshl_add_u64 v[178:179], v[178:179], 0, s[26:27]
	s_mov_b32 m0, s43
	ds_read_b128 v[188:191], v185 offset:49152
	ds_read_b128 v[192:195], v185 offset:50176
	ds_read_b128 v[196:199], v185 offset:51200
	ds_read_b128 v[200:203], v185 offset:52224
	ds_read_b128 v[204:207], v185 offset:53248
	ds_read_b128 v[208:211], v185 offset:54272
	ds_read_b128 v[212:215], v185 offset:55296
	ds_read_b128 v[216:219], v185 offset:56320
	global_load_lds_dwordx4 v[178:179], off
	s_add_i32 m0, s43, 0x2000
	s_add_u32 s50, s50, 0x40080
	v_lshl_add_u64 v[178:179], v[220:221], 0, s[26:27]
	s_addc_u32 s51, s51, 0
	s_add_i32 s43, s54, s68
	global_load_lds_dwordx4 v[178:179], off
	s_mov_b32 m0, s43
	s_nop 0
	global_load_lds_dwordx4 v158, s[50:51]
	s_add_i32 m0, s43, 0x2000
	s_nop 0
	global_load_lds_dwordx4 v162, s[50:51]
	v_lshl_add_u64 v[178:179], v[222:223], 0, s[26:27]
	s_mov_b32 m0, s75
	s_nop 0
	global_load_lds_dwordx4 v[178:179], off
	v_lshl_add_u64 v[178:179], v[224:225], 0, s[26:27]
	s_mov_b32 m0, s67
	s_nop 0
	global_load_lds_dwordx4 v[178:179], off
	s_waitcnt vmcnt(8)
	s_waitcnt lgkmcnt(0)
	s_barrier
	s_setprio 1
	s_waitcnt lgkmcnt(0)
	v_mfma_f32_16x16x32_f16 v[60:63], v[128:131], v[188:191], v[60:63]
	v_mfma_f32_16x16x32_f16 v[56:59], v[136:139], v[188:191], v[56:59]
	v_mfma_f32_16x16x32_f16 v[44:47], v[128:131], v[196:199], v[44:47]
	v_mfma_f32_16x16x32_f16 v[40:43], v[136:139], v[196:199], v[40:43]
	v_mfma_f32_16x16x32_f16 v[28:31], v[128:131], v[204:207], v[28:31]
	v_mfma_f32_16x16x32_f16 v[24:27], v[136:139], v[204:207], v[24:27]
	v_mfma_f32_16x16x32_f16 v[12:15], v[128:131], v[212:215], v[12:15]
	v_mfma_f32_16x16x32_f16 v[8:11], v[136:139], v[212:215], v[8:11]
	v_mfma_f32_16x16x32_f16 v[60:63], v[132:135], v[192:195], v[60:63]
	v_mfma_f32_16x16x32_f16 v[56:59], v[140:143], v[192:195], v[56:59]
	v_mfma_f32_16x16x32_f16 v[44:47], v[132:135], v[200:203], v[44:47]
	v_mfma_f32_16x16x32_f16 v[40:43], v[140:143], v[200:203], v[40:43]
	v_mfma_f32_16x16x32_f16 v[28:31], v[132:135], v[208:211], v[28:31]
	v_mfma_f32_16x16x32_f16 v[24:27], v[140:143], v[208:211], v[24:27]
	v_mfma_f32_16x16x32_f16 v[12:15], v[132:135], v[216:219], v[12:15]
	v_mfma_f32_16x16x32_f16 v[8:11], v[140:143], v[216:219], v[8:11]
	s_setprio 0
	s_setprio 1
	v_mfma_f32_16x16x32_f16 v[52:55], v[144:147], v[188:191], v[52:55]
	v_mfma_f32_16x16x32_f16 v[48:51], v[152:155], v[188:191], v[48:51]
	v_mfma_f32_16x16x32_f16 v[36:39], v[144:147], v[196:199], v[36:39]
	v_mfma_f32_16x16x32_f16 v[32:35], v[152:155], v[196:199], v[32:35]
	v_mfma_f32_16x16x32_f16 v[20:23], v[144:147], v[204:207], v[20:23]
	v_mfma_f32_16x16x32_f16 v[16:19], v[152:155], v[204:207], v[16:19]
	v_mfma_f32_16x16x32_f16 v[4:7], v[144:147], v[212:215], v[4:7]
	v_mfma_f32_16x16x32_f16 v[0:3], v[152:155], v[212:215], v[0:3]
	v_mfma_f32_16x16x32_f16 v[52:55], v[148:151], v[192:195], v[52:55]
	v_mfma_f32_16x16x32_f16 v[48:51], v[174:177], v[192:195], v[48:51]
	v_mfma_f32_16x16x32_f16 v[36:39], v[148:151], v[200:203], v[36:39]
	v_mfma_f32_16x16x32_f16 v[32:35], v[174:177], v[200:203], v[32:35]
	v_mfma_f32_16x16x32_f16 v[20:23], v[148:151], v[208:211], v[20:23]
	v_mfma_f32_16x16x32_f16 v[16:19], v[174:177], v[208:211], v[16:19]
	v_mfma_f32_16x16x32_f16 v[4:7], v[148:151], v[216:219], v[4:7]
	v_mfma_f32_16x16x32_f16 v[0:3], v[174:177], v[216:219], v[0:3]
	s_setprio 0
	s_barrier
	s_add_i32 s42, s42, 2
	s_add_u32 s48, s48, 0x100
	s_addc_u32 s49, s49, 0
	s_add_u32 s40, s40, 0x100
	s_addc_u32 s41, s41, 0
	s_cmp_gt_u32 s42, 13
	s_cbranch_scc0 .LBB0_2226
	s_and_b64 vcc, exec, s[16:17]
	s_cbranch_vccz .LBB0_2229
	s_barrier

; #define PG8_STAGE(bufoff, gbase, voff) do { _Pragma("unroll") for (int _i = 0; _i < 2; ++_i) \
;         __builtin_amdgcn_global_load_lds((const unsigned*)((const char*)(gbase) + (voff)[_i]), (PG8_LAS unsigned*)(lds + (bufoff) + ldsw + _i * 8192), 16, 0, 0); } while (0)
; #define PG8_WAIT_V(n) asm volatile("s_waitcnt vmcnt(" #n ")" ::: "memory")
; #define PG8_BAR __builtin_amdgcn_s_barrier()
; template <class Epi, class Sched, bool ALIGN_EPI = false, bool SP2 = false, bool F16 = false>
; __device__ __forceinline__ void gemm_phase(PG8_LAS unsigned char* lds, const Gemm g, const Sched& S, const Epi& E, const int wid_in) {
;     ...
;     for (int i = 0; i < 2; ++i) { int R, C; stage_rc(tid * 16 + i * 8192, R, C); const int Rb = Epi::PERM ? ((R & ~31) + perm32(R & 31)) : R;
;         voffA[i] = (unsigned)(R * K + C) * 2u; voffB[i] = (unsigned)(Rb * K + C) * 2u; }
;     const size_t kstep = (size_t)(BK * 2);
;     const size_t hstep = (size_t)HALF * K * 2;
;     const size_t tstep = 2 * hstep;
;     const unsigned ldsw = (unsigned)wid * 1024u;
;     const int aoff = lds_byte(wr * 64 + fr, fq * 8), boff = lds_byte(wc * 32 + fr, fq * 8);
;     ...
;         PG8_STAGE(PG8_SB(1, 0), cB + kstep, voffB); PG8_STAGE(PG8_SA(1, 0), cA + kstep, voffA); PG8_STAGE(PG8_SB(1, 1), cB + hstep + kstep, voffB);
;         PG8_WAIT_V(6); PG8_BAR;
;     } else {
;         PG8_STAGE(PG8_SB(0, 0), cB, voffB); PG8_STAGE(PG8_SA(0, 0), cA, voffA); PG8_STAGE(PG8_SB(0, 1), cB + hstep, voffB); PG8_STAGE(PG8_SA(0, 1), cA + hstep, voffA);
;         if (wr == 1) PG8_BAR;
;         PG8_WAIT_V(4); PG8_BAR;
;         PG8_STAGE(PG8_SB(1, 0), cB + kstep, voffB); PG8_STAGE(PG8_SA(1, 0), cA + kstep, voffA); PG8_STAGE(PG8_SB(1, 1), cB + hstep + kstep, voffB);
;         PG8_WAIT_V(6); PG8_BAR;
;     }
.LBB0_2479:
	s_add_u32 s18, s10, 0x7400000
	s_addc_u32 s19, s11, 0
	s_add_u32 s20, s10, 0x13400000
	s_addc_u32 s21, s11, 0
	s_add_u32 s22, s10, 0x15600000
	s_mov_b64 s[24:25], 0x80
	s_addc_u32 s23, s11, 0
	s_add_i32 m0, s74, 0x18000
	v_lshl_add_u64 v[6:7], v[6:7], 0, s[24:25]
	s_waitcnt vmcnt(2)
	s_barrier
	global_load_lds_dwordx4 v[6:7], off
	v_lshl_add_u64 v[4:5], v[4:5], 0, s[24:25]
	s_add_i32 m0, s74, 0x1a000
	v_lshl_add_u64 v[0:1], v[0:1], 0, s[24:25]
	global_load_lds_dwordx4 v[4:5], off
	s_mov_b32 m0, s75
	s_add_u32 s10, s44, 0x40080
	global_load_lds_dwordx4 v[0:1], off
	v_lshl_add_u64 v[0:1], v[2:3], 0, s[24:25]
	s_mov_b32 m0, s67
	s_addc_u32 s11, s45, 0
	global_load_lds_dwordx4 v[0:1], off
	s_add_i32 m0, s74, 0x1c000
	s_nop 0
	global_load_lds_dwordx4 v154, s[10:11]
	s_add_i32 m0, s74, 0x1e000
	v_and_b32_e32 v187, 15, v8
	global_load_lds_dwordx4 v158, s[10:11]
	v_or_b32_e32 v0, s70, v187
	v_lshlrev_b32_e32 v1, 6, v0
	v_and_b32_e32 v2, 48, v8
	s_movk_i32 s10, 0x3c0
	v_and_b32_e32 v3, 0xfffffc00, v12
	v_lshlrev_b32_e32 v0, 2, v0
	v_and_or_b32 v1, v1, s10, v2
	v_add_u32_e32 v4, s73, v3
	v_and_b32_e32 v0, 32, v0
	v_bitop3_b32 v0, v1, v4, v0 bitop3:0xde
	v_lshl_or_b32 v1, v187, 6, v2
	v_add_u32_e32 v2, s72, v3
	v_lshlrev_b32_e32 v3, 2, v8
	v_and_b32_e32 v3, 32, v3
	v_bitop3_b32 v188, v1, v2, v3 bitop3:0xde
	v_lshlrev_b32_e32 v1, 14, v9
	v_and_b32_e32 v1, 0xffff8000, v1
	v_lshl_add_u32 v1, v10, 11, v1
	v_and_b32_e32 v2, 1, v9
	v_lshl_or_b32 v1, v2, 6, v1
	v_lshl_add_u32 v160, v11, 1, v1
	v_lshlrev_b32_e32 v1, 14, v13
	v_and_b32_e32 v1, 0xffff8000, v1
	s_waitcnt vmcnt(6)
	v_lshl_add_u32 v1, v14, 11, v1
	v_and_b32_e32 v2, 1, v13
	v_lshl_or_b32 v1, v2, 6, v1
	s_add_i32 s53, 0, 0x10000
	s_add_i32 s54, 0, 0x14000
	v_ashrrev_i32_e32 v186, 4, v8
	s_ashr_i32 s50, s38, 31
	s_mov_b32 s51, s38
	s_ashr_i32 s52, s14, 31
	v_mov_b32_e32 v161, v155
	v_lshl_add_u32 v162, v15, 1, v1
	v_mov_b32_e32 v163, v155
	v_mov_b64_e32 v[164:165], 0x100
	v_mov_b64_e32 v[166:167], 0xff
	v_add_u32_e32 v189, s53, v188
	v_add_u32_e32 v190, s54, v188
	v_add_u32_e32 v191, 0, v0
	s_mov_b32 s55, 0
	s_barrier
	s_branch .LBB0_2482

; #define PG8_STAGE(bufoff, gbase, voff) do { _Pragma("unroll") for (int _i = 0; _i < 2; ++_i) \
;         __builtin_amdgcn_global_load_lds((const unsigned*)((const char*)(gbase) + (voff)[_i]), (PG8_LAS unsigned*)(lds + (bufoff) + ldsw + _i * 8192), 16, 0, 0); } while (0)
; #define PG8_LDA(dst, b, h) do { _Pragma("unroll") for (int m = 0; m < 4; ++m) _Pragma("unroll") for (int k = 0; k < 2; ++k) dst[m][k] = *(const PG8_LAS bf16x8*)(lds + PG8_SA(b, h) + aoff + m * 2048 + k * 1024); } while (0)
; #define PG8_LDB(dst, b, h) do { _Pragma("unroll") for (int n = 0; n < 2; ++n) _Pragma("unroll") for (int k = 0; k < 2; ++k) dst[n][k] = *(const PG8_LAS bf16x8*)(lds + PG8_SB(b, h) + boff + n * 2048 + k * 1024); } while (0)
; #define PG8_MMA(ai, bj, At, Bt) do { __builtin_amdgcn_s_setprio(1); _Pragma("unroll") for (int m = 0; m < 4; ++m) _Pragma("unroll") for (int n = 0; n < 2; ++n) _Pragma("unroll") for (int k = 0; k < 2; ++k) \
;         acc[ai][bj][m][n] = mma16<F16>(Bt[n][k], At[m][k], acc[ai][bj][m][n]); __builtin_amdgcn_s_setprio(0); } while (0)
; #define PG8_WAIT_V(n) asm volatile("s_waitcnt vmcnt(" #n ")" ::: "memory")
; #define PG8_WAIT_L(n) asm volatile("s_waitcnt lgkmcnt(" #n ")" ::: "memory")
; #define PG8_BAR __builtin_amdgcn_s_barrier()
; #define PG8_SCHED __builtin_amdgcn_sched_barrier(0)
; template <class Epi, class Sched, bool ALIGN_EPI = false, bool SP2 = false, bool F16 = false>
; __device__ __forceinline__ void gemm_phase(PG8_LAS unsigned char* lds, const Gemm g, const Sched& S, const Epi& E, const int wid_in) {
;     ...
;             const bool last = (t == nt - 2);
;             const char* a1 = cA + (size_t)(t + 1) * kstep;
;             const char* a2 = last ? nA : cA + (size_t)(t + 2) * kstep; const char* b2 = last ? nB : cB + (size_t)(t + 2) * kstep;
;             const char* a3 = a2 + kstep; const char* b3 = b2 + kstep;
;             if (last && has_next) S.a_ready(nxt);
;             if constexpr (SP2) {
;             PG8_LDB(B0, 0, 0); PG8_LDB(B1, 0, 1); PG8_SCHED; PG8_LDA(At, 0, 0); PG8_STAGE(PG8_SA(1, 1), a1 + hstep, voffA);
;             PG8_WAIT_V(8); PG8_WAIT_L(0); PG8_BAR; PG8_MMA(0, 0, At, B0); PG8_MMA(0, 1, At, B1); PG8_BAR; PG8_SCHED;
;             PG8_LDA(At, 0, 1); PG8_STAGE(PG8_SB(0, 0), b2, voffB); PG8_STAGE(PG8_SB(0, 1), b2 + hstep, voffB); PG8_STAGE(PG8_SA(0, 0), a2, voffA);
.LBB0_2489:
	ds_read_b128 v[128:131], v189
	ds_read_b128 v[132:135], v189 offset:1024
	ds_read_b128 v[136:139], v189 offset:2048
	ds_read_b128 v[140:143], v189 offset:3072
	ds_read_b128 v[144:147], v190
	ds_read_b128 v[148:151], v190 offset:1024
	ds_read_b128 v[168:171], v190 offset:2048
	ds_read_b128 v[172:175], v190 offset:3072
	s_add_u32 s44, s42, 0xfffc0080
	s_addc_u32 s45, s43, -1
	s_cmp_eq_u32 s59, 12
	s_cselect_b32 s47, s29, s45
	s_cselect_b32 s46, s37, s44
	s_cselect_b32 s45, s27, s58
	s_cselect_b32 s44, s56, s57
	s_mov_b32 m0, s91
	ds_read_b128 v[176:179], v191
	ds_read_b128 v[180:183], v191 offset:1024
	ds_read_b128 v[192:195], v191 offset:2048
	ds_read_b128 v[196:199], v191 offset:3072
	ds_read_b128 v[200:203], v191 offset:4096
	ds_read_b128 v[204:207], v191 offset:5120
	ds_read_b128 v[208:211], v191 offset:6144
	ds_read_b128 v[212:215], v191 offset:7168
	global_load_lds_dwordx4 v160, s[42:43]
	s_add_i32 m0, s74, 0xe000
	s_nop 0
	global_load_lds_dwordx4 v162, s[42:43]
	s_waitcnt vmcnt(8)
	s_waitcnt lgkmcnt(0)
	s_barrier
	s_setprio 1
	s_waitcnt lgkmcnt(0)
	v_mfma_f32_16x16x32_bf16 v[124:127], v[128:131], v[176:179], v[124:127]
	v_mfma_f32_16x16x32_bf16 v[120:123], v[136:139], v[176:179], v[120:123]
	v_mfma_f32_16x16x32_bf16 v[108:111], v[128:131], v[192:195], v[108:111]
	v_mfma_f32_16x16x32_bf16 v[104:107], v[136:139], v[192:195], v[104:107]
	v_mfma_f32_16x16x32_bf16 v[92:95], v[128:131], v[200:203], v[92:95]
	v_mfma_f32_16x16x32_bf16 v[88:91], v[136:139], v[200:203], v[88:91]
	v_mfma_f32_16x16x32_bf16 v[76:79], v[128:131], v[208:211], v[76:79]
	v_mfma_f32_16x16x32_bf16 v[72:75], v[136:139], v[208:211], v[72:75]
	v_mfma_f32_16x16x32_bf16 v[124:127], v[132:135], v[180:183], v[124:127]
	v_mfma_f32_16x16x32_bf16 v[120:123], v[140:143], v[180:183], v[120:123]
	v_mfma_f32_16x16x32_bf16 v[108:111], v[132:135], v[196:199], v[108:111]
	v_mfma_f32_16x16x32_bf16 v[104:107], v[140:143], v[196:199], v[104:107]
	v_mfma_f32_16x16x32_bf16 v[92:95], v[132:135], v[204:207], v[92:95]
	v_mfma_f32_16x16x32_bf16 v[88:91], v[140:143], v[204:207], v[88:91]
	v_mfma_f32_16x16x32_bf16 v[76:79], v[132:135], v[212:215], v[76:79]
	v_mfma_f32_16x16x32_bf16 v[72:75], v[140:143], v[212:215], v[72:75]
	s_setprio 0
	s_setprio 1
	v_mfma_f32_16x16x32_bf16 v[116:119], v[144:147], v[176:179], v[116:119]
	v_mfma_f32_16x16x32_bf16 v[112:115], v[168:171], v[176:179], v[112:115]
	v_mfma_f32_16x16x32_bf16 v[100:103], v[144:147], v[192:195], v[100:103]
	v_mfma_f32_16x16x32_bf16 v[96:99], v[168:171], v[192:195], v[96:99]
	v_mfma_f32_16x16x32_bf16 v[84:87], v[144:147], v[200:203], v[84:87]
	v_mfma_f32_16x16x32_bf16 v[80:83], v[168:171], v[200:203], v[80:83]
	v_mfma_f32_16x16x32_bf16 v[68:71], v[144:147], v[208:211], v[68:71]
	v_mfma_f32_16x16x32_bf16 v[64:67], v[168:171], v[208:211], v[64:67]
	v_mfma_f32_16x16x32_bf16 v[116:119], v[148:151], v[180:183], v[116:119]
	v_mfma_f32_16x16x32_bf16 v[112:115], v[172:175], v[180:183], v[112:115]
	v_mfma_f32_16x16x32_bf16 v[100:103], v[148:151], v[196:199], v[100:103]
	v_mfma_f32_16x16x32_bf16 v[96:99], v[172:175], v[196:199], v[96:99]
	v_mfma_f32_16x16x32_bf16 v[84:87], v[148:151], v[204:207], v[84:87]
	v_mfma_f32_16x16x32_bf16 v[80:83], v[172:175], v[204:207], v[80:83]
	v_mfma_f32_16x16x32_bf16 v[68:71], v[148:151], v[212:215], v[68:71]
	v_mfma_f32_16x16x32_bf16 v[64:67], v[172:175], v[212:215], v[64:67]
	s_setprio 0
	s_barrier
	s_add_i32 s60, s53, s68
	v_lshl_add_u64 v[184:185], s[44:45], 0, v[154:155]
	s_mov_b32 m0, s60
	ds_read_b128 v[176:179], v191 offset:16384
	ds_read_b128 v[180:183], v191 offset:17408
	ds_read_b128 v[192:195], v191 offset:18432
	ds_read_b128 v[196:199], v191 offset:19456
	ds_read_b128 v[200:203], v191 offset:20480
	ds_read_b128 v[204:207], v191 offset:21504
	ds_read_b128 v[208:211], v191 offset:22528
	ds_read_b128 v[212:215], v191 offset:23552
	global_load_lds_dwordx4 v[184:185], off
	s_add_i32 m0, s60, 0x2000
	s_add_u32 s60, s44, 0x40000
	v_lshl_add_u64 v[216:217], s[44:45], 0, v[158:159]
	s_addc_u32 s61, s45, 0
	s_add_i32 s62, s54, s68
	global_load_lds_dwordx4 v[216:217], off
	s_mov_b32 m0, s62
	v_lshl_add_u64 v[220:221], s[46:47], 0, v[156:157]
	global_load_lds_dwordx4 v154, s[60:61]
	s_add_i32 m0, s62, 0x2000
	s_nop 0
	global_load_lds_dwordx4 v158, s[60:61]
	v_lshl_add_u64 v[218:219], s[46:47], 0, v[152:153]
	s_mov_b32 m0, s74
	s_nop 0
	global_load_lds_dwordx4 v[218:219], off
	s_mov_b32 m0, s66
	s_nop 0
	global_load_lds_dwordx4 v[220:221], off
	s_waitcnt vmcnt(8)
	s_waitcnt lgkmcnt(0)
	s_barrier
; #define PG8_STAGE(bufoff, gbase, voff) do { _Pragma("unroll") for (int _i = 0; _i < 2; ++_i) \
;         __builtin_amdgcn_global_load_lds((const unsigned*)((const char*)(gbase) + (voff)[_i]), (PG8_LAS unsigned*)(lds + (bufoff) + ldsw + _i * 8192), 16, 0, 0); } while (0)
; #define PG8_LDA(dst, b, h) do { _Pragma("unroll") for (int m = 0; m < 4; ++m) _Pragma("unroll") for (int k = 0; k < 2; ++k) dst[m][k] = *(const PG8_LAS bf16x8*)(lds + PG8_SA(b, h) + aoff + m * 2048 + k * 1024); } while (0)
; #define PG8_LDB(dst, b, h) do { _Pragma("unroll") for (int n = 0; n < 2; ++n) _Pragma("unroll") for (int k = 0; k < 2; ++k) dst[n][k] = *(const PG8_LAS bf16x8*)(lds + PG8_SB(b, h) + boff + n * 2048 + k * 1024); } while (0)
; #define PG8_MMA(ai, bj, At, Bt) do { __builtin_amdgcn_s_setprio(1); _Pragma("unroll") for (int m = 0; m < 4; ++m) _Pragma("unroll") for (int n = 0; n < 2; ++n) _Pragma("unroll") for (int k = 0; k < 2; ++k) \
;         acc[ai][bj][m][n] = mma16<F16>(Bt[n][k], At[m][k], acc[ai][bj][m][n]); __builtin_amdgcn_s_setprio(0); } while (0)
; #define PG8_WAIT_V(n) asm volatile("s_waitcnt vmcnt(" #n ")" ::: "memory")
; #define PG8_WAIT_L(n) asm volatile("s_waitcnt lgkmcnt(" #n ")" ::: "memory")
; #define PG8_BAR __builtin_amdgcn_s_barrier()
; #define PG8_SCHED __builtin_amdgcn_sched_barrier(0)
; template <class Epi, class Sched, bool ALIGN_EPI = false, bool SP2 = false, bool F16 = false>
; __device__ __forceinline__ void gemm_phase(PG8_LAS unsigned char* lds, const Gemm g, const Sched& S, const Epi& E, const int wid_in) {
;     ...
;             PG8_LDA(At, 0, 1); PG8_STAGE(PG8_SB(0, 0), b2, voffB); PG8_STAGE(PG8_SB(0, 1), b2 + hstep, voffB); PG8_STAGE(PG8_SA(0, 0), a2, voffA);
;             PG8_WAIT_V(8); PG8_WAIT_L(0); PG8_BAR; PG8_MMA(1, 0, At, B0); PG8_MMA(1, 1, At, B1); PG8_BAR; PG8_SCHED;
;             PG8_LDB(B0, 1, 0); PG8_LDB(B1, 1, 1); PG8_SCHED; PG8_LDA(At, 1, 0); PG8_STAGE(PG8_SA(0, 1), a2 + hstep, voffA);
;             PG8_WAIT_V(8); PG8_WAIT_L(0); PG8_BAR; PG8_MMA(0, 0, At, B0); PG8_MMA(0, 1, At, B1); PG8_BAR; PG8_SCHED;
;             PG8_LDA(At, 1, 1); PG8_STAGE(PG8_SB(1, 0), b3, voffB); PG8_STAGE(PG8_SB(1, 1), b3 + hstep, voffB); PG8_STAGE(PG8_SA(1, 0), a3, voffA);
	s_setprio 1
	s_waitcnt lgkmcnt(0)
	v_mfma_f32_16x16x32_bf16 v[60:63], v[128:131], v[176:179], v[60:63]
	v_mfma_f32_16x16x32_bf16 v[56:59], v[136:139], v[176:179], v[56:59]
	v_mfma_f32_16x16x32_bf16 v[44:47], v[128:131], v[192:195], v[44:47]
	v_mfma_f32_16x16x32_bf16 v[40:43], v[136:139], v[192:195], v[40:43]
	v_mfma_f32_16x16x32_bf16 v[28:31], v[128:131], v[200:203], v[28:31]
	v_mfma_f32_16x16x32_bf16 v[24:27], v[136:139], v[200:203], v[24:27]
	v_mfma_f32_16x16x32_bf16 v[12:15], v[128:131], v[208:211], v[12:15]
	v_mfma_f32_16x16x32_bf16 v[8:11], v[136:139], v[208:211], v[8:11]
	v_mfma_f32_16x16x32_bf16 v[60:63], v[132:135], v[180:183], v[60:63]
	v_mfma_f32_16x16x32_bf16 v[56:59], v[140:143], v[180:183], v[56:59]
	v_mfma_f32_16x16x32_bf16 v[44:47], v[132:135], v[196:199], v[44:47]
	v_mfma_f32_16x16x32_bf16 v[40:43], v[140:143], v[196:199], v[40:43]
	v_mfma_f32_16x16x32_bf16 v[28:31], v[132:135], v[204:207], v[28:31]
	v_mfma_f32_16x16x32_bf16 v[24:27], v[140:143], v[204:207], v[24:27]
	v_mfma_f32_16x16x32_bf16 v[12:15], v[132:135], v[212:215], v[12:15]
	v_mfma_f32_16x16x32_bf16 v[8:11], v[140:143], v[212:215], v[8:11]
	s_setprio 0
	s_setprio 1
	v_mfma_f32_16x16x32_bf16 v[52:55], v[144:147], v[176:179], v[52:55]
	v_mfma_f32_16x16x32_bf16 v[48:51], v[168:171], v[176:179], v[48:51]
	v_mfma_f32_16x16x32_bf16 v[36:39], v[144:147], v[192:195], v[36:39]
	v_mfma_f32_16x16x32_bf16 v[32:35], v[168:171], v[192:195], v[32:35]
	v_mfma_f32_16x16x32_bf16 v[20:23], v[144:147], v[200:203], v[20:23]
	v_mfma_f32_16x16x32_bf16 v[16:19], v[168:171], v[200:203], v[16:19]
	v_mfma_f32_16x16x32_bf16 v[4:7], v[144:147], v[208:211], v[4:7]
	v_mfma_f32_16x16x32_bf16 v[0:3], v[168:171], v[208:211], v[0:3]
	v_mfma_f32_16x16x32_bf16 v[52:55], v[148:151], v[180:183], v[52:55]
	v_mfma_f32_16x16x32_bf16 v[48:51], v[172:175], v[180:183], v[48:51]
	v_mfma_f32_16x16x32_bf16 v[36:39], v[148:151], v[196:199], v[36:39]
	v_mfma_f32_16x16x32_bf16 v[32:35], v[172:175], v[196:199], v[32:35]
	v_mfma_f32_16x16x32_bf16 v[20:23], v[148:151], v[204:207], v[20:23]
	v_mfma_f32_16x16x32_bf16 v[16:19], v[172:175], v[204:207], v[16:19]
	v_mfma_f32_16x16x32_bf16 v[4:7], v[148:151], v[212:215], v[4:7]
	v_mfma_f32_16x16x32_bf16 v[0:3], v[172:175], v[212:215], v[0:3]
	s_setprio 0
	s_barrier
	s_add_i32 s60, 0, 0x18000
	s_add_i32 s61, 0, 0x1c000
	v_add_u32_e32 v140, s60, v188
	v_add_u32_e32 v172, s61, v188
	ds_read_b128 v[128:131], v140
	ds_read_b128 v[132:135], v140 offset:1024
	ds_read_b128 v[136:139], v140 offset:2048
	ds_read_b128 v[140:143], v140 offset:3072
	ds_read_b128 v[144:147], v172
	ds_read_b128 v[148:151], v172 offset:1024
	ds_read_b128 v[168:171], v172 offset:2048
	ds_read_b128 v[172:175], v172 offset:3072
	s_add_u32 s46, s46, 0x40000
	s_addc_u32 s47, s47, 0
	s_mov_b32 m0, s90
	ds_read_b128 v[176:179], v191 offset:32768
	ds_read_b128 v[180:183], v191 offset:33792
	ds_read_b128 v[192:195], v191 offset:34816
	ds_read_b128 v[196:199], v191 offset:35840
	ds_read_b128 v[200:203], v191 offset:36864
	ds_read_b128 v[204:207], v191 offset:37888
	ds_read_b128 v[208:211], v191 offset:38912
	ds_read_b128 v[212:215], v191 offset:39936
	global_load_lds_dwordx4 v152, s[46:47]
	v_lshl_add_u64 v[222:223], s[46:47], 0, v[156:157]
	s_mov_b32 m0, s49
	s_nop 0
	global_load_lds_dwordx4 v[222:223], off
	s_waitcnt vmcnt(8)
	s_waitcnt lgkmcnt(0)
	s_barrier
	s_setprio 1
	s_waitcnt lgkmcnt(0)
	v_mfma_f32_16x16x32_bf16 v[124:127], v[128:131], v[176:179], v[124:127]
	v_mfma_f32_16x16x32_bf16 v[120:123], v[136:139], v[176:179], v[120:123]
	v_mfma_f32_16x16x32_bf16 v[108:111], v[128:131], v[192:195], v[108:111]
	v_mfma_f32_16x16x32_bf16 v[104:107], v[136:139], v[192:195], v[104:107]
	v_mfma_f32_16x16x32_bf16 v[92:95], v[128:131], v[200:203], v[92:95]
	v_mfma_f32_16x16x32_bf16 v[88:91], v[136:139], v[200:203], v[88:91]
	v_mfma_f32_16x16x32_bf16 v[76:79], v[128:131], v[208:211], v[76:79]
	v_mfma_f32_16x16x32_bf16 v[72:75], v[136:139], v[208:211], v[72:75]
	v_mfma_f32_16x16x32_bf16 v[124:127], v[132:135], v[180:183], v[124:127]
	v_mfma_f32_16x16x32_bf16 v[120:123], v[140:143], v[180:183], v[120:123]
	v_mfma_f32_16x16x32_bf16 v[108:111], v[132:135], v[196:199], v[108:111]
	v_mfma_f32_16x16x32_bf16 v[104:107], v[140:143], v[196:199], v[104:107]
	v_mfma_f32_16x16x32_bf16 v[92:95], v[132:135], v[204:207], v[92:95]
	v_mfma_f32_16x16x32_bf16 v[88:91], v[140:143], v[204:207], v[88:91]
	v_mfma_f32_16x16x32_bf16 v[76:79], v[132:135], v[212:215], v[76:79]
	v_mfma_f32_16x16x32_bf16 v[72:75], v[140:143], v[212:215], v[72:75]
	s_setprio 0
	s_setprio 1
	v_mfma_f32_16x16x32_bf16 v[116:119], v[144:147], v[176:179], v[116:119]
	v_mfma_f32_16x16x32_bf16 v[112:115], v[168:171], v[176:179], v[112:115]
	v_mfma_f32_16x16x32_bf16 v[100:103], v[144:147], v[192:195], v[100:103]
	v_mfma_f32_16x16x32_bf16 v[96:99], v[168:171], v[192:195], v[96:99]
	v_mfma_f32_16x16x32_bf16 v[84:87], v[144:147], v[200:203], v[84:87]
	v_mfma_f32_16x16x32_bf16 v[80:83], v[168:171], v[200:203], v[80:83]
	v_mfma_f32_16x16x32_bf16 v[68:71], v[144:147], v[208:211], v[68:71]
	v_mfma_f32_16x16x32_bf16 v[64:67], v[168:171], v[208:211], v[64:67]
	v_mfma_f32_16x16x32_bf16 v[116:119], v[148:151], v[180:183], v[116:119]
	v_mfma_f32_16x16x32_bf16 v[112:115], v[172:175], v[180:183], v[112:115]
	v_mfma_f32_16x16x32_bf16 v[100:103], v[148:151], v[196:199], v[100:103]
	v_mfma_f32_16x16x32_bf16 v[96:99], v[172:175], v[196:199], v[96:99]
	v_mfma_f32_16x16x32_bf16 v[84:87], v[148:151], v[204:207], v[84:87]
	v_mfma_f32_16x16x32_bf16 v[80:83], v[172:175], v[204:207], v[80:83]
	v_mfma_f32_16x16x32_bf16 v[68:71], v[148:151], v[212:215], v[68:71]
	v_mfma_f32_16x16x32_bf16 v[64:67], v[172:175], v[212:215], v[64:67]
	s_setprio 0
	s_barrier
; #define PG8_STAGE(bufoff, gbase, voff) do { _Pragma("unroll") for (int _i = 0; _i < 2; ++_i) \
;         __builtin_amdgcn_global_load_lds((const unsigned*)((const char*)(gbase) + (voff)[_i]), (PG8_LAS unsigned*)(lds + (bufoff) + ldsw + _i * 8192), 16, 0, 0); } while (0)
; #define PG8_LDA(dst, b, h) do { _Pragma("unroll") for (int m = 0; m < 4; ++m) _Pragma("unroll") for (int k = 0; k < 2; ++k) dst[m][k] = *(const PG8_LAS bf16x8*)(lds + PG8_SA(b, h) + aoff + m * 2048 + k * 1024); } while (0)
; #define PG8_MMA(ai, bj, At, Bt) do { __builtin_amdgcn_s_setprio(1); _Pragma("unroll") for (int m = 0; m < 4; ++m) _Pragma("unroll") for (int n = 0; n < 2; ++n) _Pragma("unroll") for (int k = 0; k < 2; ++k) \
;         acc[ai][bj][m][n] = mma16<F16>(Bt[n][k], At[m][k], acc[ai][bj][m][n]); __builtin_amdgcn_s_setprio(0); } while (0)
; #define PG8_WAIT_V(n) asm volatile("s_waitcnt vmcnt(" #n ")" ::: "memory")
; #define PG8_WAIT_L(n) asm volatile("s_waitcnt lgkmcnt(" #n ")" ::: "memory")
; #define PG8_BAR __builtin_amdgcn_s_barrier()
; #define PG8_SCHED __builtin_amdgcn_sched_barrier(0)
; template <class Epi, class Sched, bool ALIGN_EPI = false, bool SP2 = false, bool F16 = false>
; __device__ __forceinline__ void gemm_phase(PG8_LAS unsigned char* lds, const Gemm g, const Sched& S, const Epi& E, const int wid_in) {
;     ...
;             PG8_LDA(At, 1, 1); PG8_STAGE(PG8_SB(1, 0), b3, voffB); PG8_STAGE(PG8_SB(1, 1), b3 + hstep, voffB); PG8_STAGE(PG8_SA(1, 0), a3, voffA);
;             PG8_WAIT_V(8); PG8_WAIT_L(0); PG8_BAR; PG8_MMA(1, 0, At, B0); PG8_MMA(1, 1, At, B1); PG8_BAR; PG8_SCHED;
	s_add_i32 s46, s60, s68
	v_lshl_add_u64 v[184:185], v[184:185], 0, s[24:25]
	s_mov_b32 m0, s46
	ds_read_b128 v[176:179], v191 offset:49152
	ds_read_b128 v[180:183], v191 offset:50176
	ds_read_b128 v[192:195], v191 offset:51200
	ds_read_b128 v[196:199], v191 offset:52224
	ds_read_b128 v[200:203], v191 offset:53248
	ds_read_b128 v[204:207], v191 offset:54272
	ds_read_b128 v[208:211], v191 offset:55296
	ds_read_b128 v[212:215], v191 offset:56320
	global_load_lds_dwordx4 v[184:185], off
	s_add_i32 m0, s46, 0x2000
	s_add_u32 s44, s44, 0x40080
	v_lshl_add_u64 v[184:185], v[216:217], 0, s[24:25]
	s_addc_u32 s45, s45, 0
	s_add_i32 s46, s61, s68
	global_load_lds_dwordx4 v[184:185], off
	s_mov_b32 m0, s46
	s_nop 0
	global_load_lds_dwordx4 v154, s[44:45]
	s_add_i32 m0, s46, 0x2000
	s_nop 0
	global_load_lds_dwordx4 v158, s[44:45]
	v_lshl_add_u64 v[184:185], v[218:219], 0, s[24:25]
	s_mov_b32 m0, s75
	s_nop 0
	global_load_lds_dwordx4 v[184:185], off
	v_lshl_add_u64 v[184:185], v[220:221], 0, s[24:25]
	s_mov_b32 m0, s67
	s_nop 0
	global_load_lds_dwordx4 v[184:185], off
	s_waitcnt vmcnt(8)
	s_waitcnt lgkmcnt(0)
	s_barrier
	s_setprio 1
	s_waitcnt lgkmcnt(0)
	v_mfma_f32_16x16x32_bf16 v[60:63], v[128:131], v[176:179], v[60:63]
	v_mfma_f32_16x16x32_bf16 v[56:59], v[136:139], v[176:179], v[56:59]
	v_mfma_f32_16x16x32_bf16 v[44:47], v[128:131], v[192:195], v[44:47]
	v_mfma_f32_16x16x32_bf16 v[40:43], v[136:139], v[192:195], v[40:43]
	v_mfma_f32_16x16x32_bf16 v[28:31], v[128:131], v[200:203], v[28:31]
	v_mfma_f32_16x16x32_bf16 v[24:27], v[136:139], v[200:203], v[24:27]
	v_mfma_f32_16x16x32_bf16 v[12:15], v[128:131], v[208:211], v[12:15]
	v_mfma_f32_16x16x32_bf16 v[8:11], v[136:139], v[208:211], v[8:11]
	v_mfma_f32_16x16x32_bf16 v[60:63], v[132:135], v[180:183], v[60:63]
	v_mfma_f32_16x16x32_bf16 v[56:59], v[140:143], v[180:183], v[56:59]
	v_mfma_f32_16x16x32_bf16 v[44:47], v[132:135], v[196:199], v[44:47]
	v_mfma_f32_16x16x32_bf16 v[40:43], v[140:143], v[196:199], v[40:43]
	v_mfma_f32_16x16x32_bf16 v[28:31], v[132:135], v[204:207], v[28:31]
	v_mfma_f32_16x16x32_bf16 v[24:27], v[140:143], v[204:207], v[24:27]
	v_mfma_f32_16x16x32_bf16 v[12:15], v[132:135], v[212:215], v[12:15]
	v_mfma_f32_16x16x32_bf16 v[8:11], v[140:143], v[212:215], v[8:11]
	s_setprio 0
	s_setprio 1
	v_mfma_f32_16x16x32_bf16 v[52:55], v[144:147], v[176:179], v[52:55]
	v_mfma_f32_16x16x32_bf16 v[48:51], v[168:171], v[176:179], v[48:51]
	v_mfma_f32_16x16x32_bf16 v[36:39], v[144:147], v[192:195], v[36:39]
	v_mfma_f32_16x16x32_bf16 v[32:35], v[168:171], v[192:195], v[32:35]
	v_mfma_f32_16x16x32_bf16 v[20:23], v[144:147], v[200:203], v[20:23]
	v_mfma_f32_16x16x32_bf16 v[16:19], v[168:171], v[200:203], v[16:19]
	v_mfma_f32_16x16x32_bf16 v[4:7], v[144:147], v[208:211], v[4:7]
	v_mfma_f32_16x16x32_bf16 v[0:3], v[168:171], v[208:211], v[0:3]
	v_mfma_f32_16x16x32_bf16 v[52:55], v[148:151], v[180:183], v[52:55]
	v_mfma_f32_16x16x32_bf16 v[48:51], v[172:175], v[180:183], v[48:51]
	v_mfma_f32_16x16x32_bf16 v[36:39], v[148:151], v[196:199], v[36:39]
	v_mfma_f32_16x16x32_bf16 v[32:35], v[172:175], v[196:199], v[32:35]
	v_mfma_f32_16x16x32_bf16 v[20:23], v[148:151], v[204:207], v[20:23]
	v_mfma_f32_16x16x32_bf16 v[16:19], v[172:175], v[204:207], v[16:19]
	v_mfma_f32_16x16x32_bf16 v[4:7], v[148:151], v[212:215], v[4:7]
	v_mfma_f32_16x16x32_bf16 v[0:3], v[172:175], v[212:215], v[0:3]
	s_setprio 0
	s_barrier
	s_add_i32 s59, s59, 2
	s_add_u32 s42, s42, 0x100
	s_addc_u32 s43, s43, 0
	s_add_u32 s57, s57, 0x100
	s_addc_u32 s58, s58, 0
	s_cmp_gt_u32 s59, 13
	s_cbranch_scc0 .LBB0_2489
	s_and_b64 vcc, exec, s[16:17]
	s_cbranch_vccz .LBB0_2492
	s_barrier

; #define PG8_STAGE(bufoff, gbase, voff) do { _Pragma("unroll") for (int _i = 0; _i < 2; ++_i) \
;         __builtin_amdgcn_global_load_lds((const unsigned*)((const char*)(gbase) + (voff)[_i]), (PG8_LAS unsigned*)(lds + (bufoff) + ldsw + _i * 8192), 16, 0, 0); } while (0)
; #define PG8_WAIT_V(n) asm volatile("s_waitcnt vmcnt(" #n ")" ::: "memory")
; #define PG8_BAR __builtin_amdgcn_s_barrier()
; template <class Epi, class Sched, bool ALIGN_EPI = false, bool SP2 = false, bool F16 = false>
; __device__ __forceinline__ void gemm_phase(PG8_LAS unsigned char* lds, const Gemm g, const Sched& S, const Epi& E, const int wid_in) {
;     ...
;     for (int i = 0; i < 2; ++i) { int R, C; stage_rc(tid * 16 + i * 8192, R, C); const int Rb = Epi::PERM ? ((R & ~31) + perm32(R & 31)) : R;
;         voffA[i] = (unsigned)(R * K + C) * 2u; voffB[i] = (unsigned)(Rb * K + C) * 2u; }
;     const size_t kstep = (size_t)(BK * 2);
;     const size_t hstep = (size_t)HALF * K * 2;
;     const size_t tstep = 2 * hstep;
;     const unsigned ldsw = (unsigned)wid * 1024u;
;     const int aoff = lds_byte(wr * 64 + fr, fq * 8), boff = lds_byte(wc * 32 + fr, fq * 8);
;     ...
;         PG8_STAGE(PG8_SB(1, 0), cB + kstep, voffB); PG8_STAGE(PG8_SA(1, 0), cA + kstep, voffA); PG8_STAGE(PG8_SB(1, 1), cB + hstep + kstep, voffB);
;         PG8_WAIT_V(6); PG8_BAR;
;     } else {
;         PG8_STAGE(PG8_SB(0, 0), cB, voffB); PG8_STAGE(PG8_SA(0, 0), cA, voffA); PG8_STAGE(PG8_SB(0, 1), cB + hstep, voffB); PG8_STAGE(PG8_SA(0, 1), cA + hstep, voffA);
;         if (wr == 1) PG8_BAR;
;         PG8_WAIT_V(4); PG8_BAR;
;         PG8_STAGE(PG8_SB(1, 0), cB + kstep, voffB); PG8_STAGE(PG8_SA(1, 0), cA + kstep, voffA); PG8_STAGE(PG8_SB(1, 1), cB + hstep + kstep, voffB);
;         PG8_WAIT_V(6); PG8_BAR;
;     }
.LBB0_2560:
	s_add_u32 s12, s14, 0x15600000
	s_addc_u32 s13, s15, 0
	s_add_u32 s18, s14, 0x9400000
	s_mov_b64 s[20:21], 0x80
	s_addc_u32 s19, s15, 0
	s_add_i32 m0, s74, 0x18000
	v_lshl_add_u64 v[6:7], v[6:7], 0, s[20:21]
	s_waitcnt vmcnt(2)
	s_barrier
	global_load_lds_dwordx4 v[6:7], off
	v_lshl_add_u64 v[4:5], v[4:5], 0, s[20:21]
	s_add_i32 m0, s74, 0x1a000
	v_lshl_add_u64 v[0:1], v[0:1], 0, s[20:21]
	global_load_lds_dwordx4 v[4:5], off
	s_mov_b32 m0, s75
	s_add_u32 s10, s42, 0x40080
	global_load_lds_dwordx4 v[0:1], off
	v_lshl_add_u64 v[0:1], v[2:3], 0, s[20:21]
	s_mov_b32 m0, s67
	s_addc_u32 s11, s43, 0
	global_load_lds_dwordx4 v[0:1], off
	s_add_i32 m0, s74, 0x1c000
	s_nop 0
	global_load_lds_dwordx4 v162, s[10:11]
	s_add_i32 m0, s74, 0x1e000
	v_and_b32_e32 v190, 15, v8
	global_load_lds_dwordx4 v166, s[10:11]
	v_or_b32_e32 v0, s70, v190
	v_lshlrev_b32_e32 v1, 6, v0
	v_and_b32_e32 v2, 48, v8
	s_movk_i32 s10, 0x3c0
	v_and_b32_e32 v3, 0xfffffc00, v12
	v_lshlrev_b32_e32 v0, 2, v0
	v_and_or_b32 v1, v1, s10, v2
	v_add_u32_e32 v4, s73, v3
	v_and_b32_e32 v0, 32, v0
	v_bitop3_b32 v0, v1, v4, v0 bitop3:0xde
	v_lshl_or_b32 v1, v190, 6, v2
	v_add_u32_e32 v2, s72, v3
	v_lshlrev_b32_e32 v3, 2, v8
	v_and_b32_e32 v3, 32, v3
	v_bitop3_b32 v192, v1, v2, v3 bitop3:0xde
	v_lshlrev_b32_e32 v1, 14, v9
	v_and_b32_e32 v1, 0xffff8000, v1
	v_lshl_add_u32 v1, v10, 11, v1
	v_and_b32_e32 v2, 1, v9
	v_lshl_or_b32 v1, v2, 6, v1
	v_lshl_add_u32 v168, v11, 1, v1
	v_lshlrev_b32_e32 v1, 14, v13
	v_and_b32_e32 v1, 0xffff8000, v1
	s_waitcnt vmcnt(6)
	s_mul_i32 s10, s3, 0x210
	v_lshl_add_u32 v1, v14, 11, v1
	v_and_b32_e32 v2, 1, v13
	s_add_i32 s54, s10, 0
	v_lshl_or_b32 v1, v2, 6, v1
	s_add_i32 s56, 0, 0x10000
	s_add_i32 s57, 0, 0x14000
	v_ashrrev_i32_e32 v191, 4, v8
	s_ashr_i32 s51, s38, 31
	s_mov_b32 s52, s38
	s_ashr_i32 s53, s40, 31
	s_add_i32 s54, s54, 0x20400
	v_mov_b32_e32 v169, v163
	v_lshl_add_u32 v170, v15, 1, v1
	v_mov_b32_e32 v171, v163
	v_mov_b64_e32 v[172:173], 0x580
	v_mov_b64_e32 v[174:175], 0x57f
	s_movk_i32 s55, 0xb1
	v_add_u32_e32 v193, s56, v192
	v_add_u32_e32 v194, s57, v192
	v_add_u32_e32 v195, 0, v0
	v_mov_b32_e32 v196, 0x358637bd
	s_movk_i32 s58, 0x1600
	s_barrier
	s_branch .LBB0_2563

; #define PG8_STAGE(bufoff, gbase, voff) do { _Pragma("unroll") for (int _i = 0; _i < 2; ++_i) \
;         __builtin_amdgcn_global_load_lds((const unsigned*)((const char*)(gbase) + (voff)[_i]), (PG8_LAS unsigned*)(lds + (bufoff) + ldsw + _i * 8192), 16, 0, 0); } while (0)
; #define PG8_LDA(dst, b, h) do { _Pragma("unroll") for (int m = 0; m < 4; ++m) _Pragma("unroll") for (int k = 0; k < 2; ++k) dst[m][k] = *(const PG8_LAS bf16x8*)(lds + PG8_SA(b, h) + aoff + m * 2048 + k * 1024); } while (0)
; #define PG8_LDB(dst, b, h) do { _Pragma("unroll") for (int n = 0; n < 2; ++n) _Pragma("unroll") for (int k = 0; k < 2; ++k) dst[n][k] = *(const PG8_LAS bf16x8*)(lds + PG8_SB(b, h) + boff + n * 2048 + k * 1024); } while (0)
; #define PG8_MMA(ai, bj, At, Bt) do { __builtin_amdgcn_s_setprio(1); _Pragma("unroll") for (int m = 0; m < 4; ++m) _Pragma("unroll") for (int n = 0; n < 2; ++n) _Pragma("unroll") for (int k = 0; k < 2; ++k) \
;         acc[ai][bj][m][n] = mma16<F16>(Bt[n][k], At[m][k], acc[ai][bj][m][n]); __builtin_amdgcn_s_setprio(0); } while (0)
; #define PG8_WAIT_V(n) asm volatile("s_waitcnt vmcnt(" #n ")" ::: "memory")
; #define PG8_WAIT_L(n) asm volatile("s_waitcnt lgkmcnt(" #n ")" ::: "memory")
; template <class Epi, class Sched, bool ALIGN_EPI = false, bool SP2 = false, bool F16 = false>
; __device__ __forceinline__ void gemm_phase(PG8_LAS unsigned char* lds, const Gemm g, const Sched& S, const Epi& E, const int wid_in) {
;     ...
;             const bool last = (t == nt - 2);
;             const char* a1 = cA + (size_t)(t + 1) * kstep;
;             const char* a2 = last ? nA : cA + (size_t)(t + 2) * kstep; const char* b2 = last ? nB : cB + (size_t)(t + 2) * kstep;
;             const char* a3 = a2 + kstep; const char* b3 = b2 + kstep;
;             if (last && has_next) S.a_ready(nxt);
;             if constexpr (SP2) {
;             PG8_LDB(B0, 0, 0); PG8_LDB(B1, 0, 1); PG8_SCHED; PG8_LDA(At, 0, 0); PG8_STAGE(PG8_SA(1, 1), a1 + hstep, voffA);
;             PG8_WAIT_V(8); PG8_WAIT_L(0); PG8_BAR; PG8_MMA(0, 0, At, B0); PG8_MMA(0, 1, At, B1); PG8_BAR; PG8_SCHED;
;             PG8_LDA(At, 0, 1); PG8_STAGE(PG8_SB(0, 0), b2, voffB); PG8_STAGE(PG8_SB(0, 1), b2 + hstep, voffB); PG8_STAGE(PG8_SA(0, 0), a2, voffA);
;             PG8_WAIT_V(8); PG8_WAIT_L(0); PG8_BAR; PG8_MMA(1, 0, At, B0); PG8_MMA(1, 1, At, B1); PG8_BAR; PG8_SCHED;
.LBB0_2566:
	ds_read_b128 v[0:3], v193
	ds_read_b128 v[4:7], v193 offset:1024
	ds_read_b128 v[136:139], v193 offset:2048
	ds_read_b128 v[140:143], v193 offset:3072
	ds_read_b128 v[144:147], v194
	ds_read_b128 v[148:151], v194 offset:1024
	ds_read_b128 v[152:155], v194 offset:2048
	ds_read_b128 v[156:159], v194 offset:3072
	s_add_u32 s42, s36, 0xfffc0080
	s_addc_u32 s43, s37, -1
	s_cmp_eq_u32 s62, 12
	s_cselect_b32 s45, s25, s43
	s_cselect_b32 s44, s35, s42
	s_cselect_b32 s43, s23, s61
	s_cselect_b32 s42, s59, s60
	s_mov_b32 m0, s91
	ds_read_b128 v[176:179], v195
	ds_read_b128 v[180:183], v195 offset:1024
	ds_read_b128 v[184:187], v195 offset:2048
	ds_read_b128 v[198:201], v195 offset:3072
	ds_read_b128 v[202:205], v195 offset:4096
	ds_read_b128 v[206:209], v195 offset:5120
	ds_read_b128 v[210:213], v195 offset:6144
	ds_read_b128 v[214:217], v195 offset:7168
	global_load_lds_dwordx4 v168, s[36:37]
	s_add_i32 m0, s74, 0xe000
	s_nop 0
	global_load_lds_dwordx4 v170, s[36:37]
	s_waitcnt vmcnt(8)
	s_waitcnt lgkmcnt(0)
	s_barrier
	s_setprio 1
	s_waitcnt lgkmcnt(0)
	v_mfma_f32_16x16x32_f16 v[132:135], v[0:3], v[176:179], v[132:135]
	v_mfma_f32_16x16x32_f16 v[128:131], v[136:139], v[176:179], v[128:131]
	v_mfma_f32_16x16x32_f16 v[116:119], v[0:3], v[184:187], v[116:119]
	v_mfma_f32_16x16x32_f16 v[112:115], v[136:139], v[184:187], v[112:115]
	v_mfma_f32_16x16x32_f16 v[100:103], v[0:3], v[202:205], v[100:103]
	v_mfma_f32_16x16x32_f16 v[96:99], v[136:139], v[202:205], v[96:99]
	v_mfma_f32_16x16x32_f16 v[84:87], v[0:3], v[210:213], v[84:87]
	v_mfma_f32_16x16x32_f16 v[80:83], v[136:139], v[210:213], v[80:83]
	v_mfma_f32_16x16x32_f16 v[132:135], v[4:7], v[180:183], v[132:135]
	v_mfma_f32_16x16x32_f16 v[128:131], v[140:143], v[180:183], v[128:131]
	v_mfma_f32_16x16x32_f16 v[116:119], v[4:7], v[198:201], v[116:119]
	v_mfma_f32_16x16x32_f16 v[112:115], v[140:143], v[198:201], v[112:115]
	v_mfma_f32_16x16x32_f16 v[100:103], v[4:7], v[206:209], v[100:103]
	v_mfma_f32_16x16x32_f16 v[96:99], v[140:143], v[206:209], v[96:99]
	v_mfma_f32_16x16x32_f16 v[84:87], v[4:7], v[214:217], v[84:87]
	v_mfma_f32_16x16x32_f16 v[80:83], v[140:143], v[214:217], v[80:83]
	s_setprio 0
	s_setprio 1
	v_mfma_f32_16x16x32_f16 v[124:127], v[144:147], v[176:179], v[124:127]
	v_mfma_f32_16x16x32_f16 v[120:123], v[152:155], v[176:179], v[120:123]
	v_mfma_f32_16x16x32_f16 v[108:111], v[144:147], v[184:187], v[108:111]
	v_mfma_f32_16x16x32_f16 v[104:107], v[152:155], v[184:187], v[104:107]
	v_mfma_f32_16x16x32_f16 v[92:95], v[144:147], v[202:205], v[92:95]
	v_mfma_f32_16x16x32_f16 v[88:91], v[152:155], v[202:205], v[88:91]
	v_mfma_f32_16x16x32_f16 v[76:79], v[144:147], v[210:213], v[76:79]
	v_mfma_f32_16x16x32_f16 v[72:75], v[152:155], v[210:213], v[72:75]
	v_mfma_f32_16x16x32_f16 v[124:127], v[148:151], v[180:183], v[124:127]
	v_mfma_f32_16x16x32_f16 v[120:123], v[156:159], v[180:183], v[120:123]
	v_mfma_f32_16x16x32_f16 v[108:111], v[148:151], v[198:201], v[108:111]
	v_mfma_f32_16x16x32_f16 v[104:107], v[156:159], v[198:201], v[104:107]
	v_mfma_f32_16x16x32_f16 v[92:95], v[148:151], v[206:209], v[92:95]
	v_mfma_f32_16x16x32_f16 v[88:91], v[156:159], v[206:209], v[88:91]
	v_mfma_f32_16x16x32_f16 v[76:79], v[148:151], v[214:217], v[76:79]
	v_mfma_f32_16x16x32_f16 v[72:75], v[156:159], v[214:217], v[72:75]
	s_setprio 0
	s_barrier
	s_add_i32 s63, s56, s68
	v_lshl_add_u64 v[188:189], s[42:43], 0, v[162:163]
	s_mov_b32 m0, s63
	ds_read_b128 v[176:179], v195 offset:16384
	ds_read_b128 v[180:183], v195 offset:17408
	ds_read_b128 v[184:187], v195 offset:18432
	ds_read_b128 v[198:201], v195 offset:19456
	ds_read_b128 v[202:205], v195 offset:20480
	ds_read_b128 v[206:209], v195 offset:21504
	ds_read_b128 v[210:213], v195 offset:22528
	ds_read_b128 v[214:217], v195 offset:23552
	global_load_lds_dwordx4 v[188:189], off
	s_add_i32 m0, s63, 0x2000
	s_add_u32 s64, s42, 0x40000
	v_lshl_add_u64 v[218:219], s[42:43], 0, v[166:167]
	s_addc_u32 s65, s43, 0
	s_add_i32 s63, s57, s68
	global_load_lds_dwordx4 v[218:219], off
	s_mov_b32 m0, s63
	v_lshl_add_u64 v[222:223], s[44:45], 0, v[164:165]
	global_load_lds_dwordx4 v162, s[64:65]
	s_add_i32 m0, s63, 0x2000
	s_nop 0
	global_load_lds_dwordx4 v166, s[64:65]
	v_lshl_add_u64 v[220:221], s[44:45], 0, v[160:161]
	s_mov_b32 m0, s74
	s_nop 0
	global_load_lds_dwordx4 v[220:221], off
	s_mov_b32 m0, s66
	s_nop 0
	global_load_lds_dwordx4 v[222:223], off
	s_waitcnt vmcnt(8)
	s_waitcnt lgkmcnt(0)
	s_barrier
	s_setprio 1
	s_waitcnt lgkmcnt(0)
	v_mfma_f32_16x16x32_f16 v[68:71], v[0:3], v[176:179], v[68:71]
	v_mfma_f32_16x16x32_f16 v[64:67], v[136:139], v[176:179], v[64:67]
	v_mfma_f32_16x16x32_f16 v[52:55], v[0:3], v[184:187], v[52:55]
	v_mfma_f32_16x16x32_f16 v[48:51], v[136:139], v[184:187], v[48:51]
	v_mfma_f32_16x16x32_f16 v[36:39], v[0:3], v[202:205], v[36:39]
	v_mfma_f32_16x16x32_f16 v[32:35], v[136:139], v[202:205], v[32:35]
	v_mfma_f32_16x16x32_f16 v[0:3], v[0:3], v[210:213], v[20:23]
	v_mfma_f32_16x16x32_f16 v[68:71], v[4:7], v[180:183], v[68:71]
	v_mfma_f32_16x16x32_f16 v[64:67], v[140:143], v[180:183], v[64:67]
	v_mfma_f32_16x16x32_f16 v[52:55], v[4:7], v[198:201], v[52:55]
	v_mfma_f32_16x16x32_f16 v[48:51], v[140:143], v[198:201], v[48:51]
	v_mfma_f32_16x16x32_f16 v[36:39], v[4:7], v[206:209], v[36:39]
	v_mfma_f32_16x16x32_f16 v[32:35], v[140:143], v[206:209], v[32:35]
	v_mfma_f32_16x16x32_f16 v[0:3], v[4:7], v[214:217], v[0:3]
	v_mfma_f32_16x16x32_f16 v[4:7], v[136:139], v[210:213], v[16:19]
	v_mfma_f32_16x16x32_f16 v[4:7], v[140:143], v[214:217], v[4:7]
	s_setprio 0
	s_setprio 1
	v_mfma_f32_16x16x32_f16 v[16:19], v[144:147], v[176:179], v[60:63]
	v_mfma_f32_16x16x32_f16 v[60:63], v[148:151], v[180:183], v[16:19]
	v_mfma_f32_16x16x32_f16 v[16:19], v[152:155], v[176:179], v[56:59]
	v_mfma_f32_16x16x32_f16 v[56:59], v[156:159], v[180:183], v[16:19]
	v_mfma_f32_16x16x32_f16 v[16:19], v[144:147], v[184:187], v[44:47]
	v_mfma_f32_16x16x32_f16 v[44:47], v[148:151], v[198:201], v[16:19]
	v_mfma_f32_16x16x32_f16 v[16:19], v[152:155], v[184:187], v[40:43]
	v_mfma_f32_16x16x32_f16 v[40:43], v[156:159], v[198:201], v[16:19]
	v_mfma_f32_16x16x32_f16 v[16:19], v[144:147], v[202:205], v[28:31]
	v_mfma_f32_16x16x32_f16 v[28:31], v[148:151], v[206:209], v[16:19]
	v_mfma_f32_16x16x32_f16 v[16:19], v[152:155], v[202:205], v[24:27]
	v_mfma_f32_16x16x32_f16 v[12:15], v[144:147], v[210:213], v[12:15]
	v_mfma_f32_16x16x32_f16 v[8:11], v[152:155], v[210:213], v[8:11]
	v_mfma_f32_16x16x32_f16 v[24:27], v[156:159], v[206:209], v[16:19]
	v_mfma_f32_16x16x32_f16 v[12:15], v[148:151], v[214:217], v[12:15]
	v_mfma_f32_16x16x32_f16 v[8:11], v[156:159], v[214:217], v[8:11]
	s_setprio 0
	s_barrier
; #define PG8_STAGE(bufoff, gbase, voff) do { _Pragma("unroll") for (int _i = 0; _i < 2; ++_i) \
;         __builtin_amdgcn_global_load_lds((const unsigned*)((const char*)(gbase) + (voff)[_i]), (PG8_LAS unsigned*)(lds + (bufoff) + ldsw + _i * 8192), 16, 0, 0); } while (0)
; #define PG8_LDA(dst, b, h) do { _Pragma("unroll") for (int m = 0; m < 4; ++m) _Pragma("unroll") for (int k = 0; k < 2; ++k) dst[m][k] = *(const PG8_LAS bf16x8*)(lds + PG8_SA(b, h) + aoff + m * 2048 + k * 1024); } while (0)
; #define PG8_LDB(dst, b, h) do { _Pragma("unroll") for (int n = 0; n < 2; ++n) _Pragma("unroll") for (int k = 0; k < 2; ++k) dst[n][k] = *(const PG8_LAS bf16x8*)(lds + PG8_SB(b, h) + boff + n * 2048 + k * 1024); } while (0)
; #define PG8_MMA(ai, bj, At, Bt) do { __builtin_amdgcn_s_setprio(1); _Pragma("unroll") for (int m = 0; m < 4; ++m) _Pragma("unroll") for (int n = 0; n < 2; ++n) _Pragma("unroll") for (int k = 0; k < 2; ++k) \
;         acc[ai][bj][m][n] = mma16<F16>(Bt[n][k], At[m][k], acc[ai][bj][m][n]); __builtin_amdgcn_s_setprio(0); } while (0)
; #define PG8_WAIT_V(n) asm volatile("s_waitcnt vmcnt(" #n ")" ::: "memory")
; #define PG8_WAIT_L(n) asm volatile("s_waitcnt lgkmcnt(" #n ")" ::: "memory")
; #define PG8_BAR __builtin_amdgcn_s_barrier()
; #define PG8_SCHED __builtin_amdgcn_sched_barrier(0)
; template <class Epi, class Sched, bool ALIGN_EPI = false, bool SP2 = false, bool F16 = false>
; __device__ __forceinline__ void gemm_phase(PG8_LAS unsigned char* lds, const Gemm g, const Sched& S, const Epi& E, const int wid_in) {
;     ...
;             PG8_LDB(B0, 1, 0); PG8_LDB(B1, 1, 1); PG8_SCHED; PG8_LDA(At, 1, 0); PG8_STAGE(PG8_SA(0, 1), a2 + hstep, voffA);
;             PG8_WAIT_V(8); PG8_WAIT_L(0); PG8_BAR; PG8_MMA(0, 0, At, B0); PG8_MMA(0, 1, At, B1); PG8_BAR; PG8_SCHED;
;             PG8_LDA(At, 1, 1); PG8_STAGE(PG8_SB(1, 0), b3, voffB); PG8_STAGE(PG8_SB(1, 1), b3 + hstep, voffB); PG8_STAGE(PG8_SA(1, 0), a3, voffA);
;             PG8_WAIT_V(8); PG8_WAIT_L(0); PG8_BAR; PG8_MMA(1, 0, At, B0); PG8_MMA(1, 1, At, B1); PG8_BAR; PG8_SCHED;
	s_add_i32 s63, 0, 0x18000
	s_add_i32 s64, 0, 0x1c000
	v_add_u32_e32 v140, s63, v192
	v_add_u32_e32 v156, s64, v192
	ds_read_b128 v[16:19], v140
	ds_read_b128 v[20:23], v140 offset:1024
	ds_read_b128 v[136:139], v140 offset:2048
	ds_read_b128 v[140:143], v140 offset:3072
	ds_read_b128 v[144:147], v156
	ds_read_b128 v[148:151], v156 offset:1024
	ds_read_b128 v[152:155], v156 offset:2048
	ds_read_b128 v[156:159], v156 offset:3072
	s_add_u32 s44, s44, 0x40000
	s_addc_u32 s45, s45, 0
	s_mov_b32 m0, s90
	ds_read_b128 v[176:179], v195 offset:32768
	ds_read_b128 v[180:183], v195 offset:33792
	ds_read_b128 v[184:187], v195 offset:34816
	ds_read_b128 v[198:201], v195 offset:35840
	ds_read_b128 v[202:205], v195 offset:36864
	ds_read_b128 v[206:209], v195 offset:37888
	ds_read_b128 v[210:213], v195 offset:38912
	ds_read_b128 v[214:217], v195 offset:39936
	global_load_lds_dwordx4 v160, s[44:45]
	v_lshl_add_u64 v[224:225], s[44:45], 0, v[164:165]
	s_mov_b32 m0, s31
	s_nop 0
	global_load_lds_dwordx4 v[224:225], off
	s_waitcnt vmcnt(8)
	s_waitcnt lgkmcnt(0)
	s_barrier
	s_setprio 1
	s_waitcnt lgkmcnt(0)
	v_mfma_f32_16x16x32_f16 v[132:135], v[16:19], v[176:179], v[132:135]
	v_mfma_f32_16x16x32_f16 v[128:131], v[136:139], v[176:179], v[128:131]
	v_mfma_f32_16x16x32_f16 v[116:119], v[16:19], v[184:187], v[116:119]
	v_mfma_f32_16x16x32_f16 v[112:115], v[136:139], v[184:187], v[112:115]
	v_mfma_f32_16x16x32_f16 v[100:103], v[16:19], v[202:205], v[100:103]
	v_mfma_f32_16x16x32_f16 v[96:99], v[136:139], v[202:205], v[96:99]
	v_mfma_f32_16x16x32_f16 v[84:87], v[16:19], v[210:213], v[84:87]
	v_mfma_f32_16x16x32_f16 v[80:83], v[136:139], v[210:213], v[80:83]
	v_mfma_f32_16x16x32_f16 v[132:135], v[20:23], v[180:183], v[132:135]
	v_mfma_f32_16x16x32_f16 v[128:131], v[140:143], v[180:183], v[128:131]
	v_mfma_f32_16x16x32_f16 v[116:119], v[20:23], v[198:201], v[116:119]
	v_mfma_f32_16x16x32_f16 v[112:115], v[140:143], v[198:201], v[112:115]
	v_mfma_f32_16x16x32_f16 v[100:103], v[20:23], v[206:209], v[100:103]
	v_mfma_f32_16x16x32_f16 v[96:99], v[140:143], v[206:209], v[96:99]
	v_mfma_f32_16x16x32_f16 v[84:87], v[20:23], v[214:217], v[84:87]
	v_mfma_f32_16x16x32_f16 v[80:83], v[140:143], v[214:217], v[80:83]
	s_setprio 0
	s_setprio 1
	v_mfma_f32_16x16x32_f16 v[124:127], v[144:147], v[176:179], v[124:127]
	v_mfma_f32_16x16x32_f16 v[120:123], v[152:155], v[176:179], v[120:123]
	v_mfma_f32_16x16x32_f16 v[108:111], v[144:147], v[184:187], v[108:111]
	v_mfma_f32_16x16x32_f16 v[104:107], v[152:155], v[184:187], v[104:107]
	v_mfma_f32_16x16x32_f16 v[92:95], v[144:147], v[202:205], v[92:95]
	v_mfma_f32_16x16x32_f16 v[88:91], v[152:155], v[202:205], v[88:91]
	v_mfma_f32_16x16x32_f16 v[76:79], v[144:147], v[210:213], v[76:79]
	v_mfma_f32_16x16x32_f16 v[72:75], v[152:155], v[210:213], v[72:75]
	v_mfma_f32_16x16x32_f16 v[124:127], v[148:151], v[180:183], v[124:127]
	v_mfma_f32_16x16x32_f16 v[120:123], v[156:159], v[180:183], v[120:123]
	v_mfma_f32_16x16x32_f16 v[108:111], v[148:151], v[198:201], v[108:111]
	v_mfma_f32_16x16x32_f16 v[104:107], v[156:159], v[198:201], v[104:107]
	v_mfma_f32_16x16x32_f16 v[92:95], v[148:151], v[206:209], v[92:95]
	v_mfma_f32_16x16x32_f16 v[88:91], v[156:159], v[206:209], v[88:91]
	v_mfma_f32_16x16x32_f16 v[76:79], v[148:151], v[214:217], v[76:79]
	v_mfma_f32_16x16x32_f16 v[72:75], v[156:159], v[214:217], v[72:75]
	s_setprio 0
	s_barrier
	s_add_i32 s44, s63, s68
	v_lshl_add_u64 v[188:189], v[188:189], 0, s[20:21]
	s_mov_b32 m0, s44
	ds_read_b128 v[176:179], v195 offset:49152
	ds_read_b128 v[180:183], v195 offset:50176
	ds_read_b128 v[184:187], v195 offset:51200
	ds_read_b128 v[198:201], v195 offset:52224
	ds_read_b128 v[202:205], v195 offset:53248
	ds_read_b128 v[206:209], v195 offset:54272
	ds_read_b128 v[210:213], v195 offset:55296
	ds_read_b128 v[214:217], v195 offset:56320
	global_load_lds_dwordx4 v[188:189], off
	s_add_i32 m0, s44, 0x2000
	s_add_u32 s42, s42, 0x40080
	v_lshl_add_u64 v[188:189], v[218:219], 0, s[20:21]
	s_addc_u32 s43, s43, 0
	s_add_i32 s44, s64, s68
	global_load_lds_dwordx4 v[188:189], off
	s_mov_b32 m0, s44
	s_nop 0
	global_load_lds_dwordx4 v162, s[42:43]
	s_add_i32 m0, s44, 0x2000
	s_nop 0
	global_load_lds_dwordx4 v166, s[42:43]
	v_lshl_add_u64 v[188:189], v[220:221], 0, s[20:21]
	s_mov_b32 m0, s75
	s_nop 0
	global_load_lds_dwordx4 v[188:189], off
	v_lshl_add_u64 v[188:189], v[222:223], 0, s[20:21]
	s_mov_b32 m0, s67
	s_nop 0
	global_load_lds_dwordx4 v[188:189], off
	s_waitcnt vmcnt(8)
	s_waitcnt lgkmcnt(0)
	s_barrier
	s_setprio 1
	s_waitcnt lgkmcnt(0)
	v_mfma_f32_16x16x32_f16 v[68:71], v[16:19], v[176:179], v[68:71]
	v_mfma_f32_16x16x32_f16 v[52:55], v[16:19], v[184:187], v[52:55]
	v_mfma_f32_16x16x32_f16 v[36:39], v[16:19], v[202:205], v[36:39]
	v_mfma_f32_16x16x32_f16 v[0:3], v[16:19], v[210:213], v[0:3]
	v_mfma_f32_16x16x32_f16 v[68:71], v[20:23], v[180:183], v[68:71]
	v_mfma_f32_16x16x32_f16 v[64:67], v[136:139], v[176:179], v[64:67]
	v_mfma_f32_16x16x32_f16 v[52:55], v[20:23], v[198:201], v[52:55]
	v_mfma_f32_16x16x32_f16 v[48:51], v[136:139], v[184:187], v[48:51]
	v_mfma_f32_16x16x32_f16 v[36:39], v[20:23], v[206:209], v[36:39]
	v_mfma_f32_16x16x32_f16 v[32:35], v[136:139], v[202:205], v[32:35]
	v_mfma_f32_16x16x32_f16 v[20:23], v[20:23], v[214:217], v[0:3]
	v_mfma_f32_16x16x32_f16 v[0:3], v[136:139], v[210:213], v[4:7]
	v_mfma_f32_16x16x32_f16 v[64:67], v[140:143], v[180:183], v[64:67]
	v_mfma_f32_16x16x32_f16 v[48:51], v[140:143], v[198:201], v[48:51]
	v_mfma_f32_16x16x32_f16 v[32:35], v[140:143], v[206:209], v[32:35]
	v_mfma_f32_16x16x32_f16 v[16:19], v[140:143], v[214:217], v[0:3]
	s_setprio 0
	s_setprio 1
	v_mfma_f32_16x16x32_f16 v[0:3], v[144:147], v[176:179], v[60:63]
	v_mfma_f32_16x16x32_f16 v[60:63], v[148:151], v[180:183], v[0:3]
	v_mfma_f32_16x16x32_f16 v[0:3], v[152:155], v[176:179], v[56:59]
	v_mfma_f32_16x16x32_f16 v[56:59], v[156:159], v[180:183], v[0:3]
	v_mfma_f32_16x16x32_f16 v[0:3], v[144:147], v[184:187], v[44:47]
	v_mfma_f32_16x16x32_f16 v[44:47], v[148:151], v[198:201], v[0:3]
	v_mfma_f32_16x16x32_f16 v[0:3], v[152:155], v[184:187], v[40:43]
	v_mfma_f32_16x16x32_f16 v[40:43], v[156:159], v[198:201], v[0:3]
	v_mfma_f32_16x16x32_f16 v[0:3], v[144:147], v[202:205], v[28:31]
	v_mfma_f32_16x16x32_f16 v[28:31], v[148:151], v[206:209], v[0:3]
	v_mfma_f32_16x16x32_f16 v[0:3], v[152:155], v[202:205], v[24:27]
	v_mfma_f32_16x16x32_f16 v[24:27], v[156:159], v[206:209], v[0:3]
	v_mfma_f32_16x16x32_f16 v[0:3], v[144:147], v[210:213], v[12:15]
	v_mfma_f32_16x16x32_f16 v[12:15], v[148:151], v[214:217], v[0:3]
	v_mfma_f32_16x16x32_f16 v[0:3], v[152:155], v[210:213], v[8:11]
	v_mfma_f32_16x16x32_f16 v[8:11], v[156:159], v[214:217], v[0:3]
	s_setprio 0
	s_barrier
	s_add_i32 s62, s62, 2
	s_add_u32 s36, s36, 0x100
	s_addc_u32 s37, s37, 0
	s_add_u32 s60, s60, 0x100
	s_addc_u32 s61, s61, 0
	s_cmp_gt_u32 s62, 13
	s_cbranch_scc0 .LBB0_2566
	s_and_b64 vcc, exec, s[16:17]
	s_cbranch_vccz .LBB0_2569
	s_barrier

; #define PG8_STAGE(bufoff, gbase, voff) do { _Pragma("unroll") for (int _i = 0; _i < 2; ++_i) \
;         __builtin_amdgcn_global_load_lds((const unsigned*)((const char*)(gbase) + (voff)[_i]), (PG8_LAS unsigned*)(lds + (bufoff) + ldsw + _i * 8192), 16, 0, 0); } while (0)
; #define PG8_WAIT_V(n) asm volatile("s_waitcnt vmcnt(" #n ")" ::: "memory")
; #define PG8_BAR __builtin_amdgcn_s_barrier()
; template <class Epi, class Sched, bool ALIGN_EPI = false, bool SP2 = false, bool F16 = false>
; __device__ __forceinline__ void gemm_phase(PG8_LAS unsigned char* lds, const Gemm g, const Sched& S, const Epi& E, const int wid_in) {
;     ...
;     for (int i = 0; i < 2; ++i) { int R, C; stage_rc(tid * 16 + i * 8192, R, C); const int Rb = Epi::PERM ? ((R & ~31) + perm32(R & 31)) : R;
;         voffA[i] = (unsigned)(R * K + C) * 2u; voffB[i] = (unsigned)(Rb * K + C) * 2u; }
;     const size_t kstep = (size_t)(BK * 2);
;     const size_t hstep = (size_t)HALF * K * 2;
;     const size_t tstep = 2 * hstep;
;     const unsigned ldsw = (unsigned)wid * 1024u;
;     const int aoff = lds_byte(wr * 64 + fr, fq * 8), boff = lds_byte(wc * 32 + fr, fq * 8);
;     ...
;         PG8_STAGE(PG8_SB(1, 0), cB + kstep, voffB); PG8_STAGE(PG8_SA(1, 0), cA + kstep, voffA); PG8_STAGE(PG8_SB(1, 1), cB + hstep + kstep, voffB);
;         PG8_WAIT_V(6); PG8_BAR;
;     } else {
;         PG8_STAGE(PG8_SB(0, 0), cB, voffB); PG8_STAGE(PG8_SA(0, 0), cA, voffA); PG8_STAGE(PG8_SB(0, 1), cB + hstep, voffB); PG8_STAGE(PG8_SA(0, 1), cA + hstep, voffA);
;         if (wr == 1) PG8_BAR;
;         PG8_WAIT_V(4); PG8_BAR;
;         PG8_STAGE(PG8_SB(1, 0), cB + kstep, voffB); PG8_STAGE(PG8_SA(1, 0), cA + kstep, voffA); PG8_STAGE(PG8_SB(1, 1), cB + hstep + kstep, voffB);
;         PG8_WAIT_V(6); PG8_BAR;
;     }
.LBB0_2598:
	s_add_u32 s18, s14, 0xf400000
	s_mov_b64 s[20:21], 0x80
	s_addc_u32 s19, s15, 0
	s_add_i32 m0, s74, 0x18000
	v_lshl_add_u64 v[6:7], v[6:7], 0, s[20:21]
	s_waitcnt vmcnt(2)
	s_barrier
	global_load_lds_dwordx4 v[6:7], off
	v_lshl_add_u64 v[4:5], v[4:5], 0, s[20:21]
	s_add_i32 m0, s74, 0x1a000
	v_lshl_add_u64 v[2:3], v[2:3], 0, s[20:21]
	global_load_lds_dwordx4 v[4:5], off
	s_mov_b32 m0, s75
	s_add_u32 s14, s10, 0x10080
	global_load_lds_dwordx4 v[2:3], off
	v_lshl_add_u64 v[0:1], v[0:1], 0, s[20:21]
	s_mov_b32 m0, s67
	s_addc_u32 s15, s11, 0
	global_load_lds_dwordx4 v[0:1], off
	s_add_i32 m0, s74, 0x1c000
	s_nop 0
	global_load_lds_dwordx4 v130, s[14:15]
	s_add_i32 m0, s74, 0x1e000
	v_and_b32_e32 v132, 15, v8
	global_load_lds_dwordx4 v128, s[14:15]
	v_or_b32_e32 v0, s70, v132
	v_ashrrev_i32_e32 v1, 6, v8
	v_lshlrev_b32_e32 v2, 6, v0
	v_and_b32_e32 v3, 48, v8
	s_movk_i32 s14, 0x3c0
	v_lshlrev_b32_e32 v0, 2, v0
	v_and_or_b32 v2, v2, s14, v3
	v_lshl_add_u32 v4, v1, 10, s73
	v_and_b32_e32 v0, 32, v0
	v_bitop3_b32 v0, v2, v4, v0 bitop3:0xde
	v_lshl_or_b32 v2, v132, 6, v3
	v_lshlrev_b32_e32 v3, 2, v8
	v_add_lshl_u32 v1, v1, s96, 10
	v_and_b32_e32 v3, 32, v3
	v_bitop3_b32 v1, v2, v1, v3 bitop3:0xde
	s_waitcnt vmcnt(6)
	s_add_i32 s15, 0, 0x10000
	s_add_i32 s49, 0, 0x14000
	s_add_i32 s51, 0, 0x18000
	s_add_i32 s53, 0, 0x1c000
	v_add_u32_e32 v134, s15, v1
	v_add_u32_e32 v135, s49, v1
	s_add_i32 s15, s15, s68
	s_add_i32 s49, s49, s68
	v_add_u32_e32 v137, s51, v1
	v_add_u32_e32 v138, s53, v1
	s_add_i32 s51, s51, s68
	s_add_i32 s53, s53, s68
	v_ashrrev_i32_e32 v133, 4, v8
	s_mov_b64 s[26:27], -1
	v_add_u32_e32 v136, 0, v0
	s_add_i32 s14, s74, 0xe000
	s_mov_b64 s[22:23], 0x100
	s_add_i32 s48, s15, 0x2000
	s_add_i32 s50, s49, 0x2000
	s_mov_b64 s[24:25], 0x180
	s_add_i32 s52, s51, 0x2000
	s_add_i32 s54, s53, 0x2000
	s_barrier
	s_branch .LBB0_2601

; #define PG8_STAGE(bufoff, gbase, voff) do { _Pragma("unroll") for (int _i = 0; _i < 2; ++_i) \
;         __builtin_amdgcn_global_load_lds((const unsigned*)((const char*)(gbase) + (voff)[_i]), (PG8_LAS unsigned*)(lds + (bufoff) + ldsw + _i * 8192), 16, 0, 0); } while (0)
; #define PG8_LDA(dst, b, h) do { _Pragma("unroll") for (int m = 0; m < 4; ++m) _Pragma("unroll") for (int k = 0; k < 2; ++k) dst[m][k] = *(const PG8_LAS bf16x8*)(lds + PG8_SA(b, h) + aoff + m * 2048 + k * 1024); } while (0)
; #define PG8_LDB(dst, b, h) do { _Pragma("unroll") for (int n = 0; n < 2; ++n) _Pragma("unroll") for (int k = 0; k < 2; ++k) dst[n][k] = *(const PG8_LAS bf16x8*)(lds + PG8_SB(b, h) + boff + n * 2048 + k * 1024); } while (0)
; #define PG8_MMA(ai, bj, At, Bt) do { __builtin_amdgcn_s_setprio(1); _Pragma("unroll") for (int m = 0; m < 4; ++m) _Pragma("unroll") for (int n = 0; n < 2; ++n) _Pragma("unroll") for (int k = 0; k < 2; ++k) \
;         acc[ai][bj][m][n] = mma16<F16>(Bt[n][k], At[m][k], acc[ai][bj][m][n]); __builtin_amdgcn_s_setprio(0); } while (0)
; #define PG8_BAR __builtin_amdgcn_s_barrier()
; template <class Epi, class Sched, bool ALIGN_EPI = false, bool SP2 = false, bool F16 = false>
; __device__ __forceinline__ void gemm_phase(PG8_LAS unsigned char* lds, const Gemm g, const Sched& S, const Epi& E, const int wid_in) {
;     ...
;         const bool has_next = S.next(ui + 1, nxt);
;         const char* nA = has_next ? (const char*)g.A + (size_t)nxt.pm * tstep : cA; const char* nB = has_next ? (const char*)g.Bt + (size_t)nxt.pn * tstep : cB;
;         for (int t = 0; t < nt; t += 2) {
;             const bool last = (t == nt - 2);
;             const char* a1 = cA + (size_t)(t + 1) * kstep;
;             const char* a2 = last ? nA : cA + (size_t)(t + 2) * kstep; const char* b2 = last ? nB : cB + (size_t)(t + 2) * kstep;
;             const char* a3 = a2 + kstep; const char* b3 = b2 + kstep;
;             if (last && has_next) S.a_ready(nxt);
;             if constexpr (SP2) {
;             PG8_LDB(B0, 0, 0); PG8_LDB(B1, 0, 1); PG8_SCHED; PG8_LDA(At, 0, 0); PG8_STAGE(PG8_SA(1, 1), a1 + hstep, voffA);
;             PG8_WAIT_V(8); PG8_WAIT_L(0); PG8_BAR; PG8_MMA(0, 0, At, B0); PG8_MMA(0, 1, At, B1); PG8_BAR; PG8_SCHED;
;             PG8_LDA(At, 0, 1); PG8_STAGE(PG8_SB(0, 0), b2, voffB); PG8_STAGE(PG8_SB(0, 1), b2 + hstep, voffB); PG8_STAGE(PG8_SA(0, 0), a2, voffA);
.LBB0_2601:
	s_mov_b64 s[42:43], s[10:11]
	s_add_i32 s10, s30, s40
	s_mov_b64 s[36:37], s[12:13]
	s_mov_b32 s12, s56
	s_mov_b32 s13, s55
	s_and_b32 s55, s10, 3
	s_ashr_i32 s56, s10, 2
	s_and_b64 s[10:11], s[26:27], exec
	s_cselect_b32 s12, s56, s12
	ds_read_b128 v[0:3], v134
	ds_read_b128 v[4:7], v134 offset:1024
	ds_read_b128 v[8:11], v134 offset:2048
	ds_read_b128 v[12:15], v134 offset:3072
	ds_read_b128 v[16:19], v135
	ds_read_b128 v[20:23], v135 offset:1024
	ds_read_b128 v[24:27], v135 offset:2048
	ds_read_b128 v[28:31], v135 offset:3072
	s_cselect_b32 s10, s55, s13
	s_ashr_i32 s13, s12, 31
	s_lshl_b64 s[12:13], s[12:13], 17
	s_add_u32 s12, s41, s12
	s_addc_u32 s13, s44, s13
	s_and_b64 s[30:31], s[26:27], exec
	s_cselect_b32 s35, s13, s37
	s_cselect_b32 s34, s12, s36
	s_ashr_i32 s11, s10, 31
	s_lshl_b64 s[10:11], s[10:11], 17
	s_add_u32 s10, s45, s10
	s_addc_u32 s11, s46, s11
	s_and_b64 s[30:31], s[26:27], exec
	s_cselect_b32 s31, s11, s43
	s_cselect_b32 s30, s10, s42
	s_add_u32 s58, s36, 0x10080
	s_addc_u32 s59, s37, 0
	s_mov_b32 m0, s91
	ds_read_b128 v[32:35], v136
	ds_read_b128 v[36:39], v136 offset:1024
	ds_read_b128 v[40:43], v136 offset:2048
	ds_read_b128 v[44:47], v136 offset:3072
	ds_read_b128 v[48:51], v136 offset:4096
	ds_read_b128 v[52:55], v136 offset:5120
	ds_read_b128 v[56:59], v136 offset:6144
	ds_read_b128 v[60:63], v136 offset:7168
	global_load_lds_dwordx4 v130, s[58:59]
	s_mov_b32 m0, s14
	s_nop 0
	global_load_lds_dwordx4 v128, s[58:59]
	s_waitcnt vmcnt(8)
	s_waitcnt lgkmcnt(0)
	s_barrier
	s_setprio 1
	s_waitcnt lgkmcnt(0)
	v_mfma_f32_16x16x32_bf16 v[64:67], v[0:3], v[32:35], 0
	v_mfma_f32_16x16x32_bf16 v[68:71], v[8:11], v[32:35], 0
	v_mfma_f32_16x16x32_bf16 v[72:75], v[0:3], v[40:43], 0
	v_mfma_f32_16x16x32_bf16 v[76:79], v[8:11], v[40:43], 0
	v_mfma_f32_16x16x32_bf16 v[80:83], v[0:3], v[48:51], 0
	v_mfma_f32_16x16x32_bf16 v[84:87], v[8:11], v[48:51], 0
	v_mfma_f32_16x16x32_bf16 v[88:91], v[0:3], v[56:59], 0
	v_mfma_f32_16x16x32_bf16 v[92:95], v[8:11], v[56:59], 0
	v_mfma_f32_16x16x32_bf16 v[64:67], v[4:7], v[36:39], v[64:67]
	v_mfma_f32_16x16x32_bf16 v[68:71], v[12:15], v[36:39], v[68:71]
	v_mfma_f32_16x16x32_bf16 v[72:75], v[4:7], v[44:47], v[72:75]
	v_mfma_f32_16x16x32_bf16 v[76:79], v[12:15], v[44:47], v[76:79]
	v_mfma_f32_16x16x32_bf16 v[80:83], v[4:7], v[52:55], v[80:83]
	v_mfma_f32_16x16x32_bf16 v[84:87], v[12:15], v[52:55], v[84:87]
	v_mfma_f32_16x16x32_bf16 v[88:91], v[4:7], v[60:63], v[88:91]
	v_mfma_f32_16x16x32_bf16 v[92:95], v[12:15], v[60:63], v[92:95]
	s_setprio 0
	s_setprio 1
	v_mfma_f32_16x16x32_bf16 v[96:99], v[16:19], v[32:35], 0
	v_mfma_f32_16x16x32_bf16 v[32:35], v[24:27], v[32:35], 0
	v_mfma_f32_16x16x32_bf16 v[96:99], v[20:23], v[36:39], v[96:99]
	v_mfma_f32_16x16x32_bf16 v[32:35], v[28:31], v[36:39], v[32:35]
	v_mfma_f32_16x16x32_bf16 v[36:39], v[16:19], v[40:43], 0
	v_mfma_f32_16x16x32_bf16 v[40:43], v[24:27], v[40:43], 0
	v_mfma_f32_16x16x32_bf16 v[36:39], v[20:23], v[44:47], v[36:39]
	v_mfma_f32_16x16x32_bf16 v[40:43], v[28:31], v[44:47], v[40:43]
	v_mfma_f32_16x16x32_bf16 v[44:47], v[16:19], v[48:51], 0
	v_mfma_f32_16x16x32_bf16 v[48:51], v[24:27], v[48:51], 0
	v_mfma_f32_16x16x32_bf16 v[44:47], v[20:23], v[52:55], v[44:47]
	v_mfma_f32_16x16x32_bf16 v[48:51], v[28:31], v[52:55], v[48:51]
	v_mfma_f32_16x16x32_bf16 v[52:55], v[16:19], v[56:59], 0
	v_mfma_f32_16x16x32_bf16 v[56:59], v[24:27], v[56:59], 0
	v_mfma_f32_16x16x32_bf16 v[52:55], v[20:23], v[60:63], v[52:55]
	v_mfma_f32_16x16x32_bf16 v[56:59], v[28:31], v[60:63], v[56:59]
	s_setprio 0
	s_barrier
	v_lshl_add_u64 v[204:205], s[42:43], 0, v[130:131]
	s_mov_b32 m0, s15
	v_lshl_add_u64 v[140:141], v[204:205], 0, s[22:23]
	v_lshl_add_u64 v[206:207], s[42:43], 0, v[128:129]
	s_add_u32 s58, s42, 0x10100
	ds_read_b128 v[60:63], v136 offset:16384
	ds_read_b128 v[100:103], v136 offset:17408
	ds_read_b128 v[104:107], v136 offset:18432
	ds_read_b128 v[108:111], v136 offset:19456
	ds_read_b128 v[112:115], v136 offset:20480
	ds_read_b128 v[116:119], v136 offset:21504
	ds_read_b128 v[120:123], v136 offset:22528
	ds_read_b128 v[124:127], v136 offset:23552
	global_load_lds_dwordx4 v[140:141], off
	v_lshl_add_u64 v[140:141], v[206:207], 0, s[22:23]
	s_mov_b32 m0, s48
	s_addc_u32 s59, s43, 0
	global_load_lds_dwordx4 v[140:141], off
	s_mov_b32 m0, s49
	v_lshl_add_u64 v[208:209], s[36:37], 0, v[130:131]
	global_load_lds_dwordx4 v130, s[58:59]
	s_mov_b32 m0, s50
	v_lshl_add_u64 v[210:211], s[36:37], 0, v[128:129]
	global_load_lds_dwordx4 v128, s[58:59]
	v_lshl_add_u64 v[140:141], v[208:209], 0, s[22:23]
	s_mov_b32 m0, s74
	s_nop 0
	global_load_lds_dwordx4 v[140:141], off
	v_lshl_add_u64 v[140:141], v[210:211], 0, s[22:23]
	s_mov_b32 m0, s66
	s_nop 0
	global_load_lds_dwordx4 v[140:141], off
	s_waitcnt vmcnt(8)
	s_waitcnt lgkmcnt(0)
	s_barrier
; #define PG8_STAGE(bufoff, gbase, voff) do { _Pragma("unroll") for (int _i = 0; _i < 2; ++_i) \
;         __builtin_amdgcn_global_load_lds((const unsigned*)((const char*)(gbase) + (voff)[_i]), (PG8_LAS unsigned*)(lds + (bufoff) + ldsw + _i * 8192), 16, 0, 0); } while (0)
; #define PG8_LDA(dst, b, h) do { _Pragma("unroll") for (int m = 0; m < 4; ++m) _Pragma("unroll") for (int k = 0; k < 2; ++k) dst[m][k] = *(const PG8_LAS bf16x8*)(lds + PG8_SA(b, h) + aoff + m * 2048 + k * 1024); } while (0)
; #define PG8_LDB(dst, b, h) do { _Pragma("unroll") for (int n = 0; n < 2; ++n) _Pragma("unroll") for (int k = 0; k < 2; ++k) dst[n][k] = *(const PG8_LAS bf16x8*)(lds + PG8_SB(b, h) + boff + n * 2048 + k * 1024); } while (0)
; #define PG8_MMA(ai, bj, At, Bt) do { __builtin_amdgcn_s_setprio(1); _Pragma("unroll") for (int m = 0; m < 4; ++m) _Pragma("unroll") for (int n = 0; n < 2; ++n) _Pragma("unroll") for (int k = 0; k < 2; ++k) \
;         acc[ai][bj][m][n] = mma16<F16>(Bt[n][k], At[m][k], acc[ai][bj][m][n]); __builtin_amdgcn_s_setprio(0); } while (0)
; #define PG8_WAIT_V(n) asm volatile("s_waitcnt vmcnt(" #n ")" ::: "memory")
; #define PG8_WAIT_L(n) asm volatile("s_waitcnt lgkmcnt(" #n ")" ::: "memory")
; #define PG8_BAR __builtin_amdgcn_s_barrier()
; #define PG8_SCHED __builtin_amdgcn_sched_barrier(0)
; template <class Epi, class Sched, bool ALIGN_EPI = false, bool SP2 = false, bool F16 = false>
; __device__ __forceinline__ void gemm_phase(PG8_LAS unsigned char* lds, const Gemm g, const Sched& S, const Epi& E, const int wid_in) {
;     ...
;             PG8_LDA(At, 0, 1); PG8_STAGE(PG8_SB(0, 0), b2, voffB); PG8_STAGE(PG8_SB(0, 1), b2 + hstep, voffB); PG8_STAGE(PG8_SA(0, 0), a2, voffA);
;             PG8_WAIT_V(8); PG8_WAIT_L(0); PG8_BAR; PG8_MMA(1, 0, At, B0); PG8_MMA(1, 1, At, B1); PG8_BAR; PG8_SCHED;
;             PG8_LDB(B0, 1, 0); PG8_LDB(B1, 1, 1); PG8_SCHED; PG8_LDA(At, 1, 0); PG8_STAGE(PG8_SA(0, 1), a2 + hstep, voffA);
;             PG8_WAIT_V(8); PG8_WAIT_L(0); PG8_BAR; PG8_MMA(0, 0, At, B0); PG8_MMA(0, 1, At, B1); PG8_BAR; PG8_SCHED;
	s_setprio 1
	s_waitcnt lgkmcnt(0)
	v_mfma_f32_16x16x32_bf16 v[140:143], v[0:3], v[60:63], 0
	v_mfma_f32_16x16x32_bf16 v[148:151], v[0:3], v[104:107], 0
	v_mfma_f32_16x16x32_bf16 v[156:159], v[0:3], v[112:115], 0
	v_mfma_f32_16x16x32_bf16 v[0:3], v[0:3], v[120:123], 0
	v_mfma_f32_16x16x32_bf16 v[140:143], v[4:7], v[100:103], v[140:143]
	v_mfma_f32_16x16x32_bf16 v[148:151], v[4:7], v[108:111], v[148:151]
	v_mfma_f32_16x16x32_bf16 v[156:159], v[4:7], v[116:119], v[156:159]
	v_mfma_f32_16x16x32_bf16 v[0:3], v[4:7], v[124:127], v[0:3]
	v_mfma_f32_16x16x32_bf16 v[4:7], v[8:11], v[120:123], 0
	v_mfma_f32_16x16x32_bf16 v[144:147], v[8:11], v[60:63], 0
	v_mfma_f32_16x16x32_bf16 v[152:155], v[8:11], v[104:107], 0
	v_mfma_f32_16x16x32_bf16 v[160:163], v[8:11], v[112:115], 0
	v_mfma_f32_16x16x32_bf16 v[4:7], v[12:15], v[124:127], v[4:7]
	v_mfma_f32_16x16x32_bf16 v[144:147], v[12:15], v[100:103], v[144:147]
	v_mfma_f32_16x16x32_bf16 v[152:155], v[12:15], v[108:111], v[152:155]
	v_mfma_f32_16x16x32_bf16 v[160:163], v[12:15], v[116:119], v[160:163]
	s_setprio 0
	s_setprio 1
	v_mfma_f32_16x16x32_bf16 v[8:11], v[16:19], v[60:63], 0
	v_mfma_f32_16x16x32_bf16 v[12:15], v[24:27], v[60:63], 0
	v_mfma_f32_16x16x32_bf16 v[8:11], v[20:23], v[100:103], v[8:11]
	v_mfma_f32_16x16x32_bf16 v[12:15], v[28:31], v[100:103], v[12:15]
	v_mfma_f32_16x16x32_bf16 v[60:63], v[16:19], v[104:107], 0
	v_mfma_f32_16x16x32_bf16 v[100:103], v[24:27], v[104:107], 0
	v_mfma_f32_16x16x32_bf16 v[104:107], v[16:19], v[112:115], 0
	v_mfma_f32_16x16x32_bf16 v[16:19], v[16:19], v[120:123], 0
	v_mfma_f32_16x16x32_bf16 v[60:63], v[20:23], v[108:111], v[60:63]
	v_mfma_f32_16x16x32_bf16 v[100:103], v[28:31], v[108:111], v[100:103]
	v_mfma_f32_16x16x32_bf16 v[104:107], v[20:23], v[116:119], v[104:107]
	v_mfma_f32_16x16x32_bf16 v[108:111], v[24:27], v[112:115], 0
	v_mfma_f32_16x16x32_bf16 v[16:19], v[20:23], v[124:127], v[16:19]
	v_mfma_f32_16x16x32_bf16 v[20:23], v[24:27], v[120:123], 0
	v_mfma_f32_16x16x32_bf16 v[108:111], v[28:31], v[116:119], v[108:111]
	v_mfma_f32_16x16x32_bf16 v[20:23], v[28:31], v[124:127], v[20:23]
	s_setprio 0
	s_barrier
	ds_read_b128 v[24:27], v137
	ds_read_b128 v[28:31], v137 offset:1024
	ds_read_b128 v[112:115], v137 offset:2048
	ds_read_b128 v[116:119], v137 offset:3072
	ds_read_b128 v[120:123], v138
	ds_read_b128 v[124:127], v138 offset:1024
	ds_read_b128 v[164:167], v138 offset:2048
	ds_read_b128 v[168:171], v138 offset:3072
	s_add_u32 s58, s36, 0x10100
	s_addc_u32 s59, s37, 0
	s_mov_b32 m0, s90
	ds_read_b128 v[172:175], v136 offset:32768
	ds_read_b128 v[176:179], v136 offset:33792
	ds_read_b128 v[180:183], v136 offset:34816
	ds_read_b128 v[184:187], v136 offset:35840
	ds_read_b128 v[188:191], v136 offset:36864
	ds_read_b128 v[192:195], v136 offset:37888
	ds_read_b128 v[196:199], v136 offset:38912
	ds_read_b128 v[200:203], v136 offset:39936
	global_load_lds_dwordx4 v130, s[58:59]
	s_mov_b32 m0, s47
	s_nop 0
	global_load_lds_dwordx4 v128, s[58:59]
	s_waitcnt vmcnt(8)
	s_waitcnt lgkmcnt(0)
	s_barrier
	s_setprio 1
	s_waitcnt lgkmcnt(0)
	v_mfma_f32_16x16x32_bf16 v[64:67], v[24:27], v[172:175], v[64:67]
	v_mfma_f32_16x16x32_bf16 v[68:71], v[112:115], v[172:175], v[68:71]
	v_mfma_f32_16x16x32_bf16 v[72:75], v[24:27], v[180:183], v[72:75]
	v_mfma_f32_16x16x32_bf16 v[76:79], v[112:115], v[180:183], v[76:79]
	v_mfma_f32_16x16x32_bf16 v[80:83], v[24:27], v[188:191], v[80:83]
	v_mfma_f32_16x16x32_bf16 v[84:87], v[112:115], v[188:191], v[84:87]
	v_mfma_f32_16x16x32_bf16 v[88:91], v[24:27], v[196:199], v[88:91]
	v_mfma_f32_16x16x32_bf16 v[92:95], v[112:115], v[196:199], v[92:95]
	v_mfma_f32_16x16x32_bf16 v[64:67], v[28:31], v[176:179], v[64:67]
	v_mfma_f32_16x16x32_bf16 v[68:71], v[116:119], v[176:179], v[68:71]
	v_mfma_f32_16x16x32_bf16 v[72:75], v[28:31], v[184:187], v[72:75]
	v_mfma_f32_16x16x32_bf16 v[76:79], v[116:119], v[184:187], v[76:79]
	v_mfma_f32_16x16x32_bf16 v[80:83], v[28:31], v[192:195], v[80:83]
	v_mfma_f32_16x16x32_bf16 v[84:87], v[116:119], v[192:195], v[84:87]
	v_mfma_f32_16x16x32_bf16 v[88:91], v[28:31], v[200:203], v[88:91]
	v_mfma_f32_16x16x32_bf16 v[92:95], v[116:119], v[200:203], v[92:95]
	s_setprio 0
	s_setprio 1
	v_mfma_f32_16x16x32_bf16 v[96:99], v[120:123], v[172:175], v[96:99]
	v_mfma_f32_16x16x32_bf16 v[32:35], v[164:167], v[172:175], v[32:35]
	v_mfma_f32_16x16x32_bf16 v[36:39], v[120:123], v[180:183], v[36:39]
	v_mfma_f32_16x16x32_bf16 v[40:43], v[164:167], v[180:183], v[40:43]
	v_mfma_f32_16x16x32_bf16 v[44:47], v[120:123], v[188:191], v[44:47]
	v_mfma_f32_16x16x32_bf16 v[48:51], v[164:167], v[188:191], v[48:51]
	v_mfma_f32_16x16x32_bf16 v[52:55], v[120:123], v[196:199], v[52:55]
	v_mfma_f32_16x16x32_bf16 v[56:59], v[164:167], v[196:199], v[56:59]
	v_mfma_f32_16x16x32_bf16 v[96:99], v[124:127], v[176:179], v[96:99]
	v_mfma_f32_16x16x32_bf16 v[32:35], v[168:171], v[176:179], v[32:35]
	v_mfma_f32_16x16x32_bf16 v[36:39], v[124:127], v[184:187], v[36:39]
	v_mfma_f32_16x16x32_bf16 v[40:43], v[168:171], v[184:187], v[40:43]
	v_mfma_f32_16x16x32_bf16 v[44:47], v[124:127], v[192:195], v[44:47]
	v_mfma_f32_16x16x32_bf16 v[48:51], v[168:171], v[192:195], v[48:51]
	v_mfma_f32_16x16x32_bf16 v[52:55], v[124:127], v[200:203], v[52:55]
	v_mfma_f32_16x16x32_bf16 v[56:59], v[168:171], v[200:203], v[56:59]
	s_setprio 0
	s_barrier
; #define PG8_STAGE(bufoff, gbase, voff) do { _Pragma("unroll") for (int _i = 0; _i < 2; ++_i) \
;         __builtin_amdgcn_global_load_lds((const unsigned*)((const char*)(gbase) + (voff)[_i]), (PG8_LAS unsigned*)(lds + (bufoff) + ldsw + _i * 8192), 16, 0, 0); } while (0)
; #define PG8_LDA(dst, b, h) do { _Pragma("unroll") for (int m = 0; m < 4; ++m) _Pragma("unroll") for (int k = 0; k < 2; ++k) dst[m][k] = *(const PG8_LAS bf16x8*)(lds + PG8_SA(b, h) + aoff + m * 2048 + k * 1024); } while (0)
; #define PG8_LDB(dst, b, h) do { _Pragma("unroll") for (int n = 0; n < 2; ++n) _Pragma("unroll") for (int k = 0; k < 2; ++k) dst[n][k] = *(const PG8_LAS bf16x8*)(lds + PG8_SB(b, h) + boff + n * 2048 + k * 1024); } while (0)
; #define PG8_MMA(ai, bj, At, Bt) do { __builtin_amdgcn_s_setprio(1); _Pragma("unroll") for (int m = 0; m < 4; ++m) _Pragma("unroll") for (int n = 0; n < 2; ++n) _Pragma("unroll") for (int k = 0; k < 2; ++k) \
;         acc[ai][bj][m][n] = mma16<F16>(Bt[n][k], At[m][k], acc[ai][bj][m][n]); __builtin_amdgcn_s_setprio(0); } while (0)
; #define PG8_WAIT_V(n) asm volatile("s_waitcnt vmcnt(" #n ")" ::: "memory")
; template <class Epi, class Sched, bool ALIGN_EPI = false, bool SP2 = false, bool F16 = false>
; __device__ __forceinline__ void gemm_phase(PG8_LAS unsigned char* lds, const Gemm g, const Sched& S, const Epi& E, const int wid_in) {
;     ...
;             PG8_LDB(B0, 0, 0); PG8_LDB(B1, 0, 1); PG8_SCHED; PG8_LDA(At, 0, 0); PG8_STAGE(PG8_SA(1, 1), a1 + hstep, voffA);
;             PG8_WAIT_V(8); PG8_WAIT_L(0); PG8_BAR; PG8_MMA(0, 0, At, B0); PG8_MMA(0, 1, At, B1); PG8_BAR; PG8_SCHED;
;             PG8_LDA(At, 0, 1); PG8_STAGE(PG8_SB(0, 0), b2, voffB); PG8_STAGE(PG8_SB(0, 1), b2 + hstep, voffB); PG8_STAGE(PG8_SA(0, 0), a2, voffA);
;             PG8_WAIT_V(8); PG8_WAIT_L(0); PG8_BAR; PG8_MMA(1, 0, At, B0); PG8_MMA(1, 1, At, B1); PG8_BAR; PG8_SCHED;
;             PG8_LDB(B0, 1, 0); PG8_LDB(B1, 1, 1); PG8_SCHED; PG8_LDA(At, 1, 0); PG8_STAGE(PG8_SA(0, 1), a2 + hstep, voffA);
;             PG8_WAIT_V(8); PG8_WAIT_L(0); PG8_BAR; PG8_MMA(0, 0, At, B0); PG8_MMA(0, 1, At, B1); PG8_BAR; PG8_SCHED;
;             PG8_LDA(At, 1, 1); PG8_STAGE(PG8_SB(1, 0), b3, voffB); PG8_STAGE(PG8_SB(1, 1), b3 + hstep, voffB); PG8_STAGE(PG8_SA(1, 0), a3, voffA);
;             PG8_WAIT_V(8); PG8_WAIT_L(0); PG8_BAR; PG8_MMA(1, 0, At, B0); PG8_MMA(1, 1, At, B1); PG8_BAR; PG8_SCHED;
	s_mov_b32 m0, s51
	v_lshl_add_u64 v[204:205], v[204:205], 0, s[24:25]
	s_add_u32 s42, s42, 0x10180
	ds_read_b128 v[172:175], v136 offset:49152
	ds_read_b128 v[176:179], v136 offset:50176
	ds_read_b128 v[180:183], v136 offset:51200
	ds_read_b128 v[184:187], v136 offset:52224
	ds_read_b128 v[188:191], v136 offset:53248
	ds_read_b128 v[192:195], v136 offset:54272
	ds_read_b128 v[196:199], v136 offset:55296
	ds_read_b128 v[200:203], v136 offset:56320
	global_load_lds_dwordx4 v[204:205], off
	v_lshl_add_u64 v[204:205], v[206:207], 0, s[24:25]
	s_mov_b32 m0, s52
	s_addc_u32 s43, s43, 0
	global_load_lds_dwordx4 v[204:205], off
	s_mov_b32 m0, s53
	s_nop 0
	global_load_lds_dwordx4 v130, s[42:43]
	s_mov_b32 m0, s54
	s_nop 0
	global_load_lds_dwordx4 v128, s[42:43]
	v_lshl_add_u64 v[204:205], v[208:209], 0, s[24:25]
	s_mov_b32 m0, s75
	s_nop 0
	global_load_lds_dwordx4 v[204:205], off
	v_lshl_add_u64 v[204:205], v[210:211], 0, s[24:25]
	s_mov_b32 m0, s67
	s_nop 0
	global_load_lds_dwordx4 v[204:205], off
	s_waitcnt vmcnt(8)
	s_waitcnt lgkmcnt(0)
	s_barrier
	s_setprio 1
	s_waitcnt lgkmcnt(0)
	v_mfma_f32_16x16x32_bf16 v[0:3], v[24:27], v[196:199], v[0:3]
	v_mfma_f32_16x16x32_bf16 v[4:7], v[112:115], v[196:199], v[4:7]
	v_mfma_f32_16x16x32_bf16 v[140:143], v[24:27], v[172:175], v[140:143]
	v_mfma_f32_16x16x32_bf16 v[144:147], v[112:115], v[172:175], v[144:147]
	v_mfma_f32_16x16x32_bf16 v[148:151], v[24:27], v[180:183], v[148:151]
	v_mfma_f32_16x16x32_bf16 v[152:155], v[112:115], v[180:183], v[152:155]
	v_mfma_f32_16x16x32_bf16 v[156:159], v[24:27], v[188:191], v[156:159]
	v_mfma_f32_16x16x32_bf16 v[160:163], v[112:115], v[188:191], v[160:163]
	v_mfma_f32_16x16x32_bf16 v[0:3], v[28:31], v[200:203], v[0:3]
	v_mfma_f32_16x16x32_bf16 v[4:7], v[116:119], v[200:203], v[4:7]
	v_mfma_f32_16x16x32_bf16 v[140:143], v[28:31], v[176:179], v[140:143]
	v_mfma_f32_16x16x32_bf16 v[144:147], v[116:119], v[176:179], v[144:147]
	v_mfma_f32_16x16x32_bf16 v[148:151], v[28:31], v[184:187], v[148:151]
	v_mfma_f32_16x16x32_bf16 v[152:155], v[116:119], v[184:187], v[152:155]
	v_mfma_f32_16x16x32_bf16 v[156:159], v[28:31], v[192:195], v[156:159]
	v_mfma_f32_16x16x32_bf16 v[160:163], v[116:119], v[192:195], v[160:163]
	s_setprio 0
	s_setprio 1
	v_mfma_f32_16x16x32_bf16 v[8:11], v[120:123], v[172:175], v[8:11]
	v_mfma_f32_16x16x32_bf16 v[12:15], v[164:167], v[172:175], v[12:15]
	v_mfma_f32_16x16x32_bf16 v[24:27], v[120:123], v[180:183], v[60:63]
	v_mfma_f32_16x16x32_bf16 v[28:31], v[164:167], v[180:183], v[100:103]
	v_mfma_f32_16x16x32_bf16 v[60:63], v[120:123], v[188:191], v[104:107]
	v_mfma_f32_16x16x32_bf16 v[100:103], v[164:167], v[188:191], v[108:111]
	v_mfma_f32_16x16x32_bf16 v[16:19], v[120:123], v[196:199], v[16:19]
	v_mfma_f32_16x16x32_bf16 v[20:23], v[164:167], v[196:199], v[20:23]
	v_mfma_f32_16x16x32_bf16 v[8:11], v[124:127], v[176:179], v[8:11]
	v_mfma_f32_16x16x32_bf16 v[12:15], v[168:171], v[176:179], v[12:15]
	v_mfma_f32_16x16x32_bf16 v[24:27], v[124:127], v[184:187], v[24:27]
	v_mfma_f32_16x16x32_bf16 v[28:31], v[168:171], v[184:187], v[28:31]
	v_mfma_f32_16x16x32_bf16 v[60:63], v[124:127], v[192:195], v[60:63]
	v_mfma_f32_16x16x32_bf16 v[100:103], v[168:171], v[192:195], v[100:103]
	v_mfma_f32_16x16x32_bf16 v[16:19], v[124:127], v[200:203], v[16:19]
	v_mfma_f32_16x16x32_bf16 v[20:23], v[168:171], v[200:203], v[20:23]
	s_setprio 0
	s_barrier
	ds_read_b128 v[104:107], v134
	ds_read_b128 v[108:111], v134 offset:1024
	ds_read_b128 v[112:115], v134 offset:2048
	ds_read_b128 v[116:119], v134 offset:3072
	ds_read_b128 v[120:123], v135
	ds_read_b128 v[124:127], v135 offset:1024
	ds_read_b128 v[164:167], v135 offset:2048
	ds_read_b128 v[168:171], v135 offset:3072
	s_add_u32 s36, s36, 0x10180
	s_addc_u32 s37, s37, 0
	s_mov_b32 m0, s91
	ds_read_b128 v[172:175], v136
	ds_read_b128 v[176:179], v136 offset:1024
	ds_read_b128 v[180:183], v136 offset:2048
	ds_read_b128 v[184:187], v136 offset:3072
	ds_read_b128 v[188:191], v136 offset:4096
	ds_read_b128 v[192:195], v136 offset:5120
	ds_read_b128 v[196:199], v136 offset:6144
	ds_read_b128 v[200:203], v136 offset:7168
	global_load_lds_dwordx4 v130, s[36:37]
	s_mov_b32 m0, s14
	s_nop 0
	global_load_lds_dwordx4 v128, s[36:37]
	s_waitcnt vmcnt(8)
	s_waitcnt lgkmcnt(0)
	s_barrier
	s_setprio 1
	s_waitcnt lgkmcnt(0)
	v_mfma_f32_16x16x32_bf16 v[64:67], v[104:107], v[172:175], v[64:67]
	v_mfma_f32_16x16x32_bf16 v[68:71], v[112:115], v[172:175], v[68:71]
	v_mfma_f32_16x16x32_bf16 v[72:75], v[104:107], v[180:183], v[72:75]
	v_mfma_f32_16x16x32_bf16 v[76:79], v[112:115], v[180:183], v[76:79]
	v_mfma_f32_16x16x32_bf16 v[80:83], v[104:107], v[188:191], v[80:83]
	v_mfma_f32_16x16x32_bf16 v[84:87], v[112:115], v[188:191], v[84:87]
	v_mfma_f32_16x16x32_bf16 v[88:91], v[104:107], v[196:199], v[88:91]
	v_mfma_f32_16x16x32_bf16 v[92:95], v[112:115], v[196:199], v[92:95]
	v_mfma_f32_16x16x32_bf16 v[64:67], v[108:111], v[176:179], v[64:67]
	v_mfma_f32_16x16x32_bf16 v[68:71], v[116:119], v[176:179], v[68:71]
	v_mfma_f32_16x16x32_bf16 v[72:75], v[108:111], v[184:187], v[72:75]
	v_mfma_f32_16x16x32_bf16 v[76:79], v[116:119], v[184:187], v[76:79]
	v_mfma_f32_16x16x32_bf16 v[80:83], v[108:111], v[192:195], v[80:83]
	v_mfma_f32_16x16x32_bf16 v[84:87], v[116:119], v[192:195], v[84:87]
	v_mfma_f32_16x16x32_bf16 v[88:91], v[108:111], v[200:203], v[88:91]
	v_mfma_f32_16x16x32_bf16 v[92:95], v[116:119], v[200:203], v[92:95]
	s_setprio 0
	s_setprio 1
	v_mfma_f32_16x16x32_bf16 v[32:35], v[164:167], v[172:175], v[32:35]
	v_mfma_f32_16x16x32_bf16 v[96:99], v[120:123], v[172:175], v[96:99]
	v_mfma_f32_16x16x32_bf16 v[172:175], v[168:171], v[176:179], v[32:35]
	v_mfma_f32_16x16x32_bf16 v[32:35], v[120:123], v[180:183], v[36:39]
	v_mfma_f32_16x16x32_bf16 v[204:207], v[124:127], v[176:179], v[96:99]
	v_mfma_f32_16x16x32_bf16 v[176:179], v[124:127], v[184:187], v[32:35]
	v_mfma_f32_16x16x32_bf16 v[32:35], v[164:167], v[180:183], v[40:43]
	v_mfma_f32_16x16x32_bf16 v[40:43], v[168:171], v[184:187], v[32:35]
	v_mfma_f32_16x16x32_bf16 v[32:35], v[120:123], v[188:191], v[44:47]
	v_mfma_f32_16x16x32_bf16 v[44:47], v[124:127], v[192:195], v[32:35]
	v_mfma_f32_16x16x32_bf16 v[32:35], v[164:167], v[188:191], v[48:51]
	v_mfma_f32_16x16x32_bf16 v[48:51], v[168:171], v[192:195], v[32:35]
	v_mfma_f32_16x16x32_bf16 v[32:35], v[120:123], v[196:199], v[52:55]
	v_mfma_f32_16x16x32_bf16 v[52:55], v[124:127], v[200:203], v[32:35]
	v_mfma_f32_16x16x32_bf16 v[32:35], v[164:167], v[196:199], v[56:59]
	v_mfma_f32_16x16x32_bf16 v[56:59], v[168:171], v[200:203], v[32:35]
	s_setprio 0
	s_barrier
; #define PG8_STAGE(bufoff, gbase, voff) do { _Pragma("unroll") for (int _i = 0; _i < 2; ++_i) \
;         __builtin_amdgcn_global_load_lds((const unsigned*)((const char*)(gbase) + (voff)[_i]), (PG8_LAS unsigned*)(lds + (bufoff) + ldsw + _i * 8192), 16, 0, 0); } while (0)
; #define PG8_LDA(dst, b, h) do { _Pragma("unroll") for (int m = 0; m < 4; ++m) _Pragma("unroll") for (int k = 0; k < 2; ++k) dst[m][k] = *(const PG8_LAS bf16x8*)(lds + PG8_SA(b, h) + aoff + m * 2048 + k * 1024); } while (0)
; #define PG8_LDB(dst, b, h) do { _Pragma("unroll") for (int n = 0; n < 2; ++n) _Pragma("unroll") for (int k = 0; k < 2; ++k) dst[n][k] = *(const PG8_LAS bf16x8*)(lds + PG8_SB(b, h) + boff + n * 2048 + k * 1024); } while (0)
; #define PG8_MMA(ai, bj, At, Bt) do { __builtin_amdgcn_s_setprio(1); _Pragma("unroll") for (int m = 0; m < 4; ++m) _Pragma("unroll") for (int n = 0; n < 2; ++n) _Pragma("unroll") for (int k = 0; k < 2; ++k) \
;         acc[ai][bj][m][n] = mma16<F16>(Bt[n][k], At[m][k], acc[ai][bj][m][n]); __builtin_amdgcn_s_setprio(0); } while (0)
; #define PG8_WAIT_V(n) asm volatile("s_waitcnt vmcnt(" #n ")" ::: "memory")
; #define PG8_WAIT_L(n) asm volatile("s_waitcnt lgkmcnt(" #n ")" ::: "memory")
; #define PG8_BAR __builtin_amdgcn_s_barrier()
; #define PG8_SCHED __builtin_amdgcn_sched_barrier(0)
; template <class Epi, class Sched, bool ALIGN_EPI = false, bool SP2 = false, bool F16 = false>
; __device__ __forceinline__ void gemm_phase(PG8_LAS unsigned char* lds, const Gemm g, const Sched& S, const Epi& E, const int wid_in) {
;     ...
;             PG8_LDA(At, 0, 1); PG8_STAGE(PG8_SB(0, 0), b2, voffB); PG8_STAGE(PG8_SB(0, 1), b2 + hstep, voffB); PG8_STAGE(PG8_SA(0, 0), a2, voffA);
;             PG8_WAIT_V(8); PG8_WAIT_L(0); PG8_BAR; PG8_MMA(1, 0, At, B0); PG8_MMA(1, 1, At, B1); PG8_BAR; PG8_SCHED;
;             PG8_LDB(B0, 1, 0); PG8_LDB(B1, 1, 1); PG8_SCHED; PG8_LDA(At, 1, 0); PG8_STAGE(PG8_SA(0, 1), a2 + hstep, voffA);
	s_mov_b32 m0, s15
	v_lshl_add_u64 v[240:241], s[30:31], 0, v[130:131]
	s_add_u32 s36, s30, 0x10000
	s_nop 1
	ds_read_b128 v[32:35], v136 offset:16384
	ds_read_b128 v[36:39], v136 offset:17408
	ds_read_b128 v[96:99], v136 offset:18432
	ds_read_b128 v[180:183], v136 offset:19456
	ds_read_b128 v[184:187], v136 offset:20480
	ds_read_b128 v[188:191], v136 offset:21504
	ds_read_b128 v[192:195], v136 offset:22528
	ds_read_b128 v[196:199], v136 offset:23552
	global_load_lds_dwordx4 v[240:241], off
	v_lshl_add_u64 v[242:243], s[30:31], 0, v[128:129]
	s_mov_b32 m0, s48
	s_addc_u32 s37, s31, 0
	global_load_lds_dwordx4 v[242:243], off
	s_mov_b32 m0, s49
	v_lshl_add_u64 v[244:245], s[34:35], 0, v[130:131]
	global_load_lds_dwordx4 v130, s[36:37]
	s_mov_b32 m0, s50
	v_lshl_add_u64 v[246:247], s[34:35], 0, v[128:129]
	global_load_lds_dwordx4 v128, s[36:37]
	s_mov_b32 m0, s74
	s_nop 0
	global_load_lds_dwordx4 v[244:245], off
	s_mov_b32 m0, s66
	s_nop 0
	global_load_lds_dwordx4 v[246:247], off
	s_waitcnt vmcnt(8)
	s_waitcnt lgkmcnt(0)
	s_barrier
	s_setprio 1
	s_waitcnt lgkmcnt(0)
	v_mfma_f32_16x16x32_bf16 v[0:3], v[104:107], v[192:195], v[0:3]
	v_mfma_f32_16x16x32_bf16 v[140:143], v[104:107], v[32:35], v[140:143]
	v_mfma_f32_16x16x32_bf16 v[144:147], v[112:115], v[32:35], v[144:147]
	v_mfma_f32_16x16x32_bf16 v[148:151], v[104:107], v[96:99], v[148:151]
	v_mfma_f32_16x16x32_bf16 v[152:155], v[112:115], v[96:99], v[152:155]
	v_mfma_f32_16x16x32_bf16 v[156:159], v[104:107], v[184:187], v[156:159]
	v_mfma_f32_16x16x32_bf16 v[160:163], v[112:115], v[184:187], v[160:163]
	v_mfma_f32_16x16x32_bf16 v[0:3], v[108:111], v[196:199], v[0:3]
	v_mfma_f32_16x16x32_bf16 v[4:7], v[112:115], v[192:195], v[4:7]
	v_mfma_f32_16x16x32_bf16 v[140:143], v[108:111], v[36:39], v[140:143]
	v_mfma_f32_16x16x32_bf16 v[144:147], v[116:119], v[36:39], v[144:147]
	v_mfma_f32_16x16x32_bf16 v[148:151], v[108:111], v[180:183], v[148:151]
	v_mfma_f32_16x16x32_bf16 v[152:155], v[116:119], v[180:183], v[152:155]
	v_mfma_f32_16x16x32_bf16 v[156:159], v[108:111], v[188:191], v[156:159]
	v_mfma_f32_16x16x32_bf16 v[160:163], v[116:119], v[188:191], v[160:163]
	v_mfma_f32_16x16x32_bf16 v[200:203], v[116:119], v[196:199], v[4:7]
	s_setprio 0
	s_setprio 1
	v_mfma_f32_16x16x32_bf16 v[4:7], v[120:123], v[32:35], v[8:11]
	v_mfma_f32_16x16x32_bf16 v[8:11], v[124:127], v[36:39], v[4:7]
	v_mfma_f32_16x16x32_bf16 v[4:7], v[164:167], v[32:35], v[12:15]
	v_mfma_f32_16x16x32_bf16 v[12:15], v[168:171], v[36:39], v[4:7]
	v_mfma_f32_16x16x32_bf16 v[4:7], v[120:123], v[96:99], v[24:27]
	v_mfma_f32_16x16x32_bf16 v[24:27], v[124:127], v[180:183], v[4:7]
	v_mfma_f32_16x16x32_bf16 v[4:7], v[164:167], v[96:99], v[28:31]
	v_mfma_f32_16x16x32_bf16 v[28:31], v[168:171], v[180:183], v[4:7]
	v_mfma_f32_16x16x32_bf16 v[4:7], v[120:123], v[184:187], v[60:63]
	v_mfma_f32_16x16x32_bf16 v[180:183], v[124:127], v[188:191], v[4:7]
	v_mfma_f32_16x16x32_bf16 v[4:7], v[164:167], v[184:187], v[100:103]
	v_mfma_f32_16x16x32_bf16 v[184:187], v[168:171], v[188:191], v[4:7]
	v_mfma_f32_16x16x32_bf16 v[4:7], v[120:123], v[192:195], v[16:19]
	v_mfma_f32_16x16x32_bf16 v[188:191], v[124:127], v[196:199], v[4:7]
	v_mfma_f32_16x16x32_bf16 v[4:7], v[164:167], v[192:195], v[20:23]
	v_mfma_f32_16x16x32_bf16 v[164:167], v[168:171], v[196:199], v[4:7]
	s_setprio 0
	s_barrier
	s_nop 4
	ds_read_b128 v[4:7], v137
	ds_read_b128 v[60:63], v137 offset:1024
	ds_read_b128 v[168:171], v137 offset:2048
	ds_read_b128 v[192:195], v137 offset:3072
	ds_read_b128 v[196:199], v138
	ds_read_b128 v[208:211], v138 offset:1024
	ds_read_b128 v[212:215], v138 offset:2048
	ds_read_b128 v[216:219], v138 offset:3072
	s_add_u32 s34, s34, 0x10000
	s_addc_u32 s35, s35, 0
	s_mov_b32 m0, s90
	ds_read_b128 v[16:19], v136 offset:32768
	ds_read_b128 v[20:23], v136 offset:33792
	ds_read_b128 v[104:107], v136 offset:34816
	ds_read_b128 v[220:223], v136 offset:35840
	ds_read_b128 v[224:227], v136 offset:36864
	ds_read_b128 v[228:231], v136 offset:37888
	ds_read_b128 v[232:235], v136 offset:38912
	ds_read_b128 v[236:239], v136 offset:39936
	global_load_lds_dwordx4 v130, s[34:35]
	s_mov_b32 m0, s47
	s_nop 0
	global_load_lds_dwordx4 v128, s[34:35]
	s_waitcnt vmcnt(8)
	s_waitcnt lgkmcnt(0)
	s_barrier
; #define PG8_STAGE(bufoff, gbase, voff) do { _Pragma("unroll") for (int _i = 0; _i < 2; ++_i) \
;         __builtin_amdgcn_global_load_lds((const unsigned*)((const char*)(gbase) + (voff)[_i]), (PG8_LAS unsigned*)(lds + (bufoff) + ldsw + _i * 8192), 16, 0, 0); } while (0)
; #define PG8_LDA(dst, b, h) do { _Pragma("unroll") for (int m = 0; m < 4; ++m) _Pragma("unroll") for (int k = 0; k < 2; ++k) dst[m][k] = *(const PG8_LAS bf16x8*)(lds + PG8_SA(b, h) + aoff + m * 2048 + k * 1024); } while (0)
; #define PG8_MMA(ai, bj, At, Bt) do { __builtin_amdgcn_s_setprio(1); _Pragma("unroll") for (int m = 0; m < 4; ++m) _Pragma("unroll") for (int n = 0; n < 2; ++n) _Pragma("unroll") for (int k = 0; k < 2; ++k) \
;         acc[ai][bj][m][n] = mma16<F16>(Bt[n][k], At[m][k], acc[ai][bj][m][n]); __builtin_amdgcn_s_setprio(0); } while (0)
; #define PG8_WAIT_V(n) asm volatile("s_waitcnt vmcnt(" #n ")" ::: "memory")
; #define PG8_WAIT_L(n) asm volatile("s_waitcnt lgkmcnt(" #n ")" ::: "memory")
; #define PG8_BAR __builtin_amdgcn_s_barrier()
; #define PG8_SCHED __builtin_amdgcn_sched_barrier(0)
; template <class Epi, class Sched, bool ALIGN_EPI = false, bool SP2 = false, bool F16 = false>
; __device__ __forceinline__ void gemm_phase(PG8_LAS unsigned char* lds, const Gemm g, const Sched& S, const Epi& E, const int wid_in) {
;     ...
;             PG8_WAIT_V(8); PG8_WAIT_L(0); PG8_BAR; PG8_MMA(0, 0, At, B0); PG8_MMA(0, 1, At, B1); PG8_BAR; PG8_SCHED;
;             PG8_LDA(At, 1, 1); PG8_STAGE(PG8_SB(1, 0), b3, voffB); PG8_STAGE(PG8_SB(1, 1), b3 + hstep, voffB); PG8_STAGE(PG8_SA(1, 0), a3, voffA);
;             PG8_WAIT_V(8); PG8_WAIT_L(0); PG8_BAR; PG8_MMA(1, 0, At, B0); PG8_MMA(1, 1, At, B1); PG8_BAR; PG8_SCHED;
	s_setprio 1
	s_waitcnt lgkmcnt(0)
	v_mfma_f32_16x16x32_bf16 v[32:35], v[4:7], v[16:19], v[64:67]
	v_mfma_f32_16x16x32_bf16 v[116:119], v[60:63], v[20:23], v[32:35]
	v_mfma_f32_16x16x32_bf16 v[32:35], v[168:171], v[16:19], v[68:71]
	v_mfma_f32_16x16x32_bf16 v[112:115], v[192:195], v[20:23], v[32:35]
	v_mfma_f32_16x16x32_bf16 v[32:35], v[4:7], v[104:107], v[72:75]
	v_mfma_f32_16x16x32_bf16 v[100:103], v[60:63], v[220:223], v[32:35]
	v_mfma_f32_16x16x32_bf16 v[32:35], v[168:171], v[104:107], v[76:79]
	v_mfma_f32_16x16x32_bf16 v[96:99], v[192:195], v[220:223], v[32:35]
	v_mfma_f32_16x16x32_bf16 v[32:35], v[4:7], v[224:227], v[80:83]
	v_mfma_f32_16x16x32_bf16 v[68:71], v[60:63], v[228:231], v[32:35]
	v_mfma_f32_16x16x32_bf16 v[32:35], v[168:171], v[224:227], v[84:87]
	v_mfma_f32_16x16x32_bf16 v[64:67], v[192:195], v[228:231], v[32:35]
	v_mfma_f32_16x16x32_bf16 v[32:35], v[4:7], v[232:235], v[88:91]
	v_mfma_f32_16x16x32_bf16 v[36:39], v[60:63], v[236:239], v[32:35]
	v_mfma_f32_16x16x32_bf16 v[32:35], v[168:171], v[232:235], v[92:95]
	v_mfma_f32_16x16x32_bf16 v[32:35], v[192:195], v[236:239], v[32:35]
	s_setprio 0
	s_setprio 1
	v_mfma_f32_16x16x32_bf16 v[72:75], v[196:199], v[16:19], v[204:207]
	v_mfma_f32_16x16x32_bf16 v[16:19], v[212:215], v[16:19], v[172:175]
	v_mfma_f32_16x16x32_bf16 v[120:123], v[216:219], v[20:23], v[16:19]
	v_mfma_f32_16x16x32_bf16 v[16:19], v[196:199], v[104:107], v[176:179]
	v_mfma_f32_16x16x32_bf16 v[108:111], v[208:211], v[220:223], v[16:19]
	v_mfma_f32_16x16x32_bf16 v[16:19], v[212:215], v[104:107], v[40:43]
	v_mfma_f32_16x16x32_bf16 v[104:107], v[216:219], v[220:223], v[16:19]
	v_mfma_f32_16x16x32_bf16 v[16:19], v[196:199], v[224:227], v[44:47]
	v_mfma_f32_16x16x32_bf16 v[80:83], v[208:211], v[228:231], v[16:19]
	v_mfma_f32_16x16x32_bf16 v[16:19], v[212:215], v[224:227], v[48:51]
	v_mfma_f32_16x16x32_bf16 v[124:127], v[208:211], v[20:23], v[72:75]
	v_mfma_f32_16x16x32_bf16 v[72:75], v[216:219], v[228:231], v[16:19]
	v_mfma_f32_16x16x32_bf16 v[16:19], v[196:199], v[232:235], v[52:55]
	v_mfma_f32_16x16x32_bf16 v[48:51], v[208:211], v[236:239], v[16:19]
	v_mfma_f32_16x16x32_bf16 v[16:19], v[212:215], v[232:235], v[56:59]
	v_mfma_f32_16x16x32_bf16 v[40:43], v[216:219], v[236:239], v[16:19]
	s_setprio 0
	s_barrier
	s_mov_b32 m0, s51
	s_nop 3
	v_lshl_add_u64 v[16:17], v[240:241], 0, s[20:21]
	s_add_u32 s30, s30, 0x10080
	ds_read_b128 v[56:59], v136 offset:49152
	ds_read_b128 v[88:91], v136 offset:50176
	ds_read_b128 v[172:175], v136 offset:51200
	ds_read_b128 v[176:179], v136 offset:52224
	ds_read_b128 v[204:207], v136 offset:53248
	ds_read_b128 v[220:223], v136 offset:54272
	ds_read_b128 v[224:227], v136 offset:55296
	ds_read_b128 v[228:231], v136 offset:56320
	global_load_lds_dwordx4 v[16:17], off
	v_lshl_add_u64 v[16:17], v[242:243], 0, s[20:21]
	s_mov_b32 m0, s52
	s_addc_u32 s31, s31, 0
	global_load_lds_dwordx4 v[16:17], off
	s_mov_b32 m0, s53
	s_nop 0
	global_load_lds_dwordx4 v130, s[30:31]
	s_mov_b32 m0, s54
	s_nop 0
	global_load_lds_dwordx4 v128, s[30:31]
	v_lshl_add_u64 v[16:17], v[244:245], 0, s[20:21]
	s_mov_b32 m0, s75
	s_nop 0
	global_load_lds_dwordx4 v[16:17], off
	v_lshl_add_u64 v[16:17], v[246:247], 0, s[20:21]
	s_mov_b32 m0, s67
	s_nop 0
	global_load_lds_dwordx4 v[16:17], off
	s_waitcnt vmcnt(8)
	s_waitcnt lgkmcnt(0)
	s_barrier
	s_setprio 1
	s_waitcnt lgkmcnt(0)
	v_mfma_f32_16x16x32_bf16 v[16:19], v[4:7], v[56:59], v[140:143]
	v_mfma_f32_16x16x32_bf16 v[84:87], v[60:63], v[88:91], v[16:19]
	v_mfma_f32_16x16x32_bf16 v[16:19], v[168:171], v[56:59], v[144:147]
	v_mfma_f32_16x16x32_bf16 v[76:79], v[192:195], v[88:91], v[16:19]
	v_mfma_f32_16x16x32_bf16 v[16:19], v[4:7], v[172:175], v[148:151]
	v_mfma_f32_16x16x32_bf16 v[52:55], v[60:63], v[176:179], v[16:19]
	v_mfma_f32_16x16x32_bf16 v[16:19], v[168:171], v[172:175], v[152:155]
	v_mfma_f32_16x16x32_bf16 v[44:47], v[192:195], v[176:179], v[16:19]
	v_mfma_f32_16x16x32_bf16 v[16:19], v[4:7], v[204:207], v[156:159]
	v_mfma_f32_16x16x32_bf16 v[0:3], v[4:7], v[224:227], v[0:3]
	v_mfma_f32_16x16x32_bf16 v[20:23], v[60:63], v[220:223], v[16:19]
	v_mfma_f32_16x16x32_bf16 v[16:19], v[168:171], v[204:207], v[160:163]
	v_mfma_f32_16x16x32_bf16 v[4:7], v[60:63], v[228:231], v[0:3]
	v_mfma_f32_16x16x32_bf16 v[0:3], v[168:171], v[224:227], v[200:203]
	v_mfma_f32_16x16x32_bf16 v[16:19], v[192:195], v[220:223], v[16:19]
	v_mfma_f32_16x16x32_bf16 v[0:3], v[192:195], v[228:231], v[0:3]
	s_setprio 0
	s_setprio 1
	v_mfma_f32_16x16x32_bf16 v[8:11], v[196:199], v[56:59], v[8:11]
	v_mfma_f32_16x16x32_bf16 v[92:95], v[208:211], v[88:91], v[8:11]
	v_mfma_f32_16x16x32_bf16 v[8:11], v[212:215], v[56:59], v[12:15]
	v_mfma_f32_16x16x32_bf16 v[88:91], v[216:219], v[88:91], v[8:11]
	v_mfma_f32_16x16x32_bf16 v[8:11], v[196:199], v[172:175], v[24:27]
	v_mfma_f32_16x16x32_bf16 v[60:63], v[208:211], v[176:179], v[8:11]
	v_mfma_f32_16x16x32_bf16 v[8:11], v[212:215], v[172:175], v[28:31]
	v_mfma_f32_16x16x32_bf16 v[56:59], v[216:219], v[176:179], v[8:11]
	v_mfma_f32_16x16x32_bf16 v[8:11], v[196:199], v[204:207], v[180:183]
	v_mfma_f32_16x16x32_bf16 v[28:31], v[208:211], v[220:223], v[8:11]
	v_mfma_f32_16x16x32_bf16 v[8:11], v[212:215], v[204:207], v[184:187]
	v_mfma_f32_16x16x32_bf16 v[24:27], v[216:219], v[220:223], v[8:11]
	v_mfma_f32_16x16x32_bf16 v[8:11], v[196:199], v[224:227], v[188:191]
	v_mfma_f32_16x16x32_bf16 v[12:15], v[208:211], v[228:231], v[8:11]
	v_mfma_f32_16x16x32_bf16 v[8:11], v[212:215], v[224:227], v[164:167]
	v_mfma_f32_16x16x32_bf16 v[8:11], v[216:219], v[228:231], v[8:11]
	s_setprio 0
	s_barrier
	s_and_b64 vcc, exec, s[8:9]
	s_cbranch_vccnz .LBB0_2603
	s_barrier

; #define PG8_STAGE(bufoff, gbase, voff) do { _Pragma("unroll") for (int _i = 0; _i < 2; ++_i) \
;         __builtin_amdgcn_global_load_lds((const unsigned*)((const char*)(gbase) + (voff)[_i]), (PG8_LAS unsigned*)(lds + (bufoff) + ldsw + _i * 8192), 16, 0, 0); } while (0)
; #define PG8_WAIT_V(n) asm volatile("s_waitcnt vmcnt(" #n ")" ::: "memory")
; #define PG8_BAR __builtin_amdgcn_s_barrier()
; template <class Epi, class Sched, bool ALIGN_EPI = false, bool SP2 = false, bool F16 = false>
; __device__ __forceinline__ void gemm_phase(PG8_LAS unsigned char* lds, const Gemm g, const Sched& S, const Epi& E, const int wid_in) {
;     ...
;     for (int i = 0; i < 2; ++i) { int R, C; stage_rc(tid * 16 + i * 8192, R, C); const int Rb = Epi::PERM ? ((R & ~31) + perm32(R & 31)) : R;
;         voffA[i] = (unsigned)(R * K + C) * 2u; voffB[i] = (unsigned)(Rb * K + C) * 2u; }
;     const size_t kstep = (size_t)(BK * 2);
;     const size_t hstep = (size_t)HALF * K * 2;
;     const size_t tstep = 2 * hstep;
;     const unsigned ldsw = (unsigned)wid * 1024u;
;     const int aoff = lds_byte(wr * 64 + fr, fq * 8), boff = lds_byte(wc * 32 + fr, fq * 8);
;     ...
;         PG8_STAGE(PG8_SB(1, 0), cB + kstep, voffB); PG8_STAGE(PG8_SA(1, 0), cA + kstep, voffA); PG8_STAGE(PG8_SB(1, 1), cB + hstep + kstep, voffB);
;         PG8_WAIT_V(6); PG8_BAR;
;     } else {
;         PG8_STAGE(PG8_SB(0, 0), cB, voffB); PG8_STAGE(PG8_SA(0, 0), cA, voffA); PG8_STAGE(PG8_SB(0, 1), cB + hstep, voffB); PG8_STAGE(PG8_SA(0, 1), cA + hstep, voffA);
;         if (wr == 1) PG8_BAR;
;         PG8_WAIT_V(4); PG8_BAR;
;         PG8_STAGE(PG8_SB(1, 0), cB + kstep, voffB); PG8_STAGE(PG8_SA(1, 0), cA + kstep, voffA); PG8_STAGE(PG8_SB(1, 1), cB + hstep + kstep, voffB);
;         PG8_WAIT_V(6); PG8_BAR;
;     }
.LBB0_2683:
	s_add_u32 s18, s9, 0x7400000
	s_addc_u32 s19, s10, 0
	s_add_u32 s20, s9, 0x13400000
	s_addc_u32 s21, s10, 0
	s_add_u32 s22, s9, 0x15700000
	s_mov_b64 s[24:25], 0x80
	s_addc_u32 s23, s10, 0
	s_add_i32 m0, s74, 0x18000
	v_lshl_add_u64 v[6:7], v[6:7], 0, s[24:25]
	s_waitcnt vmcnt(2)
	s_barrier
	global_load_lds_dwordx4 v[6:7], off
	v_lshl_add_u64 v[4:5], v[4:5], 0, s[24:25]
	s_add_i32 m0, s74, 0x1a000
	v_lshl_add_u64 v[0:1], v[0:1], 0, s[24:25]
	global_load_lds_dwordx4 v[4:5], off
	s_mov_b32 m0, s75
	s_add_u32 s10, s30, 0xb0080
	global_load_lds_dwordx4 v[0:1], off
	v_lshl_add_u64 v[0:1], v[2:3], 0, s[24:25]
	s_mov_b32 m0, s67
	s_addc_u32 s11, s31, 0
	global_load_lds_dwordx4 v[0:1], off
	s_add_i32 m0, s74, 0x1c000
	s_nop 0
	global_load_lds_dwordx4 v154, s[10:11]
	s_add_i32 m0, s74, 0x1e000
	v_and_b32_e32 v187, 15, v8
	global_load_lds_dwordx4 v158, s[10:11]
	v_or_b32_e32 v0, s70, v187
	v_lshlrev_b32_e32 v1, 6, v0
	v_and_b32_e32 v2, 48, v8
	s_movk_i32 s9, 0x3c0
	v_and_b32_e32 v3, 0xfffffc00, v13
	v_lshlrev_b32_e32 v0, 2, v0
	v_and_or_b32 v1, v1, s9, v2
	v_add_u32_e32 v4, s73, v3
	v_and_b32_e32 v0, 32, v0
	v_bitop3_b32 v4, v1, v4, v0 bitop3:0xde
	v_lshl_or_b32 v0, v187, 6, v2
	v_lshlrev_b32_e32 v2, 2, v8
	v_add_u32_e32 v1, s72, v3
	v_and_b32_e32 v2, 32, v2
	v_bitop3_b32 v188, v0, v1, v2 bitop3:0xde
	v_lshrrev_b32_e32 v1, 1, v9
	v_mul_lo_u32 v0, v11, s8
	s_mov_b32 s9, 0xb000
	v_mad_u64_u32 v[0:1], s[26:27], v1, s9, v[0:1]
	v_or_b32_e32 v0, v0, v10
	s_mov_b64 s[10:11], 0xb0080
	v_add_lshl_u32 v0, v0, v12, 1
	v_mov_b32_e32 v1, v155
	v_lshl_add_u64 v[160:161], v[0:1], 0, s[10:11]
	v_lshrrev_b32_e32 v1, 1, v14
	v_mul_lo_u32 v0, v15, s8
	v_mad_u64_u32 v[0:1], s[8:9], v1, s9, v[0:1]
	s_waitcnt vmcnt(6)
	v_or_b32_e32 v0, v0, v16
	v_add_lshl_u32 v0, v0, v17, 1
	v_mov_b32_e32 v1, v155
	s_add_i32 s47, 0, 0x10000
	s_add_i32 s48, 0, 0x14000
	v_ashrrev_i32_e32 v186, 4, v8
	s_ashr_i32 s44, s38, 31
	s_mov_b32 s45, s38
	s_ashr_i32 s46, s14, 31
	v_lshl_add_u64 v[162:163], v[0:1], 0, s[10:11]
	v_mov_b64_e32 v[164:165], 0x100
	v_mov_b64_e32 v[166:167], 0xff
	v_add_u32_e32 v189, s47, v188
	v_add_u32_e32 v190, s48, v188
	v_add_u32_e32 v191, 0, v4
	s_mov_b32 s49, 0
	s_barrier
	s_branch .LBB0_2686

; #define PG8_STAGE(bufoff, gbase, voff) do { _Pragma("unroll") for (int _i = 0; _i < 2; ++_i) \
;         __builtin_amdgcn_global_load_lds((const unsigned*)((const char*)(gbase) + (voff)[_i]), (PG8_LAS unsigned*)(lds + (bufoff) + ldsw + _i * 8192), 16, 0, 0); } while (0)
; #define PG8_LDA(dst, b, h) do { _Pragma("unroll") for (int m = 0; m < 4; ++m) _Pragma("unroll") for (int k = 0; k < 2; ++k) dst[m][k] = *(const PG8_LAS bf16x8*)(lds + PG8_SA(b, h) + aoff + m * 2048 + k * 1024); } while (0)
; #define PG8_LDB(dst, b, h) do { _Pragma("unroll") for (int n = 0; n < 2; ++n) _Pragma("unroll") for (int k = 0; k < 2; ++k) dst[n][k] = *(const PG8_LAS bf16x8*)(lds + PG8_SB(b, h) + boff + n * 2048 + k * 1024); } while (0)
; #define PG8_MMA(ai, bj, At, Bt) do { __builtin_amdgcn_s_setprio(1); _Pragma("unroll") for (int m = 0; m < 4; ++m) _Pragma("unroll") for (int n = 0; n < 2; ++n) _Pragma("unroll") for (int k = 0; k < 2; ++k) \
;         acc[ai][bj][m][n] = mma16<F16>(Bt[n][k], At[m][k], acc[ai][bj][m][n]); __builtin_amdgcn_s_setprio(0); } while (0)
; #define PG8_WAIT_V(n) asm volatile("s_waitcnt vmcnt(" #n ")" ::: "memory")
; #define PG8_WAIT_L(n) asm volatile("s_waitcnt lgkmcnt(" #n ")" ::: "memory")
; #define PG8_BAR __builtin_amdgcn_s_barrier()
; #define PG8_SCHED __builtin_amdgcn_sched_barrier(0)
; template <class Epi, class Sched, bool ALIGN_EPI = false, bool SP2 = false, bool F16 = false>
; __device__ __forceinline__ void gemm_phase(PG8_LAS unsigned char* lds, const Gemm g, const Sched& S, const Epi& E, const int wid_in) {
;     ...
;             const bool last = (t == nt - 2);
;             const char* a1 = cA + (size_t)(t + 1) * kstep;
;             const char* a2 = last ? nA : cA + (size_t)(t + 2) * kstep; const char* b2 = last ? nB : cB + (size_t)(t + 2) * kstep;
;             const char* a3 = a2 + kstep; const char* b3 = b2 + kstep;
;             if (last && has_next) S.a_ready(nxt);
;             if constexpr (SP2) {
;             PG8_LDB(B0, 0, 0); PG8_LDB(B1, 0, 1); PG8_SCHED; PG8_LDA(At, 0, 0); PG8_STAGE(PG8_SA(1, 1), a1 + hstep, voffA);
;             PG8_WAIT_V(8); PG8_WAIT_L(0); PG8_BAR; PG8_MMA(0, 0, At, B0); PG8_MMA(0, 1, At, B1); PG8_BAR; PG8_SCHED;
;             PG8_LDA(At, 0, 1); PG8_STAGE(PG8_SB(0, 0), b2, voffB); PG8_STAGE(PG8_SB(0, 1), b2 + hstep, voffB); PG8_STAGE(PG8_SA(0, 0), a2, voffA);
.LBB0_2697:
	ds_read_b128 v[128:131], v189
	ds_read_b128 v[132:135], v189 offset:1024
	ds_read_b128 v[136:139], v189 offset:2048
	ds_read_b128 v[140:143], v189 offset:3072
	ds_read_b128 v[144:147], v190
	ds_read_b128 v[148:151], v190 offset:1024
	ds_read_b128 v[168:171], v190 offset:2048
	ds_read_b128 v[172:175], v190 offset:3072
	s_add_u32 s30, s28, 0x100
	s_addc_u32 s31, s29, 0
	s_cmp_eq_u32 s55, 40
	s_cselect_b32 s37, s11, s31
	s_cselect_b32 s36, s10, s30
	s_cselect_b32 s35, s27, s54
	s_cselect_b32 s34, s26, s53
	s_mov_b32 m0, s91
	v_lshl_add_u64 v[184:185], s[28:29], 0, v[160:161]
	ds_read_b128 v[176:179], v191
	ds_read_b128 v[180:183], v191 offset:1024
	ds_read_b128 v[192:195], v191 offset:2048
	ds_read_b128 v[196:199], v191 offset:3072
	ds_read_b128 v[200:203], v191 offset:4096
	ds_read_b128 v[204:207], v191 offset:5120
	ds_read_b128 v[208:211], v191 offset:6144
	ds_read_b128 v[212:215], v191 offset:7168
	global_load_lds_dwordx4 v[184:185], off
	v_lshl_add_u64 v[184:185], s[28:29], 0, v[162:163]
	s_add_i32 m0, s74, 0xe000
	s_nop 0
	global_load_lds_dwordx4 v[184:185], off
	s_waitcnt vmcnt(8)
	s_waitcnt lgkmcnt(0)
	s_barrier
	s_setprio 1
	s_waitcnt lgkmcnt(0)
	v_mfma_f32_16x16x32_bf16 v[124:127], v[128:131], v[176:179], v[124:127]
	v_mfma_f32_16x16x32_bf16 v[120:123], v[136:139], v[176:179], v[120:123]
	v_mfma_f32_16x16x32_bf16 v[108:111], v[128:131], v[192:195], v[108:111]
	v_mfma_f32_16x16x32_bf16 v[104:107], v[136:139], v[192:195], v[104:107]
	v_mfma_f32_16x16x32_bf16 v[92:95], v[128:131], v[200:203], v[92:95]
	v_mfma_f32_16x16x32_bf16 v[88:91], v[136:139], v[200:203], v[88:91]
	v_mfma_f32_16x16x32_bf16 v[76:79], v[128:131], v[208:211], v[76:79]
	v_mfma_f32_16x16x32_bf16 v[72:75], v[136:139], v[208:211], v[72:75]
	v_mfma_f32_16x16x32_bf16 v[124:127], v[132:135], v[180:183], v[124:127]
	v_mfma_f32_16x16x32_bf16 v[120:123], v[140:143], v[180:183], v[120:123]
	v_mfma_f32_16x16x32_bf16 v[108:111], v[132:135], v[196:199], v[108:111]
	v_mfma_f32_16x16x32_bf16 v[104:107], v[140:143], v[196:199], v[104:107]
	v_mfma_f32_16x16x32_bf16 v[92:95], v[132:135], v[204:207], v[92:95]
	v_mfma_f32_16x16x32_bf16 v[88:91], v[140:143], v[204:207], v[88:91]
	v_mfma_f32_16x16x32_bf16 v[76:79], v[132:135], v[212:215], v[76:79]
	v_mfma_f32_16x16x32_bf16 v[72:75], v[140:143], v[212:215], v[72:75]
	s_setprio 0
	s_setprio 1
	v_mfma_f32_16x16x32_bf16 v[116:119], v[144:147], v[176:179], v[116:119]
	v_mfma_f32_16x16x32_bf16 v[112:115], v[168:171], v[176:179], v[112:115]
	v_mfma_f32_16x16x32_bf16 v[100:103], v[144:147], v[192:195], v[100:103]
	v_mfma_f32_16x16x32_bf16 v[96:99], v[168:171], v[192:195], v[96:99]
	v_mfma_f32_16x16x32_bf16 v[84:87], v[144:147], v[200:203], v[84:87]
	v_mfma_f32_16x16x32_bf16 v[80:83], v[168:171], v[200:203], v[80:83]
	v_mfma_f32_16x16x32_bf16 v[68:71], v[144:147], v[208:211], v[68:71]
	v_mfma_f32_16x16x32_bf16 v[64:67], v[168:171], v[208:211], v[64:67]
	v_mfma_f32_16x16x32_bf16 v[116:119], v[148:151], v[180:183], v[116:119]
	v_mfma_f32_16x16x32_bf16 v[112:115], v[172:175], v[180:183], v[112:115]
	v_mfma_f32_16x16x32_bf16 v[100:103], v[148:151], v[196:199], v[100:103]
	v_mfma_f32_16x16x32_bf16 v[96:99], v[172:175], v[196:199], v[96:99]
	v_mfma_f32_16x16x32_bf16 v[84:87], v[148:151], v[204:207], v[84:87]
	v_mfma_f32_16x16x32_bf16 v[80:83], v[172:175], v[204:207], v[80:83]
	v_mfma_f32_16x16x32_bf16 v[68:71], v[148:151], v[212:215], v[68:71]
	v_mfma_f32_16x16x32_bf16 v[64:67], v[172:175], v[212:215], v[64:67]
	s_setprio 0
	s_barrier
	s_add_i32 s28, s47, s68
	v_lshl_add_u64 v[184:185], s[34:35], 0, v[154:155]
	s_mov_b32 m0, s28
	ds_read_b128 v[176:179], v191 offset:16384
	ds_read_b128 v[180:183], v191 offset:17408
	ds_read_b128 v[192:195], v191 offset:18432
	ds_read_b128 v[196:199], v191 offset:19456
	ds_read_b128 v[200:203], v191 offset:20480
	ds_read_b128 v[204:207], v191 offset:21504
	ds_read_b128 v[208:211], v191 offset:22528
	ds_read_b128 v[212:215], v191 offset:23552
	global_load_lds_dwordx4 v[184:185], off
	s_add_i32 m0, s28, 0x2000
	s_add_u32 s28, s34, 0xb0000
	v_lshl_add_u64 v[216:217], s[34:35], 0, v[158:159]
	s_addc_u32 s29, s35, 0
	s_add_i32 s56, s48, s68
	global_load_lds_dwordx4 v[216:217], off
	s_mov_b32 m0, s56
	v_lshl_add_u64 v[220:221], s[36:37], 0, v[156:157]
	global_load_lds_dwordx4 v154, s[28:29]
	s_add_i32 m0, s56, 0x2000
	s_nop 0
	global_load_lds_dwordx4 v158, s[28:29]
	v_lshl_add_u64 v[218:219], s[36:37], 0, v[152:153]
	s_mov_b32 m0, s74
	s_nop 0
	global_load_lds_dwordx4 v[218:219], off
	s_mov_b32 m0, s66
	s_nop 0
	global_load_lds_dwordx4 v[220:221], off
	s_waitcnt vmcnt(8)
	s_waitcnt lgkmcnt(0)
	s_barrier
; #define PG8_STAGE(bufoff, gbase, voff) do { _Pragma("unroll") for (int _i = 0; _i < 2; ++_i) \
;         __builtin_amdgcn_global_load_lds((const unsigned*)((const char*)(gbase) + (voff)[_i]), (PG8_LAS unsigned*)(lds + (bufoff) + ldsw + _i * 8192), 16, 0, 0); } while (0)
; #define PG8_LDA(dst, b, h) do { _Pragma("unroll") for (int m = 0; m < 4; ++m) _Pragma("unroll") for (int k = 0; k < 2; ++k) dst[m][k] = *(const PG8_LAS bf16x8*)(lds + PG8_SA(b, h) + aoff + m * 2048 + k * 1024); } while (0)
; #define PG8_LDB(dst, b, h) do { _Pragma("unroll") for (int n = 0; n < 2; ++n) _Pragma("unroll") for (int k = 0; k < 2; ++k) dst[n][k] = *(const PG8_LAS bf16x8*)(lds + PG8_SB(b, h) + boff + n * 2048 + k * 1024); } while (0)
; #define PG8_MMA(ai, bj, At, Bt) do { __builtin_amdgcn_s_setprio(1); _Pragma("unroll") for (int m = 0; m < 4; ++m) _Pragma("unroll") for (int n = 0; n < 2; ++n) _Pragma("unroll") for (int k = 0; k < 2; ++k) \
;         acc[ai][bj][m][n] = mma16<F16>(Bt[n][k], At[m][k], acc[ai][bj][m][n]); __builtin_amdgcn_s_setprio(0); } while (0)
; #define PG8_WAIT_V(n) asm volatile("s_waitcnt vmcnt(" #n ")" ::: "memory")
; #define PG8_WAIT_L(n) asm volatile("s_waitcnt lgkmcnt(" #n ")" ::: "memory")
; #define PG8_BAR __builtin_amdgcn_s_barrier()
; #define PG8_SCHED __builtin_amdgcn_sched_barrier(0)
; template <class Epi, class Sched, bool ALIGN_EPI = false, bool SP2 = false, bool F16 = false>
; __device__ __forceinline__ void gemm_phase(PG8_LAS unsigned char* lds, const Gemm g, const Sched& S, const Epi& E, const int wid_in) {
;     ...
;             PG8_LDA(At, 0, 1); PG8_STAGE(PG8_SB(0, 0), b2, voffB); PG8_STAGE(PG8_SB(0, 1), b2 + hstep, voffB); PG8_STAGE(PG8_SA(0, 0), a2, voffA);
;             PG8_WAIT_V(8); PG8_WAIT_L(0); PG8_BAR; PG8_MMA(1, 0, At, B0); PG8_MMA(1, 1, At, B1); PG8_BAR; PG8_SCHED;
;             PG8_LDB(B0, 1, 0); PG8_LDB(B1, 1, 1); PG8_SCHED; PG8_LDA(At, 1, 0); PG8_STAGE(PG8_SA(0, 1), a2 + hstep, voffA);
;             PG8_WAIT_V(8); PG8_WAIT_L(0); PG8_BAR; PG8_MMA(0, 0, At, B0); PG8_MMA(0, 1, At, B1); PG8_BAR; PG8_SCHED;
;             PG8_LDA(At, 1, 1); PG8_STAGE(PG8_SB(1, 0), b3, voffB); PG8_STAGE(PG8_SB(1, 1), b3 + hstep, voffB); PG8_STAGE(PG8_SA(1, 0), a3, voffA);
	s_setprio 1
	s_waitcnt lgkmcnt(0)
	v_mfma_f32_16x16x32_bf16 v[60:63], v[128:131], v[176:179], v[60:63]
	v_mfma_f32_16x16x32_bf16 v[56:59], v[136:139], v[176:179], v[56:59]
	v_mfma_f32_16x16x32_bf16 v[44:47], v[128:131], v[192:195], v[44:47]
	v_mfma_f32_16x16x32_bf16 v[40:43], v[136:139], v[192:195], v[40:43]
	v_mfma_f32_16x16x32_bf16 v[28:31], v[128:131], v[200:203], v[28:31]
	v_mfma_f32_16x16x32_bf16 v[24:27], v[136:139], v[200:203], v[24:27]
	v_mfma_f32_16x16x32_bf16 v[12:15], v[128:131], v[208:211], v[12:15]
	v_mfma_f32_16x16x32_bf16 v[8:11], v[136:139], v[208:211], v[8:11]
	v_mfma_f32_16x16x32_bf16 v[60:63], v[132:135], v[180:183], v[60:63]
	v_mfma_f32_16x16x32_bf16 v[56:59], v[140:143], v[180:183], v[56:59]
	v_mfma_f32_16x16x32_bf16 v[44:47], v[132:135], v[196:199], v[44:47]
	v_mfma_f32_16x16x32_bf16 v[40:43], v[140:143], v[196:199], v[40:43]
	v_mfma_f32_16x16x32_bf16 v[28:31], v[132:135], v[204:207], v[28:31]
	v_mfma_f32_16x16x32_bf16 v[24:27], v[140:143], v[204:207], v[24:27]
	v_mfma_f32_16x16x32_bf16 v[12:15], v[132:135], v[212:215], v[12:15]
	v_mfma_f32_16x16x32_bf16 v[8:11], v[140:143], v[212:215], v[8:11]
	s_setprio 0
	s_setprio 1
	v_mfma_f32_16x16x32_bf16 v[52:55], v[144:147], v[176:179], v[52:55]
	v_mfma_f32_16x16x32_bf16 v[48:51], v[168:171], v[176:179], v[48:51]
	v_mfma_f32_16x16x32_bf16 v[36:39], v[144:147], v[192:195], v[36:39]
	v_mfma_f32_16x16x32_bf16 v[32:35], v[168:171], v[192:195], v[32:35]
	v_mfma_f32_16x16x32_bf16 v[20:23], v[144:147], v[200:203], v[20:23]
	v_mfma_f32_16x16x32_bf16 v[16:19], v[168:171], v[200:203], v[16:19]
	v_mfma_f32_16x16x32_bf16 v[4:7], v[144:147], v[208:211], v[4:7]
	v_mfma_f32_16x16x32_bf16 v[0:3], v[168:171], v[208:211], v[0:3]
	v_mfma_f32_16x16x32_bf16 v[52:55], v[148:151], v[180:183], v[52:55]
	v_mfma_f32_16x16x32_bf16 v[48:51], v[172:175], v[180:183], v[48:51]
	v_mfma_f32_16x16x32_bf16 v[36:39], v[148:151], v[196:199], v[36:39]
	v_mfma_f32_16x16x32_bf16 v[32:35], v[172:175], v[196:199], v[32:35]
	v_mfma_f32_16x16x32_bf16 v[20:23], v[148:151], v[204:207], v[20:23]
	v_mfma_f32_16x16x32_bf16 v[16:19], v[172:175], v[204:207], v[16:19]
	v_mfma_f32_16x16x32_bf16 v[4:7], v[148:151], v[212:215], v[4:7]
	v_mfma_f32_16x16x32_bf16 v[0:3], v[172:175], v[212:215], v[0:3]
	s_setprio 0
	s_barrier
	s_add_i32 s56, 0, 0x18000
	s_add_i32 s57, 0, 0x1c000
	v_add_u32_e32 v140, s56, v188
	v_add_u32_e32 v172, s57, v188
	ds_read_b128 v[128:131], v140
	ds_read_b128 v[132:135], v140 offset:1024
	ds_read_b128 v[136:139], v140 offset:2048
	ds_read_b128 v[140:143], v140 offset:3072
	ds_read_b128 v[144:147], v172
	ds_read_b128 v[148:151], v172 offset:1024
	ds_read_b128 v[168:171], v172 offset:2048
	ds_read_b128 v[172:175], v172 offset:3072
	s_add_u32 s28, s36, 0xb0000
	s_addc_u32 s29, s37, 0
	s_mov_b32 m0, s90
	ds_read_b128 v[176:179], v191 offset:32768
	ds_read_b128 v[180:183], v191 offset:33792
	ds_read_b128 v[192:195], v191 offset:34816
	ds_read_b128 v[196:199], v191 offset:35840
	ds_read_b128 v[200:203], v191 offset:36864
	ds_read_b128 v[204:207], v191 offset:37888
	ds_read_b128 v[208:211], v191 offset:38912
	ds_read_b128 v[212:215], v191 offset:39936
	global_load_lds_dwordx4 v152, s[28:29]
	v_lshl_add_u64 v[222:223], s[28:29], 0, v[156:157]
	s_mov_b32 m0, s43
	s_nop 0
	global_load_lds_dwordx4 v[222:223], off
	s_waitcnt vmcnt(8)
	s_waitcnt lgkmcnt(0)
	s_barrier
	s_setprio 1
	s_waitcnt lgkmcnt(0)
	v_mfma_f32_16x16x32_bf16 v[124:127], v[128:131], v[176:179], v[124:127]
	v_mfma_f32_16x16x32_bf16 v[120:123], v[136:139], v[176:179], v[120:123]
	v_mfma_f32_16x16x32_bf16 v[108:111], v[128:131], v[192:195], v[108:111]
	v_mfma_f32_16x16x32_bf16 v[104:107], v[136:139], v[192:195], v[104:107]
	v_mfma_f32_16x16x32_bf16 v[92:95], v[128:131], v[200:203], v[92:95]
	v_mfma_f32_16x16x32_bf16 v[88:91], v[136:139], v[200:203], v[88:91]
	v_mfma_f32_16x16x32_bf16 v[76:79], v[128:131], v[208:211], v[76:79]
	v_mfma_f32_16x16x32_bf16 v[72:75], v[136:139], v[208:211], v[72:75]
	v_mfma_f32_16x16x32_bf16 v[124:127], v[132:135], v[180:183], v[124:127]
	v_mfma_f32_16x16x32_bf16 v[120:123], v[140:143], v[180:183], v[120:123]
	v_mfma_f32_16x16x32_bf16 v[108:111], v[132:135], v[196:199], v[108:111]
	v_mfma_f32_16x16x32_bf16 v[104:107], v[140:143], v[196:199], v[104:107]
	v_mfma_f32_16x16x32_bf16 v[92:95], v[132:135], v[204:207], v[92:95]
	v_mfma_f32_16x16x32_bf16 v[88:91], v[140:143], v[204:207], v[88:91]
	v_mfma_f32_16x16x32_bf16 v[76:79], v[132:135], v[212:215], v[76:79]
	v_mfma_f32_16x16x32_bf16 v[72:75], v[140:143], v[212:215], v[72:75]
	s_setprio 0
	s_setprio 1
	v_mfma_f32_16x16x32_bf16 v[116:119], v[144:147], v[176:179], v[116:119]
	v_mfma_f32_16x16x32_bf16 v[112:115], v[168:171], v[176:179], v[112:115]
	v_mfma_f32_16x16x32_bf16 v[100:103], v[144:147], v[192:195], v[100:103]
	v_mfma_f32_16x16x32_bf16 v[96:99], v[168:171], v[192:195], v[96:99]
	v_mfma_f32_16x16x32_bf16 v[84:87], v[144:147], v[200:203], v[84:87]
	v_mfma_f32_16x16x32_bf16 v[80:83], v[168:171], v[200:203], v[80:83]
	v_mfma_f32_16x16x32_bf16 v[68:71], v[144:147], v[208:211], v[68:71]
	v_mfma_f32_16x16x32_bf16 v[64:67], v[168:171], v[208:211], v[64:67]
	v_mfma_f32_16x16x32_bf16 v[116:119], v[148:151], v[180:183], v[116:119]
	v_mfma_f32_16x16x32_bf16 v[112:115], v[172:175], v[180:183], v[112:115]
	v_mfma_f32_16x16x32_bf16 v[100:103], v[148:151], v[196:199], v[100:103]
	v_mfma_f32_16x16x32_bf16 v[96:99], v[172:175], v[196:199], v[96:99]
	v_mfma_f32_16x16x32_bf16 v[84:87], v[148:151], v[204:207], v[84:87]
	v_mfma_f32_16x16x32_bf16 v[80:83], v[172:175], v[204:207], v[80:83]
	v_mfma_f32_16x16x32_bf16 v[68:71], v[148:151], v[212:215], v[68:71]
	v_mfma_f32_16x16x32_bf16 v[64:67], v[172:175], v[212:215], v[64:67]
	s_setprio 0
	s_barrier
; #define PG8_STAGE(bufoff, gbase, voff) do { _Pragma("unroll") for (int _i = 0; _i < 2; ++_i) \
;         __builtin_amdgcn_global_load_lds((const unsigned*)((const char*)(gbase) + (voff)[_i]), (PG8_LAS unsigned*)(lds + (bufoff) + ldsw + _i * 8192), 16, 0, 0); } while (0)
; #define PG8_LDA(dst, b, h) do { _Pragma("unroll") for (int m = 0; m < 4; ++m) _Pragma("unroll") for (int k = 0; k < 2; ++k) dst[m][k] = *(const PG8_LAS bf16x8*)(lds + PG8_SA(b, h) + aoff + m * 2048 + k * 1024); } while (0)
; #define PG8_MMA(ai, bj, At, Bt) do { __builtin_amdgcn_s_setprio(1); _Pragma("unroll") for (int m = 0; m < 4; ++m) _Pragma("unroll") for (int n = 0; n < 2; ++n) _Pragma("unroll") for (int k = 0; k < 2; ++k) \
;         acc[ai][bj][m][n] = mma16<F16>(Bt[n][k], At[m][k], acc[ai][bj][m][n]); __builtin_amdgcn_s_setprio(0); } while (0)
; #define PG8_WAIT_V(n) asm volatile("s_waitcnt vmcnt(" #n ")" ::: "memory")
; #define PG8_WAIT_L(n) asm volatile("s_waitcnt lgkmcnt(" #n ")" ::: "memory")
; #define PG8_BAR __builtin_amdgcn_s_barrier()
; #define PG8_SCHED __builtin_amdgcn_sched_barrier(0)
; template <class Epi, class Sched, bool ALIGN_EPI = false, bool SP2 = false, bool F16 = false>
; __device__ __forceinline__ void gemm_phase(PG8_LAS unsigned char* lds, const Gemm g, const Sched& S, const Epi& E, const int wid_in) {
;     ...
;             PG8_LDA(At, 1, 1); PG8_STAGE(PG8_SB(1, 0), b3, voffB); PG8_STAGE(PG8_SB(1, 1), b3 + hstep, voffB); PG8_STAGE(PG8_SA(1, 0), a3, voffA);
;             PG8_WAIT_V(8); PG8_WAIT_L(0); PG8_BAR; PG8_MMA(1, 0, At, B0); PG8_MMA(1, 1, At, B1); PG8_BAR; PG8_SCHED;
	s_add_i32 s28, s56, s68
	v_lshl_add_u64 v[184:185], v[184:185], 0, s[24:25]
	s_mov_b32 m0, s28
	ds_read_b128 v[176:179], v191 offset:49152
	ds_read_b128 v[180:183], v191 offset:50176
	ds_read_b128 v[192:195], v191 offset:51200
	ds_read_b128 v[196:199], v191 offset:52224
	ds_read_b128 v[200:203], v191 offset:53248
	ds_read_b128 v[204:207], v191 offset:54272
	ds_read_b128 v[208:211], v191 offset:55296
	ds_read_b128 v[212:215], v191 offset:56320
	global_load_lds_dwordx4 v[184:185], off
	s_add_i32 m0, s28, 0x2000
	s_add_u32 s28, s34, 0xb0080
	v_lshl_add_u64 v[184:185], v[216:217], 0, s[24:25]
	s_addc_u32 s29, s35, 0
	s_add_i32 s34, s57, s68
	global_load_lds_dwordx4 v[184:185], off
	s_mov_b32 m0, s34
	s_nop 0
	global_load_lds_dwordx4 v154, s[28:29]
	s_add_i32 m0, s34, 0x2000
	s_nop 0
	global_load_lds_dwordx4 v158, s[28:29]
	v_lshl_add_u64 v[184:185], v[218:219], 0, s[24:25]
	s_mov_b32 m0, s75
	s_nop 0
	global_load_lds_dwordx4 v[184:185], off
	v_lshl_add_u64 v[184:185], v[220:221], 0, s[24:25]
	s_mov_b32 m0, s67
	s_nop 0
	global_load_lds_dwordx4 v[184:185], off
	s_waitcnt vmcnt(8)
	s_waitcnt lgkmcnt(0)
	s_barrier
	s_setprio 1
	s_waitcnt lgkmcnt(0)
	v_mfma_f32_16x16x32_bf16 v[60:63], v[128:131], v[176:179], v[60:63]
	v_mfma_f32_16x16x32_bf16 v[56:59], v[136:139], v[176:179], v[56:59]
	v_mfma_f32_16x16x32_bf16 v[44:47], v[128:131], v[192:195], v[44:47]
	v_mfma_f32_16x16x32_bf16 v[40:43], v[136:139], v[192:195], v[40:43]
	v_mfma_f32_16x16x32_bf16 v[28:31], v[128:131], v[200:203], v[28:31]
	v_mfma_f32_16x16x32_bf16 v[24:27], v[136:139], v[200:203], v[24:27]
	v_mfma_f32_16x16x32_bf16 v[12:15], v[128:131], v[208:211], v[12:15]
	v_mfma_f32_16x16x32_bf16 v[8:11], v[136:139], v[208:211], v[8:11]
	v_mfma_f32_16x16x32_bf16 v[60:63], v[132:135], v[180:183], v[60:63]
	v_mfma_f32_16x16x32_bf16 v[56:59], v[140:143], v[180:183], v[56:59]
	v_mfma_f32_16x16x32_bf16 v[44:47], v[132:135], v[196:199], v[44:47]
	v_mfma_f32_16x16x32_bf16 v[40:43], v[140:143], v[196:199], v[40:43]
	v_mfma_f32_16x16x32_bf16 v[28:31], v[132:135], v[204:207], v[28:31]
	v_mfma_f32_16x16x32_bf16 v[24:27], v[140:143], v[204:207], v[24:27]
	v_mfma_f32_16x16x32_bf16 v[12:15], v[132:135], v[212:215], v[12:15]
	v_mfma_f32_16x16x32_bf16 v[8:11], v[140:143], v[212:215], v[8:11]
	s_setprio 0
	s_setprio 1
	v_mfma_f32_16x16x32_bf16 v[52:55], v[144:147], v[176:179], v[52:55]
	v_mfma_f32_16x16x32_bf16 v[48:51], v[168:171], v[176:179], v[48:51]
	v_mfma_f32_16x16x32_bf16 v[36:39], v[144:147], v[192:195], v[36:39]
	v_mfma_f32_16x16x32_bf16 v[32:35], v[168:171], v[192:195], v[32:35]
	v_mfma_f32_16x16x32_bf16 v[20:23], v[144:147], v[200:203], v[20:23]
	v_mfma_f32_16x16x32_bf16 v[16:19], v[168:171], v[200:203], v[16:19]
	v_mfma_f32_16x16x32_bf16 v[4:7], v[144:147], v[208:211], v[4:7]
	v_mfma_f32_16x16x32_bf16 v[0:3], v[168:171], v[208:211], v[0:3]
	v_mfma_f32_16x16x32_bf16 v[52:55], v[148:151], v[180:183], v[52:55]
	v_mfma_f32_16x16x32_bf16 v[48:51], v[172:175], v[180:183], v[48:51]
	v_mfma_f32_16x16x32_bf16 v[36:39], v[148:151], v[196:199], v[36:39]
	v_mfma_f32_16x16x32_bf16 v[32:35], v[172:175], v[196:199], v[32:35]
	v_mfma_f32_16x16x32_bf16 v[20:23], v[148:151], v[204:207], v[20:23]
	v_mfma_f32_16x16x32_bf16 v[16:19], v[172:175], v[204:207], v[16:19]
	v_mfma_f32_16x16x32_bf16 v[4:7], v[148:151], v[212:215], v[4:7]
	v_mfma_f32_16x16x32_bf16 v[0:3], v[172:175], v[212:215], v[0:3]
	s_setprio 0
	s_barrier
	s_add_i32 s55, s55, 2
	s_add_u32 s53, s53, 0x100
	s_addc_u32 s54, s54, 0
	s_cmp_gt_u32 s55, 41
	s_mov_b64 s[28:29], s[30:31]
	s_cbranch_scc0 .LBB0_2697
	s_and_b64 vcc, exec, s[16:17]
	s_cbranch_vccz .LBB0_2700
	s_barrier

; #define PG8_STAGE(bufoff, gbase, voff) do { _Pragma("unroll") for (int _i = 0; _i < 2; ++_i) \
;         __builtin_amdgcn_global_load_lds((const unsigned*)((const char*)(gbase) + (voff)[_i]), (PG8_LAS unsigned*)(lds + (bufoff) + ldsw + _i * 8192), 16, 0, 0); } while (0)
; #define PG8_WAIT_V(n) asm volatile("s_waitcnt vmcnt(" #n ")" ::: "memory")
; #define PG8_BAR __builtin_amdgcn_s_barrier()
; template <class Epi, class Sched, bool ALIGN_EPI = false, bool SP2 = false, bool F16 = false>
; __device__ __forceinline__ void gemm_phase(PG8_LAS unsigned char* lds, const Gemm g, const Sched& S, const Epi& E, const int wid_in) {
;     ...
;     for (int i = 0; i < 2; ++i) { int R, C; stage_rc(tid * 16 + i * 8192, R, C); const int Rb = Epi::PERM ? ((R & ~31) + perm32(R & 31)) : R;
;         voffA[i] = (unsigned)(R * K + C) * 2u; voffB[i] = (unsigned)(Rb * K + C) * 2u; }
;     const size_t kstep = (size_t)(BK * 2);
;     const size_t hstep = (size_t)HALF * K * 2;
;     const size_t tstep = 2 * hstep;
;     const unsigned ldsw = (unsigned)wid * 1024u;
;     const int aoff = lds_byte(wr * 64 + fr, fq * 8), boff = lds_byte(wc * 32 + fr, fq * 8);
;     ...
;         PG8_STAGE(PG8_SB(1, 0), cB + kstep, voffB); PG8_STAGE(PG8_SA(1, 0), cA + kstep, voffA); PG8_STAGE(PG8_SB(1, 1), cB + hstep + kstep, voffB);
;         PG8_WAIT_V(6); PG8_BAR;
;     } else {
;         PG8_STAGE(PG8_SB(0, 0), cB, voffB); PG8_STAGE(PG8_SA(0, 0), cA, voffA); PG8_STAGE(PG8_SB(0, 1), cB + hstep, voffB); PG8_STAGE(PG8_SA(0, 1), cA + hstep, voffA);
;         if (wr == 1) PG8_BAR;
;         PG8_WAIT_V(4); PG8_BAR;
;         PG8_STAGE(PG8_SB(1, 0), cB + kstep, voffB); PG8_STAGE(PG8_SA(1, 0), cA + kstep, voffA); PG8_STAGE(PG8_SB(1, 1), cB + hstep + kstep, voffB);
;         PG8_WAIT_V(6); PG8_BAR;
;     }
.LBB0_2783:
	s_add_u32 s18, s8, 0x15400000
	s_addc_u32 s19, s9, 0
	s_add_u32 s20, s8, 0x13400000
	s_addc_u32 s21, s9, 0
	s_add_u32 s22, s8, 0xf400000
	s_addc_u32 s23, s9, 0
	s_add_u32 s24, s8, 0x15700000
	s_mov_b64 s[26:27], 0x80
	s_addc_u32 s25, s9, 0
	s_add_i32 m0, s74, 0x18000
	v_lshl_add_u64 v[6:7], v[6:7], 0, s[26:27]
	s_waitcnt vmcnt(2)
	s_barrier
	global_load_lds_dwordx4 v[6:7], off
	v_lshl_add_u64 v[4:5], v[4:5], 0, s[26:27]
	s_add_i32 m0, s74, 0x1a000
	v_lshl_add_u64 v[0:1], v[0:1], 0, s[26:27]
	global_load_lds_dwordx4 v[4:5], off
	s_mov_b32 m0, s75
	s_add_u32 s8, s44, 0x40080
	global_load_lds_dwordx4 v[0:1], off
	v_lshl_add_u64 v[0:1], v[2:3], 0, s[26:27]
	s_mov_b32 m0, s67
	s_addc_u32 s9, s45, 0
	global_load_lds_dwordx4 v[0:1], off
	s_add_i32 m0, s74, 0x1c000
	s_nop 0
	global_load_lds_dwordx4 v198, s[8:9]
	s_add_i32 m0, s74, 0x1e000
	v_and_b32_e32 v232, 15, v8
	global_load_lds_dwordx4 v202, s[8:9]
	v_or_b32_e32 v0, s70, v232
	v_lshlrev_b32_e32 v1, 6, v0
	v_and_b32_e32 v2, 48, v8
	s_movk_i32 s8, 0x3c0
	v_and_b32_e32 v3, 0xfffffc00, v12
	v_lshlrev_b32_e32 v0, 2, v0
	v_and_or_b32 v1, v1, s8, v2
	v_add_u32_e32 v4, s73, v3
	v_and_b32_e32 v0, 32, v0
	v_bitop3_b32 v0, v1, v4, v0 bitop3:0xde
	v_lshl_or_b32 v1, v232, 6, v2
	v_add_u32_e32 v2, s72, v3
	v_lshlrev_b32_e32 v3, 2, v8
	v_and_b32_e32 v3, 32, v3
	v_bitop3_b32 v234, v1, v2, v3 bitop3:0xde
	v_lshlrev_b32_e32 v1, 14, v9
	v_and_b32_e32 v1, 0xffff8000, v1
	v_lshl_add_u32 v1, v10, 11, v1
	v_and_b32_e32 v2, 1, v9
	v_lshl_or_b32 v1, v2, 6, v1
	v_lshl_add_u32 v204, v11, 1, v1
	v_lshlrev_b32_e32 v1, 14, v13
	v_and_b32_e32 v1, 0xffff8000, v1
	s_waitcnt vmcnt(6)
	v_lshl_add_u32 v1, v14, 11, v1
	v_and_b32_e32 v2, 1, v13
	v_lshl_or_b32 v1, v2, 6, v1
	s_add_i32 s55, 0, 0x10000
	s_add_i32 s56, 0, 0x14000
	v_ashrrev_i32_e32 v233, 4, v8
	s_ashr_i32 s52, s38, 31
	s_mov_b32 s53, s38
	s_ashr_i32 s54, s48, 31
	v_mov_b32_e32 v205, v199
	v_lshl_add_u32 v206, v15, 1, v1
	v_mov_b32_e32 v207, v199
	v_mov_b64_e32 v[208:209], 0x100
	v_mov_b64_e32 v[210:211], 0xff
	v_add_u32_e32 v235, s55, v234
	v_add_u32_e32 v236, s56, v234
	v_add_u32_e32 v237, 0, v0
	v_mov_b32_e32 v238, 0x358637bd
	s_mov_b32 s57, 0
	s_barrier
	s_branch .LBB0_2786

; #define PG8_STAGE(bufoff, gbase, voff) do { _Pragma("unroll") for (int _i = 0; _i < 2; ++_i) \
;         __builtin_amdgcn_global_load_lds((const unsigned*)((const char*)(gbase) + (voff)[_i]), (PG8_LAS unsigned*)(lds + (bufoff) + ldsw + _i * 8192), 16, 0, 0); } while (0)
; #define PG8_LDA(dst, b, h) do { _Pragma("unroll") for (int m = 0; m < 4; ++m) _Pragma("unroll") for (int k = 0; k < 2; ++k) dst[m][k] = *(const PG8_LAS bf16x8*)(lds + PG8_SA(b, h) + aoff + m * 2048 + k * 1024); } while (0)
; #define PG8_LDB(dst, b, h) do { _Pragma("unroll") for (int n = 0; n < 2; ++n) _Pragma("unroll") for (int k = 0; k < 2; ++k) dst[n][k] = *(const PG8_LAS bf16x8*)(lds + PG8_SB(b, h) + boff + n * 2048 + k * 1024); } while (0)
; #define PG8_MMA(ai, bj, At, Bt) do { __builtin_amdgcn_s_setprio(1); _Pragma("unroll") for (int m = 0; m < 4; ++m) _Pragma("unroll") for (int n = 0; n < 2; ++n) _Pragma("unroll") for (int k = 0; k < 2; ++k) \
;         acc[ai][bj][m][n] = mma16<F16>(Bt[n][k], At[m][k], acc[ai][bj][m][n]); __builtin_amdgcn_s_setprio(0); } while (0)
; #define PG8_WAIT_V(n) asm volatile("s_waitcnt vmcnt(" #n ")" ::: "memory")
; #define PG8_WAIT_L(n) asm volatile("s_waitcnt lgkmcnt(" #n ")" ::: "memory")
; template <class Epi, class Sched, bool ALIGN_EPI = false, bool SP2 = false, bool F16 = false>
; __device__ __forceinline__ void gemm_phase(PG8_LAS unsigned char* lds, const Gemm g, const Sched& S, const Epi& E, const int wid_in) {
;     ...
;             const bool last = (t == nt - 2);
;             const char* a1 = cA + (size_t)(t + 1) * kstep;
;             const char* a2 = last ? nA : cA + (size_t)(t + 2) * kstep; const char* b2 = last ? nB : cB + (size_t)(t + 2) * kstep;
;             const char* a3 = a2 + kstep; const char* b3 = b2 + kstep;
;             if (last && has_next) S.a_ready(nxt);
;             if constexpr (SP2) {
;             PG8_LDB(B0, 0, 0); PG8_LDB(B1, 0, 1); PG8_SCHED; PG8_LDA(At, 0, 0); PG8_STAGE(PG8_SA(1, 1), a1 + hstep, voffA);
;             PG8_WAIT_V(8); PG8_WAIT_L(0); PG8_BAR; PG8_MMA(0, 0, At, B0); PG8_MMA(0, 1, At, B1); PG8_BAR; PG8_SCHED;
;             PG8_LDA(At, 0, 1); PG8_STAGE(PG8_SB(0, 0), b2, voffB); PG8_STAGE(PG8_SB(0, 1), b2 + hstep, voffB); PG8_STAGE(PG8_SA(0, 0), a2, voffA);
;             PG8_WAIT_V(8); PG8_WAIT_L(0); PG8_BAR; PG8_MMA(1, 0, At, B0); PG8_MMA(1, 1, At, B1); PG8_BAR; PG8_SCHED;
.LBB0_2793:
	ds_read_b128 v[112:115], v235
	ds_read_b128 v[116:119], v235 offset:1024
	ds_read_b128 v[128:131], v235 offset:2048
	ds_read_b128 v[132:135], v235 offset:3072
	ds_read_b128 v[144:147], v236
	ds_read_b128 v[148:151], v236 offset:1024
	ds_read_b128 v[152:155], v236 offset:2048
	ds_read_b128 v[156:159], v236 offset:3072
	s_add_u32 s44, s42, 0xfffc0080
	s_addc_u32 s45, s43, -1
	s_cmp_eq_u32 s59, 12
	s_cselect_b32 s47, s14, s45
	s_cselect_b32 s46, s15, s44
	s_cselect_b32 s45, s29, s58
	s_cselect_b32 s44, s31, s41
	s_mov_b32 m0, s91
	ds_read_b128 v[160:163], v237
	ds_read_b128 v[164:167], v237 offset:1024
	ds_read_b128 v[168:171], v237 offset:2048
	ds_read_b128 v[172:175], v237 offset:3072
	ds_read_b128 v[176:179], v237 offset:4096
	ds_read_b128 v[180:183], v237 offset:5120
	ds_read_b128 v[184:187], v237 offset:6144
	ds_read_b128 v[188:191], v237 offset:7168
	global_load_lds_dwordx4 v204, s[42:43]
	s_add_i32 m0, s74, 0xe000
	s_nop 0
	global_load_lds_dwordx4 v206, s[42:43]
	s_waitcnt vmcnt(8)
	s_waitcnt lgkmcnt(0)
	s_barrier
	s_setprio 1
	s_waitcnt lgkmcnt(0)
	v_mfma_f32_16x16x32_f16 v[140:143], v[112:115], v[160:163], v[140:143]
	v_mfma_f32_16x16x32_f16 v[136:139], v[128:131], v[160:163], v[136:139]
	v_mfma_f32_16x16x32_f16 v[108:111], v[112:115], v[168:171], v[108:111]
	v_mfma_f32_16x16x32_f16 v[104:107], v[128:131], v[168:171], v[104:107]
	v_mfma_f32_16x16x32_f16 v[92:95], v[112:115], v[176:179], v[92:95]
	v_mfma_f32_16x16x32_f16 v[88:91], v[128:131], v[176:179], v[88:91]
	v_mfma_f32_16x16x32_f16 v[76:79], v[112:115], v[184:187], v[76:79]
	v_mfma_f32_16x16x32_f16 v[72:75], v[128:131], v[184:187], v[72:75]
	v_mfma_f32_16x16x32_f16 v[140:143], v[116:119], v[164:167], v[140:143]
	v_mfma_f32_16x16x32_f16 v[136:139], v[132:135], v[164:167], v[136:139]
	v_mfma_f32_16x16x32_f16 v[108:111], v[116:119], v[172:175], v[108:111]
	v_mfma_f32_16x16x32_f16 v[104:107], v[132:135], v[172:175], v[104:107]
	v_mfma_f32_16x16x32_f16 v[92:95], v[116:119], v[180:183], v[92:95]
	v_mfma_f32_16x16x32_f16 v[88:91], v[132:135], v[180:183], v[88:91]
	v_mfma_f32_16x16x32_f16 v[76:79], v[116:119], v[188:191], v[76:79]
	v_mfma_f32_16x16x32_f16 v[72:75], v[132:135], v[188:191], v[72:75]
	s_setprio 0
	s_setprio 1
	v_mfma_f32_16x16x32_f16 v[124:127], v[144:147], v[160:163], v[124:127]
	v_mfma_f32_16x16x32_f16 v[120:123], v[152:155], v[160:163], v[120:123]
	v_mfma_f32_16x16x32_f16 v[100:103], v[144:147], v[168:171], v[100:103]
	v_mfma_f32_16x16x32_f16 v[96:99], v[152:155], v[168:171], v[96:99]
	v_mfma_f32_16x16x32_f16 v[84:87], v[144:147], v[176:179], v[84:87]
	v_mfma_f32_16x16x32_f16 v[80:83], v[152:155], v[176:179], v[80:83]
	v_mfma_f32_16x16x32_f16 v[68:71], v[144:147], v[184:187], v[68:71]
	v_mfma_f32_16x16x32_f16 v[64:67], v[152:155], v[184:187], v[64:67]
	v_mfma_f32_16x16x32_f16 v[124:127], v[148:151], v[164:167], v[124:127]
	v_mfma_f32_16x16x32_f16 v[120:123], v[156:159], v[164:167], v[120:123]
	v_mfma_f32_16x16x32_f16 v[100:103], v[148:151], v[172:175], v[100:103]
	v_mfma_f32_16x16x32_f16 v[96:99], v[156:159], v[172:175], v[96:99]
	v_mfma_f32_16x16x32_f16 v[84:87], v[148:151], v[180:183], v[84:87]
	v_mfma_f32_16x16x32_f16 v[80:83], v[156:159], v[180:183], v[80:83]
	v_mfma_f32_16x16x32_f16 v[68:71], v[148:151], v[188:191], v[68:71]
	v_mfma_f32_16x16x32_f16 v[64:67], v[156:159], v[188:191], v[64:67]
	s_setprio 0
	s_barrier
	s_add_i32 s60, s55, s68
	v_lshl_add_u64 v[192:193], s[44:45], 0, v[198:199]
	s_mov_b32 m0, s60
	ds_read_b128 v[160:163], v237 offset:16384
	ds_read_b128 v[164:167], v237 offset:17408
	ds_read_b128 v[168:171], v237 offset:18432
	ds_read_b128 v[172:175], v237 offset:19456
	ds_read_b128 v[176:179], v237 offset:20480
	ds_read_b128 v[180:183], v237 offset:21504
	ds_read_b128 v[184:187], v237 offset:22528
	ds_read_b128 v[188:191], v237 offset:23552
	global_load_lds_dwordx4 v[192:193], off
	s_add_i32 m0, s60, 0x2000
	s_add_u32 s60, s44, 0x40000
	v_lshl_add_u64 v[194:195], s[44:45], 0, v[202:203]
	s_addc_u32 s61, s45, 0
	s_add_i32 s62, s56, s68
	global_load_lds_dwordx4 v[194:195], off
	s_mov_b32 m0, s62
	v_lshl_add_u64 v[214:215], s[46:47], 0, v[200:201]
	global_load_lds_dwordx4 v198, s[60:61]
	s_add_i32 m0, s62, 0x2000
	s_nop 0
	global_load_lds_dwordx4 v202, s[60:61]
	v_lshl_add_u64 v[212:213], s[46:47], 0, v[196:197]
	s_mov_b32 m0, s74
	s_nop 0
	global_load_lds_dwordx4 v[212:213], off
	s_mov_b32 m0, s66
	s_nop 0
	global_load_lds_dwordx4 v[214:215], off
	s_waitcnt vmcnt(8)
	s_waitcnt lgkmcnt(0)
	s_barrier
	s_setprio 1
	s_waitcnt lgkmcnt(0)
	v_mfma_f32_16x16x32_f16 v[60:63], v[112:115], v[160:163], v[60:63]
	v_mfma_f32_16x16x32_f16 v[56:59], v[128:131], v[160:163], v[56:59]
	v_mfma_f32_16x16x32_f16 v[44:47], v[112:115], v[168:171], v[44:47]
	v_mfma_f32_16x16x32_f16 v[40:43], v[128:131], v[168:171], v[40:43]
	v_mfma_f32_16x16x32_f16 v[28:31], v[112:115], v[176:179], v[28:31]
	v_mfma_f32_16x16x32_f16 v[24:27], v[128:131], v[176:179], v[24:27]
	v_mfma_f32_16x16x32_f16 v[12:15], v[112:115], v[184:187], v[12:15]
	v_mfma_f32_16x16x32_f16 v[8:11], v[128:131], v[184:187], v[8:11]
	v_mfma_f32_16x16x32_f16 v[60:63], v[116:119], v[164:167], v[60:63]
	v_mfma_f32_16x16x32_f16 v[56:59], v[132:135], v[164:167], v[56:59]
	v_mfma_f32_16x16x32_f16 v[44:47], v[116:119], v[172:175], v[44:47]
	v_mfma_f32_16x16x32_f16 v[40:43], v[132:135], v[172:175], v[40:43]
	v_mfma_f32_16x16x32_f16 v[28:31], v[116:119], v[180:183], v[28:31]
	v_mfma_f32_16x16x32_f16 v[24:27], v[132:135], v[180:183], v[24:27]
	v_mfma_f32_16x16x32_f16 v[12:15], v[116:119], v[188:191], v[12:15]
	v_mfma_f32_16x16x32_f16 v[8:11], v[132:135], v[188:191], v[8:11]
	s_setprio 0
	s_setprio 1
	v_mfma_f32_16x16x32_f16 v[52:55], v[144:147], v[160:163], v[52:55]
	v_mfma_f32_16x16x32_f16 v[48:51], v[152:155], v[160:163], v[48:51]
	v_mfma_f32_16x16x32_f16 v[36:39], v[144:147], v[168:171], v[36:39]
	v_mfma_f32_16x16x32_f16 v[32:35], v[152:155], v[168:171], v[32:35]
	v_mfma_f32_16x16x32_f16 v[20:23], v[144:147], v[176:179], v[20:23]
	v_mfma_f32_16x16x32_f16 v[16:19], v[152:155], v[176:179], v[16:19]
	v_mfma_f32_16x16x32_f16 v[4:7], v[144:147], v[184:187], v[4:7]
	v_mfma_f32_16x16x32_f16 v[0:3], v[152:155], v[184:187], v[0:3]
	v_mfma_f32_16x16x32_f16 v[52:55], v[148:151], v[164:167], v[52:55]
	v_mfma_f32_16x16x32_f16 v[48:51], v[156:159], v[164:167], v[48:51]
	v_mfma_f32_16x16x32_f16 v[36:39], v[148:151], v[172:175], v[36:39]
	v_mfma_f32_16x16x32_f16 v[32:35], v[156:159], v[172:175], v[32:35]
	v_mfma_f32_16x16x32_f16 v[20:23], v[148:151], v[180:183], v[20:23]
	v_mfma_f32_16x16x32_f16 v[16:19], v[156:159], v[180:183], v[16:19]
	v_mfma_f32_16x16x32_f16 v[4:7], v[148:151], v[188:191], v[4:7]
	v_mfma_f32_16x16x32_f16 v[0:3], v[156:159], v[188:191], v[0:3]
	s_setprio 0
	s_barrier
; #define PG8_STAGE(bufoff, gbase, voff) do { _Pragma("unroll") for (int _i = 0; _i < 2; ++_i) \
;         __builtin_amdgcn_global_load_lds((const unsigned*)((const char*)(gbase) + (voff)[_i]), (PG8_LAS unsigned*)(lds + (bufoff) + ldsw + _i * 8192), 16, 0, 0); } while (0)
; #define PG8_LDA(dst, b, h) do { _Pragma("unroll") for (int m = 0; m < 4; ++m) _Pragma("unroll") for (int k = 0; k < 2; ++k) dst[m][k] = *(const PG8_LAS bf16x8*)(lds + PG8_SA(b, h) + aoff + m * 2048 + k * 1024); } while (0)
; #define PG8_LDB(dst, b, h) do { _Pragma("unroll") for (int n = 0; n < 2; ++n) _Pragma("unroll") for (int k = 0; k < 2; ++k) dst[n][k] = *(const PG8_LAS bf16x8*)(lds + PG8_SB(b, h) + boff + n * 2048 + k * 1024); } while (0)
; #define PG8_MMA(ai, bj, At, Bt) do { __builtin_amdgcn_s_setprio(1); _Pragma("unroll") for (int m = 0; m < 4; ++m) _Pragma("unroll") for (int n = 0; n < 2; ++n) _Pragma("unroll") for (int k = 0; k < 2; ++k) \
;         acc[ai][bj][m][n] = mma16<F16>(Bt[n][k], At[m][k], acc[ai][bj][m][n]); __builtin_amdgcn_s_setprio(0); } while (0)
; #define PG8_WAIT_V(n) asm volatile("s_waitcnt vmcnt(" #n ")" ::: "memory")
; #define PG8_WAIT_L(n) asm volatile("s_waitcnt lgkmcnt(" #n ")" ::: "memory")
; #define PG8_BAR __builtin_amdgcn_s_barrier()
; #define PG8_SCHED __builtin_amdgcn_sched_barrier(0)
; template <class Epi, class Sched, bool ALIGN_EPI = false, bool SP2 = false, bool F16 = false>
; __device__ __forceinline__ void gemm_phase(PG8_LAS unsigned char* lds, const Gemm g, const Sched& S, const Epi& E, const int wid_in) {
;     ...
;             PG8_LDB(B0, 1, 0); PG8_LDB(B1, 1, 1); PG8_SCHED; PG8_LDA(At, 1, 0); PG8_STAGE(PG8_SA(0, 1), a2 + hstep, voffA);
;             PG8_WAIT_V(8); PG8_WAIT_L(0); PG8_BAR; PG8_MMA(0, 0, At, B0); PG8_MMA(0, 1, At, B1); PG8_BAR; PG8_SCHED;
;             PG8_LDA(At, 1, 1); PG8_STAGE(PG8_SB(1, 0), b3, voffB); PG8_STAGE(PG8_SB(1, 1), b3 + hstep, voffB); PG8_STAGE(PG8_SA(1, 0), a3, voffA);
;             PG8_WAIT_V(8); PG8_WAIT_L(0); PG8_BAR; PG8_MMA(1, 0, At, B0); PG8_MMA(1, 1, At, B1); PG8_BAR; PG8_SCHED;
	s_add_i32 s60, 0, 0x18000
	s_add_i32 s61, 0, 0x1c000
	v_add_u32_e32 v132, s60, v234
	v_add_u32_e32 v156, s61, v234
	ds_read_b128 v[112:115], v132
	ds_read_b128 v[116:119], v132 offset:1024
	ds_read_b128 v[128:131], v132 offset:2048
	ds_read_b128 v[132:135], v132 offset:3072
	ds_read_b128 v[144:147], v156
	ds_read_b128 v[148:151], v156 offset:1024
	ds_read_b128 v[152:155], v156 offset:2048
	ds_read_b128 v[156:159], v156 offset:3072
	s_add_u32 s46, s46, 0x40000
	s_addc_u32 s47, s47, 0
	s_mov_b32 m0, s90
	ds_read_b128 v[160:163], v237 offset:32768
	ds_read_b128 v[164:167], v237 offset:33792
	ds_read_b128 v[168:171], v237 offset:34816
	ds_read_b128 v[172:175], v237 offset:35840
	ds_read_b128 v[176:179], v237 offset:36864
	ds_read_b128 v[180:183], v237 offset:37888
	ds_read_b128 v[184:187], v237 offset:38912
	ds_read_b128 v[188:191], v237 offset:39936
	global_load_lds_dwordx4 v196, s[46:47]
	s_mov_b32 m0, s51
	s_nop 0
	global_load_lds_dwordx4 v200, s[46:47]
	s_waitcnt vmcnt(8)
	s_waitcnt lgkmcnt(0)
	s_barrier
	s_setprio 1
	s_waitcnt lgkmcnt(0)
	v_mfma_f32_16x16x32_f16 v[140:143], v[112:115], v[160:163], v[140:143]
	v_mfma_f32_16x16x32_f16 v[136:139], v[128:131], v[160:163], v[136:139]
	v_mfma_f32_16x16x32_f16 v[108:111], v[112:115], v[168:171], v[108:111]
	v_mfma_f32_16x16x32_f16 v[104:107], v[128:131], v[168:171], v[104:107]
	v_mfma_f32_16x16x32_f16 v[92:95], v[112:115], v[176:179], v[92:95]
	v_mfma_f32_16x16x32_f16 v[88:91], v[128:131], v[176:179], v[88:91]
	v_mfma_f32_16x16x32_f16 v[76:79], v[112:115], v[184:187], v[76:79]
	v_mfma_f32_16x16x32_f16 v[72:75], v[128:131], v[184:187], v[72:75]
	v_mfma_f32_16x16x32_f16 v[140:143], v[116:119], v[164:167], v[140:143]
	v_mfma_f32_16x16x32_f16 v[136:139], v[132:135], v[164:167], v[136:139]
	v_mfma_f32_16x16x32_f16 v[108:111], v[116:119], v[172:175], v[108:111]
	v_mfma_f32_16x16x32_f16 v[104:107], v[132:135], v[172:175], v[104:107]
	v_mfma_f32_16x16x32_f16 v[92:95], v[116:119], v[180:183], v[92:95]
	v_mfma_f32_16x16x32_f16 v[88:91], v[132:135], v[180:183], v[88:91]
	v_mfma_f32_16x16x32_f16 v[76:79], v[116:119], v[188:191], v[76:79]
	v_mfma_f32_16x16x32_f16 v[72:75], v[132:135], v[188:191], v[72:75]
	s_setprio 0
	s_setprio 1
	v_mfma_f32_16x16x32_f16 v[124:127], v[144:147], v[160:163], v[124:127]
	v_mfma_f32_16x16x32_f16 v[120:123], v[152:155], v[160:163], v[120:123]
	v_mfma_f32_16x16x32_f16 v[100:103], v[144:147], v[168:171], v[100:103]
	v_mfma_f32_16x16x32_f16 v[96:99], v[152:155], v[168:171], v[96:99]
	v_mfma_f32_16x16x32_f16 v[84:87], v[144:147], v[176:179], v[84:87]
	v_mfma_f32_16x16x32_f16 v[80:83], v[152:155], v[176:179], v[80:83]
	v_mfma_f32_16x16x32_f16 v[68:71], v[144:147], v[184:187], v[68:71]
	v_mfma_f32_16x16x32_f16 v[64:67], v[152:155], v[184:187], v[64:67]
	v_mfma_f32_16x16x32_f16 v[124:127], v[148:151], v[164:167], v[124:127]
	v_mfma_f32_16x16x32_f16 v[120:123], v[156:159], v[164:167], v[120:123]
	v_mfma_f32_16x16x32_f16 v[100:103], v[148:151], v[172:175], v[100:103]
	v_mfma_f32_16x16x32_f16 v[96:99], v[156:159], v[172:175], v[96:99]
	v_mfma_f32_16x16x32_f16 v[84:87], v[148:151], v[180:183], v[84:87]
	v_mfma_f32_16x16x32_f16 v[80:83], v[156:159], v[180:183], v[80:83]
	v_mfma_f32_16x16x32_f16 v[68:71], v[148:151], v[188:191], v[68:71]
	v_mfma_f32_16x16x32_f16 v[64:67], v[156:159], v[188:191], v[64:67]
	s_setprio 0
	s_barrier
	s_add_i32 s46, s60, s68
	v_lshl_add_u64 v[192:193], v[192:193], 0, s[26:27]
	s_mov_b32 m0, s46
	ds_read_b128 v[160:163], v237 offset:49152
	ds_read_b128 v[164:167], v237 offset:50176
	ds_read_b128 v[168:171], v237 offset:51200
	ds_read_b128 v[172:175], v237 offset:52224
	ds_read_b128 v[176:179], v237 offset:53248
	ds_read_b128 v[180:183], v237 offset:54272
	ds_read_b128 v[184:187], v237 offset:55296
	ds_read_b128 v[188:191], v237 offset:56320
	global_load_lds_dwordx4 v[192:193], off
	s_add_i32 m0, s46, 0x2000
	s_add_u32 s44, s44, 0x40080
	v_lshl_add_u64 v[192:193], v[194:195], 0, s[26:27]
	s_addc_u32 s45, s45, 0
	s_add_i32 s46, s61, s68
	global_load_lds_dwordx4 v[192:193], off
	s_mov_b32 m0, s46
	s_nop 0
	global_load_lds_dwordx4 v198, s[44:45]
	s_add_i32 m0, s46, 0x2000
	s_nop 0
	global_load_lds_dwordx4 v202, s[44:45]
	v_lshl_add_u64 v[192:193], v[212:213], 0, s[26:27]
	s_mov_b32 m0, s75
	s_nop 0
	global_load_lds_dwordx4 v[192:193], off
	v_lshl_add_u64 v[192:193], v[214:215], 0, s[26:27]
	s_mov_b32 m0, s67
	s_nop 0
	global_load_lds_dwordx4 v[192:193], off
	s_waitcnt vmcnt(8)
	s_waitcnt lgkmcnt(0)
	s_barrier
	s_setprio 1
	s_waitcnt lgkmcnt(0)
	v_mfma_f32_16x16x32_f16 v[60:63], v[112:115], v[160:163], v[60:63]
	v_mfma_f32_16x16x32_f16 v[56:59], v[128:131], v[160:163], v[56:59]
	v_mfma_f32_16x16x32_f16 v[44:47], v[112:115], v[168:171], v[44:47]
	v_mfma_f32_16x16x32_f16 v[40:43], v[128:131], v[168:171], v[40:43]
	v_mfma_f32_16x16x32_f16 v[28:31], v[112:115], v[176:179], v[28:31]
	v_mfma_f32_16x16x32_f16 v[24:27], v[128:131], v[176:179], v[24:27]
	v_mfma_f32_16x16x32_f16 v[12:15], v[112:115], v[184:187], v[12:15]
	v_mfma_f32_16x16x32_f16 v[8:11], v[128:131], v[184:187], v[8:11]
	v_mfma_f32_16x16x32_f16 v[60:63], v[116:119], v[164:167], v[60:63]
	v_mfma_f32_16x16x32_f16 v[56:59], v[132:135], v[164:167], v[56:59]
	v_mfma_f32_16x16x32_f16 v[44:47], v[116:119], v[172:175], v[44:47]
	v_mfma_f32_16x16x32_f16 v[40:43], v[132:135], v[172:175], v[40:43]
	v_mfma_f32_16x16x32_f16 v[28:31], v[116:119], v[180:183], v[28:31]
	v_mfma_f32_16x16x32_f16 v[24:27], v[132:135], v[180:183], v[24:27]
	v_mfma_f32_16x16x32_f16 v[12:15], v[116:119], v[188:191], v[12:15]
	v_mfma_f32_16x16x32_f16 v[8:11], v[132:135], v[188:191], v[8:11]
	s_setprio 0
	s_setprio 1
	v_mfma_f32_16x16x32_f16 v[52:55], v[144:147], v[160:163], v[52:55]
	v_mfma_f32_16x16x32_f16 v[48:51], v[152:155], v[160:163], v[48:51]
	v_mfma_f32_16x16x32_f16 v[36:39], v[144:147], v[168:171], v[36:39]
	v_mfma_f32_16x16x32_f16 v[32:35], v[152:155], v[168:171], v[32:35]
	v_mfma_f32_16x16x32_f16 v[20:23], v[144:147], v[176:179], v[20:23]
	v_mfma_f32_16x16x32_f16 v[16:19], v[152:155], v[176:179], v[16:19]
	v_mfma_f32_16x16x32_f16 v[4:7], v[144:147], v[184:187], v[4:7]
	v_mfma_f32_16x16x32_f16 v[0:3], v[152:155], v[184:187], v[0:3]
	v_mfma_f32_16x16x32_f16 v[52:55], v[148:151], v[164:167], v[52:55]
	v_mfma_f32_16x16x32_f16 v[48:51], v[156:159], v[164:167], v[48:51]
	v_mfma_f32_16x16x32_f16 v[36:39], v[148:151], v[172:175], v[36:39]
	v_mfma_f32_16x16x32_f16 v[32:35], v[156:159], v[172:175], v[32:35]
	v_mfma_f32_16x16x32_f16 v[20:23], v[148:151], v[180:183], v[20:23]
	v_mfma_f32_16x16x32_f16 v[16:19], v[156:159], v[180:183], v[16:19]
	v_mfma_f32_16x16x32_f16 v[4:7], v[148:151], v[188:191], v[4:7]
	v_mfma_f32_16x16x32_f16 v[0:3], v[156:159], v[188:191], v[0:3]
	s_setprio 0
	s_barrier
	s_add_i32 s59, s59, 2
	s_add_u32 s42, s42, 0x100
	s_addc_u32 s43, s43, 0
	s_add_u32 s41, s41, 0x100
	s_addc_u32 s58, s58, 0
	s_cmp_gt_u32 s59, 13
	s_cbranch_scc0 .LBB0_2793
	s_and_b64 vcc, exec, s[16:17]
	s_cbranch_vccz .LBB0_2796
	s_barrier
